# GEMM load segments: LDS-DMA pieces issued before the ds_read_b128 batch (88 of 112 segments)
# speedup vs baseline: 1.0013x; 1.0013x over previous
; #define PG8_STAGE(bufoff, gbase, voff) do { _Pragma("unroll") for (int _i = 0; _i < 2; ++_i) \
;         __builtin_amdgcn_global_load_lds((const unsigned*)((const char*)(gbase) + (voff)[_i]), (PG8_LAS unsigned*)(lds + (bufoff) + ldsw + _i * 8192), 16, 0, 0); } while (0)
; #define PG8_LDA(dst, b, h) do { _Pragma("unroll") for (int m = 0; m < 4; ++m) _Pragma("unroll") for (int k = 0; k < 2; ++k) dst[m][k] = *(const PG8_LAS bf16x8*)(lds + PG8_SA(b, h) + aoff + m * 2048 + k * 1024); } while (0)
; #define PG8_LDB(dst, b, h) do { _Pragma("unroll") for (int n = 0; n < 2; ++n) _Pragma("unroll") for (int k = 0; k < 2; ++k) dst[n][k] = *(const PG8_LAS bf16x8*)(lds + PG8_SB(b, h) + boff + n * 2048 + k * 1024); } while (0)
; #define PG8_MMA(ai, bj, At, Bt) do { __builtin_amdgcn_s_setprio(1); _Pragma("unroll") for (int m = 0; m < 4; ++m) _Pragma("unroll") for (int n = 0; n < 2; ++n) _Pragma("unroll") for (int k = 0; k < 2; ++k) \
;         acc[ai][bj][m][n] = mma16<F16>(Bt[n][k], At[m][k], acc[ai][bj][m][n]); __builtin_amdgcn_s_setprio(0); } while (0)
; #define PG8_WAIT_V(n) asm volatile("s_waitcnt vmcnt(" #n ")" ::: "memory")
; #define PG8_WAIT_L(n) asm volatile("s_waitcnt lgkmcnt(" #n ")" ::: "memory")
; #define PG8_BAR __builtin_amdgcn_s_barrier()
; #define PG8_SCHED __builtin_amdgcn_sched_barrier(0)
; template <class Epi, class Sched, bool ALIGN_EPI = false, bool SP2 = false, bool F16 = false>
; __device__ __forceinline__ void gemm_phase(PG8_LAS unsigned char* lds, const Gemm g, const Sched& S, const Epi& E, const int wid_in) {
;     ...
;             PG8_LDB(B0, 0, 0); PG8_LDB(B1, 0, 1); PG8_SCHED; PG8_LDA(At, 0, 0); PG8_STAGE(PG8_SA(1, 1), a1 + hstep, voffA);
;             PG8_WAIT_V(8); PG8_WAIT_L(0); PG8_BAR; PG8_MMA(0, 0, At, B0); PG8_MMA(0, 1, At, B1); PG8_BAR; PG8_SCHED;
;             PG8_LDA(At, 0, 1); PG8_STAGE(PG8_SB(0, 0), b2, voffB); PG8_STAGE(PG8_SB(0, 1), b2 + hstep, voffB); PG8_STAGE(PG8_SA(0, 0), a2, voffA);
.LBB0_224:
	ds_read_b128 v[128:131], v184
	ds_read_b128 v[132:135], v184 offset:1024
	ds_read_b128 v[136:139], v184 offset:2048
	ds_read_b128 v[140:143], v184 offset:3072
	ds_read_b128 v[144:147], v185
	ds_read_b128 v[148:151], v185 offset:1024
	ds_read_b128 v[152:155], v185 offset:2048
	ds_read_b128 v[174:177], v185 offset:3072
	s_add_u32 s58, s56, 0xfffc0080
	s_addc_u32 s59, s57, -1
	s_cmp_eq_u32 s62, 12
	s_cselect_b32 s61, s9, s59
	s_cselect_b32 s60, s21, s58
	s_cselect_b32 s59, s42, s51
	s_cselect_b32 s58, s43, s49
	v_lshl_add_u64 v[178:179], s[56:57], 0, v[166:167]
	s_add_i32 m0, s83, 0xc000
	ds_read_b128 v[190:193], v186
	ds_read_b128 v[194:197], v186 offset:1024
	ds_read_b128 v[198:201], v186 offset:2048
	ds_read_b128 v[202:205], v186 offset:3072
	ds_read_b128 v[206:209], v186 offset:4096
	ds_read_b128 v[210:213], v186 offset:5120
	ds_read_b128 v[214:217], v186 offset:6144
	ds_read_b128 v[218:221], v186 offset:7168
	global_load_lds_dwordx4 v[178:179], off
	v_lshl_add_u64 v[178:179], s[56:57], 0, v[168:169]
	s_add_i32 m0, s83, 0xe000
	s_nop 0
	global_load_lds_dwordx4 v[178:179], off
	s_waitcnt vmcnt(8)
	s_waitcnt lgkmcnt(0)
	s_barrier
	s_waitcnt lgkmcnt(0)
	v_mfma_f32_16x16x32_f16 v[124:127], v[128:131], v[190:193], v[124:127]
	v_mfma_f32_16x16x32_f16 v[120:123], v[136:139], v[190:193], v[120:123]
	v_mfma_f32_16x16x32_f16 v[108:111], v[128:131], v[198:201], v[108:111]
	v_mfma_f32_16x16x32_f16 v[104:107], v[136:139], v[198:201], v[104:107]
	v_mfma_f32_16x16x32_f16 v[92:95], v[128:131], v[206:209], v[92:95]
	v_mfma_f32_16x16x32_f16 v[88:91], v[136:139], v[206:209], v[88:91]
	v_mfma_f32_16x16x32_f16 v[76:79], v[128:131], v[214:217], v[76:79]
	v_mfma_f32_16x16x32_f16 v[72:75], v[136:139], v[214:217], v[72:75]
	v_mfma_f32_16x16x32_f16 v[124:127], v[132:135], v[194:197], v[124:127]
	v_mfma_f32_16x16x32_f16 v[120:123], v[140:143], v[194:197], v[120:123]
	v_mfma_f32_16x16x32_f16 v[108:111], v[132:135], v[202:205], v[108:111]
	v_mfma_f32_16x16x32_f16 v[104:107], v[140:143], v[202:205], v[104:107]
	v_mfma_f32_16x16x32_f16 v[92:95], v[132:135], v[210:213], v[92:95]
	v_mfma_f32_16x16x32_f16 v[88:91], v[140:143], v[210:213], v[88:91]
	v_mfma_f32_16x16x32_f16 v[76:79], v[132:135], v[218:221], v[76:79]
	v_mfma_f32_16x16x32_f16 v[72:75], v[140:143], v[218:221], v[72:75]
	v_mfma_f32_16x16x32_f16 v[116:119], v[144:147], v[190:193], v[116:119]
	v_mfma_f32_16x16x32_f16 v[112:115], v[152:155], v[190:193], v[112:115]
	v_mfma_f32_16x16x32_f16 v[100:103], v[144:147], v[198:201], v[100:103]
	v_mfma_f32_16x16x32_f16 v[96:99], v[152:155], v[198:201], v[96:99]
	v_mfma_f32_16x16x32_f16 v[84:87], v[144:147], v[206:209], v[84:87]
	v_mfma_f32_16x16x32_f16 v[80:83], v[152:155], v[206:209], v[80:83]
	v_mfma_f32_16x16x32_f16 v[68:71], v[144:147], v[214:217], v[68:71]
	v_mfma_f32_16x16x32_f16 v[64:67], v[152:155], v[214:217], v[64:67]
	v_mfma_f32_16x16x32_f16 v[116:119], v[148:151], v[194:197], v[116:119]
	v_mfma_f32_16x16x32_f16 v[112:115], v[174:177], v[194:197], v[112:115]
	v_mfma_f32_16x16x32_f16 v[100:103], v[148:151], v[202:205], v[100:103]
	v_mfma_f32_16x16x32_f16 v[96:99], v[174:177], v[202:205], v[96:99]
	v_mfma_f32_16x16x32_f16 v[84:87], v[148:151], v[210:213], v[84:87]
	v_mfma_f32_16x16x32_f16 v[80:83], v[174:177], v[210:213], v[80:83]
	v_mfma_f32_16x16x32_f16 v[68:71], v[148:151], v[218:221], v[68:71]
	v_mfma_f32_16x16x32_f16 v[64:67], v[174:177], v[218:221], v[64:67]
	s_barrier
	s_add_i32 s63, s40, s68
	v_lshl_add_u64 v[178:179], s[58:59], 0, v[158:159]
	s_mov_b32 m0, s63
	s_nop 0
	global_load_lds_dwordx4 v[178:179], off
	s_add_i32 m0, s63, 0x2000
	s_add_u32 s64, s58, 0x40000
	v_lshl_add_u64 v[222:223], s[58:59], 0, v[162:163]
	s_addc_u32 s65, s59, 0
	s_add_i32 s63, s41, s68
	global_load_lds_dwordx4 v[222:223], off
	v_lshl_add_u64 v[224:225], s[64:65], 0, v[158:159]
	s_mov_b32 m0, s63
	v_lshl_add_u64 v[226:227], s[60:61], 0, v[160:161]
	global_load_lds_dwordx4 v[224:225], off
	v_lshl_add_u64 v[224:225], s[64:65], 0, v[162:163]
	s_add_i32 m0, s63, 0x2000
	s_nop 0
	global_load_lds_dwordx4 v[224:225], off
	v_lshl_add_u64 v[224:225], s[60:61], 0, v[156:157]
	s_mov_b32 m0, s83
	s_nop 0
	global_load_lds_dwordx4 v[224:225], off
	s_mov_b32 m0, s84
	s_nop 0
	global_load_lds_dwordx4 v[226:227], off
	ds_read_b128 v[190:193], v186 offset:16384
	ds_read_b128 v[194:197], v186 offset:17408
	ds_read_b128 v[198:201], v186 offset:18432
	ds_read_b128 v[202:205], v186 offset:19456
	ds_read_b128 v[206:209], v186 offset:20480
	ds_read_b128 v[210:213], v186 offset:21504
	ds_read_b128 v[214:217], v186 offset:22528
	ds_read_b128 v[218:221], v186 offset:23552
	s_waitcnt vmcnt(8)
	s_waitcnt lgkmcnt(0)
	s_barrier
; #define PG8_STAGE(bufoff, gbase, voff) do { _Pragma("unroll") for (int _i = 0; _i < 2; ++_i) \
;         __builtin_amdgcn_global_load_lds((const unsigned*)((const char*)(gbase) + (voff)[_i]), (PG8_LAS unsigned*)(lds + (bufoff) + ldsw + _i * 8192), 16, 0, 0); } while (0)
; #define PG8_LDA(dst, b, h) do { _Pragma("unroll") for (int m = 0; m < 4; ++m) _Pragma("unroll") for (int k = 0; k < 2; ++k) dst[m][k] = *(const PG8_LAS bf16x8*)(lds + PG8_SA(b, h) + aoff + m * 2048 + k * 1024); } while (0)
; #define PG8_LDB(dst, b, h) do { _Pragma("unroll") for (int n = 0; n < 2; ++n) _Pragma("unroll") for (int k = 0; k < 2; ++k) dst[n][k] = *(const PG8_LAS bf16x8*)(lds + PG8_SB(b, h) + boff + n * 2048 + k * 1024); } while (0)
; #define PG8_MMA(ai, bj, At, Bt) do { __builtin_amdgcn_s_setprio(1); _Pragma("unroll") for (int m = 0; m < 4; ++m) _Pragma("unroll") for (int n = 0; n < 2; ++n) _Pragma("unroll") for (int k = 0; k < 2; ++k) \
;         acc[ai][bj][m][n] = mma16<F16>(Bt[n][k], At[m][k], acc[ai][bj][m][n]); __builtin_amdgcn_s_setprio(0); } while (0)
; #define PG8_WAIT_V(n) asm volatile("s_waitcnt vmcnt(" #n ")" ::: "memory")
; #define PG8_WAIT_L(n) asm volatile("s_waitcnt lgkmcnt(" #n ")" ::: "memory")
; #define PG8_BAR __builtin_amdgcn_s_barrier()
; #define PG8_SCHED __builtin_amdgcn_sched_barrier(0)
; template <class Epi, class Sched, bool ALIGN_EPI = false, bool SP2 = false, bool F16 = false>
; __device__ __forceinline__ void gemm_phase(PG8_LAS unsigned char* lds, const Gemm g, const Sched& S, const Epi& E, const int wid_in) {
;     ...
;             PG8_WAIT_V(8); PG8_WAIT_L(0); PG8_BAR; PG8_MMA(0, 0, At, B0); PG8_MMA(0, 1, At, B1); PG8_BAR; PG8_SCHED;
;             PG8_LDA(At, 0, 1); PG8_STAGE(PG8_SB(0, 0), b2, voffB); PG8_STAGE(PG8_SB(0, 1), b2 + hstep, voffB); PG8_STAGE(PG8_SA(0, 0), a2, voffA);
;             PG8_WAIT_V(8); PG8_WAIT_L(0); PG8_BAR; PG8_MMA(1, 0, At, B0); PG8_MMA(1, 1, At, B1); PG8_BAR; PG8_SCHED;
;             PG8_LDB(B0, 1, 0); PG8_LDB(B1, 1, 1); PG8_SCHED; PG8_LDA(At, 1, 0); PG8_STAGE(PG8_SA(0, 1), a2 + hstep, voffA);
	s_waitcnt lgkmcnt(0)
	v_mfma_f32_16x16x32_f16 v[60:63], v[128:131], v[190:193], v[60:63]
	v_mfma_f32_16x16x32_f16 v[56:59], v[136:139], v[190:193], v[56:59]
	v_mfma_f32_16x16x32_f16 v[44:47], v[128:131], v[198:201], v[44:47]
	v_mfma_f32_16x16x32_f16 v[40:43], v[136:139], v[198:201], v[40:43]
	v_mfma_f32_16x16x32_f16 v[28:31], v[128:131], v[206:209], v[28:31]
	v_mfma_f32_16x16x32_f16 v[24:27], v[136:139], v[206:209], v[24:27]
	v_mfma_f32_16x16x32_f16 v[12:15], v[128:131], v[214:217], v[12:15]
	v_mfma_f32_16x16x32_f16 v[8:11], v[136:139], v[214:217], v[8:11]
	v_mfma_f32_16x16x32_f16 v[60:63], v[132:135], v[194:197], v[60:63]
	v_mfma_f32_16x16x32_f16 v[56:59], v[140:143], v[194:197], v[56:59]
	v_mfma_f32_16x16x32_f16 v[44:47], v[132:135], v[202:205], v[44:47]
	v_mfma_f32_16x16x32_f16 v[40:43], v[140:143], v[202:205], v[40:43]
	v_mfma_f32_16x16x32_f16 v[28:31], v[132:135], v[210:213], v[28:31]
	v_mfma_f32_16x16x32_f16 v[24:27], v[140:143], v[210:213], v[24:27]
	v_mfma_f32_16x16x32_f16 v[12:15], v[132:135], v[218:221], v[12:15]
	v_mfma_f32_16x16x32_f16 v[8:11], v[140:143], v[218:221], v[8:11]
	v_mfma_f32_16x16x32_f16 v[52:55], v[144:147], v[190:193], v[52:55]
	v_mfma_f32_16x16x32_f16 v[48:51], v[152:155], v[190:193], v[48:51]
	v_mfma_f32_16x16x32_f16 v[36:39], v[144:147], v[198:201], v[36:39]
	v_mfma_f32_16x16x32_f16 v[32:35], v[152:155], v[198:201], v[32:35]
	v_mfma_f32_16x16x32_f16 v[20:23], v[144:147], v[206:209], v[20:23]
	v_mfma_f32_16x16x32_f16 v[16:19], v[152:155], v[206:209], v[16:19]
	v_mfma_f32_16x16x32_f16 v[4:7], v[144:147], v[214:217], v[4:7]
	v_mfma_f32_16x16x32_f16 v[0:3], v[152:155], v[214:217], v[0:3]
	v_mfma_f32_16x16x32_f16 v[52:55], v[148:151], v[194:197], v[52:55]
	v_mfma_f32_16x16x32_f16 v[48:51], v[174:177], v[194:197], v[48:51]
	v_mfma_f32_16x16x32_f16 v[36:39], v[148:151], v[202:205], v[36:39]
	v_mfma_f32_16x16x32_f16 v[32:35], v[174:177], v[202:205], v[32:35]
	v_mfma_f32_16x16x32_f16 v[20:23], v[148:151], v[210:213], v[20:23]
	v_mfma_f32_16x16x32_f16 v[16:19], v[174:177], v[210:213], v[16:19]
	v_mfma_f32_16x16x32_f16 v[4:7], v[148:151], v[218:221], v[4:7]
	v_mfma_f32_16x16x32_f16 v[0:3], v[174:177], v[218:221], v[0:3]
	s_barrier
	s_add_i32 s63, 0, 0x18000
	s_add_i32 s64, 0, 0x1c000
	v_add_u32_e32 v140, s63, v183
	v_add_u32_e32 v165, s64, v183
	s_add_u32 s60, s60, 0x40000
	s_addc_u32 s61, s61, 0
	s_mov_b32 m0, s85
	v_lshl_add_u64 v[228:229], s[60:61], 0, v[156:157]
	global_load_lds_dwordx4 v[228:229], off
	v_lshl_add_u64 v[228:229], s[60:61], 0, v[160:161]
	s_mov_b32 m0, s86
	s_nop 0
	global_load_lds_dwordx4 v[228:229], off
	ds_read_b128 v[128:131], v140
	ds_read_b128 v[132:135], v140 offset:1024
	ds_read_b128 v[136:139], v140 offset:2048
	ds_read_b128 v[140:143], v140 offset:3072
	ds_read_b128 v[144:147], v165
	ds_read_b128 v[148:151], v165 offset:1024
	ds_read_b128 v[152:155], v165 offset:2048
	ds_read_b128 v[174:177], v165 offset:3072
	ds_read_b128 v[190:193], v186 offset:32768
	ds_read_b128 v[194:197], v186 offset:33792
	ds_read_b128 v[198:201], v186 offset:34816
	ds_read_b128 v[202:205], v186 offset:35840
	ds_read_b128 v[206:209], v186 offset:36864
	ds_read_b128 v[210:213], v186 offset:37888
	ds_read_b128 v[214:217], v186 offset:38912
	ds_read_b128 v[218:221], v186 offset:39936
	s_waitcnt vmcnt(8)
	s_waitcnt lgkmcnt(0)
	s_barrier
	s_waitcnt lgkmcnt(0)
	v_mfma_f32_16x16x32_f16 v[124:127], v[128:131], v[190:193], v[124:127]
	v_mfma_f32_16x16x32_f16 v[120:123], v[136:139], v[190:193], v[120:123]
	v_mfma_f32_16x16x32_f16 v[108:111], v[128:131], v[198:201], v[108:111]
	v_mfma_f32_16x16x32_f16 v[104:107], v[136:139], v[198:201], v[104:107]
	v_mfma_f32_16x16x32_f16 v[92:95], v[128:131], v[206:209], v[92:95]
	v_mfma_f32_16x16x32_f16 v[88:91], v[136:139], v[206:209], v[88:91]
	v_mfma_f32_16x16x32_f16 v[76:79], v[128:131], v[214:217], v[76:79]
	v_mfma_f32_16x16x32_f16 v[72:75], v[136:139], v[214:217], v[72:75]
	v_mfma_f32_16x16x32_f16 v[124:127], v[132:135], v[194:197], v[124:127]
	v_mfma_f32_16x16x32_f16 v[120:123], v[140:143], v[194:197], v[120:123]
	v_mfma_f32_16x16x32_f16 v[108:111], v[132:135], v[202:205], v[108:111]
	v_mfma_f32_16x16x32_f16 v[104:107], v[140:143], v[202:205], v[104:107]
	v_mfma_f32_16x16x32_f16 v[92:95], v[132:135], v[210:213], v[92:95]
	v_mfma_f32_16x16x32_f16 v[88:91], v[140:143], v[210:213], v[88:91]
	v_mfma_f32_16x16x32_f16 v[76:79], v[132:135], v[218:221], v[76:79]
	v_mfma_f32_16x16x32_f16 v[72:75], v[140:143], v[218:221], v[72:75]
	v_mfma_f32_16x16x32_f16 v[116:119], v[144:147], v[190:193], v[116:119]
	v_mfma_f32_16x16x32_f16 v[112:115], v[152:155], v[190:193], v[112:115]
	v_mfma_f32_16x16x32_f16 v[100:103], v[144:147], v[198:201], v[100:103]
	v_mfma_f32_16x16x32_f16 v[96:99], v[152:155], v[198:201], v[96:99]
	v_mfma_f32_16x16x32_f16 v[84:87], v[144:147], v[206:209], v[84:87]
	v_mfma_f32_16x16x32_f16 v[80:83], v[152:155], v[206:209], v[80:83]
	v_mfma_f32_16x16x32_f16 v[68:71], v[144:147], v[214:217], v[68:71]
	v_mfma_f32_16x16x32_f16 v[64:67], v[152:155], v[214:217], v[64:67]
	v_mfma_f32_16x16x32_f16 v[116:119], v[148:151], v[194:197], v[116:119]
	v_mfma_f32_16x16x32_f16 v[112:115], v[174:177], v[194:197], v[112:115]
	v_mfma_f32_16x16x32_f16 v[100:103], v[148:151], v[202:205], v[100:103]
	v_mfma_f32_16x16x32_f16 v[96:99], v[174:177], v[202:205], v[96:99]
	v_mfma_f32_16x16x32_f16 v[84:87], v[148:151], v[210:213], v[84:87]
	v_mfma_f32_16x16x32_f16 v[80:83], v[174:177], v[210:213], v[80:83]
	v_mfma_f32_16x16x32_f16 v[68:71], v[148:151], v[218:221], v[68:71]
	v_mfma_f32_16x16x32_f16 v[64:67], v[174:177], v[218:221], v[64:67]
	s_barrier
; #define PG8_STAGE(bufoff, gbase, voff) do { _Pragma("unroll") for (int _i = 0; _i < 2; ++_i) \
;         __builtin_amdgcn_global_load_lds((const unsigned*)((const char*)(gbase) + (voff)[_i]), (PG8_LAS unsigned*)(lds + (bufoff) + ldsw + _i * 8192), 16, 0, 0); } while (0)
; #define PG8_LDA(dst, b, h) do { _Pragma("unroll") for (int m = 0; m < 4; ++m) _Pragma("unroll") for (int k = 0; k < 2; ++k) dst[m][k] = *(const PG8_LAS bf16x8*)(lds + PG8_SA(b, h) + aoff + m * 2048 + k * 1024); } while (0)
; #define PG8_MMA(ai, bj, At, Bt) do { __builtin_amdgcn_s_setprio(1); _Pragma("unroll") for (int m = 0; m < 4; ++m) _Pragma("unroll") for (int n = 0; n < 2; ++n) _Pragma("unroll") for (int k = 0; k < 2; ++k) \
;         acc[ai][bj][m][n] = mma16<F16>(Bt[n][k], At[m][k], acc[ai][bj][m][n]); __builtin_amdgcn_s_setprio(0); } while (0)
; #define PG8_WAIT_V(n) asm volatile("s_waitcnt vmcnt(" #n ")" ::: "memory")
; #define PG8_WAIT_L(n) asm volatile("s_waitcnt lgkmcnt(" #n ")" ::: "memory")
; #define PG8_BAR __builtin_amdgcn_s_barrier()
; #define PG8_SCHED __builtin_amdgcn_sched_barrier(0)
; template <class Epi, class Sched, bool ALIGN_EPI = false, bool SP2 = false, bool F16 = false>
; __device__ __forceinline__ void gemm_phase(PG8_LAS unsigned char* lds, const Gemm g, const Sched& S, const Epi& E, const int wid_in) {
;     ...
;             PG8_LDA(At, 1, 1); PG8_STAGE(PG8_SB(1, 0), b3, voffB); PG8_STAGE(PG8_SB(1, 1), b3 + hstep, voffB); PG8_STAGE(PG8_SA(1, 0), a3, voffA);
;             PG8_WAIT_V(8); PG8_WAIT_L(0); PG8_BAR; PG8_MMA(1, 0, At, B0); PG8_MMA(1, 1, At, B1); PG8_BAR; PG8_SCHED;
;     ...
;         if constexpr (ALIGN_EPI) { if (wr == 0) PG8_BAR; }
	s_add_i32 s60, s63, s68
	v_lshl_add_u64 v[178:179], v[178:179], 0, s[24:25]
	s_mov_b32 m0, s60
	s_nop 0
	global_load_lds_dwordx4 v[178:179], off
	s_add_i32 m0, s60, 0x2000
	s_add_u32 s58, s58, 0x40080
	v_lshl_add_u64 v[178:179], v[222:223], 0, s[24:25]
	s_addc_u32 s59, s59, 0
	s_add_i32 s60, s64, s68
	global_load_lds_dwordx4 v[178:179], off
	v_lshl_add_u64 v[178:179], s[58:59], 0, v[158:159]
	s_mov_b32 m0, s60
	s_nop 0
	global_load_lds_dwordx4 v[178:179], off
	v_lshl_add_u64 v[178:179], s[58:59], 0, v[162:163]
	s_add_i32 m0, s60, 0x2000
	s_nop 0
	global_load_lds_dwordx4 v[178:179], off
	v_lshl_add_u64 v[178:179], v[224:225], 0, s[24:25]
	s_mov_b32 m0, s90
	s_nop 0
	global_load_lds_dwordx4 v[178:179], off
	v_lshl_add_u64 v[178:179], v[226:227], 0, s[24:25]
	s_mov_b32 m0, s91
	s_nop 0
	global_load_lds_dwordx4 v[178:179], off
	ds_read_b128 v[190:193], v186 offset:49152
	ds_read_b128 v[194:197], v186 offset:50176
	ds_read_b128 v[198:201], v186 offset:51200
	ds_read_b128 v[202:205], v186 offset:52224
	ds_read_b128 v[206:209], v186 offset:53248
	ds_read_b128 v[210:213], v186 offset:54272
	ds_read_b128 v[214:217], v186 offset:55296
	ds_read_b128 v[218:221], v186 offset:56320
	s_waitcnt vmcnt(8)
	s_waitcnt lgkmcnt(0)
	s_barrier
	s_waitcnt lgkmcnt(0)
	v_mfma_f32_16x16x32_f16 v[60:63], v[128:131], v[190:193], v[60:63]
	v_mfma_f32_16x16x32_f16 v[56:59], v[136:139], v[190:193], v[56:59]
	v_mfma_f32_16x16x32_f16 v[44:47], v[128:131], v[198:201], v[44:47]
	v_mfma_f32_16x16x32_f16 v[40:43], v[136:139], v[198:201], v[40:43]
	v_mfma_f32_16x16x32_f16 v[28:31], v[128:131], v[206:209], v[28:31]
	v_mfma_f32_16x16x32_f16 v[24:27], v[136:139], v[206:209], v[24:27]
	v_mfma_f32_16x16x32_f16 v[12:15], v[128:131], v[214:217], v[12:15]
	v_mfma_f32_16x16x32_f16 v[8:11], v[136:139], v[214:217], v[8:11]
	v_mfma_f32_16x16x32_f16 v[60:63], v[132:135], v[194:197], v[60:63]
	v_mfma_f32_16x16x32_f16 v[56:59], v[140:143], v[194:197], v[56:59]
	v_mfma_f32_16x16x32_f16 v[44:47], v[132:135], v[202:205], v[44:47]
	v_mfma_f32_16x16x32_f16 v[40:43], v[140:143], v[202:205], v[40:43]
	v_mfma_f32_16x16x32_f16 v[28:31], v[132:135], v[210:213], v[28:31]
	v_mfma_f32_16x16x32_f16 v[24:27], v[140:143], v[210:213], v[24:27]
	v_mfma_f32_16x16x32_f16 v[12:15], v[132:135], v[218:221], v[12:15]
	v_mfma_f32_16x16x32_f16 v[8:11], v[140:143], v[218:221], v[8:11]
	v_mfma_f32_16x16x32_f16 v[52:55], v[144:147], v[190:193], v[52:55]
	v_mfma_f32_16x16x32_f16 v[48:51], v[152:155], v[190:193], v[48:51]
	v_mfma_f32_16x16x32_f16 v[36:39], v[144:147], v[198:201], v[36:39]
	v_mfma_f32_16x16x32_f16 v[32:35], v[152:155], v[198:201], v[32:35]
	v_mfma_f32_16x16x32_f16 v[20:23], v[144:147], v[206:209], v[20:23]
	v_mfma_f32_16x16x32_f16 v[16:19], v[152:155], v[206:209], v[16:19]
	v_mfma_f32_16x16x32_f16 v[4:7], v[144:147], v[214:217], v[4:7]
	v_mfma_f32_16x16x32_f16 v[0:3], v[152:155], v[214:217], v[0:3]
	v_mfma_f32_16x16x32_f16 v[52:55], v[148:151], v[194:197], v[52:55]
	v_mfma_f32_16x16x32_f16 v[48:51], v[174:177], v[194:197], v[48:51]
	v_mfma_f32_16x16x32_f16 v[36:39], v[148:151], v[202:205], v[36:39]
	v_mfma_f32_16x16x32_f16 v[32:35], v[174:177], v[202:205], v[32:35]
	v_mfma_f32_16x16x32_f16 v[20:23], v[148:151], v[210:213], v[20:23]
	v_mfma_f32_16x16x32_f16 v[16:19], v[174:177], v[210:213], v[16:19]
	v_mfma_f32_16x16x32_f16 v[4:7], v[148:151], v[218:221], v[4:7]
	v_mfma_f32_16x16x32_f16 v[0:3], v[174:177], v[218:221], v[0:3]
	s_barrier
	s_add_i32 s62, s62, 2
	s_add_u32 s56, s56, 0x100
	s_addc_u32 s57, s57, 0
	s_add_u32 s49, s49, 0x100
	s_addc_u32 s51, s51, 0
	s_cmp_gt_u32 s62, 13
	s_cbranch_scc0 .LBB0_224
	s_and_b64 vcc, exec, s[26:27]
	s_cbranch_vccz .LBB0_227
	s_barrier

; #define PG8_STAGE(bufoff, gbase, voff) do { _Pragma("unroll") for (int _i = 0; _i < 2; ++_i) \
;         __builtin_amdgcn_global_load_lds((const unsigned*)((const char*)(gbase) + (voff)[_i]), (PG8_LAS unsigned*)(lds + (bufoff) + ldsw + _i * 8192), 16, 0, 0); } while (0)
; #define PG8_LDA(dst, b, h) do { _Pragma("unroll") for (int m = 0; m < 4; ++m) _Pragma("unroll") for (int k = 0; k < 2; ++k) dst[m][k] = *(const PG8_LAS bf16x8*)(lds + PG8_SA(b, h) + aoff + m * 2048 + k * 1024); } while (0)
; #define PG8_LDB(dst, b, h) do { _Pragma("unroll") for (int n = 0; n < 2; ++n) _Pragma("unroll") for (int k = 0; k < 2; ++k) dst[n][k] = *(const PG8_LAS bf16x8*)(lds + PG8_SB(b, h) + boff + n * 2048 + k * 1024); } while (0)
; #define PG8_MMA(ai, bj, At, Bt) do { __builtin_amdgcn_s_setprio(1); _Pragma("unroll") for (int m = 0; m < 4; ++m) _Pragma("unroll") for (int n = 0; n < 2; ++n) _Pragma("unroll") for (int k = 0; k < 2; ++k) \
;         acc[ai][bj][m][n] = mma16<F16>(Bt[n][k], At[m][k], acc[ai][bj][m][n]); __builtin_amdgcn_s_setprio(0); } while (0)
; #define PG8_WAIT_V(n) asm volatile("s_waitcnt vmcnt(" #n ")" ::: "memory")
; #define PG8_WAIT_L(n) asm volatile("s_waitcnt lgkmcnt(" #n ")" ::: "memory")
; #define PG8_BAR __builtin_amdgcn_s_barrier()
; #define PG8_SCHED __builtin_amdgcn_sched_barrier(0)
; template <class Epi, class Sched, bool ALIGN_EPI = false, bool SP2 = false, bool F16 = false>
; __device__ __forceinline__ void gemm_phase(PG8_LAS unsigned char* lds, const Gemm g, const Sched& S, const Epi& E, const int wid_in) {
;     ...
;             PG8_LDB(B0, 0, 0); PG8_LDB(B1, 0, 1); PG8_SCHED; PG8_LDA(At, 0, 0); PG8_STAGE(PG8_SA(1, 1), a1 + hstep, voffA);
;             PG8_WAIT_V(8); PG8_WAIT_L(0); PG8_BAR; PG8_MMA(0, 0, At, B0); PG8_MMA(0, 1, At, B1); PG8_BAR; PG8_SCHED;
;             PG8_LDA(At, 0, 1); PG8_STAGE(PG8_SB(0, 0), b2, voffB); PG8_STAGE(PG8_SB(0, 1), b2 + hstep, voffB); PG8_STAGE(PG8_SA(0, 0), a2, voffA);
.LBB0_508:
	ds_read_b128 v[128:131], v189
	ds_read_b128 v[132:135], v189 offset:1024
	ds_read_b128 v[136:139], v189 offset:2048
	ds_read_b128 v[140:143], v189 offset:3072
	ds_read_b128 v[144:147], v190
	ds_read_b128 v[148:151], v190 offset:1024
	ds_read_b128 v[168:171], v190 offset:2048
	ds_read_b128 v[172:175], v190 offset:3072
	s_add_u32 s46, s44, 0xfffc0080
	s_addc_u32 s47, s45, -1
	s_cmp_eq_u32 s43, 12
	s_cselect_b32 s49, s10, s47
	s_cselect_b32 s48, s27, s46
	s_cselect_b32 s47, s25, s42
	s_cselect_b32 s46, s35, s37
	v_lshl_add_u64 v[184:185], s[44:45], 0, v[160:161]
	s_add_i32 m0, s74, 0xc000
	ds_read_b128 v[176:179], v191
	ds_read_b128 v[180:183], v191 offset:1024
	ds_read_b128 v[192:195], v191 offset:2048
	ds_read_b128 v[196:199], v191 offset:3072
	ds_read_b128 v[200:203], v191 offset:4096
	ds_read_b128 v[204:207], v191 offset:5120
	ds_read_b128 v[208:211], v191 offset:6144
	ds_read_b128 v[212:215], v191 offset:7168
	global_load_lds_dwordx4 v[184:185], off
	v_lshl_add_u64 v[184:185], s[44:45], 0, v[162:163]
	s_add_i32 m0, s74, 0xe000
	s_nop 0
	global_load_lds_dwordx4 v[184:185], off
	s_waitcnt vmcnt(8)
	s_waitcnt lgkmcnt(0)
	s_barrier
	s_waitcnt lgkmcnt(0)
	v_mfma_f32_16x16x32_bf16 v[124:127], v[128:131], v[176:179], v[124:127]
	v_mfma_f32_16x16x32_bf16 v[120:123], v[136:139], v[176:179], v[120:123]
	v_mfma_f32_16x16x32_bf16 v[108:111], v[128:131], v[192:195], v[108:111]
	v_mfma_f32_16x16x32_bf16 v[104:107], v[136:139], v[192:195], v[104:107]
	v_mfma_f32_16x16x32_bf16 v[92:95], v[128:131], v[200:203], v[92:95]
	v_mfma_f32_16x16x32_bf16 v[88:91], v[136:139], v[200:203], v[88:91]
	v_mfma_f32_16x16x32_bf16 v[76:79], v[128:131], v[208:211], v[76:79]
	v_mfma_f32_16x16x32_bf16 v[72:75], v[136:139], v[208:211], v[72:75]
	v_mfma_f32_16x16x32_bf16 v[124:127], v[132:135], v[180:183], v[124:127]
	v_mfma_f32_16x16x32_bf16 v[120:123], v[140:143], v[180:183], v[120:123]
	v_mfma_f32_16x16x32_bf16 v[108:111], v[132:135], v[196:199], v[108:111]
	v_mfma_f32_16x16x32_bf16 v[104:107], v[140:143], v[196:199], v[104:107]
	v_mfma_f32_16x16x32_bf16 v[92:95], v[132:135], v[204:207], v[92:95]
	v_mfma_f32_16x16x32_bf16 v[88:91], v[140:143], v[204:207], v[88:91]
	v_mfma_f32_16x16x32_bf16 v[76:79], v[132:135], v[212:215], v[76:79]
	v_mfma_f32_16x16x32_bf16 v[72:75], v[140:143], v[212:215], v[72:75]
	v_mfma_f32_16x16x32_bf16 v[116:119], v[144:147], v[176:179], v[116:119]
	v_mfma_f32_16x16x32_bf16 v[112:115], v[168:171], v[176:179], v[112:115]
	v_mfma_f32_16x16x32_bf16 v[100:103], v[144:147], v[192:195], v[100:103]
	v_mfma_f32_16x16x32_bf16 v[96:99], v[168:171], v[192:195], v[96:99]
	v_mfma_f32_16x16x32_bf16 v[84:87], v[144:147], v[200:203], v[84:87]
	v_mfma_f32_16x16x32_bf16 v[80:83], v[168:171], v[200:203], v[80:83]
	v_mfma_f32_16x16x32_bf16 v[68:71], v[144:147], v[208:211], v[68:71]
	v_mfma_f32_16x16x32_bf16 v[64:67], v[168:171], v[208:211], v[64:67]
	v_mfma_f32_16x16x32_bf16 v[116:119], v[148:151], v[180:183], v[116:119]
	v_mfma_f32_16x16x32_bf16 v[112:115], v[172:175], v[180:183], v[112:115]
	v_mfma_f32_16x16x32_bf16 v[100:103], v[148:151], v[196:199], v[100:103]
	v_mfma_f32_16x16x32_bf16 v[96:99], v[172:175], v[196:199], v[96:99]
	v_mfma_f32_16x16x32_bf16 v[84:87], v[148:151], v[204:207], v[84:87]
	v_mfma_f32_16x16x32_bf16 v[80:83], v[172:175], v[204:207], v[80:83]
	v_mfma_f32_16x16x32_bf16 v[68:71], v[148:151], v[212:215], v[68:71]
	v_mfma_f32_16x16x32_bf16 v[64:67], v[172:175], v[212:215], v[64:67]
	s_barrier
	s_add_i32 s63, s60, s68
	v_lshl_add_u64 v[184:185], s[46:47], 0, v[154:155]
	s_mov_b32 m0, s63
	s_nop 0
	global_load_lds_dwordx4 v[184:185], off
	s_add_i32 m0, s63, 0x2000
	s_add_u32 s64, s46, 0x40000
	v_lshl_add_u64 v[216:217], s[46:47], 0, v[158:159]
	s_addc_u32 s65, s47, 0
	s_add_i32 s63, s61, s68
	global_load_lds_dwordx4 v[216:217], off
	v_lshl_add_u64 v[218:219], s[64:65], 0, v[154:155]
	s_mov_b32 m0, s63
	v_lshl_add_u64 v[220:221], s[48:49], 0, v[156:157]
	global_load_lds_dwordx4 v[218:219], off
	v_lshl_add_u64 v[218:219], s[64:65], 0, v[158:159]
	s_add_i32 m0, s63, 0x2000
	s_nop 0
	global_load_lds_dwordx4 v[218:219], off
	v_lshl_add_u64 v[218:219], s[48:49], 0, v[152:153]
	s_mov_b32 m0, s74
	s_nop 0
	global_load_lds_dwordx4 v[218:219], off
	s_mov_b32 m0, s51
	s_nop 0
	global_load_lds_dwordx4 v[220:221], off
	ds_read_b128 v[176:179], v191 offset:16384
	ds_read_b128 v[180:183], v191 offset:17408
	ds_read_b128 v[192:195], v191 offset:18432
	ds_read_b128 v[196:199], v191 offset:19456
	ds_read_b128 v[200:203], v191 offset:20480
	ds_read_b128 v[204:207], v191 offset:21504
	ds_read_b128 v[208:211], v191 offset:22528
	ds_read_b128 v[212:215], v191 offset:23552
	s_waitcnt vmcnt(8)
	s_waitcnt lgkmcnt(0)
	s_barrier
; #define PG8_STAGE(bufoff, gbase, voff) do { _Pragma("unroll") for (int _i = 0; _i < 2; ++_i) \
;         __builtin_amdgcn_global_load_lds((const unsigned*)((const char*)(gbase) + (voff)[_i]), (PG8_LAS unsigned*)(lds + (bufoff) + ldsw + _i * 8192), 16, 0, 0); } while (0)
; #define PG8_LDA(dst, b, h) do { _Pragma("unroll") for (int m = 0; m < 4; ++m) _Pragma("unroll") for (int k = 0; k < 2; ++k) dst[m][k] = *(const PG8_LAS bf16x8*)(lds + PG8_SA(b, h) + aoff + m * 2048 + k * 1024); } while (0)
; #define PG8_LDB(dst, b, h) do { _Pragma("unroll") for (int n = 0; n < 2; ++n) _Pragma("unroll") for (int k = 0; k < 2; ++k) dst[n][k] = *(const PG8_LAS bf16x8*)(lds + PG8_SB(b, h) + boff + n * 2048 + k * 1024); } while (0)
; #define PG8_MMA(ai, bj, At, Bt) do { __builtin_amdgcn_s_setprio(1); _Pragma("unroll") for (int m = 0; m < 4; ++m) _Pragma("unroll") for (int n = 0; n < 2; ++n) _Pragma("unroll") for (int k = 0; k < 2; ++k) \
;         acc[ai][bj][m][n] = mma16<F16>(Bt[n][k], At[m][k], acc[ai][bj][m][n]); __builtin_amdgcn_s_setprio(0); } while (0)
; #define PG8_WAIT_V(n) asm volatile("s_waitcnt vmcnt(" #n ")" ::: "memory")
; #define PG8_WAIT_L(n) asm volatile("s_waitcnt lgkmcnt(" #n ")" ::: "memory")
; #define PG8_BAR __builtin_amdgcn_s_barrier()
; #define PG8_SCHED __builtin_amdgcn_sched_barrier(0)
; template <class Epi, class Sched, bool ALIGN_EPI = false, bool SP2 = false, bool F16 = false>
; __device__ __forceinline__ void gemm_phase(PG8_LAS unsigned char* lds, const Gemm g, const Sched& S, const Epi& E, const int wid_in) {
;     ...
;             PG8_WAIT_V(8); PG8_WAIT_L(0); PG8_BAR; PG8_MMA(0, 0, At, B0); PG8_MMA(0, 1, At, B1); PG8_BAR; PG8_SCHED;
;             PG8_LDA(At, 0, 1); PG8_STAGE(PG8_SB(0, 0), b2, voffB); PG8_STAGE(PG8_SB(0, 1), b2 + hstep, voffB); PG8_STAGE(PG8_SA(0, 0), a2, voffA);
;             PG8_WAIT_V(8); PG8_WAIT_L(0); PG8_BAR; PG8_MMA(1, 0, At, B0); PG8_MMA(1, 1, At, B1); PG8_BAR; PG8_SCHED;
;             PG8_LDB(B0, 1, 0); PG8_LDB(B1, 1, 1); PG8_SCHED; PG8_LDA(At, 1, 0); PG8_STAGE(PG8_SA(0, 1), a2 + hstep, voffA);
	s_waitcnt lgkmcnt(0)
	v_mfma_f32_16x16x32_bf16 v[60:63], v[128:131], v[176:179], v[60:63]
	v_mfma_f32_16x16x32_bf16 v[56:59], v[136:139], v[176:179], v[56:59]
	v_mfma_f32_16x16x32_bf16 v[44:47], v[128:131], v[192:195], v[44:47]
	v_mfma_f32_16x16x32_bf16 v[40:43], v[136:139], v[192:195], v[40:43]
	v_mfma_f32_16x16x32_bf16 v[28:31], v[128:131], v[200:203], v[28:31]
	v_mfma_f32_16x16x32_bf16 v[24:27], v[136:139], v[200:203], v[24:27]
	v_mfma_f32_16x16x32_bf16 v[12:15], v[128:131], v[208:211], v[12:15]
	v_mfma_f32_16x16x32_bf16 v[8:11], v[136:139], v[208:211], v[8:11]
	v_mfma_f32_16x16x32_bf16 v[60:63], v[132:135], v[180:183], v[60:63]
	v_mfma_f32_16x16x32_bf16 v[56:59], v[140:143], v[180:183], v[56:59]
	v_mfma_f32_16x16x32_bf16 v[44:47], v[132:135], v[196:199], v[44:47]
	v_mfma_f32_16x16x32_bf16 v[40:43], v[140:143], v[196:199], v[40:43]
	v_mfma_f32_16x16x32_bf16 v[28:31], v[132:135], v[204:207], v[28:31]
	v_mfma_f32_16x16x32_bf16 v[24:27], v[140:143], v[204:207], v[24:27]
	v_mfma_f32_16x16x32_bf16 v[12:15], v[132:135], v[212:215], v[12:15]
	v_mfma_f32_16x16x32_bf16 v[8:11], v[140:143], v[212:215], v[8:11]
	v_mfma_f32_16x16x32_bf16 v[52:55], v[144:147], v[176:179], v[52:55]
	v_mfma_f32_16x16x32_bf16 v[48:51], v[168:171], v[176:179], v[48:51]
	v_mfma_f32_16x16x32_bf16 v[36:39], v[144:147], v[192:195], v[36:39]
	v_mfma_f32_16x16x32_bf16 v[32:35], v[168:171], v[192:195], v[32:35]
	v_mfma_f32_16x16x32_bf16 v[20:23], v[144:147], v[200:203], v[20:23]
	v_mfma_f32_16x16x32_bf16 v[16:19], v[168:171], v[200:203], v[16:19]
	v_mfma_f32_16x16x32_bf16 v[4:7], v[144:147], v[208:211], v[4:7]
	v_mfma_f32_16x16x32_bf16 v[0:3], v[168:171], v[208:211], v[0:3]
	v_mfma_f32_16x16x32_bf16 v[52:55], v[148:151], v[180:183], v[52:55]
	v_mfma_f32_16x16x32_bf16 v[48:51], v[172:175], v[180:183], v[48:51]
	v_mfma_f32_16x16x32_bf16 v[36:39], v[148:151], v[196:199], v[36:39]
	v_mfma_f32_16x16x32_bf16 v[32:35], v[172:175], v[196:199], v[32:35]
	v_mfma_f32_16x16x32_bf16 v[20:23], v[148:151], v[204:207], v[20:23]
	v_mfma_f32_16x16x32_bf16 v[16:19], v[172:175], v[204:207], v[16:19]
	v_mfma_f32_16x16x32_bf16 v[4:7], v[148:151], v[212:215], v[4:7]
	v_mfma_f32_16x16x32_bf16 v[0:3], v[172:175], v[212:215], v[0:3]
	s_barrier
	s_add_i32 s63, 0, 0x18000
	s_add_i32 s64, 0, 0x1c000
	v_add_u32_e32 v140, s63, v188
	v_add_u32_e32 v172, s64, v188
	s_add_u32 s48, s48, 0x40000
	s_addc_u32 s49, s49, 0
	s_mov_b32 m0, s52
	v_lshl_add_u64 v[222:223], s[48:49], 0, v[152:153]
	global_load_lds_dwordx4 v[222:223], off
	v_lshl_add_u64 v[222:223], s[48:49], 0, v[156:157]
	s_mov_b32 m0, s53
	s_nop 0
	global_load_lds_dwordx4 v[222:223], off
	ds_read_b128 v[128:131], v140
	ds_read_b128 v[132:135], v140 offset:1024
	ds_read_b128 v[136:139], v140 offset:2048
	ds_read_b128 v[140:143], v140 offset:3072
	ds_read_b128 v[144:147], v172
	ds_read_b128 v[148:151], v172 offset:1024
	ds_read_b128 v[168:171], v172 offset:2048
	ds_read_b128 v[172:175], v172 offset:3072
	ds_read_b128 v[176:179], v191 offset:32768
	ds_read_b128 v[180:183], v191 offset:33792
	ds_read_b128 v[192:195], v191 offset:34816
	ds_read_b128 v[196:199], v191 offset:35840
	ds_read_b128 v[200:203], v191 offset:36864
	ds_read_b128 v[204:207], v191 offset:37888
	ds_read_b128 v[208:211], v191 offset:38912
	ds_read_b128 v[212:215], v191 offset:39936
	s_waitcnt vmcnt(8)
	s_waitcnt lgkmcnt(0)
	s_barrier
	s_waitcnt lgkmcnt(0)
	v_mfma_f32_16x16x32_bf16 v[124:127], v[128:131], v[176:179], v[124:127]
	v_mfma_f32_16x16x32_bf16 v[120:123], v[136:139], v[176:179], v[120:123]
	v_mfma_f32_16x16x32_bf16 v[108:111], v[128:131], v[192:195], v[108:111]
	v_mfma_f32_16x16x32_bf16 v[104:107], v[136:139], v[192:195], v[104:107]
	v_mfma_f32_16x16x32_bf16 v[92:95], v[128:131], v[200:203], v[92:95]
	v_mfma_f32_16x16x32_bf16 v[88:91], v[136:139], v[200:203], v[88:91]
	v_mfma_f32_16x16x32_bf16 v[76:79], v[128:131], v[208:211], v[76:79]
	v_mfma_f32_16x16x32_bf16 v[72:75], v[136:139], v[208:211], v[72:75]
	v_mfma_f32_16x16x32_bf16 v[124:127], v[132:135], v[180:183], v[124:127]
	v_mfma_f32_16x16x32_bf16 v[120:123], v[140:143], v[180:183], v[120:123]
	v_mfma_f32_16x16x32_bf16 v[108:111], v[132:135], v[196:199], v[108:111]
	v_mfma_f32_16x16x32_bf16 v[104:107], v[140:143], v[196:199], v[104:107]
	v_mfma_f32_16x16x32_bf16 v[92:95], v[132:135], v[204:207], v[92:95]
	v_mfma_f32_16x16x32_bf16 v[88:91], v[140:143], v[204:207], v[88:91]
	v_mfma_f32_16x16x32_bf16 v[76:79], v[132:135], v[212:215], v[76:79]
	v_mfma_f32_16x16x32_bf16 v[72:75], v[140:143], v[212:215], v[72:75]
	v_mfma_f32_16x16x32_bf16 v[116:119], v[144:147], v[176:179], v[116:119]
	v_mfma_f32_16x16x32_bf16 v[112:115], v[168:171], v[176:179], v[112:115]
	v_mfma_f32_16x16x32_bf16 v[100:103], v[144:147], v[192:195], v[100:103]
	v_mfma_f32_16x16x32_bf16 v[96:99], v[168:171], v[192:195], v[96:99]
	v_mfma_f32_16x16x32_bf16 v[84:87], v[144:147], v[200:203], v[84:87]
	v_mfma_f32_16x16x32_bf16 v[80:83], v[168:171], v[200:203], v[80:83]
	v_mfma_f32_16x16x32_bf16 v[68:71], v[144:147], v[208:211], v[68:71]
	v_mfma_f32_16x16x32_bf16 v[64:67], v[168:171], v[208:211], v[64:67]
	v_mfma_f32_16x16x32_bf16 v[116:119], v[148:151], v[180:183], v[116:119]
	v_mfma_f32_16x16x32_bf16 v[112:115], v[172:175], v[180:183], v[112:115]
	v_mfma_f32_16x16x32_bf16 v[100:103], v[148:151], v[196:199], v[100:103]
	v_mfma_f32_16x16x32_bf16 v[96:99], v[172:175], v[196:199], v[96:99]
	v_mfma_f32_16x16x32_bf16 v[84:87], v[148:151], v[204:207], v[84:87]
	v_mfma_f32_16x16x32_bf16 v[80:83], v[172:175], v[204:207], v[80:83]
	v_mfma_f32_16x16x32_bf16 v[68:71], v[148:151], v[212:215], v[68:71]
	v_mfma_f32_16x16x32_bf16 v[64:67], v[172:175], v[212:215], v[64:67]
	s_barrier
; #define PG8_STAGE(bufoff, gbase, voff) do { _Pragma("unroll") for (int _i = 0; _i < 2; ++_i) \
;         __builtin_amdgcn_global_load_lds((const unsigned*)((const char*)(gbase) + (voff)[_i]), (PG8_LAS unsigned*)(lds + (bufoff) + ldsw + _i * 8192), 16, 0, 0); } while (0)
; #define PG8_LDA(dst, b, h) do { _Pragma("unroll") for (int m = 0; m < 4; ++m) _Pragma("unroll") for (int k = 0; k < 2; ++k) dst[m][k] = *(const PG8_LAS bf16x8*)(lds + PG8_SA(b, h) + aoff + m * 2048 + k * 1024); } while (0)
; #define PG8_MMA(ai, bj, At, Bt) do { __builtin_amdgcn_s_setprio(1); _Pragma("unroll") for (int m = 0; m < 4; ++m) _Pragma("unroll") for (int n = 0; n < 2; ++n) _Pragma("unroll") for (int k = 0; k < 2; ++k) \
;         acc[ai][bj][m][n] = mma16<F16>(Bt[n][k], At[m][k], acc[ai][bj][m][n]); __builtin_amdgcn_s_setprio(0); } while (0)
; #define PG8_WAIT_V(n) asm volatile("s_waitcnt vmcnt(" #n ")" ::: "memory")
; #define PG8_WAIT_L(n) asm volatile("s_waitcnt lgkmcnt(" #n ")" ::: "memory")
; #define PG8_BAR __builtin_amdgcn_s_barrier()
; #define PG8_SCHED __builtin_amdgcn_sched_barrier(0)
; template <class Epi, class Sched, bool ALIGN_EPI = false, bool SP2 = false, bool F16 = false>
; __device__ __forceinline__ void gemm_phase(PG8_LAS unsigned char* lds, const Gemm g, const Sched& S, const Epi& E, const int wid_in) {
;     ...
;             PG8_LDA(At, 1, 1); PG8_STAGE(PG8_SB(1, 0), b3, voffB); PG8_STAGE(PG8_SB(1, 1), b3 + hstep, voffB); PG8_STAGE(PG8_SA(1, 0), a3, voffA);
;             PG8_WAIT_V(8); PG8_WAIT_L(0); PG8_BAR; PG8_MMA(1, 0, At, B0); PG8_MMA(1, 1, At, B1); PG8_BAR; PG8_SCHED;
;     ...
;         if constexpr (ALIGN_EPI) { if (wr == 0) PG8_BAR; }
	s_add_i32 s48, s63, s68
	v_lshl_add_u64 v[184:185], v[184:185], 0, s[22:23]
	s_mov_b32 m0, s48
	s_nop 0
	global_load_lds_dwordx4 v[184:185], off
	s_add_i32 m0, s48, 0x2000
	s_add_u32 s46, s46, 0x40080
	v_lshl_add_u64 v[184:185], v[216:217], 0, s[22:23]
	s_addc_u32 s47, s47, 0
	s_add_i32 s48, s64, s68
	global_load_lds_dwordx4 v[184:185], off
	v_lshl_add_u64 v[184:185], s[46:47], 0, v[154:155]
	s_mov_b32 m0, s48
	s_nop 0
	global_load_lds_dwordx4 v[184:185], off
	v_lshl_add_u64 v[184:185], s[46:47], 0, v[158:159]
	s_add_i32 m0, s48, 0x2000
	s_nop 0
	global_load_lds_dwordx4 v[184:185], off
	v_lshl_add_u64 v[184:185], v[218:219], 0, s[22:23]
	s_mov_b32 m0, s75
	s_nop 0
	global_load_lds_dwordx4 v[184:185], off
	v_lshl_add_u64 v[184:185], v[220:221], 0, s[22:23]
	s_mov_b32 m0, s54
	s_nop 0
	global_load_lds_dwordx4 v[184:185], off
	ds_read_b128 v[176:179], v191 offset:49152
	ds_read_b128 v[180:183], v191 offset:50176
	ds_read_b128 v[192:195], v191 offset:51200
	ds_read_b128 v[196:199], v191 offset:52224
	ds_read_b128 v[200:203], v191 offset:53248
	ds_read_b128 v[204:207], v191 offset:54272
	ds_read_b128 v[208:211], v191 offset:55296
	ds_read_b128 v[212:215], v191 offset:56320
	s_waitcnt vmcnt(8)
	s_waitcnt lgkmcnt(0)
	s_barrier
	s_waitcnt lgkmcnt(0)
	v_mfma_f32_16x16x32_bf16 v[60:63], v[128:131], v[176:179], v[60:63]
	v_mfma_f32_16x16x32_bf16 v[56:59], v[136:139], v[176:179], v[56:59]
	v_mfma_f32_16x16x32_bf16 v[44:47], v[128:131], v[192:195], v[44:47]
	v_mfma_f32_16x16x32_bf16 v[40:43], v[136:139], v[192:195], v[40:43]
	v_mfma_f32_16x16x32_bf16 v[28:31], v[128:131], v[200:203], v[28:31]
	v_mfma_f32_16x16x32_bf16 v[24:27], v[136:139], v[200:203], v[24:27]
	v_mfma_f32_16x16x32_bf16 v[12:15], v[128:131], v[208:211], v[12:15]
	v_mfma_f32_16x16x32_bf16 v[8:11], v[136:139], v[208:211], v[8:11]
	v_mfma_f32_16x16x32_bf16 v[60:63], v[132:135], v[180:183], v[60:63]
	v_mfma_f32_16x16x32_bf16 v[56:59], v[140:143], v[180:183], v[56:59]
	v_mfma_f32_16x16x32_bf16 v[44:47], v[132:135], v[196:199], v[44:47]
	v_mfma_f32_16x16x32_bf16 v[40:43], v[140:143], v[196:199], v[40:43]
	v_mfma_f32_16x16x32_bf16 v[28:31], v[132:135], v[204:207], v[28:31]
	v_mfma_f32_16x16x32_bf16 v[24:27], v[140:143], v[204:207], v[24:27]
	v_mfma_f32_16x16x32_bf16 v[12:15], v[132:135], v[212:215], v[12:15]
	v_mfma_f32_16x16x32_bf16 v[8:11], v[140:143], v[212:215], v[8:11]
	v_mfma_f32_16x16x32_bf16 v[52:55], v[144:147], v[176:179], v[52:55]
	v_mfma_f32_16x16x32_bf16 v[48:51], v[168:171], v[176:179], v[48:51]
	v_mfma_f32_16x16x32_bf16 v[36:39], v[144:147], v[192:195], v[36:39]
	v_mfma_f32_16x16x32_bf16 v[32:35], v[168:171], v[192:195], v[32:35]
	v_mfma_f32_16x16x32_bf16 v[20:23], v[144:147], v[200:203], v[20:23]
	v_mfma_f32_16x16x32_bf16 v[16:19], v[168:171], v[200:203], v[16:19]
	v_mfma_f32_16x16x32_bf16 v[4:7], v[144:147], v[208:211], v[4:7]
	v_mfma_f32_16x16x32_bf16 v[0:3], v[168:171], v[208:211], v[0:3]
	v_mfma_f32_16x16x32_bf16 v[52:55], v[148:151], v[180:183], v[52:55]
	v_mfma_f32_16x16x32_bf16 v[48:51], v[172:175], v[180:183], v[48:51]
	v_mfma_f32_16x16x32_bf16 v[36:39], v[148:151], v[196:199], v[36:39]
	v_mfma_f32_16x16x32_bf16 v[32:35], v[172:175], v[196:199], v[32:35]
	v_mfma_f32_16x16x32_bf16 v[20:23], v[148:151], v[204:207], v[20:23]
	v_mfma_f32_16x16x32_bf16 v[16:19], v[172:175], v[204:207], v[16:19]
	v_mfma_f32_16x16x32_bf16 v[4:7], v[148:151], v[212:215], v[4:7]
	v_mfma_f32_16x16x32_bf16 v[0:3], v[172:175], v[212:215], v[0:3]
	s_barrier
	s_add_i32 s43, s43, 2
	s_add_u32 s44, s44, 0x100
	s_addc_u32 s45, s45, 0
	s_add_u32 s37, s37, 0x100
	s_addc_u32 s42, s42, 0
	s_cmp_gt_u32 s43, 13
	s_cbranch_scc0 .LBB0_508
	s_and_b64 vcc, exec, s[16:17]
	s_cbranch_vccz .LBB0_511
	s_barrier

; #define PG8_STAGE(bufoff, gbase, voff) do { _Pragma("unroll") for (int _i = 0; _i < 2; ++_i) \
;         __builtin_amdgcn_global_load_lds((const unsigned*)((const char*)(gbase) + (voff)[_i]), (PG8_LAS unsigned*)(lds + (bufoff) + ldsw + _i * 8192), 16, 0, 0); } while (0)
; #define PG8_LDA(dst, b, h) do { _Pragma("unroll") for (int m = 0; m < 4; ++m) _Pragma("unroll") for (int k = 0; k < 2; ++k) dst[m][k] = *(const PG8_LAS bf16x8*)(lds + PG8_SA(b, h) + aoff + m * 2048 + k * 1024); } while (0)
; #define PG8_LDB(dst, b, h) do { _Pragma("unroll") for (int n = 0; n < 2; ++n) _Pragma("unroll") for (int k = 0; k < 2; ++k) dst[n][k] = *(const PG8_LAS bf16x8*)(lds + PG8_SB(b, h) + boff + n * 2048 + k * 1024); } while (0)
; #define PG8_MMA(ai, bj, At, Bt) do { __builtin_amdgcn_s_setprio(1); _Pragma("unroll") for (int m = 0; m < 4; ++m) _Pragma("unroll") for (int n = 0; n < 2; ++n) _Pragma("unroll") for (int k = 0; k < 2; ++k) \
;         acc[ai][bj][m][n] = mma16<F16>(Bt[n][k], At[m][k], acc[ai][bj][m][n]); __builtin_amdgcn_s_setprio(0); } while (0)
; #define PG8_WAIT_V(n) asm volatile("s_waitcnt vmcnt(" #n ")" ::: "memory")
; #define PG8_WAIT_L(n) asm volatile("s_waitcnt lgkmcnt(" #n ")" ::: "memory")
; #define PG8_BAR __builtin_amdgcn_s_barrier()
; #define PG8_SCHED __builtin_amdgcn_sched_barrier(0)
; template <class Epi, class Sched, bool ALIGN_EPI = false, bool SP2 = false, bool F16 = false>
; __device__ __forceinline__ void gemm_phase(PG8_LAS unsigned char* lds, const Gemm g, const Sched& S, const Epi& E, const int wid_in) {
;     ...
;             PG8_LDB(B0, 0, 0); PG8_LDB(B1, 0, 1); PG8_SCHED; PG8_LDA(At, 0, 0); PG8_STAGE(PG8_SA(1, 1), a1 + hstep, voffA);
;             PG8_WAIT_V(8); PG8_WAIT_L(0); PG8_BAR; PG8_MMA(0, 0, At, B0); PG8_MMA(0, 1, At, B1); PG8_BAR; PG8_SCHED;
;             PG8_LDA(At, 0, 1); PG8_STAGE(PG8_SB(0, 0), b2, voffB); PG8_STAGE(PG8_SB(0, 1), b2 + hstep, voffB); PG8_STAGE(PG8_SA(0, 0), a2, voffA);
.LBB0_585:
	ds_read_b128 v[0:3], v193
	ds_read_b128 v[4:7], v193 offset:1024
	ds_read_b128 v[136:139], v193 offset:2048
	ds_read_b128 v[140:143], v193 offset:3072
	ds_read_b128 v[144:147], v194
	ds_read_b128 v[148:151], v194 offset:1024
	ds_read_b128 v[152:155], v194 offset:2048
	ds_read_b128 v[156:159], v194 offset:3072
	s_add_u32 s36, s34, 0xfffc0080
	s_addc_u32 s37, s35, -1
	s_cmp_eq_u32 s65, 12
	s_cselect_b32 s45, s23, s37
	s_cselect_b32 s44, s31, s36
	s_cselect_b32 s37, s21, s64
	s_cselect_b32 s36, s42, s43
	v_lshl_add_u64 v[188:189], s[34:35], 0, v[168:169]
	s_add_i32 m0, s74, 0xc000
	ds_read_b128 v[176:179], v195
	ds_read_b128 v[180:183], v195 offset:1024
	ds_read_b128 v[184:187], v195 offset:2048
	ds_read_b128 v[198:201], v195 offset:3072
	ds_read_b128 v[202:205], v195 offset:4096
	ds_read_b128 v[206:209], v195 offset:5120
	ds_read_b128 v[210:213], v195 offset:6144
	ds_read_b128 v[214:217], v195 offset:7168
	global_load_lds_dwordx4 v[188:189], off
	v_lshl_add_u64 v[188:189], s[34:35], 0, v[170:171]
	s_add_i32 m0, s74, 0xe000
	s_nop 0
	global_load_lds_dwordx4 v[188:189], off
	s_waitcnt vmcnt(8)
	s_waitcnt lgkmcnt(0)
	s_barrier
	s_waitcnt lgkmcnt(0)
	v_mfma_f32_16x16x32_f16 v[132:135], v[0:3], v[176:179], v[132:135]
	v_mfma_f32_16x16x32_f16 v[128:131], v[136:139], v[176:179], v[128:131]
	v_mfma_f32_16x16x32_f16 v[116:119], v[0:3], v[184:187], v[116:119]
	v_mfma_f32_16x16x32_f16 v[112:115], v[136:139], v[184:187], v[112:115]
	v_mfma_f32_16x16x32_f16 v[100:103], v[0:3], v[202:205], v[100:103]
	v_mfma_f32_16x16x32_f16 v[96:99], v[136:139], v[202:205], v[96:99]
	v_mfma_f32_16x16x32_f16 v[84:87], v[0:3], v[210:213], v[84:87]
	v_mfma_f32_16x16x32_f16 v[80:83], v[136:139], v[210:213], v[80:83]
	v_mfma_f32_16x16x32_f16 v[132:135], v[4:7], v[180:183], v[132:135]
	v_mfma_f32_16x16x32_f16 v[128:131], v[140:143], v[180:183], v[128:131]
	v_mfma_f32_16x16x32_f16 v[116:119], v[4:7], v[198:201], v[116:119]
	v_mfma_f32_16x16x32_f16 v[112:115], v[140:143], v[198:201], v[112:115]
	v_mfma_f32_16x16x32_f16 v[100:103], v[4:7], v[206:209], v[100:103]
	v_mfma_f32_16x16x32_f16 v[96:99], v[140:143], v[206:209], v[96:99]
	v_mfma_f32_16x16x32_f16 v[84:87], v[4:7], v[214:217], v[84:87]
	v_mfma_f32_16x16x32_f16 v[80:83], v[140:143], v[214:217], v[80:83]
	v_mfma_f32_16x16x32_f16 v[124:127], v[144:147], v[176:179], v[124:127]
	v_mfma_f32_16x16x32_f16 v[120:123], v[152:155], v[176:179], v[120:123]
	v_mfma_f32_16x16x32_f16 v[108:111], v[144:147], v[184:187], v[108:111]
	v_mfma_f32_16x16x32_f16 v[104:107], v[152:155], v[184:187], v[104:107]
	v_mfma_f32_16x16x32_f16 v[92:95], v[144:147], v[202:205], v[92:95]
	v_mfma_f32_16x16x32_f16 v[88:91], v[152:155], v[202:205], v[88:91]
	v_mfma_f32_16x16x32_f16 v[76:79], v[144:147], v[210:213], v[76:79]
	v_mfma_f32_16x16x32_f16 v[72:75], v[152:155], v[210:213], v[72:75]
	v_mfma_f32_16x16x32_f16 v[124:127], v[148:151], v[180:183], v[124:127]
	v_mfma_f32_16x16x32_f16 v[120:123], v[156:159], v[180:183], v[120:123]
	v_mfma_f32_16x16x32_f16 v[108:111], v[148:151], v[198:201], v[108:111]
	v_mfma_f32_16x16x32_f16 v[104:107], v[156:159], v[198:201], v[104:107]
	v_mfma_f32_16x16x32_f16 v[92:95], v[148:151], v[206:209], v[92:95]
	v_mfma_f32_16x16x32_f16 v[88:91], v[156:159], v[206:209], v[88:91]
	v_mfma_f32_16x16x32_f16 v[76:79], v[148:151], v[214:217], v[76:79]
	v_mfma_f32_16x16x32_f16 v[72:75], v[156:159], v[214:217], v[72:75]
	s_barrier
	s_add_i32 s66, s61, s68
	v_lshl_add_u64 v[188:189], s[36:37], 0, v[162:163]
	s_mov_b32 m0, s66
	s_nop 0
	global_load_lds_dwordx4 v[188:189], off
	s_add_i32 m0, s66, 0x2000
	s_add_u32 s66, s36, 0x40000
	v_lshl_add_u64 v[218:219], s[36:37], 0, v[166:167]
	s_addc_u32 s67, s37, 0
	s_add_i32 s76, s62, s68
	global_load_lds_dwordx4 v[218:219], off
	v_lshl_add_u64 v[220:221], s[66:67], 0, v[162:163]
	s_mov_b32 m0, s76
	v_lshl_add_u64 v[222:223], s[44:45], 0, v[164:165]
	global_load_lds_dwordx4 v[220:221], off
	v_lshl_add_u64 v[220:221], s[66:67], 0, v[166:167]
	s_add_i32 m0, s76, 0x2000
	s_nop 0
	global_load_lds_dwordx4 v[220:221], off
	v_lshl_add_u64 v[220:221], s[44:45], 0, v[160:161]
	s_mov_b32 m0, s74
	s_nop 0
	global_load_lds_dwordx4 v[220:221], off
	s_mov_b32 m0, s29
	s_nop 0
	global_load_lds_dwordx4 v[222:223], off
	ds_read_b128 v[176:179], v195 offset:16384
	ds_read_b128 v[180:183], v195 offset:17408
	ds_read_b128 v[184:187], v195 offset:18432
	ds_read_b128 v[198:201], v195 offset:19456
	ds_read_b128 v[202:205], v195 offset:20480
	ds_read_b128 v[206:209], v195 offset:21504
	ds_read_b128 v[210:213], v195 offset:22528
	ds_read_b128 v[214:217], v195 offset:23552
	s_waitcnt vmcnt(8)
	s_waitcnt lgkmcnt(0)
	s_barrier
; #define PG8_STAGE(bufoff, gbase, voff) do { _Pragma("unroll") for (int _i = 0; _i < 2; ++_i) \
;         __builtin_amdgcn_global_load_lds((const unsigned*)((const char*)(gbase) + (voff)[_i]), (PG8_LAS unsigned*)(lds + (bufoff) + ldsw + _i * 8192), 16, 0, 0); } while (0)
; #define PG8_LDA(dst, b, h) do { _Pragma("unroll") for (int m = 0; m < 4; ++m) _Pragma("unroll") for (int k = 0; k < 2; ++k) dst[m][k] = *(const PG8_LAS bf16x8*)(lds + PG8_SA(b, h) + aoff + m * 2048 + k * 1024); } while (0)
; #define PG8_LDB(dst, b, h) do { _Pragma("unroll") for (int n = 0; n < 2; ++n) _Pragma("unroll") for (int k = 0; k < 2; ++k) dst[n][k] = *(const PG8_LAS bf16x8*)(lds + PG8_SB(b, h) + boff + n * 2048 + k * 1024); } while (0)
; #define PG8_MMA(ai, bj, At, Bt) do { __builtin_amdgcn_s_setprio(1); _Pragma("unroll") for (int m = 0; m < 4; ++m) _Pragma("unroll") for (int n = 0; n < 2; ++n) _Pragma("unroll") for (int k = 0; k < 2; ++k) \
;         acc[ai][bj][m][n] = mma16<F16>(Bt[n][k], At[m][k], acc[ai][bj][m][n]); __builtin_amdgcn_s_setprio(0); } while (0)
; #define PG8_WAIT_V(n) asm volatile("s_waitcnt vmcnt(" #n ")" ::: "memory")
; #define PG8_WAIT_L(n) asm volatile("s_waitcnt lgkmcnt(" #n ")" ::: "memory")
; #define PG8_BAR __builtin_amdgcn_s_barrier()
; #define PG8_SCHED __builtin_amdgcn_sched_barrier(0)
; template <class Epi, class Sched, bool ALIGN_EPI = false, bool SP2 = false, bool F16 = false>
; __device__ __forceinline__ void gemm_phase(PG8_LAS unsigned char* lds, const Gemm g, const Sched& S, const Epi& E, const int wid_in) {
;     ...
;             PG8_WAIT_V(8); PG8_WAIT_L(0); PG8_BAR; PG8_MMA(0, 0, At, B0); PG8_MMA(0, 1, At, B1); PG8_BAR; PG8_SCHED;
;             PG8_LDA(At, 0, 1); PG8_STAGE(PG8_SB(0, 0), b2, voffB); PG8_STAGE(PG8_SB(0, 1), b2 + hstep, voffB); PG8_STAGE(PG8_SA(0, 0), a2, voffA);
;             PG8_WAIT_V(8); PG8_WAIT_L(0); PG8_BAR; PG8_MMA(1, 0, At, B0); PG8_MMA(1, 1, At, B1); PG8_BAR; PG8_SCHED;
;             PG8_LDB(B0, 1, 0); PG8_LDB(B1, 1, 1); PG8_SCHED; PG8_LDA(At, 1, 0); PG8_STAGE(PG8_SA(0, 1), a2 + hstep, voffA);
	s_waitcnt lgkmcnt(0)
	v_mfma_f32_16x16x32_f16 v[68:71], v[0:3], v[176:179], v[68:71]
	v_mfma_f32_16x16x32_f16 v[64:67], v[136:139], v[176:179], v[64:67]
	v_mfma_f32_16x16x32_f16 v[52:55], v[0:3], v[184:187], v[52:55]
	v_mfma_f32_16x16x32_f16 v[48:51], v[136:139], v[184:187], v[48:51]
	v_mfma_f32_16x16x32_f16 v[36:39], v[0:3], v[202:205], v[36:39]
	v_mfma_f32_16x16x32_f16 v[32:35], v[136:139], v[202:205], v[32:35]
	v_mfma_f32_16x16x32_f16 v[0:3], v[0:3], v[210:213], v[20:23]
	v_mfma_f32_16x16x32_f16 v[68:71], v[4:7], v[180:183], v[68:71]
	v_mfma_f32_16x16x32_f16 v[64:67], v[140:143], v[180:183], v[64:67]
	v_mfma_f32_16x16x32_f16 v[52:55], v[4:7], v[198:201], v[52:55]
	v_mfma_f32_16x16x32_f16 v[48:51], v[140:143], v[198:201], v[48:51]
	v_mfma_f32_16x16x32_f16 v[36:39], v[4:7], v[206:209], v[36:39]
	v_mfma_f32_16x16x32_f16 v[32:35], v[140:143], v[206:209], v[32:35]
	v_mfma_f32_16x16x32_f16 v[0:3], v[4:7], v[214:217], v[0:3]
	v_mfma_f32_16x16x32_f16 v[4:7], v[136:139], v[210:213], v[16:19]
	v_mfma_f32_16x16x32_f16 v[4:7], v[140:143], v[214:217], v[4:7]
	v_mfma_f32_16x16x32_f16 v[16:19], v[144:147], v[176:179], v[60:63]
	v_mfma_f32_16x16x32_f16 v[60:63], v[148:151], v[180:183], v[16:19]
	v_mfma_f32_16x16x32_f16 v[16:19], v[152:155], v[176:179], v[56:59]
	v_mfma_f32_16x16x32_f16 v[56:59], v[156:159], v[180:183], v[16:19]
	v_mfma_f32_16x16x32_f16 v[16:19], v[144:147], v[184:187], v[44:47]
	v_mfma_f32_16x16x32_f16 v[44:47], v[148:151], v[198:201], v[16:19]
	v_mfma_f32_16x16x32_f16 v[16:19], v[152:155], v[184:187], v[40:43]
	v_mfma_f32_16x16x32_f16 v[40:43], v[156:159], v[198:201], v[16:19]
	v_mfma_f32_16x16x32_f16 v[16:19], v[144:147], v[202:205], v[28:31]
	v_mfma_f32_16x16x32_f16 v[28:31], v[148:151], v[206:209], v[16:19]
	v_mfma_f32_16x16x32_f16 v[16:19], v[152:155], v[202:205], v[24:27]
	v_mfma_f32_16x16x32_f16 v[12:15], v[144:147], v[210:213], v[12:15]
	v_mfma_f32_16x16x32_f16 v[8:11], v[152:155], v[210:213], v[8:11]
	v_mfma_f32_16x16x32_f16 v[24:27], v[156:159], v[206:209], v[16:19]
	v_mfma_f32_16x16x32_f16 v[12:15], v[148:151], v[214:217], v[12:15]
	v_mfma_f32_16x16x32_f16 v[8:11], v[156:159], v[214:217], v[8:11]
	s_barrier
	s_add_i32 s66, 0, 0x18000
	s_add_i32 s67, 0, 0x1c000
	v_add_u32_e32 v140, s66, v192
	v_add_u32_e32 v156, s67, v192
	s_add_u32 s44, s44, 0x40000
	s_addc_u32 s45, s45, 0
	s_mov_b32 m0, s49
	v_lshl_add_u64 v[224:225], s[44:45], 0, v[160:161]
	global_load_lds_dwordx4 v[224:225], off
	v_lshl_add_u64 v[224:225], s[44:45], 0, v[164:165]
	s_mov_b32 m0, s50
	s_nop 0
	global_load_lds_dwordx4 v[224:225], off
	ds_read_b128 v[16:19], v140
	ds_read_b128 v[20:23], v140 offset:1024
	ds_read_b128 v[136:139], v140 offset:2048
	ds_read_b128 v[140:143], v140 offset:3072
	ds_read_b128 v[144:147], v156
	ds_read_b128 v[148:151], v156 offset:1024
	ds_read_b128 v[152:155], v156 offset:2048
	ds_read_b128 v[156:159], v156 offset:3072
	ds_read_b128 v[176:179], v195 offset:32768
	ds_read_b128 v[180:183], v195 offset:33792
	ds_read_b128 v[184:187], v195 offset:34816
	ds_read_b128 v[198:201], v195 offset:35840
	ds_read_b128 v[202:205], v195 offset:36864
	ds_read_b128 v[206:209], v195 offset:37888
	ds_read_b128 v[210:213], v195 offset:38912
	ds_read_b128 v[214:217], v195 offset:39936
	s_waitcnt vmcnt(8)
	s_waitcnt lgkmcnt(0)
	s_barrier
	s_waitcnt lgkmcnt(0)
	v_mfma_f32_16x16x32_f16 v[132:135], v[16:19], v[176:179], v[132:135]
	v_mfma_f32_16x16x32_f16 v[128:131], v[136:139], v[176:179], v[128:131]
	v_mfma_f32_16x16x32_f16 v[116:119], v[16:19], v[184:187], v[116:119]
	v_mfma_f32_16x16x32_f16 v[112:115], v[136:139], v[184:187], v[112:115]
	v_mfma_f32_16x16x32_f16 v[100:103], v[16:19], v[202:205], v[100:103]
	v_mfma_f32_16x16x32_f16 v[96:99], v[136:139], v[202:205], v[96:99]
	v_mfma_f32_16x16x32_f16 v[84:87], v[16:19], v[210:213], v[84:87]
	v_mfma_f32_16x16x32_f16 v[80:83], v[136:139], v[210:213], v[80:83]
	v_mfma_f32_16x16x32_f16 v[132:135], v[20:23], v[180:183], v[132:135]
	v_mfma_f32_16x16x32_f16 v[128:131], v[140:143], v[180:183], v[128:131]
	v_mfma_f32_16x16x32_f16 v[116:119], v[20:23], v[198:201], v[116:119]
	v_mfma_f32_16x16x32_f16 v[112:115], v[140:143], v[198:201], v[112:115]
	v_mfma_f32_16x16x32_f16 v[100:103], v[20:23], v[206:209], v[100:103]
	v_mfma_f32_16x16x32_f16 v[96:99], v[140:143], v[206:209], v[96:99]
	v_mfma_f32_16x16x32_f16 v[84:87], v[20:23], v[214:217], v[84:87]
	v_mfma_f32_16x16x32_f16 v[80:83], v[140:143], v[214:217], v[80:83]
	v_mfma_f32_16x16x32_f16 v[124:127], v[144:147], v[176:179], v[124:127]
	v_mfma_f32_16x16x32_f16 v[120:123], v[152:155], v[176:179], v[120:123]
	v_mfma_f32_16x16x32_f16 v[108:111], v[144:147], v[184:187], v[108:111]
	v_mfma_f32_16x16x32_f16 v[104:107], v[152:155], v[184:187], v[104:107]
	v_mfma_f32_16x16x32_f16 v[92:95], v[144:147], v[202:205], v[92:95]
	v_mfma_f32_16x16x32_f16 v[88:91], v[152:155], v[202:205], v[88:91]
	v_mfma_f32_16x16x32_f16 v[76:79], v[144:147], v[210:213], v[76:79]
	v_mfma_f32_16x16x32_f16 v[72:75], v[152:155], v[210:213], v[72:75]
	v_mfma_f32_16x16x32_f16 v[124:127], v[148:151], v[180:183], v[124:127]
	v_mfma_f32_16x16x32_f16 v[120:123], v[156:159], v[180:183], v[120:123]
	v_mfma_f32_16x16x32_f16 v[108:111], v[148:151], v[198:201], v[108:111]
	v_mfma_f32_16x16x32_f16 v[104:107], v[156:159], v[198:201], v[104:107]
	v_mfma_f32_16x16x32_f16 v[92:95], v[148:151], v[206:209], v[92:95]
	v_mfma_f32_16x16x32_f16 v[88:91], v[156:159], v[206:209], v[88:91]
	v_mfma_f32_16x16x32_f16 v[76:79], v[148:151], v[214:217], v[76:79]
	v_mfma_f32_16x16x32_f16 v[72:75], v[156:159], v[214:217], v[72:75]
	s_barrier
; #define PG8_STAGE(bufoff, gbase, voff) do { _Pragma("unroll") for (int _i = 0; _i < 2; ++_i) \
;         __builtin_amdgcn_global_load_lds((const unsigned*)((const char*)(gbase) + (voff)[_i]), (PG8_LAS unsigned*)(lds + (bufoff) + ldsw + _i * 8192), 16, 0, 0); } while (0)
; #define PG8_LDA(dst, b, h) do { _Pragma("unroll") for (int m = 0; m < 4; ++m) _Pragma("unroll") for (int k = 0; k < 2; ++k) dst[m][k] = *(const PG8_LAS bf16x8*)(lds + PG8_SA(b, h) + aoff + m * 2048 + k * 1024); } while (0)
; #define PG8_MMA(ai, bj, At, Bt) do { __builtin_amdgcn_s_setprio(1); _Pragma("unroll") for (int m = 0; m < 4; ++m) _Pragma("unroll") for (int n = 0; n < 2; ++n) _Pragma("unroll") for (int k = 0; k < 2; ++k) \
;         acc[ai][bj][m][n] = mma16<F16>(Bt[n][k], At[m][k], acc[ai][bj][m][n]); __builtin_amdgcn_s_setprio(0); } while (0)
; #define PG8_WAIT_V(n) asm volatile("s_waitcnt vmcnt(" #n ")" ::: "memory")
; #define PG8_WAIT_L(n) asm volatile("s_waitcnt lgkmcnt(" #n ")" ::: "memory")
; #define PG8_BAR __builtin_amdgcn_s_barrier()
; #define PG8_SCHED __builtin_amdgcn_sched_barrier(0)
; template <class Epi, class Sched, bool ALIGN_EPI = false, bool SP2 = false, bool F16 = false>
; __device__ __forceinline__ void gemm_phase(PG8_LAS unsigned char* lds, const Gemm g, const Sched& S, const Epi& E, const int wid_in) {
;     ...
;             PG8_LDA(At, 1, 1); PG8_STAGE(PG8_SB(1, 0), b3, voffB); PG8_STAGE(PG8_SB(1, 1), b3 + hstep, voffB); PG8_STAGE(PG8_SA(1, 0), a3, voffA);
;             PG8_WAIT_V(8); PG8_WAIT_L(0); PG8_BAR; PG8_MMA(1, 0, At, B0); PG8_MMA(1, 1, At, B1); PG8_BAR; PG8_SCHED;
;     ...
;         if constexpr (ALIGN_EPI) { if (wr == 0) PG8_BAR; }
	s_add_i32 s44, s66, s68
	v_lshl_add_u64 v[188:189], v[188:189], 0, s[18:19]
	s_mov_b32 m0, s44
	s_nop 0
	global_load_lds_dwordx4 v[188:189], off
	s_add_i32 m0, s44, 0x2000
	s_add_u32 s36, s36, 0x40080
	v_lshl_add_u64 v[188:189], v[218:219], 0, s[18:19]
	s_addc_u32 s37, s37, 0
	s_add_i32 s44, s67, s68
	global_load_lds_dwordx4 v[188:189], off
	v_lshl_add_u64 v[188:189], s[36:37], 0, v[162:163]
	s_mov_b32 m0, s44
	s_nop 0
	global_load_lds_dwordx4 v[188:189], off
	v_lshl_add_u64 v[188:189], s[36:37], 0, v[166:167]
	s_add_i32 m0, s44, 0x2000
	s_nop 0
	global_load_lds_dwordx4 v[188:189], off
	v_lshl_add_u64 v[188:189], v[220:221], 0, s[18:19]
	s_mov_b32 m0, s75
	s_nop 0
	global_load_lds_dwordx4 v[188:189], off
	v_lshl_add_u64 v[188:189], v[222:223], 0, s[18:19]
	s_mov_b32 m0, s53
	s_nop 0
	global_load_lds_dwordx4 v[188:189], off
	ds_read_b128 v[176:179], v195 offset:49152
	ds_read_b128 v[180:183], v195 offset:50176
	ds_read_b128 v[184:187], v195 offset:51200
	ds_read_b128 v[198:201], v195 offset:52224
	ds_read_b128 v[202:205], v195 offset:53248
	ds_read_b128 v[206:209], v195 offset:54272
	ds_read_b128 v[210:213], v195 offset:55296
	ds_read_b128 v[214:217], v195 offset:56320
	s_waitcnt vmcnt(8)
	s_waitcnt lgkmcnt(0)
	s_barrier
	s_waitcnt lgkmcnt(0)
	v_mfma_f32_16x16x32_f16 v[68:71], v[16:19], v[176:179], v[68:71]
	v_mfma_f32_16x16x32_f16 v[52:55], v[16:19], v[184:187], v[52:55]
	v_mfma_f32_16x16x32_f16 v[36:39], v[16:19], v[202:205], v[36:39]
	v_mfma_f32_16x16x32_f16 v[0:3], v[16:19], v[210:213], v[0:3]
	v_mfma_f32_16x16x32_f16 v[68:71], v[20:23], v[180:183], v[68:71]
	v_mfma_f32_16x16x32_f16 v[64:67], v[136:139], v[176:179], v[64:67]
	v_mfma_f32_16x16x32_f16 v[52:55], v[20:23], v[198:201], v[52:55]
	v_mfma_f32_16x16x32_f16 v[48:51], v[136:139], v[184:187], v[48:51]
	v_mfma_f32_16x16x32_f16 v[36:39], v[20:23], v[206:209], v[36:39]
	v_mfma_f32_16x16x32_f16 v[32:35], v[136:139], v[202:205], v[32:35]
	v_mfma_f32_16x16x32_f16 v[20:23], v[20:23], v[214:217], v[0:3]
	v_mfma_f32_16x16x32_f16 v[0:3], v[136:139], v[210:213], v[4:7]
	v_mfma_f32_16x16x32_f16 v[64:67], v[140:143], v[180:183], v[64:67]
	v_mfma_f32_16x16x32_f16 v[48:51], v[140:143], v[198:201], v[48:51]
	v_mfma_f32_16x16x32_f16 v[32:35], v[140:143], v[206:209], v[32:35]
	v_mfma_f32_16x16x32_f16 v[16:19], v[140:143], v[214:217], v[0:3]
	v_mfma_f32_16x16x32_f16 v[0:3], v[144:147], v[176:179], v[60:63]
	v_mfma_f32_16x16x32_f16 v[60:63], v[148:151], v[180:183], v[0:3]
	v_mfma_f32_16x16x32_f16 v[0:3], v[152:155], v[176:179], v[56:59]
	v_mfma_f32_16x16x32_f16 v[56:59], v[156:159], v[180:183], v[0:3]
	v_mfma_f32_16x16x32_f16 v[0:3], v[144:147], v[184:187], v[44:47]
	v_mfma_f32_16x16x32_f16 v[44:47], v[148:151], v[198:201], v[0:3]
	v_mfma_f32_16x16x32_f16 v[0:3], v[152:155], v[184:187], v[40:43]
	v_mfma_f32_16x16x32_f16 v[40:43], v[156:159], v[198:201], v[0:3]
	v_mfma_f32_16x16x32_f16 v[0:3], v[144:147], v[202:205], v[28:31]
	v_mfma_f32_16x16x32_f16 v[28:31], v[148:151], v[206:209], v[0:3]
	v_mfma_f32_16x16x32_f16 v[0:3], v[152:155], v[202:205], v[24:27]
	v_mfma_f32_16x16x32_f16 v[24:27], v[156:159], v[206:209], v[0:3]
	v_mfma_f32_16x16x32_f16 v[0:3], v[144:147], v[210:213], v[12:15]
	v_mfma_f32_16x16x32_f16 v[12:15], v[148:151], v[214:217], v[0:3]
	v_mfma_f32_16x16x32_f16 v[0:3], v[152:155], v[210:213], v[8:11]
	v_mfma_f32_16x16x32_f16 v[8:11], v[156:159], v[214:217], v[0:3]
	s_barrier
	s_add_i32 s65, s65, 2
	s_add_u32 s34, s34, 0x100
	s_addc_u32 s35, s35, 0
	s_add_u32 s43, s43, 0x100
	s_addc_u32 s64, s64, 0
	s_cmp_gt_u32 s65, 13
	s_cbranch_scc0 .LBB0_585
	s_and_b64 vcc, exec, s[16:17]
	s_cbranch_vccz .LBB0_588
	s_barrier

; #define PG8_STAGE(bufoff, gbase, voff) do { _Pragma("unroll") for (int _i = 0; _i < 2; ++_i) \
;         __builtin_amdgcn_global_load_lds((const unsigned*)((const char*)(gbase) + (voff)[_i]), (PG8_LAS unsigned*)(lds + (bufoff) + ldsw + _i * 8192), 16, 0, 0); } while (0)
; #define PG8_LDA(dst, b, h) do { _Pragma("unroll") for (int m = 0; m < 4; ++m) _Pragma("unroll") for (int k = 0; k < 2; ++k) dst[m][k] = *(const PG8_LAS bf16x8*)(lds + PG8_SA(b, h) + aoff + m * 2048 + k * 1024); } while (0)
; #define PG8_LDB(dst, b, h) do { _Pragma("unroll") for (int n = 0; n < 2; ++n) _Pragma("unroll") for (int k = 0; k < 2; ++k) dst[n][k] = *(const PG8_LAS bf16x8*)(lds + PG8_SB(b, h) + boff + n * 2048 + k * 1024); } while (0)
; #define PG8_MMA(ai, bj, At, Bt) do { __builtin_amdgcn_s_setprio(1); _Pragma("unroll") for (int m = 0; m < 4; ++m) _Pragma("unroll") for (int n = 0; n < 2; ++n) _Pragma("unroll") for (int k = 0; k < 2; ++k) \
;         acc[ai][bj][m][n] = mma16<F16>(Bt[n][k], At[m][k], acc[ai][bj][m][n]); __builtin_amdgcn_s_setprio(0); } while (0)
; #define PG8_BAR __builtin_amdgcn_s_barrier()
; template <class Epi, class Sched, bool ALIGN_EPI = false, bool SP2 = false, bool F16 = false>
; __device__ __forceinline__ void gemm_phase(PG8_LAS unsigned char* lds, const Gemm g, const Sched& S, const Epi& E, const int wid_in) {
;     ...
;         const bool has_next = S.next(ui + 1, nxt);
;         const char* nA = has_next ? (const char*)g.A + (size_t)nxt.pm * tstep : cA; const char* nB = has_next ? (const char*)g.Bt + (size_t)nxt.pn * tstep : cB;
;         for (int t = 0; t < nt; t += 2) {
;             const bool last = (t == nt - 2);
;             const char* a1 = cA + (size_t)(t + 1) * kstep;
;             const char* a2 = last ? nA : cA + (size_t)(t + 2) * kstep; const char* b2 = last ? nB : cB + (size_t)(t + 2) * kstep;
;             const char* a3 = a2 + kstep; const char* b3 = b2 + kstep;
;             if (last && has_next) S.a_ready(nxt);
;             if constexpr (SP2) {
;             PG8_LDB(B0, 0, 0); PG8_LDB(B1, 0, 1); PG8_SCHED; PG8_LDA(At, 0, 0); PG8_STAGE(PG8_SA(1, 1), a1 + hstep, voffA);
;             PG8_WAIT_V(8); PG8_WAIT_L(0); PG8_BAR; PG8_MMA(0, 0, At, B0); PG8_MMA(0, 1, At, B1); PG8_BAR; PG8_SCHED;
;             PG8_LDA(At, 0, 1); PG8_STAGE(PG8_SB(0, 0), b2, voffB); PG8_STAGE(PG8_SB(0, 1), b2 + hstep, voffB); PG8_STAGE(PG8_SA(0, 0), a2, voffA);
.LBB0_620:
	s_mov_b64 s[44:45], s[10:11]
	s_add_i32 s10, s30, s40
	s_mov_b64 s[36:37], s[12:13]
	s_mov_b32 s12, s62
	s_mov_b32 s13, s61
	s_and_b32 s61, s10, 3
	s_ashr_i32 s62, s10, 2
	s_and_b64 s[10:11], s[26:27], exec
	s_cselect_b32 s12, s62, s12
	ds_read_b128 v[0:3], v134
	ds_read_b128 v[4:7], v134 offset:1024
	ds_read_b128 v[8:11], v134 offset:2048
	ds_read_b128 v[12:15], v134 offset:3072
	ds_read_b128 v[16:19], v135
	ds_read_b128 v[20:23], v135 offset:1024
	ds_read_b128 v[24:27], v135 offset:2048
	ds_read_b128 v[28:31], v135 offset:3072
	s_cselect_b32 s10, s61, s13
	s_ashr_i32 s13, s12, 31
	s_lshl_b64 s[12:13], s[12:13], 17
	s_add_u32 s12, s43, s12
	s_addc_u32 s13, s46, s13
	s_and_b64 s[30:31], s[26:27], exec
	s_cselect_b32 s35, s13, s37
	s_cselect_b32 s34, s12, s36
	s_ashr_i32 s11, s10, 31
	s_lshl_b64 s[10:11], s[10:11], 17
	s_add_u32 s10, s41, s10
	s_addc_u32 s11, s42, s11
	s_and_b64 s[30:31], s[26:27], exec
	s_cselect_b32 s31, s11, s45
	s_cselect_b32 s30, s10, s44
	s_add_u32 s64, s36, 0x10080
	s_addc_u32 s65, s37, 0
	s_mov_b32 m0, s15
	v_lshl_add_u64 v[64:65], s[64:65], 0, v[130:131]
	ds_read_b128 v[32:35], v136
	ds_read_b128 v[36:39], v136 offset:1024
	ds_read_b128 v[40:43], v136 offset:2048
	ds_read_b128 v[44:47], v136 offset:3072
	ds_read_b128 v[48:51], v136 offset:4096
	ds_read_b128 v[52:55], v136 offset:5120
	ds_read_b128 v[56:59], v136 offset:6144
	ds_read_b128 v[60:63], v136 offset:7168
	global_load_lds_dwordx4 v[64:65], off
	v_lshl_add_u64 v[64:65], s[64:65], 0, v[128:129]
	s_mov_b32 m0, s50
	s_nop 0
	global_load_lds_dwordx4 v[64:65], off
	s_waitcnt vmcnt(8)
	s_waitcnt lgkmcnt(0)
	s_barrier
	s_waitcnt lgkmcnt(0)
	v_mfma_f32_16x16x32_bf16 v[64:67], v[0:3], v[32:35], 0
	v_mfma_f32_16x16x32_bf16 v[68:71], v[8:11], v[32:35], 0
	v_mfma_f32_16x16x32_bf16 v[72:75], v[0:3], v[40:43], 0
	v_mfma_f32_16x16x32_bf16 v[76:79], v[8:11], v[40:43], 0
	v_mfma_f32_16x16x32_bf16 v[80:83], v[0:3], v[48:51], 0
	v_mfma_f32_16x16x32_bf16 v[84:87], v[8:11], v[48:51], 0
	v_mfma_f32_16x16x32_bf16 v[88:91], v[0:3], v[56:59], 0
	v_mfma_f32_16x16x32_bf16 v[92:95], v[8:11], v[56:59], 0
	v_mfma_f32_16x16x32_bf16 v[64:67], v[4:7], v[36:39], v[64:67]
	v_mfma_f32_16x16x32_bf16 v[68:71], v[12:15], v[36:39], v[68:71]
	v_mfma_f32_16x16x32_bf16 v[72:75], v[4:7], v[44:47], v[72:75]
	v_mfma_f32_16x16x32_bf16 v[76:79], v[12:15], v[44:47], v[76:79]
	v_mfma_f32_16x16x32_bf16 v[80:83], v[4:7], v[52:55], v[80:83]
	v_mfma_f32_16x16x32_bf16 v[84:87], v[12:15], v[52:55], v[84:87]
	v_mfma_f32_16x16x32_bf16 v[88:91], v[4:7], v[60:63], v[88:91]
	v_mfma_f32_16x16x32_bf16 v[92:95], v[12:15], v[60:63], v[92:95]
	v_mfma_f32_16x16x32_bf16 v[96:99], v[16:19], v[32:35], 0
	v_mfma_f32_16x16x32_bf16 v[32:35], v[24:27], v[32:35], 0
	v_mfma_f32_16x16x32_bf16 v[96:99], v[20:23], v[36:39], v[96:99]
	v_mfma_f32_16x16x32_bf16 v[32:35], v[28:31], v[36:39], v[32:35]
	v_mfma_f32_16x16x32_bf16 v[36:39], v[16:19], v[40:43], 0
	v_mfma_f32_16x16x32_bf16 v[40:43], v[24:27], v[40:43], 0
	v_mfma_f32_16x16x32_bf16 v[36:39], v[20:23], v[44:47], v[36:39]
	v_mfma_f32_16x16x32_bf16 v[40:43], v[28:31], v[44:47], v[40:43]
	v_mfma_f32_16x16x32_bf16 v[44:47], v[16:19], v[48:51], 0
	v_mfma_f32_16x16x32_bf16 v[48:51], v[24:27], v[48:51], 0
	v_mfma_f32_16x16x32_bf16 v[44:47], v[20:23], v[52:55], v[44:47]
	v_mfma_f32_16x16x32_bf16 v[48:51], v[28:31], v[52:55], v[48:51]
	v_mfma_f32_16x16x32_bf16 v[52:55], v[16:19], v[56:59], 0
	v_mfma_f32_16x16x32_bf16 v[56:59], v[24:27], v[56:59], 0
	v_mfma_f32_16x16x32_bf16 v[52:55], v[20:23], v[60:63], v[52:55]
	v_mfma_f32_16x16x32_bf16 v[56:59], v[28:31], v[60:63], v[56:59]
	s_barrier
	v_lshl_add_u64 v[204:205], s[44:45], 0, v[130:131]
	s_mov_b32 m0, s51
	v_lshl_add_u64 v[140:141], v[204:205], 0, s[22:23]
	v_lshl_add_u64 v[206:207], s[44:45], 0, v[128:129]
	s_add_u32 s64, s44, 0x10100
	global_load_lds_dwordx4 v[140:141], off
	v_lshl_add_u64 v[140:141], v[206:207], 0, s[22:23]
	s_mov_b32 m0, s52
	s_addc_u32 s65, s45, 0
	global_load_lds_dwordx4 v[140:141], off
	v_lshl_add_u64 v[140:141], s[64:65], 0, v[130:131]
	s_mov_b32 m0, s53
	v_lshl_add_u64 v[208:209], s[36:37], 0, v[130:131]
	global_load_lds_dwordx4 v[140:141], off
	v_lshl_add_u64 v[140:141], s[64:65], 0, v[128:129]
	s_mov_b32 m0, s54
	v_lshl_add_u64 v[210:211], s[36:37], 0, v[128:129]
	global_load_lds_dwordx4 v[140:141], off
	v_lshl_add_u64 v[140:141], v[208:209], 0, s[22:23]
	s_mov_b32 m0, s74
	s_nop 0
	global_load_lds_dwordx4 v[140:141], off
	v_lshl_add_u64 v[140:141], v[210:211], 0, s[22:23]
	s_mov_b32 m0, s47
	s_nop 0
	global_load_lds_dwordx4 v[140:141], off
	ds_read_b128 v[60:63], v136 offset:16384
	ds_read_b128 v[100:103], v136 offset:17408
	ds_read_b128 v[104:107], v136 offset:18432
	ds_read_b128 v[108:111], v136 offset:19456
	ds_read_b128 v[112:115], v136 offset:20480
	ds_read_b128 v[116:119], v136 offset:21504
	ds_read_b128 v[120:123], v136 offset:22528
	ds_read_b128 v[124:127], v136 offset:23552
	s_waitcnt vmcnt(8)
	s_waitcnt lgkmcnt(0)
	s_barrier
; #define PG8_STAGE(bufoff, gbase, voff) do { _Pragma("unroll") for (int _i = 0; _i < 2; ++_i) \
;         __builtin_amdgcn_global_load_lds((const unsigned*)((const char*)(gbase) + (voff)[_i]), (PG8_LAS unsigned*)(lds + (bufoff) + ldsw + _i * 8192), 16, 0, 0); } while (0)
; #define PG8_LDA(dst, b, h) do { _Pragma("unroll") for (int m = 0; m < 4; ++m) _Pragma("unroll") for (int k = 0; k < 2; ++k) dst[m][k] = *(const PG8_LAS bf16x8*)(lds + PG8_SA(b, h) + aoff + m * 2048 + k * 1024); } while (0)
; #define PG8_LDB(dst, b, h) do { _Pragma("unroll") for (int n = 0; n < 2; ++n) _Pragma("unroll") for (int k = 0; k < 2; ++k) dst[n][k] = *(const PG8_LAS bf16x8*)(lds + PG8_SB(b, h) + boff + n * 2048 + k * 1024); } while (0)
; #define PG8_MMA(ai, bj, At, Bt) do { __builtin_amdgcn_s_setprio(1); _Pragma("unroll") for (int m = 0; m < 4; ++m) _Pragma("unroll") for (int n = 0; n < 2; ++n) _Pragma("unroll") for (int k = 0; k < 2; ++k) \
;         acc[ai][bj][m][n] = mma16<F16>(Bt[n][k], At[m][k], acc[ai][bj][m][n]); __builtin_amdgcn_s_setprio(0); } while (0)
; #define PG8_WAIT_V(n) asm volatile("s_waitcnt vmcnt(" #n ")" ::: "memory")
; #define PG8_WAIT_L(n) asm volatile("s_waitcnt lgkmcnt(" #n ")" ::: "memory")
; #define PG8_BAR __builtin_amdgcn_s_barrier()
; #define PG8_SCHED __builtin_amdgcn_sched_barrier(0)
; template <class Epi, class Sched, bool ALIGN_EPI = false, bool SP2 = false, bool F16 = false>
; __device__ __forceinline__ void gemm_phase(PG8_LAS unsigned char* lds, const Gemm g, const Sched& S, const Epi& E, const int wid_in) {
;     ...
;             PG8_WAIT_V(8); PG8_WAIT_L(0); PG8_BAR; PG8_MMA(0, 0, At, B0); PG8_MMA(0, 1, At, B1); PG8_BAR; PG8_SCHED;
;             PG8_LDA(At, 0, 1); PG8_STAGE(PG8_SB(0, 0), b2, voffB); PG8_STAGE(PG8_SB(0, 1), b2 + hstep, voffB); PG8_STAGE(PG8_SA(0, 0), a2, voffA);
;             PG8_WAIT_V(8); PG8_WAIT_L(0); PG8_BAR; PG8_MMA(1, 0, At, B0); PG8_MMA(1, 1, At, B1); PG8_BAR; PG8_SCHED;
;             PG8_LDB(B0, 1, 0); PG8_LDB(B1, 1, 1); PG8_SCHED; PG8_LDA(At, 1, 0); PG8_STAGE(PG8_SA(0, 1), a2 + hstep, voffA);
;             PG8_WAIT_V(8); PG8_WAIT_L(0); PG8_BAR; PG8_MMA(0, 0, At, B0); PG8_MMA(0, 1, At, B1); PG8_BAR; PG8_SCHED;
	s_waitcnt lgkmcnt(0)
	v_mfma_f32_16x16x32_bf16 v[140:143], v[0:3], v[60:63], 0
	v_mfma_f32_16x16x32_bf16 v[148:151], v[0:3], v[104:107], 0
	v_mfma_f32_16x16x32_bf16 v[156:159], v[0:3], v[112:115], 0
	v_mfma_f32_16x16x32_bf16 v[0:3], v[0:3], v[120:123], 0
	v_mfma_f32_16x16x32_bf16 v[140:143], v[4:7], v[100:103], v[140:143]
	v_mfma_f32_16x16x32_bf16 v[148:151], v[4:7], v[108:111], v[148:151]
	v_mfma_f32_16x16x32_bf16 v[156:159], v[4:7], v[116:119], v[156:159]
	v_mfma_f32_16x16x32_bf16 v[0:3], v[4:7], v[124:127], v[0:3]
	v_mfma_f32_16x16x32_bf16 v[4:7], v[8:11], v[120:123], 0
	v_mfma_f32_16x16x32_bf16 v[144:147], v[8:11], v[60:63], 0
	v_mfma_f32_16x16x32_bf16 v[152:155], v[8:11], v[104:107], 0
	v_mfma_f32_16x16x32_bf16 v[160:163], v[8:11], v[112:115], 0
	v_mfma_f32_16x16x32_bf16 v[4:7], v[12:15], v[124:127], v[4:7]
	v_mfma_f32_16x16x32_bf16 v[144:147], v[12:15], v[100:103], v[144:147]
	v_mfma_f32_16x16x32_bf16 v[152:155], v[12:15], v[108:111], v[152:155]
	v_mfma_f32_16x16x32_bf16 v[160:163], v[12:15], v[116:119], v[160:163]
	v_mfma_f32_16x16x32_bf16 v[8:11], v[16:19], v[60:63], 0
	v_mfma_f32_16x16x32_bf16 v[12:15], v[24:27], v[60:63], 0
	v_mfma_f32_16x16x32_bf16 v[8:11], v[20:23], v[100:103], v[8:11]
	v_mfma_f32_16x16x32_bf16 v[12:15], v[28:31], v[100:103], v[12:15]
	v_mfma_f32_16x16x32_bf16 v[60:63], v[16:19], v[104:107], 0
	v_mfma_f32_16x16x32_bf16 v[100:103], v[24:27], v[104:107], 0
	v_mfma_f32_16x16x32_bf16 v[104:107], v[16:19], v[112:115], 0
	v_mfma_f32_16x16x32_bf16 v[16:19], v[16:19], v[120:123], 0
	v_mfma_f32_16x16x32_bf16 v[60:63], v[20:23], v[108:111], v[60:63]
	v_mfma_f32_16x16x32_bf16 v[100:103], v[28:31], v[108:111], v[100:103]
	v_mfma_f32_16x16x32_bf16 v[104:107], v[20:23], v[116:119], v[104:107]
	v_mfma_f32_16x16x32_bf16 v[108:111], v[24:27], v[112:115], 0
	v_mfma_f32_16x16x32_bf16 v[16:19], v[20:23], v[124:127], v[16:19]
	v_mfma_f32_16x16x32_bf16 v[20:23], v[24:27], v[120:123], 0
	v_mfma_f32_16x16x32_bf16 v[108:111], v[28:31], v[116:119], v[108:111]
	v_mfma_f32_16x16x32_bf16 v[20:23], v[28:31], v[124:127], v[20:23]
	s_barrier
	s_add_u32 s64, s36, 0x10100
	s_addc_u32 s65, s37, 0
	s_mov_b32 m0, s48
	v_lshl_add_u64 v[212:213], s[64:65], 0, v[130:131]
	global_load_lds_dwordx4 v[212:213], off
	v_lshl_add_u64 v[212:213], s[64:65], 0, v[128:129]
	s_mov_b32 m0, s49
	s_nop 0
	global_load_lds_dwordx4 v[212:213], off
	ds_read_b128 v[24:27], v137
	ds_read_b128 v[28:31], v137 offset:1024
	ds_read_b128 v[112:115], v137 offset:2048
	ds_read_b128 v[116:119], v137 offset:3072
	ds_read_b128 v[120:123], v138
	ds_read_b128 v[124:127], v138 offset:1024
	ds_read_b128 v[164:167], v138 offset:2048
	ds_read_b128 v[168:171], v138 offset:3072
	ds_read_b128 v[172:175], v136 offset:32768
	ds_read_b128 v[176:179], v136 offset:33792
	ds_read_b128 v[180:183], v136 offset:34816
	ds_read_b128 v[184:187], v136 offset:35840
	ds_read_b128 v[188:191], v136 offset:36864
	ds_read_b128 v[192:195], v136 offset:37888
	ds_read_b128 v[196:199], v136 offset:38912
	ds_read_b128 v[200:203], v136 offset:39936
	s_waitcnt vmcnt(8)
	s_waitcnt lgkmcnt(0)
	s_barrier
	s_waitcnt lgkmcnt(0)
	v_mfma_f32_16x16x32_bf16 v[64:67], v[24:27], v[172:175], v[64:67]
	v_mfma_f32_16x16x32_bf16 v[68:71], v[112:115], v[172:175], v[68:71]
	v_mfma_f32_16x16x32_bf16 v[72:75], v[24:27], v[180:183], v[72:75]
	v_mfma_f32_16x16x32_bf16 v[76:79], v[112:115], v[180:183], v[76:79]
	v_mfma_f32_16x16x32_bf16 v[80:83], v[24:27], v[188:191], v[80:83]
	v_mfma_f32_16x16x32_bf16 v[84:87], v[112:115], v[188:191], v[84:87]
	v_mfma_f32_16x16x32_bf16 v[88:91], v[24:27], v[196:199], v[88:91]
	v_mfma_f32_16x16x32_bf16 v[92:95], v[112:115], v[196:199], v[92:95]
	v_mfma_f32_16x16x32_bf16 v[64:67], v[28:31], v[176:179], v[64:67]
	v_mfma_f32_16x16x32_bf16 v[68:71], v[116:119], v[176:179], v[68:71]
	v_mfma_f32_16x16x32_bf16 v[72:75], v[28:31], v[184:187], v[72:75]
	v_mfma_f32_16x16x32_bf16 v[76:79], v[116:119], v[184:187], v[76:79]
	v_mfma_f32_16x16x32_bf16 v[80:83], v[28:31], v[192:195], v[80:83]
	v_mfma_f32_16x16x32_bf16 v[84:87], v[116:119], v[192:195], v[84:87]
	v_mfma_f32_16x16x32_bf16 v[88:91], v[28:31], v[200:203], v[88:91]
	v_mfma_f32_16x16x32_bf16 v[92:95], v[116:119], v[200:203], v[92:95]
	v_mfma_f32_16x16x32_bf16 v[96:99], v[120:123], v[172:175], v[96:99]
	v_mfma_f32_16x16x32_bf16 v[32:35], v[164:167], v[172:175], v[32:35]
	v_mfma_f32_16x16x32_bf16 v[36:39], v[120:123], v[180:183], v[36:39]
	v_mfma_f32_16x16x32_bf16 v[40:43], v[164:167], v[180:183], v[40:43]
	v_mfma_f32_16x16x32_bf16 v[44:47], v[120:123], v[188:191], v[44:47]
	v_mfma_f32_16x16x32_bf16 v[48:51], v[164:167], v[188:191], v[48:51]
	v_mfma_f32_16x16x32_bf16 v[52:55], v[120:123], v[196:199], v[52:55]
	v_mfma_f32_16x16x32_bf16 v[56:59], v[164:167], v[196:199], v[56:59]
	v_mfma_f32_16x16x32_bf16 v[96:99], v[124:127], v[176:179], v[96:99]
	v_mfma_f32_16x16x32_bf16 v[32:35], v[168:171], v[176:179], v[32:35]
	v_mfma_f32_16x16x32_bf16 v[36:39], v[124:127], v[184:187], v[36:39]
	v_mfma_f32_16x16x32_bf16 v[40:43], v[168:171], v[184:187], v[40:43]
	v_mfma_f32_16x16x32_bf16 v[44:47], v[124:127], v[192:195], v[44:47]
	v_mfma_f32_16x16x32_bf16 v[48:51], v[168:171], v[192:195], v[48:51]
	v_mfma_f32_16x16x32_bf16 v[52:55], v[124:127], v[200:203], v[52:55]
	v_mfma_f32_16x16x32_bf16 v[56:59], v[168:171], v[200:203], v[56:59]
	s_barrier
; #define PG8_STAGE(bufoff, gbase, voff) do { _Pragma("unroll") for (int _i = 0; _i < 2; ++_i) \
;         __builtin_amdgcn_global_load_lds((const unsigned*)((const char*)(gbase) + (voff)[_i]), (PG8_LAS unsigned*)(lds + (bufoff) + ldsw + _i * 8192), 16, 0, 0); } while (0)
; #define PG8_LDA(dst, b, h) do { _Pragma("unroll") for (int m = 0; m < 4; ++m) _Pragma("unroll") for (int k = 0; k < 2; ++k) dst[m][k] = *(const PG8_LAS bf16x8*)(lds + PG8_SA(b, h) + aoff + m * 2048 + k * 1024); } while (0)
; #define PG8_LDB(dst, b, h) do { _Pragma("unroll") for (int n = 0; n < 2; ++n) _Pragma("unroll") for (int k = 0; k < 2; ++k) dst[n][k] = *(const PG8_LAS bf16x8*)(lds + PG8_SB(b, h) + boff + n * 2048 + k * 1024); } while (0)
; #define PG8_MMA(ai, bj, At, Bt) do { __builtin_amdgcn_s_setprio(1); _Pragma("unroll") for (int m = 0; m < 4; ++m) _Pragma("unroll") for (int n = 0; n < 2; ++n) _Pragma("unroll") for (int k = 0; k < 2; ++k) \
;         acc[ai][bj][m][n] = mma16<F16>(Bt[n][k], At[m][k], acc[ai][bj][m][n]); __builtin_amdgcn_s_setprio(0); } while (0)
; #define PG8_WAIT_V(n) asm volatile("s_waitcnt vmcnt(" #n ")" ::: "memory")
; template <class Epi, class Sched, bool ALIGN_EPI = false, bool SP2 = false, bool F16 = false>
; __device__ __forceinline__ void gemm_phase(PG8_LAS unsigned char* lds, const Gemm g, const Sched& S, const Epi& E, const int wid_in) {
;     ...
;             PG8_LDB(B0, 0, 0); PG8_LDB(B1, 0, 1); PG8_SCHED; PG8_LDA(At, 0, 0); PG8_STAGE(PG8_SA(1, 1), a1 + hstep, voffA);
;             PG8_WAIT_V(8); PG8_WAIT_L(0); PG8_BAR; PG8_MMA(0, 0, At, B0); PG8_MMA(0, 1, At, B1); PG8_BAR; PG8_SCHED;
;             PG8_LDA(At, 0, 1); PG8_STAGE(PG8_SB(0, 0), b2, voffB); PG8_STAGE(PG8_SB(0, 1), b2 + hstep, voffB); PG8_STAGE(PG8_SA(0, 0), a2, voffA);
;             PG8_WAIT_V(8); PG8_WAIT_L(0); PG8_BAR; PG8_MMA(1, 0, At, B0); PG8_MMA(1, 1, At, B1); PG8_BAR; PG8_SCHED;
;             PG8_LDB(B0, 1, 0); PG8_LDB(B1, 1, 1); PG8_SCHED; PG8_LDA(At, 1, 0); PG8_STAGE(PG8_SA(0, 1), a2 + hstep, voffA);
;             PG8_WAIT_V(8); PG8_WAIT_L(0); PG8_BAR; PG8_MMA(0, 0, At, B0); PG8_MMA(0, 1, At, B1); PG8_BAR; PG8_SCHED;
;             PG8_LDA(At, 1, 1); PG8_STAGE(PG8_SB(1, 0), b3, voffB); PG8_STAGE(PG8_SB(1, 1), b3 + hstep, voffB); PG8_STAGE(PG8_SA(1, 0), a3, voffA);
;             PG8_WAIT_V(8); PG8_WAIT_L(0); PG8_BAR; PG8_MMA(1, 0, At, B0); PG8_MMA(1, 1, At, B1); PG8_BAR; PG8_SCHED;
	s_mov_b32 m0, s55
	v_lshl_add_u64 v[204:205], v[204:205], 0, s[24:25]
	s_add_u32 s44, s44, 0x10180
	global_load_lds_dwordx4 v[204:205], off
	v_lshl_add_u64 v[204:205], v[206:207], 0, s[24:25]
	s_mov_b32 m0, s58
	s_addc_u32 s45, s45, 0
	global_load_lds_dwordx4 v[204:205], off
	v_lshl_add_u64 v[204:205], s[44:45], 0, v[130:131]
	s_mov_b32 m0, s59
	s_nop 0
	global_load_lds_dwordx4 v[204:205], off
	v_lshl_add_u64 v[204:205], s[44:45], 0, v[128:129]
	s_mov_b32 m0, s60
	s_nop 0
	global_load_lds_dwordx4 v[204:205], off
	v_lshl_add_u64 v[204:205], v[208:209], 0, s[24:25]
	s_mov_b32 m0, s75
	s_nop 0
	global_load_lds_dwordx4 v[204:205], off
	v_lshl_add_u64 v[204:205], v[210:211], 0, s[24:25]
	s_mov_b32 m0, s14
	s_nop 0
	global_load_lds_dwordx4 v[204:205], off
	ds_read_b128 v[172:175], v136 offset:49152
	ds_read_b128 v[176:179], v136 offset:50176
	ds_read_b128 v[180:183], v136 offset:51200
	ds_read_b128 v[184:187], v136 offset:52224
	ds_read_b128 v[188:191], v136 offset:53248
	ds_read_b128 v[192:195], v136 offset:54272
	ds_read_b128 v[196:199], v136 offset:55296
	ds_read_b128 v[200:203], v136 offset:56320
	s_waitcnt vmcnt(8)
	s_waitcnt lgkmcnt(0)
	s_barrier
	s_waitcnt lgkmcnt(0)
	v_mfma_f32_16x16x32_bf16 v[0:3], v[24:27], v[196:199], v[0:3]
	v_mfma_f32_16x16x32_bf16 v[4:7], v[112:115], v[196:199], v[4:7]
	v_mfma_f32_16x16x32_bf16 v[140:143], v[24:27], v[172:175], v[140:143]
	v_mfma_f32_16x16x32_bf16 v[144:147], v[112:115], v[172:175], v[144:147]
	v_mfma_f32_16x16x32_bf16 v[148:151], v[24:27], v[180:183], v[148:151]
	v_mfma_f32_16x16x32_bf16 v[152:155], v[112:115], v[180:183], v[152:155]
	v_mfma_f32_16x16x32_bf16 v[156:159], v[24:27], v[188:191], v[156:159]
	v_mfma_f32_16x16x32_bf16 v[160:163], v[112:115], v[188:191], v[160:163]
	v_mfma_f32_16x16x32_bf16 v[0:3], v[28:31], v[200:203], v[0:3]
	v_mfma_f32_16x16x32_bf16 v[4:7], v[116:119], v[200:203], v[4:7]
	v_mfma_f32_16x16x32_bf16 v[140:143], v[28:31], v[176:179], v[140:143]
	v_mfma_f32_16x16x32_bf16 v[144:147], v[116:119], v[176:179], v[144:147]
	v_mfma_f32_16x16x32_bf16 v[148:151], v[28:31], v[184:187], v[148:151]
	v_mfma_f32_16x16x32_bf16 v[152:155], v[116:119], v[184:187], v[152:155]
	v_mfma_f32_16x16x32_bf16 v[156:159], v[28:31], v[192:195], v[156:159]
	v_mfma_f32_16x16x32_bf16 v[160:163], v[116:119], v[192:195], v[160:163]
	v_mfma_f32_16x16x32_bf16 v[8:11], v[120:123], v[172:175], v[8:11]
	v_mfma_f32_16x16x32_bf16 v[12:15], v[164:167], v[172:175], v[12:15]
	v_mfma_f32_16x16x32_bf16 v[24:27], v[120:123], v[180:183], v[60:63]
	v_mfma_f32_16x16x32_bf16 v[28:31], v[164:167], v[180:183], v[100:103]
	v_mfma_f32_16x16x32_bf16 v[60:63], v[120:123], v[188:191], v[104:107]
	v_mfma_f32_16x16x32_bf16 v[100:103], v[164:167], v[188:191], v[108:111]
	v_mfma_f32_16x16x32_bf16 v[16:19], v[120:123], v[196:199], v[16:19]
	v_mfma_f32_16x16x32_bf16 v[20:23], v[164:167], v[196:199], v[20:23]
	v_mfma_f32_16x16x32_bf16 v[8:11], v[124:127], v[176:179], v[8:11]
	v_mfma_f32_16x16x32_bf16 v[12:15], v[168:171], v[176:179], v[12:15]
	v_mfma_f32_16x16x32_bf16 v[24:27], v[124:127], v[184:187], v[24:27]
	v_mfma_f32_16x16x32_bf16 v[28:31], v[168:171], v[184:187], v[28:31]
	v_mfma_f32_16x16x32_bf16 v[60:63], v[124:127], v[192:195], v[60:63]
	v_mfma_f32_16x16x32_bf16 v[100:103], v[168:171], v[192:195], v[100:103]
	v_mfma_f32_16x16x32_bf16 v[16:19], v[124:127], v[200:203], v[16:19]
	v_mfma_f32_16x16x32_bf16 v[20:23], v[168:171], v[200:203], v[20:23]
	s_barrier
	s_add_u32 s36, s36, 0x10180
	s_addc_u32 s37, s37, 0
	s_mov_b32 m0, s15
	v_lshl_add_u64 v[204:205], s[36:37], 0, v[130:131]
	global_load_lds_dwordx4 v[204:205], off
	v_lshl_add_u64 v[204:205], s[36:37], 0, v[128:129]
	s_mov_b32 m0, s50
	s_nop 0
	global_load_lds_dwordx4 v[204:205], off
	ds_read_b128 v[104:107], v134
	ds_read_b128 v[108:111], v134 offset:1024
	ds_read_b128 v[112:115], v134 offset:2048
	ds_read_b128 v[116:119], v134 offset:3072
	ds_read_b128 v[120:123], v135
	ds_read_b128 v[124:127], v135 offset:1024
	ds_read_b128 v[164:167], v135 offset:2048
	ds_read_b128 v[168:171], v135 offset:3072
	ds_read_b128 v[172:175], v136
	ds_read_b128 v[176:179], v136 offset:1024
	ds_read_b128 v[180:183], v136 offset:2048
	ds_read_b128 v[184:187], v136 offset:3072
	ds_read_b128 v[188:191], v136 offset:4096
	ds_read_b128 v[192:195], v136 offset:5120
	ds_read_b128 v[196:199], v136 offset:6144
	ds_read_b128 v[200:203], v136 offset:7168
	s_waitcnt vmcnt(8)
	s_waitcnt lgkmcnt(0)
	s_barrier
	s_waitcnt lgkmcnt(0)
	v_mfma_f32_16x16x32_bf16 v[64:67], v[104:107], v[172:175], v[64:67]
	v_mfma_f32_16x16x32_bf16 v[68:71], v[112:115], v[172:175], v[68:71]
	v_mfma_f32_16x16x32_bf16 v[72:75], v[104:107], v[180:183], v[72:75]
	v_mfma_f32_16x16x32_bf16 v[76:79], v[112:115], v[180:183], v[76:79]
	v_mfma_f32_16x16x32_bf16 v[80:83], v[104:107], v[188:191], v[80:83]
	v_mfma_f32_16x16x32_bf16 v[84:87], v[112:115], v[188:191], v[84:87]
	v_mfma_f32_16x16x32_bf16 v[88:91], v[104:107], v[196:199], v[88:91]
	v_mfma_f32_16x16x32_bf16 v[92:95], v[112:115], v[196:199], v[92:95]
	v_mfma_f32_16x16x32_bf16 v[64:67], v[108:111], v[176:179], v[64:67]
	v_mfma_f32_16x16x32_bf16 v[68:71], v[116:119], v[176:179], v[68:71]
	v_mfma_f32_16x16x32_bf16 v[72:75], v[108:111], v[184:187], v[72:75]
	v_mfma_f32_16x16x32_bf16 v[76:79], v[116:119], v[184:187], v[76:79]
	v_mfma_f32_16x16x32_bf16 v[80:83], v[108:111], v[192:195], v[80:83]
	v_mfma_f32_16x16x32_bf16 v[84:87], v[116:119], v[192:195], v[84:87]
	v_mfma_f32_16x16x32_bf16 v[88:91], v[108:111], v[200:203], v[88:91]
	v_mfma_f32_16x16x32_bf16 v[92:95], v[116:119], v[200:203], v[92:95]
	v_mfma_f32_16x16x32_bf16 v[32:35], v[164:167], v[172:175], v[32:35]
	v_mfma_f32_16x16x32_bf16 v[96:99], v[120:123], v[172:175], v[96:99]
	v_mfma_f32_16x16x32_bf16 v[172:175], v[168:171], v[176:179], v[32:35]
	v_mfma_f32_16x16x32_bf16 v[32:35], v[120:123], v[180:183], v[36:39]
	v_mfma_f32_16x16x32_bf16 v[204:207], v[124:127], v[176:179], v[96:99]
	v_mfma_f32_16x16x32_bf16 v[176:179], v[124:127], v[184:187], v[32:35]
	v_mfma_f32_16x16x32_bf16 v[32:35], v[164:167], v[180:183], v[40:43]
	v_mfma_f32_16x16x32_bf16 v[40:43], v[168:171], v[184:187], v[32:35]
	v_mfma_f32_16x16x32_bf16 v[32:35], v[120:123], v[188:191], v[44:47]
	v_mfma_f32_16x16x32_bf16 v[44:47], v[124:127], v[192:195], v[32:35]
	v_mfma_f32_16x16x32_bf16 v[32:35], v[164:167], v[188:191], v[48:51]
	v_mfma_f32_16x16x32_bf16 v[48:51], v[168:171], v[192:195], v[32:35]
	v_mfma_f32_16x16x32_bf16 v[32:35], v[120:123], v[196:199], v[52:55]
	v_mfma_f32_16x16x32_bf16 v[52:55], v[124:127], v[200:203], v[32:35]
	v_mfma_f32_16x16x32_bf16 v[32:35], v[164:167], v[196:199], v[56:59]
	v_mfma_f32_16x16x32_bf16 v[56:59], v[168:171], v[200:203], v[32:35]
	s_barrier
; #define PG8_STAGE(bufoff, gbase, voff) do { _Pragma("unroll") for (int _i = 0; _i < 2; ++_i) \
;         __builtin_amdgcn_global_load_lds((const unsigned*)((const char*)(gbase) + (voff)[_i]), (PG8_LAS unsigned*)(lds + (bufoff) + ldsw + _i * 8192), 16, 0, 0); } while (0)
; #define PG8_LDA(dst, b, h) do { _Pragma("unroll") for (int m = 0; m < 4; ++m) _Pragma("unroll") for (int k = 0; k < 2; ++k) dst[m][k] = *(const PG8_LAS bf16x8*)(lds + PG8_SA(b, h) + aoff + m * 2048 + k * 1024); } while (0)
; #define PG8_LDB(dst, b, h) do { _Pragma("unroll") for (int n = 0; n < 2; ++n) _Pragma("unroll") for (int k = 0; k < 2; ++k) dst[n][k] = *(const PG8_LAS bf16x8*)(lds + PG8_SB(b, h) + boff + n * 2048 + k * 1024); } while (0)
; #define PG8_MMA(ai, bj, At, Bt) do { __builtin_amdgcn_s_setprio(1); _Pragma("unroll") for (int m = 0; m < 4; ++m) _Pragma("unroll") for (int n = 0; n < 2; ++n) _Pragma("unroll") for (int k = 0; k < 2; ++k) \
;         acc[ai][bj][m][n] = mma16<F16>(Bt[n][k], At[m][k], acc[ai][bj][m][n]); __builtin_amdgcn_s_setprio(0); } while (0)
; #define PG8_WAIT_V(n) asm volatile("s_waitcnt vmcnt(" #n ")" ::: "memory")
; #define PG8_WAIT_L(n) asm volatile("s_waitcnt lgkmcnt(" #n ")" ::: "memory")
; #define PG8_BAR __builtin_amdgcn_s_barrier()
; #define PG8_SCHED __builtin_amdgcn_sched_barrier(0)
; template <class Epi, class Sched, bool ALIGN_EPI = false, bool SP2 = false, bool F16 = false>
; __device__ __forceinline__ void gemm_phase(PG8_LAS unsigned char* lds, const Gemm g, const Sched& S, const Epi& E, const int wid_in) {
;     ...
;             PG8_LDA(At, 0, 1); PG8_STAGE(PG8_SB(0, 0), b2, voffB); PG8_STAGE(PG8_SB(0, 1), b2 + hstep, voffB); PG8_STAGE(PG8_SA(0, 0), a2, voffA);
;             PG8_WAIT_V(8); PG8_WAIT_L(0); PG8_BAR; PG8_MMA(1, 0, At, B0); PG8_MMA(1, 1, At, B1); PG8_BAR; PG8_SCHED;
;             PG8_LDB(B0, 1, 0); PG8_LDB(B1, 1, 1); PG8_SCHED; PG8_LDA(At, 1, 0); PG8_STAGE(PG8_SA(0, 1), a2 + hstep, voffA);
;             PG8_WAIT_V(8); PG8_WAIT_L(0); PG8_BAR; PG8_MMA(0, 0, At, B0); PG8_MMA(0, 1, At, B1); PG8_BAR; PG8_SCHED;
	s_mov_b32 m0, s51
	v_lshl_add_u64 v[240:241], s[30:31], 0, v[130:131]
	s_add_u32 s36, s30, 0x10000
	s_nop 1
	global_load_lds_dwordx4 v[240:241], off
	v_lshl_add_u64 v[242:243], s[30:31], 0, v[128:129]
	s_mov_b32 m0, s52
	s_addc_u32 s37, s31, 0
	global_load_lds_dwordx4 v[242:243], off
	v_lshl_add_u64 v[200:201], s[36:37], 0, v[130:131]
	s_mov_b32 m0, s53
	v_lshl_add_u64 v[244:245], s[34:35], 0, v[130:131]
	global_load_lds_dwordx4 v[200:201], off
	v_lshl_add_u64 v[200:201], s[36:37], 0, v[128:129]
	s_mov_b32 m0, s54
	v_lshl_add_u64 v[246:247], s[34:35], 0, v[128:129]
	global_load_lds_dwordx4 v[200:201], off
	s_mov_b32 m0, s74
	s_nop 0
	global_load_lds_dwordx4 v[244:245], off
	s_mov_b32 m0, s47
	s_nop 0
	global_load_lds_dwordx4 v[246:247], off
	ds_read_b128 v[32:35], v136 offset:16384
	ds_read_b128 v[36:39], v136 offset:17408
	ds_read_b128 v[96:99], v136 offset:18432
	ds_read_b128 v[180:183], v136 offset:19456
	ds_read_b128 v[184:187], v136 offset:20480
	ds_read_b128 v[188:191], v136 offset:21504
	ds_read_b128 v[192:195], v136 offset:22528
	ds_read_b128 v[196:199], v136 offset:23552
	s_waitcnt vmcnt(8)
	s_waitcnt lgkmcnt(0)
	s_barrier
	s_waitcnt lgkmcnt(0)
	v_mfma_f32_16x16x32_bf16 v[0:3], v[104:107], v[192:195], v[0:3]
	v_mfma_f32_16x16x32_bf16 v[140:143], v[104:107], v[32:35], v[140:143]
	v_mfma_f32_16x16x32_bf16 v[144:147], v[112:115], v[32:35], v[144:147]
	v_mfma_f32_16x16x32_bf16 v[148:151], v[104:107], v[96:99], v[148:151]
	v_mfma_f32_16x16x32_bf16 v[152:155], v[112:115], v[96:99], v[152:155]
	v_mfma_f32_16x16x32_bf16 v[156:159], v[104:107], v[184:187], v[156:159]
	v_mfma_f32_16x16x32_bf16 v[160:163], v[112:115], v[184:187], v[160:163]
	v_mfma_f32_16x16x32_bf16 v[0:3], v[108:111], v[196:199], v[0:3]
	v_mfma_f32_16x16x32_bf16 v[4:7], v[112:115], v[192:195], v[4:7]
	v_mfma_f32_16x16x32_bf16 v[140:143], v[108:111], v[36:39], v[140:143]
	v_mfma_f32_16x16x32_bf16 v[144:147], v[116:119], v[36:39], v[144:147]
	v_mfma_f32_16x16x32_bf16 v[148:151], v[108:111], v[180:183], v[148:151]
	v_mfma_f32_16x16x32_bf16 v[152:155], v[116:119], v[180:183], v[152:155]
	v_mfma_f32_16x16x32_bf16 v[156:159], v[108:111], v[188:191], v[156:159]
	v_mfma_f32_16x16x32_bf16 v[160:163], v[116:119], v[188:191], v[160:163]
	v_mfma_f32_16x16x32_bf16 v[200:203], v[116:119], v[196:199], v[4:7]
	v_mfma_f32_16x16x32_bf16 v[4:7], v[120:123], v[32:35], v[8:11]
	v_mfma_f32_16x16x32_bf16 v[8:11], v[124:127], v[36:39], v[4:7]
	v_mfma_f32_16x16x32_bf16 v[4:7], v[164:167], v[32:35], v[12:15]
	v_mfma_f32_16x16x32_bf16 v[12:15], v[168:171], v[36:39], v[4:7]
	v_mfma_f32_16x16x32_bf16 v[4:7], v[120:123], v[96:99], v[24:27]
	v_mfma_f32_16x16x32_bf16 v[24:27], v[124:127], v[180:183], v[4:7]
	v_mfma_f32_16x16x32_bf16 v[4:7], v[164:167], v[96:99], v[28:31]
	v_mfma_f32_16x16x32_bf16 v[28:31], v[168:171], v[180:183], v[4:7]
	v_mfma_f32_16x16x32_bf16 v[4:7], v[120:123], v[184:187], v[60:63]
	v_mfma_f32_16x16x32_bf16 v[180:183], v[124:127], v[188:191], v[4:7]
	v_mfma_f32_16x16x32_bf16 v[4:7], v[164:167], v[184:187], v[100:103]
	v_mfma_f32_16x16x32_bf16 v[184:187], v[168:171], v[188:191], v[4:7]
	v_mfma_f32_16x16x32_bf16 v[4:7], v[120:123], v[192:195], v[16:19]
	v_mfma_f32_16x16x32_bf16 v[188:191], v[124:127], v[196:199], v[4:7]
	v_mfma_f32_16x16x32_bf16 v[4:7], v[164:167], v[192:195], v[20:23]
	v_mfma_f32_16x16x32_bf16 v[164:167], v[168:171], v[196:199], v[4:7]
	s_barrier
	s_nop 4
	s_add_u32 s34, s34, 0x10000
	s_addc_u32 s35, s35, 0
	s_mov_b32 m0, s48
	v_lshl_add_u64 v[32:33], s[34:35], 0, v[130:131]
	global_load_lds_dwordx4 v[32:33], off
	v_lshl_add_u64 v[32:33], s[34:35], 0, v[128:129]
	s_mov_b32 m0, s49
	s_nop 0
	global_load_lds_dwordx4 v[32:33], off
	ds_read_b128 v[4:7], v137
	ds_read_b128 v[60:63], v137 offset:1024
	ds_read_b128 v[168:171], v137 offset:2048
	ds_read_b128 v[192:195], v137 offset:3072
	ds_read_b128 v[196:199], v138
	ds_read_b128 v[208:211], v138 offset:1024
	ds_read_b128 v[212:215], v138 offset:2048
	ds_read_b128 v[216:219], v138 offset:3072
	ds_read_b128 v[16:19], v136 offset:32768
	ds_read_b128 v[20:23], v136 offset:33792
	ds_read_b128 v[104:107], v136 offset:34816
	ds_read_b128 v[220:223], v136 offset:35840
	ds_read_b128 v[224:227], v136 offset:36864
	ds_read_b128 v[228:231], v136 offset:37888
	ds_read_b128 v[232:235], v136 offset:38912
	ds_read_b128 v[236:239], v136 offset:39936
	s_waitcnt vmcnt(8)
	s_waitcnt lgkmcnt(0)
	s_barrier
; #define PG8_STAGE(bufoff, gbase, voff) do { _Pragma("unroll") for (int _i = 0; _i < 2; ++_i) \
;         __builtin_amdgcn_global_load_lds((const unsigned*)((const char*)(gbase) + (voff)[_i]), (PG8_LAS unsigned*)(lds + (bufoff) + ldsw + _i * 8192), 16, 0, 0); } while (0)
; #define PG8_LDA(dst, b, h) do { _Pragma("unroll") for (int m = 0; m < 4; ++m) _Pragma("unroll") for (int k = 0; k < 2; ++k) dst[m][k] = *(const PG8_LAS bf16x8*)(lds + PG8_SA(b, h) + aoff + m * 2048 + k * 1024); } while (0)
; #define PG8_MMA(ai, bj, At, Bt) do { __builtin_amdgcn_s_setprio(1); _Pragma("unroll") for (int m = 0; m < 4; ++m) _Pragma("unroll") for (int n = 0; n < 2; ++n) _Pragma("unroll") for (int k = 0; k < 2; ++k) \
;         acc[ai][bj][m][n] = mma16<F16>(Bt[n][k], At[m][k], acc[ai][bj][m][n]); __builtin_amdgcn_s_setprio(0); } while (0)
; #define PG8_WAIT_V(n) asm volatile("s_waitcnt vmcnt(" #n ")" ::: "memory")
; #define PG8_WAIT_L(n) asm volatile("s_waitcnt lgkmcnt(" #n ")" ::: "memory")
; #define PG8_BAR __builtin_amdgcn_s_barrier()
; #define PG8_SCHED __builtin_amdgcn_sched_barrier(0)
; template <class Epi, class Sched, bool ALIGN_EPI = false, bool SP2 = false, bool F16 = false>
; __device__ __forceinline__ void gemm_phase(PG8_LAS unsigned char* lds, const Gemm g, const Sched& S, const Epi& E, const int wid_in) {
;     ...
;             PG8_WAIT_V(8); PG8_WAIT_L(0); PG8_BAR; PG8_MMA(0, 0, At, B0); PG8_MMA(0, 1, At, B1); PG8_BAR; PG8_SCHED;
;             PG8_LDA(At, 1, 1); PG8_STAGE(PG8_SB(1, 0), b3, voffB); PG8_STAGE(PG8_SB(1, 1), b3 + hstep, voffB); PG8_STAGE(PG8_SA(1, 0), a3, voffA);
;             PG8_WAIT_V(8); PG8_WAIT_L(0); PG8_BAR; PG8_MMA(1, 0, At, B0); PG8_MMA(1, 1, At, B1); PG8_BAR; PG8_SCHED;
;     ...
;         if constexpr (ALIGN_EPI) { if (wr == 0) PG8_BAR; }
	s_waitcnt lgkmcnt(0)
	v_mfma_f32_16x16x32_bf16 v[32:35], v[4:7], v[16:19], v[64:67]
	v_mfma_f32_16x16x32_bf16 v[116:119], v[60:63], v[20:23], v[32:35]
	v_mfma_f32_16x16x32_bf16 v[32:35], v[168:171], v[16:19], v[68:71]
	v_mfma_f32_16x16x32_bf16 v[112:115], v[192:195], v[20:23], v[32:35]
	v_mfma_f32_16x16x32_bf16 v[32:35], v[4:7], v[104:107], v[72:75]
	v_mfma_f32_16x16x32_bf16 v[100:103], v[60:63], v[220:223], v[32:35]
	v_mfma_f32_16x16x32_bf16 v[32:35], v[168:171], v[104:107], v[76:79]
	v_mfma_f32_16x16x32_bf16 v[96:99], v[192:195], v[220:223], v[32:35]
	v_mfma_f32_16x16x32_bf16 v[32:35], v[4:7], v[224:227], v[80:83]
	v_mfma_f32_16x16x32_bf16 v[68:71], v[60:63], v[228:231], v[32:35]
	v_mfma_f32_16x16x32_bf16 v[32:35], v[168:171], v[224:227], v[84:87]
	v_mfma_f32_16x16x32_bf16 v[64:67], v[192:195], v[228:231], v[32:35]
	v_mfma_f32_16x16x32_bf16 v[32:35], v[4:7], v[232:235], v[88:91]
	v_mfma_f32_16x16x32_bf16 v[36:39], v[60:63], v[236:239], v[32:35]
	v_mfma_f32_16x16x32_bf16 v[32:35], v[168:171], v[232:235], v[92:95]
	v_mfma_f32_16x16x32_bf16 v[32:35], v[192:195], v[236:239], v[32:35]
	v_mfma_f32_16x16x32_bf16 v[72:75], v[196:199], v[16:19], v[204:207]
	v_mfma_f32_16x16x32_bf16 v[16:19], v[212:215], v[16:19], v[172:175]
	v_mfma_f32_16x16x32_bf16 v[120:123], v[216:219], v[20:23], v[16:19]
	v_mfma_f32_16x16x32_bf16 v[16:19], v[196:199], v[104:107], v[176:179]
	v_mfma_f32_16x16x32_bf16 v[108:111], v[208:211], v[220:223], v[16:19]
	v_mfma_f32_16x16x32_bf16 v[16:19], v[212:215], v[104:107], v[40:43]
	v_mfma_f32_16x16x32_bf16 v[104:107], v[216:219], v[220:223], v[16:19]
	v_mfma_f32_16x16x32_bf16 v[16:19], v[196:199], v[224:227], v[44:47]
	v_mfma_f32_16x16x32_bf16 v[80:83], v[208:211], v[228:231], v[16:19]
	v_mfma_f32_16x16x32_bf16 v[16:19], v[212:215], v[224:227], v[48:51]
	v_mfma_f32_16x16x32_bf16 v[124:127], v[208:211], v[20:23], v[72:75]
	v_mfma_f32_16x16x32_bf16 v[72:75], v[216:219], v[228:231], v[16:19]
	v_mfma_f32_16x16x32_bf16 v[16:19], v[196:199], v[232:235], v[52:55]
	v_mfma_f32_16x16x32_bf16 v[48:51], v[208:211], v[236:239], v[16:19]
	v_mfma_f32_16x16x32_bf16 v[16:19], v[212:215], v[232:235], v[56:59]
	v_mfma_f32_16x16x32_bf16 v[40:43], v[216:219], v[236:239], v[16:19]
	s_barrier
	s_mov_b32 m0, s55
	s_nop 3
	v_lshl_add_u64 v[16:17], v[240:241], 0, s[20:21]
	s_add_u32 s30, s30, 0x10080
	global_load_lds_dwordx4 v[16:17], off
	v_lshl_add_u64 v[16:17], v[242:243], 0, s[20:21]
	s_mov_b32 m0, s58
	s_addc_u32 s31, s31, 0
	global_load_lds_dwordx4 v[16:17], off
	v_lshl_add_u64 v[16:17], s[30:31], 0, v[130:131]
	s_mov_b32 m0, s59
	s_nop 0
	global_load_lds_dwordx4 v[16:17], off
	v_lshl_add_u64 v[16:17], s[30:31], 0, v[128:129]
	s_mov_b32 m0, s60
	s_nop 0
	global_load_lds_dwordx4 v[16:17], off
	v_lshl_add_u64 v[16:17], v[244:245], 0, s[20:21]
	s_mov_b32 m0, s75
	s_nop 0
	global_load_lds_dwordx4 v[16:17], off
	v_lshl_add_u64 v[16:17], v[246:247], 0, s[20:21]
	s_mov_b32 m0, s14
	s_nop 0
	global_load_lds_dwordx4 v[16:17], off
	ds_read_b128 v[56:59], v136 offset:49152
	ds_read_b128 v[88:91], v136 offset:50176
	ds_read_b128 v[172:175], v136 offset:51200
	ds_read_b128 v[176:179], v136 offset:52224
	ds_read_b128 v[204:207], v136 offset:53248
	ds_read_b128 v[220:223], v136 offset:54272
	ds_read_b128 v[224:227], v136 offset:55296
	ds_read_b128 v[228:231], v136 offset:56320
	s_waitcnt vmcnt(8)
	s_waitcnt lgkmcnt(0)
	s_barrier
	s_waitcnt lgkmcnt(0)
	v_mfma_f32_16x16x32_bf16 v[16:19], v[4:7], v[56:59], v[140:143]
	v_mfma_f32_16x16x32_bf16 v[84:87], v[60:63], v[88:91], v[16:19]
	v_mfma_f32_16x16x32_bf16 v[16:19], v[168:171], v[56:59], v[144:147]
	v_mfma_f32_16x16x32_bf16 v[76:79], v[192:195], v[88:91], v[16:19]
	v_mfma_f32_16x16x32_bf16 v[16:19], v[4:7], v[172:175], v[148:151]
	v_mfma_f32_16x16x32_bf16 v[52:55], v[60:63], v[176:179], v[16:19]
	v_mfma_f32_16x16x32_bf16 v[16:19], v[168:171], v[172:175], v[152:155]
	v_mfma_f32_16x16x32_bf16 v[44:47], v[192:195], v[176:179], v[16:19]
	v_mfma_f32_16x16x32_bf16 v[16:19], v[4:7], v[204:207], v[156:159]
	v_mfma_f32_16x16x32_bf16 v[0:3], v[4:7], v[224:227], v[0:3]
	v_mfma_f32_16x16x32_bf16 v[20:23], v[60:63], v[220:223], v[16:19]
	v_mfma_f32_16x16x32_bf16 v[16:19], v[168:171], v[204:207], v[160:163]
	v_mfma_f32_16x16x32_bf16 v[4:7], v[60:63], v[228:231], v[0:3]
	v_mfma_f32_16x16x32_bf16 v[0:3], v[168:171], v[224:227], v[200:203]
	v_mfma_f32_16x16x32_bf16 v[16:19], v[192:195], v[220:223], v[16:19]
	v_mfma_f32_16x16x32_bf16 v[0:3], v[192:195], v[228:231], v[0:3]
	v_mfma_f32_16x16x32_bf16 v[8:11], v[196:199], v[56:59], v[8:11]
	v_mfma_f32_16x16x32_bf16 v[92:95], v[208:211], v[88:91], v[8:11]
	v_mfma_f32_16x16x32_bf16 v[8:11], v[212:215], v[56:59], v[12:15]
	v_mfma_f32_16x16x32_bf16 v[88:91], v[216:219], v[88:91], v[8:11]
	v_mfma_f32_16x16x32_bf16 v[8:11], v[196:199], v[172:175], v[24:27]
	v_mfma_f32_16x16x32_bf16 v[60:63], v[208:211], v[176:179], v[8:11]
	v_mfma_f32_16x16x32_bf16 v[8:11], v[212:215], v[172:175], v[28:31]
	v_mfma_f32_16x16x32_bf16 v[56:59], v[216:219], v[176:179], v[8:11]
	v_mfma_f32_16x16x32_bf16 v[8:11], v[196:199], v[204:207], v[180:183]
	v_mfma_f32_16x16x32_bf16 v[28:31], v[208:211], v[220:223], v[8:11]
	v_mfma_f32_16x16x32_bf16 v[8:11], v[212:215], v[204:207], v[184:187]
	v_mfma_f32_16x16x32_bf16 v[24:27], v[216:219], v[220:223], v[8:11]
	v_mfma_f32_16x16x32_bf16 v[8:11], v[196:199], v[224:227], v[188:191]
	v_mfma_f32_16x16x32_bf16 v[12:15], v[208:211], v[228:231], v[8:11]
	v_mfma_f32_16x16x32_bf16 v[8:11], v[212:215], v[224:227], v[164:167]
	v_mfma_f32_16x16x32_bf16 v[8:11], v[216:219], v[228:231], v[8:11]
	s_barrier
	s_and_b64 vcc, exec, s[8:9]
	s_cbranch_vccnz .LBB0_622
	s_barrier

; #define PG8_STAGE(bufoff, gbase, voff) do { _Pragma("unroll") for (int _i = 0; _i < 2; ++_i) \
;         __builtin_amdgcn_global_load_lds((const unsigned*)((const char*)(gbase) + (voff)[_i]), (PG8_LAS unsigned*)(lds + (bufoff) + ldsw + _i * 8192), 16, 0, 0); } while (0)
; #define PG8_LDA(dst, b, h) do { _Pragma("unroll") for (int m = 0; m < 4; ++m) _Pragma("unroll") for (int k = 0; k < 2; ++k) dst[m][k] = *(const PG8_LAS bf16x8*)(lds + PG8_SA(b, h) + aoff + m * 2048 + k * 1024); } while (0)
; #define PG8_LDB(dst, b, h) do { _Pragma("unroll") for (int n = 0; n < 2; ++n) _Pragma("unroll") for (int k = 0; k < 2; ++k) dst[n][k] = *(const PG8_LAS bf16x8*)(lds + PG8_SB(b, h) + boff + n * 2048 + k * 1024); } while (0)
; #define PG8_MMA(ai, bj, At, Bt) do { __builtin_amdgcn_s_setprio(1); _Pragma("unroll") for (int m = 0; m < 4; ++m) _Pragma("unroll") for (int n = 0; n < 2; ++n) _Pragma("unroll") for (int k = 0; k < 2; ++k) \
;         acc[ai][bj][m][n] = mma16<F16>(Bt[n][k], At[m][k], acc[ai][bj][m][n]); __builtin_amdgcn_s_setprio(0); } while (0)
; #define PG8_WAIT_V(n) asm volatile("s_waitcnt vmcnt(" #n ")" ::: "memory")
; #define PG8_WAIT_L(n) asm volatile("s_waitcnt lgkmcnt(" #n ")" ::: "memory")
; #define PG8_BAR __builtin_amdgcn_s_barrier()
; #define PG8_SCHED __builtin_amdgcn_sched_barrier(0)
; template <class Epi, class Sched, bool ALIGN_EPI = false, bool SP2 = false, bool F16 = false>
; __device__ __forceinline__ void gemm_phase(PG8_LAS unsigned char* lds, const Gemm g, const Sched& S, const Epi& E, const int wid_in) {
;     ...
;             const bool last = (t == nt - 2);
;             const char* a1 = cA + (size_t)(t + 1) * kstep;
;             const char* a2 = last ? nA : cA + (size_t)(t + 2) * kstep; const char* b2 = last ? nB : cB + (size_t)(t + 2) * kstep;
;             const char* a3 = a2 + kstep; const char* b3 = b2 + kstep;
;             if (last && has_next) S.a_ready(nxt);
;             if constexpr (SP2) {
;             PG8_LDB(B0, 0, 0); PG8_LDB(B1, 0, 1); PG8_SCHED; PG8_LDA(At, 0, 0); PG8_STAGE(PG8_SA(1, 1), a1 + hstep, voffA);
;             PG8_WAIT_V(8); PG8_WAIT_L(0); PG8_BAR; PG8_MMA(0, 0, At, B0); PG8_MMA(0, 1, At, B1); PG8_BAR; PG8_SCHED;
;             PG8_LDA(At, 0, 1); PG8_STAGE(PG8_SB(0, 0), b2, voffB); PG8_STAGE(PG8_SB(0, 1), b2 + hstep, voffB); PG8_STAGE(PG8_SA(0, 0), a2, voffA);
.LBB0_716:
	ds_read_b128 v[128:131], v189
	ds_read_b128 v[132:135], v189 offset:1024
	ds_read_b128 v[136:139], v189 offset:2048
	ds_read_b128 v[140:143], v189 offset:3072
	ds_read_b128 v[144:147], v190
	ds_read_b128 v[148:151], v190 offset:1024
	ds_read_b128 v[168:171], v190 offset:2048
	ds_read_b128 v[172:175], v190 offset:3072
	s_add_u32 s30, s28, 0x100
	s_addc_u32 s31, s29, 0
	s_cmp_eq_u32 s60, 40
	s_cselect_b32 s37, s11, s31
	s_cselect_b32 s36, s10, s30
	s_cselect_b32 s35, s27, s59
	s_cselect_b32 s34, s26, s43
	v_lshl_add_u64 v[184:185], s[28:29], 0, v[160:161]
	s_add_i32 m0, s74, 0xc000
	ds_read_b128 v[176:179], v191
	ds_read_b128 v[180:183], v191 offset:1024
	ds_read_b128 v[192:195], v191 offset:2048
	ds_read_b128 v[196:199], v191 offset:3072
	ds_read_b128 v[200:203], v191 offset:4096
	ds_read_b128 v[204:207], v191 offset:5120
	ds_read_b128 v[208:211], v191 offset:6144
	ds_read_b128 v[212:215], v191 offset:7168
	global_load_lds_dwordx4 v[184:185], off
	v_lshl_add_u64 v[184:185], s[28:29], 0, v[162:163]
	s_add_i32 m0, s74, 0xe000
	s_nop 0
	global_load_lds_dwordx4 v[184:185], off
	s_waitcnt vmcnt(8)
	s_waitcnt lgkmcnt(0)
	s_barrier
	s_waitcnt lgkmcnt(0)
	v_mfma_f32_16x16x32_bf16 v[124:127], v[128:131], v[176:179], v[124:127]
	v_mfma_f32_16x16x32_bf16 v[120:123], v[136:139], v[176:179], v[120:123]
	v_mfma_f32_16x16x32_bf16 v[108:111], v[128:131], v[192:195], v[108:111]
	v_mfma_f32_16x16x32_bf16 v[104:107], v[136:139], v[192:195], v[104:107]
	v_mfma_f32_16x16x32_bf16 v[92:95], v[128:131], v[200:203], v[92:95]
	v_mfma_f32_16x16x32_bf16 v[88:91], v[136:139], v[200:203], v[88:91]
	v_mfma_f32_16x16x32_bf16 v[76:79], v[128:131], v[208:211], v[76:79]
	v_mfma_f32_16x16x32_bf16 v[72:75], v[136:139], v[208:211], v[72:75]
	v_mfma_f32_16x16x32_bf16 v[124:127], v[132:135], v[180:183], v[124:127]
	v_mfma_f32_16x16x32_bf16 v[120:123], v[140:143], v[180:183], v[120:123]
	v_mfma_f32_16x16x32_bf16 v[108:111], v[132:135], v[196:199], v[108:111]
	v_mfma_f32_16x16x32_bf16 v[104:107], v[140:143], v[196:199], v[104:107]
	v_mfma_f32_16x16x32_bf16 v[92:95], v[132:135], v[204:207], v[92:95]
	v_mfma_f32_16x16x32_bf16 v[88:91], v[140:143], v[204:207], v[88:91]
	v_mfma_f32_16x16x32_bf16 v[76:79], v[132:135], v[212:215], v[76:79]
	v_mfma_f32_16x16x32_bf16 v[72:75], v[140:143], v[212:215], v[72:75]
	v_mfma_f32_16x16x32_bf16 v[116:119], v[144:147], v[176:179], v[116:119]
	v_mfma_f32_16x16x32_bf16 v[112:115], v[168:171], v[176:179], v[112:115]
	v_mfma_f32_16x16x32_bf16 v[100:103], v[144:147], v[192:195], v[100:103]
	v_mfma_f32_16x16x32_bf16 v[96:99], v[168:171], v[192:195], v[96:99]
	v_mfma_f32_16x16x32_bf16 v[84:87], v[144:147], v[200:203], v[84:87]
	v_mfma_f32_16x16x32_bf16 v[80:83], v[168:171], v[200:203], v[80:83]
	v_mfma_f32_16x16x32_bf16 v[68:71], v[144:147], v[208:211], v[68:71]
	v_mfma_f32_16x16x32_bf16 v[64:67], v[168:171], v[208:211], v[64:67]
	v_mfma_f32_16x16x32_bf16 v[116:119], v[148:151], v[180:183], v[116:119]
	v_mfma_f32_16x16x32_bf16 v[112:115], v[172:175], v[180:183], v[112:115]
	v_mfma_f32_16x16x32_bf16 v[100:103], v[148:151], v[196:199], v[100:103]
	v_mfma_f32_16x16x32_bf16 v[96:99], v[172:175], v[196:199], v[96:99]
	v_mfma_f32_16x16x32_bf16 v[84:87], v[148:151], v[204:207], v[84:87]
	v_mfma_f32_16x16x32_bf16 v[80:83], v[172:175], v[204:207], v[80:83]
	v_mfma_f32_16x16x32_bf16 v[68:71], v[148:151], v[212:215], v[68:71]
	v_mfma_f32_16x16x32_bf16 v[64:67], v[172:175], v[212:215], v[64:67]
	s_barrier
	s_add_i32 s28, s52, s68
	v_lshl_add_u64 v[184:185], s[34:35], 0, v[154:155]
	s_mov_b32 m0, s28
	s_nop 0
	global_load_lds_dwordx4 v[184:185], off
	s_add_i32 m0, s28, 0x2000
	s_add_u32 s28, s34, 0xb0000
	v_lshl_add_u64 v[216:217], s[34:35], 0, v[158:159]
	s_addc_u32 s29, s35, 0
	s_add_i32 s61, s53, s68
	global_load_lds_dwordx4 v[216:217], off
	v_lshl_add_u64 v[218:219], s[28:29], 0, v[154:155]
	s_mov_b32 m0, s61
	v_lshl_add_u64 v[220:221], s[36:37], 0, v[156:157]
	global_load_lds_dwordx4 v[218:219], off
	v_lshl_add_u64 v[218:219], s[28:29], 0, v[158:159]
	s_add_i32 m0, s61, 0x2000
	s_nop 0
	global_load_lds_dwordx4 v[218:219], off
	v_lshl_add_u64 v[218:219], s[36:37], 0, v[152:153]
	s_mov_b32 m0, s74
	s_nop 0
	global_load_lds_dwordx4 v[218:219], off
	s_mov_b32 m0, s45
	s_nop 0
	global_load_lds_dwordx4 v[220:221], off
	ds_read_b128 v[176:179], v191 offset:16384
	ds_read_b128 v[180:183], v191 offset:17408
	ds_read_b128 v[192:195], v191 offset:18432
	ds_read_b128 v[196:199], v191 offset:19456
	ds_read_b128 v[200:203], v191 offset:20480
	ds_read_b128 v[204:207], v191 offset:21504
	ds_read_b128 v[208:211], v191 offset:22528
	ds_read_b128 v[212:215], v191 offset:23552
	s_waitcnt vmcnt(8)
	s_waitcnt lgkmcnt(0)
	s_barrier
; #define PG8_STAGE(bufoff, gbase, voff) do { _Pragma("unroll") for (int _i = 0; _i < 2; ++_i) \
;         __builtin_amdgcn_global_load_lds((const unsigned*)((const char*)(gbase) + (voff)[_i]), (PG8_LAS unsigned*)(lds + (bufoff) + ldsw + _i * 8192), 16, 0, 0); } while (0)
; #define PG8_LDA(dst, b, h) do { _Pragma("unroll") for (int m = 0; m < 4; ++m) _Pragma("unroll") for (int k = 0; k < 2; ++k) dst[m][k] = *(const PG8_LAS bf16x8*)(lds + PG8_SA(b, h) + aoff + m * 2048 + k * 1024); } while (0)
; #define PG8_LDB(dst, b, h) do { _Pragma("unroll") for (int n = 0; n < 2; ++n) _Pragma("unroll") for (int k = 0; k < 2; ++k) dst[n][k] = *(const PG8_LAS bf16x8*)(lds + PG8_SB(b, h) + boff + n * 2048 + k * 1024); } while (0)
; #define PG8_MMA(ai, bj, At, Bt) do { __builtin_amdgcn_s_setprio(1); _Pragma("unroll") for (int m = 0; m < 4; ++m) _Pragma("unroll") for (int n = 0; n < 2; ++n) _Pragma("unroll") for (int k = 0; k < 2; ++k) \
;         acc[ai][bj][m][n] = mma16<F16>(Bt[n][k], At[m][k], acc[ai][bj][m][n]); __builtin_amdgcn_s_setprio(0); } while (0)
; #define PG8_WAIT_V(n) asm volatile("s_waitcnt vmcnt(" #n ")" ::: "memory")
; #define PG8_WAIT_L(n) asm volatile("s_waitcnt lgkmcnt(" #n ")" ::: "memory")
; #define PG8_BAR __builtin_amdgcn_s_barrier()
; #define PG8_SCHED __builtin_amdgcn_sched_barrier(0)
; template <class Epi, class Sched, bool ALIGN_EPI = false, bool SP2 = false, bool F16 = false>
; __device__ __forceinline__ void gemm_phase(PG8_LAS unsigned char* lds, const Gemm g, const Sched& S, const Epi& E, const int wid_in) {
;     ...
;             PG8_WAIT_V(8); PG8_WAIT_L(0); PG8_BAR; PG8_MMA(1, 0, At, B0); PG8_MMA(1, 1, At, B1); PG8_BAR; PG8_SCHED;
;             PG8_LDB(B0, 1, 0); PG8_LDB(B1, 1, 1); PG8_SCHED; PG8_LDA(At, 1, 0); PG8_STAGE(PG8_SA(0, 1), a2 + hstep, voffA);
;             PG8_WAIT_V(8); PG8_WAIT_L(0); PG8_BAR; PG8_MMA(0, 0, At, B0); PG8_MMA(0, 1, At, B1); PG8_BAR; PG8_SCHED;
	s_waitcnt lgkmcnt(0)
	v_mfma_f32_16x16x32_bf16 v[60:63], v[128:131], v[176:179], v[60:63]
	v_mfma_f32_16x16x32_bf16 v[56:59], v[136:139], v[176:179], v[56:59]
	v_mfma_f32_16x16x32_bf16 v[44:47], v[128:131], v[192:195], v[44:47]
	v_mfma_f32_16x16x32_bf16 v[40:43], v[136:139], v[192:195], v[40:43]
	v_mfma_f32_16x16x32_bf16 v[28:31], v[128:131], v[200:203], v[28:31]
	v_mfma_f32_16x16x32_bf16 v[24:27], v[136:139], v[200:203], v[24:27]
	v_mfma_f32_16x16x32_bf16 v[12:15], v[128:131], v[208:211], v[12:15]
	v_mfma_f32_16x16x32_bf16 v[8:11], v[136:139], v[208:211], v[8:11]
	v_mfma_f32_16x16x32_bf16 v[60:63], v[132:135], v[180:183], v[60:63]
	v_mfma_f32_16x16x32_bf16 v[56:59], v[140:143], v[180:183], v[56:59]
	v_mfma_f32_16x16x32_bf16 v[44:47], v[132:135], v[196:199], v[44:47]
	v_mfma_f32_16x16x32_bf16 v[40:43], v[140:143], v[196:199], v[40:43]
	v_mfma_f32_16x16x32_bf16 v[28:31], v[132:135], v[204:207], v[28:31]
	v_mfma_f32_16x16x32_bf16 v[24:27], v[140:143], v[204:207], v[24:27]
	v_mfma_f32_16x16x32_bf16 v[12:15], v[132:135], v[212:215], v[12:15]
	v_mfma_f32_16x16x32_bf16 v[8:11], v[140:143], v[212:215], v[8:11]
	v_mfma_f32_16x16x32_bf16 v[52:55], v[144:147], v[176:179], v[52:55]
	v_mfma_f32_16x16x32_bf16 v[48:51], v[168:171], v[176:179], v[48:51]
	v_mfma_f32_16x16x32_bf16 v[36:39], v[144:147], v[192:195], v[36:39]
	v_mfma_f32_16x16x32_bf16 v[32:35], v[168:171], v[192:195], v[32:35]
	v_mfma_f32_16x16x32_bf16 v[20:23], v[144:147], v[200:203], v[20:23]
	v_mfma_f32_16x16x32_bf16 v[16:19], v[168:171], v[200:203], v[16:19]
	v_mfma_f32_16x16x32_bf16 v[4:7], v[144:147], v[208:211], v[4:7]
	v_mfma_f32_16x16x32_bf16 v[0:3], v[168:171], v[208:211], v[0:3]
	v_mfma_f32_16x16x32_bf16 v[52:55], v[148:151], v[180:183], v[52:55]
	v_mfma_f32_16x16x32_bf16 v[48:51], v[172:175], v[180:183], v[48:51]
	v_mfma_f32_16x16x32_bf16 v[36:39], v[148:151], v[196:199], v[36:39]
	v_mfma_f32_16x16x32_bf16 v[32:35], v[172:175], v[196:199], v[32:35]
	v_mfma_f32_16x16x32_bf16 v[20:23], v[148:151], v[204:207], v[20:23]
	v_mfma_f32_16x16x32_bf16 v[16:19], v[172:175], v[204:207], v[16:19]
	v_mfma_f32_16x16x32_bf16 v[4:7], v[148:151], v[212:215], v[4:7]
	v_mfma_f32_16x16x32_bf16 v[0:3], v[172:175], v[212:215], v[0:3]
	s_barrier
	s_add_i32 s61, 0, 0x18000
	s_add_i32 s62, 0, 0x1c000
	v_add_u32_e32 v140, s61, v188
	v_add_u32_e32 v172, s62, v188
	s_add_u32 s28, s36, 0xb0000
	s_addc_u32 s29, s37, 0
	s_mov_b32 m0, s46
	v_lshl_add_u64 v[222:223], s[28:29], 0, v[152:153]
	global_load_lds_dwordx4 v[222:223], off
	v_lshl_add_u64 v[222:223], s[28:29], 0, v[156:157]
	s_mov_b32 m0, s47
	s_nop 0
	global_load_lds_dwordx4 v[222:223], off
	ds_read_b128 v[128:131], v140
	ds_read_b128 v[132:135], v140 offset:1024
	ds_read_b128 v[136:139], v140 offset:2048
	ds_read_b128 v[140:143], v140 offset:3072
	ds_read_b128 v[144:147], v172
	ds_read_b128 v[148:151], v172 offset:1024
	ds_read_b128 v[168:171], v172 offset:2048
	ds_read_b128 v[172:175], v172 offset:3072
	ds_read_b128 v[176:179], v191 offset:32768
	ds_read_b128 v[180:183], v191 offset:33792
	ds_read_b128 v[192:195], v191 offset:34816
	ds_read_b128 v[196:199], v191 offset:35840
	ds_read_b128 v[200:203], v191 offset:36864
	ds_read_b128 v[204:207], v191 offset:37888
	ds_read_b128 v[208:211], v191 offset:38912
	ds_read_b128 v[212:215], v191 offset:39936
	s_waitcnt vmcnt(8)
	s_waitcnt lgkmcnt(0)
	s_barrier
	s_waitcnt lgkmcnt(0)
	v_mfma_f32_16x16x32_bf16 v[124:127], v[128:131], v[176:179], v[124:127]
	v_mfma_f32_16x16x32_bf16 v[120:123], v[136:139], v[176:179], v[120:123]
	v_mfma_f32_16x16x32_bf16 v[108:111], v[128:131], v[192:195], v[108:111]
	v_mfma_f32_16x16x32_bf16 v[104:107], v[136:139], v[192:195], v[104:107]
	v_mfma_f32_16x16x32_bf16 v[92:95], v[128:131], v[200:203], v[92:95]
	v_mfma_f32_16x16x32_bf16 v[88:91], v[136:139], v[200:203], v[88:91]
	v_mfma_f32_16x16x32_bf16 v[76:79], v[128:131], v[208:211], v[76:79]
	v_mfma_f32_16x16x32_bf16 v[72:75], v[136:139], v[208:211], v[72:75]
	v_mfma_f32_16x16x32_bf16 v[124:127], v[132:135], v[180:183], v[124:127]
	v_mfma_f32_16x16x32_bf16 v[120:123], v[140:143], v[180:183], v[120:123]
	v_mfma_f32_16x16x32_bf16 v[108:111], v[132:135], v[196:199], v[108:111]
	v_mfma_f32_16x16x32_bf16 v[104:107], v[140:143], v[196:199], v[104:107]
	v_mfma_f32_16x16x32_bf16 v[92:95], v[132:135], v[204:207], v[92:95]
	v_mfma_f32_16x16x32_bf16 v[88:91], v[140:143], v[204:207], v[88:91]
	v_mfma_f32_16x16x32_bf16 v[76:79], v[132:135], v[212:215], v[76:79]
	v_mfma_f32_16x16x32_bf16 v[72:75], v[140:143], v[212:215], v[72:75]
	v_mfma_f32_16x16x32_bf16 v[116:119], v[144:147], v[176:179], v[116:119]
	v_mfma_f32_16x16x32_bf16 v[112:115], v[168:171], v[176:179], v[112:115]
	v_mfma_f32_16x16x32_bf16 v[100:103], v[144:147], v[192:195], v[100:103]
	v_mfma_f32_16x16x32_bf16 v[96:99], v[168:171], v[192:195], v[96:99]
	v_mfma_f32_16x16x32_bf16 v[84:87], v[144:147], v[200:203], v[84:87]
	v_mfma_f32_16x16x32_bf16 v[80:83], v[168:171], v[200:203], v[80:83]
	v_mfma_f32_16x16x32_bf16 v[68:71], v[144:147], v[208:211], v[68:71]
	v_mfma_f32_16x16x32_bf16 v[64:67], v[168:171], v[208:211], v[64:67]
	v_mfma_f32_16x16x32_bf16 v[116:119], v[148:151], v[180:183], v[116:119]
	v_mfma_f32_16x16x32_bf16 v[112:115], v[172:175], v[180:183], v[112:115]
	v_mfma_f32_16x16x32_bf16 v[100:103], v[148:151], v[196:199], v[100:103]
	v_mfma_f32_16x16x32_bf16 v[96:99], v[172:175], v[196:199], v[96:99]
	v_mfma_f32_16x16x32_bf16 v[84:87], v[148:151], v[204:207], v[84:87]
	v_mfma_f32_16x16x32_bf16 v[80:83], v[172:175], v[204:207], v[80:83]
	v_mfma_f32_16x16x32_bf16 v[68:71], v[148:151], v[212:215], v[68:71]
	v_mfma_f32_16x16x32_bf16 v[64:67], v[172:175], v[212:215], v[64:67]
	s_barrier
; #define PG8_STAGE(bufoff, gbase, voff) do { _Pragma("unroll") for (int _i = 0; _i < 2; ++_i) \
;         __builtin_amdgcn_global_load_lds((const unsigned*)((const char*)(gbase) + (voff)[_i]), (PG8_LAS unsigned*)(lds + (bufoff) + ldsw + _i * 8192), 16, 0, 0); } while (0)
; #define PG8_LDA(dst, b, h) do { _Pragma("unroll") for (int m = 0; m < 4; ++m) _Pragma("unroll") for (int k = 0; k < 2; ++k) dst[m][k] = *(const PG8_LAS bf16x8*)(lds + PG8_SA(b, h) + aoff + m * 2048 + k * 1024); } while (0)
; #define PG8_MMA(ai, bj, At, Bt) do { __builtin_amdgcn_s_setprio(1); _Pragma("unroll") for (int m = 0; m < 4; ++m) _Pragma("unroll") for (int n = 0; n < 2; ++n) _Pragma("unroll") for (int k = 0; k < 2; ++k) \
;         acc[ai][bj][m][n] = mma16<F16>(Bt[n][k], At[m][k], acc[ai][bj][m][n]); __builtin_amdgcn_s_setprio(0); } while (0)
; #define PG8_WAIT_V(n) asm volatile("s_waitcnt vmcnt(" #n ")" ::: "memory")
; #define PG8_WAIT_L(n) asm volatile("s_waitcnt lgkmcnt(" #n ")" ::: "memory")
; #define PG8_BAR __builtin_amdgcn_s_barrier()
; #define PG8_SCHED __builtin_amdgcn_sched_barrier(0)
; template <class Epi, class Sched, bool ALIGN_EPI = false, bool SP2 = false, bool F16 = false>
; __device__ __forceinline__ void gemm_phase(PG8_LAS unsigned char* lds, const Gemm g, const Sched& S, const Epi& E, const int wid_in) {
;     ...
;             PG8_LDA(At, 1, 1); PG8_STAGE(PG8_SB(1, 0), b3, voffB); PG8_STAGE(PG8_SB(1, 1), b3 + hstep, voffB); PG8_STAGE(PG8_SA(1, 0), a3, voffA);
;             PG8_WAIT_V(8); PG8_WAIT_L(0); PG8_BAR; PG8_MMA(1, 0, At, B0); PG8_MMA(1, 1, At, B1); PG8_BAR; PG8_SCHED;
;     ...
;         if constexpr (ALIGN_EPI) { if (wr == 0) PG8_BAR; }
	s_add_i32 s28, s61, s68
	v_lshl_add_u64 v[184:185], v[184:185], 0, s[24:25]
	s_mov_b32 m0, s28
	s_nop 0
	global_load_lds_dwordx4 v[184:185], off
	s_add_i32 m0, s28, 0x2000
	s_add_u32 s28, s34, 0xb0080
	v_lshl_add_u64 v[184:185], v[216:217], 0, s[24:25]
	s_addc_u32 s29, s35, 0
	s_add_i32 s34, s62, s68
	global_load_lds_dwordx4 v[184:185], off
	v_lshl_add_u64 v[184:185], s[28:29], 0, v[154:155]
	s_mov_b32 m0, s34
	s_nop 0
	global_load_lds_dwordx4 v[184:185], off
	v_lshl_add_u64 v[184:185], s[28:29], 0, v[158:159]
	s_add_i32 m0, s34, 0x2000
	s_nop 0
	global_load_lds_dwordx4 v[184:185], off
	v_lshl_add_u64 v[184:185], v[218:219], 0, s[24:25]
	s_mov_b32 m0, s75
	s_nop 0
	global_load_lds_dwordx4 v[184:185], off
	v_lshl_add_u64 v[184:185], v[220:221], 0, s[24:25]
	s_mov_b32 m0, s48
	s_nop 0
	global_load_lds_dwordx4 v[184:185], off
	ds_read_b128 v[176:179], v191 offset:49152
	ds_read_b128 v[180:183], v191 offset:50176
	ds_read_b128 v[192:195], v191 offset:51200
	ds_read_b128 v[196:199], v191 offset:52224
	ds_read_b128 v[200:203], v191 offset:53248
	ds_read_b128 v[204:207], v191 offset:54272
	ds_read_b128 v[208:211], v191 offset:55296
	ds_read_b128 v[212:215], v191 offset:56320
	s_waitcnt vmcnt(8)
	s_waitcnt lgkmcnt(0)
	s_barrier
	s_waitcnt lgkmcnt(0)
	v_mfma_f32_16x16x32_bf16 v[60:63], v[128:131], v[176:179], v[60:63]
	v_mfma_f32_16x16x32_bf16 v[56:59], v[136:139], v[176:179], v[56:59]
	v_mfma_f32_16x16x32_bf16 v[44:47], v[128:131], v[192:195], v[44:47]
	v_mfma_f32_16x16x32_bf16 v[40:43], v[136:139], v[192:195], v[40:43]
	v_mfma_f32_16x16x32_bf16 v[28:31], v[128:131], v[200:203], v[28:31]
	v_mfma_f32_16x16x32_bf16 v[24:27], v[136:139], v[200:203], v[24:27]
	v_mfma_f32_16x16x32_bf16 v[12:15], v[128:131], v[208:211], v[12:15]
	v_mfma_f32_16x16x32_bf16 v[8:11], v[136:139], v[208:211], v[8:11]
	v_mfma_f32_16x16x32_bf16 v[60:63], v[132:135], v[180:183], v[60:63]
	v_mfma_f32_16x16x32_bf16 v[56:59], v[140:143], v[180:183], v[56:59]
	v_mfma_f32_16x16x32_bf16 v[44:47], v[132:135], v[196:199], v[44:47]
	v_mfma_f32_16x16x32_bf16 v[40:43], v[140:143], v[196:199], v[40:43]
	v_mfma_f32_16x16x32_bf16 v[28:31], v[132:135], v[204:207], v[28:31]
	v_mfma_f32_16x16x32_bf16 v[24:27], v[140:143], v[204:207], v[24:27]
	v_mfma_f32_16x16x32_bf16 v[12:15], v[132:135], v[212:215], v[12:15]
	v_mfma_f32_16x16x32_bf16 v[8:11], v[140:143], v[212:215], v[8:11]
	v_mfma_f32_16x16x32_bf16 v[52:55], v[144:147], v[176:179], v[52:55]
	v_mfma_f32_16x16x32_bf16 v[48:51], v[168:171], v[176:179], v[48:51]
	v_mfma_f32_16x16x32_bf16 v[36:39], v[144:147], v[192:195], v[36:39]
	v_mfma_f32_16x16x32_bf16 v[32:35], v[168:171], v[192:195], v[32:35]
	v_mfma_f32_16x16x32_bf16 v[20:23], v[144:147], v[200:203], v[20:23]
	v_mfma_f32_16x16x32_bf16 v[16:19], v[168:171], v[200:203], v[16:19]
	v_mfma_f32_16x16x32_bf16 v[4:7], v[144:147], v[208:211], v[4:7]
	v_mfma_f32_16x16x32_bf16 v[0:3], v[168:171], v[208:211], v[0:3]
	v_mfma_f32_16x16x32_bf16 v[52:55], v[148:151], v[180:183], v[52:55]
	v_mfma_f32_16x16x32_bf16 v[48:51], v[172:175], v[180:183], v[48:51]
	v_mfma_f32_16x16x32_bf16 v[36:39], v[148:151], v[196:199], v[36:39]
	v_mfma_f32_16x16x32_bf16 v[32:35], v[172:175], v[196:199], v[32:35]
	v_mfma_f32_16x16x32_bf16 v[20:23], v[148:151], v[204:207], v[20:23]
	v_mfma_f32_16x16x32_bf16 v[16:19], v[172:175], v[204:207], v[16:19]
	v_mfma_f32_16x16x32_bf16 v[4:7], v[148:151], v[212:215], v[4:7]
	v_mfma_f32_16x16x32_bf16 v[0:3], v[172:175], v[212:215], v[0:3]
	s_barrier
	s_add_i32 s60, s60, 2
	s_add_u32 s43, s43, 0x100
	s_addc_u32 s59, s59, 0
	s_cmp_gt_u32 s60, 41
	s_mov_b64 s[28:29], s[30:31]
	s_cbranch_scc0 .LBB0_716
	s_and_b64 vcc, exec, s[16:17]
	s_cbranch_vccz .LBB0_719
	s_barrier

; #define PG8_STAGE(bufoff, gbase, voff) do { _Pragma("unroll") for (int _i = 0; _i < 2; ++_i) \
;         __builtin_amdgcn_global_load_lds((const unsigned*)((const char*)(gbase) + (voff)[_i]), (PG8_LAS unsigned*)(lds + (bufoff) + ldsw + _i * 8192), 16, 0, 0); } while (0)
; #define PG8_LDA(dst, b, h) do { _Pragma("unroll") for (int m = 0; m < 4; ++m) _Pragma("unroll") for (int k = 0; k < 2; ++k) dst[m][k] = *(const PG8_LAS bf16x8*)(lds + PG8_SA(b, h) + aoff + m * 2048 + k * 1024); } while (0)
; #define PG8_LDB(dst, b, h) do { _Pragma("unroll") for (int n = 0; n < 2; ++n) _Pragma("unroll") for (int k = 0; k < 2; ++k) dst[n][k] = *(const PG8_LAS bf16x8*)(lds + PG8_SB(b, h) + boff + n * 2048 + k * 1024); } while (0)
; #define PG8_MMA(ai, bj, At, Bt) do { __builtin_amdgcn_s_setprio(1); _Pragma("unroll") for (int m = 0; m < 4; ++m) _Pragma("unroll") for (int n = 0; n < 2; ++n) _Pragma("unroll") for (int k = 0; k < 2; ++k) \
;         acc[ai][bj][m][n] = mma16<F16>(Bt[n][k], At[m][k], acc[ai][bj][m][n]); __builtin_amdgcn_s_setprio(0); } while (0)
; #define PG8_WAIT_V(n) asm volatile("s_waitcnt vmcnt(" #n ")" ::: "memory")
; #define PG8_WAIT_L(n) asm volatile("s_waitcnt lgkmcnt(" #n ")" ::: "memory")
; #define PG8_BAR __builtin_amdgcn_s_barrier()
; #define PG8_SCHED __builtin_amdgcn_sched_barrier(0)
; template <class Epi, class Sched, bool ALIGN_EPI = false, bool SP2 = false, bool F16 = false>
; __device__ __forceinline__ void gemm_phase(PG8_LAS unsigned char* lds, const Gemm g, const Sched& S, const Epi& E, const int wid_in) {
;     ...
;             const bool last = (t == nt - 2);
;             const char* a1 = cA + (size_t)(t + 1) * kstep;
;             const char* a2 = last ? nA : cA + (size_t)(t + 2) * kstep; const char* b2 = last ? nB : cB + (size_t)(t + 2) * kstep;
;             const char* a3 = a2 + kstep; const char* b3 = b2 + kstep;
;             if (last && has_next) S.a_ready(nxt);
;             if constexpr (SP2) {
;             PG8_LDB(B0, 0, 0); PG8_LDB(B1, 0, 1); PG8_SCHED; PG8_LDA(At, 0, 0); PG8_STAGE(PG8_SA(1, 1), a1 + hstep, voffA);
;             PG8_WAIT_V(8); PG8_WAIT_L(0); PG8_BAR; PG8_MMA(0, 0, At, B0); PG8_MMA(0, 1, At, B1); PG8_BAR; PG8_SCHED;
;             PG8_LDA(At, 0, 1); PG8_STAGE(PG8_SB(0, 0), b2, voffB); PG8_STAGE(PG8_SB(0, 1), b2 + hstep, voffB); PG8_STAGE(PG8_SA(0, 0), a2, voffA);
.LBB0_812:
	ds_read_b128 v[112:115], v235
	ds_read_b128 v[116:119], v235 offset:1024
	ds_read_b128 v[128:131], v235 offset:2048
	ds_read_b128 v[132:135], v235 offset:3072
	ds_read_b128 v[144:147], v236
	ds_read_b128 v[148:151], v236 offset:1024
	ds_read_b128 v[152:155], v236 offset:2048
	ds_read_b128 v[156:159], v236 offset:3072
	s_add_u32 s43, s46, 0xfffc0080
	s_addc_u32 s45, s47, -1
	s_cmp_eq_u32 s42, 12
	s_cselect_b32 s51, s14, s45
	s_cselect_b32 s50, s15, s43
	s_cselect_b32 s49, s29, s41
	s_cselect_b32 s48, s31, s40
	v_lshl_add_u64 v[192:193], s[46:47], 0, v[204:205]
	s_add_i32 m0, s74, 0xc000
	ds_read_b128 v[160:163], v237
	ds_read_b128 v[164:167], v237 offset:1024
	ds_read_b128 v[168:171], v237 offset:2048
	ds_read_b128 v[172:175], v237 offset:3072
	ds_read_b128 v[176:179], v237 offset:4096
	ds_read_b128 v[180:183], v237 offset:5120
	ds_read_b128 v[184:187], v237 offset:6144
	ds_read_b128 v[188:191], v237 offset:7168
	global_load_lds_dwordx4 v[192:193], off
	v_lshl_add_u64 v[192:193], s[46:47], 0, v[206:207]
	s_add_i32 m0, s74, 0xe000
	s_nop 0
	global_load_lds_dwordx4 v[192:193], off
	s_waitcnt vmcnt(8)
	s_waitcnt lgkmcnt(0)
	s_barrier
	s_waitcnt lgkmcnt(0)
	v_mfma_f32_16x16x32_f16 v[140:143], v[112:115], v[160:163], v[140:143]
	v_mfma_f32_16x16x32_f16 v[136:139], v[128:131], v[160:163], v[136:139]
	v_mfma_f32_16x16x32_f16 v[108:111], v[112:115], v[168:171], v[108:111]
	v_mfma_f32_16x16x32_f16 v[104:107], v[128:131], v[168:171], v[104:107]
	v_mfma_f32_16x16x32_f16 v[92:95], v[112:115], v[176:179], v[92:95]
	v_mfma_f32_16x16x32_f16 v[88:91], v[128:131], v[176:179], v[88:91]
	v_mfma_f32_16x16x32_f16 v[76:79], v[112:115], v[184:187], v[76:79]
	v_mfma_f32_16x16x32_f16 v[72:75], v[128:131], v[184:187], v[72:75]
	v_mfma_f32_16x16x32_f16 v[140:143], v[116:119], v[164:167], v[140:143]
	v_mfma_f32_16x16x32_f16 v[136:139], v[132:135], v[164:167], v[136:139]
	v_mfma_f32_16x16x32_f16 v[108:111], v[116:119], v[172:175], v[108:111]
	v_mfma_f32_16x16x32_f16 v[104:107], v[132:135], v[172:175], v[104:107]
	v_mfma_f32_16x16x32_f16 v[92:95], v[116:119], v[180:183], v[92:95]
	v_mfma_f32_16x16x32_f16 v[88:91], v[132:135], v[180:183], v[88:91]
	v_mfma_f32_16x16x32_f16 v[76:79], v[116:119], v[188:191], v[76:79]
	v_mfma_f32_16x16x32_f16 v[72:75], v[132:135], v[188:191], v[72:75]
	v_mfma_f32_16x16x32_f16 v[124:127], v[144:147], v[160:163], v[124:127]
	v_mfma_f32_16x16x32_f16 v[120:123], v[152:155], v[160:163], v[120:123]
	v_mfma_f32_16x16x32_f16 v[100:103], v[144:147], v[168:171], v[100:103]
	v_mfma_f32_16x16x32_f16 v[96:99], v[152:155], v[168:171], v[96:99]
	v_mfma_f32_16x16x32_f16 v[84:87], v[144:147], v[176:179], v[84:87]
	v_mfma_f32_16x16x32_f16 v[80:83], v[152:155], v[176:179], v[80:83]
	v_mfma_f32_16x16x32_f16 v[68:71], v[144:147], v[184:187], v[68:71]
	v_mfma_f32_16x16x32_f16 v[64:67], v[152:155], v[184:187], v[64:67]
	v_mfma_f32_16x16x32_f16 v[124:127], v[148:151], v[164:167], v[124:127]
	v_mfma_f32_16x16x32_f16 v[120:123], v[156:159], v[164:167], v[120:123]
	v_mfma_f32_16x16x32_f16 v[100:103], v[148:151], v[172:175], v[100:103]
	v_mfma_f32_16x16x32_f16 v[96:99], v[156:159], v[172:175], v[96:99]
	v_mfma_f32_16x16x32_f16 v[84:87], v[148:151], v[180:183], v[84:87]
	v_mfma_f32_16x16x32_f16 v[80:83], v[156:159], v[180:183], v[80:83]
	v_mfma_f32_16x16x32_f16 v[68:71], v[148:151], v[188:191], v[68:71]
	v_mfma_f32_16x16x32_f16 v[64:67], v[156:159], v[188:191], v[64:67]
	s_barrier
	s_add_i32 s43, s64, s68
	v_lshl_add_u64 v[192:193], s[48:49], 0, v[198:199]
	s_mov_b32 m0, s43
	s_nop 0
	global_load_lds_dwordx4 v[192:193], off
	s_add_i32 m0, s43, 0x2000
	s_add_u32 s86, s48, 0x40000
	v_lshl_add_u64 v[194:195], s[48:49], 0, v[202:203]
	s_addc_u32 s87, s49, 0
	s_add_i32 s43, s65, s68
	global_load_lds_dwordx4 v[194:195], off
	v_lshl_add_u64 v[212:213], s[86:87], 0, v[198:199]
	s_mov_b32 m0, s43
	v_lshl_add_u64 v[214:215], s[50:51], 0, v[200:201]
	global_load_lds_dwordx4 v[212:213], off
	v_lshl_add_u64 v[212:213], s[86:87], 0, v[202:203]
	s_add_i32 m0, s43, 0x2000
	s_nop 0
	global_load_lds_dwordx4 v[212:213], off
	v_lshl_add_u64 v[212:213], s[50:51], 0, v[196:197]
	s_mov_b32 m0, s74
	s_nop 0
	global_load_lds_dwordx4 v[212:213], off
	s_mov_b32 m0, s55
	s_nop 0
	global_load_lds_dwordx4 v[214:215], off
	ds_read_b128 v[160:163], v237 offset:16384
	ds_read_b128 v[164:167], v237 offset:17408
	ds_read_b128 v[168:171], v237 offset:18432
	ds_read_b128 v[172:175], v237 offset:19456
	ds_read_b128 v[176:179], v237 offset:20480
	ds_read_b128 v[180:183], v237 offset:21504
	ds_read_b128 v[184:187], v237 offset:22528
	ds_read_b128 v[188:191], v237 offset:23552
	s_waitcnt vmcnt(8)
	s_waitcnt lgkmcnt(0)
	s_barrier
; #define PG8_STAGE(bufoff, gbase, voff) do { _Pragma("unroll") for (int _i = 0; _i < 2; ++_i) \
;         __builtin_amdgcn_global_load_lds((const unsigned*)((const char*)(gbase) + (voff)[_i]), (PG8_LAS unsigned*)(lds + (bufoff) + ldsw + _i * 8192), 16, 0, 0); } while (0)
; #define PG8_LDA(dst, b, h) do { _Pragma("unroll") for (int m = 0; m < 4; ++m) _Pragma("unroll") for (int k = 0; k < 2; ++k) dst[m][k] = *(const PG8_LAS bf16x8*)(lds + PG8_SA(b, h) + aoff + m * 2048 + k * 1024); } while (0)
; #define PG8_LDB(dst, b, h) do { _Pragma("unroll") for (int n = 0; n < 2; ++n) _Pragma("unroll") for (int k = 0; k < 2; ++k) dst[n][k] = *(const PG8_LAS bf16x8*)(lds + PG8_SB(b, h) + boff + n * 2048 + k * 1024); } while (0)
; #define PG8_MMA(ai, bj, At, Bt) do { __builtin_amdgcn_s_setprio(1); _Pragma("unroll") for (int m = 0; m < 4; ++m) _Pragma("unroll") for (int n = 0; n < 2; ++n) _Pragma("unroll") for (int k = 0; k < 2; ++k) \
;         acc[ai][bj][m][n] = mma16<F16>(Bt[n][k], At[m][k], acc[ai][bj][m][n]); __builtin_amdgcn_s_setprio(0); } while (0)
; #define PG8_WAIT_V(n) asm volatile("s_waitcnt vmcnt(" #n ")" ::: "memory")
; #define PG8_WAIT_L(n) asm volatile("s_waitcnt lgkmcnt(" #n ")" ::: "memory")
; #define PG8_BAR __builtin_amdgcn_s_barrier()
; #define PG8_SCHED __builtin_amdgcn_sched_barrier(0)
; template <class Epi, class Sched, bool ALIGN_EPI = false, bool SP2 = false, bool F16 = false>
; __device__ __forceinline__ void gemm_phase(PG8_LAS unsigned char* lds, const Gemm g, const Sched& S, const Epi& E, const int wid_in) {
;     ...
;             PG8_WAIT_V(8); PG8_WAIT_L(0); PG8_BAR; PG8_MMA(1, 0, At, B0); PG8_MMA(1, 1, At, B1); PG8_BAR; PG8_SCHED;
;             PG8_LDB(B0, 1, 0); PG8_LDB(B1, 1, 1); PG8_SCHED; PG8_LDA(At, 1, 0); PG8_STAGE(PG8_SA(0, 1), a2 + hstep, voffA);
;             PG8_WAIT_V(8); PG8_WAIT_L(0); PG8_BAR; PG8_MMA(0, 0, At, B0); PG8_MMA(0, 1, At, B1); PG8_BAR; PG8_SCHED;
	s_waitcnt lgkmcnt(0)
	v_mfma_f32_16x16x32_f16 v[60:63], v[112:115], v[160:163], v[60:63]
	v_mfma_f32_16x16x32_f16 v[56:59], v[128:131], v[160:163], v[56:59]
	v_mfma_f32_16x16x32_f16 v[44:47], v[112:115], v[168:171], v[44:47]
	v_mfma_f32_16x16x32_f16 v[40:43], v[128:131], v[168:171], v[40:43]
	v_mfma_f32_16x16x32_f16 v[28:31], v[112:115], v[176:179], v[28:31]
	v_mfma_f32_16x16x32_f16 v[24:27], v[128:131], v[176:179], v[24:27]
	v_mfma_f32_16x16x32_f16 v[12:15], v[112:115], v[184:187], v[12:15]
	v_mfma_f32_16x16x32_f16 v[8:11], v[128:131], v[184:187], v[8:11]
	v_mfma_f32_16x16x32_f16 v[60:63], v[116:119], v[164:167], v[60:63]
	v_mfma_f32_16x16x32_f16 v[56:59], v[132:135], v[164:167], v[56:59]
	v_mfma_f32_16x16x32_f16 v[44:47], v[116:119], v[172:175], v[44:47]
	v_mfma_f32_16x16x32_f16 v[40:43], v[132:135], v[172:175], v[40:43]
	v_mfma_f32_16x16x32_f16 v[28:31], v[116:119], v[180:183], v[28:31]
	v_mfma_f32_16x16x32_f16 v[24:27], v[132:135], v[180:183], v[24:27]
	v_mfma_f32_16x16x32_f16 v[12:15], v[116:119], v[188:191], v[12:15]
	v_mfma_f32_16x16x32_f16 v[8:11], v[132:135], v[188:191], v[8:11]
	v_mfma_f32_16x16x32_f16 v[52:55], v[144:147], v[160:163], v[52:55]
	v_mfma_f32_16x16x32_f16 v[48:51], v[152:155], v[160:163], v[48:51]
	v_mfma_f32_16x16x32_f16 v[36:39], v[144:147], v[168:171], v[36:39]
	v_mfma_f32_16x16x32_f16 v[32:35], v[152:155], v[168:171], v[32:35]
	v_mfma_f32_16x16x32_f16 v[20:23], v[144:147], v[176:179], v[20:23]
	v_mfma_f32_16x16x32_f16 v[16:19], v[152:155], v[176:179], v[16:19]
	v_mfma_f32_16x16x32_f16 v[4:7], v[144:147], v[184:187], v[4:7]
	v_mfma_f32_16x16x32_f16 v[0:3], v[152:155], v[184:187], v[0:3]
	v_mfma_f32_16x16x32_f16 v[52:55], v[148:151], v[164:167], v[52:55]
	v_mfma_f32_16x16x32_f16 v[48:51], v[156:159], v[164:167], v[48:51]
	v_mfma_f32_16x16x32_f16 v[36:39], v[148:151], v[172:175], v[36:39]
	v_mfma_f32_16x16x32_f16 v[32:35], v[156:159], v[172:175], v[32:35]
	v_mfma_f32_16x16x32_f16 v[20:23], v[148:151], v[180:183], v[20:23]
	v_mfma_f32_16x16x32_f16 v[16:19], v[156:159], v[180:183], v[16:19]
	v_mfma_f32_16x16x32_f16 v[4:7], v[148:151], v[188:191], v[4:7]
	v_mfma_f32_16x16x32_f16 v[0:3], v[156:159], v[188:191], v[0:3]
	s_barrier
	s_add_i32 s43, 0, 0x18000
	s_add_i32 s45, 0, 0x1c000
	v_add_u32_e32 v132, s43, v234
	v_add_u32_e32 v156, s45, v234
	s_add_u32 s50, s50, 0x40000
	s_addc_u32 s51, s51, 0
	s_mov_b32 m0, s58
	v_lshl_add_u64 v[216:217], s[50:51], 0, v[196:197]
	global_load_lds_dwordx4 v[216:217], off
	v_lshl_add_u64 v[216:217], s[50:51], 0, v[200:201]
	s_mov_b32 m0, s59
	s_nop 0
	global_load_lds_dwordx4 v[216:217], off
	ds_read_b128 v[112:115], v132
	ds_read_b128 v[116:119], v132 offset:1024
	ds_read_b128 v[128:131], v132 offset:2048
	ds_read_b128 v[132:135], v132 offset:3072
	ds_read_b128 v[144:147], v156
	ds_read_b128 v[148:151], v156 offset:1024
	ds_read_b128 v[152:155], v156 offset:2048
	ds_read_b128 v[156:159], v156 offset:3072
	ds_read_b128 v[160:163], v237 offset:32768
	ds_read_b128 v[164:167], v237 offset:33792
	ds_read_b128 v[168:171], v237 offset:34816
	ds_read_b128 v[172:175], v237 offset:35840
	ds_read_b128 v[176:179], v237 offset:36864
	ds_read_b128 v[180:183], v237 offset:37888
	ds_read_b128 v[184:187], v237 offset:38912
	ds_read_b128 v[188:191], v237 offset:39936
	s_waitcnt vmcnt(8)
	s_waitcnt lgkmcnt(0)
	s_barrier
	s_waitcnt lgkmcnt(0)
	v_mfma_f32_16x16x32_f16 v[140:143], v[112:115], v[160:163], v[140:143]
	v_mfma_f32_16x16x32_f16 v[136:139], v[128:131], v[160:163], v[136:139]
	v_mfma_f32_16x16x32_f16 v[108:111], v[112:115], v[168:171], v[108:111]
	v_mfma_f32_16x16x32_f16 v[104:107], v[128:131], v[168:171], v[104:107]
	v_mfma_f32_16x16x32_f16 v[92:95], v[112:115], v[176:179], v[92:95]
	v_mfma_f32_16x16x32_f16 v[88:91], v[128:131], v[176:179], v[88:91]
	v_mfma_f32_16x16x32_f16 v[76:79], v[112:115], v[184:187], v[76:79]
	v_mfma_f32_16x16x32_f16 v[72:75], v[128:131], v[184:187], v[72:75]
	v_mfma_f32_16x16x32_f16 v[140:143], v[116:119], v[164:167], v[140:143]
	v_mfma_f32_16x16x32_f16 v[136:139], v[132:135], v[164:167], v[136:139]
	v_mfma_f32_16x16x32_f16 v[108:111], v[116:119], v[172:175], v[108:111]
	v_mfma_f32_16x16x32_f16 v[104:107], v[132:135], v[172:175], v[104:107]
	v_mfma_f32_16x16x32_f16 v[92:95], v[116:119], v[180:183], v[92:95]
	v_mfma_f32_16x16x32_f16 v[88:91], v[132:135], v[180:183], v[88:91]
	v_mfma_f32_16x16x32_f16 v[76:79], v[116:119], v[188:191], v[76:79]
	v_mfma_f32_16x16x32_f16 v[72:75], v[132:135], v[188:191], v[72:75]
	v_mfma_f32_16x16x32_f16 v[124:127], v[144:147], v[160:163], v[124:127]
	v_mfma_f32_16x16x32_f16 v[120:123], v[152:155], v[160:163], v[120:123]
	v_mfma_f32_16x16x32_f16 v[100:103], v[144:147], v[168:171], v[100:103]
	v_mfma_f32_16x16x32_f16 v[96:99], v[152:155], v[168:171], v[96:99]
	v_mfma_f32_16x16x32_f16 v[84:87], v[144:147], v[176:179], v[84:87]
	v_mfma_f32_16x16x32_f16 v[80:83], v[152:155], v[176:179], v[80:83]
	v_mfma_f32_16x16x32_f16 v[68:71], v[144:147], v[184:187], v[68:71]
	v_mfma_f32_16x16x32_f16 v[64:67], v[152:155], v[184:187], v[64:67]
	v_mfma_f32_16x16x32_f16 v[124:127], v[148:151], v[164:167], v[124:127]
	v_mfma_f32_16x16x32_f16 v[120:123], v[156:159], v[164:167], v[120:123]
	v_mfma_f32_16x16x32_f16 v[100:103], v[148:151], v[172:175], v[100:103]
	v_mfma_f32_16x16x32_f16 v[96:99], v[156:159], v[172:175], v[96:99]
	v_mfma_f32_16x16x32_f16 v[84:87], v[148:151], v[180:183], v[84:87]
	v_mfma_f32_16x16x32_f16 v[80:83], v[156:159], v[180:183], v[80:83]
	v_mfma_f32_16x16x32_f16 v[68:71], v[148:151], v[188:191], v[68:71]
	v_mfma_f32_16x16x32_f16 v[64:67], v[156:159], v[188:191], v[64:67]
	s_barrier
; #define PG8_STAGE(bufoff, gbase, voff) do { _Pragma("unroll") for (int _i = 0; _i < 2; ++_i) \
;         __builtin_amdgcn_global_load_lds((const unsigned*)((const char*)(gbase) + (voff)[_i]), (PG8_LAS unsigned*)(lds + (bufoff) + ldsw + _i * 8192), 16, 0, 0); } while (0)
; #define PG8_LDA(dst, b, h) do { _Pragma("unroll") for (int m = 0; m < 4; ++m) _Pragma("unroll") for (int k = 0; k < 2; ++k) dst[m][k] = *(const PG8_LAS bf16x8*)(lds + PG8_SA(b, h) + aoff + m * 2048 + k * 1024); } while (0)
; #define PG8_MMA(ai, bj, At, Bt) do { __builtin_amdgcn_s_setprio(1); _Pragma("unroll") for (int m = 0; m < 4; ++m) _Pragma("unroll") for (int n = 0; n < 2; ++n) _Pragma("unroll") for (int k = 0; k < 2; ++k) \
;         acc[ai][bj][m][n] = mma16<F16>(Bt[n][k], At[m][k], acc[ai][bj][m][n]); __builtin_amdgcn_s_setprio(0); } while (0)
; #define PG8_WAIT_V(n) asm volatile("s_waitcnt vmcnt(" #n ")" ::: "memory")
; #define PG8_WAIT_L(n) asm volatile("s_waitcnt lgkmcnt(" #n ")" ::: "memory")
; #define PG8_BAR __builtin_amdgcn_s_barrier()
; #define PG8_SCHED __builtin_amdgcn_sched_barrier(0)
; template <class Epi, class Sched, bool ALIGN_EPI = false, bool SP2 = false, bool F16 = false>
; __device__ __forceinline__ void gemm_phase(PG8_LAS unsigned char* lds, const Gemm g, const Sched& S, const Epi& E, const int wid_in) {
;     ...
;             PG8_LDA(At, 1, 1); PG8_STAGE(PG8_SB(1, 0), b3, voffB); PG8_STAGE(PG8_SB(1, 1), b3 + hstep, voffB); PG8_STAGE(PG8_SA(1, 0), a3, voffA);
;             PG8_WAIT_V(8); PG8_WAIT_L(0); PG8_BAR; PG8_MMA(1, 0, At, B0); PG8_MMA(1, 1, At, B1); PG8_BAR; PG8_SCHED;
;     ...
;         if constexpr (ALIGN_EPI) { if (wr == 0) PG8_BAR; }
	s_add_i32 s43, s43, s68
	v_lshl_add_u64 v[192:193], v[192:193], 0, s[26:27]
	s_mov_b32 m0, s43
	s_nop 0
	global_load_lds_dwordx4 v[192:193], off
	s_add_i32 m0, s43, 0x2000
	s_add_u32 s48, s48, 0x40080
	v_lshl_add_u64 v[192:193], v[194:195], 0, s[26:27]
	s_addc_u32 s49, s49, 0
	s_add_i32 s43, s45, s68
	global_load_lds_dwordx4 v[192:193], off
	v_lshl_add_u64 v[192:193], s[48:49], 0, v[198:199]
	s_mov_b32 m0, s43
	s_nop 0
	global_load_lds_dwordx4 v[192:193], off
	v_lshl_add_u64 v[192:193], s[48:49], 0, v[202:203]
	s_add_i32 m0, s43, 0x2000
	s_nop 0
	global_load_lds_dwordx4 v[192:193], off
	v_lshl_add_u64 v[192:193], v[212:213], 0, s[26:27]
	s_mov_b32 m0, s75
	s_nop 0
	global_load_lds_dwordx4 v[192:193], off
	v_lshl_add_u64 v[192:193], v[214:215], 0, s[26:27]
	s_mov_b32 m0, s60
	s_nop 0
	global_load_lds_dwordx4 v[192:193], off
	ds_read_b128 v[160:163], v237 offset:49152
	ds_read_b128 v[164:167], v237 offset:50176
	ds_read_b128 v[168:171], v237 offset:51200
	ds_read_b128 v[172:175], v237 offset:52224
	ds_read_b128 v[176:179], v237 offset:53248
	ds_read_b128 v[180:183], v237 offset:54272
	ds_read_b128 v[184:187], v237 offset:55296
	ds_read_b128 v[188:191], v237 offset:56320
	s_waitcnt vmcnt(8)
	s_waitcnt lgkmcnt(0)
	s_barrier
	s_waitcnt lgkmcnt(0)
	v_mfma_f32_16x16x32_f16 v[60:63], v[112:115], v[160:163], v[60:63]
	v_mfma_f32_16x16x32_f16 v[56:59], v[128:131], v[160:163], v[56:59]
	v_mfma_f32_16x16x32_f16 v[44:47], v[112:115], v[168:171], v[44:47]
	v_mfma_f32_16x16x32_f16 v[40:43], v[128:131], v[168:171], v[40:43]
	v_mfma_f32_16x16x32_f16 v[28:31], v[112:115], v[176:179], v[28:31]
	v_mfma_f32_16x16x32_f16 v[24:27], v[128:131], v[176:179], v[24:27]
	v_mfma_f32_16x16x32_f16 v[12:15], v[112:115], v[184:187], v[12:15]
	v_mfma_f32_16x16x32_f16 v[8:11], v[128:131], v[184:187], v[8:11]
	v_mfma_f32_16x16x32_f16 v[60:63], v[116:119], v[164:167], v[60:63]
	v_mfma_f32_16x16x32_f16 v[56:59], v[132:135], v[164:167], v[56:59]
	v_mfma_f32_16x16x32_f16 v[44:47], v[116:119], v[172:175], v[44:47]
	v_mfma_f32_16x16x32_f16 v[40:43], v[132:135], v[172:175], v[40:43]
	v_mfma_f32_16x16x32_f16 v[28:31], v[116:119], v[180:183], v[28:31]
	v_mfma_f32_16x16x32_f16 v[24:27], v[132:135], v[180:183], v[24:27]
	v_mfma_f32_16x16x32_f16 v[12:15], v[116:119], v[188:191], v[12:15]
	v_mfma_f32_16x16x32_f16 v[8:11], v[132:135], v[188:191], v[8:11]
	v_mfma_f32_16x16x32_f16 v[52:55], v[144:147], v[160:163], v[52:55]
	v_mfma_f32_16x16x32_f16 v[48:51], v[152:155], v[160:163], v[48:51]
	v_mfma_f32_16x16x32_f16 v[36:39], v[144:147], v[168:171], v[36:39]
	v_mfma_f32_16x16x32_f16 v[32:35], v[152:155], v[168:171], v[32:35]
	v_mfma_f32_16x16x32_f16 v[20:23], v[144:147], v[176:179], v[20:23]
	v_mfma_f32_16x16x32_f16 v[16:19], v[152:155], v[176:179], v[16:19]
	v_mfma_f32_16x16x32_f16 v[4:7], v[144:147], v[184:187], v[4:7]
	v_mfma_f32_16x16x32_f16 v[0:3], v[152:155], v[184:187], v[0:3]
	v_mfma_f32_16x16x32_f16 v[52:55], v[148:151], v[164:167], v[52:55]
	v_mfma_f32_16x16x32_f16 v[48:51], v[156:159], v[164:167], v[48:51]
	v_mfma_f32_16x16x32_f16 v[36:39], v[148:151], v[172:175], v[36:39]
	v_mfma_f32_16x16x32_f16 v[32:35], v[156:159], v[172:175], v[32:35]
	v_mfma_f32_16x16x32_f16 v[20:23], v[148:151], v[180:183], v[20:23]
	v_mfma_f32_16x16x32_f16 v[16:19], v[156:159], v[180:183], v[16:19]
	v_mfma_f32_16x16x32_f16 v[4:7], v[148:151], v[188:191], v[4:7]
	v_mfma_f32_16x16x32_f16 v[0:3], v[156:159], v[188:191], v[0:3]
	s_barrier
	s_add_i32 s42, s42, 2
	s_add_u32 s46, s46, 0x100
	s_addc_u32 s47, s47, 0
	s_add_u32 s40, s40, 0x100
	s_addc_u32 s41, s41, 0
	s_cmp_gt_u32 s42, 13
	s_cbranch_scc0 .LBB0_812
	s_and_b64 vcc, exec, s[16:17]
	s_cbranch_vccz .LBB0_815
	s_barrier

; #define PG8_STAGE(bufoff, gbase, voff) do { _Pragma("unroll") for (int _i = 0; _i < 2; ++_i) \
;         __builtin_amdgcn_global_load_lds((const unsigned*)((const char*)(gbase) + (voff)[_i]), (PG8_LAS unsigned*)(lds + (bufoff) + ldsw + _i * 8192), 16, 0, 0); } while (0)
; #define PG8_LDA(dst, b, h) do { _Pragma("unroll") for (int m = 0; m < 4; ++m) _Pragma("unroll") for (int k = 0; k < 2; ++k) dst[m][k] = *(const PG8_LAS bf16x8*)(lds + PG8_SA(b, h) + aoff + m * 2048 + k * 1024); } while (0)
; #define PG8_LDB(dst, b, h) do { _Pragma("unroll") for (int n = 0; n < 2; ++n) _Pragma("unroll") for (int k = 0; k < 2; ++k) dst[n][k] = *(const PG8_LAS bf16x8*)(lds + PG8_SB(b, h) + boff + n * 2048 + k * 1024); } while (0)
; #define PG8_MMA(ai, bj, At, Bt) do { __builtin_amdgcn_s_setprio(1); _Pragma("unroll") for (int m = 0; m < 4; ++m) _Pragma("unroll") for (int n = 0; n < 2; ++n) _Pragma("unroll") for (int k = 0; k < 2; ++k) \
;         acc[ai][bj][m][n] = mma16<F16>(Bt[n][k], At[m][k], acc[ai][bj][m][n]); __builtin_amdgcn_s_setprio(0); } while (0)
; #define PG8_WAIT_V(n) asm volatile("s_waitcnt vmcnt(" #n ")" ::: "memory")
; #define PG8_WAIT_L(n) asm volatile("s_waitcnt lgkmcnt(" #n ")" ::: "memory")
; #define PG8_BAR __builtin_amdgcn_s_barrier()
; #define PG8_SCHED __builtin_amdgcn_sched_barrier(0)
; template <class Epi, class Sched, bool ALIGN_EPI = false, bool SP2 = false, bool F16 = false>
; __device__ __forceinline__ void gemm_phase(PG8_LAS unsigned char* lds, const Gemm g, const Sched& S, const Epi& E, const int wid_in) {
;     ...
;             const bool last = (t == nt - 2);
;             const char* a1 = cA + (size_t)(t + 1) * kstep;
;             const char* a2 = last ? nA : cA + (size_t)(t + 2) * kstep; const char* b2 = last ? nB : cB + (size_t)(t + 2) * kstep;
;             const char* a3 = a2 + kstep; const char* b3 = b2 + kstep;
;             if (last && has_next) S.a_ready(nxt);
;             if constexpr (SP2) {
;             PG8_LDB(B0, 0, 0); PG8_LDB(B1, 0, 1); PG8_SCHED; PG8_LDA(At, 0, 0); PG8_STAGE(PG8_SA(1, 1), a1 + hstep, voffA);
;             PG8_WAIT_V(8); PG8_WAIT_L(0); PG8_BAR; PG8_MMA(0, 0, At, B0); PG8_MMA(0, 1, At, B1); PG8_BAR; PG8_SCHED;
;             PG8_LDA(At, 0, 1); PG8_STAGE(PG8_SB(0, 0), b2, voffB); PG8_STAGE(PG8_SB(0, 1), b2 + hstep, voffB); PG8_STAGE(PG8_SA(0, 0), a2, voffA);
.LBB0_902:
	ds_read_b128 v[128:131], v183
	ds_read_b128 v[132:135], v183 offset:1024
	ds_read_b128 v[136:139], v183 offset:2048
	ds_read_b128 v[140:143], v183 offset:3072
	ds_read_b128 v[144:147], v184
	ds_read_b128 v[148:151], v184 offset:1024
	ds_read_b128 v[152:155], v184 offset:2048
	ds_read_b128 v[174:177], v184 offset:3072
	s_add_u32 s48, s46, 0xfffc0080
	s_addc_u32 s49, s47, -1
	s_cmp_eq_u32 s52, 12
	s_cselect_b32 s51, s11, s49
	s_cselect_b32 s50, s13, s48
	s_cselect_b32 s49, s31, s43
	s_cselect_b32 s48, s35, s42
	v_lshl_add_u64 v[178:179], s[46:47], 0, v[166:167]
	s_add_i32 m0, s74, 0xc000
	ds_read_b128 v[188:191], v185
	ds_read_b128 v[192:195], v185 offset:1024
	ds_read_b128 v[196:199], v185 offset:2048
	ds_read_b128 v[200:203], v185 offset:3072
	ds_read_b128 v[204:207], v185 offset:4096
	ds_read_b128 v[208:211], v185 offset:5120
	ds_read_b128 v[212:215], v185 offset:6144
	ds_read_b128 v[216:219], v185 offset:7168
	global_load_lds_dwordx4 v[178:179], off
	v_lshl_add_u64 v[178:179], s[46:47], 0, v[168:169]
	s_add_i32 m0, s74, 0xe000
	s_nop 0
	global_load_lds_dwordx4 v[178:179], off
	s_waitcnt vmcnt(8)
	s_waitcnt lgkmcnt(0)
	s_barrier
	s_waitcnt lgkmcnt(0)
	v_mfma_f32_16x16x32_f16 v[124:127], v[128:131], v[188:191], v[124:127]
	v_mfma_f32_16x16x32_f16 v[120:123], v[136:139], v[188:191], v[120:123]
	v_mfma_f32_16x16x32_f16 v[108:111], v[128:131], v[196:199], v[108:111]
	v_mfma_f32_16x16x32_f16 v[104:107], v[136:139], v[196:199], v[104:107]
	v_mfma_f32_16x16x32_f16 v[92:95], v[128:131], v[204:207], v[92:95]
	v_mfma_f32_16x16x32_f16 v[88:91], v[136:139], v[204:207], v[88:91]
	v_mfma_f32_16x16x32_f16 v[76:79], v[128:131], v[212:215], v[76:79]
	v_mfma_f32_16x16x32_f16 v[72:75], v[136:139], v[212:215], v[72:75]
	v_mfma_f32_16x16x32_f16 v[124:127], v[132:135], v[192:195], v[124:127]
	v_mfma_f32_16x16x32_f16 v[120:123], v[140:143], v[192:195], v[120:123]
	v_mfma_f32_16x16x32_f16 v[108:111], v[132:135], v[200:203], v[108:111]
	v_mfma_f32_16x16x32_f16 v[104:107], v[140:143], v[200:203], v[104:107]
	v_mfma_f32_16x16x32_f16 v[92:95], v[132:135], v[208:211], v[92:95]
	v_mfma_f32_16x16x32_f16 v[88:91], v[140:143], v[208:211], v[88:91]
	v_mfma_f32_16x16x32_f16 v[76:79], v[132:135], v[216:219], v[76:79]
	v_mfma_f32_16x16x32_f16 v[72:75], v[140:143], v[216:219], v[72:75]
	v_mfma_f32_16x16x32_f16 v[116:119], v[144:147], v[188:191], v[116:119]
	v_mfma_f32_16x16x32_f16 v[112:115], v[152:155], v[188:191], v[112:115]
	v_mfma_f32_16x16x32_f16 v[100:103], v[144:147], v[196:199], v[100:103]
	v_mfma_f32_16x16x32_f16 v[96:99], v[152:155], v[196:199], v[96:99]
	v_mfma_f32_16x16x32_f16 v[84:87], v[144:147], v[204:207], v[84:87]
	v_mfma_f32_16x16x32_f16 v[80:83], v[152:155], v[204:207], v[80:83]
	v_mfma_f32_16x16x32_f16 v[68:71], v[144:147], v[212:215], v[68:71]
	v_mfma_f32_16x16x32_f16 v[64:67], v[152:155], v[212:215], v[64:67]
	v_mfma_f32_16x16x32_f16 v[116:119], v[148:151], v[192:195], v[116:119]
	v_mfma_f32_16x16x32_f16 v[112:115], v[174:177], v[192:195], v[112:115]
	v_mfma_f32_16x16x32_f16 v[100:103], v[148:151], v[200:203], v[100:103]
	v_mfma_f32_16x16x32_f16 v[96:99], v[174:177], v[200:203], v[96:99]
	v_mfma_f32_16x16x32_f16 v[84:87], v[148:151], v[208:211], v[84:87]
	v_mfma_f32_16x16x32_f16 v[80:83], v[174:177], v[208:211], v[80:83]
	v_mfma_f32_16x16x32_f16 v[68:71], v[148:151], v[216:219], v[68:71]
	v_mfma_f32_16x16x32_f16 v[64:67], v[174:177], v[216:219], v[64:67]
	s_barrier
	s_add_i32 s53, s40, s68
	v_lshl_add_u64 v[178:179], s[48:49], 0, v[158:159]
	s_mov_b32 m0, s53
	s_nop 0
	global_load_lds_dwordx4 v[178:179], off
	s_add_i32 m0, s53, 0x2000
	s_add_u32 s54, s48, 0x40000
	v_lshl_add_u64 v[220:221], s[48:49], 0, v[162:163]
	s_addc_u32 s55, s49, 0
	s_add_i32 s53, s41, s68
	global_load_lds_dwordx4 v[220:221], off
	v_lshl_add_u64 v[222:223], s[54:55], 0, v[158:159]
	s_mov_b32 m0, s53
	v_lshl_add_u64 v[224:225], s[50:51], 0, v[160:161]
	global_load_lds_dwordx4 v[222:223], off
	v_lshl_add_u64 v[222:223], s[54:55], 0, v[162:163]
	s_add_i32 m0, s53, 0x2000
	s_nop 0
	global_load_lds_dwordx4 v[222:223], off
	v_lshl_add_u64 v[222:223], s[50:51], 0, v[156:157]
	s_mov_b32 m0, s74
	s_nop 0
	global_load_lds_dwordx4 v[222:223], off
	s_mov_b32 m0, s65
	s_nop 0
	global_load_lds_dwordx4 v[224:225], off
	ds_read_b128 v[188:191], v185 offset:16384
	ds_read_b128 v[192:195], v185 offset:17408
	ds_read_b128 v[196:199], v185 offset:18432
	ds_read_b128 v[200:203], v185 offset:19456
	ds_read_b128 v[204:207], v185 offset:20480
	ds_read_b128 v[208:211], v185 offset:21504
	ds_read_b128 v[212:215], v185 offset:22528
	ds_read_b128 v[216:219], v185 offset:23552
	s_waitcnt vmcnt(8)
	s_waitcnt lgkmcnt(0)
	s_barrier
; #define PG8_STAGE(bufoff, gbase, voff) do { _Pragma("unroll") for (int _i = 0; _i < 2; ++_i) \
;         __builtin_amdgcn_global_load_lds((const unsigned*)((const char*)(gbase) + (voff)[_i]), (PG8_LAS unsigned*)(lds + (bufoff) + ldsw + _i * 8192), 16, 0, 0); } while (0)
; #define PG8_LDA(dst, b, h) do { _Pragma("unroll") for (int m = 0; m < 4; ++m) _Pragma("unroll") for (int k = 0; k < 2; ++k) dst[m][k] = *(const PG8_LAS bf16x8*)(lds + PG8_SA(b, h) + aoff + m * 2048 + k * 1024); } while (0)
; #define PG8_LDB(dst, b, h) do { _Pragma("unroll") for (int n = 0; n < 2; ++n) _Pragma("unroll") for (int k = 0; k < 2; ++k) dst[n][k] = *(const PG8_LAS bf16x8*)(lds + PG8_SB(b, h) + boff + n * 2048 + k * 1024); } while (0)
; #define PG8_MMA(ai, bj, At, Bt) do { __builtin_amdgcn_s_setprio(1); _Pragma("unroll") for (int m = 0; m < 4; ++m) _Pragma("unroll") for (int n = 0; n < 2; ++n) _Pragma("unroll") for (int k = 0; k < 2; ++k) \
;         acc[ai][bj][m][n] = mma16<F16>(Bt[n][k], At[m][k], acc[ai][bj][m][n]); __builtin_amdgcn_s_setprio(0); } while (0)
; #define PG8_WAIT_V(n) asm volatile("s_waitcnt vmcnt(" #n ")" ::: "memory")
; #define PG8_WAIT_L(n) asm volatile("s_waitcnt lgkmcnt(" #n ")" ::: "memory")
; #define PG8_BAR __builtin_amdgcn_s_barrier()
; #define PG8_SCHED __builtin_amdgcn_sched_barrier(0)
; template <class Epi, class Sched, bool ALIGN_EPI = false, bool SP2 = false, bool F16 = false>
; __device__ __forceinline__ void gemm_phase(PG8_LAS unsigned char* lds, const Gemm g, const Sched& S, const Epi& E, const int wid_in) {
;     ...
;             PG8_WAIT_V(8); PG8_WAIT_L(0); PG8_BAR; PG8_MMA(1, 0, At, B0); PG8_MMA(1, 1, At, B1); PG8_BAR; PG8_SCHED;
;             PG8_LDB(B0, 1, 0); PG8_LDB(B1, 1, 1); PG8_SCHED; PG8_LDA(At, 1, 0); PG8_STAGE(PG8_SA(0, 1), a2 + hstep, voffA);
;             PG8_WAIT_V(8); PG8_WAIT_L(0); PG8_BAR; PG8_MMA(0, 0, At, B0); PG8_MMA(0, 1, At, B1); PG8_BAR; PG8_SCHED;
	s_waitcnt lgkmcnt(0)
	v_mfma_f32_16x16x32_f16 v[60:63], v[128:131], v[188:191], v[60:63]
	v_mfma_f32_16x16x32_f16 v[56:59], v[136:139], v[188:191], v[56:59]
	v_mfma_f32_16x16x32_f16 v[44:47], v[128:131], v[196:199], v[44:47]
	v_mfma_f32_16x16x32_f16 v[40:43], v[136:139], v[196:199], v[40:43]
	v_mfma_f32_16x16x32_f16 v[28:31], v[128:131], v[204:207], v[28:31]
	v_mfma_f32_16x16x32_f16 v[24:27], v[136:139], v[204:207], v[24:27]
	v_mfma_f32_16x16x32_f16 v[12:15], v[128:131], v[212:215], v[12:15]
	v_mfma_f32_16x16x32_f16 v[8:11], v[136:139], v[212:215], v[8:11]
	v_mfma_f32_16x16x32_f16 v[60:63], v[132:135], v[192:195], v[60:63]
	v_mfma_f32_16x16x32_f16 v[56:59], v[140:143], v[192:195], v[56:59]
	v_mfma_f32_16x16x32_f16 v[44:47], v[132:135], v[200:203], v[44:47]
	v_mfma_f32_16x16x32_f16 v[40:43], v[140:143], v[200:203], v[40:43]
	v_mfma_f32_16x16x32_f16 v[28:31], v[132:135], v[208:211], v[28:31]
	v_mfma_f32_16x16x32_f16 v[24:27], v[140:143], v[208:211], v[24:27]
	v_mfma_f32_16x16x32_f16 v[12:15], v[132:135], v[216:219], v[12:15]
	v_mfma_f32_16x16x32_f16 v[8:11], v[140:143], v[216:219], v[8:11]
	v_mfma_f32_16x16x32_f16 v[52:55], v[144:147], v[188:191], v[52:55]
	v_mfma_f32_16x16x32_f16 v[48:51], v[152:155], v[188:191], v[48:51]
	v_mfma_f32_16x16x32_f16 v[36:39], v[144:147], v[196:199], v[36:39]
	v_mfma_f32_16x16x32_f16 v[32:35], v[152:155], v[196:199], v[32:35]
	v_mfma_f32_16x16x32_f16 v[20:23], v[144:147], v[204:207], v[20:23]
	v_mfma_f32_16x16x32_f16 v[16:19], v[152:155], v[204:207], v[16:19]
	v_mfma_f32_16x16x32_f16 v[4:7], v[144:147], v[212:215], v[4:7]
	v_mfma_f32_16x16x32_f16 v[0:3], v[152:155], v[212:215], v[0:3]
	v_mfma_f32_16x16x32_f16 v[52:55], v[148:151], v[192:195], v[52:55]
	v_mfma_f32_16x16x32_f16 v[48:51], v[174:177], v[192:195], v[48:51]
	v_mfma_f32_16x16x32_f16 v[36:39], v[148:151], v[200:203], v[36:39]
	v_mfma_f32_16x16x32_f16 v[32:35], v[174:177], v[200:203], v[32:35]
	v_mfma_f32_16x16x32_f16 v[20:23], v[148:151], v[208:211], v[20:23]
	v_mfma_f32_16x16x32_f16 v[16:19], v[174:177], v[208:211], v[16:19]
	v_mfma_f32_16x16x32_f16 v[4:7], v[148:151], v[216:219], v[4:7]
	v_mfma_f32_16x16x32_f16 v[0:3], v[174:177], v[216:219], v[0:3]
	s_barrier
	s_add_i32 s53, 0, 0x18000
	s_add_i32 s54, 0, 0x1c000
	v_add_u32_e32 v140, s53, v182
	v_add_u32_e32 v165, s54, v182
	s_add_u32 s50, s50, 0x40000
	s_addc_u32 s51, s51, 0
	s_mov_b32 m0, s66
	v_lshl_add_u64 v[226:227], s[50:51], 0, v[156:157]
	global_load_lds_dwordx4 v[226:227], off
	v_lshl_add_u64 v[226:227], s[50:51], 0, v[160:161]
	s_mov_b32 m0, s67
	s_nop 0
	global_load_lds_dwordx4 v[226:227], off
	ds_read_b128 v[128:131], v140
	ds_read_b128 v[132:135], v140 offset:1024
	ds_read_b128 v[136:139], v140 offset:2048
	ds_read_b128 v[140:143], v140 offset:3072
	ds_read_b128 v[144:147], v165
	ds_read_b128 v[148:151], v165 offset:1024
	ds_read_b128 v[152:155], v165 offset:2048
	ds_read_b128 v[174:177], v165 offset:3072
	ds_read_b128 v[188:191], v185 offset:32768
	ds_read_b128 v[192:195], v185 offset:33792
	ds_read_b128 v[196:199], v185 offset:34816
	ds_read_b128 v[200:203], v185 offset:35840
	ds_read_b128 v[204:207], v185 offset:36864
	ds_read_b128 v[208:211], v185 offset:37888
	ds_read_b128 v[212:215], v185 offset:38912
	ds_read_b128 v[216:219], v185 offset:39936
	s_waitcnt vmcnt(8)
	s_waitcnt lgkmcnt(0)
	s_barrier
	s_waitcnt lgkmcnt(0)
	v_mfma_f32_16x16x32_f16 v[124:127], v[128:131], v[188:191], v[124:127]
	v_mfma_f32_16x16x32_f16 v[120:123], v[136:139], v[188:191], v[120:123]
	v_mfma_f32_16x16x32_f16 v[108:111], v[128:131], v[196:199], v[108:111]
	v_mfma_f32_16x16x32_f16 v[104:107], v[136:139], v[196:199], v[104:107]
	v_mfma_f32_16x16x32_f16 v[92:95], v[128:131], v[204:207], v[92:95]
	v_mfma_f32_16x16x32_f16 v[88:91], v[136:139], v[204:207], v[88:91]
	v_mfma_f32_16x16x32_f16 v[76:79], v[128:131], v[212:215], v[76:79]
	v_mfma_f32_16x16x32_f16 v[72:75], v[136:139], v[212:215], v[72:75]
	v_mfma_f32_16x16x32_f16 v[124:127], v[132:135], v[192:195], v[124:127]
	v_mfma_f32_16x16x32_f16 v[120:123], v[140:143], v[192:195], v[120:123]
	v_mfma_f32_16x16x32_f16 v[108:111], v[132:135], v[200:203], v[108:111]
	v_mfma_f32_16x16x32_f16 v[104:107], v[140:143], v[200:203], v[104:107]
	v_mfma_f32_16x16x32_f16 v[92:95], v[132:135], v[208:211], v[92:95]
	v_mfma_f32_16x16x32_f16 v[88:91], v[140:143], v[208:211], v[88:91]
	v_mfma_f32_16x16x32_f16 v[76:79], v[132:135], v[216:219], v[76:79]
	v_mfma_f32_16x16x32_f16 v[72:75], v[140:143], v[216:219], v[72:75]
	v_mfma_f32_16x16x32_f16 v[116:119], v[144:147], v[188:191], v[116:119]
	v_mfma_f32_16x16x32_f16 v[112:115], v[152:155], v[188:191], v[112:115]
	v_mfma_f32_16x16x32_f16 v[100:103], v[144:147], v[196:199], v[100:103]
	v_mfma_f32_16x16x32_f16 v[96:99], v[152:155], v[196:199], v[96:99]
	v_mfma_f32_16x16x32_f16 v[84:87], v[144:147], v[204:207], v[84:87]
	v_mfma_f32_16x16x32_f16 v[80:83], v[152:155], v[204:207], v[80:83]
	v_mfma_f32_16x16x32_f16 v[68:71], v[144:147], v[212:215], v[68:71]
	v_mfma_f32_16x16x32_f16 v[64:67], v[152:155], v[212:215], v[64:67]
	v_mfma_f32_16x16x32_f16 v[116:119], v[148:151], v[192:195], v[116:119]
	v_mfma_f32_16x16x32_f16 v[112:115], v[174:177], v[192:195], v[112:115]
	v_mfma_f32_16x16x32_f16 v[100:103], v[148:151], v[200:203], v[100:103]
	v_mfma_f32_16x16x32_f16 v[96:99], v[174:177], v[200:203], v[96:99]
	v_mfma_f32_16x16x32_f16 v[84:87], v[148:151], v[208:211], v[84:87]
	v_mfma_f32_16x16x32_f16 v[80:83], v[174:177], v[208:211], v[80:83]
	v_mfma_f32_16x16x32_f16 v[68:71], v[148:151], v[216:219], v[68:71]
	v_mfma_f32_16x16x32_f16 v[64:67], v[174:177], v[216:219], v[64:67]
	s_barrier
; #define PG8_STAGE(bufoff, gbase, voff) do { _Pragma("unroll") for (int _i = 0; _i < 2; ++_i) \
;         __builtin_amdgcn_global_load_lds((const unsigned*)((const char*)(gbase) + (voff)[_i]), (PG8_LAS unsigned*)(lds + (bufoff) + ldsw + _i * 8192), 16, 0, 0); } while (0)
; #define PG8_LDA(dst, b, h) do { _Pragma("unroll") for (int m = 0; m < 4; ++m) _Pragma("unroll") for (int k = 0; k < 2; ++k) dst[m][k] = *(const PG8_LAS bf16x8*)(lds + PG8_SA(b, h) + aoff + m * 2048 + k * 1024); } while (0)
; #define PG8_MMA(ai, bj, At, Bt) do { __builtin_amdgcn_s_setprio(1); _Pragma("unroll") for (int m = 0; m < 4; ++m) _Pragma("unroll") for (int n = 0; n < 2; ++n) _Pragma("unroll") for (int k = 0; k < 2; ++k) \
;         acc[ai][bj][m][n] = mma16<F16>(Bt[n][k], At[m][k], acc[ai][bj][m][n]); __builtin_amdgcn_s_setprio(0); } while (0)
; #define PG8_WAIT_V(n) asm volatile("s_waitcnt vmcnt(" #n ")" ::: "memory")
; #define PG8_WAIT_L(n) asm volatile("s_waitcnt lgkmcnt(" #n ")" ::: "memory")
; #define PG8_BAR __builtin_amdgcn_s_barrier()
; #define PG8_SCHED __builtin_amdgcn_sched_barrier(0)
; template <class Epi, class Sched, bool ALIGN_EPI = false, bool SP2 = false, bool F16 = false>
; __device__ __forceinline__ void gemm_phase(PG8_LAS unsigned char* lds, const Gemm g, const Sched& S, const Epi& E, const int wid_in) {
;     ...
;             PG8_LDA(At, 1, 1); PG8_STAGE(PG8_SB(1, 0), b3, voffB); PG8_STAGE(PG8_SB(1, 1), b3 + hstep, voffB); PG8_STAGE(PG8_SA(1, 0), a3, voffA);
;             PG8_WAIT_V(8); PG8_WAIT_L(0); PG8_BAR; PG8_MMA(1, 0, At, B0); PG8_MMA(1, 1, At, B1); PG8_BAR; PG8_SCHED;
;     ...
;         if constexpr (ALIGN_EPI) { if (wr == 0) PG8_BAR; }
	s_add_i32 s50, s53, s68
	v_lshl_add_u64 v[178:179], v[178:179], 0, s[20:21]
	s_mov_b32 m0, s50
	s_nop 0
	global_load_lds_dwordx4 v[178:179], off
	s_add_i32 m0, s50, 0x2000
	s_add_u32 s48, s48, 0x40080
	v_lshl_add_u64 v[178:179], v[220:221], 0, s[20:21]
	s_addc_u32 s49, s49, 0
	s_add_i32 s50, s54, s68
	global_load_lds_dwordx4 v[178:179], off
	v_lshl_add_u64 v[178:179], s[48:49], 0, v[158:159]
	s_mov_b32 m0, s50
	s_nop 0
	global_load_lds_dwordx4 v[178:179], off
	v_lshl_add_u64 v[178:179], s[48:49], 0, v[162:163]
	s_add_i32 m0, s50, 0x2000
	s_nop 0
	global_load_lds_dwordx4 v[178:179], off
	v_lshl_add_u64 v[178:179], v[222:223], 0, s[20:21]
	s_mov_b32 m0, s75
	s_nop 0
	global_load_lds_dwordx4 v[178:179], off
	v_lshl_add_u64 v[178:179], v[224:225], 0, s[20:21]
	s_mov_b32 m0, s89
	s_nop 0
	global_load_lds_dwordx4 v[178:179], off
	ds_read_b128 v[188:191], v185 offset:49152
	ds_read_b128 v[192:195], v185 offset:50176
	ds_read_b128 v[196:199], v185 offset:51200
	ds_read_b128 v[200:203], v185 offset:52224
	ds_read_b128 v[204:207], v185 offset:53248
	ds_read_b128 v[208:211], v185 offset:54272
	ds_read_b128 v[212:215], v185 offset:55296
	ds_read_b128 v[216:219], v185 offset:56320
	s_waitcnt vmcnt(8)
	s_waitcnt lgkmcnt(0)
	s_barrier
	s_waitcnt lgkmcnt(0)
	v_mfma_f32_16x16x32_f16 v[60:63], v[128:131], v[188:191], v[60:63]
	v_mfma_f32_16x16x32_f16 v[56:59], v[136:139], v[188:191], v[56:59]
	v_mfma_f32_16x16x32_f16 v[44:47], v[128:131], v[196:199], v[44:47]
	v_mfma_f32_16x16x32_f16 v[40:43], v[136:139], v[196:199], v[40:43]
	v_mfma_f32_16x16x32_f16 v[28:31], v[128:131], v[204:207], v[28:31]
	v_mfma_f32_16x16x32_f16 v[24:27], v[136:139], v[204:207], v[24:27]
	v_mfma_f32_16x16x32_f16 v[12:15], v[128:131], v[212:215], v[12:15]
	v_mfma_f32_16x16x32_f16 v[8:11], v[136:139], v[212:215], v[8:11]
	v_mfma_f32_16x16x32_f16 v[60:63], v[132:135], v[192:195], v[60:63]
	v_mfma_f32_16x16x32_f16 v[56:59], v[140:143], v[192:195], v[56:59]
	v_mfma_f32_16x16x32_f16 v[44:47], v[132:135], v[200:203], v[44:47]
	v_mfma_f32_16x16x32_f16 v[40:43], v[140:143], v[200:203], v[40:43]
	v_mfma_f32_16x16x32_f16 v[28:31], v[132:135], v[208:211], v[28:31]
	v_mfma_f32_16x16x32_f16 v[24:27], v[140:143], v[208:211], v[24:27]
	v_mfma_f32_16x16x32_f16 v[12:15], v[132:135], v[216:219], v[12:15]
	v_mfma_f32_16x16x32_f16 v[8:11], v[140:143], v[216:219], v[8:11]
	v_mfma_f32_16x16x32_f16 v[52:55], v[144:147], v[188:191], v[52:55]
	v_mfma_f32_16x16x32_f16 v[48:51], v[152:155], v[188:191], v[48:51]
	v_mfma_f32_16x16x32_f16 v[36:39], v[144:147], v[196:199], v[36:39]
	v_mfma_f32_16x16x32_f16 v[32:35], v[152:155], v[196:199], v[32:35]
	v_mfma_f32_16x16x32_f16 v[20:23], v[144:147], v[204:207], v[20:23]
	v_mfma_f32_16x16x32_f16 v[16:19], v[152:155], v[204:207], v[16:19]
	v_mfma_f32_16x16x32_f16 v[4:7], v[144:147], v[212:215], v[4:7]
	v_mfma_f32_16x16x32_f16 v[0:3], v[152:155], v[212:215], v[0:3]
	v_mfma_f32_16x16x32_f16 v[52:55], v[148:151], v[192:195], v[52:55]
	v_mfma_f32_16x16x32_f16 v[48:51], v[174:177], v[192:195], v[48:51]
	v_mfma_f32_16x16x32_f16 v[36:39], v[148:151], v[200:203], v[36:39]
	v_mfma_f32_16x16x32_f16 v[32:35], v[174:177], v[200:203], v[32:35]
	v_mfma_f32_16x16x32_f16 v[20:23], v[148:151], v[208:211], v[20:23]
	v_mfma_f32_16x16x32_f16 v[16:19], v[174:177], v[208:211], v[16:19]
	v_mfma_f32_16x16x32_f16 v[4:7], v[148:151], v[216:219], v[4:7]
	v_mfma_f32_16x16x32_f16 v[0:3], v[174:177], v[216:219], v[0:3]
	s_barrier
	s_add_i32 s52, s52, 2
	s_add_u32 s46, s46, 0x100
	s_addc_u32 s47, s47, 0
	s_add_u32 s42, s42, 0x100
	s_addc_u32 s43, s43, 0
	s_cmp_gt_u32 s52, 13
	s_cbranch_scc0 .LBB0_902
	s_and_b64 vcc, exec, s[16:17]
	s_cbranch_vccz .LBB0_905
	s_barrier

; #define PG8_STAGE(bufoff, gbase, voff) do { _Pragma("unroll") for (int _i = 0; _i < 2; ++_i) \
;         __builtin_amdgcn_global_load_lds((const unsigned*)((const char*)(gbase) + (voff)[_i]), (PG8_LAS unsigned*)(lds + (bufoff) + ldsw + _i * 8192), 16, 0, 0); } while (0)
; #define PG8_LDA(dst, b, h) do { _Pragma("unroll") for (int m = 0; m < 4; ++m) _Pragma("unroll") for (int k = 0; k < 2; ++k) dst[m][k] = *(const PG8_LAS bf16x8*)(lds + PG8_SA(b, h) + aoff + m * 2048 + k * 1024); } while (0)
; #define PG8_LDB(dst, b, h) do { _Pragma("unroll") for (int n = 0; n < 2; ++n) _Pragma("unroll") for (int k = 0; k < 2; ++k) dst[n][k] = *(const PG8_LAS bf16x8*)(lds + PG8_SB(b, h) + boff + n * 2048 + k * 1024); } while (0)
; #define PG8_MMA(ai, bj, At, Bt) do { __builtin_amdgcn_s_setprio(1); _Pragma("unroll") for (int m = 0; m < 4; ++m) _Pragma("unroll") for (int n = 0; n < 2; ++n) _Pragma("unroll") for (int k = 0; k < 2; ++k) \
;         acc[ai][bj][m][n] = mma16<F16>(Bt[n][k], At[m][k], acc[ai][bj][m][n]); __builtin_amdgcn_s_setprio(0); } while (0)
; #define PG8_WAIT_V(n) asm volatile("s_waitcnt vmcnt(" #n ")" ::: "memory")
; #define PG8_WAIT_L(n) asm volatile("s_waitcnt lgkmcnt(" #n ")" ::: "memory")
; #define PG8_BAR __builtin_amdgcn_s_barrier()
; #define PG8_SCHED __builtin_amdgcn_sched_barrier(0)
; template <class Epi, class Sched, bool ALIGN_EPI = false, bool SP2 = false, bool F16 = false>
; __device__ __forceinline__ void gemm_phase(PG8_LAS unsigned char* lds, const Gemm g, const Sched& S, const Epi& E, const int wid_in) {
;     ...
;             const bool last = (t == nt - 2);
;             const char* a1 = cA + (size_t)(t + 1) * kstep;
;             const char* a2 = last ? nA : cA + (size_t)(t + 2) * kstep; const char* b2 = last ? nB : cB + (size_t)(t + 2) * kstep;
;             const char* a3 = a2 + kstep; const char* b3 = b2 + kstep;
;             if (last && has_next) S.a_ready(nxt);
;             if constexpr (SP2) {
;             PG8_LDB(B0, 0, 0); PG8_LDB(B1, 0, 1); PG8_SCHED; PG8_LDA(At, 0, 0); PG8_STAGE(PG8_SA(1, 1), a1 + hstep, voffA);
;             PG8_WAIT_V(8); PG8_WAIT_L(0); PG8_BAR; PG8_MMA(0, 0, At, B0); PG8_MMA(0, 1, At, B1); PG8_BAR; PG8_SCHED;
;             PG8_LDA(At, 0, 1); PG8_STAGE(PG8_SB(0, 0), b2, voffB); PG8_STAGE(PG8_SB(0, 1), b2 + hstep, voffB); PG8_STAGE(PG8_SA(0, 0), a2, voffA);
.LBB0_1165:
	ds_read_b128 v[128:131], v189
	ds_read_b128 v[132:135], v189 offset:1024
	ds_read_b128 v[136:139], v189 offset:2048
	ds_read_b128 v[140:143], v189 offset:3072
	ds_read_b128 v[144:147], v190
	ds_read_b128 v[148:151], v190 offset:1024
	ds_read_b128 v[168:171], v190 offset:2048
	ds_read_b128 v[172:175], v190 offset:3072
	s_add_u32 s50, s48, 0xfffc0080
	s_addc_u32 s51, s49, -1
	s_cmp_eq_u32 s64, 12
	s_cselect_b32 s53, s35, s51
	s_cselect_b32 s52, s42, s50
	s_cselect_b32 s51, s31, s63
	s_cselect_b32 s50, s43, s47
	v_lshl_add_u64 v[184:185], s[48:49], 0, v[160:161]
	s_add_i32 m0, s74, 0xc000
	ds_read_b128 v[176:179], v191
	ds_read_b128 v[180:183], v191 offset:1024
	ds_read_b128 v[192:195], v191 offset:2048
	ds_read_b128 v[196:199], v191 offset:3072
	ds_read_b128 v[200:203], v191 offset:4096
	ds_read_b128 v[204:207], v191 offset:5120
	ds_read_b128 v[208:211], v191 offset:6144
	ds_read_b128 v[212:215], v191 offset:7168
	global_load_lds_dwordx4 v[184:185], off
	v_lshl_add_u64 v[184:185], s[48:49], 0, v[162:163]
	s_add_i32 m0, s74, 0xe000
	s_nop 0
	global_load_lds_dwordx4 v[184:185], off
	s_waitcnt vmcnt(8)
	s_waitcnt lgkmcnt(0)
	s_barrier
	s_waitcnt lgkmcnt(0)
	v_mfma_f32_16x16x32_bf16 v[124:127], v[128:131], v[176:179], v[124:127]
	v_mfma_f32_16x16x32_bf16 v[120:123], v[136:139], v[176:179], v[120:123]
	v_mfma_f32_16x16x32_bf16 v[108:111], v[128:131], v[192:195], v[108:111]
	v_mfma_f32_16x16x32_bf16 v[104:107], v[136:139], v[192:195], v[104:107]
	v_mfma_f32_16x16x32_bf16 v[92:95], v[128:131], v[200:203], v[92:95]
	v_mfma_f32_16x16x32_bf16 v[88:91], v[136:139], v[200:203], v[88:91]
	v_mfma_f32_16x16x32_bf16 v[76:79], v[128:131], v[208:211], v[76:79]
	v_mfma_f32_16x16x32_bf16 v[72:75], v[136:139], v[208:211], v[72:75]
	v_mfma_f32_16x16x32_bf16 v[124:127], v[132:135], v[180:183], v[124:127]
	v_mfma_f32_16x16x32_bf16 v[120:123], v[140:143], v[180:183], v[120:123]
	v_mfma_f32_16x16x32_bf16 v[108:111], v[132:135], v[196:199], v[108:111]
	v_mfma_f32_16x16x32_bf16 v[104:107], v[140:143], v[196:199], v[104:107]
	v_mfma_f32_16x16x32_bf16 v[92:95], v[132:135], v[204:207], v[92:95]
	v_mfma_f32_16x16x32_bf16 v[88:91], v[140:143], v[204:207], v[88:91]
	v_mfma_f32_16x16x32_bf16 v[76:79], v[132:135], v[212:215], v[76:79]
	v_mfma_f32_16x16x32_bf16 v[72:75], v[140:143], v[212:215], v[72:75]
	v_mfma_f32_16x16x32_bf16 v[116:119], v[144:147], v[176:179], v[116:119]
	v_mfma_f32_16x16x32_bf16 v[112:115], v[168:171], v[176:179], v[112:115]
	v_mfma_f32_16x16x32_bf16 v[100:103], v[144:147], v[192:195], v[100:103]
	v_mfma_f32_16x16x32_bf16 v[96:99], v[168:171], v[192:195], v[96:99]
	v_mfma_f32_16x16x32_bf16 v[84:87], v[144:147], v[200:203], v[84:87]
	v_mfma_f32_16x16x32_bf16 v[80:83], v[168:171], v[200:203], v[80:83]
	v_mfma_f32_16x16x32_bf16 v[68:71], v[144:147], v[208:211], v[68:71]
	v_mfma_f32_16x16x32_bf16 v[64:67], v[168:171], v[208:211], v[64:67]
	v_mfma_f32_16x16x32_bf16 v[116:119], v[148:151], v[180:183], v[116:119]
	v_mfma_f32_16x16x32_bf16 v[112:115], v[172:175], v[180:183], v[112:115]
	v_mfma_f32_16x16x32_bf16 v[100:103], v[148:151], v[196:199], v[100:103]
	v_mfma_f32_16x16x32_bf16 v[96:99], v[172:175], v[196:199], v[96:99]
	v_mfma_f32_16x16x32_bf16 v[84:87], v[148:151], v[204:207], v[84:87]
	v_mfma_f32_16x16x32_bf16 v[80:83], v[172:175], v[204:207], v[80:83]
	v_mfma_f32_16x16x32_bf16 v[68:71], v[148:151], v[212:215], v[68:71]
	v_mfma_f32_16x16x32_bf16 v[64:67], v[172:175], v[212:215], v[64:67]
	s_barrier
	s_add_i32 s65, s60, s68
	v_lshl_add_u64 v[184:185], s[50:51], 0, v[154:155]
	s_mov_b32 m0, s65
	s_nop 0
	global_load_lds_dwordx4 v[184:185], off
	s_add_i32 m0, s65, 0x2000
	s_add_u32 s66, s50, 0x40000
	v_lshl_add_u64 v[216:217], s[50:51], 0, v[158:159]
	s_addc_u32 s67, s51, 0
	s_add_i32 s65, s61, s68
	global_load_lds_dwordx4 v[216:217], off
	v_lshl_add_u64 v[218:219], s[66:67], 0, v[154:155]
	s_mov_b32 m0, s65
	v_lshl_add_u64 v[220:221], s[52:53], 0, v[156:157]
	global_load_lds_dwordx4 v[218:219], off
	v_lshl_add_u64 v[218:219], s[66:67], 0, v[158:159]
	s_add_i32 m0, s65, 0x2000
	s_nop 0
	global_load_lds_dwordx4 v[218:219], off
	v_lshl_add_u64 v[218:219], s[52:53], 0, v[152:153]
	s_mov_b32 m0, s74
	s_nop 0
	global_load_lds_dwordx4 v[218:219], off
	s_mov_b32 m0, s41
	s_nop 0
	global_load_lds_dwordx4 v[220:221], off
	ds_read_b128 v[176:179], v191 offset:16384
	ds_read_b128 v[180:183], v191 offset:17408
	ds_read_b128 v[192:195], v191 offset:18432
	ds_read_b128 v[196:199], v191 offset:19456
	ds_read_b128 v[200:203], v191 offset:20480
	ds_read_b128 v[204:207], v191 offset:21504
	ds_read_b128 v[208:211], v191 offset:22528
	ds_read_b128 v[212:215], v191 offset:23552
	s_waitcnt vmcnt(8)
	s_waitcnt lgkmcnt(0)
	s_barrier
; #define PG8_STAGE(bufoff, gbase, voff) do { _Pragma("unroll") for (int _i = 0; _i < 2; ++_i) \
;         __builtin_amdgcn_global_load_lds((const unsigned*)((const char*)(gbase) + (voff)[_i]), (PG8_LAS unsigned*)(lds + (bufoff) + ldsw + _i * 8192), 16, 0, 0); } while (0)
; #define PG8_LDA(dst, b, h) do { _Pragma("unroll") for (int m = 0; m < 4; ++m) _Pragma("unroll") for (int k = 0; k < 2; ++k) dst[m][k] = *(const PG8_LAS bf16x8*)(lds + PG8_SA(b, h) + aoff + m * 2048 + k * 1024); } while (0)
; #define PG8_LDB(dst, b, h) do { _Pragma("unroll") for (int n = 0; n < 2; ++n) _Pragma("unroll") for (int k = 0; k < 2; ++k) dst[n][k] = *(const PG8_LAS bf16x8*)(lds + PG8_SB(b, h) + boff + n * 2048 + k * 1024); } while (0)
; #define PG8_MMA(ai, bj, At, Bt) do { __builtin_amdgcn_s_setprio(1); _Pragma("unroll") for (int m = 0; m < 4; ++m) _Pragma("unroll") for (int n = 0; n < 2; ++n) _Pragma("unroll") for (int k = 0; k < 2; ++k) \
;         acc[ai][bj][m][n] = mma16<F16>(Bt[n][k], At[m][k], acc[ai][bj][m][n]); __builtin_amdgcn_s_setprio(0); } while (0)
; #define PG8_WAIT_V(n) asm volatile("s_waitcnt vmcnt(" #n ")" ::: "memory")
; #define PG8_WAIT_L(n) asm volatile("s_waitcnt lgkmcnt(" #n ")" ::: "memory")
; #define PG8_BAR __builtin_amdgcn_s_barrier()
; #define PG8_SCHED __builtin_amdgcn_sched_barrier(0)
; template <class Epi, class Sched, bool ALIGN_EPI = false, bool SP2 = false, bool F16 = false>
; __device__ __forceinline__ void gemm_phase(PG8_LAS unsigned char* lds, const Gemm g, const Sched& S, const Epi& E, const int wid_in) {
;     ...
;             PG8_WAIT_V(8); PG8_WAIT_L(0); PG8_BAR; PG8_MMA(1, 0, At, B0); PG8_MMA(1, 1, At, B1); PG8_BAR; PG8_SCHED;
;             PG8_LDB(B0, 1, 0); PG8_LDB(B1, 1, 1); PG8_SCHED; PG8_LDA(At, 1, 0); PG8_STAGE(PG8_SA(0, 1), a2 + hstep, voffA);
;             PG8_WAIT_V(8); PG8_WAIT_L(0); PG8_BAR; PG8_MMA(0, 0, At, B0); PG8_MMA(0, 1, At, B1); PG8_BAR; PG8_SCHED;
	s_waitcnt lgkmcnt(0)
	v_mfma_f32_16x16x32_bf16 v[60:63], v[128:131], v[176:179], v[60:63]
	v_mfma_f32_16x16x32_bf16 v[56:59], v[136:139], v[176:179], v[56:59]
	v_mfma_f32_16x16x32_bf16 v[44:47], v[128:131], v[192:195], v[44:47]
	v_mfma_f32_16x16x32_bf16 v[40:43], v[136:139], v[192:195], v[40:43]
	v_mfma_f32_16x16x32_bf16 v[28:31], v[128:131], v[200:203], v[28:31]
	v_mfma_f32_16x16x32_bf16 v[24:27], v[136:139], v[200:203], v[24:27]
	v_mfma_f32_16x16x32_bf16 v[12:15], v[128:131], v[208:211], v[12:15]
	v_mfma_f32_16x16x32_bf16 v[8:11], v[136:139], v[208:211], v[8:11]
	v_mfma_f32_16x16x32_bf16 v[60:63], v[132:135], v[180:183], v[60:63]
	v_mfma_f32_16x16x32_bf16 v[56:59], v[140:143], v[180:183], v[56:59]
	v_mfma_f32_16x16x32_bf16 v[44:47], v[132:135], v[196:199], v[44:47]
	v_mfma_f32_16x16x32_bf16 v[40:43], v[140:143], v[196:199], v[40:43]
	v_mfma_f32_16x16x32_bf16 v[28:31], v[132:135], v[204:207], v[28:31]
	v_mfma_f32_16x16x32_bf16 v[24:27], v[140:143], v[204:207], v[24:27]
	v_mfma_f32_16x16x32_bf16 v[12:15], v[132:135], v[212:215], v[12:15]
	v_mfma_f32_16x16x32_bf16 v[8:11], v[140:143], v[212:215], v[8:11]
	v_mfma_f32_16x16x32_bf16 v[52:55], v[144:147], v[176:179], v[52:55]
	v_mfma_f32_16x16x32_bf16 v[48:51], v[168:171], v[176:179], v[48:51]
	v_mfma_f32_16x16x32_bf16 v[36:39], v[144:147], v[192:195], v[36:39]
	v_mfma_f32_16x16x32_bf16 v[32:35], v[168:171], v[192:195], v[32:35]
	v_mfma_f32_16x16x32_bf16 v[20:23], v[144:147], v[200:203], v[20:23]
	v_mfma_f32_16x16x32_bf16 v[16:19], v[168:171], v[200:203], v[16:19]
	v_mfma_f32_16x16x32_bf16 v[4:7], v[144:147], v[208:211], v[4:7]
	v_mfma_f32_16x16x32_bf16 v[0:3], v[168:171], v[208:211], v[0:3]
	v_mfma_f32_16x16x32_bf16 v[52:55], v[148:151], v[180:183], v[52:55]
	v_mfma_f32_16x16x32_bf16 v[48:51], v[172:175], v[180:183], v[48:51]
	v_mfma_f32_16x16x32_bf16 v[36:39], v[148:151], v[196:199], v[36:39]
	v_mfma_f32_16x16x32_bf16 v[32:35], v[172:175], v[196:199], v[32:35]
	v_mfma_f32_16x16x32_bf16 v[20:23], v[148:151], v[204:207], v[20:23]
	v_mfma_f32_16x16x32_bf16 v[16:19], v[172:175], v[204:207], v[16:19]
	v_mfma_f32_16x16x32_bf16 v[4:7], v[148:151], v[212:215], v[4:7]
	v_mfma_f32_16x16x32_bf16 v[0:3], v[172:175], v[212:215], v[0:3]
	s_barrier
	s_add_i32 s65, 0, 0x18000
	s_add_i32 s66, 0, 0x1c000
	v_add_u32_e32 v140, s65, v188
	v_add_u32_e32 v172, s66, v188
	s_add_u32 s52, s52, 0x40000
	s_addc_u32 s53, s53, 0
	s_mov_b32 m0, s54
	v_lshl_add_u64 v[222:223], s[52:53], 0, v[152:153]
	global_load_lds_dwordx4 v[222:223], off
	v_lshl_add_u64 v[222:223], s[52:53], 0, v[156:157]
	s_mov_b32 m0, s55
	s_nop 0
	global_load_lds_dwordx4 v[222:223], off
	ds_read_b128 v[128:131], v140
	ds_read_b128 v[132:135], v140 offset:1024
	ds_read_b128 v[136:139], v140 offset:2048
	ds_read_b128 v[140:143], v140 offset:3072
	ds_read_b128 v[144:147], v172
	ds_read_b128 v[148:151], v172 offset:1024
	ds_read_b128 v[168:171], v172 offset:2048
	ds_read_b128 v[172:175], v172 offset:3072
	ds_read_b128 v[176:179], v191 offset:32768
	ds_read_b128 v[180:183], v191 offset:33792
	ds_read_b128 v[192:195], v191 offset:34816
	ds_read_b128 v[196:199], v191 offset:35840
	ds_read_b128 v[200:203], v191 offset:36864
	ds_read_b128 v[204:207], v191 offset:37888
	ds_read_b128 v[208:211], v191 offset:38912
	ds_read_b128 v[212:215], v191 offset:39936
	s_waitcnt vmcnt(8)
	s_waitcnt lgkmcnt(0)
	s_barrier
	s_waitcnt lgkmcnt(0)
	v_mfma_f32_16x16x32_bf16 v[124:127], v[128:131], v[176:179], v[124:127]
	v_mfma_f32_16x16x32_bf16 v[120:123], v[136:139], v[176:179], v[120:123]
	v_mfma_f32_16x16x32_bf16 v[108:111], v[128:131], v[192:195], v[108:111]
	v_mfma_f32_16x16x32_bf16 v[104:107], v[136:139], v[192:195], v[104:107]
	v_mfma_f32_16x16x32_bf16 v[92:95], v[128:131], v[200:203], v[92:95]
	v_mfma_f32_16x16x32_bf16 v[88:91], v[136:139], v[200:203], v[88:91]
	v_mfma_f32_16x16x32_bf16 v[76:79], v[128:131], v[208:211], v[76:79]
	v_mfma_f32_16x16x32_bf16 v[72:75], v[136:139], v[208:211], v[72:75]
	v_mfma_f32_16x16x32_bf16 v[124:127], v[132:135], v[180:183], v[124:127]
	v_mfma_f32_16x16x32_bf16 v[120:123], v[140:143], v[180:183], v[120:123]
	v_mfma_f32_16x16x32_bf16 v[108:111], v[132:135], v[196:199], v[108:111]
	v_mfma_f32_16x16x32_bf16 v[104:107], v[140:143], v[196:199], v[104:107]
	v_mfma_f32_16x16x32_bf16 v[92:95], v[132:135], v[204:207], v[92:95]
	v_mfma_f32_16x16x32_bf16 v[88:91], v[140:143], v[204:207], v[88:91]
	v_mfma_f32_16x16x32_bf16 v[76:79], v[132:135], v[212:215], v[76:79]
	v_mfma_f32_16x16x32_bf16 v[72:75], v[140:143], v[212:215], v[72:75]
	v_mfma_f32_16x16x32_bf16 v[116:119], v[144:147], v[176:179], v[116:119]
	v_mfma_f32_16x16x32_bf16 v[112:115], v[168:171], v[176:179], v[112:115]
	v_mfma_f32_16x16x32_bf16 v[100:103], v[144:147], v[192:195], v[100:103]
	v_mfma_f32_16x16x32_bf16 v[96:99], v[168:171], v[192:195], v[96:99]
	v_mfma_f32_16x16x32_bf16 v[84:87], v[144:147], v[200:203], v[84:87]
	v_mfma_f32_16x16x32_bf16 v[80:83], v[168:171], v[200:203], v[80:83]
	v_mfma_f32_16x16x32_bf16 v[68:71], v[144:147], v[208:211], v[68:71]
	v_mfma_f32_16x16x32_bf16 v[64:67], v[168:171], v[208:211], v[64:67]
	v_mfma_f32_16x16x32_bf16 v[116:119], v[148:151], v[180:183], v[116:119]
	v_mfma_f32_16x16x32_bf16 v[112:115], v[172:175], v[180:183], v[112:115]
	v_mfma_f32_16x16x32_bf16 v[100:103], v[148:151], v[196:199], v[100:103]
	v_mfma_f32_16x16x32_bf16 v[96:99], v[172:175], v[196:199], v[96:99]
	v_mfma_f32_16x16x32_bf16 v[84:87], v[148:151], v[204:207], v[84:87]
	v_mfma_f32_16x16x32_bf16 v[80:83], v[172:175], v[204:207], v[80:83]
	v_mfma_f32_16x16x32_bf16 v[68:71], v[148:151], v[212:215], v[68:71]
	v_mfma_f32_16x16x32_bf16 v[64:67], v[172:175], v[212:215], v[64:67]
	s_barrier
; #define PG8_STAGE(bufoff, gbase, voff) do { _Pragma("unroll") for (int _i = 0; _i < 2; ++_i) \
;         __builtin_amdgcn_global_load_lds((const unsigned*)((const char*)(gbase) + (voff)[_i]), (PG8_LAS unsigned*)(lds + (bufoff) + ldsw + _i * 8192), 16, 0, 0); } while (0)
; #define PG8_LDA(dst, b, h) do { _Pragma("unroll") for (int m = 0; m < 4; ++m) _Pragma("unroll") for (int k = 0; k < 2; ++k) dst[m][k] = *(const PG8_LAS bf16x8*)(lds + PG8_SA(b, h) + aoff + m * 2048 + k * 1024); } while (0)
; #define PG8_MMA(ai, bj, At, Bt) do { __builtin_amdgcn_s_setprio(1); _Pragma("unroll") for (int m = 0; m < 4; ++m) _Pragma("unroll") for (int n = 0; n < 2; ++n) _Pragma("unroll") for (int k = 0; k < 2; ++k) \
;         acc[ai][bj][m][n] = mma16<F16>(Bt[n][k], At[m][k], acc[ai][bj][m][n]); __builtin_amdgcn_s_setprio(0); } while (0)
; #define PG8_WAIT_V(n) asm volatile("s_waitcnt vmcnt(" #n ")" ::: "memory")
; #define PG8_WAIT_L(n) asm volatile("s_waitcnt lgkmcnt(" #n ")" ::: "memory")
; #define PG8_BAR __builtin_amdgcn_s_barrier()
; #define PG8_SCHED __builtin_amdgcn_sched_barrier(0)
; template <class Epi, class Sched, bool ALIGN_EPI = false, bool SP2 = false, bool F16 = false>
; __device__ __forceinline__ void gemm_phase(PG8_LAS unsigned char* lds, const Gemm g, const Sched& S, const Epi& E, const int wid_in) {
;     ...
;             PG8_LDA(At, 1, 1); PG8_STAGE(PG8_SB(1, 0), b3, voffB); PG8_STAGE(PG8_SB(1, 1), b3 + hstep, voffB); PG8_STAGE(PG8_SA(1, 0), a3, voffA);
;             PG8_WAIT_V(8); PG8_WAIT_L(0); PG8_BAR; PG8_MMA(1, 0, At, B0); PG8_MMA(1, 1, At, B1); PG8_BAR; PG8_SCHED;
;     ...
;         if constexpr (ALIGN_EPI) { if (wr == 0) PG8_BAR; }
	s_add_i32 s52, s65, s68
	v_lshl_add_u64 v[184:185], v[184:185], 0, s[28:29]
	s_mov_b32 m0, s52
	s_nop 0
	global_load_lds_dwordx4 v[184:185], off
	s_add_i32 m0, s52, 0x2000
	s_add_u32 s50, s50, 0x40080
	v_lshl_add_u64 v[184:185], v[216:217], 0, s[28:29]
	s_addc_u32 s51, s51, 0
	s_add_i32 s52, s66, s68
	global_load_lds_dwordx4 v[184:185], off
	v_lshl_add_u64 v[184:185], s[50:51], 0, v[154:155]
	s_mov_b32 m0, s52
	s_nop 0
	global_load_lds_dwordx4 v[184:185], off
	v_lshl_add_u64 v[184:185], s[50:51], 0, v[158:159]
	s_add_i32 m0, s52, 0x2000
	s_nop 0
	global_load_lds_dwordx4 v[184:185], off
	v_lshl_add_u64 v[184:185], v[218:219], 0, s[28:29]
	s_mov_b32 m0, s75
	s_nop 0
	global_load_lds_dwordx4 v[184:185], off
	v_lshl_add_u64 v[184:185], v[220:221], 0, s[28:29]
	s_mov_b32 m0, s56
	s_nop 0
	global_load_lds_dwordx4 v[184:185], off
	ds_read_b128 v[176:179], v191 offset:49152
	ds_read_b128 v[180:183], v191 offset:50176
	ds_read_b128 v[192:195], v191 offset:51200
	ds_read_b128 v[196:199], v191 offset:52224
	ds_read_b128 v[200:203], v191 offset:53248
	ds_read_b128 v[204:207], v191 offset:54272
	ds_read_b128 v[208:211], v191 offset:55296
	ds_read_b128 v[212:215], v191 offset:56320
	s_waitcnt vmcnt(8)
	s_waitcnt lgkmcnt(0)
	s_barrier
	s_waitcnt lgkmcnt(0)
	v_mfma_f32_16x16x32_bf16 v[60:63], v[128:131], v[176:179], v[60:63]
	v_mfma_f32_16x16x32_bf16 v[56:59], v[136:139], v[176:179], v[56:59]
	v_mfma_f32_16x16x32_bf16 v[44:47], v[128:131], v[192:195], v[44:47]
	v_mfma_f32_16x16x32_bf16 v[40:43], v[136:139], v[192:195], v[40:43]
	v_mfma_f32_16x16x32_bf16 v[28:31], v[128:131], v[200:203], v[28:31]
	v_mfma_f32_16x16x32_bf16 v[24:27], v[136:139], v[200:203], v[24:27]
	v_mfma_f32_16x16x32_bf16 v[12:15], v[128:131], v[208:211], v[12:15]
	v_mfma_f32_16x16x32_bf16 v[8:11], v[136:139], v[208:211], v[8:11]
	v_mfma_f32_16x16x32_bf16 v[60:63], v[132:135], v[180:183], v[60:63]
	v_mfma_f32_16x16x32_bf16 v[56:59], v[140:143], v[180:183], v[56:59]
	v_mfma_f32_16x16x32_bf16 v[44:47], v[132:135], v[196:199], v[44:47]
	v_mfma_f32_16x16x32_bf16 v[40:43], v[140:143], v[196:199], v[40:43]
	v_mfma_f32_16x16x32_bf16 v[28:31], v[132:135], v[204:207], v[28:31]
	v_mfma_f32_16x16x32_bf16 v[24:27], v[140:143], v[204:207], v[24:27]
	v_mfma_f32_16x16x32_bf16 v[12:15], v[132:135], v[212:215], v[12:15]
	v_mfma_f32_16x16x32_bf16 v[8:11], v[140:143], v[212:215], v[8:11]
	v_mfma_f32_16x16x32_bf16 v[52:55], v[144:147], v[176:179], v[52:55]
	v_mfma_f32_16x16x32_bf16 v[48:51], v[168:171], v[176:179], v[48:51]
	v_mfma_f32_16x16x32_bf16 v[36:39], v[144:147], v[192:195], v[36:39]
	v_mfma_f32_16x16x32_bf16 v[32:35], v[168:171], v[192:195], v[32:35]
	v_mfma_f32_16x16x32_bf16 v[20:23], v[144:147], v[200:203], v[20:23]
	v_mfma_f32_16x16x32_bf16 v[16:19], v[168:171], v[200:203], v[16:19]
	v_mfma_f32_16x16x32_bf16 v[4:7], v[144:147], v[208:211], v[4:7]
	v_mfma_f32_16x16x32_bf16 v[0:3], v[168:171], v[208:211], v[0:3]
	v_mfma_f32_16x16x32_bf16 v[52:55], v[148:151], v[180:183], v[52:55]
	v_mfma_f32_16x16x32_bf16 v[48:51], v[172:175], v[180:183], v[48:51]
	v_mfma_f32_16x16x32_bf16 v[36:39], v[148:151], v[196:199], v[36:39]
	v_mfma_f32_16x16x32_bf16 v[32:35], v[172:175], v[196:199], v[32:35]
	v_mfma_f32_16x16x32_bf16 v[20:23], v[148:151], v[204:207], v[20:23]
	v_mfma_f32_16x16x32_bf16 v[16:19], v[172:175], v[204:207], v[16:19]
	v_mfma_f32_16x16x32_bf16 v[4:7], v[148:151], v[212:215], v[4:7]
	v_mfma_f32_16x16x32_bf16 v[0:3], v[172:175], v[212:215], v[0:3]
	s_barrier
	s_add_i32 s64, s64, 2
	s_add_u32 s48, s48, 0x100
	s_addc_u32 s49, s49, 0
	s_add_u32 s47, s47, 0x100
	s_addc_u32 s63, s63, 0
	s_cmp_gt_u32 s64, 13
	s_cbranch_scc0 .LBB0_1165
	s_and_b64 vcc, exec, s[16:17]
	s_cbranch_vccz .LBB0_1168
	s_barrier

; #define PG8_STAGE(bufoff, gbase, voff) do { _Pragma("unroll") for (int _i = 0; _i < 2; ++_i) \
;         __builtin_amdgcn_global_load_lds((const unsigned*)((const char*)(gbase) + (voff)[_i]), (PG8_LAS unsigned*)(lds + (bufoff) + ldsw + _i * 8192), 16, 0, 0); } while (0)
; #define PG8_LDA(dst, b, h) do { _Pragma("unroll") for (int m = 0; m < 4; ++m) _Pragma("unroll") for (int k = 0; k < 2; ++k) dst[m][k] = *(const PG8_LAS bf16x8*)(lds + PG8_SA(b, h) + aoff + m * 2048 + k * 1024); } while (0)
; #define PG8_LDB(dst, b, h) do { _Pragma("unroll") for (int n = 0; n < 2; ++n) _Pragma("unroll") for (int k = 0; k < 2; ++k) dst[n][k] = *(const PG8_LAS bf16x8*)(lds + PG8_SB(b, h) + boff + n * 2048 + k * 1024); } while (0)
; #define PG8_MMA(ai, bj, At, Bt) do { __builtin_amdgcn_s_setprio(1); _Pragma("unroll") for (int m = 0; m < 4; ++m) _Pragma("unroll") for (int n = 0; n < 2; ++n) _Pragma("unroll") for (int k = 0; k < 2; ++k) \
;         acc[ai][bj][m][n] = mma16<F16>(Bt[n][k], At[m][k], acc[ai][bj][m][n]); __builtin_amdgcn_s_setprio(0); } while (0)
; #define PG8_WAIT_V(n) asm volatile("s_waitcnt vmcnt(" #n ")" ::: "memory")
; #define PG8_WAIT_L(n) asm volatile("s_waitcnt lgkmcnt(" #n ")" ::: "memory")
; #define PG8_BAR __builtin_amdgcn_s_barrier()
; #define PG8_SCHED __builtin_amdgcn_sched_barrier(0)
; template <class Epi, class Sched, bool ALIGN_EPI = false, bool SP2 = false, bool F16 = false>
; __device__ __forceinline__ void gemm_phase(PG8_LAS unsigned char* lds, const Gemm g, const Sched& S, const Epi& E, const int wid_in) {
;     ...
;             const bool last = (t == nt - 2);
;             const char* a1 = cA + (size_t)(t + 1) * kstep;
;             const char* a2 = last ? nA : cA + (size_t)(t + 2) * kstep; const char* b2 = last ? nB : cB + (size_t)(t + 2) * kstep;
;             const char* a3 = a2 + kstep; const char* b3 = b2 + kstep;
;             if (last && has_next) S.a_ready(nxt);
;             if constexpr (SP2) {
;             PG8_LDB(B0, 0, 0); PG8_LDB(B1, 0, 1); PG8_SCHED; PG8_LDA(At, 0, 0); PG8_STAGE(PG8_SA(1, 1), a1 + hstep, voffA);
;             PG8_WAIT_V(8); PG8_WAIT_L(0); PG8_BAR; PG8_MMA(0, 0, At, B0); PG8_MMA(0, 1, At, B1); PG8_BAR; PG8_SCHED;
;             PG8_LDA(At, 0, 1); PG8_STAGE(PG8_SB(0, 0), b2, voffB); PG8_STAGE(PG8_SB(0, 1), b2 + hstep, voffB); PG8_STAGE(PG8_SA(0, 0), a2, voffA);
.LBB0_1242:
	ds_read_b128 v[0:3], v193
	ds_read_b128 v[4:7], v193 offset:1024
	ds_read_b128 v[136:139], v193 offset:2048
	ds_read_b128 v[140:143], v193 offset:3072
	ds_read_b128 v[144:147], v194
	ds_read_b128 v[148:151], v194 offset:1024
	ds_read_b128 v[152:155], v194 offset:2048
	ds_read_b128 v[156:159], v194 offset:3072
	s_add_u32 s48, s46, 0xfffc0080
	s_addc_u32 s49, s47, -1
	s_cmp_eq_u32 s67, 12
	s_cselect_b32 s51, s29, s49
	s_cselect_b32 s50, s42, s48
	s_cselect_b32 s49, s27, s66
	s_cselect_b32 s48, s43, s45
	v_lshl_add_u64 v[188:189], s[46:47], 0, v[168:169]
	s_add_i32 m0, s74, 0xc000
	ds_read_b128 v[176:179], v195
	ds_read_b128 v[180:183], v195 offset:1024
	ds_read_b128 v[184:187], v195 offset:2048
	ds_read_b128 v[198:201], v195 offset:3072
	ds_read_b128 v[202:205], v195 offset:4096
	ds_read_b128 v[206:209], v195 offset:5120
	ds_read_b128 v[210:213], v195 offset:6144
	ds_read_b128 v[214:217], v195 offset:7168
	global_load_lds_dwordx4 v[188:189], off
	v_lshl_add_u64 v[188:189], s[46:47], 0, v[170:171]
	s_add_i32 m0, s74, 0xe000
	s_nop 0
	global_load_lds_dwordx4 v[188:189], off
	s_waitcnt vmcnt(8)
	s_waitcnt lgkmcnt(0)
	s_barrier
	s_waitcnt lgkmcnt(0)
	v_mfma_f32_16x16x32_f16 v[132:135], v[0:3], v[176:179], v[132:135]
	v_mfma_f32_16x16x32_f16 v[128:131], v[136:139], v[176:179], v[128:131]
	v_mfma_f32_16x16x32_f16 v[116:119], v[0:3], v[184:187], v[116:119]
	v_mfma_f32_16x16x32_f16 v[112:115], v[136:139], v[184:187], v[112:115]
	v_mfma_f32_16x16x32_f16 v[100:103], v[0:3], v[202:205], v[100:103]
	v_mfma_f32_16x16x32_f16 v[96:99], v[136:139], v[202:205], v[96:99]
	v_mfma_f32_16x16x32_f16 v[84:87], v[0:3], v[210:213], v[84:87]
	v_mfma_f32_16x16x32_f16 v[80:83], v[136:139], v[210:213], v[80:83]
	v_mfma_f32_16x16x32_f16 v[132:135], v[4:7], v[180:183], v[132:135]
	v_mfma_f32_16x16x32_f16 v[128:131], v[140:143], v[180:183], v[128:131]
	v_mfma_f32_16x16x32_f16 v[116:119], v[4:7], v[198:201], v[116:119]
	v_mfma_f32_16x16x32_f16 v[112:115], v[140:143], v[198:201], v[112:115]
	v_mfma_f32_16x16x32_f16 v[100:103], v[4:7], v[206:209], v[100:103]
	v_mfma_f32_16x16x32_f16 v[96:99], v[140:143], v[206:209], v[96:99]
	v_mfma_f32_16x16x32_f16 v[84:87], v[4:7], v[214:217], v[84:87]
	v_mfma_f32_16x16x32_f16 v[80:83], v[140:143], v[214:217], v[80:83]
	v_mfma_f32_16x16x32_f16 v[124:127], v[144:147], v[176:179], v[124:127]
	v_mfma_f32_16x16x32_f16 v[120:123], v[152:155], v[176:179], v[120:123]
	v_mfma_f32_16x16x32_f16 v[108:111], v[144:147], v[184:187], v[108:111]
	v_mfma_f32_16x16x32_f16 v[104:107], v[152:155], v[184:187], v[104:107]
	v_mfma_f32_16x16x32_f16 v[92:95], v[144:147], v[202:205], v[92:95]
	v_mfma_f32_16x16x32_f16 v[88:91], v[152:155], v[202:205], v[88:91]
	v_mfma_f32_16x16x32_f16 v[76:79], v[144:147], v[210:213], v[76:79]
	v_mfma_f32_16x16x32_f16 v[72:75], v[152:155], v[210:213], v[72:75]
	v_mfma_f32_16x16x32_f16 v[124:127], v[148:151], v[180:183], v[124:127]
	v_mfma_f32_16x16x32_f16 v[120:123], v[156:159], v[180:183], v[120:123]
	v_mfma_f32_16x16x32_f16 v[108:111], v[148:151], v[198:201], v[108:111]
	v_mfma_f32_16x16x32_f16 v[104:107], v[156:159], v[198:201], v[104:107]
	v_mfma_f32_16x16x32_f16 v[92:95], v[148:151], v[206:209], v[92:95]
	v_mfma_f32_16x16x32_f16 v[88:91], v[156:159], v[206:209], v[88:91]
	v_mfma_f32_16x16x32_f16 v[76:79], v[148:151], v[214:217], v[76:79]
	v_mfma_f32_16x16x32_f16 v[72:75], v[156:159], v[214:217], v[72:75]
	s_barrier
	s_add_i32 s76, s63, s68
	v_lshl_add_u64 v[188:189], s[48:49], 0, v[162:163]
	s_mov_b32 m0, s76
	s_nop 0
	global_load_lds_dwordx4 v[188:189], off
	s_add_i32 m0, s76, 0x2000
	s_add_u32 s90, s48, 0x40000
	v_lshl_add_u64 v[218:219], s[48:49], 0, v[166:167]
	s_addc_u32 s91, s49, 0
	s_add_i32 s76, s64, s68
	global_load_lds_dwordx4 v[218:219], off
	v_lshl_add_u64 v[220:221], s[90:91], 0, v[162:163]
	s_mov_b32 m0, s76
	v_lshl_add_u64 v[222:223], s[50:51], 0, v[164:165]
	global_load_lds_dwordx4 v[220:221], off
	v_lshl_add_u64 v[220:221], s[90:91], 0, v[166:167]
	s_add_i32 m0, s76, 0x2000
	s_nop 0
	global_load_lds_dwordx4 v[220:221], off
	v_lshl_add_u64 v[220:221], s[50:51], 0, v[160:161]
	s_mov_b32 m0, s74
	s_nop 0
	global_load_lds_dwordx4 v[220:221], off
	s_mov_b32 m0, s37
	s_nop 0
	global_load_lds_dwordx4 v[222:223], off
	ds_read_b128 v[176:179], v195 offset:16384
	ds_read_b128 v[180:183], v195 offset:17408
	ds_read_b128 v[184:187], v195 offset:18432
	ds_read_b128 v[198:201], v195 offset:19456
	ds_read_b128 v[202:205], v195 offset:20480
	ds_read_b128 v[206:209], v195 offset:21504
	ds_read_b128 v[210:213], v195 offset:22528
	ds_read_b128 v[214:217], v195 offset:23552
	s_waitcnt vmcnt(8)
	s_waitcnt lgkmcnt(0)
	s_barrier
; #define PG8_STAGE(bufoff, gbase, voff) do { _Pragma("unroll") for (int _i = 0; _i < 2; ++_i) \
;         __builtin_amdgcn_global_load_lds((const unsigned*)((const char*)(gbase) + (voff)[_i]), (PG8_LAS unsigned*)(lds + (bufoff) + ldsw + _i * 8192), 16, 0, 0); } while (0)
; #define PG8_LDA(dst, b, h) do { _Pragma("unroll") for (int m = 0; m < 4; ++m) _Pragma("unroll") for (int k = 0; k < 2; ++k) dst[m][k] = *(const PG8_LAS bf16x8*)(lds + PG8_SA(b, h) + aoff + m * 2048 + k * 1024); } while (0)
; #define PG8_LDB(dst, b, h) do { _Pragma("unroll") for (int n = 0; n < 2; ++n) _Pragma("unroll") for (int k = 0; k < 2; ++k) dst[n][k] = *(const PG8_LAS bf16x8*)(lds + PG8_SB(b, h) + boff + n * 2048 + k * 1024); } while (0)
; #define PG8_MMA(ai, bj, At, Bt) do { __builtin_amdgcn_s_setprio(1); _Pragma("unroll") for (int m = 0; m < 4; ++m) _Pragma("unroll") for (int n = 0; n < 2; ++n) _Pragma("unroll") for (int k = 0; k < 2; ++k) \
;         acc[ai][bj][m][n] = mma16<F16>(Bt[n][k], At[m][k], acc[ai][bj][m][n]); __builtin_amdgcn_s_setprio(0); } while (0)
; #define PG8_WAIT_V(n) asm volatile("s_waitcnt vmcnt(" #n ")" ::: "memory")
; #define PG8_WAIT_L(n) asm volatile("s_waitcnt lgkmcnt(" #n ")" ::: "memory")
; #define PG8_BAR __builtin_amdgcn_s_barrier()
; #define PG8_SCHED __builtin_amdgcn_sched_barrier(0)
; template <class Epi, class Sched, bool ALIGN_EPI = false, bool SP2 = false, bool F16 = false>
; __device__ __forceinline__ void gemm_phase(PG8_LAS unsigned char* lds, const Gemm g, const Sched& S, const Epi& E, const int wid_in) {
;     ...
;             PG8_WAIT_V(8); PG8_WAIT_L(0); PG8_BAR; PG8_MMA(1, 0, At, B0); PG8_MMA(1, 1, At, B1); PG8_BAR; PG8_SCHED;
;             PG8_LDB(B0, 1, 0); PG8_LDB(B1, 1, 1); PG8_SCHED; PG8_LDA(At, 1, 0); PG8_STAGE(PG8_SA(0, 1), a2 + hstep, voffA);
;             PG8_WAIT_V(8); PG8_WAIT_L(0); PG8_BAR; PG8_MMA(0, 0, At, B0); PG8_MMA(0, 1, At, B1); PG8_BAR; PG8_SCHED;
	s_waitcnt lgkmcnt(0)
	v_mfma_f32_16x16x32_f16 v[68:71], v[0:3], v[176:179], v[68:71]
	v_mfma_f32_16x16x32_f16 v[64:67], v[136:139], v[176:179], v[64:67]
	v_mfma_f32_16x16x32_f16 v[52:55], v[0:3], v[184:187], v[52:55]
	v_mfma_f32_16x16x32_f16 v[48:51], v[136:139], v[184:187], v[48:51]
	v_mfma_f32_16x16x32_f16 v[36:39], v[0:3], v[202:205], v[36:39]
	v_mfma_f32_16x16x32_f16 v[32:35], v[136:139], v[202:205], v[32:35]
	v_mfma_f32_16x16x32_f16 v[0:3], v[0:3], v[210:213], v[20:23]
	v_mfma_f32_16x16x32_f16 v[68:71], v[4:7], v[180:183], v[68:71]
	v_mfma_f32_16x16x32_f16 v[64:67], v[140:143], v[180:183], v[64:67]
	v_mfma_f32_16x16x32_f16 v[52:55], v[4:7], v[198:201], v[52:55]
	v_mfma_f32_16x16x32_f16 v[48:51], v[140:143], v[198:201], v[48:51]
	v_mfma_f32_16x16x32_f16 v[36:39], v[4:7], v[206:209], v[36:39]
	v_mfma_f32_16x16x32_f16 v[32:35], v[140:143], v[206:209], v[32:35]
	v_mfma_f32_16x16x32_f16 v[0:3], v[4:7], v[214:217], v[0:3]
	v_mfma_f32_16x16x32_f16 v[4:7], v[136:139], v[210:213], v[16:19]
	v_mfma_f32_16x16x32_f16 v[4:7], v[140:143], v[214:217], v[4:7]
	v_mfma_f32_16x16x32_f16 v[16:19], v[144:147], v[176:179], v[60:63]
	v_mfma_f32_16x16x32_f16 v[60:63], v[148:151], v[180:183], v[16:19]
	v_mfma_f32_16x16x32_f16 v[16:19], v[152:155], v[176:179], v[56:59]
	v_mfma_f32_16x16x32_f16 v[56:59], v[156:159], v[180:183], v[16:19]
	v_mfma_f32_16x16x32_f16 v[16:19], v[144:147], v[184:187], v[44:47]
	v_mfma_f32_16x16x32_f16 v[44:47], v[148:151], v[198:201], v[16:19]
	v_mfma_f32_16x16x32_f16 v[16:19], v[152:155], v[184:187], v[40:43]
	v_mfma_f32_16x16x32_f16 v[40:43], v[156:159], v[198:201], v[16:19]
	v_mfma_f32_16x16x32_f16 v[16:19], v[144:147], v[202:205], v[28:31]
	v_mfma_f32_16x16x32_f16 v[28:31], v[148:151], v[206:209], v[16:19]
	v_mfma_f32_16x16x32_f16 v[16:19], v[152:155], v[202:205], v[24:27]
	v_mfma_f32_16x16x32_f16 v[12:15], v[144:147], v[210:213], v[12:15]
	v_mfma_f32_16x16x32_f16 v[8:11], v[152:155], v[210:213], v[8:11]
	v_mfma_f32_16x16x32_f16 v[24:27], v[156:159], v[206:209], v[16:19]
	v_mfma_f32_16x16x32_f16 v[12:15], v[148:151], v[214:217], v[12:15]
	v_mfma_f32_16x16x32_f16 v[8:11], v[156:159], v[214:217], v[8:11]
	s_barrier
	s_add_i32 s76, 0, 0x18000
	s_add_i32 s83, 0, 0x1c000
	v_add_u32_e32 v140, s76, v192
	v_add_u32_e32 v156, s83, v192
	s_add_u32 s50, s50, 0x40000
	s_addc_u32 s51, s51, 0
	s_mov_b32 m0, s53
	v_lshl_add_u64 v[224:225], s[50:51], 0, v[160:161]
	global_load_lds_dwordx4 v[224:225], off
	v_lshl_add_u64 v[224:225], s[50:51], 0, v[164:165]
	s_mov_b32 m0, s54
	s_nop 0
	global_load_lds_dwordx4 v[224:225], off
	ds_read_b128 v[16:19], v140
	ds_read_b128 v[20:23], v140 offset:1024
	ds_read_b128 v[136:139], v140 offset:2048
	ds_read_b128 v[140:143], v140 offset:3072
	ds_read_b128 v[144:147], v156
	ds_read_b128 v[148:151], v156 offset:1024
	ds_read_b128 v[152:155], v156 offset:2048
	ds_read_b128 v[156:159], v156 offset:3072
	ds_read_b128 v[176:179], v195 offset:32768
	ds_read_b128 v[180:183], v195 offset:33792
	ds_read_b128 v[184:187], v195 offset:34816
	ds_read_b128 v[198:201], v195 offset:35840
	ds_read_b128 v[202:205], v195 offset:36864
	ds_read_b128 v[206:209], v195 offset:37888
	ds_read_b128 v[210:213], v195 offset:38912
	ds_read_b128 v[214:217], v195 offset:39936
	s_waitcnt vmcnt(8)
	s_waitcnt lgkmcnt(0)
	s_barrier
	s_waitcnt lgkmcnt(0)
	v_mfma_f32_16x16x32_f16 v[132:135], v[16:19], v[176:179], v[132:135]
	v_mfma_f32_16x16x32_f16 v[128:131], v[136:139], v[176:179], v[128:131]
	v_mfma_f32_16x16x32_f16 v[116:119], v[16:19], v[184:187], v[116:119]
	v_mfma_f32_16x16x32_f16 v[112:115], v[136:139], v[184:187], v[112:115]
	v_mfma_f32_16x16x32_f16 v[100:103], v[16:19], v[202:205], v[100:103]
	v_mfma_f32_16x16x32_f16 v[96:99], v[136:139], v[202:205], v[96:99]
	v_mfma_f32_16x16x32_f16 v[84:87], v[16:19], v[210:213], v[84:87]
	v_mfma_f32_16x16x32_f16 v[80:83], v[136:139], v[210:213], v[80:83]
	v_mfma_f32_16x16x32_f16 v[132:135], v[20:23], v[180:183], v[132:135]
	v_mfma_f32_16x16x32_f16 v[128:131], v[140:143], v[180:183], v[128:131]
	v_mfma_f32_16x16x32_f16 v[116:119], v[20:23], v[198:201], v[116:119]
	v_mfma_f32_16x16x32_f16 v[112:115], v[140:143], v[198:201], v[112:115]
	v_mfma_f32_16x16x32_f16 v[100:103], v[20:23], v[206:209], v[100:103]
	v_mfma_f32_16x16x32_f16 v[96:99], v[140:143], v[206:209], v[96:99]
	v_mfma_f32_16x16x32_f16 v[84:87], v[20:23], v[214:217], v[84:87]
	v_mfma_f32_16x16x32_f16 v[80:83], v[140:143], v[214:217], v[80:83]
	v_mfma_f32_16x16x32_f16 v[124:127], v[144:147], v[176:179], v[124:127]
	v_mfma_f32_16x16x32_f16 v[120:123], v[152:155], v[176:179], v[120:123]
	v_mfma_f32_16x16x32_f16 v[108:111], v[144:147], v[184:187], v[108:111]
	v_mfma_f32_16x16x32_f16 v[104:107], v[152:155], v[184:187], v[104:107]
	v_mfma_f32_16x16x32_f16 v[92:95], v[144:147], v[202:205], v[92:95]
	v_mfma_f32_16x16x32_f16 v[88:91], v[152:155], v[202:205], v[88:91]
	v_mfma_f32_16x16x32_f16 v[76:79], v[144:147], v[210:213], v[76:79]
	v_mfma_f32_16x16x32_f16 v[72:75], v[152:155], v[210:213], v[72:75]
	v_mfma_f32_16x16x32_f16 v[124:127], v[148:151], v[180:183], v[124:127]
	v_mfma_f32_16x16x32_f16 v[120:123], v[156:159], v[180:183], v[120:123]
	v_mfma_f32_16x16x32_f16 v[108:111], v[148:151], v[198:201], v[108:111]
	v_mfma_f32_16x16x32_f16 v[104:107], v[156:159], v[198:201], v[104:107]
	v_mfma_f32_16x16x32_f16 v[92:95], v[148:151], v[206:209], v[92:95]
	v_mfma_f32_16x16x32_f16 v[88:91], v[156:159], v[206:209], v[88:91]
	v_mfma_f32_16x16x32_f16 v[76:79], v[148:151], v[214:217], v[76:79]
	v_mfma_f32_16x16x32_f16 v[72:75], v[156:159], v[214:217], v[72:75]
	s_barrier
; #define PG8_STAGE(bufoff, gbase, voff) do { _Pragma("unroll") for (int _i = 0; _i < 2; ++_i) \
;         __builtin_amdgcn_global_load_lds((const unsigned*)((const char*)(gbase) + (voff)[_i]), (PG8_LAS unsigned*)(lds + (bufoff) + ldsw + _i * 8192), 16, 0, 0); } while (0)
; #define PG8_LDA(dst, b, h) do { _Pragma("unroll") for (int m = 0; m < 4; ++m) _Pragma("unroll") for (int k = 0; k < 2; ++k) dst[m][k] = *(const PG8_LAS bf16x8*)(lds + PG8_SA(b, h) + aoff + m * 2048 + k * 1024); } while (0)
; #define PG8_MMA(ai, bj, At, Bt) do { __builtin_amdgcn_s_setprio(1); _Pragma("unroll") for (int m = 0; m < 4; ++m) _Pragma("unroll") for (int n = 0; n < 2; ++n) _Pragma("unroll") for (int k = 0; k < 2; ++k) \
;         acc[ai][bj][m][n] = mma16<F16>(Bt[n][k], At[m][k], acc[ai][bj][m][n]); __builtin_amdgcn_s_setprio(0); } while (0)
; #define PG8_WAIT_V(n) asm volatile("s_waitcnt vmcnt(" #n ")" ::: "memory")
; #define PG8_WAIT_L(n) asm volatile("s_waitcnt lgkmcnt(" #n ")" ::: "memory")
; #define PG8_BAR __builtin_amdgcn_s_barrier()
; #define PG8_SCHED __builtin_amdgcn_sched_barrier(0)
; template <class Epi, class Sched, bool ALIGN_EPI = false, bool SP2 = false, bool F16 = false>
; __device__ __forceinline__ void gemm_phase(PG8_LAS unsigned char* lds, const Gemm g, const Sched& S, const Epi& E, const int wid_in) {
;     ...
;             PG8_LDA(At, 1, 1); PG8_STAGE(PG8_SB(1, 0), b3, voffB); PG8_STAGE(PG8_SB(1, 1), b3 + hstep, voffB); PG8_STAGE(PG8_SA(1, 0), a3, voffA);
;             PG8_WAIT_V(8); PG8_WAIT_L(0); PG8_BAR; PG8_MMA(1, 0, At, B0); PG8_MMA(1, 1, At, B1); PG8_BAR; PG8_SCHED;
;     ...
;         if constexpr (ALIGN_EPI) { if (wr == 0) PG8_BAR; }
	s_add_i32 s50, s76, s68
	v_lshl_add_u64 v[188:189], v[188:189], 0, s[24:25]
	s_mov_b32 m0, s50
	s_nop 0
	global_load_lds_dwordx4 v[188:189], off
	s_add_i32 m0, s50, 0x2000
	s_add_u32 s48, s48, 0x40080
	v_lshl_add_u64 v[188:189], v[218:219], 0, s[24:25]
	s_addc_u32 s49, s49, 0
	s_add_i32 s50, s83, s68
	global_load_lds_dwordx4 v[188:189], off
	v_lshl_add_u64 v[188:189], s[48:49], 0, v[162:163]
	s_mov_b32 m0, s50
	s_nop 0
	global_load_lds_dwordx4 v[188:189], off
	v_lshl_add_u64 v[188:189], s[48:49], 0, v[166:167]
	s_add_i32 m0, s50, 0x2000
	s_nop 0
	global_load_lds_dwordx4 v[188:189], off
	v_lshl_add_u64 v[188:189], v[220:221], 0, s[24:25]
	s_mov_b32 m0, s75
	s_nop 0
	global_load_lds_dwordx4 v[188:189], off
	v_lshl_add_u64 v[188:189], v[222:223], 0, s[24:25]
	s_mov_b32 m0, s57
	s_nop 0
	global_load_lds_dwordx4 v[188:189], off
	ds_read_b128 v[176:179], v195 offset:49152
	ds_read_b128 v[180:183], v195 offset:50176
	ds_read_b128 v[184:187], v195 offset:51200
	ds_read_b128 v[198:201], v195 offset:52224
	ds_read_b128 v[202:205], v195 offset:53248
	ds_read_b128 v[206:209], v195 offset:54272
	ds_read_b128 v[210:213], v195 offset:55296
	ds_read_b128 v[214:217], v195 offset:56320
	s_waitcnt vmcnt(8)
	s_waitcnt lgkmcnt(0)
	s_barrier
	s_waitcnt lgkmcnt(0)
	v_mfma_f32_16x16x32_f16 v[68:71], v[16:19], v[176:179], v[68:71]
	v_mfma_f32_16x16x32_f16 v[52:55], v[16:19], v[184:187], v[52:55]
	v_mfma_f32_16x16x32_f16 v[36:39], v[16:19], v[202:205], v[36:39]
	v_mfma_f32_16x16x32_f16 v[0:3], v[16:19], v[210:213], v[0:3]
	v_mfma_f32_16x16x32_f16 v[68:71], v[20:23], v[180:183], v[68:71]
	v_mfma_f32_16x16x32_f16 v[64:67], v[136:139], v[176:179], v[64:67]
	v_mfma_f32_16x16x32_f16 v[52:55], v[20:23], v[198:201], v[52:55]
	v_mfma_f32_16x16x32_f16 v[48:51], v[136:139], v[184:187], v[48:51]
	v_mfma_f32_16x16x32_f16 v[36:39], v[20:23], v[206:209], v[36:39]
	v_mfma_f32_16x16x32_f16 v[32:35], v[136:139], v[202:205], v[32:35]
	v_mfma_f32_16x16x32_f16 v[20:23], v[20:23], v[214:217], v[0:3]
	v_mfma_f32_16x16x32_f16 v[0:3], v[136:139], v[210:213], v[4:7]
	v_mfma_f32_16x16x32_f16 v[64:67], v[140:143], v[180:183], v[64:67]
	v_mfma_f32_16x16x32_f16 v[48:51], v[140:143], v[198:201], v[48:51]
	v_mfma_f32_16x16x32_f16 v[32:35], v[140:143], v[206:209], v[32:35]
	v_mfma_f32_16x16x32_f16 v[16:19], v[140:143], v[214:217], v[0:3]
	v_mfma_f32_16x16x32_f16 v[0:3], v[144:147], v[176:179], v[60:63]
	v_mfma_f32_16x16x32_f16 v[60:63], v[148:151], v[180:183], v[0:3]
	v_mfma_f32_16x16x32_f16 v[0:3], v[152:155], v[176:179], v[56:59]
	v_mfma_f32_16x16x32_f16 v[56:59], v[156:159], v[180:183], v[0:3]
	v_mfma_f32_16x16x32_f16 v[0:3], v[144:147], v[184:187], v[44:47]
	v_mfma_f32_16x16x32_f16 v[44:47], v[148:151], v[198:201], v[0:3]
	v_mfma_f32_16x16x32_f16 v[0:3], v[152:155], v[184:187], v[40:43]
	v_mfma_f32_16x16x32_f16 v[40:43], v[156:159], v[198:201], v[0:3]
	v_mfma_f32_16x16x32_f16 v[0:3], v[144:147], v[202:205], v[28:31]
	v_mfma_f32_16x16x32_f16 v[28:31], v[148:151], v[206:209], v[0:3]
	v_mfma_f32_16x16x32_f16 v[0:3], v[152:155], v[202:205], v[24:27]
	v_mfma_f32_16x16x32_f16 v[24:27], v[156:159], v[206:209], v[0:3]
	v_mfma_f32_16x16x32_f16 v[0:3], v[144:147], v[210:213], v[12:15]
	v_mfma_f32_16x16x32_f16 v[12:15], v[148:151], v[214:217], v[0:3]
	v_mfma_f32_16x16x32_f16 v[0:3], v[152:155], v[210:213], v[8:11]
	v_mfma_f32_16x16x32_f16 v[8:11], v[156:159], v[214:217], v[0:3]
	s_barrier
	s_add_i32 s67, s67, 2
	s_add_u32 s46, s46, 0x100
	s_addc_u32 s47, s47, 0
	s_add_u32 s45, s45, 0x100
	s_addc_u32 s66, s66, 0
	s_cmp_gt_u32 s67, 13
	s_cbranch_scc0 .LBB0_1242
	s_and_b64 vcc, exec, s[16:17]
	s_cbranch_vccz .LBB0_1245
	s_barrier

; #define PG8_STAGE(bufoff, gbase, voff) do { _Pragma("unroll") for (int _i = 0; _i < 2; ++_i) \
;         __builtin_amdgcn_global_load_lds((const unsigned*)((const char*)(gbase) + (voff)[_i]), (PG8_LAS unsigned*)(lds + (bufoff) + ldsw + _i * 8192), 16, 0, 0); } while (0)
; #define PG8_LDA(dst, b, h) do { _Pragma("unroll") for (int m = 0; m < 4; ++m) _Pragma("unroll") for (int k = 0; k < 2; ++k) dst[m][k] = *(const PG8_LAS bf16x8*)(lds + PG8_SA(b, h) + aoff + m * 2048 + k * 1024); } while (0)
; #define PG8_LDB(dst, b, h) do { _Pragma("unroll") for (int n = 0; n < 2; ++n) _Pragma("unroll") for (int k = 0; k < 2; ++k) dst[n][k] = *(const PG8_LAS bf16x8*)(lds + PG8_SB(b, h) + boff + n * 2048 + k * 1024); } while (0)
; #define PG8_MMA(ai, bj, At, Bt) do { __builtin_amdgcn_s_setprio(1); _Pragma("unroll") for (int m = 0; m < 4; ++m) _Pragma("unroll") for (int n = 0; n < 2; ++n) _Pragma("unroll") for (int k = 0; k < 2; ++k) \
;         acc[ai][bj][m][n] = mma16<F16>(Bt[n][k], At[m][k], acc[ai][bj][m][n]); __builtin_amdgcn_s_setprio(0); } while (0)
; #define PG8_BAR __builtin_amdgcn_s_barrier()
; template <class Epi, class Sched, bool ALIGN_EPI = false, bool SP2 = false, bool F16 = false>
; __device__ __forceinline__ void gemm_phase(PG8_LAS unsigned char* lds, const Gemm g, const Sched& S, const Epi& E, const int wid_in) {
;     ...
;         const bool has_next = S.next(ui + 1, nxt);
;         const char* nA = has_next ? (const char*)g.A + (size_t)nxt.pm * tstep : cA; const char* nB = has_next ? (const char*)g.Bt + (size_t)nxt.pn * tstep : cB;
;         for (int t = 0; t < nt; t += 2) {
;             const bool last = (t == nt - 2);
;             const char* a1 = cA + (size_t)(t + 1) * kstep;
;             const char* a2 = last ? nA : cA + (size_t)(t + 2) * kstep; const char* b2 = last ? nB : cB + (size_t)(t + 2) * kstep;
;             const char* a3 = a2 + kstep; const char* b3 = b2 + kstep;
;             if (last && has_next) S.a_ready(nxt);
;             if constexpr (SP2) {
;             PG8_LDB(B0, 0, 0); PG8_LDB(B1, 0, 1); PG8_SCHED; PG8_LDA(At, 0, 0); PG8_STAGE(PG8_SA(1, 1), a1 + hstep, voffA);
;             PG8_WAIT_V(8); PG8_WAIT_L(0); PG8_BAR; PG8_MMA(0, 0, At, B0); PG8_MMA(0, 1, At, B1); PG8_BAR; PG8_SCHED;
;             PG8_LDA(At, 0, 1); PG8_STAGE(PG8_SB(0, 0), b2, voffB); PG8_STAGE(PG8_SB(0, 1), b2 + hstep, voffB); PG8_STAGE(PG8_SA(0, 0), a2, voffA);
.LBB0_1277:
	s_mov_b64 s[48:49], s[10:11]
	s_add_i32 s10, s36, s19
	s_mov_b64 s[46:47], s[12:13]
	s_mov_b32 s12, s62
	s_mov_b32 s13, s61
	s_and_b32 s61, s10, 3
	s_ashr_i32 s62, s10, 2
	s_and_b64 s[10:11], s[30:31], exec
	s_cselect_b32 s12, s62, s12
	ds_read_b128 v[0:3], v134
	ds_read_b128 v[4:7], v134 offset:1024
	ds_read_b128 v[8:11], v134 offset:2048
	ds_read_b128 v[12:15], v134 offset:3072
	ds_read_b128 v[16:19], v135
	ds_read_b128 v[20:23], v135 offset:1024
	ds_read_b128 v[24:27], v135 offset:2048
	ds_read_b128 v[28:31], v135 offset:3072
	s_cselect_b32 s10, s61, s13
	s_ashr_i32 s13, s12, 31
	s_lshl_b64 s[12:13], s[12:13], 17
	s_add_u32 s12, s21, s12
	s_addc_u32 s13, s40, s13
	s_and_b64 s[36:37], s[30:31], exec
	s_cselect_b32 s45, s13, s47
	s_cselect_b32 s44, s12, s46
	s_ashr_i32 s11, s10, 31
	s_lshl_b64 s[10:11], s[10:11], 17
	s_add_u32 s10, s41, s10
	s_addc_u32 s11, s42, s11
	s_and_b64 s[36:37], s[30:31], exec
	s_cselect_b32 s37, s11, s49
	s_cselect_b32 s36, s10, s48
	s_add_u32 s64, s46, 0x10080
	s_addc_u32 s65, s47, 0
	s_mov_b32 m0, s15
	v_lshl_add_u64 v[64:65], s[64:65], 0, v[130:131]
	ds_read_b128 v[32:35], v136
	ds_read_b128 v[36:39], v136 offset:1024
	ds_read_b128 v[40:43], v136 offset:2048
	ds_read_b128 v[44:47], v136 offset:3072
	ds_read_b128 v[48:51], v136 offset:4096
	ds_read_b128 v[52:55], v136 offset:5120
	ds_read_b128 v[56:59], v136 offset:6144
	ds_read_b128 v[60:63], v136 offset:7168
	global_load_lds_dwordx4 v[64:65], off
	v_lshl_add_u64 v[64:65], s[64:65], 0, v[128:129]
	s_mov_b32 m0, s52
	s_nop 0
	global_load_lds_dwordx4 v[64:65], off
	s_waitcnt vmcnt(8)
	s_waitcnt lgkmcnt(0)
	s_barrier
	s_waitcnt lgkmcnt(0)
	v_mfma_f32_16x16x32_bf16 v[64:67], v[0:3], v[32:35], 0
	v_mfma_f32_16x16x32_bf16 v[68:71], v[8:11], v[32:35], 0
	v_mfma_f32_16x16x32_bf16 v[72:75], v[0:3], v[40:43], 0
	v_mfma_f32_16x16x32_bf16 v[76:79], v[8:11], v[40:43], 0
	v_mfma_f32_16x16x32_bf16 v[80:83], v[0:3], v[48:51], 0
	v_mfma_f32_16x16x32_bf16 v[84:87], v[8:11], v[48:51], 0
	v_mfma_f32_16x16x32_bf16 v[88:91], v[0:3], v[56:59], 0
	v_mfma_f32_16x16x32_bf16 v[92:95], v[8:11], v[56:59], 0
	v_mfma_f32_16x16x32_bf16 v[64:67], v[4:7], v[36:39], v[64:67]
	v_mfma_f32_16x16x32_bf16 v[68:71], v[12:15], v[36:39], v[68:71]
	v_mfma_f32_16x16x32_bf16 v[72:75], v[4:7], v[44:47], v[72:75]
	v_mfma_f32_16x16x32_bf16 v[76:79], v[12:15], v[44:47], v[76:79]
	v_mfma_f32_16x16x32_bf16 v[80:83], v[4:7], v[52:55], v[80:83]
	v_mfma_f32_16x16x32_bf16 v[84:87], v[12:15], v[52:55], v[84:87]
	v_mfma_f32_16x16x32_bf16 v[88:91], v[4:7], v[60:63], v[88:91]
	v_mfma_f32_16x16x32_bf16 v[92:95], v[12:15], v[60:63], v[92:95]
	v_mfma_f32_16x16x32_bf16 v[96:99], v[16:19], v[32:35], 0
	v_mfma_f32_16x16x32_bf16 v[32:35], v[24:27], v[32:35], 0
	v_mfma_f32_16x16x32_bf16 v[96:99], v[20:23], v[36:39], v[96:99]
	v_mfma_f32_16x16x32_bf16 v[32:35], v[28:31], v[36:39], v[32:35]
	v_mfma_f32_16x16x32_bf16 v[36:39], v[16:19], v[40:43], 0
	v_mfma_f32_16x16x32_bf16 v[40:43], v[24:27], v[40:43], 0
	v_mfma_f32_16x16x32_bf16 v[36:39], v[20:23], v[44:47], v[36:39]
	v_mfma_f32_16x16x32_bf16 v[40:43], v[28:31], v[44:47], v[40:43]
	v_mfma_f32_16x16x32_bf16 v[44:47], v[16:19], v[48:51], 0
	v_mfma_f32_16x16x32_bf16 v[48:51], v[24:27], v[48:51], 0
	v_mfma_f32_16x16x32_bf16 v[44:47], v[20:23], v[52:55], v[44:47]
	v_mfma_f32_16x16x32_bf16 v[48:51], v[28:31], v[52:55], v[48:51]
	v_mfma_f32_16x16x32_bf16 v[52:55], v[16:19], v[56:59], 0
	v_mfma_f32_16x16x32_bf16 v[56:59], v[24:27], v[56:59], 0
	v_mfma_f32_16x16x32_bf16 v[52:55], v[20:23], v[60:63], v[52:55]
	v_mfma_f32_16x16x32_bf16 v[56:59], v[28:31], v[60:63], v[56:59]
	s_barrier
	v_lshl_add_u64 v[204:205], s[48:49], 0, v[130:131]
	s_mov_b32 m0, s53
	v_lshl_add_u64 v[140:141], v[204:205], 0, s[26:27]
	v_lshl_add_u64 v[206:207], s[48:49], 0, v[128:129]
	s_add_u32 s64, s48, 0x10100
	global_load_lds_dwordx4 v[140:141], off
	v_lshl_add_u64 v[140:141], v[206:207], 0, s[26:27]
	s_mov_b32 m0, s54
	s_addc_u32 s65, s49, 0
	global_load_lds_dwordx4 v[140:141], off
	v_lshl_add_u64 v[140:141], s[64:65], 0, v[130:131]
	s_mov_b32 m0, s55
	v_lshl_add_u64 v[208:209], s[46:47], 0, v[130:131]
	global_load_lds_dwordx4 v[140:141], off
	v_lshl_add_u64 v[140:141], s[64:65], 0, v[128:129]
	s_mov_b32 m0, s56
	v_lshl_add_u64 v[210:211], s[46:47], 0, v[128:129]
	global_load_lds_dwordx4 v[140:141], off
	v_lshl_add_u64 v[140:141], v[208:209], 0, s[26:27]
	s_mov_b32 m0, s74
	s_nop 0
	global_load_lds_dwordx4 v[140:141], off
	v_lshl_add_u64 v[140:141], v[210:211], 0, s[26:27]
	s_mov_b32 m0, s43
	s_nop 0
	global_load_lds_dwordx4 v[140:141], off
	ds_read_b128 v[60:63], v136 offset:16384
	ds_read_b128 v[100:103], v136 offset:17408
	ds_read_b128 v[104:107], v136 offset:18432
	ds_read_b128 v[108:111], v136 offset:19456
	ds_read_b128 v[112:115], v136 offset:20480
	ds_read_b128 v[116:119], v136 offset:21504
	ds_read_b128 v[120:123], v136 offset:22528
	ds_read_b128 v[124:127], v136 offset:23552
	s_waitcnt vmcnt(8)
	s_waitcnt lgkmcnt(0)
	s_barrier
; #define PG8_STAGE(bufoff, gbase, voff) do { _Pragma("unroll") for (int _i = 0; _i < 2; ++_i) \
;         __builtin_amdgcn_global_load_lds((const unsigned*)((const char*)(gbase) + (voff)[_i]), (PG8_LAS unsigned*)(lds + (bufoff) + ldsw + _i * 8192), 16, 0, 0); } while (0)
; #define PG8_LDA(dst, b, h) do { _Pragma("unroll") for (int m = 0; m < 4; ++m) _Pragma("unroll") for (int k = 0; k < 2; ++k) dst[m][k] = *(const PG8_LAS bf16x8*)(lds + PG8_SA(b, h) + aoff + m * 2048 + k * 1024); } while (0)
; #define PG8_LDB(dst, b, h) do { _Pragma("unroll") for (int n = 0; n < 2; ++n) _Pragma("unroll") for (int k = 0; k < 2; ++k) dst[n][k] = *(const PG8_LAS bf16x8*)(lds + PG8_SB(b, h) + boff + n * 2048 + k * 1024); } while (0)
; #define PG8_MMA(ai, bj, At, Bt) do { __builtin_amdgcn_s_setprio(1); _Pragma("unroll") for (int m = 0; m < 4; ++m) _Pragma("unroll") for (int n = 0; n < 2; ++n) _Pragma("unroll") for (int k = 0; k < 2; ++k) \
;         acc[ai][bj][m][n] = mma16<F16>(Bt[n][k], At[m][k], acc[ai][bj][m][n]); __builtin_amdgcn_s_setprio(0); } while (0)
; #define PG8_WAIT_V(n) asm volatile("s_waitcnt vmcnt(" #n ")" ::: "memory")
; #define PG8_WAIT_L(n) asm volatile("s_waitcnt lgkmcnt(" #n ")" ::: "memory")
; #define PG8_BAR __builtin_amdgcn_s_barrier()
; #define PG8_SCHED __builtin_amdgcn_sched_barrier(0)
; template <class Epi, class Sched, bool ALIGN_EPI = false, bool SP2 = false, bool F16 = false>
; __device__ __forceinline__ void gemm_phase(PG8_LAS unsigned char* lds, const Gemm g, const Sched& S, const Epi& E, const int wid_in) {
;     ...
;             PG8_LDA(At, 0, 1); PG8_STAGE(PG8_SB(0, 0), b2, voffB); PG8_STAGE(PG8_SB(0, 1), b2 + hstep, voffB); PG8_STAGE(PG8_SA(0, 0), a2, voffA);
;             PG8_WAIT_V(8); PG8_WAIT_L(0); PG8_BAR; PG8_MMA(1, 0, At, B0); PG8_MMA(1, 1, At, B1); PG8_BAR; PG8_SCHED;
;             PG8_LDB(B0, 1, 0); PG8_LDB(B1, 1, 1); PG8_SCHED; PG8_LDA(At, 1, 0); PG8_STAGE(PG8_SA(0, 1), a2 + hstep, voffA);
;             PG8_WAIT_V(8); PG8_WAIT_L(0); PG8_BAR; PG8_MMA(0, 0, At, B0); PG8_MMA(0, 1, At, B1); PG8_BAR; PG8_SCHED;
	s_waitcnt lgkmcnt(0)
	v_mfma_f32_16x16x32_bf16 v[140:143], v[0:3], v[60:63], 0
	v_mfma_f32_16x16x32_bf16 v[148:151], v[0:3], v[104:107], 0
	v_mfma_f32_16x16x32_bf16 v[156:159], v[0:3], v[112:115], 0
	v_mfma_f32_16x16x32_bf16 v[0:3], v[0:3], v[120:123], 0
	v_mfma_f32_16x16x32_bf16 v[140:143], v[4:7], v[100:103], v[140:143]
	v_mfma_f32_16x16x32_bf16 v[148:151], v[4:7], v[108:111], v[148:151]
	v_mfma_f32_16x16x32_bf16 v[156:159], v[4:7], v[116:119], v[156:159]
	v_mfma_f32_16x16x32_bf16 v[0:3], v[4:7], v[124:127], v[0:3]
	v_mfma_f32_16x16x32_bf16 v[4:7], v[8:11], v[120:123], 0
	v_mfma_f32_16x16x32_bf16 v[144:147], v[8:11], v[60:63], 0
	v_mfma_f32_16x16x32_bf16 v[152:155], v[8:11], v[104:107], 0
	v_mfma_f32_16x16x32_bf16 v[160:163], v[8:11], v[112:115], 0
	v_mfma_f32_16x16x32_bf16 v[4:7], v[12:15], v[124:127], v[4:7]
	v_mfma_f32_16x16x32_bf16 v[144:147], v[12:15], v[100:103], v[144:147]
	v_mfma_f32_16x16x32_bf16 v[152:155], v[12:15], v[108:111], v[152:155]
	v_mfma_f32_16x16x32_bf16 v[160:163], v[12:15], v[116:119], v[160:163]
	v_mfma_f32_16x16x32_bf16 v[8:11], v[16:19], v[60:63], 0
	v_mfma_f32_16x16x32_bf16 v[12:15], v[24:27], v[60:63], 0
	v_mfma_f32_16x16x32_bf16 v[8:11], v[20:23], v[100:103], v[8:11]
	v_mfma_f32_16x16x32_bf16 v[12:15], v[28:31], v[100:103], v[12:15]
	v_mfma_f32_16x16x32_bf16 v[60:63], v[16:19], v[104:107], 0
	v_mfma_f32_16x16x32_bf16 v[100:103], v[24:27], v[104:107], 0
	v_mfma_f32_16x16x32_bf16 v[104:107], v[16:19], v[112:115], 0
	v_mfma_f32_16x16x32_bf16 v[16:19], v[16:19], v[120:123], 0
	v_mfma_f32_16x16x32_bf16 v[60:63], v[20:23], v[108:111], v[60:63]
	v_mfma_f32_16x16x32_bf16 v[100:103], v[28:31], v[108:111], v[100:103]
	v_mfma_f32_16x16x32_bf16 v[104:107], v[20:23], v[116:119], v[104:107]
	v_mfma_f32_16x16x32_bf16 v[108:111], v[24:27], v[112:115], 0
	v_mfma_f32_16x16x32_bf16 v[16:19], v[20:23], v[124:127], v[16:19]
	v_mfma_f32_16x16x32_bf16 v[20:23], v[24:27], v[120:123], 0
	v_mfma_f32_16x16x32_bf16 v[108:111], v[28:31], v[116:119], v[108:111]
	v_mfma_f32_16x16x32_bf16 v[20:23], v[28:31], v[124:127], v[20:23]
	s_barrier
	s_add_u32 s64, s46, 0x10100
	s_addc_u32 s65, s47, 0
	s_mov_b32 m0, s50
	v_lshl_add_u64 v[212:213], s[64:65], 0, v[130:131]
	global_load_lds_dwordx4 v[212:213], off
	v_lshl_add_u64 v[212:213], s[64:65], 0, v[128:129]
	s_mov_b32 m0, s51
	s_nop 0
	global_load_lds_dwordx4 v[212:213], off
	ds_read_b128 v[24:27], v137
	ds_read_b128 v[28:31], v137 offset:1024
	ds_read_b128 v[112:115], v137 offset:2048
	ds_read_b128 v[116:119], v137 offset:3072
	ds_read_b128 v[120:123], v138
	ds_read_b128 v[124:127], v138 offset:1024
	ds_read_b128 v[164:167], v138 offset:2048
	ds_read_b128 v[168:171], v138 offset:3072
	ds_read_b128 v[172:175], v136 offset:32768
	ds_read_b128 v[176:179], v136 offset:33792
	ds_read_b128 v[180:183], v136 offset:34816
	ds_read_b128 v[184:187], v136 offset:35840
	ds_read_b128 v[188:191], v136 offset:36864
	ds_read_b128 v[192:195], v136 offset:37888
	ds_read_b128 v[196:199], v136 offset:38912
	ds_read_b128 v[200:203], v136 offset:39936
	s_waitcnt vmcnt(8)
	s_waitcnt lgkmcnt(0)
	s_barrier
	s_waitcnt lgkmcnt(0)
	v_mfma_f32_16x16x32_bf16 v[64:67], v[24:27], v[172:175], v[64:67]
	v_mfma_f32_16x16x32_bf16 v[68:71], v[112:115], v[172:175], v[68:71]
	v_mfma_f32_16x16x32_bf16 v[72:75], v[24:27], v[180:183], v[72:75]
	v_mfma_f32_16x16x32_bf16 v[76:79], v[112:115], v[180:183], v[76:79]
	v_mfma_f32_16x16x32_bf16 v[80:83], v[24:27], v[188:191], v[80:83]
	v_mfma_f32_16x16x32_bf16 v[84:87], v[112:115], v[188:191], v[84:87]
	v_mfma_f32_16x16x32_bf16 v[88:91], v[24:27], v[196:199], v[88:91]
	v_mfma_f32_16x16x32_bf16 v[92:95], v[112:115], v[196:199], v[92:95]
	v_mfma_f32_16x16x32_bf16 v[64:67], v[28:31], v[176:179], v[64:67]
	v_mfma_f32_16x16x32_bf16 v[68:71], v[116:119], v[176:179], v[68:71]
	v_mfma_f32_16x16x32_bf16 v[72:75], v[28:31], v[184:187], v[72:75]
	v_mfma_f32_16x16x32_bf16 v[76:79], v[116:119], v[184:187], v[76:79]
	v_mfma_f32_16x16x32_bf16 v[80:83], v[28:31], v[192:195], v[80:83]
	v_mfma_f32_16x16x32_bf16 v[84:87], v[116:119], v[192:195], v[84:87]
	v_mfma_f32_16x16x32_bf16 v[88:91], v[28:31], v[200:203], v[88:91]
	v_mfma_f32_16x16x32_bf16 v[92:95], v[116:119], v[200:203], v[92:95]
	v_mfma_f32_16x16x32_bf16 v[96:99], v[120:123], v[172:175], v[96:99]
	v_mfma_f32_16x16x32_bf16 v[32:35], v[164:167], v[172:175], v[32:35]
	v_mfma_f32_16x16x32_bf16 v[36:39], v[120:123], v[180:183], v[36:39]
	v_mfma_f32_16x16x32_bf16 v[40:43], v[164:167], v[180:183], v[40:43]
	v_mfma_f32_16x16x32_bf16 v[44:47], v[120:123], v[188:191], v[44:47]
	v_mfma_f32_16x16x32_bf16 v[48:51], v[164:167], v[188:191], v[48:51]
	v_mfma_f32_16x16x32_bf16 v[52:55], v[120:123], v[196:199], v[52:55]
	v_mfma_f32_16x16x32_bf16 v[56:59], v[164:167], v[196:199], v[56:59]
	v_mfma_f32_16x16x32_bf16 v[96:99], v[124:127], v[176:179], v[96:99]
	v_mfma_f32_16x16x32_bf16 v[32:35], v[168:171], v[176:179], v[32:35]
	v_mfma_f32_16x16x32_bf16 v[36:39], v[124:127], v[184:187], v[36:39]
	v_mfma_f32_16x16x32_bf16 v[40:43], v[168:171], v[184:187], v[40:43]
	v_mfma_f32_16x16x32_bf16 v[44:47], v[124:127], v[192:195], v[44:47]
	v_mfma_f32_16x16x32_bf16 v[48:51], v[168:171], v[192:195], v[48:51]
	v_mfma_f32_16x16x32_bf16 v[52:55], v[124:127], v[200:203], v[52:55]
	v_mfma_f32_16x16x32_bf16 v[56:59], v[168:171], v[200:203], v[56:59]
	s_barrier
; #define PG8_STAGE(bufoff, gbase, voff) do { _Pragma("unroll") for (int _i = 0; _i < 2; ++_i) \
;         __builtin_amdgcn_global_load_lds((const unsigned*)((const char*)(gbase) + (voff)[_i]), (PG8_LAS unsigned*)(lds + (bufoff) + ldsw + _i * 8192), 16, 0, 0); } while (0)
; #define PG8_LDA(dst, b, h) do { _Pragma("unroll") for (int m = 0; m < 4; ++m) _Pragma("unroll") for (int k = 0; k < 2; ++k) dst[m][k] = *(const PG8_LAS bf16x8*)(lds + PG8_SA(b, h) + aoff + m * 2048 + k * 1024); } while (0)
; #define PG8_LDB(dst, b, h) do { _Pragma("unroll") for (int n = 0; n < 2; ++n) _Pragma("unroll") for (int k = 0; k < 2; ++k) dst[n][k] = *(const PG8_LAS bf16x8*)(lds + PG8_SB(b, h) + boff + n * 2048 + k * 1024); } while (0)
; #define PG8_MMA(ai, bj, At, Bt) do { __builtin_amdgcn_s_setprio(1); _Pragma("unroll") for (int m = 0; m < 4; ++m) _Pragma("unroll") for (int n = 0; n < 2; ++n) _Pragma("unroll") for (int k = 0; k < 2; ++k) \
;         acc[ai][bj][m][n] = mma16<F16>(Bt[n][k], At[m][k], acc[ai][bj][m][n]); __builtin_amdgcn_s_setprio(0); } while (0)
; #define PG8_WAIT_V(n) asm volatile("s_waitcnt vmcnt(" #n ")" ::: "memory")
; template <class Epi, class Sched, bool ALIGN_EPI = false, bool SP2 = false, bool F16 = false>
; __device__ __forceinline__ void gemm_phase(PG8_LAS unsigned char* lds, const Gemm g, const Sched& S, const Epi& E, const int wid_in) {
;     ...
;             PG8_LDB(B0, 0, 0); PG8_LDB(B1, 0, 1); PG8_SCHED; PG8_LDA(At, 0, 0); PG8_STAGE(PG8_SA(1, 1), a1 + hstep, voffA);
;             PG8_WAIT_V(8); PG8_WAIT_L(0); PG8_BAR; PG8_MMA(0, 0, At, B0); PG8_MMA(0, 1, At, B1); PG8_BAR; PG8_SCHED;
;             PG8_LDA(At, 0, 1); PG8_STAGE(PG8_SB(0, 0), b2, voffB); PG8_STAGE(PG8_SB(0, 1), b2 + hstep, voffB); PG8_STAGE(PG8_SA(0, 0), a2, voffA);
;             PG8_WAIT_V(8); PG8_WAIT_L(0); PG8_BAR; PG8_MMA(1, 0, At, B0); PG8_MMA(1, 1, At, B1); PG8_BAR; PG8_SCHED;
;             PG8_LDB(B0, 1, 0); PG8_LDB(B1, 1, 1); PG8_SCHED; PG8_LDA(At, 1, 0); PG8_STAGE(PG8_SA(0, 1), a2 + hstep, voffA);
;             PG8_WAIT_V(8); PG8_WAIT_L(0); PG8_BAR; PG8_MMA(0, 0, At, B0); PG8_MMA(0, 1, At, B1); PG8_BAR; PG8_SCHED;
;             PG8_LDA(At, 1, 1); PG8_STAGE(PG8_SB(1, 0), b3, voffB); PG8_STAGE(PG8_SB(1, 1), b3 + hstep, voffB); PG8_STAGE(PG8_SA(1, 0), a3, voffA);
;             PG8_WAIT_V(8); PG8_WAIT_L(0); PG8_BAR; PG8_MMA(1, 0, At, B0); PG8_MMA(1, 1, At, B1); PG8_BAR; PG8_SCHED;
	s_mov_b32 m0, s57
	v_lshl_add_u64 v[204:205], v[204:205], 0, s[28:29]
	s_add_u32 s48, s48, 0x10180
	global_load_lds_dwordx4 v[204:205], off
	v_lshl_add_u64 v[204:205], v[206:207], 0, s[28:29]
	s_mov_b32 m0, s58
	s_addc_u32 s49, s49, 0
	global_load_lds_dwordx4 v[204:205], off
	v_lshl_add_u64 v[204:205], s[48:49], 0, v[130:131]
	s_mov_b32 m0, s59
	s_nop 0
	global_load_lds_dwordx4 v[204:205], off
	v_lshl_add_u64 v[204:205], s[48:49], 0, v[128:129]
	s_mov_b32 m0, s60
	s_nop 0
	global_load_lds_dwordx4 v[204:205], off
	v_lshl_add_u64 v[204:205], v[208:209], 0, s[28:29]
	s_mov_b32 m0, s75
	s_nop 0
	global_load_lds_dwordx4 v[204:205], off
	v_lshl_add_u64 v[204:205], v[210:211], 0, s[28:29]
	s_mov_b32 m0, s14
	s_nop 0
	global_load_lds_dwordx4 v[204:205], off
	ds_read_b128 v[172:175], v136 offset:49152
	ds_read_b128 v[176:179], v136 offset:50176
	ds_read_b128 v[180:183], v136 offset:51200
	ds_read_b128 v[184:187], v136 offset:52224
	ds_read_b128 v[188:191], v136 offset:53248
	ds_read_b128 v[192:195], v136 offset:54272
	ds_read_b128 v[196:199], v136 offset:55296
	ds_read_b128 v[200:203], v136 offset:56320
	s_waitcnt vmcnt(8)
	s_waitcnt lgkmcnt(0)
	s_barrier
	s_waitcnt lgkmcnt(0)
	v_mfma_f32_16x16x32_bf16 v[0:3], v[24:27], v[196:199], v[0:3]
	v_mfma_f32_16x16x32_bf16 v[4:7], v[112:115], v[196:199], v[4:7]
	v_mfma_f32_16x16x32_bf16 v[140:143], v[24:27], v[172:175], v[140:143]
	v_mfma_f32_16x16x32_bf16 v[144:147], v[112:115], v[172:175], v[144:147]
	v_mfma_f32_16x16x32_bf16 v[148:151], v[24:27], v[180:183], v[148:151]
	v_mfma_f32_16x16x32_bf16 v[152:155], v[112:115], v[180:183], v[152:155]
	v_mfma_f32_16x16x32_bf16 v[156:159], v[24:27], v[188:191], v[156:159]
	v_mfma_f32_16x16x32_bf16 v[160:163], v[112:115], v[188:191], v[160:163]
	v_mfma_f32_16x16x32_bf16 v[0:3], v[28:31], v[200:203], v[0:3]
	v_mfma_f32_16x16x32_bf16 v[4:7], v[116:119], v[200:203], v[4:7]
	v_mfma_f32_16x16x32_bf16 v[140:143], v[28:31], v[176:179], v[140:143]
	v_mfma_f32_16x16x32_bf16 v[144:147], v[116:119], v[176:179], v[144:147]
	v_mfma_f32_16x16x32_bf16 v[148:151], v[28:31], v[184:187], v[148:151]
	v_mfma_f32_16x16x32_bf16 v[152:155], v[116:119], v[184:187], v[152:155]
	v_mfma_f32_16x16x32_bf16 v[156:159], v[28:31], v[192:195], v[156:159]
	v_mfma_f32_16x16x32_bf16 v[160:163], v[116:119], v[192:195], v[160:163]
	v_mfma_f32_16x16x32_bf16 v[8:11], v[120:123], v[172:175], v[8:11]
	v_mfma_f32_16x16x32_bf16 v[12:15], v[164:167], v[172:175], v[12:15]
	v_mfma_f32_16x16x32_bf16 v[24:27], v[120:123], v[180:183], v[60:63]
	v_mfma_f32_16x16x32_bf16 v[28:31], v[164:167], v[180:183], v[100:103]
	v_mfma_f32_16x16x32_bf16 v[60:63], v[120:123], v[188:191], v[104:107]
	v_mfma_f32_16x16x32_bf16 v[100:103], v[164:167], v[188:191], v[108:111]
	v_mfma_f32_16x16x32_bf16 v[16:19], v[120:123], v[196:199], v[16:19]
	v_mfma_f32_16x16x32_bf16 v[20:23], v[164:167], v[196:199], v[20:23]
	v_mfma_f32_16x16x32_bf16 v[8:11], v[124:127], v[176:179], v[8:11]
	v_mfma_f32_16x16x32_bf16 v[12:15], v[168:171], v[176:179], v[12:15]
	v_mfma_f32_16x16x32_bf16 v[24:27], v[124:127], v[184:187], v[24:27]
	v_mfma_f32_16x16x32_bf16 v[28:31], v[168:171], v[184:187], v[28:31]
	v_mfma_f32_16x16x32_bf16 v[60:63], v[124:127], v[192:195], v[60:63]
	v_mfma_f32_16x16x32_bf16 v[100:103], v[168:171], v[192:195], v[100:103]
	v_mfma_f32_16x16x32_bf16 v[16:19], v[124:127], v[200:203], v[16:19]
	v_mfma_f32_16x16x32_bf16 v[20:23], v[168:171], v[200:203], v[20:23]
	s_barrier
	s_add_u32 s46, s46, 0x10180
	s_addc_u32 s47, s47, 0
	s_mov_b32 m0, s15
	v_lshl_add_u64 v[204:205], s[46:47], 0, v[130:131]
	global_load_lds_dwordx4 v[204:205], off
	v_lshl_add_u64 v[204:205], s[46:47], 0, v[128:129]
	s_mov_b32 m0, s52
	s_nop 0
	global_load_lds_dwordx4 v[204:205], off
	ds_read_b128 v[104:107], v134
	ds_read_b128 v[108:111], v134 offset:1024
	ds_read_b128 v[112:115], v134 offset:2048
	ds_read_b128 v[116:119], v134 offset:3072
	ds_read_b128 v[120:123], v135
	ds_read_b128 v[124:127], v135 offset:1024
	ds_read_b128 v[164:167], v135 offset:2048
	ds_read_b128 v[168:171], v135 offset:3072
	ds_read_b128 v[172:175], v136
	ds_read_b128 v[176:179], v136 offset:1024
	ds_read_b128 v[180:183], v136 offset:2048
	ds_read_b128 v[184:187], v136 offset:3072
	ds_read_b128 v[188:191], v136 offset:4096
	ds_read_b128 v[192:195], v136 offset:5120
	ds_read_b128 v[196:199], v136 offset:6144
	ds_read_b128 v[200:203], v136 offset:7168
	s_waitcnt vmcnt(8)
	s_waitcnt lgkmcnt(0)
	s_barrier
	s_waitcnt lgkmcnt(0)
	v_mfma_f32_16x16x32_bf16 v[64:67], v[104:107], v[172:175], v[64:67]
	v_mfma_f32_16x16x32_bf16 v[68:71], v[112:115], v[172:175], v[68:71]
	v_mfma_f32_16x16x32_bf16 v[72:75], v[104:107], v[180:183], v[72:75]
	v_mfma_f32_16x16x32_bf16 v[76:79], v[112:115], v[180:183], v[76:79]
	v_mfma_f32_16x16x32_bf16 v[80:83], v[104:107], v[188:191], v[80:83]
	v_mfma_f32_16x16x32_bf16 v[84:87], v[112:115], v[188:191], v[84:87]
	v_mfma_f32_16x16x32_bf16 v[88:91], v[104:107], v[196:199], v[88:91]
	v_mfma_f32_16x16x32_bf16 v[92:95], v[112:115], v[196:199], v[92:95]
	v_mfma_f32_16x16x32_bf16 v[64:67], v[108:111], v[176:179], v[64:67]
	v_mfma_f32_16x16x32_bf16 v[68:71], v[116:119], v[176:179], v[68:71]
	v_mfma_f32_16x16x32_bf16 v[72:75], v[108:111], v[184:187], v[72:75]
	v_mfma_f32_16x16x32_bf16 v[76:79], v[116:119], v[184:187], v[76:79]
	v_mfma_f32_16x16x32_bf16 v[80:83], v[108:111], v[192:195], v[80:83]
	v_mfma_f32_16x16x32_bf16 v[84:87], v[116:119], v[192:195], v[84:87]
	v_mfma_f32_16x16x32_bf16 v[88:91], v[108:111], v[200:203], v[88:91]
	v_mfma_f32_16x16x32_bf16 v[92:95], v[116:119], v[200:203], v[92:95]
	v_mfma_f32_16x16x32_bf16 v[32:35], v[164:167], v[172:175], v[32:35]
	v_mfma_f32_16x16x32_bf16 v[96:99], v[120:123], v[172:175], v[96:99]
	v_mfma_f32_16x16x32_bf16 v[172:175], v[168:171], v[176:179], v[32:35]
	v_mfma_f32_16x16x32_bf16 v[32:35], v[120:123], v[180:183], v[36:39]
	v_mfma_f32_16x16x32_bf16 v[204:207], v[124:127], v[176:179], v[96:99]
	v_mfma_f32_16x16x32_bf16 v[176:179], v[124:127], v[184:187], v[32:35]
	v_mfma_f32_16x16x32_bf16 v[32:35], v[164:167], v[180:183], v[40:43]
	v_mfma_f32_16x16x32_bf16 v[40:43], v[168:171], v[184:187], v[32:35]
	v_mfma_f32_16x16x32_bf16 v[32:35], v[120:123], v[188:191], v[44:47]
	v_mfma_f32_16x16x32_bf16 v[44:47], v[124:127], v[192:195], v[32:35]
	v_mfma_f32_16x16x32_bf16 v[32:35], v[164:167], v[188:191], v[48:51]
	v_mfma_f32_16x16x32_bf16 v[48:51], v[168:171], v[192:195], v[32:35]
	v_mfma_f32_16x16x32_bf16 v[32:35], v[120:123], v[196:199], v[52:55]
	v_mfma_f32_16x16x32_bf16 v[52:55], v[124:127], v[200:203], v[32:35]
	v_mfma_f32_16x16x32_bf16 v[32:35], v[164:167], v[196:199], v[56:59]
	v_mfma_f32_16x16x32_bf16 v[56:59], v[168:171], v[200:203], v[32:35]
	s_barrier
; #define PG8_STAGE(bufoff, gbase, voff) do { _Pragma("unroll") for (int _i = 0; _i < 2; ++_i) \
;         __builtin_amdgcn_global_load_lds((const unsigned*)((const char*)(gbase) + (voff)[_i]), (PG8_LAS unsigned*)(lds + (bufoff) + ldsw + _i * 8192), 16, 0, 0); } while (0)
; #define PG8_LDA(dst, b, h) do { _Pragma("unroll") for (int m = 0; m < 4; ++m) _Pragma("unroll") for (int k = 0; k < 2; ++k) dst[m][k] = *(const PG8_LAS bf16x8*)(lds + PG8_SA(b, h) + aoff + m * 2048 + k * 1024); } while (0)
; #define PG8_LDB(dst, b, h) do { _Pragma("unroll") for (int n = 0; n < 2; ++n) _Pragma("unroll") for (int k = 0; k < 2; ++k) dst[n][k] = *(const PG8_LAS bf16x8*)(lds + PG8_SB(b, h) + boff + n * 2048 + k * 1024); } while (0)
; #define PG8_MMA(ai, bj, At, Bt) do { __builtin_amdgcn_s_setprio(1); _Pragma("unroll") for (int m = 0; m < 4; ++m) _Pragma("unroll") for (int n = 0; n < 2; ++n) _Pragma("unroll") for (int k = 0; k < 2; ++k) \
;         acc[ai][bj][m][n] = mma16<F16>(Bt[n][k], At[m][k], acc[ai][bj][m][n]); __builtin_amdgcn_s_setprio(0); } while (0)
; #define PG8_WAIT_V(n) asm volatile("s_waitcnt vmcnt(" #n ")" ::: "memory")
; #define PG8_WAIT_L(n) asm volatile("s_waitcnt lgkmcnt(" #n ")" ::: "memory")
; #define PG8_BAR __builtin_amdgcn_s_barrier()
; #define PG8_SCHED __builtin_amdgcn_sched_barrier(0)
; template <class Epi, class Sched, bool ALIGN_EPI = false, bool SP2 = false, bool F16 = false>
; __device__ __forceinline__ void gemm_phase(PG8_LAS unsigned char* lds, const Gemm g, const Sched& S, const Epi& E, const int wid_in) {
;     ...
;             PG8_LDA(At, 0, 1); PG8_STAGE(PG8_SB(0, 0), b2, voffB); PG8_STAGE(PG8_SB(0, 1), b2 + hstep, voffB); PG8_STAGE(PG8_SA(0, 0), a2, voffA);
;             PG8_WAIT_V(8); PG8_WAIT_L(0); PG8_BAR; PG8_MMA(1, 0, At, B0); PG8_MMA(1, 1, At, B1); PG8_BAR; PG8_SCHED;
;             PG8_LDB(B0, 1, 0); PG8_LDB(B1, 1, 1); PG8_SCHED; PG8_LDA(At, 1, 0); PG8_STAGE(PG8_SA(0, 1), a2 + hstep, voffA);
;             PG8_WAIT_V(8); PG8_WAIT_L(0); PG8_BAR; PG8_MMA(0, 0, At, B0); PG8_MMA(0, 1, At, B1); PG8_BAR; PG8_SCHED;
	s_mov_b32 m0, s53
	v_lshl_add_u64 v[240:241], s[36:37], 0, v[130:131]
	s_add_u32 s46, s36, 0x10000
	s_nop 1
	global_load_lds_dwordx4 v[240:241], off
	v_lshl_add_u64 v[242:243], s[36:37], 0, v[128:129]
	s_mov_b32 m0, s54
	s_addc_u32 s47, s37, 0
	global_load_lds_dwordx4 v[242:243], off
	v_lshl_add_u64 v[200:201], s[46:47], 0, v[130:131]
	s_mov_b32 m0, s55
	v_lshl_add_u64 v[244:245], s[44:45], 0, v[130:131]
	global_load_lds_dwordx4 v[200:201], off
	v_lshl_add_u64 v[200:201], s[46:47], 0, v[128:129]
	s_mov_b32 m0, s56
	v_lshl_add_u64 v[246:247], s[44:45], 0, v[128:129]
	global_load_lds_dwordx4 v[200:201], off
	s_mov_b32 m0, s74
	s_nop 0
	global_load_lds_dwordx4 v[244:245], off
	s_mov_b32 m0, s43
	s_nop 0
	global_load_lds_dwordx4 v[246:247], off
	ds_read_b128 v[32:35], v136 offset:16384
	ds_read_b128 v[36:39], v136 offset:17408
	ds_read_b128 v[96:99], v136 offset:18432
	ds_read_b128 v[180:183], v136 offset:19456
	ds_read_b128 v[184:187], v136 offset:20480
	ds_read_b128 v[188:191], v136 offset:21504
	ds_read_b128 v[192:195], v136 offset:22528
	ds_read_b128 v[196:199], v136 offset:23552
	s_waitcnt vmcnt(8)
	s_waitcnt lgkmcnt(0)
	s_barrier
	s_waitcnt lgkmcnt(0)
	v_mfma_f32_16x16x32_bf16 v[0:3], v[104:107], v[192:195], v[0:3]
	v_mfma_f32_16x16x32_bf16 v[140:143], v[104:107], v[32:35], v[140:143]
	v_mfma_f32_16x16x32_bf16 v[144:147], v[112:115], v[32:35], v[144:147]
	v_mfma_f32_16x16x32_bf16 v[148:151], v[104:107], v[96:99], v[148:151]
	v_mfma_f32_16x16x32_bf16 v[152:155], v[112:115], v[96:99], v[152:155]
	v_mfma_f32_16x16x32_bf16 v[156:159], v[104:107], v[184:187], v[156:159]
	v_mfma_f32_16x16x32_bf16 v[160:163], v[112:115], v[184:187], v[160:163]
	v_mfma_f32_16x16x32_bf16 v[0:3], v[108:111], v[196:199], v[0:3]
	v_mfma_f32_16x16x32_bf16 v[4:7], v[112:115], v[192:195], v[4:7]
	v_mfma_f32_16x16x32_bf16 v[140:143], v[108:111], v[36:39], v[140:143]
	v_mfma_f32_16x16x32_bf16 v[144:147], v[116:119], v[36:39], v[144:147]
	v_mfma_f32_16x16x32_bf16 v[148:151], v[108:111], v[180:183], v[148:151]
	v_mfma_f32_16x16x32_bf16 v[152:155], v[116:119], v[180:183], v[152:155]
	v_mfma_f32_16x16x32_bf16 v[156:159], v[108:111], v[188:191], v[156:159]
	v_mfma_f32_16x16x32_bf16 v[160:163], v[116:119], v[188:191], v[160:163]
	v_mfma_f32_16x16x32_bf16 v[200:203], v[116:119], v[196:199], v[4:7]
	v_mfma_f32_16x16x32_bf16 v[4:7], v[120:123], v[32:35], v[8:11]
	v_mfma_f32_16x16x32_bf16 v[8:11], v[124:127], v[36:39], v[4:7]
	v_mfma_f32_16x16x32_bf16 v[4:7], v[164:167], v[32:35], v[12:15]
	v_mfma_f32_16x16x32_bf16 v[12:15], v[168:171], v[36:39], v[4:7]
	v_mfma_f32_16x16x32_bf16 v[4:7], v[120:123], v[96:99], v[24:27]
	v_mfma_f32_16x16x32_bf16 v[24:27], v[124:127], v[180:183], v[4:7]
	v_mfma_f32_16x16x32_bf16 v[4:7], v[164:167], v[96:99], v[28:31]
	v_mfma_f32_16x16x32_bf16 v[28:31], v[168:171], v[180:183], v[4:7]
	v_mfma_f32_16x16x32_bf16 v[4:7], v[120:123], v[184:187], v[60:63]
	v_mfma_f32_16x16x32_bf16 v[180:183], v[124:127], v[188:191], v[4:7]
	v_mfma_f32_16x16x32_bf16 v[4:7], v[164:167], v[184:187], v[100:103]
	v_mfma_f32_16x16x32_bf16 v[184:187], v[168:171], v[188:191], v[4:7]
	v_mfma_f32_16x16x32_bf16 v[4:7], v[120:123], v[192:195], v[16:19]
	v_mfma_f32_16x16x32_bf16 v[188:191], v[124:127], v[196:199], v[4:7]
	v_mfma_f32_16x16x32_bf16 v[4:7], v[164:167], v[192:195], v[20:23]
	v_mfma_f32_16x16x32_bf16 v[164:167], v[168:171], v[196:199], v[4:7]
	s_barrier
	s_nop 4
	s_add_u32 s44, s44, 0x10000
	s_addc_u32 s45, s45, 0
	s_mov_b32 m0, s50
	v_lshl_add_u64 v[32:33], s[44:45], 0, v[130:131]
	global_load_lds_dwordx4 v[32:33], off
	v_lshl_add_u64 v[32:33], s[44:45], 0, v[128:129]
	s_mov_b32 m0, s51
	s_nop 0
	global_load_lds_dwordx4 v[32:33], off
	ds_read_b128 v[4:7], v137
	ds_read_b128 v[60:63], v137 offset:1024
	ds_read_b128 v[168:171], v137 offset:2048
	ds_read_b128 v[192:195], v137 offset:3072
	ds_read_b128 v[196:199], v138
	ds_read_b128 v[208:211], v138 offset:1024
	ds_read_b128 v[212:215], v138 offset:2048
	ds_read_b128 v[216:219], v138 offset:3072
	ds_read_b128 v[16:19], v136 offset:32768
	ds_read_b128 v[20:23], v136 offset:33792
	ds_read_b128 v[104:107], v136 offset:34816
	ds_read_b128 v[220:223], v136 offset:35840
	ds_read_b128 v[224:227], v136 offset:36864
	ds_read_b128 v[228:231], v136 offset:37888
	ds_read_b128 v[232:235], v136 offset:38912
	ds_read_b128 v[236:239], v136 offset:39936
	s_waitcnt vmcnt(8)
	s_waitcnt lgkmcnt(0)
	s_barrier
; #define PG8_STAGE(bufoff, gbase, voff) do { _Pragma("unroll") for (int _i = 0; _i < 2; ++_i) \
;         __builtin_amdgcn_global_load_lds((const unsigned*)((const char*)(gbase) + (voff)[_i]), (PG8_LAS unsigned*)(lds + (bufoff) + ldsw + _i * 8192), 16, 0, 0); } while (0)
; #define PG8_LDA(dst, b, h) do { _Pragma("unroll") for (int m = 0; m < 4; ++m) _Pragma("unroll") for (int k = 0; k < 2; ++k) dst[m][k] = *(const PG8_LAS bf16x8*)(lds + PG8_SA(b, h) + aoff + m * 2048 + k * 1024); } while (0)
; #define PG8_MMA(ai, bj, At, Bt) do { __builtin_amdgcn_s_setprio(1); _Pragma("unroll") for (int m = 0; m < 4; ++m) _Pragma("unroll") for (int n = 0; n < 2; ++n) _Pragma("unroll") for (int k = 0; k < 2; ++k) \
;         acc[ai][bj][m][n] = mma16<F16>(Bt[n][k], At[m][k], acc[ai][bj][m][n]); __builtin_amdgcn_s_setprio(0); } while (0)
; #define PG8_WAIT_V(n) asm volatile("s_waitcnt vmcnt(" #n ")" ::: "memory")
; #define PG8_WAIT_L(n) asm volatile("s_waitcnt lgkmcnt(" #n ")" ::: "memory")
; #define PG8_BAR __builtin_amdgcn_s_barrier()
; #define PG8_SCHED __builtin_amdgcn_sched_barrier(0)
; template <class Epi, class Sched, bool ALIGN_EPI = false, bool SP2 = false, bool F16 = false>
; __device__ __forceinline__ void gemm_phase(PG8_LAS unsigned char* lds, const Gemm g, const Sched& S, const Epi& E, const int wid_in) {
;     ...
;             PG8_WAIT_V(8); PG8_WAIT_L(0); PG8_BAR; PG8_MMA(0, 0, At, B0); PG8_MMA(0, 1, At, B1); PG8_BAR; PG8_SCHED;
;             PG8_LDA(At, 1, 1); PG8_STAGE(PG8_SB(1, 0), b3, voffB); PG8_STAGE(PG8_SB(1, 1), b3 + hstep, voffB); PG8_STAGE(PG8_SA(1, 0), a3, voffA);
;             PG8_WAIT_V(8); PG8_WAIT_L(0); PG8_BAR; PG8_MMA(1, 0, At, B0); PG8_MMA(1, 1, At, B1); PG8_BAR; PG8_SCHED;
;     ...
;         if constexpr (ALIGN_EPI) { if (wr == 0) PG8_BAR; }
	s_waitcnt lgkmcnt(0)
	v_mfma_f32_16x16x32_bf16 v[32:35], v[4:7], v[16:19], v[64:67]
	v_mfma_f32_16x16x32_bf16 v[116:119], v[60:63], v[20:23], v[32:35]
	v_mfma_f32_16x16x32_bf16 v[32:35], v[168:171], v[16:19], v[68:71]
	v_mfma_f32_16x16x32_bf16 v[112:115], v[192:195], v[20:23], v[32:35]
	v_mfma_f32_16x16x32_bf16 v[32:35], v[4:7], v[104:107], v[72:75]
	v_mfma_f32_16x16x32_bf16 v[100:103], v[60:63], v[220:223], v[32:35]
	v_mfma_f32_16x16x32_bf16 v[32:35], v[168:171], v[104:107], v[76:79]
	v_mfma_f32_16x16x32_bf16 v[96:99], v[192:195], v[220:223], v[32:35]
	v_mfma_f32_16x16x32_bf16 v[32:35], v[4:7], v[224:227], v[80:83]
	v_mfma_f32_16x16x32_bf16 v[68:71], v[60:63], v[228:231], v[32:35]
	v_mfma_f32_16x16x32_bf16 v[32:35], v[168:171], v[224:227], v[84:87]
	v_mfma_f32_16x16x32_bf16 v[64:67], v[192:195], v[228:231], v[32:35]
	v_mfma_f32_16x16x32_bf16 v[32:35], v[4:7], v[232:235], v[88:91]
	v_mfma_f32_16x16x32_bf16 v[36:39], v[60:63], v[236:239], v[32:35]
	v_mfma_f32_16x16x32_bf16 v[32:35], v[168:171], v[232:235], v[92:95]
	v_mfma_f32_16x16x32_bf16 v[32:35], v[192:195], v[236:239], v[32:35]
	v_mfma_f32_16x16x32_bf16 v[72:75], v[196:199], v[16:19], v[204:207]
	v_mfma_f32_16x16x32_bf16 v[16:19], v[212:215], v[16:19], v[172:175]
	v_mfma_f32_16x16x32_bf16 v[120:123], v[216:219], v[20:23], v[16:19]
	v_mfma_f32_16x16x32_bf16 v[16:19], v[196:199], v[104:107], v[176:179]
	v_mfma_f32_16x16x32_bf16 v[108:111], v[208:211], v[220:223], v[16:19]
	v_mfma_f32_16x16x32_bf16 v[16:19], v[212:215], v[104:107], v[40:43]
	v_mfma_f32_16x16x32_bf16 v[104:107], v[216:219], v[220:223], v[16:19]
	v_mfma_f32_16x16x32_bf16 v[16:19], v[196:199], v[224:227], v[44:47]
	v_mfma_f32_16x16x32_bf16 v[80:83], v[208:211], v[228:231], v[16:19]
	v_mfma_f32_16x16x32_bf16 v[16:19], v[212:215], v[224:227], v[48:51]
	v_mfma_f32_16x16x32_bf16 v[124:127], v[208:211], v[20:23], v[72:75]
	v_mfma_f32_16x16x32_bf16 v[72:75], v[216:219], v[228:231], v[16:19]
	v_mfma_f32_16x16x32_bf16 v[16:19], v[196:199], v[232:235], v[52:55]
	v_mfma_f32_16x16x32_bf16 v[48:51], v[208:211], v[236:239], v[16:19]
	v_mfma_f32_16x16x32_bf16 v[16:19], v[212:215], v[232:235], v[56:59]
	v_mfma_f32_16x16x32_bf16 v[40:43], v[216:219], v[236:239], v[16:19]
	s_barrier
	s_mov_b32 m0, s57
	s_nop 3
	v_lshl_add_u64 v[16:17], v[240:241], 0, s[24:25]
	s_add_u32 s36, s36, 0x10080
	global_load_lds_dwordx4 v[16:17], off
	v_lshl_add_u64 v[16:17], v[242:243], 0, s[24:25]
	s_mov_b32 m0, s58
	s_addc_u32 s37, s37, 0
	global_load_lds_dwordx4 v[16:17], off
	v_lshl_add_u64 v[16:17], s[36:37], 0, v[130:131]
	s_mov_b32 m0, s59
	s_nop 0
	global_load_lds_dwordx4 v[16:17], off
	v_lshl_add_u64 v[16:17], s[36:37], 0, v[128:129]
	s_mov_b32 m0, s60
	s_nop 0
	global_load_lds_dwordx4 v[16:17], off
	v_lshl_add_u64 v[16:17], v[244:245], 0, s[24:25]
	s_mov_b32 m0, s75
	s_nop 0
	global_load_lds_dwordx4 v[16:17], off
	v_lshl_add_u64 v[16:17], v[246:247], 0, s[24:25]
	s_mov_b32 m0, s14
	s_nop 0
	global_load_lds_dwordx4 v[16:17], off
	ds_read_b128 v[56:59], v136 offset:49152
	ds_read_b128 v[88:91], v136 offset:50176
	ds_read_b128 v[172:175], v136 offset:51200
	ds_read_b128 v[176:179], v136 offset:52224
	ds_read_b128 v[204:207], v136 offset:53248
	ds_read_b128 v[220:223], v136 offset:54272
	ds_read_b128 v[224:227], v136 offset:55296
	ds_read_b128 v[228:231], v136 offset:56320
	s_waitcnt vmcnt(8)
	s_waitcnt lgkmcnt(0)
	s_barrier
	s_waitcnt lgkmcnt(0)
	v_mfma_f32_16x16x32_bf16 v[16:19], v[4:7], v[56:59], v[140:143]
	v_mfma_f32_16x16x32_bf16 v[84:87], v[60:63], v[88:91], v[16:19]
	v_mfma_f32_16x16x32_bf16 v[16:19], v[168:171], v[56:59], v[144:147]
	v_mfma_f32_16x16x32_bf16 v[76:79], v[192:195], v[88:91], v[16:19]
	v_mfma_f32_16x16x32_bf16 v[16:19], v[4:7], v[172:175], v[148:151]
	v_mfma_f32_16x16x32_bf16 v[52:55], v[60:63], v[176:179], v[16:19]
	v_mfma_f32_16x16x32_bf16 v[16:19], v[168:171], v[172:175], v[152:155]
	v_mfma_f32_16x16x32_bf16 v[44:47], v[192:195], v[176:179], v[16:19]
	v_mfma_f32_16x16x32_bf16 v[16:19], v[4:7], v[204:207], v[156:159]
	v_mfma_f32_16x16x32_bf16 v[0:3], v[4:7], v[224:227], v[0:3]
	v_mfma_f32_16x16x32_bf16 v[20:23], v[60:63], v[220:223], v[16:19]
	v_mfma_f32_16x16x32_bf16 v[16:19], v[168:171], v[204:207], v[160:163]
	v_mfma_f32_16x16x32_bf16 v[4:7], v[60:63], v[228:231], v[0:3]
	v_mfma_f32_16x16x32_bf16 v[0:3], v[168:171], v[224:227], v[200:203]
	v_mfma_f32_16x16x32_bf16 v[16:19], v[192:195], v[220:223], v[16:19]
	v_mfma_f32_16x16x32_bf16 v[0:3], v[192:195], v[228:231], v[0:3]
	v_mfma_f32_16x16x32_bf16 v[8:11], v[196:199], v[56:59], v[8:11]
	v_mfma_f32_16x16x32_bf16 v[92:95], v[208:211], v[88:91], v[8:11]
	v_mfma_f32_16x16x32_bf16 v[8:11], v[212:215], v[56:59], v[12:15]
	v_mfma_f32_16x16x32_bf16 v[88:91], v[216:219], v[88:91], v[8:11]
	v_mfma_f32_16x16x32_bf16 v[8:11], v[196:199], v[172:175], v[24:27]
	v_mfma_f32_16x16x32_bf16 v[60:63], v[208:211], v[176:179], v[8:11]
	v_mfma_f32_16x16x32_bf16 v[8:11], v[212:215], v[172:175], v[28:31]
	v_mfma_f32_16x16x32_bf16 v[56:59], v[216:219], v[176:179], v[8:11]
	v_mfma_f32_16x16x32_bf16 v[8:11], v[196:199], v[204:207], v[180:183]
	v_mfma_f32_16x16x32_bf16 v[28:31], v[208:211], v[220:223], v[8:11]
	v_mfma_f32_16x16x32_bf16 v[8:11], v[212:215], v[204:207], v[184:187]
	v_mfma_f32_16x16x32_bf16 v[24:27], v[216:219], v[220:223], v[8:11]
	v_mfma_f32_16x16x32_bf16 v[8:11], v[196:199], v[224:227], v[188:191]
	v_mfma_f32_16x16x32_bf16 v[12:15], v[208:211], v[228:231], v[8:11]
	v_mfma_f32_16x16x32_bf16 v[8:11], v[212:215], v[224:227], v[164:167]
	v_mfma_f32_16x16x32_bf16 v[8:11], v[216:219], v[228:231], v[8:11]
	s_barrier
	s_and_b64 vcc, exec, s[8:9]
	s_cbranch_vccnz .LBB0_1279
	s_barrier

; #define PG8_STAGE(bufoff, gbase, voff) do { _Pragma("unroll") for (int _i = 0; _i < 2; ++_i) \
;         __builtin_amdgcn_global_load_lds((const unsigned*)((const char*)(gbase) + (voff)[_i]), (PG8_LAS unsigned*)(lds + (bufoff) + ldsw + _i * 8192), 16, 0, 0); } while (0)
; #define PG8_LDA(dst, b, h) do { _Pragma("unroll") for (int m = 0; m < 4; ++m) _Pragma("unroll") for (int k = 0; k < 2; ++k) dst[m][k] = *(const PG8_LAS bf16x8*)(lds + PG8_SA(b, h) + aoff + m * 2048 + k * 1024); } while (0)
; #define PG8_LDB(dst, b, h) do { _Pragma("unroll") for (int n = 0; n < 2; ++n) _Pragma("unroll") for (int k = 0; k < 2; ++k) dst[n][k] = *(const PG8_LAS bf16x8*)(lds + PG8_SB(b, h) + boff + n * 2048 + k * 1024); } while (0)
; #define PG8_MMA(ai, bj, At, Bt) do { __builtin_amdgcn_s_setprio(1); _Pragma("unroll") for (int m = 0; m < 4; ++m) _Pragma("unroll") for (int n = 0; n < 2; ++n) _Pragma("unroll") for (int k = 0; k < 2; ++k) \
;         acc[ai][bj][m][n] = mma16<F16>(Bt[n][k], At[m][k], acc[ai][bj][m][n]); __builtin_amdgcn_s_setprio(0); } while (0)
; #define PG8_WAIT_V(n) asm volatile("s_waitcnt vmcnt(" #n ")" ::: "memory")
; #define PG8_BAR __builtin_amdgcn_s_barrier()
; template <class Epi, class Sched, bool ALIGN_EPI = false, bool SP2 = false, bool F16 = false>
; __device__ __forceinline__ void gemm_phase(PG8_LAS unsigned char* lds, const Gemm g, const Sched& S, const Epi& E, const int wid_in) {
;     ...
;         for (int t = 0; t < nt; t += 2) {
;             const bool last = (t == nt - 2);
;             const char* a1 = cA + (size_t)(t + 1) * kstep;
;             const char* a2 = last ? nA : cA + (size_t)(t + 2) * kstep; const char* b2 = last ? nB : cB + (size_t)(t + 2) * kstep;
;             const char* a3 = a2 + kstep; const char* b3 = b2 + kstep;
;             if (last && has_next) S.a_ready(nxt);
;             if constexpr (SP2) {
;             PG8_LDB(B0, 0, 0); PG8_LDB(B1, 0, 1); PG8_SCHED; PG8_LDA(At, 0, 0); PG8_STAGE(PG8_SA(1, 1), a1 + hstep, voffA);
;             PG8_WAIT_V(8); PG8_WAIT_L(0); PG8_BAR; PG8_MMA(0, 0, At, B0); PG8_MMA(0, 1, At, B1); PG8_BAR; PG8_SCHED;
;             PG8_LDA(At, 0, 1); PG8_STAGE(PG8_SB(0, 0), b2, voffB); PG8_STAGE(PG8_SB(0, 1), b2 + hstep, voffB); PG8_STAGE(PG8_SA(0, 0), a2, voffA);
;             PG8_WAIT_V(8); PG8_WAIT_L(0); PG8_BAR; PG8_MMA(1, 0, At, B0); PG8_MMA(1, 1, At, B1); PG8_BAR; PG8_SCHED;
.LBB0_1373:
	ds_read_b128 v[128:131], v189
	ds_read_b128 v[132:135], v189 offset:1024
	ds_read_b128 v[136:139], v189 offset:2048
	ds_read_b128 v[140:143], v189 offset:3072
	ds_read_b128 v[144:147], v190
	ds_read_b128 v[148:151], v190 offset:1024
	ds_read_b128 v[168:171], v190 offset:2048
	ds_read_b128 v[172:175], v190 offset:3072
	s_add_u32 s44, s36, 0x100
	s_addc_u32 s45, s37, 0
	s_cmp_eq_u32 s62, 40
	s_cselect_b32 s49, s13, s45
	s_cselect_b32 s48, s12, s44
	s_cselect_b32 s47, s35, s61
	s_cselect_b32 s46, s34, s43
	v_lshl_add_u64 v[184:185], s[36:37], 0, v[160:161]
	s_add_i32 m0, s74, 0xc000
	ds_read_b128 v[176:179], v191
	ds_read_b128 v[180:183], v191 offset:1024
	ds_read_b128 v[192:195], v191 offset:2048
	ds_read_b128 v[196:199], v191 offset:3072
	ds_read_b128 v[200:203], v191 offset:4096
	ds_read_b128 v[204:207], v191 offset:5120
	ds_read_b128 v[208:211], v191 offset:6144
	ds_read_b128 v[212:215], v191 offset:7168
	global_load_lds_dwordx4 v[184:185], off
	v_lshl_add_u64 v[184:185], s[36:37], 0, v[162:163]
	s_add_i32 m0, s74, 0xe000
	s_nop 0
	global_load_lds_dwordx4 v[184:185], off
	s_waitcnt vmcnt(8)
	s_waitcnt lgkmcnt(0)
	s_barrier
	s_waitcnt lgkmcnt(0)
	v_mfma_f32_16x16x32_bf16 v[124:127], v[128:131], v[176:179], v[124:127]
	v_mfma_f32_16x16x32_bf16 v[120:123], v[136:139], v[176:179], v[120:123]
	v_mfma_f32_16x16x32_bf16 v[108:111], v[128:131], v[192:195], v[108:111]
	v_mfma_f32_16x16x32_bf16 v[104:107], v[136:139], v[192:195], v[104:107]
	v_mfma_f32_16x16x32_bf16 v[92:95], v[128:131], v[200:203], v[92:95]
	v_mfma_f32_16x16x32_bf16 v[88:91], v[136:139], v[200:203], v[88:91]
	v_mfma_f32_16x16x32_bf16 v[76:79], v[128:131], v[208:211], v[76:79]
	v_mfma_f32_16x16x32_bf16 v[72:75], v[136:139], v[208:211], v[72:75]
	v_mfma_f32_16x16x32_bf16 v[124:127], v[132:135], v[180:183], v[124:127]
	v_mfma_f32_16x16x32_bf16 v[120:123], v[140:143], v[180:183], v[120:123]
	v_mfma_f32_16x16x32_bf16 v[108:111], v[132:135], v[196:199], v[108:111]
	v_mfma_f32_16x16x32_bf16 v[104:107], v[140:143], v[196:199], v[104:107]
	v_mfma_f32_16x16x32_bf16 v[92:95], v[132:135], v[204:207], v[92:95]
	v_mfma_f32_16x16x32_bf16 v[88:91], v[140:143], v[204:207], v[88:91]
	v_mfma_f32_16x16x32_bf16 v[76:79], v[132:135], v[212:215], v[76:79]
	v_mfma_f32_16x16x32_bf16 v[72:75], v[140:143], v[212:215], v[72:75]
	v_mfma_f32_16x16x32_bf16 v[116:119], v[144:147], v[176:179], v[116:119]
	v_mfma_f32_16x16x32_bf16 v[112:115], v[168:171], v[176:179], v[112:115]
	v_mfma_f32_16x16x32_bf16 v[100:103], v[144:147], v[192:195], v[100:103]
	v_mfma_f32_16x16x32_bf16 v[96:99], v[168:171], v[192:195], v[96:99]
	v_mfma_f32_16x16x32_bf16 v[84:87], v[144:147], v[200:203], v[84:87]
	v_mfma_f32_16x16x32_bf16 v[80:83], v[168:171], v[200:203], v[80:83]
	v_mfma_f32_16x16x32_bf16 v[68:71], v[144:147], v[208:211], v[68:71]
	v_mfma_f32_16x16x32_bf16 v[64:67], v[168:171], v[208:211], v[64:67]
	v_mfma_f32_16x16x32_bf16 v[116:119], v[148:151], v[180:183], v[116:119]
	v_mfma_f32_16x16x32_bf16 v[112:115], v[172:175], v[180:183], v[112:115]
	v_mfma_f32_16x16x32_bf16 v[100:103], v[148:151], v[196:199], v[100:103]
	v_mfma_f32_16x16x32_bf16 v[96:99], v[172:175], v[196:199], v[96:99]
	v_mfma_f32_16x16x32_bf16 v[84:87], v[148:151], v[204:207], v[84:87]
	v_mfma_f32_16x16x32_bf16 v[80:83], v[172:175], v[204:207], v[80:83]
	v_mfma_f32_16x16x32_bf16 v[68:71], v[148:151], v[212:215], v[68:71]
	v_mfma_f32_16x16x32_bf16 v[64:67], v[172:175], v[212:215], v[64:67]
	s_barrier
	s_add_i32 s36, s56, s68
	v_lshl_add_u64 v[184:185], s[46:47], 0, v[154:155]
	s_mov_b32 m0, s36
	s_nop 0
	global_load_lds_dwordx4 v[184:185], off
	s_add_i32 m0, s36, 0x2000
	s_add_u32 s36, s46, 0xb0000
	v_lshl_add_u64 v[216:217], s[46:47], 0, v[158:159]
	s_addc_u32 s37, s47, 0
	s_add_i32 s63, s57, s68
	global_load_lds_dwordx4 v[216:217], off
	v_lshl_add_u64 v[218:219], s[36:37], 0, v[154:155]
	s_mov_b32 m0, s63
	v_lshl_add_u64 v[220:221], s[48:49], 0, v[156:157]
	global_load_lds_dwordx4 v[218:219], off
	v_lshl_add_u64 v[218:219], s[36:37], 0, v[158:159]
	s_add_i32 m0, s63, 0x2000
	s_nop 0
	global_load_lds_dwordx4 v[218:219], off
	v_lshl_add_u64 v[218:219], s[48:49], 0, v[152:153]
	s_mov_b32 m0, s74
	s_nop 0
	global_load_lds_dwordx4 v[218:219], off
	s_mov_b32 m0, s41
	s_nop 0
	global_load_lds_dwordx4 v[220:221], off
	ds_read_b128 v[176:179], v191 offset:16384
	ds_read_b128 v[180:183], v191 offset:17408
	ds_read_b128 v[192:195], v191 offset:18432
	ds_read_b128 v[196:199], v191 offset:19456
	ds_read_b128 v[200:203], v191 offset:20480
	ds_read_b128 v[204:207], v191 offset:21504
	ds_read_b128 v[208:211], v191 offset:22528
	ds_read_b128 v[212:215], v191 offset:23552
	s_waitcnt vmcnt(8)
	s_waitcnt lgkmcnt(0)
	s_barrier
; #define PG8_STAGE(bufoff, gbase, voff) do { _Pragma("unroll") for (int _i = 0; _i < 2; ++_i) \
;         __builtin_amdgcn_global_load_lds((const unsigned*)((const char*)(gbase) + (voff)[_i]), (PG8_LAS unsigned*)(lds + (bufoff) + ldsw + _i * 8192), 16, 0, 0); } while (0)
; #define PG8_LDA(dst, b, h) do { _Pragma("unroll") for (int m = 0; m < 4; ++m) _Pragma("unroll") for (int k = 0; k < 2; ++k) dst[m][k] = *(const PG8_LAS bf16x8*)(lds + PG8_SA(b, h) + aoff + m * 2048 + k * 1024); } while (0)
; #define PG8_LDB(dst, b, h) do { _Pragma("unroll") for (int n = 0; n < 2; ++n) _Pragma("unroll") for (int k = 0; k < 2; ++k) dst[n][k] = *(const PG8_LAS bf16x8*)(lds + PG8_SB(b, h) + boff + n * 2048 + k * 1024); } while (0)
; #define PG8_MMA(ai, bj, At, Bt) do { __builtin_amdgcn_s_setprio(1); _Pragma("unroll") for (int m = 0; m < 4; ++m) _Pragma("unroll") for (int n = 0; n < 2; ++n) _Pragma("unroll") for (int k = 0; k < 2; ++k) \
;         acc[ai][bj][m][n] = mma16<F16>(Bt[n][k], At[m][k], acc[ai][bj][m][n]); __builtin_amdgcn_s_setprio(0); } while (0)
; #define PG8_WAIT_V(n) asm volatile("s_waitcnt vmcnt(" #n ")" ::: "memory")
; #define PG8_WAIT_L(n) asm volatile("s_waitcnt lgkmcnt(" #n ")" ::: "memory")
; #define PG8_BAR __builtin_amdgcn_s_barrier()
; #define PG8_SCHED __builtin_amdgcn_sched_barrier(0)
; template <class Epi, class Sched, bool ALIGN_EPI = false, bool SP2 = false, bool F16 = false>
; __device__ __forceinline__ void gemm_phase(PG8_LAS unsigned char* lds, const Gemm g, const Sched& S, const Epi& E, const int wid_in) {
;     ...
;             PG8_WAIT_V(8); PG8_WAIT_L(0); PG8_BAR; PG8_MMA(1, 0, At, B0); PG8_MMA(1, 1, At, B1); PG8_BAR; PG8_SCHED;
;             PG8_LDB(B0, 1, 0); PG8_LDB(B1, 1, 1); PG8_SCHED; PG8_LDA(At, 1, 0); PG8_STAGE(PG8_SA(0, 1), a2 + hstep, voffA);
;             PG8_WAIT_V(8); PG8_WAIT_L(0); PG8_BAR; PG8_MMA(0, 0, At, B0); PG8_MMA(0, 1, At, B1); PG8_BAR; PG8_SCHED;
	s_waitcnt lgkmcnt(0)
	v_mfma_f32_16x16x32_bf16 v[60:63], v[128:131], v[176:179], v[60:63]
	v_mfma_f32_16x16x32_bf16 v[56:59], v[136:139], v[176:179], v[56:59]
	v_mfma_f32_16x16x32_bf16 v[44:47], v[128:131], v[192:195], v[44:47]
	v_mfma_f32_16x16x32_bf16 v[40:43], v[136:139], v[192:195], v[40:43]
	v_mfma_f32_16x16x32_bf16 v[28:31], v[128:131], v[200:203], v[28:31]
	v_mfma_f32_16x16x32_bf16 v[24:27], v[136:139], v[200:203], v[24:27]
	v_mfma_f32_16x16x32_bf16 v[12:15], v[128:131], v[208:211], v[12:15]
	v_mfma_f32_16x16x32_bf16 v[8:11], v[136:139], v[208:211], v[8:11]
	v_mfma_f32_16x16x32_bf16 v[60:63], v[132:135], v[180:183], v[60:63]
	v_mfma_f32_16x16x32_bf16 v[56:59], v[140:143], v[180:183], v[56:59]
	v_mfma_f32_16x16x32_bf16 v[44:47], v[132:135], v[196:199], v[44:47]
	v_mfma_f32_16x16x32_bf16 v[40:43], v[140:143], v[196:199], v[40:43]
	v_mfma_f32_16x16x32_bf16 v[28:31], v[132:135], v[204:207], v[28:31]
	v_mfma_f32_16x16x32_bf16 v[24:27], v[140:143], v[204:207], v[24:27]
	v_mfma_f32_16x16x32_bf16 v[12:15], v[132:135], v[212:215], v[12:15]
	v_mfma_f32_16x16x32_bf16 v[8:11], v[140:143], v[212:215], v[8:11]
	v_mfma_f32_16x16x32_bf16 v[52:55], v[144:147], v[176:179], v[52:55]
	v_mfma_f32_16x16x32_bf16 v[48:51], v[168:171], v[176:179], v[48:51]
	v_mfma_f32_16x16x32_bf16 v[36:39], v[144:147], v[192:195], v[36:39]
	v_mfma_f32_16x16x32_bf16 v[32:35], v[168:171], v[192:195], v[32:35]
	v_mfma_f32_16x16x32_bf16 v[20:23], v[144:147], v[200:203], v[20:23]
	v_mfma_f32_16x16x32_bf16 v[16:19], v[168:171], v[200:203], v[16:19]
	v_mfma_f32_16x16x32_bf16 v[4:7], v[144:147], v[208:211], v[4:7]
	v_mfma_f32_16x16x32_bf16 v[0:3], v[168:171], v[208:211], v[0:3]
	v_mfma_f32_16x16x32_bf16 v[52:55], v[148:151], v[180:183], v[52:55]
	v_mfma_f32_16x16x32_bf16 v[48:51], v[172:175], v[180:183], v[48:51]
	v_mfma_f32_16x16x32_bf16 v[36:39], v[148:151], v[196:199], v[36:39]
	v_mfma_f32_16x16x32_bf16 v[32:35], v[172:175], v[196:199], v[32:35]
	v_mfma_f32_16x16x32_bf16 v[20:23], v[148:151], v[204:207], v[20:23]
	v_mfma_f32_16x16x32_bf16 v[16:19], v[172:175], v[204:207], v[16:19]
	v_mfma_f32_16x16x32_bf16 v[4:7], v[148:151], v[212:215], v[4:7]
	v_mfma_f32_16x16x32_bf16 v[0:3], v[172:175], v[212:215], v[0:3]
	s_barrier
	s_add_i32 s63, 0, 0x18000
	s_add_i32 s64, 0, 0x1c000
	v_add_u32_e32 v140, s63, v188
	v_add_u32_e32 v172, s64, v188
	s_add_u32 s36, s48, 0xb0000
	s_addc_u32 s37, s49, 0
	s_mov_b32 m0, s50
	v_lshl_add_u64 v[222:223], s[36:37], 0, v[152:153]
	global_load_lds_dwordx4 v[222:223], off
	v_lshl_add_u64 v[222:223], s[36:37], 0, v[156:157]
	s_mov_b32 m0, s51
	s_nop 0
	global_load_lds_dwordx4 v[222:223], off
	ds_read_b128 v[128:131], v140
	ds_read_b128 v[132:135], v140 offset:1024
	ds_read_b128 v[136:139], v140 offset:2048
	ds_read_b128 v[140:143], v140 offset:3072
	ds_read_b128 v[144:147], v172
	ds_read_b128 v[148:151], v172 offset:1024
	ds_read_b128 v[168:171], v172 offset:2048
	ds_read_b128 v[172:175], v172 offset:3072
	ds_read_b128 v[176:179], v191 offset:32768
	ds_read_b128 v[180:183], v191 offset:33792
	ds_read_b128 v[192:195], v191 offset:34816
	ds_read_b128 v[196:199], v191 offset:35840
	ds_read_b128 v[200:203], v191 offset:36864
	ds_read_b128 v[204:207], v191 offset:37888
	ds_read_b128 v[208:211], v191 offset:38912
	ds_read_b128 v[212:215], v191 offset:39936
	s_waitcnt vmcnt(8)
	s_waitcnt lgkmcnt(0)
	s_barrier
	s_waitcnt lgkmcnt(0)
	v_mfma_f32_16x16x32_bf16 v[124:127], v[128:131], v[176:179], v[124:127]
	v_mfma_f32_16x16x32_bf16 v[120:123], v[136:139], v[176:179], v[120:123]
	v_mfma_f32_16x16x32_bf16 v[108:111], v[128:131], v[192:195], v[108:111]
	v_mfma_f32_16x16x32_bf16 v[104:107], v[136:139], v[192:195], v[104:107]
	v_mfma_f32_16x16x32_bf16 v[92:95], v[128:131], v[200:203], v[92:95]
	v_mfma_f32_16x16x32_bf16 v[88:91], v[136:139], v[200:203], v[88:91]
	v_mfma_f32_16x16x32_bf16 v[76:79], v[128:131], v[208:211], v[76:79]
	v_mfma_f32_16x16x32_bf16 v[72:75], v[136:139], v[208:211], v[72:75]
	v_mfma_f32_16x16x32_bf16 v[124:127], v[132:135], v[180:183], v[124:127]
	v_mfma_f32_16x16x32_bf16 v[120:123], v[140:143], v[180:183], v[120:123]
	v_mfma_f32_16x16x32_bf16 v[108:111], v[132:135], v[196:199], v[108:111]
	v_mfma_f32_16x16x32_bf16 v[104:107], v[140:143], v[196:199], v[104:107]
	v_mfma_f32_16x16x32_bf16 v[92:95], v[132:135], v[204:207], v[92:95]
	v_mfma_f32_16x16x32_bf16 v[88:91], v[140:143], v[204:207], v[88:91]
	v_mfma_f32_16x16x32_bf16 v[76:79], v[132:135], v[212:215], v[76:79]
	v_mfma_f32_16x16x32_bf16 v[72:75], v[140:143], v[212:215], v[72:75]
	v_mfma_f32_16x16x32_bf16 v[116:119], v[144:147], v[176:179], v[116:119]
	v_mfma_f32_16x16x32_bf16 v[112:115], v[168:171], v[176:179], v[112:115]
	v_mfma_f32_16x16x32_bf16 v[100:103], v[144:147], v[192:195], v[100:103]
	v_mfma_f32_16x16x32_bf16 v[96:99], v[168:171], v[192:195], v[96:99]
	v_mfma_f32_16x16x32_bf16 v[84:87], v[144:147], v[200:203], v[84:87]
	v_mfma_f32_16x16x32_bf16 v[80:83], v[168:171], v[200:203], v[80:83]
	v_mfma_f32_16x16x32_bf16 v[68:71], v[144:147], v[208:211], v[68:71]
	v_mfma_f32_16x16x32_bf16 v[64:67], v[168:171], v[208:211], v[64:67]
	v_mfma_f32_16x16x32_bf16 v[116:119], v[148:151], v[180:183], v[116:119]
	v_mfma_f32_16x16x32_bf16 v[112:115], v[172:175], v[180:183], v[112:115]
	v_mfma_f32_16x16x32_bf16 v[100:103], v[148:151], v[196:199], v[100:103]
	v_mfma_f32_16x16x32_bf16 v[96:99], v[172:175], v[196:199], v[96:99]
	v_mfma_f32_16x16x32_bf16 v[84:87], v[148:151], v[204:207], v[84:87]
	v_mfma_f32_16x16x32_bf16 v[80:83], v[172:175], v[204:207], v[80:83]
	v_mfma_f32_16x16x32_bf16 v[68:71], v[148:151], v[212:215], v[68:71]
	v_mfma_f32_16x16x32_bf16 v[64:67], v[172:175], v[212:215], v[64:67]
	s_barrier
; #define PG8_STAGE(bufoff, gbase, voff) do { _Pragma("unroll") for (int _i = 0; _i < 2; ++_i) \
;         __builtin_amdgcn_global_load_lds((const unsigned*)((const char*)(gbase) + (voff)[_i]), (PG8_LAS unsigned*)(lds + (bufoff) + ldsw + _i * 8192), 16, 0, 0); } while (0)
; #define PG8_LDA(dst, b, h) do { _Pragma("unroll") for (int m = 0; m < 4; ++m) _Pragma("unroll") for (int k = 0; k < 2; ++k) dst[m][k] = *(const PG8_LAS bf16x8*)(lds + PG8_SA(b, h) + aoff + m * 2048 + k * 1024); } while (0)
; #define PG8_MMA(ai, bj, At, Bt) do { __builtin_amdgcn_s_setprio(1); _Pragma("unroll") for (int m = 0; m < 4; ++m) _Pragma("unroll") for (int n = 0; n < 2; ++n) _Pragma("unroll") for (int k = 0; k < 2; ++k) \
;         acc[ai][bj][m][n] = mma16<F16>(Bt[n][k], At[m][k], acc[ai][bj][m][n]); __builtin_amdgcn_s_setprio(0); } while (0)
; #define PG8_WAIT_V(n) asm volatile("s_waitcnt vmcnt(" #n ")" ::: "memory")
; #define PG8_WAIT_L(n) asm volatile("s_waitcnt lgkmcnt(" #n ")" ::: "memory")
; #define PG8_BAR __builtin_amdgcn_s_barrier()
; #define PG8_SCHED __builtin_amdgcn_sched_barrier(0)
; template <class Epi, class Sched, bool ALIGN_EPI = false, bool SP2 = false, bool F16 = false>
; __device__ __forceinline__ void gemm_phase(PG8_LAS unsigned char* lds, const Gemm g, const Sched& S, const Epi& E, const int wid_in) {
;     ...
;             PG8_LDA(At, 1, 1); PG8_STAGE(PG8_SB(1, 0), b3, voffB); PG8_STAGE(PG8_SB(1, 1), b3 + hstep, voffB); PG8_STAGE(PG8_SA(1, 0), a3, voffA);
;             PG8_WAIT_V(8); PG8_WAIT_L(0); PG8_BAR; PG8_MMA(1, 0, At, B0); PG8_MMA(1, 1, At, B1); PG8_BAR; PG8_SCHED;
	s_add_i32 s36, s63, s68
	v_lshl_add_u64 v[184:185], v[184:185], 0, s[30:31]
	s_mov_b32 m0, s36
	s_nop 0
	global_load_lds_dwordx4 v[184:185], off
	s_add_i32 m0, s36, 0x2000
	s_add_u32 s36, s46, 0xb0080
	v_lshl_add_u64 v[184:185], v[216:217], 0, s[30:31]
	s_addc_u32 s37, s47, 0
	s_add_i32 s46, s64, s68
	global_load_lds_dwordx4 v[184:185], off
	v_lshl_add_u64 v[184:185], s[36:37], 0, v[154:155]
	s_mov_b32 m0, s46
	s_nop 0
	global_load_lds_dwordx4 v[184:185], off
	v_lshl_add_u64 v[184:185], s[36:37], 0, v[158:159]
	s_add_i32 m0, s46, 0x2000
	s_nop 0
	global_load_lds_dwordx4 v[184:185], off
	v_lshl_add_u64 v[184:185], v[218:219], 0, s[30:31]
	s_mov_b32 m0, s75
	s_nop 0
	global_load_lds_dwordx4 v[184:185], off
	v_lshl_add_u64 v[184:185], v[220:221], 0, s[30:31]
	s_mov_b32 m0, s52
	s_nop 0
	global_load_lds_dwordx4 v[184:185], off
	ds_read_b128 v[176:179], v191 offset:49152
	ds_read_b128 v[180:183], v191 offset:50176
	ds_read_b128 v[192:195], v191 offset:51200
	ds_read_b128 v[196:199], v191 offset:52224
	ds_read_b128 v[200:203], v191 offset:53248
	ds_read_b128 v[204:207], v191 offset:54272
	ds_read_b128 v[208:211], v191 offset:55296
	ds_read_b128 v[212:215], v191 offset:56320
	s_waitcnt vmcnt(8)
	s_waitcnt lgkmcnt(0)
	s_barrier
	s_waitcnt lgkmcnt(0)
	v_mfma_f32_16x16x32_bf16 v[60:63], v[128:131], v[176:179], v[60:63]
	v_mfma_f32_16x16x32_bf16 v[56:59], v[136:139], v[176:179], v[56:59]
	v_mfma_f32_16x16x32_bf16 v[44:47], v[128:131], v[192:195], v[44:47]
	v_mfma_f32_16x16x32_bf16 v[40:43], v[136:139], v[192:195], v[40:43]
	v_mfma_f32_16x16x32_bf16 v[28:31], v[128:131], v[200:203], v[28:31]
	v_mfma_f32_16x16x32_bf16 v[24:27], v[136:139], v[200:203], v[24:27]
	v_mfma_f32_16x16x32_bf16 v[12:15], v[128:131], v[208:211], v[12:15]
	v_mfma_f32_16x16x32_bf16 v[8:11], v[136:139], v[208:211], v[8:11]
	v_mfma_f32_16x16x32_bf16 v[60:63], v[132:135], v[180:183], v[60:63]
	v_mfma_f32_16x16x32_bf16 v[56:59], v[140:143], v[180:183], v[56:59]
	v_mfma_f32_16x16x32_bf16 v[44:47], v[132:135], v[196:199], v[44:47]
	v_mfma_f32_16x16x32_bf16 v[40:43], v[140:143], v[196:199], v[40:43]
	v_mfma_f32_16x16x32_bf16 v[28:31], v[132:135], v[204:207], v[28:31]
	v_mfma_f32_16x16x32_bf16 v[24:27], v[140:143], v[204:207], v[24:27]
	v_mfma_f32_16x16x32_bf16 v[12:15], v[132:135], v[212:215], v[12:15]
	v_mfma_f32_16x16x32_bf16 v[8:11], v[140:143], v[212:215], v[8:11]
	v_mfma_f32_16x16x32_bf16 v[52:55], v[144:147], v[176:179], v[52:55]
	v_mfma_f32_16x16x32_bf16 v[48:51], v[168:171], v[176:179], v[48:51]
	v_mfma_f32_16x16x32_bf16 v[36:39], v[144:147], v[192:195], v[36:39]
	v_mfma_f32_16x16x32_bf16 v[32:35], v[168:171], v[192:195], v[32:35]
	v_mfma_f32_16x16x32_bf16 v[20:23], v[144:147], v[200:203], v[20:23]
	v_mfma_f32_16x16x32_bf16 v[16:19], v[168:171], v[200:203], v[16:19]
	v_mfma_f32_16x16x32_bf16 v[4:7], v[144:147], v[208:211], v[4:7]
	v_mfma_f32_16x16x32_bf16 v[0:3], v[168:171], v[208:211], v[0:3]
	v_mfma_f32_16x16x32_bf16 v[52:55], v[148:151], v[180:183], v[52:55]
	v_mfma_f32_16x16x32_bf16 v[48:51], v[172:175], v[180:183], v[48:51]
	v_mfma_f32_16x16x32_bf16 v[36:39], v[148:151], v[196:199], v[36:39]
	v_mfma_f32_16x16x32_bf16 v[32:35], v[172:175], v[196:199], v[32:35]
	v_mfma_f32_16x16x32_bf16 v[20:23], v[148:151], v[204:207], v[20:23]
	v_mfma_f32_16x16x32_bf16 v[16:19], v[172:175], v[204:207], v[16:19]
	v_mfma_f32_16x16x32_bf16 v[4:7], v[148:151], v[212:215], v[4:7]
	v_mfma_f32_16x16x32_bf16 v[0:3], v[172:175], v[212:215], v[0:3]
	s_barrier
	s_add_i32 s62, s62, 2
	s_add_u32 s43, s43, 0x100
	s_addc_u32 s61, s61, 0
	s_cmp_gt_u32 s62, 41
	s_mov_b64 s[36:37], s[44:45]
	s_cbranch_scc0 .LBB0_1373
	s_and_b64 vcc, exec, s[16:17]
	s_cbranch_vccz .LBB0_1376
	s_barrier

; #define PG8_STAGE(bufoff, gbase, voff) do { _Pragma("unroll") for (int _i = 0; _i < 2; ++_i) \
;         __builtin_amdgcn_global_load_lds((const unsigned*)((const char*)(gbase) + (voff)[_i]), (PG8_LAS unsigned*)(lds + (bufoff) + ldsw + _i * 8192), 16, 0, 0); } while (0)
; #define PG8_LDA(dst, b, h) do { _Pragma("unroll") for (int m = 0; m < 4; ++m) _Pragma("unroll") for (int k = 0; k < 2; ++k) dst[m][k] = *(const PG8_LAS bf16x8*)(lds + PG8_SA(b, h) + aoff + m * 2048 + k * 1024); } while (0)
; #define PG8_LDB(dst, b, h) do { _Pragma("unroll") for (int n = 0; n < 2; ++n) _Pragma("unroll") for (int k = 0; k < 2; ++k) dst[n][k] = *(const PG8_LAS bf16x8*)(lds + PG8_SB(b, h) + boff + n * 2048 + k * 1024); } while (0)
; #define PG8_MMA(ai, bj, At, Bt) do { __builtin_amdgcn_s_setprio(1); _Pragma("unroll") for (int m = 0; m < 4; ++m) _Pragma("unroll") for (int n = 0; n < 2; ++n) _Pragma("unroll") for (int k = 0; k < 2; ++k) \
;         acc[ai][bj][m][n] = mma16<F16>(Bt[n][k], At[m][k], acc[ai][bj][m][n]); __builtin_amdgcn_s_setprio(0); } while (0)
; #define PG8_WAIT_V(n) asm volatile("s_waitcnt vmcnt(" #n ")" ::: "memory")
; #define PG8_BAR __builtin_amdgcn_s_barrier()
; template <class Epi, class Sched, bool ALIGN_EPI = false, bool SP2 = false, bool F16 = false>
; __device__ __forceinline__ void gemm_phase(PG8_LAS unsigned char* lds, const Gemm g, const Sched& S, const Epi& E, const int wid_in) {
;     ...
;         for (int t = 0; t < nt; t += 2) {
;             const bool last = (t == nt - 2);
;             const char* a1 = cA + (size_t)(t + 1) * kstep;
;             const char* a2 = last ? nA : cA + (size_t)(t + 2) * kstep; const char* b2 = last ? nB : cB + (size_t)(t + 2) * kstep;
;             const char* a3 = a2 + kstep; const char* b3 = b2 + kstep;
;             if (last && has_next) S.a_ready(nxt);
;             if constexpr (SP2) {
;             PG8_LDB(B0, 0, 0); PG8_LDB(B1, 0, 1); PG8_SCHED; PG8_LDA(At, 0, 0); PG8_STAGE(PG8_SA(1, 1), a1 + hstep, voffA);
;             PG8_WAIT_V(8); PG8_WAIT_L(0); PG8_BAR; PG8_MMA(0, 0, At, B0); PG8_MMA(0, 1, At, B1); PG8_BAR; PG8_SCHED;
;             PG8_LDA(At, 0, 1); PG8_STAGE(PG8_SB(0, 0), b2, voffB); PG8_STAGE(PG8_SB(0, 1), b2 + hstep, voffB); PG8_STAGE(PG8_SA(0, 0), a2, voffA);
;             PG8_WAIT_V(8); PG8_WAIT_L(0); PG8_BAR; PG8_MMA(1, 0, At, B0); PG8_MMA(1, 1, At, B1); PG8_BAR; PG8_SCHED;
.LBB0_1469:
	ds_read_b128 v[112:115], v235
	ds_read_b128 v[116:119], v235 offset:1024
	ds_read_b128 v[128:131], v235 offset:2048
	ds_read_b128 v[132:135], v235 offset:3072
	ds_read_b128 v[144:147], v236
	ds_read_b128 v[148:151], v236 offset:1024
	ds_read_b128 v[152:155], v236 offset:2048
	ds_read_b128 v[156:159], v236 offset:3072
	s_add_u32 s45, s52, 0xfffc0080
	s_addc_u32 s51, s53, -1
	s_cmp_eq_u32 s43, 12
	s_cselect_b32 s57, s14, s51
	s_cselect_b32 s56, s15, s45
	s_cselect_b32 s55, s37, s42
	s_cselect_b32 s54, s40, s41
	v_lshl_add_u64 v[192:193], s[52:53], 0, v[204:205]
	s_add_i32 m0, s74, 0xc000
	ds_read_b128 v[160:163], v237
	ds_read_b128 v[164:167], v237 offset:1024
	ds_read_b128 v[168:171], v237 offset:2048
	ds_read_b128 v[172:175], v237 offset:3072
	ds_read_b128 v[176:179], v237 offset:4096
	ds_read_b128 v[180:183], v237 offset:5120
	ds_read_b128 v[184:187], v237 offset:6144
	ds_read_b128 v[188:191], v237 offset:7168
	global_load_lds_dwordx4 v[192:193], off
	v_lshl_add_u64 v[192:193], s[52:53], 0, v[206:207]
	s_add_i32 m0, s74, 0xe000
	s_nop 0
	global_load_lds_dwordx4 v[192:193], off
	s_waitcnt vmcnt(8)
	s_waitcnt lgkmcnt(0)
	s_barrier
	s_waitcnt lgkmcnt(0)
	v_mfma_f32_16x16x32_f16 v[140:143], v[112:115], v[160:163], v[140:143]
	v_mfma_f32_16x16x32_f16 v[136:139], v[128:131], v[160:163], v[136:139]
	v_mfma_f32_16x16x32_f16 v[108:111], v[112:115], v[168:171], v[108:111]
	v_mfma_f32_16x16x32_f16 v[104:107], v[128:131], v[168:171], v[104:107]
	v_mfma_f32_16x16x32_f16 v[92:95], v[112:115], v[176:179], v[92:95]
	v_mfma_f32_16x16x32_f16 v[88:91], v[128:131], v[176:179], v[88:91]
	v_mfma_f32_16x16x32_f16 v[76:79], v[112:115], v[184:187], v[76:79]
	v_mfma_f32_16x16x32_f16 v[72:75], v[128:131], v[184:187], v[72:75]
	v_mfma_f32_16x16x32_f16 v[140:143], v[116:119], v[164:167], v[140:143]
	v_mfma_f32_16x16x32_f16 v[136:139], v[132:135], v[164:167], v[136:139]
	v_mfma_f32_16x16x32_f16 v[108:111], v[116:119], v[172:175], v[108:111]
	v_mfma_f32_16x16x32_f16 v[104:107], v[132:135], v[172:175], v[104:107]
	v_mfma_f32_16x16x32_f16 v[92:95], v[116:119], v[180:183], v[92:95]
	v_mfma_f32_16x16x32_f16 v[88:91], v[132:135], v[180:183], v[88:91]
	v_mfma_f32_16x16x32_f16 v[76:79], v[116:119], v[188:191], v[76:79]
	v_mfma_f32_16x16x32_f16 v[72:75], v[132:135], v[188:191], v[72:75]
	v_mfma_f32_16x16x32_f16 v[124:127], v[144:147], v[160:163], v[124:127]
	v_mfma_f32_16x16x32_f16 v[120:123], v[152:155], v[160:163], v[120:123]
	v_mfma_f32_16x16x32_f16 v[100:103], v[144:147], v[168:171], v[100:103]
	v_mfma_f32_16x16x32_f16 v[96:99], v[152:155], v[168:171], v[96:99]
	v_mfma_f32_16x16x32_f16 v[84:87], v[144:147], v[176:179], v[84:87]
	v_mfma_f32_16x16x32_f16 v[80:83], v[152:155], v[176:179], v[80:83]
	v_mfma_f32_16x16x32_f16 v[68:71], v[144:147], v[184:187], v[68:71]
	v_mfma_f32_16x16x32_f16 v[64:67], v[152:155], v[184:187], v[64:67]
	v_mfma_f32_16x16x32_f16 v[124:127], v[148:151], v[164:167], v[124:127]
	v_mfma_f32_16x16x32_f16 v[120:123], v[156:159], v[164:167], v[120:123]
	v_mfma_f32_16x16x32_f16 v[100:103], v[148:151], v[172:175], v[100:103]
	v_mfma_f32_16x16x32_f16 v[96:99], v[156:159], v[172:175], v[96:99]
	v_mfma_f32_16x16x32_f16 v[84:87], v[148:151], v[180:183], v[84:87]
	v_mfma_f32_16x16x32_f16 v[80:83], v[156:159], v[180:183], v[80:83]
	v_mfma_f32_16x16x32_f16 v[68:71], v[148:151], v[188:191], v[68:71]
	v_mfma_f32_16x16x32_f16 v[64:67], v[156:159], v[188:191], v[64:67]
	s_barrier
	s_add_i32 s45, s66, s68
	v_lshl_add_u64 v[192:193], s[54:55], 0, v[198:199]
	s_mov_b32 m0, s45
	s_nop 0
	global_load_lds_dwordx4 v[192:193], off
	s_add_i32 m0, s45, 0x2000
	s_add_u32 s94, s54, 0x40000
	v_lshl_add_u64 v[194:195], s[54:55], 0, v[202:203]
	s_addc_u32 s95, s55, 0
	s_add_i32 s45, s67, s68
	global_load_lds_dwordx4 v[194:195], off
	v_lshl_add_u64 v[212:213], s[94:95], 0, v[198:199]
	s_mov_b32 m0, s45
	v_lshl_add_u64 v[214:215], s[56:57], 0, v[200:201]
	global_load_lds_dwordx4 v[212:213], off
	v_lshl_add_u64 v[212:213], s[94:95], 0, v[202:203]
	s_add_i32 m0, s45, 0x2000
	s_nop 0
	global_load_lds_dwordx4 v[212:213], off
	v_lshl_add_u64 v[212:213], s[56:57], 0, v[196:197]
	s_mov_b32 m0, s74
	s_nop 0
	global_load_lds_dwordx4 v[212:213], off
	s_mov_b32 m0, s59
	s_nop 0
	global_load_lds_dwordx4 v[214:215], off
	ds_read_b128 v[160:163], v237 offset:16384
	ds_read_b128 v[164:167], v237 offset:17408
	ds_read_b128 v[168:171], v237 offset:18432
	ds_read_b128 v[172:175], v237 offset:19456
	ds_read_b128 v[176:179], v237 offset:20480
	ds_read_b128 v[180:183], v237 offset:21504
	ds_read_b128 v[184:187], v237 offset:22528
	ds_read_b128 v[188:191], v237 offset:23552
	s_waitcnt vmcnt(8)
	s_waitcnt lgkmcnt(0)
	s_barrier
; #define PG8_STAGE(bufoff, gbase, voff) do { _Pragma("unroll") for (int _i = 0; _i < 2; ++_i) \
;         __builtin_amdgcn_global_load_lds((const unsigned*)((const char*)(gbase) + (voff)[_i]), (PG8_LAS unsigned*)(lds + (bufoff) + ldsw + _i * 8192), 16, 0, 0); } while (0)
; #define PG8_LDA(dst, b, h) do { _Pragma("unroll") for (int m = 0; m < 4; ++m) _Pragma("unroll") for (int k = 0; k < 2; ++k) dst[m][k] = *(const PG8_LAS bf16x8*)(lds + PG8_SA(b, h) + aoff + m * 2048 + k * 1024); } while (0)
; #define PG8_LDB(dst, b, h) do { _Pragma("unroll") for (int n = 0; n < 2; ++n) _Pragma("unroll") for (int k = 0; k < 2; ++k) dst[n][k] = *(const PG8_LAS bf16x8*)(lds + PG8_SB(b, h) + boff + n * 2048 + k * 1024); } while (0)
; #define PG8_MMA(ai, bj, At, Bt) do { __builtin_amdgcn_s_setprio(1); _Pragma("unroll") for (int m = 0; m < 4; ++m) _Pragma("unroll") for (int n = 0; n < 2; ++n) _Pragma("unroll") for (int k = 0; k < 2; ++k) \
;         acc[ai][bj][m][n] = mma16<F16>(Bt[n][k], At[m][k], acc[ai][bj][m][n]); __builtin_amdgcn_s_setprio(0); } while (0)
; #define PG8_WAIT_V(n) asm volatile("s_waitcnt vmcnt(" #n ")" ::: "memory")
; #define PG8_WAIT_L(n) asm volatile("s_waitcnt lgkmcnt(" #n ")" ::: "memory")
; #define PG8_BAR __builtin_amdgcn_s_barrier()
; #define PG8_SCHED __builtin_amdgcn_sched_barrier(0)
; template <class Epi, class Sched, bool ALIGN_EPI = false, bool SP2 = false, bool F16 = false>
; __device__ __forceinline__ void gemm_phase(PG8_LAS unsigned char* lds, const Gemm g, const Sched& S, const Epi& E, const int wid_in) {
;     ...
;             PG8_WAIT_V(8); PG8_WAIT_L(0); PG8_BAR; PG8_MMA(1, 0, At, B0); PG8_MMA(1, 1, At, B1); PG8_BAR; PG8_SCHED;
;             PG8_LDB(B0, 1, 0); PG8_LDB(B1, 1, 1); PG8_SCHED; PG8_LDA(At, 1, 0); PG8_STAGE(PG8_SA(0, 1), a2 + hstep, voffA);
;             PG8_WAIT_V(8); PG8_WAIT_L(0); PG8_BAR; PG8_MMA(0, 0, At, B0); PG8_MMA(0, 1, At, B1); PG8_BAR; PG8_SCHED;
	s_waitcnt lgkmcnt(0)
	v_mfma_f32_16x16x32_f16 v[60:63], v[112:115], v[160:163], v[60:63]
	v_mfma_f32_16x16x32_f16 v[56:59], v[128:131], v[160:163], v[56:59]
	v_mfma_f32_16x16x32_f16 v[44:47], v[112:115], v[168:171], v[44:47]
	v_mfma_f32_16x16x32_f16 v[40:43], v[128:131], v[168:171], v[40:43]
	v_mfma_f32_16x16x32_f16 v[28:31], v[112:115], v[176:179], v[28:31]
	v_mfma_f32_16x16x32_f16 v[24:27], v[128:131], v[176:179], v[24:27]
	v_mfma_f32_16x16x32_f16 v[12:15], v[112:115], v[184:187], v[12:15]
	v_mfma_f32_16x16x32_f16 v[8:11], v[128:131], v[184:187], v[8:11]
	v_mfma_f32_16x16x32_f16 v[60:63], v[116:119], v[164:167], v[60:63]
	v_mfma_f32_16x16x32_f16 v[56:59], v[132:135], v[164:167], v[56:59]
	v_mfma_f32_16x16x32_f16 v[44:47], v[116:119], v[172:175], v[44:47]
	v_mfma_f32_16x16x32_f16 v[40:43], v[132:135], v[172:175], v[40:43]
	v_mfma_f32_16x16x32_f16 v[28:31], v[116:119], v[180:183], v[28:31]
	v_mfma_f32_16x16x32_f16 v[24:27], v[132:135], v[180:183], v[24:27]
	v_mfma_f32_16x16x32_f16 v[12:15], v[116:119], v[188:191], v[12:15]
	v_mfma_f32_16x16x32_f16 v[8:11], v[132:135], v[188:191], v[8:11]
	v_mfma_f32_16x16x32_f16 v[52:55], v[144:147], v[160:163], v[52:55]
	v_mfma_f32_16x16x32_f16 v[48:51], v[152:155], v[160:163], v[48:51]
	v_mfma_f32_16x16x32_f16 v[36:39], v[144:147], v[168:171], v[36:39]
	v_mfma_f32_16x16x32_f16 v[32:35], v[152:155], v[168:171], v[32:35]
	v_mfma_f32_16x16x32_f16 v[20:23], v[144:147], v[176:179], v[20:23]
	v_mfma_f32_16x16x32_f16 v[16:19], v[152:155], v[176:179], v[16:19]
	v_mfma_f32_16x16x32_f16 v[4:7], v[144:147], v[184:187], v[4:7]
	v_mfma_f32_16x16x32_f16 v[0:3], v[152:155], v[184:187], v[0:3]
	v_mfma_f32_16x16x32_f16 v[52:55], v[148:151], v[164:167], v[52:55]
	v_mfma_f32_16x16x32_f16 v[48:51], v[156:159], v[164:167], v[48:51]
	v_mfma_f32_16x16x32_f16 v[36:39], v[148:151], v[172:175], v[36:39]
	v_mfma_f32_16x16x32_f16 v[32:35], v[156:159], v[172:175], v[32:35]
	v_mfma_f32_16x16x32_f16 v[20:23], v[148:151], v[180:183], v[20:23]
	v_mfma_f32_16x16x32_f16 v[16:19], v[156:159], v[180:183], v[16:19]
	v_mfma_f32_16x16x32_f16 v[4:7], v[148:151], v[188:191], v[4:7]
	v_mfma_f32_16x16x32_f16 v[0:3], v[156:159], v[188:191], v[0:3]
	s_barrier
	s_add_i32 s45, 0, 0x18000
	s_add_i32 s51, 0, 0x1c000
	v_add_u32_e32 v132, s45, v234
	v_add_u32_e32 v156, s51, v234
	s_add_u32 s56, s56, 0x40000
	s_addc_u32 s57, s57, 0
	s_mov_b32 m0, s60
	v_lshl_add_u64 v[216:217], s[56:57], 0, v[196:197]
	global_load_lds_dwordx4 v[216:217], off
	v_lshl_add_u64 v[216:217], s[56:57], 0, v[200:201]
	s_mov_b32 m0, s61
	s_nop 0
	global_load_lds_dwordx4 v[216:217], off
	ds_read_b128 v[112:115], v132
	ds_read_b128 v[116:119], v132 offset:1024
	ds_read_b128 v[128:131], v132 offset:2048
	ds_read_b128 v[132:135], v132 offset:3072
	ds_read_b128 v[144:147], v156
	ds_read_b128 v[148:151], v156 offset:1024
	ds_read_b128 v[152:155], v156 offset:2048
	ds_read_b128 v[156:159], v156 offset:3072
	ds_read_b128 v[160:163], v237 offset:32768
	ds_read_b128 v[164:167], v237 offset:33792
	ds_read_b128 v[168:171], v237 offset:34816
	ds_read_b128 v[172:175], v237 offset:35840
	ds_read_b128 v[176:179], v237 offset:36864
	ds_read_b128 v[180:183], v237 offset:37888
	ds_read_b128 v[184:187], v237 offset:38912
	ds_read_b128 v[188:191], v237 offset:39936
	s_waitcnt vmcnt(8)
	s_waitcnt lgkmcnt(0)
	s_barrier
	s_waitcnt lgkmcnt(0)
	v_mfma_f32_16x16x32_f16 v[140:143], v[112:115], v[160:163], v[140:143]
	v_mfma_f32_16x16x32_f16 v[136:139], v[128:131], v[160:163], v[136:139]
	v_mfma_f32_16x16x32_f16 v[108:111], v[112:115], v[168:171], v[108:111]
	v_mfma_f32_16x16x32_f16 v[104:107], v[128:131], v[168:171], v[104:107]
	v_mfma_f32_16x16x32_f16 v[92:95], v[112:115], v[176:179], v[92:95]
	v_mfma_f32_16x16x32_f16 v[88:91], v[128:131], v[176:179], v[88:91]
	v_mfma_f32_16x16x32_f16 v[76:79], v[112:115], v[184:187], v[76:79]
	v_mfma_f32_16x16x32_f16 v[72:75], v[128:131], v[184:187], v[72:75]
	v_mfma_f32_16x16x32_f16 v[140:143], v[116:119], v[164:167], v[140:143]
	v_mfma_f32_16x16x32_f16 v[136:139], v[132:135], v[164:167], v[136:139]
	v_mfma_f32_16x16x32_f16 v[108:111], v[116:119], v[172:175], v[108:111]
	v_mfma_f32_16x16x32_f16 v[104:107], v[132:135], v[172:175], v[104:107]
	v_mfma_f32_16x16x32_f16 v[92:95], v[116:119], v[180:183], v[92:95]
	v_mfma_f32_16x16x32_f16 v[88:91], v[132:135], v[180:183], v[88:91]
	v_mfma_f32_16x16x32_f16 v[76:79], v[116:119], v[188:191], v[76:79]
	v_mfma_f32_16x16x32_f16 v[72:75], v[132:135], v[188:191], v[72:75]
	v_mfma_f32_16x16x32_f16 v[124:127], v[144:147], v[160:163], v[124:127]
	v_mfma_f32_16x16x32_f16 v[120:123], v[152:155], v[160:163], v[120:123]
	v_mfma_f32_16x16x32_f16 v[100:103], v[144:147], v[168:171], v[100:103]
	v_mfma_f32_16x16x32_f16 v[96:99], v[152:155], v[168:171], v[96:99]
	v_mfma_f32_16x16x32_f16 v[84:87], v[144:147], v[176:179], v[84:87]
	v_mfma_f32_16x16x32_f16 v[80:83], v[152:155], v[176:179], v[80:83]
	v_mfma_f32_16x16x32_f16 v[68:71], v[144:147], v[184:187], v[68:71]
	v_mfma_f32_16x16x32_f16 v[64:67], v[152:155], v[184:187], v[64:67]
	v_mfma_f32_16x16x32_f16 v[124:127], v[148:151], v[164:167], v[124:127]
	v_mfma_f32_16x16x32_f16 v[120:123], v[156:159], v[164:167], v[120:123]
	v_mfma_f32_16x16x32_f16 v[100:103], v[148:151], v[172:175], v[100:103]
	v_mfma_f32_16x16x32_f16 v[96:99], v[156:159], v[172:175], v[96:99]
	v_mfma_f32_16x16x32_f16 v[84:87], v[148:151], v[180:183], v[84:87]
	v_mfma_f32_16x16x32_f16 v[80:83], v[156:159], v[180:183], v[80:83]
	v_mfma_f32_16x16x32_f16 v[68:71], v[148:151], v[188:191], v[68:71]
	v_mfma_f32_16x16x32_f16 v[64:67], v[156:159], v[188:191], v[64:67]
	s_barrier
; #define PG8_STAGE(bufoff, gbase, voff) do { _Pragma("unroll") for (int _i = 0; _i < 2; ++_i) \
;         __builtin_amdgcn_global_load_lds((const unsigned*)((const char*)(gbase) + (voff)[_i]), (PG8_LAS unsigned*)(lds + (bufoff) + ldsw + _i * 8192), 16, 0, 0); } while (0)
; #define PG8_LDA(dst, b, h) do { _Pragma("unroll") for (int m = 0; m < 4; ++m) _Pragma("unroll") for (int k = 0; k < 2; ++k) dst[m][k] = *(const PG8_LAS bf16x8*)(lds + PG8_SA(b, h) + aoff + m * 2048 + k * 1024); } while (0)
; #define PG8_MMA(ai, bj, At, Bt) do { __builtin_amdgcn_s_setprio(1); _Pragma("unroll") for (int m = 0; m < 4; ++m) _Pragma("unroll") for (int n = 0; n < 2; ++n) _Pragma("unroll") for (int k = 0; k < 2; ++k) \
;         acc[ai][bj][m][n] = mma16<F16>(Bt[n][k], At[m][k], acc[ai][bj][m][n]); __builtin_amdgcn_s_setprio(0); } while (0)
; #define PG8_WAIT_V(n) asm volatile("s_waitcnt vmcnt(" #n ")" ::: "memory")
; #define PG8_WAIT_L(n) asm volatile("s_waitcnt lgkmcnt(" #n ")" ::: "memory")
; #define PG8_BAR __builtin_amdgcn_s_barrier()
; #define PG8_SCHED __builtin_amdgcn_sched_barrier(0)
; template <class Epi, class Sched, bool ALIGN_EPI = false, bool SP2 = false, bool F16 = false>
; __device__ __forceinline__ void gemm_phase(PG8_LAS unsigned char* lds, const Gemm g, const Sched& S, const Epi& E, const int wid_in) {
;     ...
;             PG8_LDA(At, 1, 1); PG8_STAGE(PG8_SB(1, 0), b3, voffB); PG8_STAGE(PG8_SB(1, 1), b3 + hstep, voffB); PG8_STAGE(PG8_SA(1, 0), a3, voffA);
;             PG8_WAIT_V(8); PG8_WAIT_L(0); PG8_BAR; PG8_MMA(1, 0, At, B0); PG8_MMA(1, 1, At, B1); PG8_BAR; PG8_SCHED;
	s_add_i32 s45, s45, s68
	v_lshl_add_u64 v[192:193], v[192:193], 0, s[34:35]
	s_mov_b32 m0, s45
	s_nop 0
	global_load_lds_dwordx4 v[192:193], off
	s_add_i32 m0, s45, 0x2000
	s_add_u32 s54, s54, 0x40080
	v_lshl_add_u64 v[192:193], v[194:195], 0, s[34:35]
	s_addc_u32 s55, s55, 0
	s_add_i32 s45, s51, s68
	global_load_lds_dwordx4 v[192:193], off
	v_lshl_add_u64 v[192:193], s[54:55], 0, v[198:199]
	s_mov_b32 m0, s45
	s_nop 0
	global_load_lds_dwordx4 v[192:193], off
	v_lshl_add_u64 v[192:193], s[54:55], 0, v[202:203]
	s_add_i32 m0, s45, 0x2000
	s_nop 0
	global_load_lds_dwordx4 v[192:193], off
	v_lshl_add_u64 v[192:193], v[212:213], 0, s[34:35]
	s_mov_b32 m0, s75
	s_nop 0
	global_load_lds_dwordx4 v[192:193], off
	v_lshl_add_u64 v[192:193], v[214:215], 0, s[34:35]
	s_mov_b32 m0, s62
	s_nop 0
	global_load_lds_dwordx4 v[192:193], off
	ds_read_b128 v[160:163], v237 offset:49152
	ds_read_b128 v[164:167], v237 offset:50176
	ds_read_b128 v[168:171], v237 offset:51200
	ds_read_b128 v[172:175], v237 offset:52224
	ds_read_b128 v[176:179], v237 offset:53248
	ds_read_b128 v[180:183], v237 offset:54272
	ds_read_b128 v[184:187], v237 offset:55296
	ds_read_b128 v[188:191], v237 offset:56320
	s_waitcnt vmcnt(8)
	s_waitcnt lgkmcnt(0)
	s_barrier
	s_waitcnt lgkmcnt(0)
	v_mfma_f32_16x16x32_f16 v[60:63], v[112:115], v[160:163], v[60:63]
	v_mfma_f32_16x16x32_f16 v[56:59], v[128:131], v[160:163], v[56:59]
	v_mfma_f32_16x16x32_f16 v[44:47], v[112:115], v[168:171], v[44:47]
	v_mfma_f32_16x16x32_f16 v[40:43], v[128:131], v[168:171], v[40:43]
	v_mfma_f32_16x16x32_f16 v[28:31], v[112:115], v[176:179], v[28:31]
	v_mfma_f32_16x16x32_f16 v[24:27], v[128:131], v[176:179], v[24:27]
	v_mfma_f32_16x16x32_f16 v[12:15], v[112:115], v[184:187], v[12:15]
	v_mfma_f32_16x16x32_f16 v[8:11], v[128:131], v[184:187], v[8:11]
	v_mfma_f32_16x16x32_f16 v[60:63], v[116:119], v[164:167], v[60:63]
	v_mfma_f32_16x16x32_f16 v[56:59], v[132:135], v[164:167], v[56:59]
	v_mfma_f32_16x16x32_f16 v[44:47], v[116:119], v[172:175], v[44:47]
	v_mfma_f32_16x16x32_f16 v[40:43], v[132:135], v[172:175], v[40:43]
	v_mfma_f32_16x16x32_f16 v[28:31], v[116:119], v[180:183], v[28:31]
	v_mfma_f32_16x16x32_f16 v[24:27], v[132:135], v[180:183], v[24:27]
	v_mfma_f32_16x16x32_f16 v[12:15], v[116:119], v[188:191], v[12:15]
	v_mfma_f32_16x16x32_f16 v[8:11], v[132:135], v[188:191], v[8:11]
	v_mfma_f32_16x16x32_f16 v[52:55], v[144:147], v[160:163], v[52:55]
	v_mfma_f32_16x16x32_f16 v[48:51], v[152:155], v[160:163], v[48:51]
	v_mfma_f32_16x16x32_f16 v[36:39], v[144:147], v[168:171], v[36:39]
	v_mfma_f32_16x16x32_f16 v[32:35], v[152:155], v[168:171], v[32:35]
	v_mfma_f32_16x16x32_f16 v[20:23], v[144:147], v[176:179], v[20:23]
	v_mfma_f32_16x16x32_f16 v[16:19], v[152:155], v[176:179], v[16:19]
	v_mfma_f32_16x16x32_f16 v[4:7], v[144:147], v[184:187], v[4:7]
	v_mfma_f32_16x16x32_f16 v[0:3], v[152:155], v[184:187], v[0:3]
	v_mfma_f32_16x16x32_f16 v[52:55], v[148:151], v[164:167], v[52:55]
	v_mfma_f32_16x16x32_f16 v[48:51], v[156:159], v[164:167], v[48:51]
	v_mfma_f32_16x16x32_f16 v[36:39], v[148:151], v[172:175], v[36:39]
	v_mfma_f32_16x16x32_f16 v[32:35], v[156:159], v[172:175], v[32:35]
	v_mfma_f32_16x16x32_f16 v[20:23], v[148:151], v[180:183], v[20:23]
	v_mfma_f32_16x16x32_f16 v[16:19], v[156:159], v[180:183], v[16:19]
	v_mfma_f32_16x16x32_f16 v[4:7], v[148:151], v[188:191], v[4:7]
	v_mfma_f32_16x16x32_f16 v[0:3], v[156:159], v[188:191], v[0:3]
	s_barrier
	s_add_i32 s43, s43, 2
	s_add_u32 s52, s52, 0x100
	s_addc_u32 s53, s53, 0
	s_add_u32 s41, s41, 0x100
	s_addc_u32 s42, s42, 0
	s_cmp_gt_u32 s43, 13
	s_cbranch_scc0 .LBB0_1469
	s_and_b64 vcc, exec, s[16:17]
	s_cbranch_vccz .LBB0_1472
	s_barrier

; #define PG8_STAGE(bufoff, gbase, voff) do { _Pragma("unroll") for (int _i = 0; _i < 2; ++_i) \
;         __builtin_amdgcn_global_load_lds((const unsigned*)((const char*)(gbase) + (voff)[_i]), (PG8_LAS unsigned*)(lds + (bufoff) + ldsw + _i * 8192), 16, 0, 0); } while (0)
; #define PG8_LDA(dst, b, h) do { _Pragma("unroll") for (int m = 0; m < 4; ++m) _Pragma("unroll") for (int k = 0; k < 2; ++k) dst[m][k] = *(const PG8_LAS bf16x8*)(lds + PG8_SA(b, h) + aoff + m * 2048 + k * 1024); } while (0)
; #define PG8_LDB(dst, b, h) do { _Pragma("unroll") for (int n = 0; n < 2; ++n) _Pragma("unroll") for (int k = 0; k < 2; ++k) dst[n][k] = *(const PG8_LAS bf16x8*)(lds + PG8_SB(b, h) + boff + n * 2048 + k * 1024); } while (0)
; #define PG8_MMA(ai, bj, At, Bt) do { __builtin_amdgcn_s_setprio(1); _Pragma("unroll") for (int m = 0; m < 4; ++m) _Pragma("unroll") for (int n = 0; n < 2; ++n) _Pragma("unroll") for (int k = 0; k < 2; ++k) \
;         acc[ai][bj][m][n] = mma16<F16>(Bt[n][k], At[m][k], acc[ai][bj][m][n]); __builtin_amdgcn_s_setprio(0); } while (0)
; #define PG8_WAIT_V(n) asm volatile("s_waitcnt vmcnt(" #n ")" ::: "memory")
; #define PG8_BAR __builtin_amdgcn_s_barrier()
; template <class Epi, class Sched, bool ALIGN_EPI = false, bool SP2 = false, bool F16 = false>
; __device__ __forceinline__ void gemm_phase(PG8_LAS unsigned char* lds, const Gemm g, const Sched& S, const Epi& E, const int wid_in) {
;     ...
;         for (int t = 0; t < nt; t += 2) {
;             const bool last = (t == nt - 2);
;             const char* a1 = cA + (size_t)(t + 1) * kstep;
;             const char* a2 = last ? nA : cA + (size_t)(t + 2) * kstep; const char* b2 = last ? nB : cB + (size_t)(t + 2) * kstep;
;             const char* a3 = a2 + kstep; const char* b3 = b2 + kstep;
;             if (last && has_next) S.a_ready(nxt);
;             if constexpr (SP2) {
;             PG8_LDB(B0, 0, 0); PG8_LDB(B1, 0, 1); PG8_SCHED; PG8_LDA(At, 0, 0); PG8_STAGE(PG8_SA(1, 1), a1 + hstep, voffA);
;             PG8_WAIT_V(8); PG8_WAIT_L(0); PG8_BAR; PG8_MMA(0, 0, At, B0); PG8_MMA(0, 1, At, B1); PG8_BAR; PG8_SCHED;
;             PG8_LDA(At, 0, 1); PG8_STAGE(PG8_SB(0, 0), b2, voffB); PG8_STAGE(PG8_SB(0, 1), b2 + hstep, voffB); PG8_STAGE(PG8_SA(0, 0), a2, voffA);
;             PG8_WAIT_V(8); PG8_WAIT_L(0); PG8_BAR; PG8_MMA(1, 0, At, B0); PG8_MMA(1, 1, At, B1); PG8_BAR; PG8_SCHED;
.LBB0_1548:
	ds_read_b128 v[128:131], v184
	ds_read_b128 v[132:135], v184 offset:1024
	ds_read_b128 v[136:139], v184 offset:2048
	ds_read_b128 v[140:143], v184 offset:3072
	ds_read_b128 v[144:147], v185
	ds_read_b128 v[148:151], v185 offset:1024
	ds_read_b128 v[152:155], v185 offset:2048
	ds_read_b128 v[174:177], v185 offset:3072
	s_add_u32 s45, s50, 0xfffc0080
	s_addc_u32 s52, s51, -1
	s_cmp_eq_u32 s43, 12
	s_cselect_b32 s55, s13, s52
	s_cselect_b32 s54, s31, s45
	s_cselect_b32 s53, s37, s42
	s_cselect_b32 s52, s40, s41
	v_lshl_add_u64 v[178:179], s[50:51], 0, v[166:167]
	s_add_i32 m0, s74, 0xc000
	ds_read_b128 v[190:193], v186
	ds_read_b128 v[194:197], v186 offset:1024
	ds_read_b128 v[198:201], v186 offset:2048
	ds_read_b128 v[202:205], v186 offset:3072
	ds_read_b128 v[206:209], v186 offset:4096
	ds_read_b128 v[210:213], v186 offset:5120
	ds_read_b128 v[214:217], v186 offset:6144
	ds_read_b128 v[218:221], v186 offset:7168
	global_load_lds_dwordx4 v[178:179], off
	v_lshl_add_u64 v[178:179], s[50:51], 0, v[168:169]
	s_add_i32 m0, s74, 0xe000
	s_nop 0
	global_load_lds_dwordx4 v[178:179], off
	s_waitcnt vmcnt(8)
	s_waitcnt lgkmcnt(0)
	s_barrier
	s_waitcnt lgkmcnt(0)
	v_mfma_f32_16x16x32_f16 v[124:127], v[128:131], v[190:193], v[124:127]
	v_mfma_f32_16x16x32_f16 v[120:123], v[136:139], v[190:193], v[120:123]
	v_mfma_f32_16x16x32_f16 v[108:111], v[128:131], v[198:201], v[108:111]
	v_mfma_f32_16x16x32_f16 v[104:107], v[136:139], v[198:201], v[104:107]
	v_mfma_f32_16x16x32_f16 v[92:95], v[128:131], v[206:209], v[92:95]
	v_mfma_f32_16x16x32_f16 v[88:91], v[136:139], v[206:209], v[88:91]
	v_mfma_f32_16x16x32_f16 v[76:79], v[128:131], v[214:217], v[76:79]
	v_mfma_f32_16x16x32_f16 v[72:75], v[136:139], v[214:217], v[72:75]
	v_mfma_f32_16x16x32_f16 v[124:127], v[132:135], v[194:197], v[124:127]
	v_mfma_f32_16x16x32_f16 v[120:123], v[140:143], v[194:197], v[120:123]
	v_mfma_f32_16x16x32_f16 v[108:111], v[132:135], v[202:205], v[108:111]
	v_mfma_f32_16x16x32_f16 v[104:107], v[140:143], v[202:205], v[104:107]
	v_mfma_f32_16x16x32_f16 v[92:95], v[132:135], v[210:213], v[92:95]
	v_mfma_f32_16x16x32_f16 v[88:91], v[140:143], v[210:213], v[88:91]
	v_mfma_f32_16x16x32_f16 v[76:79], v[132:135], v[218:221], v[76:79]
	v_mfma_f32_16x16x32_f16 v[72:75], v[140:143], v[218:221], v[72:75]
	v_mfma_f32_16x16x32_f16 v[116:119], v[144:147], v[190:193], v[116:119]
	v_mfma_f32_16x16x32_f16 v[112:115], v[152:155], v[190:193], v[112:115]
	v_mfma_f32_16x16x32_f16 v[100:103], v[144:147], v[198:201], v[100:103]
	v_mfma_f32_16x16x32_f16 v[96:99], v[152:155], v[198:201], v[96:99]
	v_mfma_f32_16x16x32_f16 v[84:87], v[144:147], v[206:209], v[84:87]
	v_mfma_f32_16x16x32_f16 v[80:83], v[152:155], v[206:209], v[80:83]
	v_mfma_f32_16x16x32_f16 v[68:71], v[144:147], v[214:217], v[68:71]
	v_mfma_f32_16x16x32_f16 v[64:67], v[152:155], v[214:217], v[64:67]
	v_mfma_f32_16x16x32_f16 v[116:119], v[148:151], v[194:197], v[116:119]
	v_mfma_f32_16x16x32_f16 v[112:115], v[174:177], v[194:197], v[112:115]
	v_mfma_f32_16x16x32_f16 v[100:103], v[148:151], v[202:205], v[100:103]
	v_mfma_f32_16x16x32_f16 v[96:99], v[174:177], v[202:205], v[96:99]
	v_mfma_f32_16x16x32_f16 v[84:87], v[148:151], v[210:213], v[84:87]
	v_mfma_f32_16x16x32_f16 v[80:83], v[174:177], v[210:213], v[80:83]
	v_mfma_f32_16x16x32_f16 v[68:71], v[148:151], v[218:221], v[68:71]
	v_mfma_f32_16x16x32_f16 v[64:67], v[174:177], v[218:221], v[64:67]
	s_barrier
	s_add_i32 s45, s90, s68
	v_lshl_add_u64 v[178:179], s[52:53], 0, v[158:159]
	s_mov_b32 m0, s45
	s_nop 0
	global_load_lds_dwordx4 v[178:179], off
	s_add_i32 m0, s45, 0x2000
	s_add_u32 s56, s52, 0x40000
	v_lshl_add_u64 v[222:223], s[52:53], 0, v[162:163]
	s_addc_u32 s57, s53, 0
	s_add_i32 s45, s84, s68
	global_load_lds_dwordx4 v[222:223], off
	v_lshl_add_u64 v[224:225], s[56:57], 0, v[158:159]
	s_mov_b32 m0, s45
	v_lshl_add_u64 v[226:227], s[54:55], 0, v[160:161]
	global_load_lds_dwordx4 v[224:225], off
	v_lshl_add_u64 v[224:225], s[56:57], 0, v[162:163]
	s_add_i32 m0, s45, 0x2000
	s_nop 0
	global_load_lds_dwordx4 v[224:225], off
	v_lshl_add_u64 v[224:225], s[54:55], 0, v[156:157]
	s_mov_b32 m0, s74
	s_nop 0
	global_load_lds_dwordx4 v[224:225], off
	s_mov_b32 m0, s66
	s_nop 0
	global_load_lds_dwordx4 v[226:227], off
	ds_read_b128 v[190:193], v186 offset:16384
	ds_read_b128 v[194:197], v186 offset:17408
	ds_read_b128 v[198:201], v186 offset:18432
	ds_read_b128 v[202:205], v186 offset:19456
	ds_read_b128 v[206:209], v186 offset:20480
	ds_read_b128 v[210:213], v186 offset:21504
	ds_read_b128 v[214:217], v186 offset:22528
	ds_read_b128 v[218:221], v186 offset:23552
	s_waitcnt vmcnt(8)
	s_waitcnt lgkmcnt(0)
	s_barrier
; #define PG8_STAGE(bufoff, gbase, voff) do { _Pragma("unroll") for (int _i = 0; _i < 2; ++_i) \
;         __builtin_amdgcn_global_load_lds((const unsigned*)((const char*)(gbase) + (voff)[_i]), (PG8_LAS unsigned*)(lds + (bufoff) + ldsw + _i * 8192), 16, 0, 0); } while (0)
; #define PG8_LDA(dst, b, h) do { _Pragma("unroll") for (int m = 0; m < 4; ++m) _Pragma("unroll") for (int k = 0; k < 2; ++k) dst[m][k] = *(const PG8_LAS bf16x8*)(lds + PG8_SA(b, h) + aoff + m * 2048 + k * 1024); } while (0)
; #define PG8_LDB(dst, b, h) do { _Pragma("unroll") for (int n = 0; n < 2; ++n) _Pragma("unroll") for (int k = 0; k < 2; ++k) dst[n][k] = *(const PG8_LAS bf16x8*)(lds + PG8_SB(b, h) + boff + n * 2048 + k * 1024); } while (0)
; #define PG8_MMA(ai, bj, At, Bt) do { __builtin_amdgcn_s_setprio(1); _Pragma("unroll") for (int m = 0; m < 4; ++m) _Pragma("unroll") for (int n = 0; n < 2; ++n) _Pragma("unroll") for (int k = 0; k < 2; ++k) \
;         acc[ai][bj][m][n] = mma16<F16>(Bt[n][k], At[m][k], acc[ai][bj][m][n]); __builtin_amdgcn_s_setprio(0); } while (0)
; #define PG8_WAIT_V(n) asm volatile("s_waitcnt vmcnt(" #n ")" ::: "memory")
; #define PG8_WAIT_L(n) asm volatile("s_waitcnt lgkmcnt(" #n ")" ::: "memory")
; #define PG8_BAR __builtin_amdgcn_s_barrier()
; #define PG8_SCHED __builtin_amdgcn_sched_barrier(0)
; template <class Epi, class Sched, bool ALIGN_EPI = false, bool SP2 = false, bool F16 = false>
; __device__ __forceinline__ void gemm_phase(PG8_LAS unsigned char* lds, const Gemm g, const Sched& S, const Epi& E, const int wid_in) {
;     ...
;             PG8_WAIT_V(8); PG8_WAIT_L(0); PG8_BAR; PG8_MMA(1, 0, At, B0); PG8_MMA(1, 1, At, B1); PG8_BAR; PG8_SCHED;
;             PG8_LDB(B0, 1, 0); PG8_LDB(B1, 1, 1); PG8_SCHED; PG8_LDA(At, 1, 0); PG8_STAGE(PG8_SA(0, 1), a2 + hstep, voffA);
;             PG8_WAIT_V(8); PG8_WAIT_L(0); PG8_BAR; PG8_MMA(0, 0, At, B0); PG8_MMA(0, 1, At, B1); PG8_BAR; PG8_SCHED;
	s_waitcnt lgkmcnt(0)
	v_mfma_f32_16x16x32_f16 v[60:63], v[128:131], v[190:193], v[60:63]
	v_mfma_f32_16x16x32_f16 v[56:59], v[136:139], v[190:193], v[56:59]
	v_mfma_f32_16x16x32_f16 v[44:47], v[128:131], v[198:201], v[44:47]
	v_mfma_f32_16x16x32_f16 v[40:43], v[136:139], v[198:201], v[40:43]
	v_mfma_f32_16x16x32_f16 v[28:31], v[128:131], v[206:209], v[28:31]
	v_mfma_f32_16x16x32_f16 v[24:27], v[136:139], v[206:209], v[24:27]
	v_mfma_f32_16x16x32_f16 v[12:15], v[128:131], v[214:217], v[12:15]
	v_mfma_f32_16x16x32_f16 v[8:11], v[136:139], v[214:217], v[8:11]
	v_mfma_f32_16x16x32_f16 v[60:63], v[132:135], v[194:197], v[60:63]
	v_mfma_f32_16x16x32_f16 v[56:59], v[140:143], v[194:197], v[56:59]
	v_mfma_f32_16x16x32_f16 v[44:47], v[132:135], v[202:205], v[44:47]
	v_mfma_f32_16x16x32_f16 v[40:43], v[140:143], v[202:205], v[40:43]
	v_mfma_f32_16x16x32_f16 v[28:31], v[132:135], v[210:213], v[28:31]
	v_mfma_f32_16x16x32_f16 v[24:27], v[140:143], v[210:213], v[24:27]
	v_mfma_f32_16x16x32_f16 v[12:15], v[132:135], v[218:221], v[12:15]
	v_mfma_f32_16x16x32_f16 v[8:11], v[140:143], v[218:221], v[8:11]
	v_mfma_f32_16x16x32_f16 v[52:55], v[144:147], v[190:193], v[52:55]
	v_mfma_f32_16x16x32_f16 v[48:51], v[152:155], v[190:193], v[48:51]
	v_mfma_f32_16x16x32_f16 v[36:39], v[144:147], v[198:201], v[36:39]
	v_mfma_f32_16x16x32_f16 v[32:35], v[152:155], v[198:201], v[32:35]
	v_mfma_f32_16x16x32_f16 v[20:23], v[144:147], v[206:209], v[20:23]
	v_mfma_f32_16x16x32_f16 v[16:19], v[152:155], v[206:209], v[16:19]
	v_mfma_f32_16x16x32_f16 v[4:7], v[144:147], v[214:217], v[4:7]
	v_mfma_f32_16x16x32_f16 v[0:3], v[152:155], v[214:217], v[0:3]
	v_mfma_f32_16x16x32_f16 v[52:55], v[148:151], v[194:197], v[52:55]
	v_mfma_f32_16x16x32_f16 v[48:51], v[174:177], v[194:197], v[48:51]
	v_mfma_f32_16x16x32_f16 v[36:39], v[148:151], v[202:205], v[36:39]
	v_mfma_f32_16x16x32_f16 v[32:35], v[174:177], v[202:205], v[32:35]
	v_mfma_f32_16x16x32_f16 v[20:23], v[148:151], v[210:213], v[20:23]
	v_mfma_f32_16x16x32_f16 v[16:19], v[174:177], v[210:213], v[16:19]
	v_mfma_f32_16x16x32_f16 v[4:7], v[148:151], v[218:221], v[4:7]
	v_mfma_f32_16x16x32_f16 v[0:3], v[174:177], v[218:221], v[0:3]
	s_barrier
	s_add_i32 s45, 0, 0x18000
	s_add_i32 s56, 0, 0x1c000
	v_add_u32_e32 v140, s45, v183
	v_add_u32_e32 v165, s56, v183
	s_add_u32 s54, s54, 0x40000
	s_addc_u32 s55, s55, 0
	s_mov_b32 m0, s67
	v_lshl_add_u64 v[228:229], s[54:55], 0, v[156:157]
	global_load_lds_dwordx4 v[228:229], off
	v_lshl_add_u64 v[228:229], s[54:55], 0, v[160:161]
	s_mov_b32 m0, s91
	s_nop 0
	global_load_lds_dwordx4 v[228:229], off
	ds_read_b128 v[128:131], v140
	ds_read_b128 v[132:135], v140 offset:1024
	ds_read_b128 v[136:139], v140 offset:2048
	ds_read_b128 v[140:143], v140 offset:3072
	ds_read_b128 v[144:147], v165
	ds_read_b128 v[148:151], v165 offset:1024
	ds_read_b128 v[152:155], v165 offset:2048
	ds_read_b128 v[174:177], v165 offset:3072
	ds_read_b128 v[190:193], v186 offset:32768
	ds_read_b128 v[194:197], v186 offset:33792
	ds_read_b128 v[198:201], v186 offset:34816
	ds_read_b128 v[202:205], v186 offset:35840
	ds_read_b128 v[206:209], v186 offset:36864
	ds_read_b128 v[210:213], v186 offset:37888
	ds_read_b128 v[214:217], v186 offset:38912
	ds_read_b128 v[218:221], v186 offset:39936
	s_waitcnt vmcnt(8)
	s_waitcnt lgkmcnt(0)
	s_barrier
	s_waitcnt lgkmcnt(0)
	v_mfma_f32_16x16x32_f16 v[124:127], v[128:131], v[190:193], v[124:127]
	v_mfma_f32_16x16x32_f16 v[120:123], v[136:139], v[190:193], v[120:123]
	v_mfma_f32_16x16x32_f16 v[108:111], v[128:131], v[198:201], v[108:111]
	v_mfma_f32_16x16x32_f16 v[104:107], v[136:139], v[198:201], v[104:107]
	v_mfma_f32_16x16x32_f16 v[92:95], v[128:131], v[206:209], v[92:95]
	v_mfma_f32_16x16x32_f16 v[88:91], v[136:139], v[206:209], v[88:91]
	v_mfma_f32_16x16x32_f16 v[76:79], v[128:131], v[214:217], v[76:79]
	v_mfma_f32_16x16x32_f16 v[72:75], v[136:139], v[214:217], v[72:75]
	v_mfma_f32_16x16x32_f16 v[124:127], v[132:135], v[194:197], v[124:127]
	v_mfma_f32_16x16x32_f16 v[120:123], v[140:143], v[194:197], v[120:123]
	v_mfma_f32_16x16x32_f16 v[108:111], v[132:135], v[202:205], v[108:111]
	v_mfma_f32_16x16x32_f16 v[104:107], v[140:143], v[202:205], v[104:107]
	v_mfma_f32_16x16x32_f16 v[92:95], v[132:135], v[210:213], v[92:95]
	v_mfma_f32_16x16x32_f16 v[88:91], v[140:143], v[210:213], v[88:91]
	v_mfma_f32_16x16x32_f16 v[76:79], v[132:135], v[218:221], v[76:79]
	v_mfma_f32_16x16x32_f16 v[72:75], v[140:143], v[218:221], v[72:75]
	v_mfma_f32_16x16x32_f16 v[116:119], v[144:147], v[190:193], v[116:119]
	v_mfma_f32_16x16x32_f16 v[112:115], v[152:155], v[190:193], v[112:115]
	v_mfma_f32_16x16x32_f16 v[100:103], v[144:147], v[198:201], v[100:103]
	v_mfma_f32_16x16x32_f16 v[96:99], v[152:155], v[198:201], v[96:99]
	v_mfma_f32_16x16x32_f16 v[84:87], v[144:147], v[206:209], v[84:87]
	v_mfma_f32_16x16x32_f16 v[80:83], v[152:155], v[206:209], v[80:83]
	v_mfma_f32_16x16x32_f16 v[68:71], v[144:147], v[214:217], v[68:71]
	v_mfma_f32_16x16x32_f16 v[64:67], v[152:155], v[214:217], v[64:67]
	v_mfma_f32_16x16x32_f16 v[116:119], v[148:151], v[194:197], v[116:119]
	v_mfma_f32_16x16x32_f16 v[112:115], v[174:177], v[194:197], v[112:115]
	v_mfma_f32_16x16x32_f16 v[100:103], v[148:151], v[202:205], v[100:103]
	v_mfma_f32_16x16x32_f16 v[96:99], v[174:177], v[202:205], v[96:99]
	v_mfma_f32_16x16x32_f16 v[84:87], v[148:151], v[210:213], v[84:87]
	v_mfma_f32_16x16x32_f16 v[80:83], v[174:177], v[210:213], v[80:83]
	v_mfma_f32_16x16x32_f16 v[68:71], v[148:151], v[218:221], v[68:71]
	v_mfma_f32_16x16x32_f16 v[64:67], v[174:177], v[218:221], v[64:67]
	s_barrier
; #define PG8_STAGE(bufoff, gbase, voff) do { _Pragma("unroll") for (int _i = 0; _i < 2; ++_i) \
;         __builtin_amdgcn_global_load_lds((const unsigned*)((const char*)(gbase) + (voff)[_i]), (PG8_LAS unsigned*)(lds + (bufoff) + ldsw + _i * 8192), 16, 0, 0); } while (0)
; #define PG8_LDA(dst, b, h) do { _Pragma("unroll") for (int m = 0; m < 4; ++m) _Pragma("unroll") for (int k = 0; k < 2; ++k) dst[m][k] = *(const PG8_LAS bf16x8*)(lds + PG8_SA(b, h) + aoff + m * 2048 + k * 1024); } while (0)
; #define PG8_MMA(ai, bj, At, Bt) do { __builtin_amdgcn_s_setprio(1); _Pragma("unroll") for (int m = 0; m < 4; ++m) _Pragma("unroll") for (int n = 0; n < 2; ++n) _Pragma("unroll") for (int k = 0; k < 2; ++k) \
;         acc[ai][bj][m][n] = mma16<F16>(Bt[n][k], At[m][k], acc[ai][bj][m][n]); __builtin_amdgcn_s_setprio(0); } while (0)
; #define PG8_WAIT_V(n) asm volatile("s_waitcnt vmcnt(" #n ")" ::: "memory")
; #define PG8_WAIT_L(n) asm volatile("s_waitcnt lgkmcnt(" #n ")" ::: "memory")
; #define PG8_BAR __builtin_amdgcn_s_barrier()
; #define PG8_SCHED __builtin_amdgcn_sched_barrier(0)
; template <class Epi, class Sched, bool ALIGN_EPI = false, bool SP2 = false, bool F16 = false>
; __device__ __forceinline__ void gemm_phase(PG8_LAS unsigned char* lds, const Gemm g, const Sched& S, const Epi& E, const int wid_in) {
;     ...
;             PG8_LDA(At, 1, 1); PG8_STAGE(PG8_SB(1, 0), b3, voffB); PG8_STAGE(PG8_SB(1, 1), b3 + hstep, voffB); PG8_STAGE(PG8_SA(1, 0), a3, voffA);
;             PG8_WAIT_V(8); PG8_WAIT_L(0); PG8_BAR; PG8_MMA(1, 0, At, B0); PG8_MMA(1, 1, At, B1); PG8_BAR; PG8_SCHED;
	s_add_i32 s45, s45, s68
	v_lshl_add_u64 v[178:179], v[178:179], 0, s[34:35]
	s_mov_b32 m0, s45
	s_nop 0
	global_load_lds_dwordx4 v[178:179], off
	s_add_i32 m0, s45, 0x2000
	s_add_u32 s52, s52, 0x40080
	v_lshl_add_u64 v[178:179], v[222:223], 0, s[34:35]
	s_addc_u32 s53, s53, 0
	s_add_i32 s45, s56, s68
	global_load_lds_dwordx4 v[178:179], off
	v_lshl_add_u64 v[178:179], s[52:53], 0, v[158:159]
	s_mov_b32 m0, s45
	s_nop 0
	global_load_lds_dwordx4 v[178:179], off
	v_lshl_add_u64 v[178:179], s[52:53], 0, v[162:163]
	s_add_i32 m0, s45, 0x2000
	s_nop 0
	global_load_lds_dwordx4 v[178:179], off
	v_lshl_add_u64 v[178:179], v[224:225], 0, s[34:35]
	s_mov_b32 m0, s75
	s_nop 0
	global_load_lds_dwordx4 v[178:179], off
	v_lshl_add_u64 v[178:179], v[226:227], 0, s[34:35]
	s_mov_b32 m0, s97
	s_nop 0
	global_load_lds_dwordx4 v[178:179], off
	ds_read_b128 v[190:193], v186 offset:49152
	ds_read_b128 v[194:197], v186 offset:50176
	ds_read_b128 v[198:201], v186 offset:51200
	ds_read_b128 v[202:205], v186 offset:52224
	ds_read_b128 v[206:209], v186 offset:53248
	ds_read_b128 v[210:213], v186 offset:54272
	ds_read_b128 v[214:217], v186 offset:55296
	ds_read_b128 v[218:221], v186 offset:56320
	s_waitcnt vmcnt(8)
	s_waitcnt lgkmcnt(0)
	s_barrier
	s_waitcnt lgkmcnt(0)
	v_mfma_f32_16x16x32_f16 v[60:63], v[128:131], v[190:193], v[60:63]
	v_mfma_f32_16x16x32_f16 v[56:59], v[136:139], v[190:193], v[56:59]
	v_mfma_f32_16x16x32_f16 v[44:47], v[128:131], v[198:201], v[44:47]
	v_mfma_f32_16x16x32_f16 v[40:43], v[136:139], v[198:201], v[40:43]
	v_mfma_f32_16x16x32_f16 v[28:31], v[128:131], v[206:209], v[28:31]
	v_mfma_f32_16x16x32_f16 v[24:27], v[136:139], v[206:209], v[24:27]
	v_mfma_f32_16x16x32_f16 v[12:15], v[128:131], v[214:217], v[12:15]
	v_mfma_f32_16x16x32_f16 v[8:11], v[136:139], v[214:217], v[8:11]
	v_mfma_f32_16x16x32_f16 v[60:63], v[132:135], v[194:197], v[60:63]
	v_mfma_f32_16x16x32_f16 v[56:59], v[140:143], v[194:197], v[56:59]
	v_mfma_f32_16x16x32_f16 v[44:47], v[132:135], v[202:205], v[44:47]
	v_mfma_f32_16x16x32_f16 v[40:43], v[140:143], v[202:205], v[40:43]
	v_mfma_f32_16x16x32_f16 v[28:31], v[132:135], v[210:213], v[28:31]
	v_mfma_f32_16x16x32_f16 v[24:27], v[140:143], v[210:213], v[24:27]
	v_mfma_f32_16x16x32_f16 v[12:15], v[132:135], v[218:221], v[12:15]
	v_mfma_f32_16x16x32_f16 v[8:11], v[140:143], v[218:221], v[8:11]
	v_mfma_f32_16x16x32_f16 v[52:55], v[144:147], v[190:193], v[52:55]
	v_mfma_f32_16x16x32_f16 v[48:51], v[152:155], v[190:193], v[48:51]
	v_mfma_f32_16x16x32_f16 v[36:39], v[144:147], v[198:201], v[36:39]
	v_mfma_f32_16x16x32_f16 v[32:35], v[152:155], v[198:201], v[32:35]
	v_mfma_f32_16x16x32_f16 v[20:23], v[144:147], v[206:209], v[20:23]
	v_mfma_f32_16x16x32_f16 v[16:19], v[152:155], v[206:209], v[16:19]
	v_mfma_f32_16x16x32_f16 v[4:7], v[144:147], v[214:217], v[4:7]
	v_mfma_f32_16x16x32_f16 v[0:3], v[152:155], v[214:217], v[0:3]
	v_mfma_f32_16x16x32_f16 v[52:55], v[148:151], v[194:197], v[52:55]
	v_mfma_f32_16x16x32_f16 v[48:51], v[174:177], v[194:197], v[48:51]
	v_mfma_f32_16x16x32_f16 v[36:39], v[148:151], v[202:205], v[36:39]
	v_mfma_f32_16x16x32_f16 v[32:35], v[174:177], v[202:205], v[32:35]
	v_mfma_f32_16x16x32_f16 v[20:23], v[148:151], v[210:213], v[20:23]
	v_mfma_f32_16x16x32_f16 v[16:19], v[174:177], v[210:213], v[16:19]
	v_mfma_f32_16x16x32_f16 v[4:7], v[148:151], v[218:221], v[4:7]
	v_mfma_f32_16x16x32_f16 v[0:3], v[174:177], v[218:221], v[0:3]
	s_barrier
	s_add_i32 s43, s43, 2
	s_add_u32 s50, s50, 0x100
	s_addc_u32 s51, s51, 0
	s_add_u32 s41, s41, 0x100
	s_addc_u32 s42, s42, 0
	s_cmp_gt_u32 s43, 13
	s_cbranch_scc0 .LBB0_1548
	s_and_b64 vcc, exec, s[16:17]
	s_cbranch_vccz .LBB0_1551
	s_barrier

; #define PG8_STAGE(bufoff, gbase, voff) do { _Pragma("unroll") for (int _i = 0; _i < 2; ++_i) \
;         __builtin_amdgcn_global_load_lds((const unsigned*)((const char*)(gbase) + (voff)[_i]), (PG8_LAS unsigned*)(lds + (bufoff) + ldsw + _i * 8192), 16, 0, 0); } while (0)
; #define PG8_LDA(dst, b, h) do { _Pragma("unroll") for (int m = 0; m < 4; ++m) _Pragma("unroll") for (int k = 0; k < 2; ++k) dst[m][k] = *(const PG8_LAS bf16x8*)(lds + PG8_SA(b, h) + aoff + m * 2048 + k * 1024); } while (0)
; #define PG8_LDB(dst, b, h) do { _Pragma("unroll") for (int n = 0; n < 2; ++n) _Pragma("unroll") for (int k = 0; k < 2; ++k) dst[n][k] = *(const PG8_LAS bf16x8*)(lds + PG8_SB(b, h) + boff + n * 2048 + k * 1024); } while (0)
; #define PG8_MMA(ai, bj, At, Bt) do { __builtin_amdgcn_s_setprio(1); _Pragma("unroll") for (int m = 0; m < 4; ++m) _Pragma("unroll") for (int n = 0; n < 2; ++n) _Pragma("unroll") for (int k = 0; k < 2; ++k) \
;         acc[ai][bj][m][n] = mma16<F16>(Bt[n][k], At[m][k], acc[ai][bj][m][n]); __builtin_amdgcn_s_setprio(0); } while (0)
; #define PG8_WAIT_V(n) asm volatile("s_waitcnt vmcnt(" #n ")" ::: "memory")
; #define PG8_BAR __builtin_amdgcn_s_barrier()
; template <class Epi, class Sched, bool ALIGN_EPI = false, bool SP2 = false, bool F16 = false>
; __device__ __forceinline__ void gemm_phase(PG8_LAS unsigned char* lds, const Gemm g, const Sched& S, const Epi& E, const int wid_in) {
;     ...
;         for (int t = 0; t < nt; t += 2) {
;             const bool last = (t == nt - 2);
;             const char* a1 = cA + (size_t)(t + 1) * kstep;
;             const char* a2 = last ? nA : cA + (size_t)(t + 2) * kstep; const char* b2 = last ? nB : cB + (size_t)(t + 2) * kstep;
;             const char* a3 = a2 + kstep; const char* b3 = b2 + kstep;
;             if (last && has_next) S.a_ready(nxt);
;             if constexpr (SP2) {
;             PG8_LDB(B0, 0, 0); PG8_LDB(B1, 0, 1); PG8_SCHED; PG8_LDA(At, 0, 0); PG8_STAGE(PG8_SA(1, 1), a1 + hstep, voffA);
;             PG8_WAIT_V(8); PG8_WAIT_L(0); PG8_BAR; PG8_MMA(0, 0, At, B0); PG8_MMA(0, 1, At, B1); PG8_BAR; PG8_SCHED;
;             PG8_LDA(At, 0, 1); PG8_STAGE(PG8_SB(0, 0), b2, voffB); PG8_STAGE(PG8_SB(0, 1), b2 + hstep, voffB); PG8_STAGE(PG8_SA(0, 0), a2, voffA);
;             PG8_WAIT_V(8); PG8_WAIT_L(0); PG8_BAR; PG8_MMA(1, 0, At, B0); PG8_MMA(1, 1, At, B1); PG8_BAR; PG8_SCHED;
.LBB0_1832:
	ds_read_b128 v[128:131], v189
	ds_read_b128 v[132:135], v189 offset:1024
	ds_read_b128 v[136:139], v189 offset:2048
	ds_read_b128 v[140:143], v189 offset:3072
	ds_read_b128 v[144:147], v190
	ds_read_b128 v[148:151], v190 offset:1024
	ds_read_b128 v[168:171], v190 offset:2048
	ds_read_b128 v[172:175], v190 offset:3072
	s_add_u32 s50, s48, 0xfffc0080
	s_addc_u32 s51, s49, -1
	s_cmp_eq_u32 s61, 12
	s_cselect_b32 s53, s35, s51
	s_cselect_b32 s52, s42, s50
	s_cselect_b32 s51, s31, s60
	s_cselect_b32 s50, s43, s47
	s_mov_b32 m0, s91
	v_lshl_add_u64 v[184:185], s[48:49], 0, v[160:161]
	ds_read_b128 v[176:179], v191
	ds_read_b128 v[180:183], v191 offset:1024
	ds_read_b128 v[192:195], v191 offset:2048
	ds_read_b128 v[196:199], v191 offset:3072
	ds_read_b128 v[200:203], v191 offset:4096
	ds_read_b128 v[204:207], v191 offset:5120
	ds_read_b128 v[208:211], v191 offset:6144
	ds_read_b128 v[212:215], v191 offset:7168
	global_load_lds_dwordx4 v[184:185], off
	v_lshl_add_u64 v[184:185], s[48:49], 0, v[162:163]
	s_add_i32 m0, s74, 0xe000
	s_nop 0
	global_load_lds_dwordx4 v[184:185], off
	s_waitcnt vmcnt(8)
	s_waitcnt lgkmcnt(0)
	s_barrier
	s_waitcnt lgkmcnt(0)
	v_mfma_f32_16x16x32_bf16 v[124:127], v[128:131], v[176:179], v[124:127]
	v_mfma_f32_16x16x32_bf16 v[120:123], v[136:139], v[176:179], v[120:123]
	v_mfma_f32_16x16x32_bf16 v[108:111], v[128:131], v[192:195], v[108:111]
	v_mfma_f32_16x16x32_bf16 v[104:107], v[136:139], v[192:195], v[104:107]
	v_mfma_f32_16x16x32_bf16 v[92:95], v[128:131], v[200:203], v[92:95]
	v_mfma_f32_16x16x32_bf16 v[88:91], v[136:139], v[200:203], v[88:91]
	v_mfma_f32_16x16x32_bf16 v[76:79], v[128:131], v[208:211], v[76:79]
	v_mfma_f32_16x16x32_bf16 v[72:75], v[136:139], v[208:211], v[72:75]
	v_mfma_f32_16x16x32_bf16 v[124:127], v[132:135], v[180:183], v[124:127]
	v_mfma_f32_16x16x32_bf16 v[120:123], v[140:143], v[180:183], v[120:123]
	v_mfma_f32_16x16x32_bf16 v[108:111], v[132:135], v[196:199], v[108:111]
	v_mfma_f32_16x16x32_bf16 v[104:107], v[140:143], v[196:199], v[104:107]
	v_mfma_f32_16x16x32_bf16 v[92:95], v[132:135], v[204:207], v[92:95]
	v_mfma_f32_16x16x32_bf16 v[88:91], v[140:143], v[204:207], v[88:91]
	v_mfma_f32_16x16x32_bf16 v[76:79], v[132:135], v[212:215], v[76:79]
	v_mfma_f32_16x16x32_bf16 v[72:75], v[140:143], v[212:215], v[72:75]
	v_mfma_f32_16x16x32_bf16 v[116:119], v[144:147], v[176:179], v[116:119]
	v_mfma_f32_16x16x32_bf16 v[112:115], v[168:171], v[176:179], v[112:115]
	v_mfma_f32_16x16x32_bf16 v[100:103], v[144:147], v[192:195], v[100:103]
	v_mfma_f32_16x16x32_bf16 v[96:99], v[168:171], v[192:195], v[96:99]
	v_mfma_f32_16x16x32_bf16 v[84:87], v[144:147], v[200:203], v[84:87]
	v_mfma_f32_16x16x32_bf16 v[80:83], v[168:171], v[200:203], v[80:83]
	v_mfma_f32_16x16x32_bf16 v[68:71], v[144:147], v[208:211], v[68:71]
	v_mfma_f32_16x16x32_bf16 v[64:67], v[168:171], v[208:211], v[64:67]
	v_mfma_f32_16x16x32_bf16 v[116:119], v[148:151], v[180:183], v[116:119]
	v_mfma_f32_16x16x32_bf16 v[112:115], v[172:175], v[180:183], v[112:115]
	v_mfma_f32_16x16x32_bf16 v[100:103], v[148:151], v[196:199], v[100:103]
	v_mfma_f32_16x16x32_bf16 v[96:99], v[172:175], v[196:199], v[96:99]
	v_mfma_f32_16x16x32_bf16 v[84:87], v[148:151], v[204:207], v[84:87]
	v_mfma_f32_16x16x32_bf16 v[80:83], v[172:175], v[204:207], v[80:83]
	v_mfma_f32_16x16x32_bf16 v[68:71], v[148:151], v[212:215], v[68:71]
	v_mfma_f32_16x16x32_bf16 v[64:67], v[172:175], v[212:215], v[64:67]
	s_barrier
	s_add_i32 s62, s57, s68
	v_lshl_add_u64 v[184:185], s[50:51], 0, v[154:155]
	s_mov_b32 m0, s62
	s_nop 0
	global_load_lds_dwordx4 v[184:185], off
	s_add_i32 m0, s62, 0x2000
	s_add_u32 s62, s50, 0x40000
	v_lshl_add_u64 v[216:217], s[50:51], 0, v[158:159]
	s_addc_u32 s63, s51, 0
	s_add_i32 s64, s58, s68
	global_load_lds_dwordx4 v[216:217], off
	v_lshl_add_u64 v[218:219], s[62:63], 0, v[154:155]
	s_mov_b32 m0, s64
	v_lshl_add_u64 v[220:221], s[52:53], 0, v[156:157]
	global_load_lds_dwordx4 v[218:219], off
	v_lshl_add_u64 v[218:219], s[62:63], 0, v[158:159]
	s_add_i32 m0, s64, 0x2000
	s_nop 0
	global_load_lds_dwordx4 v[218:219], off
	v_lshl_add_u64 v[218:219], s[52:53], 0, v[152:153]
	s_mov_b32 m0, s74
	s_nop 0
	global_load_lds_dwordx4 v[218:219], off
	s_mov_b32 m0, s66
	s_nop 0
	global_load_lds_dwordx4 v[220:221], off
	ds_read_b128 v[176:179], v191 offset:16384
	ds_read_b128 v[180:183], v191 offset:17408
	ds_read_b128 v[192:195], v191 offset:18432
	ds_read_b128 v[196:199], v191 offset:19456
	ds_read_b128 v[200:203], v191 offset:20480
	ds_read_b128 v[204:207], v191 offset:21504
	ds_read_b128 v[208:211], v191 offset:22528
	ds_read_b128 v[212:215], v191 offset:23552
	s_waitcnt vmcnt(8)
	s_waitcnt lgkmcnt(0)
	s_barrier
; #define PG8_STAGE(bufoff, gbase, voff) do { _Pragma("unroll") for (int _i = 0; _i < 2; ++_i) \
;         __builtin_amdgcn_global_load_lds((const unsigned*)((const char*)(gbase) + (voff)[_i]), (PG8_LAS unsigned*)(lds + (bufoff) + ldsw + _i * 8192), 16, 0, 0); } while (0)
; #define PG8_LDA(dst, b, h) do { _Pragma("unroll") for (int m = 0; m < 4; ++m) _Pragma("unroll") for (int k = 0; k < 2; ++k) dst[m][k] = *(const PG8_LAS bf16x8*)(lds + PG8_SA(b, h) + aoff + m * 2048 + k * 1024); } while (0)
; #define PG8_LDB(dst, b, h) do { _Pragma("unroll") for (int n = 0; n < 2; ++n) _Pragma("unroll") for (int k = 0; k < 2; ++k) dst[n][k] = *(const PG8_LAS bf16x8*)(lds + PG8_SB(b, h) + boff + n * 2048 + k * 1024); } while (0)
; #define PG8_MMA(ai, bj, At, Bt) do { __builtin_amdgcn_s_setprio(1); _Pragma("unroll") for (int m = 0; m < 4; ++m) _Pragma("unroll") for (int n = 0; n < 2; ++n) _Pragma("unroll") for (int k = 0; k < 2; ++k) \
;         acc[ai][bj][m][n] = mma16<F16>(Bt[n][k], At[m][k], acc[ai][bj][m][n]); __builtin_amdgcn_s_setprio(0); } while (0)
; #define PG8_WAIT_V(n) asm volatile("s_waitcnt vmcnt(" #n ")" ::: "memory")
; #define PG8_WAIT_L(n) asm volatile("s_waitcnt lgkmcnt(" #n ")" ::: "memory")
; #define PG8_BAR __builtin_amdgcn_s_barrier()
; #define PG8_SCHED __builtin_amdgcn_sched_barrier(0)
; template <class Epi, class Sched, bool ALIGN_EPI = false, bool SP2 = false, bool F16 = false>
; __device__ __forceinline__ void gemm_phase(PG8_LAS unsigned char* lds, const Gemm g, const Sched& S, const Epi& E, const int wid_in) {
;     ...
;             PG8_WAIT_V(8); PG8_WAIT_L(0); PG8_BAR; PG8_MMA(1, 0, At, B0); PG8_MMA(1, 1, At, B1); PG8_BAR; PG8_SCHED;
;             PG8_LDB(B0, 1, 0); PG8_LDB(B1, 1, 1); PG8_SCHED; PG8_LDA(At, 1, 0); PG8_STAGE(PG8_SA(0, 1), a2 + hstep, voffA);
;             PG8_WAIT_V(8); PG8_WAIT_L(0); PG8_BAR; PG8_MMA(0, 0, At, B0); PG8_MMA(0, 1, At, B1); PG8_BAR; PG8_SCHED;
	s_waitcnt lgkmcnt(0)
	v_mfma_f32_16x16x32_bf16 v[60:63], v[128:131], v[176:179], v[60:63]
	v_mfma_f32_16x16x32_bf16 v[56:59], v[136:139], v[176:179], v[56:59]
	v_mfma_f32_16x16x32_bf16 v[44:47], v[128:131], v[192:195], v[44:47]
	v_mfma_f32_16x16x32_bf16 v[40:43], v[136:139], v[192:195], v[40:43]
	v_mfma_f32_16x16x32_bf16 v[28:31], v[128:131], v[200:203], v[28:31]
	v_mfma_f32_16x16x32_bf16 v[24:27], v[136:139], v[200:203], v[24:27]
	v_mfma_f32_16x16x32_bf16 v[12:15], v[128:131], v[208:211], v[12:15]
	v_mfma_f32_16x16x32_bf16 v[8:11], v[136:139], v[208:211], v[8:11]
	v_mfma_f32_16x16x32_bf16 v[60:63], v[132:135], v[180:183], v[60:63]
	v_mfma_f32_16x16x32_bf16 v[56:59], v[140:143], v[180:183], v[56:59]
	v_mfma_f32_16x16x32_bf16 v[44:47], v[132:135], v[196:199], v[44:47]
	v_mfma_f32_16x16x32_bf16 v[40:43], v[140:143], v[196:199], v[40:43]
	v_mfma_f32_16x16x32_bf16 v[28:31], v[132:135], v[204:207], v[28:31]
	v_mfma_f32_16x16x32_bf16 v[24:27], v[140:143], v[204:207], v[24:27]
	v_mfma_f32_16x16x32_bf16 v[12:15], v[132:135], v[212:215], v[12:15]
	v_mfma_f32_16x16x32_bf16 v[8:11], v[140:143], v[212:215], v[8:11]
	v_mfma_f32_16x16x32_bf16 v[52:55], v[144:147], v[176:179], v[52:55]
	v_mfma_f32_16x16x32_bf16 v[48:51], v[168:171], v[176:179], v[48:51]
	v_mfma_f32_16x16x32_bf16 v[36:39], v[144:147], v[192:195], v[36:39]
	v_mfma_f32_16x16x32_bf16 v[32:35], v[168:171], v[192:195], v[32:35]
	v_mfma_f32_16x16x32_bf16 v[20:23], v[144:147], v[200:203], v[20:23]
	v_mfma_f32_16x16x32_bf16 v[16:19], v[168:171], v[200:203], v[16:19]
	v_mfma_f32_16x16x32_bf16 v[4:7], v[144:147], v[208:211], v[4:7]
	v_mfma_f32_16x16x32_bf16 v[0:3], v[168:171], v[208:211], v[0:3]
	v_mfma_f32_16x16x32_bf16 v[52:55], v[148:151], v[180:183], v[52:55]
	v_mfma_f32_16x16x32_bf16 v[48:51], v[172:175], v[180:183], v[48:51]
	v_mfma_f32_16x16x32_bf16 v[36:39], v[148:151], v[196:199], v[36:39]
	v_mfma_f32_16x16x32_bf16 v[32:35], v[172:175], v[196:199], v[32:35]
	v_mfma_f32_16x16x32_bf16 v[20:23], v[148:151], v[204:207], v[20:23]
	v_mfma_f32_16x16x32_bf16 v[16:19], v[172:175], v[204:207], v[16:19]
	v_mfma_f32_16x16x32_bf16 v[4:7], v[148:151], v[212:215], v[4:7]
	v_mfma_f32_16x16x32_bf16 v[0:3], v[172:175], v[212:215], v[0:3]
	s_barrier
	s_add_i32 s62, 0, 0x18000
	s_add_i32 s63, 0, 0x1c000
	v_add_u32_e32 v140, s62, v188
	v_add_u32_e32 v172, s63, v188
	s_add_u32 s52, s52, 0x40000
	s_addc_u32 s53, s53, 0
	s_mov_b32 m0, s90
	v_lshl_add_u64 v[222:223], s[52:53], 0, v[152:153]
	global_load_lds_dwordx4 v[222:223], off
	v_lshl_add_u64 v[222:223], s[52:53], 0, v[156:157]
	s_mov_b32 m0, s41
	s_nop 0
	global_load_lds_dwordx4 v[222:223], off
	ds_read_b128 v[128:131], v140
	ds_read_b128 v[132:135], v140 offset:1024
	ds_read_b128 v[136:139], v140 offset:2048
	ds_read_b128 v[140:143], v140 offset:3072
	ds_read_b128 v[144:147], v172
	ds_read_b128 v[148:151], v172 offset:1024
	ds_read_b128 v[168:171], v172 offset:2048
	ds_read_b128 v[172:175], v172 offset:3072
	ds_read_b128 v[176:179], v191 offset:32768
	ds_read_b128 v[180:183], v191 offset:33792
	ds_read_b128 v[192:195], v191 offset:34816
	ds_read_b128 v[196:199], v191 offset:35840
	ds_read_b128 v[200:203], v191 offset:36864
	ds_read_b128 v[204:207], v191 offset:37888
	ds_read_b128 v[208:211], v191 offset:38912
	ds_read_b128 v[212:215], v191 offset:39936
	s_waitcnt vmcnt(8)
	s_waitcnt lgkmcnt(0)
	s_barrier
	s_waitcnt lgkmcnt(0)
	v_mfma_f32_16x16x32_bf16 v[124:127], v[128:131], v[176:179], v[124:127]
	v_mfma_f32_16x16x32_bf16 v[120:123], v[136:139], v[176:179], v[120:123]
	v_mfma_f32_16x16x32_bf16 v[108:111], v[128:131], v[192:195], v[108:111]
	v_mfma_f32_16x16x32_bf16 v[104:107], v[136:139], v[192:195], v[104:107]
	v_mfma_f32_16x16x32_bf16 v[92:95], v[128:131], v[200:203], v[92:95]
	v_mfma_f32_16x16x32_bf16 v[88:91], v[136:139], v[200:203], v[88:91]
	v_mfma_f32_16x16x32_bf16 v[76:79], v[128:131], v[208:211], v[76:79]
	v_mfma_f32_16x16x32_bf16 v[72:75], v[136:139], v[208:211], v[72:75]
	v_mfma_f32_16x16x32_bf16 v[124:127], v[132:135], v[180:183], v[124:127]
	v_mfma_f32_16x16x32_bf16 v[120:123], v[140:143], v[180:183], v[120:123]
	v_mfma_f32_16x16x32_bf16 v[108:111], v[132:135], v[196:199], v[108:111]
	v_mfma_f32_16x16x32_bf16 v[104:107], v[140:143], v[196:199], v[104:107]
	v_mfma_f32_16x16x32_bf16 v[92:95], v[132:135], v[204:207], v[92:95]
	v_mfma_f32_16x16x32_bf16 v[88:91], v[140:143], v[204:207], v[88:91]
	v_mfma_f32_16x16x32_bf16 v[76:79], v[132:135], v[212:215], v[76:79]
	v_mfma_f32_16x16x32_bf16 v[72:75], v[140:143], v[212:215], v[72:75]
	v_mfma_f32_16x16x32_bf16 v[116:119], v[144:147], v[176:179], v[116:119]
	v_mfma_f32_16x16x32_bf16 v[112:115], v[168:171], v[176:179], v[112:115]
	v_mfma_f32_16x16x32_bf16 v[100:103], v[144:147], v[192:195], v[100:103]
	v_mfma_f32_16x16x32_bf16 v[96:99], v[168:171], v[192:195], v[96:99]
	v_mfma_f32_16x16x32_bf16 v[84:87], v[144:147], v[200:203], v[84:87]
	v_mfma_f32_16x16x32_bf16 v[80:83], v[168:171], v[200:203], v[80:83]
	v_mfma_f32_16x16x32_bf16 v[68:71], v[144:147], v[208:211], v[68:71]
	v_mfma_f32_16x16x32_bf16 v[64:67], v[168:171], v[208:211], v[64:67]
	v_mfma_f32_16x16x32_bf16 v[116:119], v[148:151], v[180:183], v[116:119]
	v_mfma_f32_16x16x32_bf16 v[112:115], v[172:175], v[180:183], v[112:115]
	v_mfma_f32_16x16x32_bf16 v[100:103], v[148:151], v[196:199], v[100:103]
	v_mfma_f32_16x16x32_bf16 v[96:99], v[172:175], v[196:199], v[96:99]
	v_mfma_f32_16x16x32_bf16 v[84:87], v[148:151], v[204:207], v[84:87]
	v_mfma_f32_16x16x32_bf16 v[80:83], v[172:175], v[204:207], v[80:83]
	v_mfma_f32_16x16x32_bf16 v[68:71], v[148:151], v[212:215], v[68:71]
	v_mfma_f32_16x16x32_bf16 v[64:67], v[172:175], v[212:215], v[64:67]
	s_barrier
; #define PG8_STAGE(bufoff, gbase, voff) do { _Pragma("unroll") for (int _i = 0; _i < 2; ++_i) \
;         __builtin_amdgcn_global_load_lds((const unsigned*)((const char*)(gbase) + (voff)[_i]), (PG8_LAS unsigned*)(lds + (bufoff) + ldsw + _i * 8192), 16, 0, 0); } while (0)
; #define PG8_LDA(dst, b, h) do { _Pragma("unroll") for (int m = 0; m < 4; ++m) _Pragma("unroll") for (int k = 0; k < 2; ++k) dst[m][k] = *(const PG8_LAS bf16x8*)(lds + PG8_SA(b, h) + aoff + m * 2048 + k * 1024); } while (0)
; #define PG8_MMA(ai, bj, At, Bt) do { __builtin_amdgcn_s_setprio(1); _Pragma("unroll") for (int m = 0; m < 4; ++m) _Pragma("unroll") for (int n = 0; n < 2; ++n) _Pragma("unroll") for (int k = 0; k < 2; ++k) \
;         acc[ai][bj][m][n] = mma16<F16>(Bt[n][k], At[m][k], acc[ai][bj][m][n]); __builtin_amdgcn_s_setprio(0); } while (0)
; #define PG8_WAIT_V(n) asm volatile("s_waitcnt vmcnt(" #n ")" ::: "memory")
; #define PG8_WAIT_L(n) asm volatile("s_waitcnt lgkmcnt(" #n ")" ::: "memory")
; #define PG8_BAR __builtin_amdgcn_s_barrier()
; #define PG8_SCHED __builtin_amdgcn_sched_barrier(0)
; template <class Epi, class Sched, bool ALIGN_EPI = false, bool SP2 = false, bool F16 = false>
; __device__ __forceinline__ void gemm_phase(PG8_LAS unsigned char* lds, const Gemm g, const Sched& S, const Epi& E, const int wid_in) {
;     ...
;             PG8_LDA(At, 1, 1); PG8_STAGE(PG8_SB(1, 0), b3, voffB); PG8_STAGE(PG8_SB(1, 1), b3 + hstep, voffB); PG8_STAGE(PG8_SA(1, 0), a3, voffA);
;             PG8_WAIT_V(8); PG8_WAIT_L(0); PG8_BAR; PG8_MMA(1, 0, At, B0); PG8_MMA(1, 1, At, B1); PG8_BAR; PG8_SCHED;
	s_add_i32 s52, s62, s68
	v_lshl_add_u64 v[184:185], v[184:185], 0, s[28:29]
	s_mov_b32 m0, s52
	s_nop 0
	global_load_lds_dwordx4 v[184:185], off
	s_add_i32 m0, s52, 0x2000
	s_add_u32 s50, s50, 0x40080
	v_lshl_add_u64 v[184:185], v[216:217], 0, s[28:29]
	s_addc_u32 s51, s51, 0
	s_add_i32 s52, s63, s68
	global_load_lds_dwordx4 v[184:185], off
	v_lshl_add_u64 v[184:185], s[50:51], 0, v[154:155]
	s_mov_b32 m0, s52
	s_nop 0
	global_load_lds_dwordx4 v[184:185], off
	v_lshl_add_u64 v[184:185], s[50:51], 0, v[158:159]
	s_add_i32 m0, s52, 0x2000
	s_nop 0
	global_load_lds_dwordx4 v[184:185], off
	v_lshl_add_u64 v[184:185], v[218:219], 0, s[28:29]
	s_mov_b32 m0, s75
	s_nop 0
	global_load_lds_dwordx4 v[184:185], off
	v_lshl_add_u64 v[184:185], v[220:221], 0, s[28:29]
	s_mov_b32 m0, s67
	s_nop 0
	global_load_lds_dwordx4 v[184:185], off
	ds_read_b128 v[176:179], v191 offset:49152
	ds_read_b128 v[180:183], v191 offset:50176
	ds_read_b128 v[192:195], v191 offset:51200
	ds_read_b128 v[196:199], v191 offset:52224
	ds_read_b128 v[200:203], v191 offset:53248
	ds_read_b128 v[204:207], v191 offset:54272
	ds_read_b128 v[208:211], v191 offset:55296
	ds_read_b128 v[212:215], v191 offset:56320
	s_waitcnt vmcnt(8)
	s_waitcnt lgkmcnt(0)
	s_barrier
	s_waitcnt lgkmcnt(0)
	v_mfma_f32_16x16x32_bf16 v[60:63], v[128:131], v[176:179], v[60:63]
	v_mfma_f32_16x16x32_bf16 v[56:59], v[136:139], v[176:179], v[56:59]
	v_mfma_f32_16x16x32_bf16 v[44:47], v[128:131], v[192:195], v[44:47]
	v_mfma_f32_16x16x32_bf16 v[40:43], v[136:139], v[192:195], v[40:43]
	v_mfma_f32_16x16x32_bf16 v[28:31], v[128:131], v[200:203], v[28:31]
	v_mfma_f32_16x16x32_bf16 v[24:27], v[136:139], v[200:203], v[24:27]
	v_mfma_f32_16x16x32_bf16 v[12:15], v[128:131], v[208:211], v[12:15]
	v_mfma_f32_16x16x32_bf16 v[8:11], v[136:139], v[208:211], v[8:11]
	v_mfma_f32_16x16x32_bf16 v[60:63], v[132:135], v[180:183], v[60:63]
	v_mfma_f32_16x16x32_bf16 v[56:59], v[140:143], v[180:183], v[56:59]
	v_mfma_f32_16x16x32_bf16 v[44:47], v[132:135], v[196:199], v[44:47]
	v_mfma_f32_16x16x32_bf16 v[40:43], v[140:143], v[196:199], v[40:43]
	v_mfma_f32_16x16x32_bf16 v[28:31], v[132:135], v[204:207], v[28:31]
	v_mfma_f32_16x16x32_bf16 v[24:27], v[140:143], v[204:207], v[24:27]
	v_mfma_f32_16x16x32_bf16 v[12:15], v[132:135], v[212:215], v[12:15]
	v_mfma_f32_16x16x32_bf16 v[8:11], v[140:143], v[212:215], v[8:11]
	v_mfma_f32_16x16x32_bf16 v[52:55], v[144:147], v[176:179], v[52:55]
	v_mfma_f32_16x16x32_bf16 v[48:51], v[168:171], v[176:179], v[48:51]
	v_mfma_f32_16x16x32_bf16 v[36:39], v[144:147], v[192:195], v[36:39]
	v_mfma_f32_16x16x32_bf16 v[32:35], v[168:171], v[192:195], v[32:35]
	v_mfma_f32_16x16x32_bf16 v[20:23], v[144:147], v[200:203], v[20:23]
	v_mfma_f32_16x16x32_bf16 v[16:19], v[168:171], v[200:203], v[16:19]
	v_mfma_f32_16x16x32_bf16 v[4:7], v[144:147], v[208:211], v[4:7]
	v_mfma_f32_16x16x32_bf16 v[0:3], v[168:171], v[208:211], v[0:3]
	v_mfma_f32_16x16x32_bf16 v[52:55], v[148:151], v[180:183], v[52:55]
	v_mfma_f32_16x16x32_bf16 v[48:51], v[172:175], v[180:183], v[48:51]
	v_mfma_f32_16x16x32_bf16 v[36:39], v[148:151], v[196:199], v[36:39]
	v_mfma_f32_16x16x32_bf16 v[32:35], v[172:175], v[196:199], v[32:35]
	v_mfma_f32_16x16x32_bf16 v[20:23], v[148:151], v[204:207], v[20:23]
	v_mfma_f32_16x16x32_bf16 v[16:19], v[172:175], v[204:207], v[16:19]
	v_mfma_f32_16x16x32_bf16 v[4:7], v[148:151], v[212:215], v[4:7]
	v_mfma_f32_16x16x32_bf16 v[0:3], v[172:175], v[212:215], v[0:3]
	s_barrier
	s_add_i32 s61, s61, 2
	s_add_u32 s48, s48, 0x100
	s_addc_u32 s49, s49, 0
	s_add_u32 s47, s47, 0x100
	s_addc_u32 s60, s60, 0
	s_cmp_gt_u32 s61, 13
	s_cbranch_scc0 .LBB0_1832
	s_and_b64 vcc, exec, s[16:17]
	s_cbranch_vccz .LBB0_1835
	s_barrier

; #define PG8_STAGE(bufoff, gbase, voff) do { _Pragma("unroll") for (int _i = 0; _i < 2; ++_i) \
;         __builtin_amdgcn_global_load_lds((const unsigned*)((const char*)(gbase) + (voff)[_i]), (PG8_LAS unsigned*)(lds + (bufoff) + ldsw + _i * 8192), 16, 0, 0); } while (0)
; #define PG8_LDA(dst, b, h) do { _Pragma("unroll") for (int m = 0; m < 4; ++m) _Pragma("unroll") for (int k = 0; k < 2; ++k) dst[m][k] = *(const PG8_LAS bf16x8*)(lds + PG8_SA(b, h) + aoff + m * 2048 + k * 1024); } while (0)
; #define PG8_LDB(dst, b, h) do { _Pragma("unroll") for (int n = 0; n < 2; ++n) _Pragma("unroll") for (int k = 0; k < 2; ++k) dst[n][k] = *(const PG8_LAS bf16x8*)(lds + PG8_SB(b, h) + boff + n * 2048 + k * 1024); } while (0)
; #define PG8_MMA(ai, bj, At, Bt) do { __builtin_amdgcn_s_setprio(1); _Pragma("unroll") for (int m = 0; m < 4; ++m) _Pragma("unroll") for (int n = 0; n < 2; ++n) _Pragma("unroll") for (int k = 0; k < 2; ++k) \
;         acc[ai][bj][m][n] = mma16<F16>(Bt[n][k], At[m][k], acc[ai][bj][m][n]); __builtin_amdgcn_s_setprio(0); } while (0)
; #define PG8_WAIT_V(n) asm volatile("s_waitcnt vmcnt(" #n ")" ::: "memory")
; #define PG8_BAR __builtin_amdgcn_s_barrier()
; template <class Epi, class Sched, bool ALIGN_EPI = false, bool SP2 = false, bool F16 = false>
; __device__ __forceinline__ void gemm_phase(PG8_LAS unsigned char* lds, const Gemm g, const Sched& S, const Epi& E, const int wid_in) {
;     ...
;         for (int t = 0; t < nt; t += 2) {
;             const bool last = (t == nt - 2);
;             const char* a1 = cA + (size_t)(t + 1) * kstep;
;             const char* a2 = last ? nA : cA + (size_t)(t + 2) * kstep; const char* b2 = last ? nB : cB + (size_t)(t + 2) * kstep;
;             const char* a3 = a2 + kstep; const char* b3 = b2 + kstep;
;             if (last && has_next) S.a_ready(nxt);
;             if constexpr (SP2) {
;             PG8_LDB(B0, 0, 0); PG8_LDB(B1, 0, 1); PG8_SCHED; PG8_LDA(At, 0, 0); PG8_STAGE(PG8_SA(1, 1), a1 + hstep, voffA);
;             PG8_WAIT_V(8); PG8_WAIT_L(0); PG8_BAR; PG8_MMA(0, 0, At, B0); PG8_MMA(0, 1, At, B1); PG8_BAR; PG8_SCHED;
;             PG8_LDA(At, 0, 1); PG8_STAGE(PG8_SB(0, 0), b2, voffB); PG8_STAGE(PG8_SB(0, 1), b2 + hstep, voffB); PG8_STAGE(PG8_SA(0, 0), a2, voffA);
;             PG8_WAIT_V(8); PG8_WAIT_L(0); PG8_BAR; PG8_MMA(1, 0, At, B0); PG8_MMA(1, 1, At, B1); PG8_BAR; PG8_SCHED;
.LBB0_1909:
	ds_read_b128 v[0:3], v193
	ds_read_b128 v[4:7], v193 offset:1024
	ds_read_b128 v[136:139], v193 offset:2048
	ds_read_b128 v[140:143], v193 offset:3072
	ds_read_b128 v[144:147], v194
	ds_read_b128 v[148:151], v194 offset:1024
	ds_read_b128 v[152:155], v194 offset:2048
	ds_read_b128 v[156:159], v194 offset:3072
	s_add_u32 s48, s46, 0xfffc0080
	s_addc_u32 s49, s47, -1
	s_cmp_eq_u32 s64, 12
	s_cselect_b32 s51, s29, s49
	s_cselect_b32 s50, s42, s48
	s_cselect_b32 s49, s27, s63
	s_cselect_b32 s48, s43, s45
	s_mov_b32 m0, s91
	v_lshl_add_u64 v[188:189], s[46:47], 0, v[168:169]
	ds_read_b128 v[176:179], v195
	ds_read_b128 v[180:183], v195 offset:1024
	ds_read_b128 v[184:187], v195 offset:2048
	ds_read_b128 v[198:201], v195 offset:3072
	ds_read_b128 v[202:205], v195 offset:4096
	ds_read_b128 v[206:209], v195 offset:5120
	ds_read_b128 v[210:213], v195 offset:6144
	ds_read_b128 v[214:217], v195 offset:7168
	global_load_lds_dwordx4 v[188:189], off
	v_lshl_add_u64 v[188:189], s[46:47], 0, v[170:171]
	s_add_i32 m0, s74, 0xe000
	s_nop 0
	global_load_lds_dwordx4 v[188:189], off
	s_waitcnt vmcnt(8)
	s_waitcnt lgkmcnt(0)
	s_barrier
	s_waitcnt lgkmcnt(0)
	v_mfma_f32_16x16x32_f16 v[132:135], v[0:3], v[176:179], v[132:135]
	v_mfma_f32_16x16x32_f16 v[128:131], v[136:139], v[176:179], v[128:131]
	v_mfma_f32_16x16x32_f16 v[116:119], v[0:3], v[184:187], v[116:119]
	v_mfma_f32_16x16x32_f16 v[112:115], v[136:139], v[184:187], v[112:115]
	v_mfma_f32_16x16x32_f16 v[100:103], v[0:3], v[202:205], v[100:103]
	v_mfma_f32_16x16x32_f16 v[96:99], v[136:139], v[202:205], v[96:99]
	v_mfma_f32_16x16x32_f16 v[84:87], v[0:3], v[210:213], v[84:87]
	v_mfma_f32_16x16x32_f16 v[80:83], v[136:139], v[210:213], v[80:83]
	v_mfma_f32_16x16x32_f16 v[132:135], v[4:7], v[180:183], v[132:135]
	v_mfma_f32_16x16x32_f16 v[128:131], v[140:143], v[180:183], v[128:131]
	v_mfma_f32_16x16x32_f16 v[116:119], v[4:7], v[198:201], v[116:119]
	v_mfma_f32_16x16x32_f16 v[112:115], v[140:143], v[198:201], v[112:115]
	v_mfma_f32_16x16x32_f16 v[100:103], v[4:7], v[206:209], v[100:103]
	v_mfma_f32_16x16x32_f16 v[96:99], v[140:143], v[206:209], v[96:99]
	v_mfma_f32_16x16x32_f16 v[84:87], v[4:7], v[214:217], v[84:87]
	v_mfma_f32_16x16x32_f16 v[80:83], v[140:143], v[214:217], v[80:83]
	v_mfma_f32_16x16x32_f16 v[124:127], v[144:147], v[176:179], v[124:127]
	v_mfma_f32_16x16x32_f16 v[120:123], v[152:155], v[176:179], v[120:123]
	v_mfma_f32_16x16x32_f16 v[108:111], v[144:147], v[184:187], v[108:111]
	v_mfma_f32_16x16x32_f16 v[104:107], v[152:155], v[184:187], v[104:107]
	v_mfma_f32_16x16x32_f16 v[92:95], v[144:147], v[202:205], v[92:95]
	v_mfma_f32_16x16x32_f16 v[88:91], v[152:155], v[202:205], v[88:91]
	v_mfma_f32_16x16x32_f16 v[76:79], v[144:147], v[210:213], v[76:79]
	v_mfma_f32_16x16x32_f16 v[72:75], v[152:155], v[210:213], v[72:75]
	v_mfma_f32_16x16x32_f16 v[124:127], v[148:151], v[180:183], v[124:127]
	v_mfma_f32_16x16x32_f16 v[120:123], v[156:159], v[180:183], v[120:123]
	v_mfma_f32_16x16x32_f16 v[108:111], v[148:151], v[198:201], v[108:111]
	v_mfma_f32_16x16x32_f16 v[104:107], v[156:159], v[198:201], v[104:107]
	v_mfma_f32_16x16x32_f16 v[92:95], v[148:151], v[206:209], v[92:95]
	v_mfma_f32_16x16x32_f16 v[88:91], v[156:159], v[206:209], v[88:91]
	v_mfma_f32_16x16x32_f16 v[76:79], v[148:151], v[214:217], v[76:79]
	v_mfma_f32_16x16x32_f16 v[72:75], v[156:159], v[214:217], v[72:75]
	s_barrier
	s_add_i32 s65, s60, s68
	v_lshl_add_u64 v[188:189], s[48:49], 0, v[162:163]
	s_mov_b32 m0, s65
	s_nop 0
	global_load_lds_dwordx4 v[188:189], off
	s_add_i32 m0, s65, 0x2000
	s_add_u32 s84, s48, 0x40000
	v_lshl_add_u64 v[218:219], s[48:49], 0, v[166:167]
	s_addc_u32 s85, s49, 0
	s_add_i32 s65, s61, s68
	global_load_lds_dwordx4 v[218:219], off
	v_lshl_add_u64 v[220:221], s[84:85], 0, v[162:163]
	s_mov_b32 m0, s65
	v_lshl_add_u64 v[222:223], s[50:51], 0, v[164:165]
	global_load_lds_dwordx4 v[220:221], off
	v_lshl_add_u64 v[220:221], s[84:85], 0, v[166:167]
	s_add_i32 m0, s65, 0x2000
	s_nop 0
	global_load_lds_dwordx4 v[220:221], off
	v_lshl_add_u64 v[220:221], s[50:51], 0, v[160:161]
	s_mov_b32 m0, s74
	s_nop 0
	global_load_lds_dwordx4 v[220:221], off
	s_mov_b32 m0, s66
	s_nop 0
	global_load_lds_dwordx4 v[222:223], off
	ds_read_b128 v[176:179], v195 offset:16384
	ds_read_b128 v[180:183], v195 offset:17408
	ds_read_b128 v[184:187], v195 offset:18432
	ds_read_b128 v[198:201], v195 offset:19456
	ds_read_b128 v[202:205], v195 offset:20480
	ds_read_b128 v[206:209], v195 offset:21504
	ds_read_b128 v[210:213], v195 offset:22528
	ds_read_b128 v[214:217], v195 offset:23552
	s_waitcnt vmcnt(8)
	s_waitcnt lgkmcnt(0)
	s_barrier
; #define PG8_STAGE(bufoff, gbase, voff) do { _Pragma("unroll") for (int _i = 0; _i < 2; ++_i) \
;         __builtin_amdgcn_global_load_lds((const unsigned*)((const char*)(gbase) + (voff)[_i]), (PG8_LAS unsigned*)(lds + (bufoff) + ldsw + _i * 8192), 16, 0, 0); } while (0)
; #define PG8_LDA(dst, b, h) do { _Pragma("unroll") for (int m = 0; m < 4; ++m) _Pragma("unroll") for (int k = 0; k < 2; ++k) dst[m][k] = *(const PG8_LAS bf16x8*)(lds + PG8_SA(b, h) + aoff + m * 2048 + k * 1024); } while (0)
; #define PG8_LDB(dst, b, h) do { _Pragma("unroll") for (int n = 0; n < 2; ++n) _Pragma("unroll") for (int k = 0; k < 2; ++k) dst[n][k] = *(const PG8_LAS bf16x8*)(lds + PG8_SB(b, h) + boff + n * 2048 + k * 1024); } while (0)
; #define PG8_MMA(ai, bj, At, Bt) do { __builtin_amdgcn_s_setprio(1); _Pragma("unroll") for (int m = 0; m < 4; ++m) _Pragma("unroll") for (int n = 0; n < 2; ++n) _Pragma("unroll") for (int k = 0; k < 2; ++k) \
;         acc[ai][bj][m][n] = mma16<F16>(Bt[n][k], At[m][k], acc[ai][bj][m][n]); __builtin_amdgcn_s_setprio(0); } while (0)
; #define PG8_WAIT_V(n) asm volatile("s_waitcnt vmcnt(" #n ")" ::: "memory")
; #define PG8_WAIT_L(n) asm volatile("s_waitcnt lgkmcnt(" #n ")" ::: "memory")
; #define PG8_BAR __builtin_amdgcn_s_barrier()
; #define PG8_SCHED __builtin_amdgcn_sched_barrier(0)
; template <class Epi, class Sched, bool ALIGN_EPI = false, bool SP2 = false, bool F16 = false>
; __device__ __forceinline__ void gemm_phase(PG8_LAS unsigned char* lds, const Gemm g, const Sched& S, const Epi& E, const int wid_in) {
;     ...
;             PG8_WAIT_V(8); PG8_WAIT_L(0); PG8_BAR; PG8_MMA(1, 0, At, B0); PG8_MMA(1, 1, At, B1); PG8_BAR; PG8_SCHED;
;             PG8_LDB(B0, 1, 0); PG8_LDB(B1, 1, 1); PG8_SCHED; PG8_LDA(At, 1, 0); PG8_STAGE(PG8_SA(0, 1), a2 + hstep, voffA);
;             PG8_WAIT_V(8); PG8_WAIT_L(0); PG8_BAR; PG8_MMA(0, 0, At, B0); PG8_MMA(0, 1, At, B1); PG8_BAR; PG8_SCHED;
	s_waitcnt lgkmcnt(0)
	v_mfma_f32_16x16x32_f16 v[68:71], v[0:3], v[176:179], v[68:71]
	v_mfma_f32_16x16x32_f16 v[64:67], v[136:139], v[176:179], v[64:67]
	v_mfma_f32_16x16x32_f16 v[52:55], v[0:3], v[184:187], v[52:55]
	v_mfma_f32_16x16x32_f16 v[48:51], v[136:139], v[184:187], v[48:51]
	v_mfma_f32_16x16x32_f16 v[36:39], v[0:3], v[202:205], v[36:39]
	v_mfma_f32_16x16x32_f16 v[32:35], v[136:139], v[202:205], v[32:35]
	v_mfma_f32_16x16x32_f16 v[0:3], v[0:3], v[210:213], v[20:23]
	v_mfma_f32_16x16x32_f16 v[68:71], v[4:7], v[180:183], v[68:71]
	v_mfma_f32_16x16x32_f16 v[64:67], v[140:143], v[180:183], v[64:67]
	v_mfma_f32_16x16x32_f16 v[52:55], v[4:7], v[198:201], v[52:55]
	v_mfma_f32_16x16x32_f16 v[48:51], v[140:143], v[198:201], v[48:51]
	v_mfma_f32_16x16x32_f16 v[36:39], v[4:7], v[206:209], v[36:39]
	v_mfma_f32_16x16x32_f16 v[32:35], v[140:143], v[206:209], v[32:35]
	v_mfma_f32_16x16x32_f16 v[0:3], v[4:7], v[214:217], v[0:3]
	v_mfma_f32_16x16x32_f16 v[4:7], v[136:139], v[210:213], v[16:19]
	v_mfma_f32_16x16x32_f16 v[4:7], v[140:143], v[214:217], v[4:7]
	v_mfma_f32_16x16x32_f16 v[16:19], v[144:147], v[176:179], v[60:63]
	v_mfma_f32_16x16x32_f16 v[60:63], v[148:151], v[180:183], v[16:19]
	v_mfma_f32_16x16x32_f16 v[16:19], v[152:155], v[176:179], v[56:59]
	v_mfma_f32_16x16x32_f16 v[56:59], v[156:159], v[180:183], v[16:19]
	v_mfma_f32_16x16x32_f16 v[16:19], v[144:147], v[184:187], v[44:47]
	v_mfma_f32_16x16x32_f16 v[44:47], v[148:151], v[198:201], v[16:19]
	v_mfma_f32_16x16x32_f16 v[16:19], v[152:155], v[184:187], v[40:43]
	v_mfma_f32_16x16x32_f16 v[40:43], v[156:159], v[198:201], v[16:19]
	v_mfma_f32_16x16x32_f16 v[16:19], v[144:147], v[202:205], v[28:31]
	v_mfma_f32_16x16x32_f16 v[28:31], v[148:151], v[206:209], v[16:19]
	v_mfma_f32_16x16x32_f16 v[16:19], v[152:155], v[202:205], v[24:27]
	v_mfma_f32_16x16x32_f16 v[12:15], v[144:147], v[210:213], v[12:15]
	v_mfma_f32_16x16x32_f16 v[8:11], v[152:155], v[210:213], v[8:11]
	v_mfma_f32_16x16x32_f16 v[24:27], v[156:159], v[206:209], v[16:19]
	v_mfma_f32_16x16x32_f16 v[12:15], v[148:151], v[214:217], v[12:15]
	v_mfma_f32_16x16x32_f16 v[8:11], v[156:159], v[214:217], v[8:11]
	s_barrier
	s_add_i32 s65, 0, 0x18000
	s_add_i32 s76, 0, 0x1c000
	v_add_u32_e32 v140, s65, v192
	v_add_u32_e32 v156, s76, v192
	s_add_u32 s50, s50, 0x40000
	s_addc_u32 s51, s51, 0
	s_mov_b32 m0, s90
	v_lshl_add_u64 v[224:225], s[50:51], 0, v[160:161]
	global_load_lds_dwordx4 v[224:225], off
	v_lshl_add_u64 v[224:225], s[50:51], 0, v[164:165]
	s_mov_b32 m0, s37
	s_nop 0
	global_load_lds_dwordx4 v[224:225], off
	ds_read_b128 v[16:19], v140
	ds_read_b128 v[20:23], v140 offset:1024
	ds_read_b128 v[136:139], v140 offset:2048
	ds_read_b128 v[140:143], v140 offset:3072
	ds_read_b128 v[144:147], v156
	ds_read_b128 v[148:151], v156 offset:1024
	ds_read_b128 v[152:155], v156 offset:2048
	ds_read_b128 v[156:159], v156 offset:3072
	ds_read_b128 v[176:179], v195 offset:32768
	ds_read_b128 v[180:183], v195 offset:33792
	ds_read_b128 v[184:187], v195 offset:34816
	ds_read_b128 v[198:201], v195 offset:35840
	ds_read_b128 v[202:205], v195 offset:36864
	ds_read_b128 v[206:209], v195 offset:37888
	ds_read_b128 v[210:213], v195 offset:38912
	ds_read_b128 v[214:217], v195 offset:39936
	s_waitcnt vmcnt(8)
	s_waitcnt lgkmcnt(0)
	s_barrier
	s_waitcnt lgkmcnt(0)
	v_mfma_f32_16x16x32_f16 v[132:135], v[16:19], v[176:179], v[132:135]
	v_mfma_f32_16x16x32_f16 v[128:131], v[136:139], v[176:179], v[128:131]
	v_mfma_f32_16x16x32_f16 v[116:119], v[16:19], v[184:187], v[116:119]
	v_mfma_f32_16x16x32_f16 v[112:115], v[136:139], v[184:187], v[112:115]
	v_mfma_f32_16x16x32_f16 v[100:103], v[16:19], v[202:205], v[100:103]
	v_mfma_f32_16x16x32_f16 v[96:99], v[136:139], v[202:205], v[96:99]
	v_mfma_f32_16x16x32_f16 v[84:87], v[16:19], v[210:213], v[84:87]
	v_mfma_f32_16x16x32_f16 v[80:83], v[136:139], v[210:213], v[80:83]
	v_mfma_f32_16x16x32_f16 v[132:135], v[20:23], v[180:183], v[132:135]
	v_mfma_f32_16x16x32_f16 v[128:131], v[140:143], v[180:183], v[128:131]
	v_mfma_f32_16x16x32_f16 v[116:119], v[20:23], v[198:201], v[116:119]
	v_mfma_f32_16x16x32_f16 v[112:115], v[140:143], v[198:201], v[112:115]
	v_mfma_f32_16x16x32_f16 v[100:103], v[20:23], v[206:209], v[100:103]
	v_mfma_f32_16x16x32_f16 v[96:99], v[140:143], v[206:209], v[96:99]
	v_mfma_f32_16x16x32_f16 v[84:87], v[20:23], v[214:217], v[84:87]
	v_mfma_f32_16x16x32_f16 v[80:83], v[140:143], v[214:217], v[80:83]
	v_mfma_f32_16x16x32_f16 v[124:127], v[144:147], v[176:179], v[124:127]
	v_mfma_f32_16x16x32_f16 v[120:123], v[152:155], v[176:179], v[120:123]
	v_mfma_f32_16x16x32_f16 v[108:111], v[144:147], v[184:187], v[108:111]
	v_mfma_f32_16x16x32_f16 v[104:107], v[152:155], v[184:187], v[104:107]
	v_mfma_f32_16x16x32_f16 v[92:95], v[144:147], v[202:205], v[92:95]
	v_mfma_f32_16x16x32_f16 v[88:91], v[152:155], v[202:205], v[88:91]
	v_mfma_f32_16x16x32_f16 v[76:79], v[144:147], v[210:213], v[76:79]
	v_mfma_f32_16x16x32_f16 v[72:75], v[152:155], v[210:213], v[72:75]
	v_mfma_f32_16x16x32_f16 v[124:127], v[148:151], v[180:183], v[124:127]
	v_mfma_f32_16x16x32_f16 v[120:123], v[156:159], v[180:183], v[120:123]
	v_mfma_f32_16x16x32_f16 v[108:111], v[148:151], v[198:201], v[108:111]
	v_mfma_f32_16x16x32_f16 v[104:107], v[156:159], v[198:201], v[104:107]
	v_mfma_f32_16x16x32_f16 v[92:95], v[148:151], v[206:209], v[92:95]
	v_mfma_f32_16x16x32_f16 v[88:91], v[156:159], v[206:209], v[88:91]
	v_mfma_f32_16x16x32_f16 v[76:79], v[148:151], v[214:217], v[76:79]
	v_mfma_f32_16x16x32_f16 v[72:75], v[156:159], v[214:217], v[72:75]
	s_barrier
; #define PG8_STAGE(bufoff, gbase, voff) do { _Pragma("unroll") for (int _i = 0; _i < 2; ++_i) \
;         __builtin_amdgcn_global_load_lds((const unsigned*)((const char*)(gbase) + (voff)[_i]), (PG8_LAS unsigned*)(lds + (bufoff) + ldsw + _i * 8192), 16, 0, 0); } while (0)
; #define PG8_LDA(dst, b, h) do { _Pragma("unroll") for (int m = 0; m < 4; ++m) _Pragma("unroll") for (int k = 0; k < 2; ++k) dst[m][k] = *(const PG8_LAS bf16x8*)(lds + PG8_SA(b, h) + aoff + m * 2048 + k * 1024); } while (0)
; #define PG8_MMA(ai, bj, At, Bt) do { __builtin_amdgcn_s_setprio(1); _Pragma("unroll") for (int m = 0; m < 4; ++m) _Pragma("unroll") for (int n = 0; n < 2; ++n) _Pragma("unroll") for (int k = 0; k < 2; ++k) \
;         acc[ai][bj][m][n] = mma16<F16>(Bt[n][k], At[m][k], acc[ai][bj][m][n]); __builtin_amdgcn_s_setprio(0); } while (0)
; #define PG8_WAIT_V(n) asm volatile("s_waitcnt vmcnt(" #n ")" ::: "memory")
; #define PG8_WAIT_L(n) asm volatile("s_waitcnt lgkmcnt(" #n ")" ::: "memory")
; #define PG8_BAR __builtin_amdgcn_s_barrier()
; #define PG8_SCHED __builtin_amdgcn_sched_barrier(0)
; template <class Epi, class Sched, bool ALIGN_EPI = false, bool SP2 = false, bool F16 = false>
; __device__ __forceinline__ void gemm_phase(PG8_LAS unsigned char* lds, const Gemm g, const Sched& S, const Epi& E, const int wid_in) {
;     ...
;             PG8_LDA(At, 1, 1); PG8_STAGE(PG8_SB(1, 0), b3, voffB); PG8_STAGE(PG8_SB(1, 1), b3 + hstep, voffB); PG8_STAGE(PG8_SA(1, 0), a3, voffA);
;             PG8_WAIT_V(8); PG8_WAIT_L(0); PG8_BAR; PG8_MMA(1, 0, At, B0); PG8_MMA(1, 1, At, B1); PG8_BAR; PG8_SCHED;
	s_add_i32 s50, s65, s68
	v_lshl_add_u64 v[188:189], v[188:189], 0, s[24:25]
	s_mov_b32 m0, s50
	s_nop 0
	global_load_lds_dwordx4 v[188:189], off
	s_add_i32 m0, s50, 0x2000
	s_add_u32 s48, s48, 0x40080
	v_lshl_add_u64 v[188:189], v[218:219], 0, s[24:25]
	s_addc_u32 s49, s49, 0
	s_add_i32 s50, s76, s68
	global_load_lds_dwordx4 v[188:189], off
	v_lshl_add_u64 v[188:189], s[48:49], 0, v[162:163]
	s_mov_b32 m0, s50
	s_nop 0
	global_load_lds_dwordx4 v[188:189], off
	v_lshl_add_u64 v[188:189], s[48:49], 0, v[166:167]
	s_add_i32 m0, s50, 0x2000
	s_nop 0
	global_load_lds_dwordx4 v[188:189], off
	v_lshl_add_u64 v[188:189], v[220:221], 0, s[24:25]
	s_mov_b32 m0, s75
	s_nop 0
	global_load_lds_dwordx4 v[188:189], off
	v_lshl_add_u64 v[188:189], v[222:223], 0, s[24:25]
	s_mov_b32 m0, s67
	s_nop 0
	global_load_lds_dwordx4 v[188:189], off
	ds_read_b128 v[176:179], v195 offset:49152
	ds_read_b128 v[180:183], v195 offset:50176
	ds_read_b128 v[184:187], v195 offset:51200
	ds_read_b128 v[198:201], v195 offset:52224
	ds_read_b128 v[202:205], v195 offset:53248
	ds_read_b128 v[206:209], v195 offset:54272
	ds_read_b128 v[210:213], v195 offset:55296
	ds_read_b128 v[214:217], v195 offset:56320
	s_waitcnt vmcnt(8)
	s_waitcnt lgkmcnt(0)
	s_barrier
	s_waitcnt lgkmcnt(0)
	v_mfma_f32_16x16x32_f16 v[68:71], v[16:19], v[176:179], v[68:71]
	v_mfma_f32_16x16x32_f16 v[52:55], v[16:19], v[184:187], v[52:55]
	v_mfma_f32_16x16x32_f16 v[36:39], v[16:19], v[202:205], v[36:39]
	v_mfma_f32_16x16x32_f16 v[0:3], v[16:19], v[210:213], v[0:3]
	v_mfma_f32_16x16x32_f16 v[68:71], v[20:23], v[180:183], v[68:71]
	v_mfma_f32_16x16x32_f16 v[64:67], v[136:139], v[176:179], v[64:67]
	v_mfma_f32_16x16x32_f16 v[52:55], v[20:23], v[198:201], v[52:55]
	v_mfma_f32_16x16x32_f16 v[48:51], v[136:139], v[184:187], v[48:51]
	v_mfma_f32_16x16x32_f16 v[36:39], v[20:23], v[206:209], v[36:39]
	v_mfma_f32_16x16x32_f16 v[32:35], v[136:139], v[202:205], v[32:35]
	v_mfma_f32_16x16x32_f16 v[20:23], v[20:23], v[214:217], v[0:3]
	v_mfma_f32_16x16x32_f16 v[0:3], v[136:139], v[210:213], v[4:7]
	v_mfma_f32_16x16x32_f16 v[64:67], v[140:143], v[180:183], v[64:67]
	v_mfma_f32_16x16x32_f16 v[48:51], v[140:143], v[198:201], v[48:51]
	v_mfma_f32_16x16x32_f16 v[32:35], v[140:143], v[206:209], v[32:35]
	v_mfma_f32_16x16x32_f16 v[16:19], v[140:143], v[214:217], v[0:3]
	v_mfma_f32_16x16x32_f16 v[0:3], v[144:147], v[176:179], v[60:63]
	v_mfma_f32_16x16x32_f16 v[60:63], v[148:151], v[180:183], v[0:3]
	v_mfma_f32_16x16x32_f16 v[0:3], v[152:155], v[176:179], v[56:59]
	v_mfma_f32_16x16x32_f16 v[56:59], v[156:159], v[180:183], v[0:3]
	v_mfma_f32_16x16x32_f16 v[0:3], v[144:147], v[184:187], v[44:47]
	v_mfma_f32_16x16x32_f16 v[44:47], v[148:151], v[198:201], v[0:3]
	v_mfma_f32_16x16x32_f16 v[0:3], v[152:155], v[184:187], v[40:43]
	v_mfma_f32_16x16x32_f16 v[40:43], v[156:159], v[198:201], v[0:3]
	v_mfma_f32_16x16x32_f16 v[0:3], v[144:147], v[202:205], v[28:31]
	v_mfma_f32_16x16x32_f16 v[28:31], v[148:151], v[206:209], v[0:3]
	v_mfma_f32_16x16x32_f16 v[0:3], v[152:155], v[202:205], v[24:27]
	v_mfma_f32_16x16x32_f16 v[24:27], v[156:159], v[206:209], v[0:3]
	v_mfma_f32_16x16x32_f16 v[0:3], v[144:147], v[210:213], v[12:15]
	v_mfma_f32_16x16x32_f16 v[12:15], v[148:151], v[214:217], v[0:3]
	v_mfma_f32_16x16x32_f16 v[0:3], v[152:155], v[210:213], v[8:11]
	v_mfma_f32_16x16x32_f16 v[8:11], v[156:159], v[214:217], v[0:3]
	s_barrier
	s_add_i32 s64, s64, 2
	s_add_u32 s46, s46, 0x100
	s_addc_u32 s47, s47, 0
	s_add_u32 s45, s45, 0x100
	s_addc_u32 s63, s63, 0
	s_cmp_gt_u32 s64, 13
	s_cbranch_scc0 .LBB0_1909
	s_and_b64 vcc, exec, s[16:17]
	s_cbranch_vccz .LBB0_1912
	s_barrier

; #define PG8_STAGE(bufoff, gbase, voff) do { _Pragma("unroll") for (int _i = 0; _i < 2; ++_i) \
;         __builtin_amdgcn_global_load_lds((const unsigned*)((const char*)(gbase) + (voff)[_i]), (PG8_LAS unsigned*)(lds + (bufoff) + ldsw + _i * 8192), 16, 0, 0); } while (0)
; #define PG8_LDA(dst, b, h) do { _Pragma("unroll") for (int m = 0; m < 4; ++m) _Pragma("unroll") for (int k = 0; k < 2; ++k) dst[m][k] = *(const PG8_LAS bf16x8*)(lds + PG8_SA(b, h) + aoff + m * 2048 + k * 1024); } while (0)
; #define PG8_LDB(dst, b, h) do { _Pragma("unroll") for (int n = 0; n < 2; ++n) _Pragma("unroll") for (int k = 0; k < 2; ++k) dst[n][k] = *(const PG8_LAS bf16x8*)(lds + PG8_SB(b, h) + boff + n * 2048 + k * 1024); } while (0)
; #define PG8_WAIT_V(n) asm volatile("s_waitcnt vmcnt(" #n ")" ::: "memory")
; #define PG8_WAIT_L(n) asm volatile("s_waitcnt lgkmcnt(" #n ")" ::: "memory")
; #define PG8_BAR __builtin_amdgcn_s_barrier()
; #define PG8_SCHED __builtin_amdgcn_sched_barrier(0)
; template <class Epi, class Sched, bool ALIGN_EPI = false, bool SP2 = false, bool F16 = false>
; __device__ __forceinline__ void gemm_phase(PG8_LAS unsigned char* lds, const Gemm g, const Sched& S, const Epi& E, const int wid_in) {
;     ...
;         const bool has_next = S.next(ui + 1, nxt);
;         const char* nA = has_next ? (const char*)g.A + (size_t)nxt.pm * tstep : cA; const char* nB = has_next ? (const char*)g.Bt + (size_t)nxt.pn * tstep : cB;
;         for (int t = 0; t < nt; t += 2) {
;             const bool last = (t == nt - 2);
;             const char* a1 = cA + (size_t)(t + 1) * kstep;
;             const char* a2 = last ? nA : cA + (size_t)(t + 2) * kstep; const char* b2 = last ? nB : cB + (size_t)(t + 2) * kstep;
;             const char* a3 = a2 + kstep; const char* b3 = b2 + kstep;
;             if (last && has_next) S.a_ready(nxt);
;             if constexpr (SP2) {
;             PG8_LDB(B0, 0, 0); PG8_LDB(B1, 0, 1); PG8_SCHED; PG8_LDA(At, 0, 0); PG8_STAGE(PG8_SA(1, 1), a1 + hstep, voffA);
;             PG8_WAIT_V(8); PG8_WAIT_L(0); PG8_BAR; PG8_MMA(0, 0, At, B0); PG8_MMA(0, 1, At, B1); PG8_BAR; PG8_SCHED;
;             PG8_LDA(At, 0, 1); PG8_STAGE(PG8_SB(0, 0), b2, voffB); PG8_STAGE(PG8_SB(0, 1), b2 + hstep, voffB); PG8_STAGE(PG8_SA(0, 0), a2, voffA);
;             PG8_WAIT_V(8); PG8_WAIT_L(0); PG8_BAR; PG8_MMA(1, 0, At, B0); PG8_MMA(1, 1, At, B1); PG8_BAR; PG8_SCHED;
.LBB0_1944:
	s_mov_b64 s[48:49], s[10:11]
	s_add_i32 s10, s36, s19
	s_mov_b64 s[46:47], s[12:13]
	s_mov_b32 s12, s58
	s_mov_b32 s13, s57
	s_and_b32 s57, s10, 3
	s_ashr_i32 s58, s10, 2
	s_and_b64 s[10:11], s[30:31], exec
	s_cselect_b32 s12, s58, s12
	ds_read_b128 v[0:3], v134
	ds_read_b128 v[4:7], v134 offset:1024
	ds_read_b128 v[8:11], v134 offset:2048
	ds_read_b128 v[12:15], v134 offset:3072
	ds_read_b128 v[16:19], v135
	ds_read_b128 v[20:23], v135 offset:1024
	ds_read_b128 v[24:27], v135 offset:2048
	ds_read_b128 v[28:31], v135 offset:3072
	s_cselect_b32 s10, s57, s13
	s_ashr_i32 s13, s12, 31
	s_lshl_b64 s[12:13], s[12:13], 17
	s_add_u32 s12, s21, s12
	s_addc_u32 s13, s40, s13
	s_and_b64 s[36:37], s[30:31], exec
	s_cselect_b32 s45, s13, s47
	s_cselect_b32 s44, s12, s46
	s_ashr_i32 s11, s10, 31
	s_lshl_b64 s[10:11], s[10:11], 17
	s_add_u32 s10, s41, s10
	s_addc_u32 s11, s42, s11
	s_and_b64 s[36:37], s[30:31], exec
	s_cselect_b32 s37, s11, s49
	s_cselect_b32 s36, s10, s48
	s_add_u32 s60, s46, 0x10080
	s_addc_u32 s61, s47, 0
	s_mov_b32 m0, s91
	v_lshl_add_u64 v[64:65], s[60:61], 0, v[130:131]
	ds_read_b128 v[32:35], v136
	ds_read_b128 v[36:39], v136 offset:1024
	ds_read_b128 v[40:43], v136 offset:2048
	ds_read_b128 v[44:47], v136 offset:3072
	ds_read_b128 v[48:51], v136 offset:4096
	ds_read_b128 v[52:55], v136 offset:5120
	ds_read_b128 v[56:59], v136 offset:6144
	ds_read_b128 v[60:63], v136 offset:7168
	global_load_lds_dwordx4 v[64:65], off
	v_lshl_add_u64 v[64:65], s[60:61], 0, v[128:129]
	s_mov_b32 m0, s14
	s_nop 0
	global_load_lds_dwordx4 v[64:65], off
	s_waitcnt vmcnt(8)
	s_waitcnt lgkmcnt(0)
	s_barrier
	s_waitcnt lgkmcnt(0)
	v_mfma_f32_16x16x32_bf16 v[64:67], v[0:3], v[32:35], 0
	v_mfma_f32_16x16x32_bf16 v[68:71], v[8:11], v[32:35], 0
	v_mfma_f32_16x16x32_bf16 v[72:75], v[0:3], v[40:43], 0
	v_mfma_f32_16x16x32_bf16 v[76:79], v[8:11], v[40:43], 0
	v_mfma_f32_16x16x32_bf16 v[80:83], v[0:3], v[48:51], 0
	v_mfma_f32_16x16x32_bf16 v[84:87], v[8:11], v[48:51], 0
	v_mfma_f32_16x16x32_bf16 v[88:91], v[0:3], v[56:59], 0
	v_mfma_f32_16x16x32_bf16 v[92:95], v[8:11], v[56:59], 0
	v_mfma_f32_16x16x32_bf16 v[64:67], v[4:7], v[36:39], v[64:67]
	v_mfma_f32_16x16x32_bf16 v[68:71], v[12:15], v[36:39], v[68:71]
	v_mfma_f32_16x16x32_bf16 v[72:75], v[4:7], v[44:47], v[72:75]
	v_mfma_f32_16x16x32_bf16 v[76:79], v[12:15], v[44:47], v[76:79]
	v_mfma_f32_16x16x32_bf16 v[80:83], v[4:7], v[52:55], v[80:83]
	v_mfma_f32_16x16x32_bf16 v[84:87], v[12:15], v[52:55], v[84:87]
	v_mfma_f32_16x16x32_bf16 v[88:91], v[4:7], v[60:63], v[88:91]
	v_mfma_f32_16x16x32_bf16 v[92:95], v[12:15], v[60:63], v[92:95]
	v_mfma_f32_16x16x32_bf16 v[96:99], v[16:19], v[32:35], 0
	v_mfma_f32_16x16x32_bf16 v[32:35], v[24:27], v[32:35], 0
	v_mfma_f32_16x16x32_bf16 v[96:99], v[20:23], v[36:39], v[96:99]
	v_mfma_f32_16x16x32_bf16 v[32:35], v[28:31], v[36:39], v[32:35]
	v_mfma_f32_16x16x32_bf16 v[36:39], v[16:19], v[40:43], 0
	v_mfma_f32_16x16x32_bf16 v[40:43], v[24:27], v[40:43], 0
	v_mfma_f32_16x16x32_bf16 v[36:39], v[20:23], v[44:47], v[36:39]
	v_mfma_f32_16x16x32_bf16 v[40:43], v[28:31], v[44:47], v[40:43]
	v_mfma_f32_16x16x32_bf16 v[44:47], v[16:19], v[48:51], 0
	v_mfma_f32_16x16x32_bf16 v[48:51], v[24:27], v[48:51], 0
	v_mfma_f32_16x16x32_bf16 v[44:47], v[20:23], v[52:55], v[44:47]
	v_mfma_f32_16x16x32_bf16 v[48:51], v[28:31], v[52:55], v[48:51]
	v_mfma_f32_16x16x32_bf16 v[52:55], v[16:19], v[56:59], 0
	v_mfma_f32_16x16x32_bf16 v[56:59], v[24:27], v[56:59], 0
	v_mfma_f32_16x16x32_bf16 v[52:55], v[20:23], v[60:63], v[52:55]
	v_mfma_f32_16x16x32_bf16 v[56:59], v[28:31], v[60:63], v[56:59]
	s_barrier
	v_lshl_add_u64 v[204:205], s[48:49], 0, v[130:131]
	s_mov_b32 m0, s15
	v_lshl_add_u64 v[140:141], v[204:205], 0, s[26:27]
	v_lshl_add_u64 v[206:207], s[48:49], 0, v[128:129]
	s_add_u32 s60, s48, 0x10100
	global_load_lds_dwordx4 v[140:141], off
	v_lshl_add_u64 v[140:141], v[206:207], 0, s[26:27]
	s_mov_b32 m0, s50
	s_addc_u32 s61, s49, 0
	global_load_lds_dwordx4 v[140:141], off
	v_lshl_add_u64 v[140:141], s[60:61], 0, v[130:131]
	s_mov_b32 m0, s51
	v_lshl_add_u64 v[208:209], s[46:47], 0, v[130:131]
	global_load_lds_dwordx4 v[140:141], off
	v_lshl_add_u64 v[140:141], s[60:61], 0, v[128:129]
	s_mov_b32 m0, s52
	v_lshl_add_u64 v[210:211], s[46:47], 0, v[128:129]
	global_load_lds_dwordx4 v[140:141], off
	v_lshl_add_u64 v[140:141], v[208:209], 0, s[26:27]
	s_mov_b32 m0, s74
	s_nop 0
	global_load_lds_dwordx4 v[140:141], off
	v_lshl_add_u64 v[140:141], v[210:211], 0, s[26:27]
	s_mov_b32 m0, s66
	s_nop 0
	global_load_lds_dwordx4 v[140:141], off
	ds_read_b128 v[60:63], v136 offset:16384
	ds_read_b128 v[100:103], v136 offset:17408
	ds_read_b128 v[104:107], v136 offset:18432
	ds_read_b128 v[108:111], v136 offset:19456
	ds_read_b128 v[112:115], v136 offset:20480
	ds_read_b128 v[116:119], v136 offset:21504
	ds_read_b128 v[120:123], v136 offset:22528
	ds_read_b128 v[124:127], v136 offset:23552
	s_waitcnt vmcnt(8)
	s_waitcnt lgkmcnt(0)
	s_barrier
; #define PG8_STAGE(bufoff, gbase, voff) do { _Pragma("unroll") for (int _i = 0; _i < 2; ++_i) \
;         __builtin_amdgcn_global_load_lds((const unsigned*)((const char*)(gbase) + (voff)[_i]), (PG8_LAS unsigned*)(lds + (bufoff) + ldsw + _i * 8192), 16, 0, 0); } while (0)
; #define PG8_LDA(dst, b, h) do { _Pragma("unroll") for (int m = 0; m < 4; ++m) _Pragma("unroll") for (int k = 0; k < 2; ++k) dst[m][k] = *(const PG8_LAS bf16x8*)(lds + PG8_SA(b, h) + aoff + m * 2048 + k * 1024); } while (0)
; #define PG8_LDB(dst, b, h) do { _Pragma("unroll") for (int n = 0; n < 2; ++n) _Pragma("unroll") for (int k = 0; k < 2; ++k) dst[n][k] = *(const PG8_LAS bf16x8*)(lds + PG8_SB(b, h) + boff + n * 2048 + k * 1024); } while (0)
; #define PG8_MMA(ai, bj, At, Bt) do { __builtin_amdgcn_s_setprio(1); _Pragma("unroll") for (int m = 0; m < 4; ++m) _Pragma("unroll") for (int n = 0; n < 2; ++n) _Pragma("unroll") for (int k = 0; k < 2; ++k) \
;         acc[ai][bj][m][n] = mma16<F16>(Bt[n][k], At[m][k], acc[ai][bj][m][n]); __builtin_amdgcn_s_setprio(0); } while (0)
; #define PG8_WAIT_V(n) asm volatile("s_waitcnt vmcnt(" #n ")" ::: "memory")
; #define PG8_WAIT_L(n) asm volatile("s_waitcnt lgkmcnt(" #n ")" ::: "memory")
; #define PG8_BAR __builtin_amdgcn_s_barrier()
; #define PG8_SCHED __builtin_amdgcn_sched_barrier(0)
; template <class Epi, class Sched, bool ALIGN_EPI = false, bool SP2 = false, bool F16 = false>
; __device__ __forceinline__ void gemm_phase(PG8_LAS unsigned char* lds, const Gemm g, const Sched& S, const Epi& E, const int wid_in) {
;     ...
;             PG8_WAIT_V(8); PG8_WAIT_L(0); PG8_BAR; PG8_MMA(1, 0, At, B0); PG8_MMA(1, 1, At, B1); PG8_BAR; PG8_SCHED;
;             PG8_LDB(B0, 1, 0); PG8_LDB(B1, 1, 1); PG8_SCHED; PG8_LDA(At, 1, 0); PG8_STAGE(PG8_SA(0, 1), a2 + hstep, voffA);
;             PG8_WAIT_V(8); PG8_WAIT_L(0); PG8_BAR; PG8_MMA(0, 0, At, B0); PG8_MMA(0, 1, At, B1); PG8_BAR; PG8_SCHED;
	s_waitcnt lgkmcnt(0)
	v_mfma_f32_16x16x32_bf16 v[140:143], v[0:3], v[60:63], 0
	v_mfma_f32_16x16x32_bf16 v[148:151], v[0:3], v[104:107], 0
	v_mfma_f32_16x16x32_bf16 v[156:159], v[0:3], v[112:115], 0
	v_mfma_f32_16x16x32_bf16 v[0:3], v[0:3], v[120:123], 0
	v_mfma_f32_16x16x32_bf16 v[140:143], v[4:7], v[100:103], v[140:143]
	v_mfma_f32_16x16x32_bf16 v[148:151], v[4:7], v[108:111], v[148:151]
	v_mfma_f32_16x16x32_bf16 v[156:159], v[4:7], v[116:119], v[156:159]
	v_mfma_f32_16x16x32_bf16 v[0:3], v[4:7], v[124:127], v[0:3]
	v_mfma_f32_16x16x32_bf16 v[4:7], v[8:11], v[120:123], 0
	v_mfma_f32_16x16x32_bf16 v[144:147], v[8:11], v[60:63], 0
	v_mfma_f32_16x16x32_bf16 v[152:155], v[8:11], v[104:107], 0
	v_mfma_f32_16x16x32_bf16 v[160:163], v[8:11], v[112:115], 0
	v_mfma_f32_16x16x32_bf16 v[4:7], v[12:15], v[124:127], v[4:7]
	v_mfma_f32_16x16x32_bf16 v[144:147], v[12:15], v[100:103], v[144:147]
	v_mfma_f32_16x16x32_bf16 v[152:155], v[12:15], v[108:111], v[152:155]
	v_mfma_f32_16x16x32_bf16 v[160:163], v[12:15], v[116:119], v[160:163]
	v_mfma_f32_16x16x32_bf16 v[8:11], v[16:19], v[60:63], 0
	v_mfma_f32_16x16x32_bf16 v[12:15], v[24:27], v[60:63], 0
	v_mfma_f32_16x16x32_bf16 v[8:11], v[20:23], v[100:103], v[8:11]
	v_mfma_f32_16x16x32_bf16 v[12:15], v[28:31], v[100:103], v[12:15]
	v_mfma_f32_16x16x32_bf16 v[60:63], v[16:19], v[104:107], 0
	v_mfma_f32_16x16x32_bf16 v[100:103], v[24:27], v[104:107], 0
	v_mfma_f32_16x16x32_bf16 v[104:107], v[16:19], v[112:115], 0
	v_mfma_f32_16x16x32_bf16 v[16:19], v[16:19], v[120:123], 0
	v_mfma_f32_16x16x32_bf16 v[60:63], v[20:23], v[108:111], v[60:63]
	v_mfma_f32_16x16x32_bf16 v[100:103], v[28:31], v[108:111], v[100:103]
	v_mfma_f32_16x16x32_bf16 v[104:107], v[20:23], v[116:119], v[104:107]
	v_mfma_f32_16x16x32_bf16 v[108:111], v[24:27], v[112:115], 0
	v_mfma_f32_16x16x32_bf16 v[16:19], v[20:23], v[124:127], v[16:19]
	v_mfma_f32_16x16x32_bf16 v[20:23], v[24:27], v[120:123], 0
	v_mfma_f32_16x16x32_bf16 v[108:111], v[28:31], v[116:119], v[108:111]
	v_mfma_f32_16x16x32_bf16 v[20:23], v[28:31], v[124:127], v[20:23]
	s_barrier
	s_add_u32 s60, s46, 0x10100
	s_addc_u32 s61, s47, 0
	s_mov_b32 m0, s90
	v_lshl_add_u64 v[212:213], s[60:61], 0, v[130:131]
	global_load_lds_dwordx4 v[212:213], off
	v_lshl_add_u64 v[212:213], s[60:61], 0, v[128:129]
	s_mov_b32 m0, s43
	s_nop 0
	global_load_lds_dwordx4 v[212:213], off
	ds_read_b128 v[24:27], v137
	ds_read_b128 v[28:31], v137 offset:1024
	ds_read_b128 v[112:115], v137 offset:2048
	ds_read_b128 v[116:119], v137 offset:3072
	ds_read_b128 v[120:123], v138
	ds_read_b128 v[124:127], v138 offset:1024
	ds_read_b128 v[164:167], v138 offset:2048
	ds_read_b128 v[168:171], v138 offset:3072
	ds_read_b128 v[172:175], v136 offset:32768
	ds_read_b128 v[176:179], v136 offset:33792
	ds_read_b128 v[180:183], v136 offset:34816
	ds_read_b128 v[184:187], v136 offset:35840
	ds_read_b128 v[188:191], v136 offset:36864
	ds_read_b128 v[192:195], v136 offset:37888
	ds_read_b128 v[196:199], v136 offset:38912
	ds_read_b128 v[200:203], v136 offset:39936
	s_waitcnt vmcnt(8)
	s_waitcnt lgkmcnt(0)
	s_barrier
	s_waitcnt lgkmcnt(0)
	v_mfma_f32_16x16x32_bf16 v[64:67], v[24:27], v[172:175], v[64:67]
	v_mfma_f32_16x16x32_bf16 v[68:71], v[112:115], v[172:175], v[68:71]
	v_mfma_f32_16x16x32_bf16 v[72:75], v[24:27], v[180:183], v[72:75]
	v_mfma_f32_16x16x32_bf16 v[76:79], v[112:115], v[180:183], v[76:79]
	v_mfma_f32_16x16x32_bf16 v[80:83], v[24:27], v[188:191], v[80:83]
	v_mfma_f32_16x16x32_bf16 v[84:87], v[112:115], v[188:191], v[84:87]
	v_mfma_f32_16x16x32_bf16 v[88:91], v[24:27], v[196:199], v[88:91]
	v_mfma_f32_16x16x32_bf16 v[92:95], v[112:115], v[196:199], v[92:95]
	v_mfma_f32_16x16x32_bf16 v[64:67], v[28:31], v[176:179], v[64:67]
	v_mfma_f32_16x16x32_bf16 v[68:71], v[116:119], v[176:179], v[68:71]
	v_mfma_f32_16x16x32_bf16 v[72:75], v[28:31], v[184:187], v[72:75]
	v_mfma_f32_16x16x32_bf16 v[76:79], v[116:119], v[184:187], v[76:79]
	v_mfma_f32_16x16x32_bf16 v[80:83], v[28:31], v[192:195], v[80:83]
	v_mfma_f32_16x16x32_bf16 v[84:87], v[116:119], v[192:195], v[84:87]
	v_mfma_f32_16x16x32_bf16 v[88:91], v[28:31], v[200:203], v[88:91]
	v_mfma_f32_16x16x32_bf16 v[92:95], v[116:119], v[200:203], v[92:95]
	v_mfma_f32_16x16x32_bf16 v[96:99], v[120:123], v[172:175], v[96:99]
	v_mfma_f32_16x16x32_bf16 v[32:35], v[164:167], v[172:175], v[32:35]
	v_mfma_f32_16x16x32_bf16 v[36:39], v[120:123], v[180:183], v[36:39]
	v_mfma_f32_16x16x32_bf16 v[40:43], v[164:167], v[180:183], v[40:43]
	v_mfma_f32_16x16x32_bf16 v[44:47], v[120:123], v[188:191], v[44:47]
	v_mfma_f32_16x16x32_bf16 v[48:51], v[164:167], v[188:191], v[48:51]
	v_mfma_f32_16x16x32_bf16 v[52:55], v[120:123], v[196:199], v[52:55]
	v_mfma_f32_16x16x32_bf16 v[56:59], v[164:167], v[196:199], v[56:59]
	v_mfma_f32_16x16x32_bf16 v[96:99], v[124:127], v[176:179], v[96:99]
	v_mfma_f32_16x16x32_bf16 v[32:35], v[168:171], v[176:179], v[32:35]
	v_mfma_f32_16x16x32_bf16 v[36:39], v[124:127], v[184:187], v[36:39]
	v_mfma_f32_16x16x32_bf16 v[40:43], v[168:171], v[184:187], v[40:43]
	v_mfma_f32_16x16x32_bf16 v[44:47], v[124:127], v[192:195], v[44:47]
	v_mfma_f32_16x16x32_bf16 v[48:51], v[168:171], v[192:195], v[48:51]
	v_mfma_f32_16x16x32_bf16 v[52:55], v[124:127], v[200:203], v[52:55]
	v_mfma_f32_16x16x32_bf16 v[56:59], v[168:171], v[200:203], v[56:59]
	s_barrier
; #define PG8_STAGE(bufoff, gbase, voff) do { _Pragma("unroll") for (int _i = 0; _i < 2; ++_i) \
;         __builtin_amdgcn_global_load_lds((const unsigned*)((const char*)(gbase) + (voff)[_i]), (PG8_LAS unsigned*)(lds + (bufoff) + ldsw + _i * 8192), 16, 0, 0); } while (0)
; #define PG8_LDA(dst, b, h) do { _Pragma("unroll") for (int m = 0; m < 4; ++m) _Pragma("unroll") for (int k = 0; k < 2; ++k) dst[m][k] = *(const PG8_LAS bf16x8*)(lds + PG8_SA(b, h) + aoff + m * 2048 + k * 1024); } while (0)
; #define PG8_LDB(dst, b, h) do { _Pragma("unroll") for (int n = 0; n < 2; ++n) _Pragma("unroll") for (int k = 0; k < 2; ++k) dst[n][k] = *(const PG8_LAS bf16x8*)(lds + PG8_SB(b, h) + boff + n * 2048 + k * 1024); } while (0)
; #define PG8_MMA(ai, bj, At, Bt) do { __builtin_amdgcn_s_setprio(1); _Pragma("unroll") for (int m = 0; m < 4; ++m) _Pragma("unroll") for (int n = 0; n < 2; ++n) _Pragma("unroll") for (int k = 0; k < 2; ++k) \
;         acc[ai][bj][m][n] = mma16<F16>(Bt[n][k], At[m][k], acc[ai][bj][m][n]); __builtin_amdgcn_s_setprio(0); } while (0)
; #define PG8_WAIT_V(n) asm volatile("s_waitcnt vmcnt(" #n ")" ::: "memory")
; #define PG8_WAIT_L(n) asm volatile("s_waitcnt lgkmcnt(" #n ")" ::: "memory")
; #define PG8_BAR __builtin_amdgcn_s_barrier()
; #define PG8_SCHED __builtin_amdgcn_sched_barrier(0)
; template <class Epi, class Sched, bool ALIGN_EPI = false, bool SP2 = false, bool F16 = false>
; __device__ __forceinline__ void gemm_phase(PG8_LAS unsigned char* lds, const Gemm g, const Sched& S, const Epi& E, const int wid_in) {
;     ...
;             PG8_LDB(B0, 0, 0); PG8_LDB(B1, 0, 1); PG8_SCHED; PG8_LDA(At, 0, 0); PG8_STAGE(PG8_SA(1, 1), a1 + hstep, voffA);
;             PG8_WAIT_V(8); PG8_WAIT_L(0); PG8_BAR; PG8_MMA(0, 0, At, B0); PG8_MMA(0, 1, At, B1); PG8_BAR; PG8_SCHED;
;     ...
;             PG8_LDA(At, 1, 1); PG8_STAGE(PG8_SB(1, 0), b3, voffB); PG8_STAGE(PG8_SB(1, 1), b3 + hstep, voffB); PG8_STAGE(PG8_SA(1, 0), a3, voffA);
;             PG8_WAIT_V(8); PG8_WAIT_L(0); PG8_BAR; PG8_MMA(1, 0, At, B0); PG8_MMA(1, 1, At, B1); PG8_BAR; PG8_SCHED;
	s_mov_b32 m0, s53
	v_lshl_add_u64 v[204:205], v[204:205], 0, s[28:29]
	s_add_u32 s48, s48, 0x10180
	global_load_lds_dwordx4 v[204:205], off
	v_lshl_add_u64 v[204:205], v[206:207], 0, s[28:29]
	s_mov_b32 m0, s54
	s_addc_u32 s49, s49, 0
	global_load_lds_dwordx4 v[204:205], off
	v_lshl_add_u64 v[204:205], s[48:49], 0, v[130:131]
	s_mov_b32 m0, s55
	s_nop 0
	global_load_lds_dwordx4 v[204:205], off
	v_lshl_add_u64 v[204:205], s[48:49], 0, v[128:129]
	s_mov_b32 m0, s56
	s_nop 0
	global_load_lds_dwordx4 v[204:205], off
	v_lshl_add_u64 v[204:205], v[208:209], 0, s[28:29]
	s_mov_b32 m0, s75
	s_nop 0
	global_load_lds_dwordx4 v[204:205], off
	v_lshl_add_u64 v[204:205], v[210:211], 0, s[28:29]
	s_mov_b32 m0, s67
	s_nop 0
	global_load_lds_dwordx4 v[204:205], off
	ds_read_b128 v[172:175], v136 offset:49152
	ds_read_b128 v[176:179], v136 offset:50176
	ds_read_b128 v[180:183], v136 offset:51200
	ds_read_b128 v[184:187], v136 offset:52224
	ds_read_b128 v[188:191], v136 offset:53248
	ds_read_b128 v[192:195], v136 offset:54272
	ds_read_b128 v[196:199], v136 offset:55296
	ds_read_b128 v[200:203], v136 offset:56320
	s_waitcnt vmcnt(8)
	s_waitcnt lgkmcnt(0)
	s_barrier
	s_waitcnt lgkmcnt(0)
	v_mfma_f32_16x16x32_bf16 v[0:3], v[24:27], v[196:199], v[0:3]
	v_mfma_f32_16x16x32_bf16 v[4:7], v[112:115], v[196:199], v[4:7]
	v_mfma_f32_16x16x32_bf16 v[140:143], v[24:27], v[172:175], v[140:143]
	v_mfma_f32_16x16x32_bf16 v[144:147], v[112:115], v[172:175], v[144:147]
	v_mfma_f32_16x16x32_bf16 v[148:151], v[24:27], v[180:183], v[148:151]
	v_mfma_f32_16x16x32_bf16 v[152:155], v[112:115], v[180:183], v[152:155]
	v_mfma_f32_16x16x32_bf16 v[156:159], v[24:27], v[188:191], v[156:159]
	v_mfma_f32_16x16x32_bf16 v[160:163], v[112:115], v[188:191], v[160:163]
	v_mfma_f32_16x16x32_bf16 v[0:3], v[28:31], v[200:203], v[0:3]
	v_mfma_f32_16x16x32_bf16 v[4:7], v[116:119], v[200:203], v[4:7]
	v_mfma_f32_16x16x32_bf16 v[140:143], v[28:31], v[176:179], v[140:143]
	v_mfma_f32_16x16x32_bf16 v[144:147], v[116:119], v[176:179], v[144:147]
	v_mfma_f32_16x16x32_bf16 v[148:151], v[28:31], v[184:187], v[148:151]
	v_mfma_f32_16x16x32_bf16 v[152:155], v[116:119], v[184:187], v[152:155]
	v_mfma_f32_16x16x32_bf16 v[156:159], v[28:31], v[192:195], v[156:159]
	v_mfma_f32_16x16x32_bf16 v[160:163], v[116:119], v[192:195], v[160:163]
	v_mfma_f32_16x16x32_bf16 v[8:11], v[120:123], v[172:175], v[8:11]
	v_mfma_f32_16x16x32_bf16 v[12:15], v[164:167], v[172:175], v[12:15]
	v_mfma_f32_16x16x32_bf16 v[24:27], v[120:123], v[180:183], v[60:63]
	v_mfma_f32_16x16x32_bf16 v[28:31], v[164:167], v[180:183], v[100:103]
	v_mfma_f32_16x16x32_bf16 v[60:63], v[120:123], v[188:191], v[104:107]
	v_mfma_f32_16x16x32_bf16 v[100:103], v[164:167], v[188:191], v[108:111]
	v_mfma_f32_16x16x32_bf16 v[16:19], v[120:123], v[196:199], v[16:19]
	v_mfma_f32_16x16x32_bf16 v[20:23], v[164:167], v[196:199], v[20:23]
	v_mfma_f32_16x16x32_bf16 v[8:11], v[124:127], v[176:179], v[8:11]
	v_mfma_f32_16x16x32_bf16 v[12:15], v[168:171], v[176:179], v[12:15]
	v_mfma_f32_16x16x32_bf16 v[24:27], v[124:127], v[184:187], v[24:27]
	v_mfma_f32_16x16x32_bf16 v[28:31], v[168:171], v[184:187], v[28:31]
	v_mfma_f32_16x16x32_bf16 v[60:63], v[124:127], v[192:195], v[60:63]
	v_mfma_f32_16x16x32_bf16 v[100:103], v[168:171], v[192:195], v[100:103]
	v_mfma_f32_16x16x32_bf16 v[16:19], v[124:127], v[200:203], v[16:19]
	v_mfma_f32_16x16x32_bf16 v[20:23], v[168:171], v[200:203], v[20:23]
	s_barrier
	s_add_u32 s46, s46, 0x10180
	s_addc_u32 s47, s47, 0
	s_mov_b32 m0, s91
	v_lshl_add_u64 v[204:205], s[46:47], 0, v[130:131]
	global_load_lds_dwordx4 v[204:205], off
	v_lshl_add_u64 v[204:205], s[46:47], 0, v[128:129]
	s_mov_b32 m0, s14
	s_nop 0
	global_load_lds_dwordx4 v[204:205], off
	ds_read_b128 v[104:107], v134
	ds_read_b128 v[108:111], v134 offset:1024
	ds_read_b128 v[112:115], v134 offset:2048
	ds_read_b128 v[116:119], v134 offset:3072
	ds_read_b128 v[120:123], v135
	ds_read_b128 v[124:127], v135 offset:1024
	ds_read_b128 v[164:167], v135 offset:2048
	ds_read_b128 v[168:171], v135 offset:3072
	ds_read_b128 v[172:175], v136
	ds_read_b128 v[176:179], v136 offset:1024
	ds_read_b128 v[180:183], v136 offset:2048
	ds_read_b128 v[184:187], v136 offset:3072
	ds_read_b128 v[188:191], v136 offset:4096
	ds_read_b128 v[192:195], v136 offset:5120
	ds_read_b128 v[196:199], v136 offset:6144
	ds_read_b128 v[200:203], v136 offset:7168
	s_waitcnt vmcnt(8)
	s_waitcnt lgkmcnt(0)
	s_barrier
	s_waitcnt lgkmcnt(0)
	v_mfma_f32_16x16x32_bf16 v[64:67], v[104:107], v[172:175], v[64:67]
	v_mfma_f32_16x16x32_bf16 v[68:71], v[112:115], v[172:175], v[68:71]
	v_mfma_f32_16x16x32_bf16 v[72:75], v[104:107], v[180:183], v[72:75]
	v_mfma_f32_16x16x32_bf16 v[76:79], v[112:115], v[180:183], v[76:79]
	v_mfma_f32_16x16x32_bf16 v[80:83], v[104:107], v[188:191], v[80:83]
	v_mfma_f32_16x16x32_bf16 v[84:87], v[112:115], v[188:191], v[84:87]
	v_mfma_f32_16x16x32_bf16 v[88:91], v[104:107], v[196:199], v[88:91]
	v_mfma_f32_16x16x32_bf16 v[92:95], v[112:115], v[196:199], v[92:95]
	v_mfma_f32_16x16x32_bf16 v[64:67], v[108:111], v[176:179], v[64:67]
	v_mfma_f32_16x16x32_bf16 v[68:71], v[116:119], v[176:179], v[68:71]
	v_mfma_f32_16x16x32_bf16 v[72:75], v[108:111], v[184:187], v[72:75]
	v_mfma_f32_16x16x32_bf16 v[76:79], v[116:119], v[184:187], v[76:79]
	v_mfma_f32_16x16x32_bf16 v[80:83], v[108:111], v[192:195], v[80:83]
	v_mfma_f32_16x16x32_bf16 v[84:87], v[116:119], v[192:195], v[84:87]
	v_mfma_f32_16x16x32_bf16 v[88:91], v[108:111], v[200:203], v[88:91]
	v_mfma_f32_16x16x32_bf16 v[92:95], v[116:119], v[200:203], v[92:95]
	v_mfma_f32_16x16x32_bf16 v[32:35], v[164:167], v[172:175], v[32:35]
	v_mfma_f32_16x16x32_bf16 v[96:99], v[120:123], v[172:175], v[96:99]
	v_mfma_f32_16x16x32_bf16 v[172:175], v[168:171], v[176:179], v[32:35]
	v_mfma_f32_16x16x32_bf16 v[32:35], v[120:123], v[180:183], v[36:39]
	v_mfma_f32_16x16x32_bf16 v[204:207], v[124:127], v[176:179], v[96:99]
	v_mfma_f32_16x16x32_bf16 v[176:179], v[124:127], v[184:187], v[32:35]
	v_mfma_f32_16x16x32_bf16 v[32:35], v[164:167], v[180:183], v[40:43]
	v_mfma_f32_16x16x32_bf16 v[40:43], v[168:171], v[184:187], v[32:35]
	v_mfma_f32_16x16x32_bf16 v[32:35], v[120:123], v[188:191], v[44:47]
	v_mfma_f32_16x16x32_bf16 v[44:47], v[124:127], v[192:195], v[32:35]
	v_mfma_f32_16x16x32_bf16 v[32:35], v[164:167], v[188:191], v[48:51]
	v_mfma_f32_16x16x32_bf16 v[48:51], v[168:171], v[192:195], v[32:35]
	v_mfma_f32_16x16x32_bf16 v[32:35], v[120:123], v[196:199], v[52:55]
	v_mfma_f32_16x16x32_bf16 v[52:55], v[124:127], v[200:203], v[32:35]
	v_mfma_f32_16x16x32_bf16 v[32:35], v[164:167], v[196:199], v[56:59]
	v_mfma_f32_16x16x32_bf16 v[56:59], v[168:171], v[200:203], v[32:35]
	s_barrier
; #define PG8_STAGE(bufoff, gbase, voff) do { _Pragma("unroll") for (int _i = 0; _i < 2; ++_i) \
;         __builtin_amdgcn_global_load_lds((const unsigned*)((const char*)(gbase) + (voff)[_i]), (PG8_LAS unsigned*)(lds + (bufoff) + ldsw + _i * 8192), 16, 0, 0); } while (0)
; #define PG8_LDA(dst, b, h) do { _Pragma("unroll") for (int m = 0; m < 4; ++m) _Pragma("unroll") for (int k = 0; k < 2; ++k) dst[m][k] = *(const PG8_LAS bf16x8*)(lds + PG8_SA(b, h) + aoff + m * 2048 + k * 1024); } while (0)
; #define PG8_LDB(dst, b, h) do { _Pragma("unroll") for (int n = 0; n < 2; ++n) _Pragma("unroll") for (int k = 0; k < 2; ++k) dst[n][k] = *(const PG8_LAS bf16x8*)(lds + PG8_SB(b, h) + boff + n * 2048 + k * 1024); } while (0)
; #define PG8_MMA(ai, bj, At, Bt) do { __builtin_amdgcn_s_setprio(1); _Pragma("unroll") for (int m = 0; m < 4; ++m) _Pragma("unroll") for (int n = 0; n < 2; ++n) _Pragma("unroll") for (int k = 0; k < 2; ++k) \
;         acc[ai][bj][m][n] = mma16<F16>(Bt[n][k], At[m][k], acc[ai][bj][m][n]); __builtin_amdgcn_s_setprio(0); } while (0)
; #define PG8_WAIT_V(n) asm volatile("s_waitcnt vmcnt(" #n ")" ::: "memory")
; #define PG8_WAIT_L(n) asm volatile("s_waitcnt lgkmcnt(" #n ")" ::: "memory")
; #define PG8_BAR __builtin_amdgcn_s_barrier()
; #define PG8_SCHED __builtin_amdgcn_sched_barrier(0)
; template <class Epi, class Sched, bool ALIGN_EPI = false, bool SP2 = false, bool F16 = false>
; __device__ __forceinline__ void gemm_phase(PG8_LAS unsigned char* lds, const Gemm g, const Sched& S, const Epi& E, const int wid_in) {
;     ...
;             PG8_LDA(At, 0, 1); PG8_STAGE(PG8_SB(0, 0), b2, voffB); PG8_STAGE(PG8_SB(0, 1), b2 + hstep, voffB); PG8_STAGE(PG8_SA(0, 0), a2, voffA);
;             PG8_WAIT_V(8); PG8_WAIT_L(0); PG8_BAR; PG8_MMA(1, 0, At, B0); PG8_MMA(1, 1, At, B1); PG8_BAR; PG8_SCHED;
;             PG8_LDB(B0, 1, 0); PG8_LDB(B1, 1, 1); PG8_SCHED; PG8_LDA(At, 1, 0); PG8_STAGE(PG8_SA(0, 1), a2 + hstep, voffA);
	s_mov_b32 m0, s15
	v_lshl_add_u64 v[240:241], s[36:37], 0, v[130:131]
	s_add_u32 s46, s36, 0x10000
	s_nop 1
	global_load_lds_dwordx4 v[240:241], off
	v_lshl_add_u64 v[242:243], s[36:37], 0, v[128:129]
	s_mov_b32 m0, s50
	s_addc_u32 s47, s37, 0
	global_load_lds_dwordx4 v[242:243], off
	v_lshl_add_u64 v[200:201], s[46:47], 0, v[130:131]
	s_mov_b32 m0, s51
	v_lshl_add_u64 v[244:245], s[44:45], 0, v[130:131]
	global_load_lds_dwordx4 v[200:201], off
	v_lshl_add_u64 v[200:201], s[46:47], 0, v[128:129]
	s_mov_b32 m0, s52
	v_lshl_add_u64 v[246:247], s[44:45], 0, v[128:129]
	global_load_lds_dwordx4 v[200:201], off
	s_mov_b32 m0, s74
	s_nop 0
	global_load_lds_dwordx4 v[244:245], off
	s_mov_b32 m0, s66
	s_nop 0
	global_load_lds_dwordx4 v[246:247], off
	ds_read_b128 v[32:35], v136 offset:16384
	ds_read_b128 v[36:39], v136 offset:17408
	ds_read_b128 v[96:99], v136 offset:18432
	ds_read_b128 v[180:183], v136 offset:19456
	ds_read_b128 v[184:187], v136 offset:20480
	ds_read_b128 v[188:191], v136 offset:21504
	ds_read_b128 v[192:195], v136 offset:22528
	ds_read_b128 v[196:199], v136 offset:23552
	s_waitcnt vmcnt(8)
	s_waitcnt lgkmcnt(0)
	s_barrier
	s_waitcnt lgkmcnt(0)
	v_mfma_f32_16x16x32_bf16 v[0:3], v[104:107], v[192:195], v[0:3]
	v_mfma_f32_16x16x32_bf16 v[140:143], v[104:107], v[32:35], v[140:143]
	v_mfma_f32_16x16x32_bf16 v[144:147], v[112:115], v[32:35], v[144:147]
	v_mfma_f32_16x16x32_bf16 v[148:151], v[104:107], v[96:99], v[148:151]
	v_mfma_f32_16x16x32_bf16 v[152:155], v[112:115], v[96:99], v[152:155]
	v_mfma_f32_16x16x32_bf16 v[156:159], v[104:107], v[184:187], v[156:159]
	v_mfma_f32_16x16x32_bf16 v[160:163], v[112:115], v[184:187], v[160:163]
	v_mfma_f32_16x16x32_bf16 v[0:3], v[108:111], v[196:199], v[0:3]
	v_mfma_f32_16x16x32_bf16 v[4:7], v[112:115], v[192:195], v[4:7]
	v_mfma_f32_16x16x32_bf16 v[140:143], v[108:111], v[36:39], v[140:143]
	v_mfma_f32_16x16x32_bf16 v[144:147], v[116:119], v[36:39], v[144:147]
	v_mfma_f32_16x16x32_bf16 v[148:151], v[108:111], v[180:183], v[148:151]
	v_mfma_f32_16x16x32_bf16 v[152:155], v[116:119], v[180:183], v[152:155]
	v_mfma_f32_16x16x32_bf16 v[156:159], v[108:111], v[188:191], v[156:159]
	v_mfma_f32_16x16x32_bf16 v[160:163], v[116:119], v[188:191], v[160:163]
	v_mfma_f32_16x16x32_bf16 v[200:203], v[116:119], v[196:199], v[4:7]
	v_mfma_f32_16x16x32_bf16 v[4:7], v[120:123], v[32:35], v[8:11]
	v_mfma_f32_16x16x32_bf16 v[8:11], v[124:127], v[36:39], v[4:7]
	v_mfma_f32_16x16x32_bf16 v[4:7], v[164:167], v[32:35], v[12:15]
	v_mfma_f32_16x16x32_bf16 v[12:15], v[168:171], v[36:39], v[4:7]
	v_mfma_f32_16x16x32_bf16 v[4:7], v[120:123], v[96:99], v[24:27]
	v_mfma_f32_16x16x32_bf16 v[24:27], v[124:127], v[180:183], v[4:7]
	v_mfma_f32_16x16x32_bf16 v[4:7], v[164:167], v[96:99], v[28:31]
	v_mfma_f32_16x16x32_bf16 v[28:31], v[168:171], v[180:183], v[4:7]
	v_mfma_f32_16x16x32_bf16 v[4:7], v[120:123], v[184:187], v[60:63]
	v_mfma_f32_16x16x32_bf16 v[180:183], v[124:127], v[188:191], v[4:7]
	v_mfma_f32_16x16x32_bf16 v[4:7], v[164:167], v[184:187], v[100:103]
	v_mfma_f32_16x16x32_bf16 v[184:187], v[168:171], v[188:191], v[4:7]
	v_mfma_f32_16x16x32_bf16 v[4:7], v[120:123], v[192:195], v[16:19]
	v_mfma_f32_16x16x32_bf16 v[188:191], v[124:127], v[196:199], v[4:7]
	v_mfma_f32_16x16x32_bf16 v[4:7], v[164:167], v[192:195], v[20:23]
	v_mfma_f32_16x16x32_bf16 v[164:167], v[168:171], v[196:199], v[4:7]
	s_barrier
	s_nop 4
	s_add_u32 s44, s44, 0x10000
	s_addc_u32 s45, s45, 0
	s_mov_b32 m0, s90
	v_lshl_add_u64 v[32:33], s[44:45], 0, v[130:131]
	global_load_lds_dwordx4 v[32:33], off
	v_lshl_add_u64 v[32:33], s[44:45], 0, v[128:129]
	s_mov_b32 m0, s43
	s_nop 0
	global_load_lds_dwordx4 v[32:33], off
	ds_read_b128 v[4:7], v137
	ds_read_b128 v[60:63], v137 offset:1024
	ds_read_b128 v[168:171], v137 offset:2048
	ds_read_b128 v[192:195], v137 offset:3072
	ds_read_b128 v[196:199], v138
	ds_read_b128 v[208:211], v138 offset:1024
	ds_read_b128 v[212:215], v138 offset:2048
	ds_read_b128 v[216:219], v138 offset:3072
	ds_read_b128 v[16:19], v136 offset:32768
	ds_read_b128 v[20:23], v136 offset:33792
	ds_read_b128 v[104:107], v136 offset:34816
	ds_read_b128 v[220:223], v136 offset:35840
	ds_read_b128 v[224:227], v136 offset:36864
	ds_read_b128 v[228:231], v136 offset:37888
	ds_read_b128 v[232:235], v136 offset:38912
	ds_read_b128 v[236:239], v136 offset:39936
	s_waitcnt vmcnt(8)
	s_waitcnt lgkmcnt(0)
	s_barrier
; #define PG8_STAGE(bufoff, gbase, voff) do { _Pragma("unroll") for (int _i = 0; _i < 2; ++_i) \
;         __builtin_amdgcn_global_load_lds((const unsigned*)((const char*)(gbase) + (voff)[_i]), (PG8_LAS unsigned*)(lds + (bufoff) + ldsw + _i * 8192), 16, 0, 0); } while (0)
; #define PG8_LDA(dst, b, h) do { _Pragma("unroll") for (int m = 0; m < 4; ++m) _Pragma("unroll") for (int k = 0; k < 2; ++k) dst[m][k] = *(const PG8_LAS bf16x8*)(lds + PG8_SA(b, h) + aoff + m * 2048 + k * 1024); } while (0)
; #define PG8_LDB(dst, b, h) do { _Pragma("unroll") for (int n = 0; n < 2; ++n) _Pragma("unroll") for (int k = 0; k < 2; ++k) dst[n][k] = *(const PG8_LAS bf16x8*)(lds + PG8_SB(b, h) + boff + n * 2048 + k * 1024); } while (0)
; #define PG8_MMA(ai, bj, At, Bt) do { __builtin_amdgcn_s_setprio(1); _Pragma("unroll") for (int m = 0; m < 4; ++m) _Pragma("unroll") for (int n = 0; n < 2; ++n) _Pragma("unroll") for (int k = 0; k < 2; ++k) \
;         acc[ai][bj][m][n] = mma16<F16>(Bt[n][k], At[m][k], acc[ai][bj][m][n]); __builtin_amdgcn_s_setprio(0); } while (0)
; #define PG8_WAIT_V(n) asm volatile("s_waitcnt vmcnt(" #n ")" ::: "memory")
; #define PG8_WAIT_L(n) asm volatile("s_waitcnt lgkmcnt(" #n ")" ::: "memory")
; #define PG8_BAR __builtin_amdgcn_s_barrier()
; #define PG8_SCHED __builtin_amdgcn_sched_barrier(0)
; template <class Epi, class Sched, bool ALIGN_EPI = false, bool SP2 = false, bool F16 = false>
; __device__ __forceinline__ void gemm_phase(PG8_LAS unsigned char* lds, const Gemm g, const Sched& S, const Epi& E, const int wid_in) {
;     ...
;             PG8_LDB(B0, 1, 0); PG8_LDB(B1, 1, 1); PG8_SCHED; PG8_LDA(At, 1, 0); PG8_STAGE(PG8_SA(0, 1), a2 + hstep, voffA);
;             PG8_WAIT_V(8); PG8_WAIT_L(0); PG8_BAR; PG8_MMA(0, 0, At, B0); PG8_MMA(0, 1, At, B1); PG8_BAR; PG8_SCHED;
;             PG8_LDA(At, 1, 1); PG8_STAGE(PG8_SB(1, 0), b3, voffB); PG8_STAGE(PG8_SB(1, 1), b3 + hstep, voffB); PG8_STAGE(PG8_SA(1, 0), a3, voffA);
;             PG8_WAIT_V(8); PG8_WAIT_L(0); PG8_BAR; PG8_MMA(1, 0, At, B0); PG8_MMA(1, 1, At, B1); PG8_BAR; PG8_SCHED;
	s_waitcnt lgkmcnt(0)
	v_mfma_f32_16x16x32_bf16 v[32:35], v[4:7], v[16:19], v[64:67]
	v_mfma_f32_16x16x32_bf16 v[116:119], v[60:63], v[20:23], v[32:35]
	v_mfma_f32_16x16x32_bf16 v[32:35], v[168:171], v[16:19], v[68:71]
	v_mfma_f32_16x16x32_bf16 v[112:115], v[192:195], v[20:23], v[32:35]
	v_mfma_f32_16x16x32_bf16 v[32:35], v[4:7], v[104:107], v[72:75]
	v_mfma_f32_16x16x32_bf16 v[100:103], v[60:63], v[220:223], v[32:35]
	v_mfma_f32_16x16x32_bf16 v[32:35], v[168:171], v[104:107], v[76:79]
	v_mfma_f32_16x16x32_bf16 v[96:99], v[192:195], v[220:223], v[32:35]
	v_mfma_f32_16x16x32_bf16 v[32:35], v[4:7], v[224:227], v[80:83]
	v_mfma_f32_16x16x32_bf16 v[68:71], v[60:63], v[228:231], v[32:35]
	v_mfma_f32_16x16x32_bf16 v[32:35], v[168:171], v[224:227], v[84:87]
	v_mfma_f32_16x16x32_bf16 v[64:67], v[192:195], v[228:231], v[32:35]
	v_mfma_f32_16x16x32_bf16 v[32:35], v[4:7], v[232:235], v[88:91]
	v_mfma_f32_16x16x32_bf16 v[36:39], v[60:63], v[236:239], v[32:35]
	v_mfma_f32_16x16x32_bf16 v[32:35], v[168:171], v[232:235], v[92:95]
	v_mfma_f32_16x16x32_bf16 v[32:35], v[192:195], v[236:239], v[32:35]
	v_mfma_f32_16x16x32_bf16 v[72:75], v[196:199], v[16:19], v[204:207]
	v_mfma_f32_16x16x32_bf16 v[16:19], v[212:215], v[16:19], v[172:175]
	v_mfma_f32_16x16x32_bf16 v[120:123], v[216:219], v[20:23], v[16:19]
	v_mfma_f32_16x16x32_bf16 v[16:19], v[196:199], v[104:107], v[176:179]
	v_mfma_f32_16x16x32_bf16 v[108:111], v[208:211], v[220:223], v[16:19]
	v_mfma_f32_16x16x32_bf16 v[16:19], v[212:215], v[104:107], v[40:43]
	v_mfma_f32_16x16x32_bf16 v[104:107], v[216:219], v[220:223], v[16:19]
	v_mfma_f32_16x16x32_bf16 v[16:19], v[196:199], v[224:227], v[44:47]
	v_mfma_f32_16x16x32_bf16 v[80:83], v[208:211], v[228:231], v[16:19]
	v_mfma_f32_16x16x32_bf16 v[16:19], v[212:215], v[224:227], v[48:51]
	v_mfma_f32_16x16x32_bf16 v[124:127], v[208:211], v[20:23], v[72:75]
	v_mfma_f32_16x16x32_bf16 v[72:75], v[216:219], v[228:231], v[16:19]
	v_mfma_f32_16x16x32_bf16 v[16:19], v[196:199], v[232:235], v[52:55]
	v_mfma_f32_16x16x32_bf16 v[48:51], v[208:211], v[236:239], v[16:19]
	v_mfma_f32_16x16x32_bf16 v[16:19], v[212:215], v[232:235], v[56:59]
	v_mfma_f32_16x16x32_bf16 v[40:43], v[216:219], v[236:239], v[16:19]
	s_barrier
	s_mov_b32 m0, s53
	s_nop 3
	v_lshl_add_u64 v[16:17], v[240:241], 0, s[24:25]
	s_add_u32 s36, s36, 0x10080
	global_load_lds_dwordx4 v[16:17], off
	v_lshl_add_u64 v[16:17], v[242:243], 0, s[24:25]
	s_mov_b32 m0, s54
	s_addc_u32 s37, s37, 0
	global_load_lds_dwordx4 v[16:17], off
	v_lshl_add_u64 v[16:17], s[36:37], 0, v[130:131]
	s_mov_b32 m0, s55
	s_nop 0
	global_load_lds_dwordx4 v[16:17], off
	v_lshl_add_u64 v[16:17], s[36:37], 0, v[128:129]
	s_mov_b32 m0, s56
	s_nop 0
	global_load_lds_dwordx4 v[16:17], off
	v_lshl_add_u64 v[16:17], v[244:245], 0, s[24:25]
	s_mov_b32 m0, s75
	s_nop 0
	global_load_lds_dwordx4 v[16:17], off
	v_lshl_add_u64 v[16:17], v[246:247], 0, s[24:25]
	s_mov_b32 m0, s67
	s_nop 0
	global_load_lds_dwordx4 v[16:17], off
	ds_read_b128 v[56:59], v136 offset:49152
	ds_read_b128 v[88:91], v136 offset:50176
	ds_read_b128 v[172:175], v136 offset:51200
	ds_read_b128 v[176:179], v136 offset:52224
	ds_read_b128 v[204:207], v136 offset:53248
	ds_read_b128 v[220:223], v136 offset:54272
	ds_read_b128 v[224:227], v136 offset:55296
	ds_read_b128 v[228:231], v136 offset:56320
	s_waitcnt vmcnt(8)
	s_waitcnt lgkmcnt(0)
	s_barrier
	s_waitcnt lgkmcnt(0)
	v_mfma_f32_16x16x32_bf16 v[16:19], v[4:7], v[56:59], v[140:143]
	v_mfma_f32_16x16x32_bf16 v[84:87], v[60:63], v[88:91], v[16:19]
	v_mfma_f32_16x16x32_bf16 v[16:19], v[168:171], v[56:59], v[144:147]
	v_mfma_f32_16x16x32_bf16 v[76:79], v[192:195], v[88:91], v[16:19]
	v_mfma_f32_16x16x32_bf16 v[16:19], v[4:7], v[172:175], v[148:151]
	v_mfma_f32_16x16x32_bf16 v[52:55], v[60:63], v[176:179], v[16:19]
	v_mfma_f32_16x16x32_bf16 v[16:19], v[168:171], v[172:175], v[152:155]
	v_mfma_f32_16x16x32_bf16 v[44:47], v[192:195], v[176:179], v[16:19]
	v_mfma_f32_16x16x32_bf16 v[16:19], v[4:7], v[204:207], v[156:159]
	v_mfma_f32_16x16x32_bf16 v[0:3], v[4:7], v[224:227], v[0:3]
	v_mfma_f32_16x16x32_bf16 v[20:23], v[60:63], v[220:223], v[16:19]
	v_mfma_f32_16x16x32_bf16 v[16:19], v[168:171], v[204:207], v[160:163]
	v_mfma_f32_16x16x32_bf16 v[4:7], v[60:63], v[228:231], v[0:3]
	v_mfma_f32_16x16x32_bf16 v[0:3], v[168:171], v[224:227], v[200:203]
	v_mfma_f32_16x16x32_bf16 v[16:19], v[192:195], v[220:223], v[16:19]
	v_mfma_f32_16x16x32_bf16 v[0:3], v[192:195], v[228:231], v[0:3]
	v_mfma_f32_16x16x32_bf16 v[8:11], v[196:199], v[56:59], v[8:11]
	v_mfma_f32_16x16x32_bf16 v[92:95], v[208:211], v[88:91], v[8:11]
	v_mfma_f32_16x16x32_bf16 v[8:11], v[212:215], v[56:59], v[12:15]
	v_mfma_f32_16x16x32_bf16 v[88:91], v[216:219], v[88:91], v[8:11]
	v_mfma_f32_16x16x32_bf16 v[8:11], v[196:199], v[172:175], v[24:27]
	v_mfma_f32_16x16x32_bf16 v[60:63], v[208:211], v[176:179], v[8:11]
	v_mfma_f32_16x16x32_bf16 v[8:11], v[212:215], v[172:175], v[28:31]
	v_mfma_f32_16x16x32_bf16 v[56:59], v[216:219], v[176:179], v[8:11]
	v_mfma_f32_16x16x32_bf16 v[8:11], v[196:199], v[204:207], v[180:183]
	v_mfma_f32_16x16x32_bf16 v[28:31], v[208:211], v[220:223], v[8:11]
	v_mfma_f32_16x16x32_bf16 v[8:11], v[212:215], v[204:207], v[184:187]
	v_mfma_f32_16x16x32_bf16 v[24:27], v[216:219], v[220:223], v[8:11]
	v_mfma_f32_16x16x32_bf16 v[8:11], v[196:199], v[224:227], v[188:191]
	v_mfma_f32_16x16x32_bf16 v[12:15], v[208:211], v[228:231], v[8:11]
	v_mfma_f32_16x16x32_bf16 v[8:11], v[212:215], v[224:227], v[164:167]
	v_mfma_f32_16x16x32_bf16 v[8:11], v[216:219], v[228:231], v[8:11]
	s_barrier
	s_and_b64 vcc, exec, s[8:9]
	s_cbranch_vccnz .LBB0_1946
	s_barrier

; #define PG8_STAGE(bufoff, gbase, voff) do { _Pragma("unroll") for (int _i = 0; _i < 2; ++_i) \
;         __builtin_amdgcn_global_load_lds((const unsigned*)((const char*)(gbase) + (voff)[_i]), (PG8_LAS unsigned*)(lds + (bufoff) + ldsw + _i * 8192), 16, 0, 0); } while (0)
; #define PG8_LDA(dst, b, h) do { _Pragma("unroll") for (int m = 0; m < 4; ++m) _Pragma("unroll") for (int k = 0; k < 2; ++k) dst[m][k] = *(const PG8_LAS bf16x8*)(lds + PG8_SA(b, h) + aoff + m * 2048 + k * 1024); } while (0)
; #define PG8_LDB(dst, b, h) do { _Pragma("unroll") for (int n = 0; n < 2; ++n) _Pragma("unroll") for (int k = 0; k < 2; ++k) dst[n][k] = *(const PG8_LAS bf16x8*)(lds + PG8_SB(b, h) + boff + n * 2048 + k * 1024); } while (0)
; #define PG8_MMA(ai, bj, At, Bt) do { __builtin_amdgcn_s_setprio(1); _Pragma("unroll") for (int m = 0; m < 4; ++m) _Pragma("unroll") for (int n = 0; n < 2; ++n) _Pragma("unroll") for (int k = 0; k < 2; ++k) \
;         acc[ai][bj][m][n] = mma16<F16>(Bt[n][k], At[m][k], acc[ai][bj][m][n]); __builtin_amdgcn_s_setprio(0); } while (0)
; #define PG8_WAIT_V(n) asm volatile("s_waitcnt vmcnt(" #n ")" ::: "memory")
; #define PG8_BAR __builtin_amdgcn_s_barrier()
; template <class Epi, class Sched, bool ALIGN_EPI = false, bool SP2 = false, bool F16 = false>
; __device__ __forceinline__ void gemm_phase(PG8_LAS unsigned char* lds, const Gemm g, const Sched& S, const Epi& E, const int wid_in) {
;     ...
;         for (int t = 0; t < nt; t += 2) {
;             const bool last = (t == nt - 2);
;             const char* a1 = cA + (size_t)(t + 1) * kstep;
;             const char* a2 = last ? nA : cA + (size_t)(t + 2) * kstep; const char* b2 = last ? nB : cB + (size_t)(t + 2) * kstep;
;             const char* a3 = a2 + kstep; const char* b3 = b2 + kstep;
;             if (last && has_next) S.a_ready(nxt);
;             if constexpr (SP2) {
;             PG8_LDB(B0, 0, 0); PG8_LDB(B1, 0, 1); PG8_SCHED; PG8_LDA(At, 0, 0); PG8_STAGE(PG8_SA(1, 1), a1 + hstep, voffA);
;             PG8_WAIT_V(8); PG8_WAIT_L(0); PG8_BAR; PG8_MMA(0, 0, At, B0); PG8_MMA(0, 1, At, B1); PG8_BAR; PG8_SCHED;
;             PG8_LDA(At, 0, 1); PG8_STAGE(PG8_SB(0, 0), b2, voffB); PG8_STAGE(PG8_SB(0, 1), b2 + hstep, voffB); PG8_STAGE(PG8_SA(0, 0), a2, voffA);
;             PG8_WAIT_V(8); PG8_WAIT_L(0); PG8_BAR; PG8_MMA(1, 0, At, B0); PG8_MMA(1, 1, At, B1); PG8_BAR; PG8_SCHED;
.LBB0_2040:
	ds_read_b128 v[128:131], v189
	ds_read_b128 v[132:135], v189 offset:1024
	ds_read_b128 v[136:139], v189 offset:2048
	ds_read_b128 v[140:143], v189 offset:3072
	ds_read_b128 v[144:147], v190
	ds_read_b128 v[148:151], v190 offset:1024
	ds_read_b128 v[168:171], v190 offset:2048
	ds_read_b128 v[172:175], v190 offset:3072
	s_add_u32 s44, s36, 0x100
	s_addc_u32 s45, s37, 0
	s_cmp_eq_u32 s59, 40
	s_cselect_b32 s49, s13, s45
	s_cselect_b32 s48, s12, s44
	s_cselect_b32 s47, s35, s58
	s_cselect_b32 s46, s34, s43
	s_mov_b32 m0, s91
	v_lshl_add_u64 v[184:185], s[36:37], 0, v[160:161]
	ds_read_b128 v[176:179], v191
	ds_read_b128 v[180:183], v191 offset:1024
	ds_read_b128 v[192:195], v191 offset:2048
	ds_read_b128 v[196:199], v191 offset:3072
	ds_read_b128 v[200:203], v191 offset:4096
	ds_read_b128 v[204:207], v191 offset:5120
	ds_read_b128 v[208:211], v191 offset:6144
	ds_read_b128 v[212:215], v191 offset:7168
	global_load_lds_dwordx4 v[184:185], off
	v_lshl_add_u64 v[184:185], s[36:37], 0, v[162:163]
	s_add_i32 m0, s74, 0xe000
	s_nop 0
	global_load_lds_dwordx4 v[184:185], off
	s_waitcnt vmcnt(8)
	s_waitcnt lgkmcnt(0)
	s_barrier
	s_waitcnt lgkmcnt(0)
	v_mfma_f32_16x16x32_bf16 v[124:127], v[128:131], v[176:179], v[124:127]
	v_mfma_f32_16x16x32_bf16 v[120:123], v[136:139], v[176:179], v[120:123]
	v_mfma_f32_16x16x32_bf16 v[108:111], v[128:131], v[192:195], v[108:111]
	v_mfma_f32_16x16x32_bf16 v[104:107], v[136:139], v[192:195], v[104:107]
	v_mfma_f32_16x16x32_bf16 v[92:95], v[128:131], v[200:203], v[92:95]
	v_mfma_f32_16x16x32_bf16 v[88:91], v[136:139], v[200:203], v[88:91]
	v_mfma_f32_16x16x32_bf16 v[76:79], v[128:131], v[208:211], v[76:79]
	v_mfma_f32_16x16x32_bf16 v[72:75], v[136:139], v[208:211], v[72:75]
	v_mfma_f32_16x16x32_bf16 v[124:127], v[132:135], v[180:183], v[124:127]
	v_mfma_f32_16x16x32_bf16 v[120:123], v[140:143], v[180:183], v[120:123]
	v_mfma_f32_16x16x32_bf16 v[108:111], v[132:135], v[196:199], v[108:111]
	v_mfma_f32_16x16x32_bf16 v[104:107], v[140:143], v[196:199], v[104:107]
	v_mfma_f32_16x16x32_bf16 v[92:95], v[132:135], v[204:207], v[92:95]
	v_mfma_f32_16x16x32_bf16 v[88:91], v[140:143], v[204:207], v[88:91]
	v_mfma_f32_16x16x32_bf16 v[76:79], v[132:135], v[212:215], v[76:79]
	v_mfma_f32_16x16x32_bf16 v[72:75], v[140:143], v[212:215], v[72:75]
	v_mfma_f32_16x16x32_bf16 v[116:119], v[144:147], v[176:179], v[116:119]
	v_mfma_f32_16x16x32_bf16 v[112:115], v[168:171], v[176:179], v[112:115]
	v_mfma_f32_16x16x32_bf16 v[100:103], v[144:147], v[192:195], v[100:103]
	v_mfma_f32_16x16x32_bf16 v[96:99], v[168:171], v[192:195], v[96:99]
	v_mfma_f32_16x16x32_bf16 v[84:87], v[144:147], v[200:203], v[84:87]
	v_mfma_f32_16x16x32_bf16 v[80:83], v[168:171], v[200:203], v[80:83]
	v_mfma_f32_16x16x32_bf16 v[68:71], v[144:147], v[208:211], v[68:71]
	v_mfma_f32_16x16x32_bf16 v[64:67], v[168:171], v[208:211], v[64:67]
	v_mfma_f32_16x16x32_bf16 v[116:119], v[148:151], v[180:183], v[116:119]
	v_mfma_f32_16x16x32_bf16 v[112:115], v[172:175], v[180:183], v[112:115]
	v_mfma_f32_16x16x32_bf16 v[100:103], v[148:151], v[196:199], v[100:103]
	v_mfma_f32_16x16x32_bf16 v[96:99], v[172:175], v[196:199], v[96:99]
	v_mfma_f32_16x16x32_bf16 v[84:87], v[148:151], v[204:207], v[84:87]
	v_mfma_f32_16x16x32_bf16 v[80:83], v[172:175], v[204:207], v[80:83]
	v_mfma_f32_16x16x32_bf16 v[68:71], v[148:151], v[212:215], v[68:71]
	v_mfma_f32_16x16x32_bf16 v[64:67], v[172:175], v[212:215], v[64:67]
	s_barrier
	s_add_i32 s36, s53, s68
	v_lshl_add_u64 v[184:185], s[46:47], 0, v[154:155]
	s_mov_b32 m0, s36
	s_nop 0
	global_load_lds_dwordx4 v[184:185], off
	s_add_i32 m0, s36, 0x2000
	s_add_u32 s36, s46, 0xb0000
	v_lshl_add_u64 v[216:217], s[46:47], 0, v[158:159]
	s_addc_u32 s37, s47, 0
	s_add_i32 s60, s54, s68
	global_load_lds_dwordx4 v[216:217], off
	v_lshl_add_u64 v[218:219], s[36:37], 0, v[154:155]
	s_mov_b32 m0, s60
	v_lshl_add_u64 v[220:221], s[48:49], 0, v[156:157]
	global_load_lds_dwordx4 v[218:219], off
	v_lshl_add_u64 v[218:219], s[36:37], 0, v[158:159]
	s_add_i32 m0, s60, 0x2000
	s_nop 0
	global_load_lds_dwordx4 v[218:219], off
	v_lshl_add_u64 v[218:219], s[48:49], 0, v[152:153]
	s_mov_b32 m0, s74
	s_nop 0
	global_load_lds_dwordx4 v[218:219], off
	s_mov_b32 m0, s66
	s_nop 0
	global_load_lds_dwordx4 v[220:221], off
	ds_read_b128 v[176:179], v191 offset:16384
	ds_read_b128 v[180:183], v191 offset:17408
	ds_read_b128 v[192:195], v191 offset:18432
	ds_read_b128 v[196:199], v191 offset:19456
	ds_read_b128 v[200:203], v191 offset:20480
	ds_read_b128 v[204:207], v191 offset:21504
	ds_read_b128 v[208:211], v191 offset:22528
	ds_read_b128 v[212:215], v191 offset:23552
	s_waitcnt vmcnt(8)
	s_waitcnt lgkmcnt(0)
	s_barrier
; #define PG8_STAGE(bufoff, gbase, voff) do { _Pragma("unroll") for (int _i = 0; _i < 2; ++_i) \
;         __builtin_amdgcn_global_load_lds((const unsigned*)((const char*)(gbase) + (voff)[_i]), (PG8_LAS unsigned*)(lds + (bufoff) + ldsw + _i * 8192), 16, 0, 0); } while (0)
; #define PG8_LDA(dst, b, h) do { _Pragma("unroll") for (int m = 0; m < 4; ++m) _Pragma("unroll") for (int k = 0; k < 2; ++k) dst[m][k] = *(const PG8_LAS bf16x8*)(lds + PG8_SA(b, h) + aoff + m * 2048 + k * 1024); } while (0)
; #define PG8_LDB(dst, b, h) do { _Pragma("unroll") for (int n = 0; n < 2; ++n) _Pragma("unroll") for (int k = 0; k < 2; ++k) dst[n][k] = *(const PG8_LAS bf16x8*)(lds + PG8_SB(b, h) + boff + n * 2048 + k * 1024); } while (0)
; #define PG8_MMA(ai, bj, At, Bt) do { __builtin_amdgcn_s_setprio(1); _Pragma("unroll") for (int m = 0; m < 4; ++m) _Pragma("unroll") for (int n = 0; n < 2; ++n) _Pragma("unroll") for (int k = 0; k < 2; ++k) \
;         acc[ai][bj][m][n] = mma16<F16>(Bt[n][k], At[m][k], acc[ai][bj][m][n]); __builtin_amdgcn_s_setprio(0); } while (0)
; #define PG8_WAIT_V(n) asm volatile("s_waitcnt vmcnt(" #n ")" ::: "memory")
; #define PG8_WAIT_L(n) asm volatile("s_waitcnt lgkmcnt(" #n ")" ::: "memory")
; #define PG8_BAR __builtin_amdgcn_s_barrier()
; #define PG8_SCHED __builtin_amdgcn_sched_barrier(0)
; template <class Epi, class Sched, bool ALIGN_EPI = false, bool SP2 = false, bool F16 = false>
; __device__ __forceinline__ void gemm_phase(PG8_LAS unsigned char* lds, const Gemm g, const Sched& S, const Epi& E, const int wid_in) {
;     ...
;             PG8_WAIT_V(8); PG8_WAIT_L(0); PG8_BAR; PG8_MMA(1, 0, At, B0); PG8_MMA(1, 1, At, B1); PG8_BAR; PG8_SCHED;
;             PG8_LDB(B0, 1, 0); PG8_LDB(B1, 1, 1); PG8_SCHED; PG8_LDA(At, 1, 0); PG8_STAGE(PG8_SA(0, 1), a2 + hstep, voffA);
;             PG8_WAIT_V(8); PG8_WAIT_L(0); PG8_BAR; PG8_MMA(0, 0, At, B0); PG8_MMA(0, 1, At, B1); PG8_BAR; PG8_SCHED;
	s_waitcnt lgkmcnt(0)
	v_mfma_f32_16x16x32_bf16 v[60:63], v[128:131], v[176:179], v[60:63]
	v_mfma_f32_16x16x32_bf16 v[56:59], v[136:139], v[176:179], v[56:59]
	v_mfma_f32_16x16x32_bf16 v[44:47], v[128:131], v[192:195], v[44:47]
	v_mfma_f32_16x16x32_bf16 v[40:43], v[136:139], v[192:195], v[40:43]
	v_mfma_f32_16x16x32_bf16 v[28:31], v[128:131], v[200:203], v[28:31]
	v_mfma_f32_16x16x32_bf16 v[24:27], v[136:139], v[200:203], v[24:27]
	v_mfma_f32_16x16x32_bf16 v[12:15], v[128:131], v[208:211], v[12:15]
	v_mfma_f32_16x16x32_bf16 v[8:11], v[136:139], v[208:211], v[8:11]
	v_mfma_f32_16x16x32_bf16 v[60:63], v[132:135], v[180:183], v[60:63]
	v_mfma_f32_16x16x32_bf16 v[56:59], v[140:143], v[180:183], v[56:59]
	v_mfma_f32_16x16x32_bf16 v[44:47], v[132:135], v[196:199], v[44:47]
	v_mfma_f32_16x16x32_bf16 v[40:43], v[140:143], v[196:199], v[40:43]
	v_mfma_f32_16x16x32_bf16 v[28:31], v[132:135], v[204:207], v[28:31]
	v_mfma_f32_16x16x32_bf16 v[24:27], v[140:143], v[204:207], v[24:27]
	v_mfma_f32_16x16x32_bf16 v[12:15], v[132:135], v[212:215], v[12:15]
	v_mfma_f32_16x16x32_bf16 v[8:11], v[140:143], v[212:215], v[8:11]
	v_mfma_f32_16x16x32_bf16 v[52:55], v[144:147], v[176:179], v[52:55]
	v_mfma_f32_16x16x32_bf16 v[48:51], v[168:171], v[176:179], v[48:51]
	v_mfma_f32_16x16x32_bf16 v[36:39], v[144:147], v[192:195], v[36:39]
	v_mfma_f32_16x16x32_bf16 v[32:35], v[168:171], v[192:195], v[32:35]
	v_mfma_f32_16x16x32_bf16 v[20:23], v[144:147], v[200:203], v[20:23]
	v_mfma_f32_16x16x32_bf16 v[16:19], v[168:171], v[200:203], v[16:19]
	v_mfma_f32_16x16x32_bf16 v[4:7], v[144:147], v[208:211], v[4:7]
	v_mfma_f32_16x16x32_bf16 v[0:3], v[168:171], v[208:211], v[0:3]
	v_mfma_f32_16x16x32_bf16 v[52:55], v[148:151], v[180:183], v[52:55]
	v_mfma_f32_16x16x32_bf16 v[48:51], v[172:175], v[180:183], v[48:51]
	v_mfma_f32_16x16x32_bf16 v[36:39], v[148:151], v[196:199], v[36:39]
	v_mfma_f32_16x16x32_bf16 v[32:35], v[172:175], v[196:199], v[32:35]
	v_mfma_f32_16x16x32_bf16 v[20:23], v[148:151], v[204:207], v[20:23]
	v_mfma_f32_16x16x32_bf16 v[16:19], v[172:175], v[204:207], v[16:19]
	v_mfma_f32_16x16x32_bf16 v[4:7], v[148:151], v[212:215], v[4:7]
	v_mfma_f32_16x16x32_bf16 v[0:3], v[172:175], v[212:215], v[0:3]
	s_barrier
	s_add_i32 s60, 0, 0x18000
	s_add_i32 s61, 0, 0x1c000
	v_add_u32_e32 v140, s60, v188
	v_add_u32_e32 v172, s61, v188
	s_add_u32 s36, s48, 0xb0000
	s_addc_u32 s37, s49, 0
	s_mov_b32 m0, s90
	v_lshl_add_u64 v[222:223], s[36:37], 0, v[152:153]
	global_load_lds_dwordx4 v[222:223], off
	v_lshl_add_u64 v[222:223], s[36:37], 0, v[156:157]
	s_mov_b32 m0, s41
	s_nop 0
	global_load_lds_dwordx4 v[222:223], off
	ds_read_b128 v[128:131], v140
	ds_read_b128 v[132:135], v140 offset:1024
	ds_read_b128 v[136:139], v140 offset:2048
	ds_read_b128 v[140:143], v140 offset:3072
	ds_read_b128 v[144:147], v172
	ds_read_b128 v[148:151], v172 offset:1024
	ds_read_b128 v[168:171], v172 offset:2048
	ds_read_b128 v[172:175], v172 offset:3072
	ds_read_b128 v[176:179], v191 offset:32768
	ds_read_b128 v[180:183], v191 offset:33792
	ds_read_b128 v[192:195], v191 offset:34816
	ds_read_b128 v[196:199], v191 offset:35840
	ds_read_b128 v[200:203], v191 offset:36864
	ds_read_b128 v[204:207], v191 offset:37888
	ds_read_b128 v[208:211], v191 offset:38912
	ds_read_b128 v[212:215], v191 offset:39936
	s_waitcnt vmcnt(8)
	s_waitcnt lgkmcnt(0)
	s_barrier
	s_waitcnt lgkmcnt(0)
	v_mfma_f32_16x16x32_bf16 v[124:127], v[128:131], v[176:179], v[124:127]
	v_mfma_f32_16x16x32_bf16 v[120:123], v[136:139], v[176:179], v[120:123]
	v_mfma_f32_16x16x32_bf16 v[108:111], v[128:131], v[192:195], v[108:111]
	v_mfma_f32_16x16x32_bf16 v[104:107], v[136:139], v[192:195], v[104:107]
	v_mfma_f32_16x16x32_bf16 v[92:95], v[128:131], v[200:203], v[92:95]
	v_mfma_f32_16x16x32_bf16 v[88:91], v[136:139], v[200:203], v[88:91]
	v_mfma_f32_16x16x32_bf16 v[76:79], v[128:131], v[208:211], v[76:79]
	v_mfma_f32_16x16x32_bf16 v[72:75], v[136:139], v[208:211], v[72:75]
	v_mfma_f32_16x16x32_bf16 v[124:127], v[132:135], v[180:183], v[124:127]
	v_mfma_f32_16x16x32_bf16 v[120:123], v[140:143], v[180:183], v[120:123]
	v_mfma_f32_16x16x32_bf16 v[108:111], v[132:135], v[196:199], v[108:111]
	v_mfma_f32_16x16x32_bf16 v[104:107], v[140:143], v[196:199], v[104:107]
	v_mfma_f32_16x16x32_bf16 v[92:95], v[132:135], v[204:207], v[92:95]
	v_mfma_f32_16x16x32_bf16 v[88:91], v[140:143], v[204:207], v[88:91]
	v_mfma_f32_16x16x32_bf16 v[76:79], v[132:135], v[212:215], v[76:79]
	v_mfma_f32_16x16x32_bf16 v[72:75], v[140:143], v[212:215], v[72:75]
	v_mfma_f32_16x16x32_bf16 v[116:119], v[144:147], v[176:179], v[116:119]
	v_mfma_f32_16x16x32_bf16 v[112:115], v[168:171], v[176:179], v[112:115]
	v_mfma_f32_16x16x32_bf16 v[100:103], v[144:147], v[192:195], v[100:103]
	v_mfma_f32_16x16x32_bf16 v[96:99], v[168:171], v[192:195], v[96:99]
	v_mfma_f32_16x16x32_bf16 v[84:87], v[144:147], v[200:203], v[84:87]
	v_mfma_f32_16x16x32_bf16 v[80:83], v[168:171], v[200:203], v[80:83]
	v_mfma_f32_16x16x32_bf16 v[68:71], v[144:147], v[208:211], v[68:71]
	v_mfma_f32_16x16x32_bf16 v[64:67], v[168:171], v[208:211], v[64:67]
	v_mfma_f32_16x16x32_bf16 v[116:119], v[148:151], v[180:183], v[116:119]
	v_mfma_f32_16x16x32_bf16 v[112:115], v[172:175], v[180:183], v[112:115]
	v_mfma_f32_16x16x32_bf16 v[100:103], v[148:151], v[196:199], v[100:103]
	v_mfma_f32_16x16x32_bf16 v[96:99], v[172:175], v[196:199], v[96:99]
	v_mfma_f32_16x16x32_bf16 v[84:87], v[148:151], v[204:207], v[84:87]
	v_mfma_f32_16x16x32_bf16 v[80:83], v[172:175], v[204:207], v[80:83]
	v_mfma_f32_16x16x32_bf16 v[68:71], v[148:151], v[212:215], v[68:71]
	v_mfma_f32_16x16x32_bf16 v[64:67], v[172:175], v[212:215], v[64:67]
	s_barrier
; #define PG8_STAGE(bufoff, gbase, voff) do { _Pragma("unroll") for (int _i = 0; _i < 2; ++_i) \
;         __builtin_amdgcn_global_load_lds((const unsigned*)((const char*)(gbase) + (voff)[_i]), (PG8_LAS unsigned*)(lds + (bufoff) + ldsw + _i * 8192), 16, 0, 0); } while (0)
; #define PG8_LDA(dst, b, h) do { _Pragma("unroll") for (int m = 0; m < 4; ++m) _Pragma("unroll") for (int k = 0; k < 2; ++k) dst[m][k] = *(const PG8_LAS bf16x8*)(lds + PG8_SA(b, h) + aoff + m * 2048 + k * 1024); } while (0)
; #define PG8_MMA(ai, bj, At, Bt) do { __builtin_amdgcn_s_setprio(1); _Pragma("unroll") for (int m = 0; m < 4; ++m) _Pragma("unroll") for (int n = 0; n < 2; ++n) _Pragma("unroll") for (int k = 0; k < 2; ++k) \
;         acc[ai][bj][m][n] = mma16<F16>(Bt[n][k], At[m][k], acc[ai][bj][m][n]); __builtin_amdgcn_s_setprio(0); } while (0)
; #define PG8_WAIT_V(n) asm volatile("s_waitcnt vmcnt(" #n ")" ::: "memory")
; #define PG8_WAIT_L(n) asm volatile("s_waitcnt lgkmcnt(" #n ")" ::: "memory")
; #define PG8_BAR __builtin_amdgcn_s_barrier()
; #define PG8_SCHED __builtin_amdgcn_sched_barrier(0)
; template <class Epi, class Sched, bool ALIGN_EPI = false, bool SP2 = false, bool F16 = false>
; __device__ __forceinline__ void gemm_phase(PG8_LAS unsigned char* lds, const Gemm g, const Sched& S, const Epi& E, const int wid_in) {
;     ...
;             PG8_LDA(At, 1, 1); PG8_STAGE(PG8_SB(1, 0), b3, voffB); PG8_STAGE(PG8_SB(1, 1), b3 + hstep, voffB); PG8_STAGE(PG8_SA(1, 0), a3, voffA);
;             PG8_WAIT_V(8); PG8_WAIT_L(0); PG8_BAR; PG8_MMA(1, 0, At, B0); PG8_MMA(1, 1, At, B1); PG8_BAR; PG8_SCHED;
	s_add_i32 s36, s60, s68
	v_lshl_add_u64 v[184:185], v[184:185], 0, s[30:31]
	s_mov_b32 m0, s36
	s_nop 0
	global_load_lds_dwordx4 v[184:185], off
	s_add_i32 m0, s36, 0x2000
	s_add_u32 s36, s46, 0xb0080
	v_lshl_add_u64 v[184:185], v[216:217], 0, s[30:31]
	s_addc_u32 s37, s47, 0
	s_add_i32 s46, s61, s68
	global_load_lds_dwordx4 v[184:185], off
	v_lshl_add_u64 v[184:185], s[36:37], 0, v[154:155]
	s_mov_b32 m0, s46
	s_nop 0
	global_load_lds_dwordx4 v[184:185], off
	v_lshl_add_u64 v[184:185], s[36:37], 0, v[158:159]
	s_add_i32 m0, s46, 0x2000
	s_nop 0
	global_load_lds_dwordx4 v[184:185], off
	v_lshl_add_u64 v[184:185], v[218:219], 0, s[30:31]
	s_mov_b32 m0, s75
	s_nop 0
	global_load_lds_dwordx4 v[184:185], off
	v_lshl_add_u64 v[184:185], v[220:221], 0, s[30:31]
	s_mov_b32 m0, s67
	s_nop 0
	global_load_lds_dwordx4 v[184:185], off
	ds_read_b128 v[176:179], v191 offset:49152
	ds_read_b128 v[180:183], v191 offset:50176
	ds_read_b128 v[192:195], v191 offset:51200
	ds_read_b128 v[196:199], v191 offset:52224
	ds_read_b128 v[200:203], v191 offset:53248
	ds_read_b128 v[204:207], v191 offset:54272
	ds_read_b128 v[208:211], v191 offset:55296
	ds_read_b128 v[212:215], v191 offset:56320
	s_waitcnt vmcnt(8)
	s_waitcnt lgkmcnt(0)
	s_barrier
	s_waitcnt lgkmcnt(0)
	v_mfma_f32_16x16x32_bf16 v[60:63], v[128:131], v[176:179], v[60:63]
	v_mfma_f32_16x16x32_bf16 v[56:59], v[136:139], v[176:179], v[56:59]
	v_mfma_f32_16x16x32_bf16 v[44:47], v[128:131], v[192:195], v[44:47]
	v_mfma_f32_16x16x32_bf16 v[40:43], v[136:139], v[192:195], v[40:43]
	v_mfma_f32_16x16x32_bf16 v[28:31], v[128:131], v[200:203], v[28:31]
	v_mfma_f32_16x16x32_bf16 v[24:27], v[136:139], v[200:203], v[24:27]
	v_mfma_f32_16x16x32_bf16 v[12:15], v[128:131], v[208:211], v[12:15]
	v_mfma_f32_16x16x32_bf16 v[8:11], v[136:139], v[208:211], v[8:11]
	v_mfma_f32_16x16x32_bf16 v[60:63], v[132:135], v[180:183], v[60:63]
	v_mfma_f32_16x16x32_bf16 v[56:59], v[140:143], v[180:183], v[56:59]
	v_mfma_f32_16x16x32_bf16 v[44:47], v[132:135], v[196:199], v[44:47]
	v_mfma_f32_16x16x32_bf16 v[40:43], v[140:143], v[196:199], v[40:43]
	v_mfma_f32_16x16x32_bf16 v[28:31], v[132:135], v[204:207], v[28:31]
	v_mfma_f32_16x16x32_bf16 v[24:27], v[140:143], v[204:207], v[24:27]
	v_mfma_f32_16x16x32_bf16 v[12:15], v[132:135], v[212:215], v[12:15]
	v_mfma_f32_16x16x32_bf16 v[8:11], v[140:143], v[212:215], v[8:11]
	v_mfma_f32_16x16x32_bf16 v[52:55], v[144:147], v[176:179], v[52:55]
	v_mfma_f32_16x16x32_bf16 v[48:51], v[168:171], v[176:179], v[48:51]
	v_mfma_f32_16x16x32_bf16 v[36:39], v[144:147], v[192:195], v[36:39]
	v_mfma_f32_16x16x32_bf16 v[32:35], v[168:171], v[192:195], v[32:35]
	v_mfma_f32_16x16x32_bf16 v[20:23], v[144:147], v[200:203], v[20:23]
	v_mfma_f32_16x16x32_bf16 v[16:19], v[168:171], v[200:203], v[16:19]
	v_mfma_f32_16x16x32_bf16 v[4:7], v[144:147], v[208:211], v[4:7]
	v_mfma_f32_16x16x32_bf16 v[0:3], v[168:171], v[208:211], v[0:3]
	v_mfma_f32_16x16x32_bf16 v[52:55], v[148:151], v[180:183], v[52:55]
	v_mfma_f32_16x16x32_bf16 v[48:51], v[172:175], v[180:183], v[48:51]
	v_mfma_f32_16x16x32_bf16 v[36:39], v[148:151], v[196:199], v[36:39]
	v_mfma_f32_16x16x32_bf16 v[32:35], v[172:175], v[196:199], v[32:35]
	v_mfma_f32_16x16x32_bf16 v[20:23], v[148:151], v[204:207], v[20:23]
	v_mfma_f32_16x16x32_bf16 v[16:19], v[172:175], v[204:207], v[16:19]
	v_mfma_f32_16x16x32_bf16 v[4:7], v[148:151], v[212:215], v[4:7]
	v_mfma_f32_16x16x32_bf16 v[0:3], v[172:175], v[212:215], v[0:3]
	s_barrier
	s_add_i32 s59, s59, 2
	s_add_u32 s43, s43, 0x100
	s_addc_u32 s58, s58, 0
	s_cmp_gt_u32 s59, 41
	s_mov_b64 s[36:37], s[44:45]
	s_cbranch_scc0 .LBB0_2040
	s_and_b64 vcc, exec, s[16:17]
	s_cbranch_vccz .LBB0_2043
	s_barrier

; #define PG8_STAGE(bufoff, gbase, voff) do { _Pragma("unroll") for (int _i = 0; _i < 2; ++_i) \
;         __builtin_amdgcn_global_load_lds((const unsigned*)((const char*)(gbase) + (voff)[_i]), (PG8_LAS unsigned*)(lds + (bufoff) + ldsw + _i * 8192), 16, 0, 0); } while (0)
; #define PG8_LDA(dst, b, h) do { _Pragma("unroll") for (int m = 0; m < 4; ++m) _Pragma("unroll") for (int k = 0; k < 2; ++k) dst[m][k] = *(const PG8_LAS bf16x8*)(lds + PG8_SA(b, h) + aoff + m * 2048 + k * 1024); } while (0)
; #define PG8_LDB(dst, b, h) do { _Pragma("unroll") for (int n = 0; n < 2; ++n) _Pragma("unroll") for (int k = 0; k < 2; ++k) dst[n][k] = *(const PG8_LAS bf16x8*)(lds + PG8_SB(b, h) + boff + n * 2048 + k * 1024); } while (0)
; #define PG8_MMA(ai, bj, At, Bt) do { __builtin_amdgcn_s_setprio(1); _Pragma("unroll") for (int m = 0; m < 4; ++m) _Pragma("unroll") for (int n = 0; n < 2; ++n) _Pragma("unroll") for (int k = 0; k < 2; ++k) \
;         acc[ai][bj][m][n] = mma16<F16>(Bt[n][k], At[m][k], acc[ai][bj][m][n]); __builtin_amdgcn_s_setprio(0); } while (0)
; #define PG8_WAIT_V(n) asm volatile("s_waitcnt vmcnt(" #n ")" ::: "memory")
; #define PG8_BAR __builtin_amdgcn_s_barrier()
; template <class Epi, class Sched, bool ALIGN_EPI = false, bool SP2 = false, bool F16 = false>
; __device__ __forceinline__ void gemm_phase(PG8_LAS unsigned char* lds, const Gemm g, const Sched& S, const Epi& E, const int wid_in) {
;     ...
;         for (int t = 0; t < nt; t += 2) {
;             const bool last = (t == nt - 2);
;             const char* a1 = cA + (size_t)(t + 1) * kstep;
;             const char* a2 = last ? nA : cA + (size_t)(t + 2) * kstep; const char* b2 = last ? nB : cB + (size_t)(t + 2) * kstep;
;             const char* a3 = a2 + kstep; const char* b3 = b2 + kstep;
;             if (last && has_next) S.a_ready(nxt);
;             if constexpr (SP2) {
;             PG8_LDB(B0, 0, 0); PG8_LDB(B1, 0, 1); PG8_SCHED; PG8_LDA(At, 0, 0); PG8_STAGE(PG8_SA(1, 1), a1 + hstep, voffA);
;             PG8_WAIT_V(8); PG8_WAIT_L(0); PG8_BAR; PG8_MMA(0, 0, At, B0); PG8_MMA(0, 1, At, B1); PG8_BAR; PG8_SCHED;
;             PG8_LDA(At, 0, 1); PG8_STAGE(PG8_SB(0, 0), b2, voffB); PG8_STAGE(PG8_SB(0, 1), b2 + hstep, voffB); PG8_STAGE(PG8_SA(0, 0), a2, voffA);
;             PG8_WAIT_V(8); PG8_WAIT_L(0); PG8_BAR; PG8_MMA(1, 0, At, B0); PG8_MMA(1, 1, At, B1); PG8_BAR; PG8_SCHED;
.LBB0_2136:
	ds_read_b128 v[112:115], v235
	ds_read_b128 v[116:119], v235 offset:1024
	ds_read_b128 v[128:131], v235 offset:2048
	ds_read_b128 v[132:135], v235 offset:3072
	ds_read_b128 v[144:147], v236
	ds_read_b128 v[148:151], v236 offset:1024
	ds_read_b128 v[152:155], v236 offset:2048
	ds_read_b128 v[156:159], v236 offset:3072
	s_add_u32 s45, s52, 0xfffc0080
	s_addc_u32 s51, s53, -1
	s_cmp_eq_u32 s43, 12
	s_cselect_b32 s57, s14, s51
	s_cselect_b32 s56, s15, s45
	s_cselect_b32 s55, s37, s42
	s_cselect_b32 s54, s40, s41
	s_mov_b32 m0, s91
	v_lshl_add_u64 v[192:193], s[52:53], 0, v[204:205]
	ds_read_b128 v[160:163], v237
	ds_read_b128 v[164:167], v237 offset:1024
	ds_read_b128 v[168:171], v237 offset:2048
	ds_read_b128 v[172:175], v237 offset:3072
	ds_read_b128 v[176:179], v237 offset:4096
	ds_read_b128 v[180:183], v237 offset:5120
	ds_read_b128 v[184:187], v237 offset:6144
	ds_read_b128 v[188:191], v237 offset:7168
	global_load_lds_dwordx4 v[192:193], off
	v_lshl_add_u64 v[192:193], s[52:53], 0, v[206:207]
	s_add_i32 m0, s74, 0xe000
	s_nop 0
	global_load_lds_dwordx4 v[192:193], off
	s_waitcnt vmcnt(8)
	s_waitcnt lgkmcnt(0)
	s_barrier
	s_waitcnt lgkmcnt(0)
	v_mfma_f32_16x16x32_f16 v[140:143], v[112:115], v[160:163], v[140:143]
	v_mfma_f32_16x16x32_f16 v[136:139], v[128:131], v[160:163], v[136:139]
	v_mfma_f32_16x16x32_f16 v[108:111], v[112:115], v[168:171], v[108:111]
	v_mfma_f32_16x16x32_f16 v[104:107], v[128:131], v[168:171], v[104:107]
	v_mfma_f32_16x16x32_f16 v[92:95], v[112:115], v[176:179], v[92:95]
	v_mfma_f32_16x16x32_f16 v[88:91], v[128:131], v[176:179], v[88:91]
	v_mfma_f32_16x16x32_f16 v[76:79], v[112:115], v[184:187], v[76:79]
	v_mfma_f32_16x16x32_f16 v[72:75], v[128:131], v[184:187], v[72:75]
	v_mfma_f32_16x16x32_f16 v[140:143], v[116:119], v[164:167], v[140:143]
	v_mfma_f32_16x16x32_f16 v[136:139], v[132:135], v[164:167], v[136:139]
	v_mfma_f32_16x16x32_f16 v[108:111], v[116:119], v[172:175], v[108:111]
	v_mfma_f32_16x16x32_f16 v[104:107], v[132:135], v[172:175], v[104:107]
	v_mfma_f32_16x16x32_f16 v[92:95], v[116:119], v[180:183], v[92:95]
	v_mfma_f32_16x16x32_f16 v[88:91], v[132:135], v[180:183], v[88:91]
	v_mfma_f32_16x16x32_f16 v[76:79], v[116:119], v[188:191], v[76:79]
	v_mfma_f32_16x16x32_f16 v[72:75], v[132:135], v[188:191], v[72:75]
	v_mfma_f32_16x16x32_f16 v[124:127], v[144:147], v[160:163], v[124:127]
	v_mfma_f32_16x16x32_f16 v[120:123], v[152:155], v[160:163], v[120:123]
	v_mfma_f32_16x16x32_f16 v[100:103], v[144:147], v[168:171], v[100:103]
	v_mfma_f32_16x16x32_f16 v[96:99], v[152:155], v[168:171], v[96:99]
	v_mfma_f32_16x16x32_f16 v[84:87], v[144:147], v[176:179], v[84:87]
	v_mfma_f32_16x16x32_f16 v[80:83], v[152:155], v[176:179], v[80:83]
	v_mfma_f32_16x16x32_f16 v[68:71], v[144:147], v[184:187], v[68:71]
	v_mfma_f32_16x16x32_f16 v[64:67], v[152:155], v[184:187], v[64:67]
	v_mfma_f32_16x16x32_f16 v[124:127], v[148:151], v[164:167], v[124:127]
	v_mfma_f32_16x16x32_f16 v[120:123], v[156:159], v[164:167], v[120:123]
	v_mfma_f32_16x16x32_f16 v[100:103], v[148:151], v[172:175], v[100:103]
	v_mfma_f32_16x16x32_f16 v[96:99], v[156:159], v[172:175], v[96:99]
	v_mfma_f32_16x16x32_f16 v[84:87], v[148:151], v[180:183], v[84:87]
	v_mfma_f32_16x16x32_f16 v[80:83], v[156:159], v[180:183], v[80:83]
	v_mfma_f32_16x16x32_f16 v[68:71], v[148:151], v[188:191], v[68:71]
	v_mfma_f32_16x16x32_f16 v[64:67], v[156:159], v[188:191], v[64:67]
	s_barrier
	s_add_i32 s45, s63, s68
	v_lshl_add_u64 v[192:193], s[54:55], 0, v[198:199]
	s_mov_b32 m0, s45
	s_nop 0
	global_load_lds_dwordx4 v[192:193], off
	s_add_i32 m0, s45, 0x2000
	s_add_u32 s84, s54, 0x40000
	v_lshl_add_u64 v[194:195], s[54:55], 0, v[202:203]
	s_addc_u32 s85, s55, 0
	s_add_i32 s45, s64, s68
	global_load_lds_dwordx4 v[194:195], off
	v_lshl_add_u64 v[212:213], s[84:85], 0, v[198:199]
	s_mov_b32 m0, s45
	v_lshl_add_u64 v[214:215], s[56:57], 0, v[200:201]
	global_load_lds_dwordx4 v[212:213], off
	v_lshl_add_u64 v[212:213], s[84:85], 0, v[202:203]
	s_add_i32 m0, s45, 0x2000
	s_nop 0
	global_load_lds_dwordx4 v[212:213], off
	v_lshl_add_u64 v[212:213], s[56:57], 0, v[196:197]
	s_mov_b32 m0, s74
	s_nop 0
	global_load_lds_dwordx4 v[212:213], off
	s_mov_b32 m0, s66
	s_nop 0
	global_load_lds_dwordx4 v[214:215], off
	ds_read_b128 v[160:163], v237 offset:16384
	ds_read_b128 v[164:167], v237 offset:17408
	ds_read_b128 v[168:171], v237 offset:18432
	ds_read_b128 v[172:175], v237 offset:19456
	ds_read_b128 v[176:179], v237 offset:20480
	ds_read_b128 v[180:183], v237 offset:21504
	ds_read_b128 v[184:187], v237 offset:22528
	ds_read_b128 v[188:191], v237 offset:23552
	s_waitcnt vmcnt(8)
	s_waitcnt lgkmcnt(0)
	s_barrier
; #define PG8_STAGE(bufoff, gbase, voff) do { _Pragma("unroll") for (int _i = 0; _i < 2; ++_i) \
;         __builtin_amdgcn_global_load_lds((const unsigned*)((const char*)(gbase) + (voff)[_i]), (PG8_LAS unsigned*)(lds + (bufoff) + ldsw + _i * 8192), 16, 0, 0); } while (0)
; #define PG8_LDA(dst, b, h) do { _Pragma("unroll") for (int m = 0; m < 4; ++m) _Pragma("unroll") for (int k = 0; k < 2; ++k) dst[m][k] = *(const PG8_LAS bf16x8*)(lds + PG8_SA(b, h) + aoff + m * 2048 + k * 1024); } while (0)
; #define PG8_LDB(dst, b, h) do { _Pragma("unroll") for (int n = 0; n < 2; ++n) _Pragma("unroll") for (int k = 0; k < 2; ++k) dst[n][k] = *(const PG8_LAS bf16x8*)(lds + PG8_SB(b, h) + boff + n * 2048 + k * 1024); } while (0)
; #define PG8_MMA(ai, bj, At, Bt) do { __builtin_amdgcn_s_setprio(1); _Pragma("unroll") for (int m = 0; m < 4; ++m) _Pragma("unroll") for (int n = 0; n < 2; ++n) _Pragma("unroll") for (int k = 0; k < 2; ++k) \
;         acc[ai][bj][m][n] = mma16<F16>(Bt[n][k], At[m][k], acc[ai][bj][m][n]); __builtin_amdgcn_s_setprio(0); } while (0)
; #define PG8_WAIT_V(n) asm volatile("s_waitcnt vmcnt(" #n ")" ::: "memory")
; #define PG8_WAIT_L(n) asm volatile("s_waitcnt lgkmcnt(" #n ")" ::: "memory")
; #define PG8_BAR __builtin_amdgcn_s_barrier()
; #define PG8_SCHED __builtin_amdgcn_sched_barrier(0)
; template <class Epi, class Sched, bool ALIGN_EPI = false, bool SP2 = false, bool F16 = false>
; __device__ __forceinline__ void gemm_phase(PG8_LAS unsigned char* lds, const Gemm g, const Sched& S, const Epi& E, const int wid_in) {
;     ...
;             PG8_WAIT_V(8); PG8_WAIT_L(0); PG8_BAR; PG8_MMA(1, 0, At, B0); PG8_MMA(1, 1, At, B1); PG8_BAR; PG8_SCHED;
;             PG8_LDB(B0, 1, 0); PG8_LDB(B1, 1, 1); PG8_SCHED; PG8_LDA(At, 1, 0); PG8_STAGE(PG8_SA(0, 1), a2 + hstep, voffA);
;             PG8_WAIT_V(8); PG8_WAIT_L(0); PG8_BAR; PG8_MMA(0, 0, At, B0); PG8_MMA(0, 1, At, B1); PG8_BAR; PG8_SCHED;
	s_waitcnt lgkmcnt(0)
	v_mfma_f32_16x16x32_f16 v[60:63], v[112:115], v[160:163], v[60:63]
	v_mfma_f32_16x16x32_f16 v[56:59], v[128:131], v[160:163], v[56:59]
	v_mfma_f32_16x16x32_f16 v[44:47], v[112:115], v[168:171], v[44:47]
	v_mfma_f32_16x16x32_f16 v[40:43], v[128:131], v[168:171], v[40:43]
	v_mfma_f32_16x16x32_f16 v[28:31], v[112:115], v[176:179], v[28:31]
	v_mfma_f32_16x16x32_f16 v[24:27], v[128:131], v[176:179], v[24:27]
	v_mfma_f32_16x16x32_f16 v[12:15], v[112:115], v[184:187], v[12:15]
	v_mfma_f32_16x16x32_f16 v[8:11], v[128:131], v[184:187], v[8:11]
	v_mfma_f32_16x16x32_f16 v[60:63], v[116:119], v[164:167], v[60:63]
	v_mfma_f32_16x16x32_f16 v[56:59], v[132:135], v[164:167], v[56:59]
	v_mfma_f32_16x16x32_f16 v[44:47], v[116:119], v[172:175], v[44:47]
	v_mfma_f32_16x16x32_f16 v[40:43], v[132:135], v[172:175], v[40:43]
	v_mfma_f32_16x16x32_f16 v[28:31], v[116:119], v[180:183], v[28:31]
	v_mfma_f32_16x16x32_f16 v[24:27], v[132:135], v[180:183], v[24:27]
	v_mfma_f32_16x16x32_f16 v[12:15], v[116:119], v[188:191], v[12:15]
	v_mfma_f32_16x16x32_f16 v[8:11], v[132:135], v[188:191], v[8:11]
	v_mfma_f32_16x16x32_f16 v[52:55], v[144:147], v[160:163], v[52:55]
	v_mfma_f32_16x16x32_f16 v[48:51], v[152:155], v[160:163], v[48:51]
	v_mfma_f32_16x16x32_f16 v[36:39], v[144:147], v[168:171], v[36:39]
	v_mfma_f32_16x16x32_f16 v[32:35], v[152:155], v[168:171], v[32:35]
	v_mfma_f32_16x16x32_f16 v[20:23], v[144:147], v[176:179], v[20:23]
	v_mfma_f32_16x16x32_f16 v[16:19], v[152:155], v[176:179], v[16:19]
	v_mfma_f32_16x16x32_f16 v[4:7], v[144:147], v[184:187], v[4:7]
	v_mfma_f32_16x16x32_f16 v[0:3], v[152:155], v[184:187], v[0:3]
	v_mfma_f32_16x16x32_f16 v[52:55], v[148:151], v[164:167], v[52:55]
	v_mfma_f32_16x16x32_f16 v[48:51], v[156:159], v[164:167], v[48:51]
	v_mfma_f32_16x16x32_f16 v[36:39], v[148:151], v[172:175], v[36:39]
	v_mfma_f32_16x16x32_f16 v[32:35], v[156:159], v[172:175], v[32:35]
	v_mfma_f32_16x16x32_f16 v[20:23], v[148:151], v[180:183], v[20:23]
	v_mfma_f32_16x16x32_f16 v[16:19], v[156:159], v[180:183], v[16:19]
	v_mfma_f32_16x16x32_f16 v[4:7], v[148:151], v[188:191], v[4:7]
	v_mfma_f32_16x16x32_f16 v[0:3], v[156:159], v[188:191], v[0:3]
	s_barrier
	s_add_i32 s45, 0, 0x18000
	s_add_i32 s51, 0, 0x1c000
	v_add_u32_e32 v132, s45, v234
	v_add_u32_e32 v156, s51, v234
	s_add_u32 s56, s56, 0x40000
	s_addc_u32 s57, s57, 0
	s_mov_b32 m0, s90
	v_lshl_add_u64 v[216:217], s[56:57], 0, v[196:197]
	global_load_lds_dwordx4 v[216:217], off
	v_lshl_add_u64 v[216:217], s[56:57], 0, v[200:201]
	s_mov_b32 m0, s59
	s_nop 0
	global_load_lds_dwordx4 v[216:217], off
	ds_read_b128 v[112:115], v132
	ds_read_b128 v[116:119], v132 offset:1024
	ds_read_b128 v[128:131], v132 offset:2048
	ds_read_b128 v[132:135], v132 offset:3072
	ds_read_b128 v[144:147], v156
	ds_read_b128 v[148:151], v156 offset:1024
	ds_read_b128 v[152:155], v156 offset:2048
	ds_read_b128 v[156:159], v156 offset:3072
	ds_read_b128 v[160:163], v237 offset:32768
	ds_read_b128 v[164:167], v237 offset:33792
	ds_read_b128 v[168:171], v237 offset:34816
	ds_read_b128 v[172:175], v237 offset:35840
	ds_read_b128 v[176:179], v237 offset:36864
	ds_read_b128 v[180:183], v237 offset:37888
	ds_read_b128 v[184:187], v237 offset:38912
	ds_read_b128 v[188:191], v237 offset:39936
	s_waitcnt vmcnt(8)
	s_waitcnt lgkmcnt(0)
	s_barrier
	s_waitcnt lgkmcnt(0)
	v_mfma_f32_16x16x32_f16 v[140:143], v[112:115], v[160:163], v[140:143]
	v_mfma_f32_16x16x32_f16 v[136:139], v[128:131], v[160:163], v[136:139]
	v_mfma_f32_16x16x32_f16 v[108:111], v[112:115], v[168:171], v[108:111]
	v_mfma_f32_16x16x32_f16 v[104:107], v[128:131], v[168:171], v[104:107]
	v_mfma_f32_16x16x32_f16 v[92:95], v[112:115], v[176:179], v[92:95]
	v_mfma_f32_16x16x32_f16 v[88:91], v[128:131], v[176:179], v[88:91]
	v_mfma_f32_16x16x32_f16 v[76:79], v[112:115], v[184:187], v[76:79]
	v_mfma_f32_16x16x32_f16 v[72:75], v[128:131], v[184:187], v[72:75]
	v_mfma_f32_16x16x32_f16 v[140:143], v[116:119], v[164:167], v[140:143]
	v_mfma_f32_16x16x32_f16 v[136:139], v[132:135], v[164:167], v[136:139]
	v_mfma_f32_16x16x32_f16 v[108:111], v[116:119], v[172:175], v[108:111]
	v_mfma_f32_16x16x32_f16 v[104:107], v[132:135], v[172:175], v[104:107]
	v_mfma_f32_16x16x32_f16 v[92:95], v[116:119], v[180:183], v[92:95]
	v_mfma_f32_16x16x32_f16 v[88:91], v[132:135], v[180:183], v[88:91]
	v_mfma_f32_16x16x32_f16 v[76:79], v[116:119], v[188:191], v[76:79]
	v_mfma_f32_16x16x32_f16 v[72:75], v[132:135], v[188:191], v[72:75]
	v_mfma_f32_16x16x32_f16 v[124:127], v[144:147], v[160:163], v[124:127]
	v_mfma_f32_16x16x32_f16 v[120:123], v[152:155], v[160:163], v[120:123]
	v_mfma_f32_16x16x32_f16 v[100:103], v[144:147], v[168:171], v[100:103]
	v_mfma_f32_16x16x32_f16 v[96:99], v[152:155], v[168:171], v[96:99]
	v_mfma_f32_16x16x32_f16 v[84:87], v[144:147], v[176:179], v[84:87]
	v_mfma_f32_16x16x32_f16 v[80:83], v[152:155], v[176:179], v[80:83]
	v_mfma_f32_16x16x32_f16 v[68:71], v[144:147], v[184:187], v[68:71]
	v_mfma_f32_16x16x32_f16 v[64:67], v[152:155], v[184:187], v[64:67]
	v_mfma_f32_16x16x32_f16 v[124:127], v[148:151], v[164:167], v[124:127]
	v_mfma_f32_16x16x32_f16 v[120:123], v[156:159], v[164:167], v[120:123]
	v_mfma_f32_16x16x32_f16 v[100:103], v[148:151], v[172:175], v[100:103]
	v_mfma_f32_16x16x32_f16 v[96:99], v[156:159], v[172:175], v[96:99]
	v_mfma_f32_16x16x32_f16 v[84:87], v[148:151], v[180:183], v[84:87]
	v_mfma_f32_16x16x32_f16 v[80:83], v[156:159], v[180:183], v[80:83]
	v_mfma_f32_16x16x32_f16 v[68:71], v[148:151], v[188:191], v[68:71]
	v_mfma_f32_16x16x32_f16 v[64:67], v[156:159], v[188:191], v[64:67]
	s_barrier
; #define PG8_STAGE(bufoff, gbase, voff) do { _Pragma("unroll") for (int _i = 0; _i < 2; ++_i) \
;         __builtin_amdgcn_global_load_lds((const unsigned*)((const char*)(gbase) + (voff)[_i]), (PG8_LAS unsigned*)(lds + (bufoff) + ldsw + _i * 8192), 16, 0, 0); } while (0)
; #define PG8_LDA(dst, b, h) do { _Pragma("unroll") for (int m = 0; m < 4; ++m) _Pragma("unroll") for (int k = 0; k < 2; ++k) dst[m][k] = *(const PG8_LAS bf16x8*)(lds + PG8_SA(b, h) + aoff + m * 2048 + k * 1024); } while (0)
; #define PG8_MMA(ai, bj, At, Bt) do { __builtin_amdgcn_s_setprio(1); _Pragma("unroll") for (int m = 0; m < 4; ++m) _Pragma("unroll") for (int n = 0; n < 2; ++n) _Pragma("unroll") for (int k = 0; k < 2; ++k) \
;         acc[ai][bj][m][n] = mma16<F16>(Bt[n][k], At[m][k], acc[ai][bj][m][n]); __builtin_amdgcn_s_setprio(0); } while (0)
; #define PG8_WAIT_V(n) asm volatile("s_waitcnt vmcnt(" #n ")" ::: "memory")
; #define PG8_WAIT_L(n) asm volatile("s_waitcnt lgkmcnt(" #n ")" ::: "memory")
; #define PG8_BAR __builtin_amdgcn_s_barrier()
; #define PG8_SCHED __builtin_amdgcn_sched_barrier(0)
; template <class Epi, class Sched, bool ALIGN_EPI = false, bool SP2 = false, bool F16 = false>
; __device__ __forceinline__ void gemm_phase(PG8_LAS unsigned char* lds, const Gemm g, const Sched& S, const Epi& E, const int wid_in) {
;     ...
;             PG8_LDA(At, 1, 1); PG8_STAGE(PG8_SB(1, 0), b3, voffB); PG8_STAGE(PG8_SB(1, 1), b3 + hstep, voffB); PG8_STAGE(PG8_SA(1, 0), a3, voffA);
;             PG8_WAIT_V(8); PG8_WAIT_L(0); PG8_BAR; PG8_MMA(1, 0, At, B0); PG8_MMA(1, 1, At, B1); PG8_BAR; PG8_SCHED;
	s_add_i32 s45, s45, s68
	v_lshl_add_u64 v[192:193], v[192:193], 0, s[34:35]
	s_mov_b32 m0, s45
	s_nop 0
	global_load_lds_dwordx4 v[192:193], off
	s_add_i32 m0, s45, 0x2000
	s_add_u32 s54, s54, 0x40080
	v_lshl_add_u64 v[192:193], v[194:195], 0, s[34:35]
	s_addc_u32 s55, s55, 0
	s_add_i32 s45, s51, s68
	global_load_lds_dwordx4 v[192:193], off
	v_lshl_add_u64 v[192:193], s[54:55], 0, v[198:199]
	s_mov_b32 m0, s45
	s_nop 0
	global_load_lds_dwordx4 v[192:193], off
	v_lshl_add_u64 v[192:193], s[54:55], 0, v[202:203]
	s_add_i32 m0, s45, 0x2000
	s_nop 0
	global_load_lds_dwordx4 v[192:193], off
	v_lshl_add_u64 v[192:193], v[212:213], 0, s[34:35]
	s_mov_b32 m0, s75
	s_nop 0
	global_load_lds_dwordx4 v[192:193], off
	v_lshl_add_u64 v[192:193], v[214:215], 0, s[34:35]
	s_mov_b32 m0, s67
	s_nop 0
	global_load_lds_dwordx4 v[192:193], off
	ds_read_b128 v[160:163], v237 offset:49152
	ds_read_b128 v[164:167], v237 offset:50176
	ds_read_b128 v[168:171], v237 offset:51200
	ds_read_b128 v[172:175], v237 offset:52224
	ds_read_b128 v[176:179], v237 offset:53248
	ds_read_b128 v[180:183], v237 offset:54272
	ds_read_b128 v[184:187], v237 offset:55296
	ds_read_b128 v[188:191], v237 offset:56320
	s_waitcnt vmcnt(8)
	s_waitcnt lgkmcnt(0)
	s_barrier
	s_waitcnt lgkmcnt(0)
	v_mfma_f32_16x16x32_f16 v[60:63], v[112:115], v[160:163], v[60:63]
	v_mfma_f32_16x16x32_f16 v[56:59], v[128:131], v[160:163], v[56:59]
	v_mfma_f32_16x16x32_f16 v[44:47], v[112:115], v[168:171], v[44:47]
	v_mfma_f32_16x16x32_f16 v[40:43], v[128:131], v[168:171], v[40:43]
	v_mfma_f32_16x16x32_f16 v[28:31], v[112:115], v[176:179], v[28:31]
	v_mfma_f32_16x16x32_f16 v[24:27], v[128:131], v[176:179], v[24:27]
	v_mfma_f32_16x16x32_f16 v[12:15], v[112:115], v[184:187], v[12:15]
	v_mfma_f32_16x16x32_f16 v[8:11], v[128:131], v[184:187], v[8:11]
	v_mfma_f32_16x16x32_f16 v[60:63], v[116:119], v[164:167], v[60:63]
	v_mfma_f32_16x16x32_f16 v[56:59], v[132:135], v[164:167], v[56:59]
	v_mfma_f32_16x16x32_f16 v[44:47], v[116:119], v[172:175], v[44:47]
	v_mfma_f32_16x16x32_f16 v[40:43], v[132:135], v[172:175], v[40:43]
	v_mfma_f32_16x16x32_f16 v[28:31], v[116:119], v[180:183], v[28:31]
	v_mfma_f32_16x16x32_f16 v[24:27], v[132:135], v[180:183], v[24:27]
	v_mfma_f32_16x16x32_f16 v[12:15], v[116:119], v[188:191], v[12:15]
	v_mfma_f32_16x16x32_f16 v[8:11], v[132:135], v[188:191], v[8:11]
	v_mfma_f32_16x16x32_f16 v[52:55], v[144:147], v[160:163], v[52:55]
	v_mfma_f32_16x16x32_f16 v[48:51], v[152:155], v[160:163], v[48:51]
	v_mfma_f32_16x16x32_f16 v[36:39], v[144:147], v[168:171], v[36:39]
	v_mfma_f32_16x16x32_f16 v[32:35], v[152:155], v[168:171], v[32:35]
	v_mfma_f32_16x16x32_f16 v[20:23], v[144:147], v[176:179], v[20:23]
	v_mfma_f32_16x16x32_f16 v[16:19], v[152:155], v[176:179], v[16:19]
	v_mfma_f32_16x16x32_f16 v[4:7], v[144:147], v[184:187], v[4:7]
	v_mfma_f32_16x16x32_f16 v[0:3], v[152:155], v[184:187], v[0:3]
	v_mfma_f32_16x16x32_f16 v[52:55], v[148:151], v[164:167], v[52:55]
	v_mfma_f32_16x16x32_f16 v[48:51], v[156:159], v[164:167], v[48:51]
	v_mfma_f32_16x16x32_f16 v[36:39], v[148:151], v[172:175], v[36:39]
	v_mfma_f32_16x16x32_f16 v[32:35], v[156:159], v[172:175], v[32:35]
	v_mfma_f32_16x16x32_f16 v[20:23], v[148:151], v[180:183], v[20:23]
	v_mfma_f32_16x16x32_f16 v[16:19], v[156:159], v[180:183], v[16:19]
	v_mfma_f32_16x16x32_f16 v[4:7], v[148:151], v[188:191], v[4:7]
	v_mfma_f32_16x16x32_f16 v[0:3], v[156:159], v[188:191], v[0:3]
	s_barrier
	s_add_i32 s43, s43, 2
	s_add_u32 s52, s52, 0x100
	s_addc_u32 s53, s53, 0
	s_add_u32 s41, s41, 0x100
	s_addc_u32 s42, s42, 0
	s_cmp_gt_u32 s43, 13
	s_cbranch_scc0 .LBB0_2136
	s_and_b64 vcc, exec, s[16:17]
	s_cbranch_vccz .LBB0_2139
	s_barrier

; #define PG8_STAGE(bufoff, gbase, voff) do { _Pragma("unroll") for (int _i = 0; _i < 2; ++_i) \
;         __builtin_amdgcn_global_load_lds((const unsigned*)((const char*)(gbase) + (voff)[_i]), (PG8_LAS unsigned*)(lds + (bufoff) + ldsw + _i * 8192), 16, 0, 0); } while (0)
; #define PG8_LDA(dst, b, h) do { _Pragma("unroll") for (int m = 0; m < 4; ++m) _Pragma("unroll") for (int k = 0; k < 2; ++k) dst[m][k] = *(const PG8_LAS bf16x8*)(lds + PG8_SA(b, h) + aoff + m * 2048 + k * 1024); } while (0)
; #define PG8_LDB(dst, b, h) do { _Pragma("unroll") for (int n = 0; n < 2; ++n) _Pragma("unroll") for (int k = 0; k < 2; ++k) dst[n][k] = *(const PG8_LAS bf16x8*)(lds + PG8_SB(b, h) + boff + n * 2048 + k * 1024); } while (0)
; #define PG8_MMA(ai, bj, At, Bt) do { __builtin_amdgcn_s_setprio(1); _Pragma("unroll") for (int m = 0; m < 4; ++m) _Pragma("unroll") for (int n = 0; n < 2; ++n) _Pragma("unroll") for (int k = 0; k < 2; ++k) \
;         acc[ai][bj][m][n] = mma16<F16>(Bt[n][k], At[m][k], acc[ai][bj][m][n]); __builtin_amdgcn_s_setprio(0); } while (0)
; #define PG8_WAIT_V(n) asm volatile("s_waitcnt vmcnt(" #n ")" ::: "memory")
; #define PG8_WAIT_L(n) asm volatile("s_waitcnt lgkmcnt(" #n ")" ::: "memory")
; template <class Epi, class Sched, bool ALIGN_EPI = false, bool SP2 = false, bool F16 = false>
; __device__ __forceinline__ void gemm_phase(PG8_LAS unsigned char* lds, const Gemm g, const Sched& S, const Epi& E, const int wid_in) {
;     ...
;             const bool last = (t == nt - 2);
;             const char* a1 = cA + (size_t)(t + 1) * kstep;
;             const char* a2 = last ? nA : cA + (size_t)(t + 2) * kstep; const char* b2 = last ? nB : cB + (size_t)(t + 2) * kstep;
;             const char* a3 = a2 + kstep; const char* b3 = b2 + kstep;
;             if (last && has_next) S.a_ready(nxt);
;             if constexpr (SP2) {
;             PG8_LDB(B0, 0, 0); PG8_LDB(B1, 0, 1); PG8_SCHED; PG8_LDA(At, 0, 0); PG8_STAGE(PG8_SA(1, 1), a1 + hstep, voffA);
;             PG8_WAIT_V(8); PG8_WAIT_L(0); PG8_BAR; PG8_MMA(0, 0, At, B0); PG8_MMA(0, 1, At, B1); PG8_BAR; PG8_SCHED;
;             PG8_LDA(At, 0, 1); PG8_STAGE(PG8_SB(0, 0), b2, voffB); PG8_STAGE(PG8_SB(0, 1), b2 + hstep, voffB); PG8_STAGE(PG8_SA(0, 0), a2, voffA);
;             PG8_WAIT_V(8); PG8_WAIT_L(0); PG8_BAR; PG8_MMA(1, 0, At, B0); PG8_MMA(1, 1, At, B1); PG8_BAR; PG8_SCHED;
.LBB0_2226:
	ds_read_b128 v[128:131], v183
	ds_read_b128 v[132:135], v183 offset:1024
	ds_read_b128 v[136:139], v183 offset:2048
	ds_read_b128 v[140:143], v183 offset:3072
	ds_read_b128 v[144:147], v184
	ds_read_b128 v[148:151], v184 offset:1024
	ds_read_b128 v[152:155], v184 offset:2048
	ds_read_b128 v[174:177], v184 offset:3072
	s_add_u32 s43, s48, 0xfffc0080
	s_addc_u32 s50, s49, -1
	s_cmp_eq_u32 s42, 12
	s_cselect_b32 s53, s13, s50
	s_cselect_b32 s52, s23, s43
	s_cselect_b32 s51, s35, s41
	s_cselect_b32 s50, s37, s40
	s_mov_b32 m0, s91
	v_lshl_add_u64 v[178:179], s[48:49], 0, v[166:167]
	ds_read_b128 v[188:191], v185
	ds_read_b128 v[192:195], v185 offset:1024
	ds_read_b128 v[196:199], v185 offset:2048
	ds_read_b128 v[200:203], v185 offset:3072
	ds_read_b128 v[204:207], v185 offset:4096
	ds_read_b128 v[208:211], v185 offset:5120
	ds_read_b128 v[212:215], v185 offset:6144
	ds_read_b128 v[216:219], v185 offset:7168
	global_load_lds_dwordx4 v[178:179], off
	v_lshl_add_u64 v[178:179], s[48:49], 0, v[168:169]
	s_add_i32 m0, s74, 0xe000
	s_nop 0
	global_load_lds_dwordx4 v[178:179], off
	s_waitcnt vmcnt(8)
	s_waitcnt lgkmcnt(0)
	s_barrier
	s_waitcnt lgkmcnt(0)
	v_mfma_f32_16x16x32_f16 v[124:127], v[128:131], v[188:191], v[124:127]
	v_mfma_f32_16x16x32_f16 v[120:123], v[136:139], v[188:191], v[120:123]
	v_mfma_f32_16x16x32_f16 v[108:111], v[128:131], v[196:199], v[108:111]
	v_mfma_f32_16x16x32_f16 v[104:107], v[136:139], v[196:199], v[104:107]
	v_mfma_f32_16x16x32_f16 v[92:95], v[128:131], v[204:207], v[92:95]
	v_mfma_f32_16x16x32_f16 v[88:91], v[136:139], v[204:207], v[88:91]
	v_mfma_f32_16x16x32_f16 v[76:79], v[128:131], v[212:215], v[76:79]
	v_mfma_f32_16x16x32_f16 v[72:75], v[136:139], v[212:215], v[72:75]
	v_mfma_f32_16x16x32_f16 v[124:127], v[132:135], v[192:195], v[124:127]
	v_mfma_f32_16x16x32_f16 v[120:123], v[140:143], v[192:195], v[120:123]
	v_mfma_f32_16x16x32_f16 v[108:111], v[132:135], v[200:203], v[108:111]
	v_mfma_f32_16x16x32_f16 v[104:107], v[140:143], v[200:203], v[104:107]
	v_mfma_f32_16x16x32_f16 v[92:95], v[132:135], v[208:211], v[92:95]
	v_mfma_f32_16x16x32_f16 v[88:91], v[140:143], v[208:211], v[88:91]
	v_mfma_f32_16x16x32_f16 v[76:79], v[132:135], v[216:219], v[76:79]
	v_mfma_f32_16x16x32_f16 v[72:75], v[140:143], v[216:219], v[72:75]
	v_mfma_f32_16x16x32_f16 v[116:119], v[144:147], v[188:191], v[116:119]
	v_mfma_f32_16x16x32_f16 v[112:115], v[152:155], v[188:191], v[112:115]
	v_mfma_f32_16x16x32_f16 v[100:103], v[144:147], v[196:199], v[100:103]
	v_mfma_f32_16x16x32_f16 v[96:99], v[152:155], v[196:199], v[96:99]
	v_mfma_f32_16x16x32_f16 v[84:87], v[144:147], v[204:207], v[84:87]
	v_mfma_f32_16x16x32_f16 v[80:83], v[152:155], v[204:207], v[80:83]
	v_mfma_f32_16x16x32_f16 v[68:71], v[144:147], v[212:215], v[68:71]
	v_mfma_f32_16x16x32_f16 v[64:67], v[152:155], v[212:215], v[64:67]
	v_mfma_f32_16x16x32_f16 v[116:119], v[148:151], v[192:195], v[116:119]
	v_mfma_f32_16x16x32_f16 v[112:115], v[174:177], v[192:195], v[112:115]
	v_mfma_f32_16x16x32_f16 v[100:103], v[148:151], v[200:203], v[100:103]
	v_mfma_f32_16x16x32_f16 v[96:99], v[174:177], v[200:203], v[96:99]
	v_mfma_f32_16x16x32_f16 v[84:87], v[148:151], v[208:211], v[84:87]
	v_mfma_f32_16x16x32_f16 v[80:83], v[174:177], v[208:211], v[80:83]
	v_mfma_f32_16x16x32_f16 v[68:71], v[148:151], v[216:219], v[68:71]
	v_mfma_f32_16x16x32_f16 v[64:67], v[174:177], v[216:219], v[64:67]
	s_barrier
	s_add_i32 s43, s84, s68
	v_lshl_add_u64 v[178:179], s[50:51], 0, v[158:159]
	s_mov_b32 m0, s43
	s_nop 0
	global_load_lds_dwordx4 v[178:179], off
	s_add_i32 m0, s43, 0x2000
	s_add_u32 s54, s50, 0x40000
	v_lshl_add_u64 v[220:221], s[50:51], 0, v[162:163]
	s_addc_u32 s55, s51, 0
	s_add_i32 s43, s93, s68
	global_load_lds_dwordx4 v[220:221], off
	v_lshl_add_u64 v[222:223], s[54:55], 0, v[158:159]
	s_mov_b32 m0, s43
	v_lshl_add_u64 v[224:225], s[52:53], 0, v[160:161]
	global_load_lds_dwordx4 v[222:223], off
	v_lshl_add_u64 v[222:223], s[54:55], 0, v[162:163]
	s_add_i32 m0, s43, 0x2000
	s_nop 0
	global_load_lds_dwordx4 v[222:223], off
	v_lshl_add_u64 v[222:223], s[52:53], 0, v[156:157]
	s_mov_b32 m0, s74
	s_nop 0
	global_load_lds_dwordx4 v[222:223], off
	s_mov_b32 m0, s66
	s_nop 0
	global_load_lds_dwordx4 v[224:225], off
	ds_read_b128 v[188:191], v185 offset:16384
	ds_read_b128 v[192:195], v185 offset:17408
	ds_read_b128 v[196:199], v185 offset:18432
	ds_read_b128 v[200:203], v185 offset:19456
	ds_read_b128 v[204:207], v185 offset:20480
	ds_read_b128 v[208:211], v185 offset:21504
	ds_read_b128 v[212:215], v185 offset:22528
	ds_read_b128 v[216:219], v185 offset:23552
	s_waitcnt vmcnt(8)
	s_waitcnt lgkmcnt(0)
	s_barrier
; #define PG8_STAGE(bufoff, gbase, voff) do { _Pragma("unroll") for (int _i = 0; _i < 2; ++_i) \
;         __builtin_amdgcn_global_load_lds((const unsigned*)((const char*)(gbase) + (voff)[_i]), (PG8_LAS unsigned*)(lds + (bufoff) + ldsw + _i * 8192), 16, 0, 0); } while (0)
; #define PG8_LDA(dst, b, h) do { _Pragma("unroll") for (int m = 0; m < 4; ++m) _Pragma("unroll") for (int k = 0; k < 2; ++k) dst[m][k] = *(const PG8_LAS bf16x8*)(lds + PG8_SA(b, h) + aoff + m * 2048 + k * 1024); } while (0)
; #define PG8_LDB(dst, b, h) do { _Pragma("unroll") for (int n = 0; n < 2; ++n) _Pragma("unroll") for (int k = 0; k < 2; ++k) dst[n][k] = *(const PG8_LAS bf16x8*)(lds + PG8_SB(b, h) + boff + n * 2048 + k * 1024); } while (0)
; #define PG8_MMA(ai, bj, At, Bt) do { __builtin_amdgcn_s_setprio(1); _Pragma("unroll") for (int m = 0; m < 4; ++m) _Pragma("unroll") for (int n = 0; n < 2; ++n) _Pragma("unroll") for (int k = 0; k < 2; ++k) \
;         acc[ai][bj][m][n] = mma16<F16>(Bt[n][k], At[m][k], acc[ai][bj][m][n]); __builtin_amdgcn_s_setprio(0); } while (0)
; #define PG8_WAIT_V(n) asm volatile("s_waitcnt vmcnt(" #n ")" ::: "memory")
; #define PG8_WAIT_L(n) asm volatile("s_waitcnt lgkmcnt(" #n ")" ::: "memory")
; #define PG8_BAR __builtin_amdgcn_s_barrier()
; #define PG8_SCHED __builtin_amdgcn_sched_barrier(0)
; template <class Epi, class Sched, bool ALIGN_EPI = false, bool SP2 = false, bool F16 = false>
; __device__ __forceinline__ void gemm_phase(PG8_LAS unsigned char* lds, const Gemm g, const Sched& S, const Epi& E, const int wid_in) {
;     ...
;             PG8_WAIT_V(8); PG8_WAIT_L(0); PG8_BAR; PG8_MMA(1, 0, At, B0); PG8_MMA(1, 1, At, B1); PG8_BAR; PG8_SCHED;
;             PG8_LDB(B0, 1, 0); PG8_LDB(B1, 1, 1); PG8_SCHED; PG8_LDA(At, 1, 0); PG8_STAGE(PG8_SA(0, 1), a2 + hstep, voffA);
;             PG8_WAIT_V(8); PG8_WAIT_L(0); PG8_BAR; PG8_MMA(0, 0, At, B0); PG8_MMA(0, 1, At, B1); PG8_BAR; PG8_SCHED;
	s_waitcnt lgkmcnt(0)
	v_mfma_f32_16x16x32_f16 v[60:63], v[128:131], v[188:191], v[60:63]
	v_mfma_f32_16x16x32_f16 v[56:59], v[136:139], v[188:191], v[56:59]
	v_mfma_f32_16x16x32_f16 v[44:47], v[128:131], v[196:199], v[44:47]
	v_mfma_f32_16x16x32_f16 v[40:43], v[136:139], v[196:199], v[40:43]
	v_mfma_f32_16x16x32_f16 v[28:31], v[128:131], v[204:207], v[28:31]
	v_mfma_f32_16x16x32_f16 v[24:27], v[136:139], v[204:207], v[24:27]
	v_mfma_f32_16x16x32_f16 v[12:15], v[128:131], v[212:215], v[12:15]
	v_mfma_f32_16x16x32_f16 v[8:11], v[136:139], v[212:215], v[8:11]
	v_mfma_f32_16x16x32_f16 v[60:63], v[132:135], v[192:195], v[60:63]
	v_mfma_f32_16x16x32_f16 v[56:59], v[140:143], v[192:195], v[56:59]
	v_mfma_f32_16x16x32_f16 v[44:47], v[132:135], v[200:203], v[44:47]
	v_mfma_f32_16x16x32_f16 v[40:43], v[140:143], v[200:203], v[40:43]
	v_mfma_f32_16x16x32_f16 v[28:31], v[132:135], v[208:211], v[28:31]
	v_mfma_f32_16x16x32_f16 v[24:27], v[140:143], v[208:211], v[24:27]
	v_mfma_f32_16x16x32_f16 v[12:15], v[132:135], v[216:219], v[12:15]
	v_mfma_f32_16x16x32_f16 v[8:11], v[140:143], v[216:219], v[8:11]
	v_mfma_f32_16x16x32_f16 v[52:55], v[144:147], v[188:191], v[52:55]
	v_mfma_f32_16x16x32_f16 v[48:51], v[152:155], v[188:191], v[48:51]
	v_mfma_f32_16x16x32_f16 v[36:39], v[144:147], v[196:199], v[36:39]
	v_mfma_f32_16x16x32_f16 v[32:35], v[152:155], v[196:199], v[32:35]
	v_mfma_f32_16x16x32_f16 v[20:23], v[144:147], v[204:207], v[20:23]
	v_mfma_f32_16x16x32_f16 v[16:19], v[152:155], v[204:207], v[16:19]
	v_mfma_f32_16x16x32_f16 v[4:7], v[144:147], v[212:215], v[4:7]
	v_mfma_f32_16x16x32_f16 v[0:3], v[152:155], v[212:215], v[0:3]
	v_mfma_f32_16x16x32_f16 v[52:55], v[148:151], v[192:195], v[52:55]
	v_mfma_f32_16x16x32_f16 v[48:51], v[174:177], v[192:195], v[48:51]
	v_mfma_f32_16x16x32_f16 v[36:39], v[148:151], v[200:203], v[36:39]
	v_mfma_f32_16x16x32_f16 v[32:35], v[174:177], v[200:203], v[32:35]
	v_mfma_f32_16x16x32_f16 v[20:23], v[148:151], v[208:211], v[20:23]
	v_mfma_f32_16x16x32_f16 v[16:19], v[174:177], v[208:211], v[16:19]
	v_mfma_f32_16x16x32_f16 v[4:7], v[148:151], v[216:219], v[4:7]
	v_mfma_f32_16x16x32_f16 v[0:3], v[174:177], v[216:219], v[0:3]
	s_barrier
	s_add_i32 s43, 0, 0x18000
	s_add_i32 s54, 0, 0x1c000
	v_add_u32_e32 v140, s43, v182
	v_add_u32_e32 v165, s54, v182
	s_add_u32 s52, s52, 0x40000
	s_addc_u32 s53, s53, 0
	s_mov_b32 m0, s90
	v_lshl_add_u64 v[226:227], s[52:53], 0, v[156:157]
	global_load_lds_dwordx4 v[226:227], off
	v_lshl_add_u64 v[226:227], s[52:53], 0, v[160:161]
	s_mov_b32 m0, s63
	s_nop 0
	global_load_lds_dwordx4 v[226:227], off
	ds_read_b128 v[128:131], v140
	ds_read_b128 v[132:135], v140 offset:1024
	ds_read_b128 v[136:139], v140 offset:2048
	ds_read_b128 v[140:143], v140 offset:3072
	ds_read_b128 v[144:147], v165
	ds_read_b128 v[148:151], v165 offset:1024
	ds_read_b128 v[152:155], v165 offset:2048
	ds_read_b128 v[174:177], v165 offset:3072
	ds_read_b128 v[188:191], v185 offset:32768
	ds_read_b128 v[192:195], v185 offset:33792
	ds_read_b128 v[196:199], v185 offset:34816
	ds_read_b128 v[200:203], v185 offset:35840
	ds_read_b128 v[204:207], v185 offset:36864
	ds_read_b128 v[208:211], v185 offset:37888
	ds_read_b128 v[212:215], v185 offset:38912
	ds_read_b128 v[216:219], v185 offset:39936
	s_waitcnt vmcnt(8)
	s_waitcnt lgkmcnt(0)
	s_barrier
	s_waitcnt lgkmcnt(0)
	v_mfma_f32_16x16x32_f16 v[124:127], v[128:131], v[188:191], v[124:127]
	v_mfma_f32_16x16x32_f16 v[120:123], v[136:139], v[188:191], v[120:123]
	v_mfma_f32_16x16x32_f16 v[108:111], v[128:131], v[196:199], v[108:111]
	v_mfma_f32_16x16x32_f16 v[104:107], v[136:139], v[196:199], v[104:107]
	v_mfma_f32_16x16x32_f16 v[92:95], v[128:131], v[204:207], v[92:95]
	v_mfma_f32_16x16x32_f16 v[88:91], v[136:139], v[204:207], v[88:91]
	v_mfma_f32_16x16x32_f16 v[76:79], v[128:131], v[212:215], v[76:79]
	v_mfma_f32_16x16x32_f16 v[72:75], v[136:139], v[212:215], v[72:75]
	v_mfma_f32_16x16x32_f16 v[124:127], v[132:135], v[192:195], v[124:127]
	v_mfma_f32_16x16x32_f16 v[120:123], v[140:143], v[192:195], v[120:123]
	v_mfma_f32_16x16x32_f16 v[108:111], v[132:135], v[200:203], v[108:111]
	v_mfma_f32_16x16x32_f16 v[104:107], v[140:143], v[200:203], v[104:107]
	v_mfma_f32_16x16x32_f16 v[92:95], v[132:135], v[208:211], v[92:95]
	v_mfma_f32_16x16x32_f16 v[88:91], v[140:143], v[208:211], v[88:91]
	v_mfma_f32_16x16x32_f16 v[76:79], v[132:135], v[216:219], v[76:79]
	v_mfma_f32_16x16x32_f16 v[72:75], v[140:143], v[216:219], v[72:75]
	v_mfma_f32_16x16x32_f16 v[116:119], v[144:147], v[188:191], v[116:119]
	v_mfma_f32_16x16x32_f16 v[112:115], v[152:155], v[188:191], v[112:115]
	v_mfma_f32_16x16x32_f16 v[100:103], v[144:147], v[196:199], v[100:103]
	v_mfma_f32_16x16x32_f16 v[96:99], v[152:155], v[196:199], v[96:99]
	v_mfma_f32_16x16x32_f16 v[84:87], v[144:147], v[204:207], v[84:87]
	v_mfma_f32_16x16x32_f16 v[80:83], v[152:155], v[204:207], v[80:83]
	v_mfma_f32_16x16x32_f16 v[68:71], v[144:147], v[212:215], v[68:71]
	v_mfma_f32_16x16x32_f16 v[64:67], v[152:155], v[212:215], v[64:67]
	v_mfma_f32_16x16x32_f16 v[116:119], v[148:151], v[192:195], v[116:119]
	v_mfma_f32_16x16x32_f16 v[112:115], v[174:177], v[192:195], v[112:115]
	v_mfma_f32_16x16x32_f16 v[100:103], v[148:151], v[200:203], v[100:103]
	v_mfma_f32_16x16x32_f16 v[96:99], v[174:177], v[200:203], v[96:99]
	v_mfma_f32_16x16x32_f16 v[84:87], v[148:151], v[208:211], v[84:87]
	v_mfma_f32_16x16x32_f16 v[80:83], v[174:177], v[208:211], v[80:83]
	v_mfma_f32_16x16x32_f16 v[68:71], v[148:151], v[216:219], v[68:71]
	v_mfma_f32_16x16x32_f16 v[64:67], v[174:177], v[216:219], v[64:67]
	s_barrier
; #define PG8_STAGE(bufoff, gbase, voff) do { _Pragma("unroll") for (int _i = 0; _i < 2; ++_i) \
;         __builtin_amdgcn_global_load_lds((const unsigned*)((const char*)(gbase) + (voff)[_i]), (PG8_LAS unsigned*)(lds + (bufoff) + ldsw + _i * 8192), 16, 0, 0); } while (0)
; #define PG8_LDA(dst, b, h) do { _Pragma("unroll") for (int m = 0; m < 4; ++m) _Pragma("unroll") for (int k = 0; k < 2; ++k) dst[m][k] = *(const PG8_LAS bf16x8*)(lds + PG8_SA(b, h) + aoff + m * 2048 + k * 1024); } while (0)
; #define PG8_MMA(ai, bj, At, Bt) do { __builtin_amdgcn_s_setprio(1); _Pragma("unroll") for (int m = 0; m < 4; ++m) _Pragma("unroll") for (int n = 0; n < 2; ++n) _Pragma("unroll") for (int k = 0; k < 2; ++k) \
;         acc[ai][bj][m][n] = mma16<F16>(Bt[n][k], At[m][k], acc[ai][bj][m][n]); __builtin_amdgcn_s_setprio(0); } while (0)
; #define PG8_WAIT_V(n) asm volatile("s_waitcnt vmcnt(" #n ")" ::: "memory")
; #define PG8_WAIT_L(n) asm volatile("s_waitcnt lgkmcnt(" #n ")" ::: "memory")
; #define PG8_BAR __builtin_amdgcn_s_barrier()
; #define PG8_SCHED __builtin_amdgcn_sched_barrier(0)
; template <class Epi, class Sched, bool ALIGN_EPI = false, bool SP2 = false, bool F16 = false>
; __device__ __forceinline__ void gemm_phase(PG8_LAS unsigned char* lds, const Gemm g, const Sched& S, const Epi& E, const int wid_in) {
;     ...
;             PG8_LDA(At, 1, 1); PG8_STAGE(PG8_SB(1, 0), b3, voffB); PG8_STAGE(PG8_SB(1, 1), b3 + hstep, voffB); PG8_STAGE(PG8_SA(1, 0), a3, voffA);
;             PG8_WAIT_V(8); PG8_WAIT_L(0); PG8_BAR; PG8_MMA(1, 0, At, B0); PG8_MMA(1, 1, At, B1); PG8_BAR; PG8_SCHED;
	s_add_i32 s43, s43, s68
	v_lshl_add_u64 v[178:179], v[178:179], 0, s[26:27]
	s_mov_b32 m0, s43
	s_nop 0
	global_load_lds_dwordx4 v[178:179], off
	s_add_i32 m0, s43, 0x2000
	s_add_u32 s50, s50, 0x40080
	v_lshl_add_u64 v[178:179], v[220:221], 0, s[26:27]
	s_addc_u32 s51, s51, 0
	s_add_i32 s43, s54, s68
	global_load_lds_dwordx4 v[178:179], off
	v_lshl_add_u64 v[178:179], s[50:51], 0, v[158:159]
	s_mov_b32 m0, s43
	s_nop 0
	global_load_lds_dwordx4 v[178:179], off
	v_lshl_add_u64 v[178:179], s[50:51], 0, v[162:163]
	s_add_i32 m0, s43, 0x2000
	s_nop 0
	global_load_lds_dwordx4 v[178:179], off
	v_lshl_add_u64 v[178:179], v[222:223], 0, s[26:27]
	s_mov_b32 m0, s75
	s_nop 0
	global_load_lds_dwordx4 v[178:179], off
	v_lshl_add_u64 v[178:179], v[224:225], 0, s[26:27]
	s_mov_b32 m0, s67
	s_nop 0
	global_load_lds_dwordx4 v[178:179], off
	ds_read_b128 v[188:191], v185 offset:49152
	ds_read_b128 v[192:195], v185 offset:50176
	ds_read_b128 v[196:199], v185 offset:51200
	ds_read_b128 v[200:203], v185 offset:52224
	ds_read_b128 v[204:207], v185 offset:53248
	ds_read_b128 v[208:211], v185 offset:54272
	ds_read_b128 v[212:215], v185 offset:55296
	ds_read_b128 v[216:219], v185 offset:56320
	s_waitcnt vmcnt(8)
	s_waitcnt lgkmcnt(0)
	s_barrier
	s_waitcnt lgkmcnt(0)
	v_mfma_f32_16x16x32_f16 v[60:63], v[128:131], v[188:191], v[60:63]
	v_mfma_f32_16x16x32_f16 v[56:59], v[136:139], v[188:191], v[56:59]
	v_mfma_f32_16x16x32_f16 v[44:47], v[128:131], v[196:199], v[44:47]
	v_mfma_f32_16x16x32_f16 v[40:43], v[136:139], v[196:199], v[40:43]
	v_mfma_f32_16x16x32_f16 v[28:31], v[128:131], v[204:207], v[28:31]
	v_mfma_f32_16x16x32_f16 v[24:27], v[136:139], v[204:207], v[24:27]
	v_mfma_f32_16x16x32_f16 v[12:15], v[128:131], v[212:215], v[12:15]
	v_mfma_f32_16x16x32_f16 v[8:11], v[136:139], v[212:215], v[8:11]
	v_mfma_f32_16x16x32_f16 v[60:63], v[132:135], v[192:195], v[60:63]
	v_mfma_f32_16x16x32_f16 v[56:59], v[140:143], v[192:195], v[56:59]
	v_mfma_f32_16x16x32_f16 v[44:47], v[132:135], v[200:203], v[44:47]
	v_mfma_f32_16x16x32_f16 v[40:43], v[140:143], v[200:203], v[40:43]
	v_mfma_f32_16x16x32_f16 v[28:31], v[132:135], v[208:211], v[28:31]
	v_mfma_f32_16x16x32_f16 v[24:27], v[140:143], v[208:211], v[24:27]
	v_mfma_f32_16x16x32_f16 v[12:15], v[132:135], v[216:219], v[12:15]
	v_mfma_f32_16x16x32_f16 v[8:11], v[140:143], v[216:219], v[8:11]
	v_mfma_f32_16x16x32_f16 v[52:55], v[144:147], v[188:191], v[52:55]
	v_mfma_f32_16x16x32_f16 v[48:51], v[152:155], v[188:191], v[48:51]
	v_mfma_f32_16x16x32_f16 v[36:39], v[144:147], v[196:199], v[36:39]
	v_mfma_f32_16x16x32_f16 v[32:35], v[152:155], v[196:199], v[32:35]
	v_mfma_f32_16x16x32_f16 v[20:23], v[144:147], v[204:207], v[20:23]
	v_mfma_f32_16x16x32_f16 v[16:19], v[152:155], v[204:207], v[16:19]
	v_mfma_f32_16x16x32_f16 v[4:7], v[144:147], v[212:215], v[4:7]
	v_mfma_f32_16x16x32_f16 v[0:3], v[152:155], v[212:215], v[0:3]
	v_mfma_f32_16x16x32_f16 v[52:55], v[148:151], v[192:195], v[52:55]
	v_mfma_f32_16x16x32_f16 v[48:51], v[174:177], v[192:195], v[48:51]
	v_mfma_f32_16x16x32_f16 v[36:39], v[148:151], v[200:203], v[36:39]
	v_mfma_f32_16x16x32_f16 v[32:35], v[174:177], v[200:203], v[32:35]
	v_mfma_f32_16x16x32_f16 v[20:23], v[148:151], v[208:211], v[20:23]
	v_mfma_f32_16x16x32_f16 v[16:19], v[174:177], v[208:211], v[16:19]
	v_mfma_f32_16x16x32_f16 v[4:7], v[148:151], v[216:219], v[4:7]
	v_mfma_f32_16x16x32_f16 v[0:3], v[174:177], v[216:219], v[0:3]
	s_barrier
	s_add_i32 s42, s42, 2
	s_add_u32 s48, s48, 0x100
	s_addc_u32 s49, s49, 0
	s_add_u32 s40, s40, 0x100
	s_addc_u32 s41, s41, 0
	s_cmp_gt_u32 s42, 13
	s_cbranch_scc0 .LBB0_2226
	s_and_b64 vcc, exec, s[16:17]
	s_cbranch_vccz .LBB0_2229
	s_barrier

; #define PG8_STAGE(bufoff, gbase, voff) do { _Pragma("unroll") for (int _i = 0; _i < 2; ++_i) \
;         __builtin_amdgcn_global_load_lds((const unsigned*)((const char*)(gbase) + (voff)[_i]), (PG8_LAS unsigned*)(lds + (bufoff) + ldsw + _i * 8192), 16, 0, 0); } while (0)
; #define PG8_LDA(dst, b, h) do { _Pragma("unroll") for (int m = 0; m < 4; ++m) _Pragma("unroll") for (int k = 0; k < 2; ++k) dst[m][k] = *(const PG8_LAS bf16x8*)(lds + PG8_SA(b, h) + aoff + m * 2048 + k * 1024); } while (0)
; #define PG8_LDB(dst, b, h) do { _Pragma("unroll") for (int n = 0; n < 2; ++n) _Pragma("unroll") for (int k = 0; k < 2; ++k) dst[n][k] = *(const PG8_LAS bf16x8*)(lds + PG8_SB(b, h) + boff + n * 2048 + k * 1024); } while (0)
; #define PG8_MMA(ai, bj, At, Bt) do { __builtin_amdgcn_s_setprio(1); _Pragma("unroll") for (int m = 0; m < 4; ++m) _Pragma("unroll") for (int n = 0; n < 2; ++n) _Pragma("unroll") for (int k = 0; k < 2; ++k) \
;         acc[ai][bj][m][n] = mma16<F16>(Bt[n][k], At[m][k], acc[ai][bj][m][n]); __builtin_amdgcn_s_setprio(0); } while (0)
; #define PG8_WAIT_V(n) asm volatile("s_waitcnt vmcnt(" #n ")" ::: "memory")
; #define PG8_WAIT_L(n) asm volatile("s_waitcnt lgkmcnt(" #n ")" ::: "memory")
; template <class Epi, class Sched, bool ALIGN_EPI = false, bool SP2 = false, bool F16 = false>
; __device__ __forceinline__ void gemm_phase(PG8_LAS unsigned char* lds, const Gemm g, const Sched& S, const Epi& E, const int wid_in) {
;     ...
;             const bool last = (t == nt - 2);
;             const char* a1 = cA + (size_t)(t + 1) * kstep;
;             const char* a2 = last ? nA : cA + (size_t)(t + 2) * kstep; const char* b2 = last ? nB : cB + (size_t)(t + 2) * kstep;
;             const char* a3 = a2 + kstep; const char* b3 = b2 + kstep;
;             if (last && has_next) S.a_ready(nxt);
;             if constexpr (SP2) {
;             PG8_LDB(B0, 0, 0); PG8_LDB(B1, 0, 1); PG8_SCHED; PG8_LDA(At, 0, 0); PG8_STAGE(PG8_SA(1, 1), a1 + hstep, voffA);
;             PG8_WAIT_V(8); PG8_WAIT_L(0); PG8_BAR; PG8_MMA(0, 0, At, B0); PG8_MMA(0, 1, At, B1); PG8_BAR; PG8_SCHED;
;             PG8_LDA(At, 0, 1); PG8_STAGE(PG8_SB(0, 0), b2, voffB); PG8_STAGE(PG8_SB(0, 1), b2 + hstep, voffB); PG8_STAGE(PG8_SA(0, 0), a2, voffA);
;             PG8_WAIT_V(8); PG8_WAIT_L(0); PG8_BAR; PG8_MMA(1, 0, At, B0); PG8_MMA(1, 1, At, B1); PG8_BAR; PG8_SCHED;
.LBB0_2489:
	ds_read_b128 v[128:131], v189
	ds_read_b128 v[132:135], v189 offset:1024
	ds_read_b128 v[136:139], v189 offset:2048
	ds_read_b128 v[140:143], v189 offset:3072
	ds_read_b128 v[144:147], v190
	ds_read_b128 v[148:151], v190 offset:1024
	ds_read_b128 v[168:171], v190 offset:2048
	ds_read_b128 v[172:175], v190 offset:3072
	s_add_u32 s44, s42, 0xfffc0080
	s_addc_u32 s45, s43, -1
	s_cmp_eq_u32 s59, 12
	s_cselect_b32 s47, s29, s45
	s_cselect_b32 s46, s37, s44
	s_cselect_b32 s45, s27, s58
	s_cselect_b32 s44, s56, s57
	s_mov_b32 m0, s91
	v_lshl_add_u64 v[184:185], s[42:43], 0, v[160:161]
	ds_read_b128 v[176:179], v191
	ds_read_b128 v[180:183], v191 offset:1024
	ds_read_b128 v[192:195], v191 offset:2048
	ds_read_b128 v[196:199], v191 offset:3072
	ds_read_b128 v[200:203], v191 offset:4096
	ds_read_b128 v[204:207], v191 offset:5120
	ds_read_b128 v[208:211], v191 offset:6144
	ds_read_b128 v[212:215], v191 offset:7168
	global_load_lds_dwordx4 v[184:185], off
	v_lshl_add_u64 v[184:185], s[42:43], 0, v[162:163]
	s_add_i32 m0, s74, 0xe000
	s_nop 0
	global_load_lds_dwordx4 v[184:185], off
	s_waitcnt vmcnt(8)
	s_waitcnt lgkmcnt(0)
	s_barrier
	s_waitcnt lgkmcnt(0)
	v_mfma_f32_16x16x32_bf16 v[124:127], v[128:131], v[176:179], v[124:127]
	v_mfma_f32_16x16x32_bf16 v[120:123], v[136:139], v[176:179], v[120:123]
	v_mfma_f32_16x16x32_bf16 v[108:111], v[128:131], v[192:195], v[108:111]
	v_mfma_f32_16x16x32_bf16 v[104:107], v[136:139], v[192:195], v[104:107]
	v_mfma_f32_16x16x32_bf16 v[92:95], v[128:131], v[200:203], v[92:95]
	v_mfma_f32_16x16x32_bf16 v[88:91], v[136:139], v[200:203], v[88:91]
	v_mfma_f32_16x16x32_bf16 v[76:79], v[128:131], v[208:211], v[76:79]
	v_mfma_f32_16x16x32_bf16 v[72:75], v[136:139], v[208:211], v[72:75]
	v_mfma_f32_16x16x32_bf16 v[124:127], v[132:135], v[180:183], v[124:127]
	v_mfma_f32_16x16x32_bf16 v[120:123], v[140:143], v[180:183], v[120:123]
	v_mfma_f32_16x16x32_bf16 v[108:111], v[132:135], v[196:199], v[108:111]
	v_mfma_f32_16x16x32_bf16 v[104:107], v[140:143], v[196:199], v[104:107]
	v_mfma_f32_16x16x32_bf16 v[92:95], v[132:135], v[204:207], v[92:95]
	v_mfma_f32_16x16x32_bf16 v[88:91], v[140:143], v[204:207], v[88:91]
	v_mfma_f32_16x16x32_bf16 v[76:79], v[132:135], v[212:215], v[76:79]
	v_mfma_f32_16x16x32_bf16 v[72:75], v[140:143], v[212:215], v[72:75]
	v_mfma_f32_16x16x32_bf16 v[116:119], v[144:147], v[176:179], v[116:119]
	v_mfma_f32_16x16x32_bf16 v[112:115], v[168:171], v[176:179], v[112:115]
	v_mfma_f32_16x16x32_bf16 v[100:103], v[144:147], v[192:195], v[100:103]
	v_mfma_f32_16x16x32_bf16 v[96:99], v[168:171], v[192:195], v[96:99]
	v_mfma_f32_16x16x32_bf16 v[84:87], v[144:147], v[200:203], v[84:87]
	v_mfma_f32_16x16x32_bf16 v[80:83], v[168:171], v[200:203], v[80:83]
	v_mfma_f32_16x16x32_bf16 v[68:71], v[144:147], v[208:211], v[68:71]
	v_mfma_f32_16x16x32_bf16 v[64:67], v[168:171], v[208:211], v[64:67]
	v_mfma_f32_16x16x32_bf16 v[116:119], v[148:151], v[180:183], v[116:119]
	v_mfma_f32_16x16x32_bf16 v[112:115], v[172:175], v[180:183], v[112:115]
	v_mfma_f32_16x16x32_bf16 v[100:103], v[148:151], v[196:199], v[100:103]
	v_mfma_f32_16x16x32_bf16 v[96:99], v[172:175], v[196:199], v[96:99]
	v_mfma_f32_16x16x32_bf16 v[84:87], v[148:151], v[204:207], v[84:87]
	v_mfma_f32_16x16x32_bf16 v[80:83], v[172:175], v[204:207], v[80:83]
	v_mfma_f32_16x16x32_bf16 v[68:71], v[148:151], v[212:215], v[68:71]
	v_mfma_f32_16x16x32_bf16 v[64:67], v[172:175], v[212:215], v[64:67]
	s_barrier
	s_add_i32 s60, s53, s68
	v_lshl_add_u64 v[184:185], s[44:45], 0, v[154:155]
	s_mov_b32 m0, s60
	s_nop 0
	global_load_lds_dwordx4 v[184:185], off
	s_add_i32 m0, s60, 0x2000
	s_add_u32 s60, s44, 0x40000
	v_lshl_add_u64 v[216:217], s[44:45], 0, v[158:159]
	s_addc_u32 s61, s45, 0
	s_add_i32 s62, s54, s68
	global_load_lds_dwordx4 v[216:217], off
	v_lshl_add_u64 v[218:219], s[60:61], 0, v[154:155]
	s_mov_b32 m0, s62
	v_lshl_add_u64 v[220:221], s[46:47], 0, v[156:157]
	global_load_lds_dwordx4 v[218:219], off
	v_lshl_add_u64 v[218:219], s[60:61], 0, v[158:159]
	s_add_i32 m0, s62, 0x2000
	s_nop 0
	global_load_lds_dwordx4 v[218:219], off
	v_lshl_add_u64 v[218:219], s[46:47], 0, v[152:153]
	s_mov_b32 m0, s74
	s_nop 0
	global_load_lds_dwordx4 v[218:219], off
	s_mov_b32 m0, s66
	s_nop 0
	global_load_lds_dwordx4 v[220:221], off
	ds_read_b128 v[176:179], v191 offset:16384
	ds_read_b128 v[180:183], v191 offset:17408
	ds_read_b128 v[192:195], v191 offset:18432
	ds_read_b128 v[196:199], v191 offset:19456
	ds_read_b128 v[200:203], v191 offset:20480
	ds_read_b128 v[204:207], v191 offset:21504
	ds_read_b128 v[208:211], v191 offset:22528
	ds_read_b128 v[212:215], v191 offset:23552
	s_waitcnt vmcnt(8)
	s_waitcnt lgkmcnt(0)
	s_barrier
; #define PG8_STAGE(bufoff, gbase, voff) do { _Pragma("unroll") for (int _i = 0; _i < 2; ++_i) \
;         __builtin_amdgcn_global_load_lds((const unsigned*)((const char*)(gbase) + (voff)[_i]), (PG8_LAS unsigned*)(lds + (bufoff) + ldsw + _i * 8192), 16, 0, 0); } while (0)
; #define PG8_LDA(dst, b, h) do { _Pragma("unroll") for (int m = 0; m < 4; ++m) _Pragma("unroll") for (int k = 0; k < 2; ++k) dst[m][k] = *(const PG8_LAS bf16x8*)(lds + PG8_SA(b, h) + aoff + m * 2048 + k * 1024); } while (0)
; #define PG8_LDB(dst, b, h) do { _Pragma("unroll") for (int n = 0; n < 2; ++n) _Pragma("unroll") for (int k = 0; k < 2; ++k) dst[n][k] = *(const PG8_LAS bf16x8*)(lds + PG8_SB(b, h) + boff + n * 2048 + k * 1024); } while (0)
; #define PG8_MMA(ai, bj, At, Bt) do { __builtin_amdgcn_s_setprio(1); _Pragma("unroll") for (int m = 0; m < 4; ++m) _Pragma("unroll") for (int n = 0; n < 2; ++n) _Pragma("unroll") for (int k = 0; k < 2; ++k) \
;         acc[ai][bj][m][n] = mma16<F16>(Bt[n][k], At[m][k], acc[ai][bj][m][n]); __builtin_amdgcn_s_setprio(0); } while (0)
; #define PG8_WAIT_V(n) asm volatile("s_waitcnt vmcnt(" #n ")" ::: "memory")
; #define PG8_WAIT_L(n) asm volatile("s_waitcnt lgkmcnt(" #n ")" ::: "memory")
; #define PG8_BAR __builtin_amdgcn_s_barrier()
; #define PG8_SCHED __builtin_amdgcn_sched_barrier(0)
; template <class Epi, class Sched, bool ALIGN_EPI = false, bool SP2 = false, bool F16 = false>
; __device__ __forceinline__ void gemm_phase(PG8_LAS unsigned char* lds, const Gemm g, const Sched& S, const Epi& E, const int wid_in) {
;     ...
;             PG8_WAIT_V(8); PG8_WAIT_L(0); PG8_BAR; PG8_MMA(1, 0, At, B0); PG8_MMA(1, 1, At, B1); PG8_BAR; PG8_SCHED;
;             PG8_LDB(B0, 1, 0); PG8_LDB(B1, 1, 1); PG8_SCHED; PG8_LDA(At, 1, 0); PG8_STAGE(PG8_SA(0, 1), a2 + hstep, voffA);
;             PG8_WAIT_V(8); PG8_WAIT_L(0); PG8_BAR; PG8_MMA(0, 0, At, B0); PG8_MMA(0, 1, At, B1); PG8_BAR; PG8_SCHED;
	s_waitcnt lgkmcnt(0)
	v_mfma_f32_16x16x32_bf16 v[60:63], v[128:131], v[176:179], v[60:63]
	v_mfma_f32_16x16x32_bf16 v[56:59], v[136:139], v[176:179], v[56:59]
	v_mfma_f32_16x16x32_bf16 v[44:47], v[128:131], v[192:195], v[44:47]
	v_mfma_f32_16x16x32_bf16 v[40:43], v[136:139], v[192:195], v[40:43]
	v_mfma_f32_16x16x32_bf16 v[28:31], v[128:131], v[200:203], v[28:31]
	v_mfma_f32_16x16x32_bf16 v[24:27], v[136:139], v[200:203], v[24:27]
	v_mfma_f32_16x16x32_bf16 v[12:15], v[128:131], v[208:211], v[12:15]
	v_mfma_f32_16x16x32_bf16 v[8:11], v[136:139], v[208:211], v[8:11]
	v_mfma_f32_16x16x32_bf16 v[60:63], v[132:135], v[180:183], v[60:63]
	v_mfma_f32_16x16x32_bf16 v[56:59], v[140:143], v[180:183], v[56:59]
	v_mfma_f32_16x16x32_bf16 v[44:47], v[132:135], v[196:199], v[44:47]
	v_mfma_f32_16x16x32_bf16 v[40:43], v[140:143], v[196:199], v[40:43]
	v_mfma_f32_16x16x32_bf16 v[28:31], v[132:135], v[204:207], v[28:31]
	v_mfma_f32_16x16x32_bf16 v[24:27], v[140:143], v[204:207], v[24:27]
	v_mfma_f32_16x16x32_bf16 v[12:15], v[132:135], v[212:215], v[12:15]
	v_mfma_f32_16x16x32_bf16 v[8:11], v[140:143], v[212:215], v[8:11]
	v_mfma_f32_16x16x32_bf16 v[52:55], v[144:147], v[176:179], v[52:55]
	v_mfma_f32_16x16x32_bf16 v[48:51], v[168:171], v[176:179], v[48:51]
	v_mfma_f32_16x16x32_bf16 v[36:39], v[144:147], v[192:195], v[36:39]
	v_mfma_f32_16x16x32_bf16 v[32:35], v[168:171], v[192:195], v[32:35]
	v_mfma_f32_16x16x32_bf16 v[20:23], v[144:147], v[200:203], v[20:23]
	v_mfma_f32_16x16x32_bf16 v[16:19], v[168:171], v[200:203], v[16:19]
	v_mfma_f32_16x16x32_bf16 v[4:7], v[144:147], v[208:211], v[4:7]
	v_mfma_f32_16x16x32_bf16 v[0:3], v[168:171], v[208:211], v[0:3]
	v_mfma_f32_16x16x32_bf16 v[52:55], v[148:151], v[180:183], v[52:55]
	v_mfma_f32_16x16x32_bf16 v[48:51], v[172:175], v[180:183], v[48:51]
	v_mfma_f32_16x16x32_bf16 v[36:39], v[148:151], v[196:199], v[36:39]
	v_mfma_f32_16x16x32_bf16 v[32:35], v[172:175], v[196:199], v[32:35]
	v_mfma_f32_16x16x32_bf16 v[20:23], v[148:151], v[204:207], v[20:23]
	v_mfma_f32_16x16x32_bf16 v[16:19], v[172:175], v[204:207], v[16:19]
	v_mfma_f32_16x16x32_bf16 v[4:7], v[148:151], v[212:215], v[4:7]
	v_mfma_f32_16x16x32_bf16 v[0:3], v[172:175], v[212:215], v[0:3]
	s_barrier
	s_add_i32 s60, 0, 0x18000
	s_add_i32 s61, 0, 0x1c000
	v_add_u32_e32 v140, s60, v188
	v_add_u32_e32 v172, s61, v188
	s_add_u32 s46, s46, 0x40000
	s_addc_u32 s47, s47, 0
	s_mov_b32 m0, s90
	v_lshl_add_u64 v[222:223], s[46:47], 0, v[152:153]
	global_load_lds_dwordx4 v[222:223], off
	v_lshl_add_u64 v[222:223], s[46:47], 0, v[156:157]
	s_mov_b32 m0, s49
	s_nop 0
	global_load_lds_dwordx4 v[222:223], off
	ds_read_b128 v[128:131], v140
	ds_read_b128 v[132:135], v140 offset:1024
	ds_read_b128 v[136:139], v140 offset:2048
	ds_read_b128 v[140:143], v140 offset:3072
	ds_read_b128 v[144:147], v172
	ds_read_b128 v[148:151], v172 offset:1024
	ds_read_b128 v[168:171], v172 offset:2048
	ds_read_b128 v[172:175], v172 offset:3072
	ds_read_b128 v[176:179], v191 offset:32768
	ds_read_b128 v[180:183], v191 offset:33792
	ds_read_b128 v[192:195], v191 offset:34816
	ds_read_b128 v[196:199], v191 offset:35840
	ds_read_b128 v[200:203], v191 offset:36864
	ds_read_b128 v[204:207], v191 offset:37888
	ds_read_b128 v[208:211], v191 offset:38912
	ds_read_b128 v[212:215], v191 offset:39936
	s_waitcnt vmcnt(8)
	s_waitcnt lgkmcnt(0)
	s_barrier
	s_waitcnt lgkmcnt(0)
	v_mfma_f32_16x16x32_bf16 v[124:127], v[128:131], v[176:179], v[124:127]
	v_mfma_f32_16x16x32_bf16 v[120:123], v[136:139], v[176:179], v[120:123]
	v_mfma_f32_16x16x32_bf16 v[108:111], v[128:131], v[192:195], v[108:111]
	v_mfma_f32_16x16x32_bf16 v[104:107], v[136:139], v[192:195], v[104:107]
	v_mfma_f32_16x16x32_bf16 v[92:95], v[128:131], v[200:203], v[92:95]
	v_mfma_f32_16x16x32_bf16 v[88:91], v[136:139], v[200:203], v[88:91]
	v_mfma_f32_16x16x32_bf16 v[76:79], v[128:131], v[208:211], v[76:79]
	v_mfma_f32_16x16x32_bf16 v[72:75], v[136:139], v[208:211], v[72:75]
	v_mfma_f32_16x16x32_bf16 v[124:127], v[132:135], v[180:183], v[124:127]
	v_mfma_f32_16x16x32_bf16 v[120:123], v[140:143], v[180:183], v[120:123]
	v_mfma_f32_16x16x32_bf16 v[108:111], v[132:135], v[196:199], v[108:111]
	v_mfma_f32_16x16x32_bf16 v[104:107], v[140:143], v[196:199], v[104:107]
	v_mfma_f32_16x16x32_bf16 v[92:95], v[132:135], v[204:207], v[92:95]
	v_mfma_f32_16x16x32_bf16 v[88:91], v[140:143], v[204:207], v[88:91]
	v_mfma_f32_16x16x32_bf16 v[76:79], v[132:135], v[212:215], v[76:79]
	v_mfma_f32_16x16x32_bf16 v[72:75], v[140:143], v[212:215], v[72:75]
	v_mfma_f32_16x16x32_bf16 v[116:119], v[144:147], v[176:179], v[116:119]
	v_mfma_f32_16x16x32_bf16 v[112:115], v[168:171], v[176:179], v[112:115]
	v_mfma_f32_16x16x32_bf16 v[100:103], v[144:147], v[192:195], v[100:103]
	v_mfma_f32_16x16x32_bf16 v[96:99], v[168:171], v[192:195], v[96:99]
	v_mfma_f32_16x16x32_bf16 v[84:87], v[144:147], v[200:203], v[84:87]
	v_mfma_f32_16x16x32_bf16 v[80:83], v[168:171], v[200:203], v[80:83]
	v_mfma_f32_16x16x32_bf16 v[68:71], v[144:147], v[208:211], v[68:71]
	v_mfma_f32_16x16x32_bf16 v[64:67], v[168:171], v[208:211], v[64:67]
	v_mfma_f32_16x16x32_bf16 v[116:119], v[148:151], v[180:183], v[116:119]
	v_mfma_f32_16x16x32_bf16 v[112:115], v[172:175], v[180:183], v[112:115]
	v_mfma_f32_16x16x32_bf16 v[100:103], v[148:151], v[196:199], v[100:103]
	v_mfma_f32_16x16x32_bf16 v[96:99], v[172:175], v[196:199], v[96:99]
	v_mfma_f32_16x16x32_bf16 v[84:87], v[148:151], v[204:207], v[84:87]
	v_mfma_f32_16x16x32_bf16 v[80:83], v[172:175], v[204:207], v[80:83]
	v_mfma_f32_16x16x32_bf16 v[68:71], v[148:151], v[212:215], v[68:71]
	v_mfma_f32_16x16x32_bf16 v[64:67], v[172:175], v[212:215], v[64:67]
	s_barrier
; #define PG8_STAGE(bufoff, gbase, voff) do { _Pragma("unroll") for (int _i = 0; _i < 2; ++_i) \
;         __builtin_amdgcn_global_load_lds((const unsigned*)((const char*)(gbase) + (voff)[_i]), (PG8_LAS unsigned*)(lds + (bufoff) + ldsw + _i * 8192), 16, 0, 0); } while (0)
; #define PG8_LDA(dst, b, h) do { _Pragma("unroll") for (int m = 0; m < 4; ++m) _Pragma("unroll") for (int k = 0; k < 2; ++k) dst[m][k] = *(const PG8_LAS bf16x8*)(lds + PG8_SA(b, h) + aoff + m * 2048 + k * 1024); } while (0)
; #define PG8_MMA(ai, bj, At, Bt) do { __builtin_amdgcn_s_setprio(1); _Pragma("unroll") for (int m = 0; m < 4; ++m) _Pragma("unroll") for (int n = 0; n < 2; ++n) _Pragma("unroll") for (int k = 0; k < 2; ++k) \
;         acc[ai][bj][m][n] = mma16<F16>(Bt[n][k], At[m][k], acc[ai][bj][m][n]); __builtin_amdgcn_s_setprio(0); } while (0)
; #define PG8_WAIT_V(n) asm volatile("s_waitcnt vmcnt(" #n ")" ::: "memory")
; #define PG8_WAIT_L(n) asm volatile("s_waitcnt lgkmcnt(" #n ")" ::: "memory")
; #define PG8_BAR __builtin_amdgcn_s_barrier()
; #define PG8_SCHED __builtin_amdgcn_sched_barrier(0)
; template <class Epi, class Sched, bool ALIGN_EPI = false, bool SP2 = false, bool F16 = false>
; __device__ __forceinline__ void gemm_phase(PG8_LAS unsigned char* lds, const Gemm g, const Sched& S, const Epi& E, const int wid_in) {
;     ...
;             PG8_LDA(At, 1, 1); PG8_STAGE(PG8_SB(1, 0), b3, voffB); PG8_STAGE(PG8_SB(1, 1), b3 + hstep, voffB); PG8_STAGE(PG8_SA(1, 0), a3, voffA);
;             PG8_WAIT_V(8); PG8_WAIT_L(0); PG8_BAR; PG8_MMA(1, 0, At, B0); PG8_MMA(1, 1, At, B1); PG8_BAR; PG8_SCHED;
	s_add_i32 s46, s60, s68
	v_lshl_add_u64 v[184:185], v[184:185], 0, s[24:25]
	s_mov_b32 m0, s46
	s_nop 0
	global_load_lds_dwordx4 v[184:185], off
	s_add_i32 m0, s46, 0x2000
	s_add_u32 s44, s44, 0x40080
	v_lshl_add_u64 v[184:185], v[216:217], 0, s[24:25]
	s_addc_u32 s45, s45, 0
	s_add_i32 s46, s61, s68
	global_load_lds_dwordx4 v[184:185], off
	v_lshl_add_u64 v[184:185], s[44:45], 0, v[154:155]
	s_mov_b32 m0, s46
	s_nop 0
	global_load_lds_dwordx4 v[184:185], off
	v_lshl_add_u64 v[184:185], s[44:45], 0, v[158:159]
	s_add_i32 m0, s46, 0x2000
	s_nop 0
	global_load_lds_dwordx4 v[184:185], off
	v_lshl_add_u64 v[184:185], v[218:219], 0, s[24:25]
	s_mov_b32 m0, s75
	s_nop 0
	global_load_lds_dwordx4 v[184:185], off
	v_lshl_add_u64 v[184:185], v[220:221], 0, s[24:25]
	s_mov_b32 m0, s67
	s_nop 0
	global_load_lds_dwordx4 v[184:185], off
	ds_read_b128 v[176:179], v191 offset:49152
	ds_read_b128 v[180:183], v191 offset:50176
	ds_read_b128 v[192:195], v191 offset:51200
	ds_read_b128 v[196:199], v191 offset:52224
	ds_read_b128 v[200:203], v191 offset:53248
	ds_read_b128 v[204:207], v191 offset:54272
	ds_read_b128 v[208:211], v191 offset:55296
	ds_read_b128 v[212:215], v191 offset:56320
	s_waitcnt vmcnt(8)
	s_waitcnt lgkmcnt(0)
	s_barrier
	s_waitcnt lgkmcnt(0)
	v_mfma_f32_16x16x32_bf16 v[60:63], v[128:131], v[176:179], v[60:63]
	v_mfma_f32_16x16x32_bf16 v[56:59], v[136:139], v[176:179], v[56:59]
	v_mfma_f32_16x16x32_bf16 v[44:47], v[128:131], v[192:195], v[44:47]
	v_mfma_f32_16x16x32_bf16 v[40:43], v[136:139], v[192:195], v[40:43]
	v_mfma_f32_16x16x32_bf16 v[28:31], v[128:131], v[200:203], v[28:31]
	v_mfma_f32_16x16x32_bf16 v[24:27], v[136:139], v[200:203], v[24:27]
	v_mfma_f32_16x16x32_bf16 v[12:15], v[128:131], v[208:211], v[12:15]
	v_mfma_f32_16x16x32_bf16 v[8:11], v[136:139], v[208:211], v[8:11]
	v_mfma_f32_16x16x32_bf16 v[60:63], v[132:135], v[180:183], v[60:63]
	v_mfma_f32_16x16x32_bf16 v[56:59], v[140:143], v[180:183], v[56:59]
	v_mfma_f32_16x16x32_bf16 v[44:47], v[132:135], v[196:199], v[44:47]
	v_mfma_f32_16x16x32_bf16 v[40:43], v[140:143], v[196:199], v[40:43]
	v_mfma_f32_16x16x32_bf16 v[28:31], v[132:135], v[204:207], v[28:31]
	v_mfma_f32_16x16x32_bf16 v[24:27], v[140:143], v[204:207], v[24:27]
	v_mfma_f32_16x16x32_bf16 v[12:15], v[132:135], v[212:215], v[12:15]
	v_mfma_f32_16x16x32_bf16 v[8:11], v[140:143], v[212:215], v[8:11]
	v_mfma_f32_16x16x32_bf16 v[52:55], v[144:147], v[176:179], v[52:55]
	v_mfma_f32_16x16x32_bf16 v[48:51], v[168:171], v[176:179], v[48:51]
	v_mfma_f32_16x16x32_bf16 v[36:39], v[144:147], v[192:195], v[36:39]
	v_mfma_f32_16x16x32_bf16 v[32:35], v[168:171], v[192:195], v[32:35]
	v_mfma_f32_16x16x32_bf16 v[20:23], v[144:147], v[200:203], v[20:23]
	v_mfma_f32_16x16x32_bf16 v[16:19], v[168:171], v[200:203], v[16:19]
	v_mfma_f32_16x16x32_bf16 v[4:7], v[144:147], v[208:211], v[4:7]
	v_mfma_f32_16x16x32_bf16 v[0:3], v[168:171], v[208:211], v[0:3]
	v_mfma_f32_16x16x32_bf16 v[52:55], v[148:151], v[180:183], v[52:55]
	v_mfma_f32_16x16x32_bf16 v[48:51], v[172:175], v[180:183], v[48:51]
	v_mfma_f32_16x16x32_bf16 v[36:39], v[148:151], v[196:199], v[36:39]
	v_mfma_f32_16x16x32_bf16 v[32:35], v[172:175], v[196:199], v[32:35]
	v_mfma_f32_16x16x32_bf16 v[20:23], v[148:151], v[204:207], v[20:23]
	v_mfma_f32_16x16x32_bf16 v[16:19], v[172:175], v[204:207], v[16:19]
	v_mfma_f32_16x16x32_bf16 v[4:7], v[148:151], v[212:215], v[4:7]
	v_mfma_f32_16x16x32_bf16 v[0:3], v[172:175], v[212:215], v[0:3]
	s_barrier
	s_add_i32 s59, s59, 2
	s_add_u32 s42, s42, 0x100
	s_addc_u32 s43, s43, 0
	s_add_u32 s57, s57, 0x100
	s_addc_u32 s58, s58, 0
	s_cmp_gt_u32 s59, 13
	s_cbranch_scc0 .LBB0_2489
	s_and_b64 vcc, exec, s[16:17]
	s_cbranch_vccz .LBB0_2492
	s_barrier

; #define PG8_STAGE(bufoff, gbase, voff) do { _Pragma("unroll") for (int _i = 0; _i < 2; ++_i) \
;         __builtin_amdgcn_global_load_lds((const unsigned*)((const char*)(gbase) + (voff)[_i]), (PG8_LAS unsigned*)(lds + (bufoff) + ldsw + _i * 8192), 16, 0, 0); } while (0)
; #define PG8_LDA(dst, b, h) do { _Pragma("unroll") for (int m = 0; m < 4; ++m) _Pragma("unroll") for (int k = 0; k < 2; ++k) dst[m][k] = *(const PG8_LAS bf16x8*)(lds + PG8_SA(b, h) + aoff + m * 2048 + k * 1024); } while (0)
; #define PG8_LDB(dst, b, h) do { _Pragma("unroll") for (int n = 0; n < 2; ++n) _Pragma("unroll") for (int k = 0; k < 2; ++k) dst[n][k] = *(const PG8_LAS bf16x8*)(lds + PG8_SB(b, h) + boff + n * 2048 + k * 1024); } while (0)
; #define PG8_MMA(ai, bj, At, Bt) do { __builtin_amdgcn_s_setprio(1); _Pragma("unroll") for (int m = 0; m < 4; ++m) _Pragma("unroll") for (int n = 0; n < 2; ++n) _Pragma("unroll") for (int k = 0; k < 2; ++k) \
;         acc[ai][bj][m][n] = mma16<F16>(Bt[n][k], At[m][k], acc[ai][bj][m][n]); __builtin_amdgcn_s_setprio(0); } while (0)
; #define PG8_WAIT_V(n) asm volatile("s_waitcnt vmcnt(" #n ")" ::: "memory")
; #define PG8_WAIT_L(n) asm volatile("s_waitcnt lgkmcnt(" #n ")" ::: "memory")
; template <class Epi, class Sched, bool ALIGN_EPI = false, bool SP2 = false, bool F16 = false>
; __device__ __forceinline__ void gemm_phase(PG8_LAS unsigned char* lds, const Gemm g, const Sched& S, const Epi& E, const int wid_in) {
;     ...
;             const bool last = (t == nt - 2);
;             const char* a1 = cA + (size_t)(t + 1) * kstep;
;             const char* a2 = last ? nA : cA + (size_t)(t + 2) * kstep; const char* b2 = last ? nB : cB + (size_t)(t + 2) * kstep;
;             const char* a3 = a2 + kstep; const char* b3 = b2 + kstep;
;             if (last && has_next) S.a_ready(nxt);
;             if constexpr (SP2) {
;             PG8_LDB(B0, 0, 0); PG8_LDB(B1, 0, 1); PG8_SCHED; PG8_LDA(At, 0, 0); PG8_STAGE(PG8_SA(1, 1), a1 + hstep, voffA);
;             PG8_WAIT_V(8); PG8_WAIT_L(0); PG8_BAR; PG8_MMA(0, 0, At, B0); PG8_MMA(0, 1, At, B1); PG8_BAR; PG8_SCHED;
;             PG8_LDA(At, 0, 1); PG8_STAGE(PG8_SB(0, 0), b2, voffB); PG8_STAGE(PG8_SB(0, 1), b2 + hstep, voffB); PG8_STAGE(PG8_SA(0, 0), a2, voffA);
;             PG8_WAIT_V(8); PG8_WAIT_L(0); PG8_BAR; PG8_MMA(1, 0, At, B0); PG8_MMA(1, 1, At, B1); PG8_BAR; PG8_SCHED;
.LBB0_2566:
	ds_read_b128 v[0:3], v193
	ds_read_b128 v[4:7], v193 offset:1024
	ds_read_b128 v[136:139], v193 offset:2048
	ds_read_b128 v[140:143], v193 offset:3072
	ds_read_b128 v[144:147], v194
	ds_read_b128 v[148:151], v194 offset:1024
	ds_read_b128 v[152:155], v194 offset:2048
	ds_read_b128 v[156:159], v194 offset:3072
	s_add_u32 s42, s36, 0xfffc0080
	s_addc_u32 s43, s37, -1
	s_cmp_eq_u32 s62, 12
	s_cselect_b32 s45, s25, s43
	s_cselect_b32 s44, s35, s42
	s_cselect_b32 s43, s23, s61
	s_cselect_b32 s42, s59, s60
	s_mov_b32 m0, s91
	v_lshl_add_u64 v[188:189], s[36:37], 0, v[168:169]
	ds_read_b128 v[176:179], v195
	ds_read_b128 v[180:183], v195 offset:1024
	ds_read_b128 v[184:187], v195 offset:2048
	ds_read_b128 v[198:201], v195 offset:3072
	ds_read_b128 v[202:205], v195 offset:4096
	ds_read_b128 v[206:209], v195 offset:5120
	ds_read_b128 v[210:213], v195 offset:6144
	ds_read_b128 v[214:217], v195 offset:7168
	global_load_lds_dwordx4 v[188:189], off
	v_lshl_add_u64 v[188:189], s[36:37], 0, v[170:171]
	s_add_i32 m0, s74, 0xe000
	s_nop 0
	global_load_lds_dwordx4 v[188:189], off
	s_waitcnt vmcnt(8)
	s_waitcnt lgkmcnt(0)
	s_barrier
	s_waitcnt lgkmcnt(0)
	v_mfma_f32_16x16x32_f16 v[132:135], v[0:3], v[176:179], v[132:135]
	v_mfma_f32_16x16x32_f16 v[128:131], v[136:139], v[176:179], v[128:131]
	v_mfma_f32_16x16x32_f16 v[116:119], v[0:3], v[184:187], v[116:119]
	v_mfma_f32_16x16x32_f16 v[112:115], v[136:139], v[184:187], v[112:115]
	v_mfma_f32_16x16x32_f16 v[100:103], v[0:3], v[202:205], v[100:103]
	v_mfma_f32_16x16x32_f16 v[96:99], v[136:139], v[202:205], v[96:99]
	v_mfma_f32_16x16x32_f16 v[84:87], v[0:3], v[210:213], v[84:87]
	v_mfma_f32_16x16x32_f16 v[80:83], v[136:139], v[210:213], v[80:83]
	v_mfma_f32_16x16x32_f16 v[132:135], v[4:7], v[180:183], v[132:135]
	v_mfma_f32_16x16x32_f16 v[128:131], v[140:143], v[180:183], v[128:131]
	v_mfma_f32_16x16x32_f16 v[116:119], v[4:7], v[198:201], v[116:119]
	v_mfma_f32_16x16x32_f16 v[112:115], v[140:143], v[198:201], v[112:115]
	v_mfma_f32_16x16x32_f16 v[100:103], v[4:7], v[206:209], v[100:103]
	v_mfma_f32_16x16x32_f16 v[96:99], v[140:143], v[206:209], v[96:99]
	v_mfma_f32_16x16x32_f16 v[84:87], v[4:7], v[214:217], v[84:87]
	v_mfma_f32_16x16x32_f16 v[80:83], v[140:143], v[214:217], v[80:83]
	v_mfma_f32_16x16x32_f16 v[124:127], v[144:147], v[176:179], v[124:127]
	v_mfma_f32_16x16x32_f16 v[120:123], v[152:155], v[176:179], v[120:123]
	v_mfma_f32_16x16x32_f16 v[108:111], v[144:147], v[184:187], v[108:111]
	v_mfma_f32_16x16x32_f16 v[104:107], v[152:155], v[184:187], v[104:107]
	v_mfma_f32_16x16x32_f16 v[92:95], v[144:147], v[202:205], v[92:95]
	v_mfma_f32_16x16x32_f16 v[88:91], v[152:155], v[202:205], v[88:91]
	v_mfma_f32_16x16x32_f16 v[76:79], v[144:147], v[210:213], v[76:79]
	v_mfma_f32_16x16x32_f16 v[72:75], v[152:155], v[210:213], v[72:75]
	v_mfma_f32_16x16x32_f16 v[124:127], v[148:151], v[180:183], v[124:127]
	v_mfma_f32_16x16x32_f16 v[120:123], v[156:159], v[180:183], v[120:123]
	v_mfma_f32_16x16x32_f16 v[108:111], v[148:151], v[198:201], v[108:111]
	v_mfma_f32_16x16x32_f16 v[104:107], v[156:159], v[198:201], v[104:107]
	v_mfma_f32_16x16x32_f16 v[92:95], v[148:151], v[206:209], v[92:95]
	v_mfma_f32_16x16x32_f16 v[88:91], v[156:159], v[206:209], v[88:91]
	v_mfma_f32_16x16x32_f16 v[76:79], v[148:151], v[214:217], v[76:79]
	v_mfma_f32_16x16x32_f16 v[72:75], v[156:159], v[214:217], v[72:75]
	s_barrier
	s_add_i32 s63, s56, s68
	v_lshl_add_u64 v[188:189], s[42:43], 0, v[162:163]
	s_mov_b32 m0, s63
	s_nop 0
	global_load_lds_dwordx4 v[188:189], off
	s_add_i32 m0, s63, 0x2000
	s_add_u32 s64, s42, 0x40000
	v_lshl_add_u64 v[218:219], s[42:43], 0, v[166:167]
	s_addc_u32 s65, s43, 0
	s_add_i32 s63, s57, s68
	global_load_lds_dwordx4 v[218:219], off
	v_lshl_add_u64 v[220:221], s[64:65], 0, v[162:163]
	s_mov_b32 m0, s63
	v_lshl_add_u64 v[222:223], s[44:45], 0, v[164:165]
	global_load_lds_dwordx4 v[220:221], off
	v_lshl_add_u64 v[220:221], s[64:65], 0, v[166:167]
	s_add_i32 m0, s63, 0x2000
	s_nop 0
	global_load_lds_dwordx4 v[220:221], off
	v_lshl_add_u64 v[220:221], s[44:45], 0, v[160:161]
	s_mov_b32 m0, s74
	s_nop 0
	global_load_lds_dwordx4 v[220:221], off
	s_mov_b32 m0, s66
	s_nop 0
	global_load_lds_dwordx4 v[222:223], off
	ds_read_b128 v[176:179], v195 offset:16384
	ds_read_b128 v[180:183], v195 offset:17408
	ds_read_b128 v[184:187], v195 offset:18432
	ds_read_b128 v[198:201], v195 offset:19456
	ds_read_b128 v[202:205], v195 offset:20480
	ds_read_b128 v[206:209], v195 offset:21504
	ds_read_b128 v[210:213], v195 offset:22528
	ds_read_b128 v[214:217], v195 offset:23552
	s_waitcnt vmcnt(8)
	s_waitcnt lgkmcnt(0)
	s_barrier
; #define PG8_STAGE(bufoff, gbase, voff) do { _Pragma("unroll") for (int _i = 0; _i < 2; ++_i) \
;         __builtin_amdgcn_global_load_lds((const unsigned*)((const char*)(gbase) + (voff)[_i]), (PG8_LAS unsigned*)(lds + (bufoff) + ldsw + _i * 8192), 16, 0, 0); } while (0)
; #define PG8_LDA(dst, b, h) do { _Pragma("unroll") for (int m = 0; m < 4; ++m) _Pragma("unroll") for (int k = 0; k < 2; ++k) dst[m][k] = *(const PG8_LAS bf16x8*)(lds + PG8_SA(b, h) + aoff + m * 2048 + k * 1024); } while (0)
; #define PG8_LDB(dst, b, h) do { _Pragma("unroll") for (int n = 0; n < 2; ++n) _Pragma("unroll") for (int k = 0; k < 2; ++k) dst[n][k] = *(const PG8_LAS bf16x8*)(lds + PG8_SB(b, h) + boff + n * 2048 + k * 1024); } while (0)
; #define PG8_MMA(ai, bj, At, Bt) do { __builtin_amdgcn_s_setprio(1); _Pragma("unroll") for (int m = 0; m < 4; ++m) _Pragma("unroll") for (int n = 0; n < 2; ++n) _Pragma("unroll") for (int k = 0; k < 2; ++k) \
;         acc[ai][bj][m][n] = mma16<F16>(Bt[n][k], At[m][k], acc[ai][bj][m][n]); __builtin_amdgcn_s_setprio(0); } while (0)
; #define PG8_WAIT_V(n) asm volatile("s_waitcnt vmcnt(" #n ")" ::: "memory")
; #define PG8_WAIT_L(n) asm volatile("s_waitcnt lgkmcnt(" #n ")" ::: "memory")
; #define PG8_BAR __builtin_amdgcn_s_barrier()
; #define PG8_SCHED __builtin_amdgcn_sched_barrier(0)
; template <class Epi, class Sched, bool ALIGN_EPI = false, bool SP2 = false, bool F16 = false>
; __device__ __forceinline__ void gemm_phase(PG8_LAS unsigned char* lds, const Gemm g, const Sched& S, const Epi& E, const int wid_in) {
;     ...
;             PG8_WAIT_V(8); PG8_WAIT_L(0); PG8_BAR; PG8_MMA(1, 0, At, B0); PG8_MMA(1, 1, At, B1); PG8_BAR; PG8_SCHED;
;             PG8_LDB(B0, 1, 0); PG8_LDB(B1, 1, 1); PG8_SCHED; PG8_LDA(At, 1, 0); PG8_STAGE(PG8_SA(0, 1), a2 + hstep, voffA);
;             PG8_WAIT_V(8); PG8_WAIT_L(0); PG8_BAR; PG8_MMA(0, 0, At, B0); PG8_MMA(0, 1, At, B1); PG8_BAR; PG8_SCHED;
	s_waitcnt lgkmcnt(0)
	v_mfma_f32_16x16x32_f16 v[68:71], v[0:3], v[176:179], v[68:71]
	v_mfma_f32_16x16x32_f16 v[64:67], v[136:139], v[176:179], v[64:67]
	v_mfma_f32_16x16x32_f16 v[52:55], v[0:3], v[184:187], v[52:55]
	v_mfma_f32_16x16x32_f16 v[48:51], v[136:139], v[184:187], v[48:51]
	v_mfma_f32_16x16x32_f16 v[36:39], v[0:3], v[202:205], v[36:39]
	v_mfma_f32_16x16x32_f16 v[32:35], v[136:139], v[202:205], v[32:35]
	v_mfma_f32_16x16x32_f16 v[0:3], v[0:3], v[210:213], v[20:23]
	v_mfma_f32_16x16x32_f16 v[68:71], v[4:7], v[180:183], v[68:71]
	v_mfma_f32_16x16x32_f16 v[64:67], v[140:143], v[180:183], v[64:67]
	v_mfma_f32_16x16x32_f16 v[52:55], v[4:7], v[198:201], v[52:55]
	v_mfma_f32_16x16x32_f16 v[48:51], v[140:143], v[198:201], v[48:51]
	v_mfma_f32_16x16x32_f16 v[36:39], v[4:7], v[206:209], v[36:39]
	v_mfma_f32_16x16x32_f16 v[32:35], v[140:143], v[206:209], v[32:35]
	v_mfma_f32_16x16x32_f16 v[0:3], v[4:7], v[214:217], v[0:3]
	v_mfma_f32_16x16x32_f16 v[4:7], v[136:139], v[210:213], v[16:19]
	v_mfma_f32_16x16x32_f16 v[4:7], v[140:143], v[214:217], v[4:7]
	v_mfma_f32_16x16x32_f16 v[16:19], v[144:147], v[176:179], v[60:63]
	v_mfma_f32_16x16x32_f16 v[60:63], v[148:151], v[180:183], v[16:19]
	v_mfma_f32_16x16x32_f16 v[16:19], v[152:155], v[176:179], v[56:59]
	v_mfma_f32_16x16x32_f16 v[56:59], v[156:159], v[180:183], v[16:19]
	v_mfma_f32_16x16x32_f16 v[16:19], v[144:147], v[184:187], v[44:47]
	v_mfma_f32_16x16x32_f16 v[44:47], v[148:151], v[198:201], v[16:19]
	v_mfma_f32_16x16x32_f16 v[16:19], v[152:155], v[184:187], v[40:43]
	v_mfma_f32_16x16x32_f16 v[40:43], v[156:159], v[198:201], v[16:19]
	v_mfma_f32_16x16x32_f16 v[16:19], v[144:147], v[202:205], v[28:31]
	v_mfma_f32_16x16x32_f16 v[28:31], v[148:151], v[206:209], v[16:19]
	v_mfma_f32_16x16x32_f16 v[16:19], v[152:155], v[202:205], v[24:27]
	v_mfma_f32_16x16x32_f16 v[12:15], v[144:147], v[210:213], v[12:15]
	v_mfma_f32_16x16x32_f16 v[8:11], v[152:155], v[210:213], v[8:11]
	v_mfma_f32_16x16x32_f16 v[24:27], v[156:159], v[206:209], v[16:19]
	v_mfma_f32_16x16x32_f16 v[12:15], v[148:151], v[214:217], v[12:15]
	v_mfma_f32_16x16x32_f16 v[8:11], v[156:159], v[214:217], v[8:11]
	s_barrier
	s_add_i32 s63, 0, 0x18000
	s_add_i32 s64, 0, 0x1c000
	v_add_u32_e32 v140, s63, v192
	v_add_u32_e32 v156, s64, v192
	s_add_u32 s44, s44, 0x40000
	s_addc_u32 s45, s45, 0
	s_mov_b32 m0, s90
	v_lshl_add_u64 v[224:225], s[44:45], 0, v[160:161]
	global_load_lds_dwordx4 v[224:225], off
	v_lshl_add_u64 v[224:225], s[44:45], 0, v[164:165]
	s_mov_b32 m0, s31
	s_nop 0
	global_load_lds_dwordx4 v[224:225], off
	ds_read_b128 v[16:19], v140
	ds_read_b128 v[20:23], v140 offset:1024
	ds_read_b128 v[136:139], v140 offset:2048
	ds_read_b128 v[140:143], v140 offset:3072
	ds_read_b128 v[144:147], v156
	ds_read_b128 v[148:151], v156 offset:1024
	ds_read_b128 v[152:155], v156 offset:2048
	ds_read_b128 v[156:159], v156 offset:3072
	ds_read_b128 v[176:179], v195 offset:32768
	ds_read_b128 v[180:183], v195 offset:33792
	ds_read_b128 v[184:187], v195 offset:34816
	ds_read_b128 v[198:201], v195 offset:35840
	ds_read_b128 v[202:205], v195 offset:36864
	ds_read_b128 v[206:209], v195 offset:37888
	ds_read_b128 v[210:213], v195 offset:38912
	ds_read_b128 v[214:217], v195 offset:39936
	s_waitcnt vmcnt(8)
	s_waitcnt lgkmcnt(0)
	s_barrier
	s_waitcnt lgkmcnt(0)
	v_mfma_f32_16x16x32_f16 v[132:135], v[16:19], v[176:179], v[132:135]
	v_mfma_f32_16x16x32_f16 v[128:131], v[136:139], v[176:179], v[128:131]
	v_mfma_f32_16x16x32_f16 v[116:119], v[16:19], v[184:187], v[116:119]
	v_mfma_f32_16x16x32_f16 v[112:115], v[136:139], v[184:187], v[112:115]
	v_mfma_f32_16x16x32_f16 v[100:103], v[16:19], v[202:205], v[100:103]
	v_mfma_f32_16x16x32_f16 v[96:99], v[136:139], v[202:205], v[96:99]
	v_mfma_f32_16x16x32_f16 v[84:87], v[16:19], v[210:213], v[84:87]
	v_mfma_f32_16x16x32_f16 v[80:83], v[136:139], v[210:213], v[80:83]
	v_mfma_f32_16x16x32_f16 v[132:135], v[20:23], v[180:183], v[132:135]
	v_mfma_f32_16x16x32_f16 v[128:131], v[140:143], v[180:183], v[128:131]
	v_mfma_f32_16x16x32_f16 v[116:119], v[20:23], v[198:201], v[116:119]
	v_mfma_f32_16x16x32_f16 v[112:115], v[140:143], v[198:201], v[112:115]
	v_mfma_f32_16x16x32_f16 v[100:103], v[20:23], v[206:209], v[100:103]
	v_mfma_f32_16x16x32_f16 v[96:99], v[140:143], v[206:209], v[96:99]
	v_mfma_f32_16x16x32_f16 v[84:87], v[20:23], v[214:217], v[84:87]
	v_mfma_f32_16x16x32_f16 v[80:83], v[140:143], v[214:217], v[80:83]
	v_mfma_f32_16x16x32_f16 v[124:127], v[144:147], v[176:179], v[124:127]
	v_mfma_f32_16x16x32_f16 v[120:123], v[152:155], v[176:179], v[120:123]
	v_mfma_f32_16x16x32_f16 v[108:111], v[144:147], v[184:187], v[108:111]
	v_mfma_f32_16x16x32_f16 v[104:107], v[152:155], v[184:187], v[104:107]
	v_mfma_f32_16x16x32_f16 v[92:95], v[144:147], v[202:205], v[92:95]
	v_mfma_f32_16x16x32_f16 v[88:91], v[152:155], v[202:205], v[88:91]
	v_mfma_f32_16x16x32_f16 v[76:79], v[144:147], v[210:213], v[76:79]
	v_mfma_f32_16x16x32_f16 v[72:75], v[152:155], v[210:213], v[72:75]
	v_mfma_f32_16x16x32_f16 v[124:127], v[148:151], v[180:183], v[124:127]
	v_mfma_f32_16x16x32_f16 v[120:123], v[156:159], v[180:183], v[120:123]
	v_mfma_f32_16x16x32_f16 v[108:111], v[148:151], v[198:201], v[108:111]
	v_mfma_f32_16x16x32_f16 v[104:107], v[156:159], v[198:201], v[104:107]
	v_mfma_f32_16x16x32_f16 v[92:95], v[148:151], v[206:209], v[92:95]
	v_mfma_f32_16x16x32_f16 v[88:91], v[156:159], v[206:209], v[88:91]
	v_mfma_f32_16x16x32_f16 v[76:79], v[148:151], v[214:217], v[76:79]
	v_mfma_f32_16x16x32_f16 v[72:75], v[156:159], v[214:217], v[72:75]
	s_barrier
; #define PG8_STAGE(bufoff, gbase, voff) do { _Pragma("unroll") for (int _i = 0; _i < 2; ++_i) \
;         __builtin_amdgcn_global_load_lds((const unsigned*)((const char*)(gbase) + (voff)[_i]), (PG8_LAS unsigned*)(lds + (bufoff) + ldsw + _i * 8192), 16, 0, 0); } while (0)
; #define PG8_LDA(dst, b, h) do { _Pragma("unroll") for (int m = 0; m < 4; ++m) _Pragma("unroll") for (int k = 0; k < 2; ++k) dst[m][k] = *(const PG8_LAS bf16x8*)(lds + PG8_SA(b, h) + aoff + m * 2048 + k * 1024); } while (0)
; #define PG8_MMA(ai, bj, At, Bt) do { __builtin_amdgcn_s_setprio(1); _Pragma("unroll") for (int m = 0; m < 4; ++m) _Pragma("unroll") for (int n = 0; n < 2; ++n) _Pragma("unroll") for (int k = 0; k < 2; ++k) \
;         acc[ai][bj][m][n] = mma16<F16>(Bt[n][k], At[m][k], acc[ai][bj][m][n]); __builtin_amdgcn_s_setprio(0); } while (0)
; #define PG8_WAIT_V(n) asm volatile("s_waitcnt vmcnt(" #n ")" ::: "memory")
; #define PG8_WAIT_L(n) asm volatile("s_waitcnt lgkmcnt(" #n ")" ::: "memory")
; #define PG8_BAR __builtin_amdgcn_s_barrier()
; #define PG8_SCHED __builtin_amdgcn_sched_barrier(0)
; template <class Epi, class Sched, bool ALIGN_EPI = false, bool SP2 = false, bool F16 = false>
; __device__ __forceinline__ void gemm_phase(PG8_LAS unsigned char* lds, const Gemm g, const Sched& S, const Epi& E, const int wid_in) {
;     ...
;             PG8_LDA(At, 1, 1); PG8_STAGE(PG8_SB(1, 0), b3, voffB); PG8_STAGE(PG8_SB(1, 1), b3 + hstep, voffB); PG8_STAGE(PG8_SA(1, 0), a3, voffA);
;             PG8_WAIT_V(8); PG8_WAIT_L(0); PG8_BAR; PG8_MMA(1, 0, At, B0); PG8_MMA(1, 1, At, B1); PG8_BAR; PG8_SCHED;
	s_add_i32 s44, s63, s68
	v_lshl_add_u64 v[188:189], v[188:189], 0, s[20:21]
	s_mov_b32 m0, s44
	s_nop 0
	global_load_lds_dwordx4 v[188:189], off
	s_add_i32 m0, s44, 0x2000
	s_add_u32 s42, s42, 0x40080
	v_lshl_add_u64 v[188:189], v[218:219], 0, s[20:21]
	s_addc_u32 s43, s43, 0
	s_add_i32 s44, s64, s68
	global_load_lds_dwordx4 v[188:189], off
	v_lshl_add_u64 v[188:189], s[42:43], 0, v[162:163]
	s_mov_b32 m0, s44
	s_nop 0
	global_load_lds_dwordx4 v[188:189], off
	v_lshl_add_u64 v[188:189], s[42:43], 0, v[166:167]
	s_add_i32 m0, s44, 0x2000
	s_nop 0
	global_load_lds_dwordx4 v[188:189], off
	v_lshl_add_u64 v[188:189], v[220:221], 0, s[20:21]
	s_mov_b32 m0, s75
	s_nop 0
	global_load_lds_dwordx4 v[188:189], off
	v_lshl_add_u64 v[188:189], v[222:223], 0, s[20:21]
	s_mov_b32 m0, s67
	s_nop 0
	global_load_lds_dwordx4 v[188:189], off
	ds_read_b128 v[176:179], v195 offset:49152
	ds_read_b128 v[180:183], v195 offset:50176
	ds_read_b128 v[184:187], v195 offset:51200
	ds_read_b128 v[198:201], v195 offset:52224
	ds_read_b128 v[202:205], v195 offset:53248
	ds_read_b128 v[206:209], v195 offset:54272
	ds_read_b128 v[210:213], v195 offset:55296
	ds_read_b128 v[214:217], v195 offset:56320
	s_waitcnt vmcnt(8)
	s_waitcnt lgkmcnt(0)
	s_barrier
	s_waitcnt lgkmcnt(0)
	v_mfma_f32_16x16x32_f16 v[68:71], v[16:19], v[176:179], v[68:71]
	v_mfma_f32_16x16x32_f16 v[52:55], v[16:19], v[184:187], v[52:55]
	v_mfma_f32_16x16x32_f16 v[36:39], v[16:19], v[202:205], v[36:39]
	v_mfma_f32_16x16x32_f16 v[0:3], v[16:19], v[210:213], v[0:3]
	v_mfma_f32_16x16x32_f16 v[68:71], v[20:23], v[180:183], v[68:71]
	v_mfma_f32_16x16x32_f16 v[64:67], v[136:139], v[176:179], v[64:67]
	v_mfma_f32_16x16x32_f16 v[52:55], v[20:23], v[198:201], v[52:55]
	v_mfma_f32_16x16x32_f16 v[48:51], v[136:139], v[184:187], v[48:51]
	v_mfma_f32_16x16x32_f16 v[36:39], v[20:23], v[206:209], v[36:39]
	v_mfma_f32_16x16x32_f16 v[32:35], v[136:139], v[202:205], v[32:35]
	v_mfma_f32_16x16x32_f16 v[20:23], v[20:23], v[214:217], v[0:3]
	v_mfma_f32_16x16x32_f16 v[0:3], v[136:139], v[210:213], v[4:7]
	v_mfma_f32_16x16x32_f16 v[64:67], v[140:143], v[180:183], v[64:67]
	v_mfma_f32_16x16x32_f16 v[48:51], v[140:143], v[198:201], v[48:51]
	v_mfma_f32_16x16x32_f16 v[32:35], v[140:143], v[206:209], v[32:35]
	v_mfma_f32_16x16x32_f16 v[16:19], v[140:143], v[214:217], v[0:3]
	v_mfma_f32_16x16x32_f16 v[0:3], v[144:147], v[176:179], v[60:63]
	v_mfma_f32_16x16x32_f16 v[60:63], v[148:151], v[180:183], v[0:3]
	v_mfma_f32_16x16x32_f16 v[0:3], v[152:155], v[176:179], v[56:59]
	v_mfma_f32_16x16x32_f16 v[56:59], v[156:159], v[180:183], v[0:3]
	v_mfma_f32_16x16x32_f16 v[0:3], v[144:147], v[184:187], v[44:47]
	v_mfma_f32_16x16x32_f16 v[44:47], v[148:151], v[198:201], v[0:3]
	v_mfma_f32_16x16x32_f16 v[0:3], v[152:155], v[184:187], v[40:43]
	v_mfma_f32_16x16x32_f16 v[40:43], v[156:159], v[198:201], v[0:3]
	v_mfma_f32_16x16x32_f16 v[0:3], v[144:147], v[202:205], v[28:31]
	v_mfma_f32_16x16x32_f16 v[28:31], v[148:151], v[206:209], v[0:3]
	v_mfma_f32_16x16x32_f16 v[0:3], v[152:155], v[202:205], v[24:27]
	v_mfma_f32_16x16x32_f16 v[24:27], v[156:159], v[206:209], v[0:3]
	v_mfma_f32_16x16x32_f16 v[0:3], v[144:147], v[210:213], v[12:15]
	v_mfma_f32_16x16x32_f16 v[12:15], v[148:151], v[214:217], v[0:3]
	v_mfma_f32_16x16x32_f16 v[0:3], v[152:155], v[210:213], v[8:11]
	v_mfma_f32_16x16x32_f16 v[8:11], v[156:159], v[214:217], v[0:3]
	s_barrier
	s_add_i32 s62, s62, 2
	s_add_u32 s36, s36, 0x100
	s_addc_u32 s37, s37, 0
	s_add_u32 s60, s60, 0x100
	s_addc_u32 s61, s61, 0
	s_cmp_gt_u32 s62, 13
	s_cbranch_scc0 .LBB0_2566
	s_and_b64 vcc, exec, s[16:17]
	s_cbranch_vccz .LBB0_2569
	s_barrier

; #define PG8_STAGE(bufoff, gbase, voff) do { _Pragma("unroll") for (int _i = 0; _i < 2; ++_i) \
;         __builtin_amdgcn_global_load_lds((const unsigned*)((const char*)(gbase) + (voff)[_i]), (PG8_LAS unsigned*)(lds + (bufoff) + ldsw + _i * 8192), 16, 0, 0); } while (0)
; #define PG8_LDA(dst, b, h) do { _Pragma("unroll") for (int m = 0; m < 4; ++m) _Pragma("unroll") for (int k = 0; k < 2; ++k) dst[m][k] = *(const PG8_LAS bf16x8*)(lds + PG8_SA(b, h) + aoff + m * 2048 + k * 1024); } while (0)
; #define PG8_LDB(dst, b, h) do { _Pragma("unroll") for (int n = 0; n < 2; ++n) _Pragma("unroll") for (int k = 0; k < 2; ++k) dst[n][k] = *(const PG8_LAS bf16x8*)(lds + PG8_SB(b, h) + boff + n * 2048 + k * 1024); } while (0)
; #define PG8_WAIT_V(n) asm volatile("s_waitcnt vmcnt(" #n ")" ::: "memory")
; #define PG8_WAIT_L(n) asm volatile("s_waitcnt lgkmcnt(" #n ")" ::: "memory")
; #define PG8_BAR __builtin_amdgcn_s_barrier()
; #define PG8_SCHED __builtin_amdgcn_sched_barrier(0)
; template <class Epi, class Sched, bool ALIGN_EPI = false, bool SP2 = false, bool F16 = false>
; __device__ __forceinline__ void gemm_phase(PG8_LAS unsigned char* lds, const Gemm g, const Sched& S, const Epi& E, const int wid_in) {
;     ...
;         const bool has_next = S.next(ui + 1, nxt);
;         const char* nA = has_next ? (const char*)g.A + (size_t)nxt.pm * tstep : cA; const char* nB = has_next ? (const char*)g.Bt + (size_t)nxt.pn * tstep : cB;
;         for (int t = 0; t < nt; t += 2) {
;             const bool last = (t == nt - 2);
;             const char* a1 = cA + (size_t)(t + 1) * kstep;
;             const char* a2 = last ? nA : cA + (size_t)(t + 2) * kstep; const char* b2 = last ? nB : cB + (size_t)(t + 2) * kstep;
;             const char* a3 = a2 + kstep; const char* b3 = b2 + kstep;
;             if (last && has_next) S.a_ready(nxt);
;             if constexpr (SP2) {
;             PG8_LDB(B0, 0, 0); PG8_LDB(B1, 0, 1); PG8_SCHED; PG8_LDA(At, 0, 0); PG8_STAGE(PG8_SA(1, 1), a1 + hstep, voffA);
;             PG8_WAIT_V(8); PG8_WAIT_L(0); PG8_BAR; PG8_MMA(0, 0, At, B0); PG8_MMA(0, 1, At, B1); PG8_BAR; PG8_SCHED;
;             PG8_LDA(At, 0, 1); PG8_STAGE(PG8_SB(0, 0), b2, voffB); PG8_STAGE(PG8_SB(0, 1), b2 + hstep, voffB); PG8_STAGE(PG8_SA(0, 0), a2, voffA);
;             PG8_WAIT_V(8); PG8_WAIT_L(0); PG8_BAR; PG8_MMA(1, 0, At, B0); PG8_MMA(1, 1, At, B1); PG8_BAR; PG8_SCHED;
.LBB0_2601:
	s_mov_b64 s[42:43], s[10:11]
	s_add_i32 s10, s30, s40
	s_mov_b64 s[36:37], s[12:13]
	s_mov_b32 s12, s56
	s_mov_b32 s13, s55
	s_and_b32 s55, s10, 3
	s_ashr_i32 s56, s10, 2
	s_and_b64 s[10:11], s[26:27], exec
	s_cselect_b32 s12, s56, s12
	ds_read_b128 v[0:3], v134
	ds_read_b128 v[4:7], v134 offset:1024
	ds_read_b128 v[8:11], v134 offset:2048
	ds_read_b128 v[12:15], v134 offset:3072
	ds_read_b128 v[16:19], v135
	ds_read_b128 v[20:23], v135 offset:1024
	ds_read_b128 v[24:27], v135 offset:2048
	ds_read_b128 v[28:31], v135 offset:3072
	s_cselect_b32 s10, s55, s13
	s_ashr_i32 s13, s12, 31
	s_lshl_b64 s[12:13], s[12:13], 17
	s_add_u32 s12, s41, s12
	s_addc_u32 s13, s44, s13
	s_and_b64 s[30:31], s[26:27], exec
	s_cselect_b32 s35, s13, s37
	s_cselect_b32 s34, s12, s36
	s_ashr_i32 s11, s10, 31
	s_lshl_b64 s[10:11], s[10:11], 17
	s_add_u32 s10, s45, s10
	s_addc_u32 s11, s46, s11
	s_and_b64 s[30:31], s[26:27], exec
	s_cselect_b32 s31, s11, s43
	s_cselect_b32 s30, s10, s42
	s_add_u32 s58, s36, 0x10080
	s_addc_u32 s59, s37, 0
	s_mov_b32 m0, s91
	v_lshl_add_u64 v[64:65], s[58:59], 0, v[130:131]
	ds_read_b128 v[32:35], v136
	ds_read_b128 v[36:39], v136 offset:1024
	ds_read_b128 v[40:43], v136 offset:2048
	ds_read_b128 v[44:47], v136 offset:3072
	ds_read_b128 v[48:51], v136 offset:4096
	ds_read_b128 v[52:55], v136 offset:5120
	ds_read_b128 v[56:59], v136 offset:6144
	ds_read_b128 v[60:63], v136 offset:7168
	global_load_lds_dwordx4 v[64:65], off
	v_lshl_add_u64 v[64:65], s[58:59], 0, v[128:129]
	s_mov_b32 m0, s14
	s_nop 0
	global_load_lds_dwordx4 v[64:65], off
	s_waitcnt vmcnt(8)
	s_waitcnt lgkmcnt(0)
	s_barrier
	s_waitcnt lgkmcnt(0)
	v_mfma_f32_16x16x32_bf16 v[64:67], v[0:3], v[32:35], 0
	v_mfma_f32_16x16x32_bf16 v[68:71], v[8:11], v[32:35], 0
	v_mfma_f32_16x16x32_bf16 v[72:75], v[0:3], v[40:43], 0
	v_mfma_f32_16x16x32_bf16 v[76:79], v[8:11], v[40:43], 0
	v_mfma_f32_16x16x32_bf16 v[80:83], v[0:3], v[48:51], 0
	v_mfma_f32_16x16x32_bf16 v[84:87], v[8:11], v[48:51], 0
	v_mfma_f32_16x16x32_bf16 v[88:91], v[0:3], v[56:59], 0
	v_mfma_f32_16x16x32_bf16 v[92:95], v[8:11], v[56:59], 0
	v_mfma_f32_16x16x32_bf16 v[64:67], v[4:7], v[36:39], v[64:67]
	v_mfma_f32_16x16x32_bf16 v[68:71], v[12:15], v[36:39], v[68:71]
	v_mfma_f32_16x16x32_bf16 v[72:75], v[4:7], v[44:47], v[72:75]
	v_mfma_f32_16x16x32_bf16 v[76:79], v[12:15], v[44:47], v[76:79]
	v_mfma_f32_16x16x32_bf16 v[80:83], v[4:7], v[52:55], v[80:83]
	v_mfma_f32_16x16x32_bf16 v[84:87], v[12:15], v[52:55], v[84:87]
	v_mfma_f32_16x16x32_bf16 v[88:91], v[4:7], v[60:63], v[88:91]
	v_mfma_f32_16x16x32_bf16 v[92:95], v[12:15], v[60:63], v[92:95]
	v_mfma_f32_16x16x32_bf16 v[96:99], v[16:19], v[32:35], 0
	v_mfma_f32_16x16x32_bf16 v[32:35], v[24:27], v[32:35], 0
	v_mfma_f32_16x16x32_bf16 v[96:99], v[20:23], v[36:39], v[96:99]
	v_mfma_f32_16x16x32_bf16 v[32:35], v[28:31], v[36:39], v[32:35]
	v_mfma_f32_16x16x32_bf16 v[36:39], v[16:19], v[40:43], 0
	v_mfma_f32_16x16x32_bf16 v[40:43], v[24:27], v[40:43], 0
	v_mfma_f32_16x16x32_bf16 v[36:39], v[20:23], v[44:47], v[36:39]
	v_mfma_f32_16x16x32_bf16 v[40:43], v[28:31], v[44:47], v[40:43]
	v_mfma_f32_16x16x32_bf16 v[44:47], v[16:19], v[48:51], 0
	v_mfma_f32_16x16x32_bf16 v[48:51], v[24:27], v[48:51], 0
	v_mfma_f32_16x16x32_bf16 v[44:47], v[20:23], v[52:55], v[44:47]
	v_mfma_f32_16x16x32_bf16 v[48:51], v[28:31], v[52:55], v[48:51]
	v_mfma_f32_16x16x32_bf16 v[52:55], v[16:19], v[56:59], 0
	v_mfma_f32_16x16x32_bf16 v[56:59], v[24:27], v[56:59], 0
	v_mfma_f32_16x16x32_bf16 v[52:55], v[20:23], v[60:63], v[52:55]
	v_mfma_f32_16x16x32_bf16 v[56:59], v[28:31], v[60:63], v[56:59]
	s_barrier
	v_lshl_add_u64 v[204:205], s[42:43], 0, v[130:131]
	s_mov_b32 m0, s15
	v_lshl_add_u64 v[140:141], v[204:205], 0, s[22:23]
	v_lshl_add_u64 v[206:207], s[42:43], 0, v[128:129]
	s_add_u32 s58, s42, 0x10100
	global_load_lds_dwordx4 v[140:141], off
	v_lshl_add_u64 v[140:141], v[206:207], 0, s[22:23]
	s_mov_b32 m0, s48
	s_addc_u32 s59, s43, 0
	global_load_lds_dwordx4 v[140:141], off
	v_lshl_add_u64 v[140:141], s[58:59], 0, v[130:131]
	s_mov_b32 m0, s49
	v_lshl_add_u64 v[208:209], s[36:37], 0, v[130:131]
	global_load_lds_dwordx4 v[140:141], off
	v_lshl_add_u64 v[140:141], s[58:59], 0, v[128:129]
	s_mov_b32 m0, s50
	v_lshl_add_u64 v[210:211], s[36:37], 0, v[128:129]
	global_load_lds_dwordx4 v[140:141], off
	v_lshl_add_u64 v[140:141], v[208:209], 0, s[22:23]
	s_mov_b32 m0, s74
	s_nop 0
	global_load_lds_dwordx4 v[140:141], off
	v_lshl_add_u64 v[140:141], v[210:211], 0, s[22:23]
	s_mov_b32 m0, s66
	s_nop 0
	global_load_lds_dwordx4 v[140:141], off
	ds_read_b128 v[60:63], v136 offset:16384
	ds_read_b128 v[100:103], v136 offset:17408
	ds_read_b128 v[104:107], v136 offset:18432
	ds_read_b128 v[108:111], v136 offset:19456
	ds_read_b128 v[112:115], v136 offset:20480
	ds_read_b128 v[116:119], v136 offset:21504
	ds_read_b128 v[120:123], v136 offset:22528
	ds_read_b128 v[124:127], v136 offset:23552
	s_waitcnt vmcnt(8)
	s_waitcnt lgkmcnt(0)
	s_barrier
; #define PG8_STAGE(bufoff, gbase, voff) do { _Pragma("unroll") for (int _i = 0; _i < 2; ++_i) \
;         __builtin_amdgcn_global_load_lds((const unsigned*)((const char*)(gbase) + (voff)[_i]), (PG8_LAS unsigned*)(lds + (bufoff) + ldsw + _i * 8192), 16, 0, 0); } while (0)
; #define PG8_LDA(dst, b, h) do { _Pragma("unroll") for (int m = 0; m < 4; ++m) _Pragma("unroll") for (int k = 0; k < 2; ++k) dst[m][k] = *(const PG8_LAS bf16x8*)(lds + PG8_SA(b, h) + aoff + m * 2048 + k * 1024); } while (0)
; #define PG8_LDB(dst, b, h) do { _Pragma("unroll") for (int n = 0; n < 2; ++n) _Pragma("unroll") for (int k = 0; k < 2; ++k) dst[n][k] = *(const PG8_LAS bf16x8*)(lds + PG8_SB(b, h) + boff + n * 2048 + k * 1024); } while (0)
; #define PG8_MMA(ai, bj, At, Bt) do { __builtin_amdgcn_s_setprio(1); _Pragma("unroll") for (int m = 0; m < 4; ++m) _Pragma("unroll") for (int n = 0; n < 2; ++n) _Pragma("unroll") for (int k = 0; k < 2; ++k) \
;         acc[ai][bj][m][n] = mma16<F16>(Bt[n][k], At[m][k], acc[ai][bj][m][n]); __builtin_amdgcn_s_setprio(0); } while (0)
; #define PG8_WAIT_V(n) asm volatile("s_waitcnt vmcnt(" #n ")" ::: "memory")
; #define PG8_WAIT_L(n) asm volatile("s_waitcnt lgkmcnt(" #n ")" ::: "memory")
; #define PG8_BAR __builtin_amdgcn_s_barrier()
; #define PG8_SCHED __builtin_amdgcn_sched_barrier(0)
; template <class Epi, class Sched, bool ALIGN_EPI = false, bool SP2 = false, bool F16 = false>
; __device__ __forceinline__ void gemm_phase(PG8_LAS unsigned char* lds, const Gemm g, const Sched& S, const Epi& E, const int wid_in) {
;     ...
;             PG8_WAIT_V(8); PG8_WAIT_L(0); PG8_BAR; PG8_MMA(1, 0, At, B0); PG8_MMA(1, 1, At, B1); PG8_BAR; PG8_SCHED;
;             PG8_LDB(B0, 1, 0); PG8_LDB(B1, 1, 1); PG8_SCHED; PG8_LDA(At, 1, 0); PG8_STAGE(PG8_SA(0, 1), a2 + hstep, voffA);
;             PG8_WAIT_V(8); PG8_WAIT_L(0); PG8_BAR; PG8_MMA(0, 0, At, B0); PG8_MMA(0, 1, At, B1); PG8_BAR; PG8_SCHED;
	s_waitcnt lgkmcnt(0)
	v_mfma_f32_16x16x32_bf16 v[140:143], v[0:3], v[60:63], 0
	v_mfma_f32_16x16x32_bf16 v[148:151], v[0:3], v[104:107], 0
	v_mfma_f32_16x16x32_bf16 v[156:159], v[0:3], v[112:115], 0
	v_mfma_f32_16x16x32_bf16 v[0:3], v[0:3], v[120:123], 0
	v_mfma_f32_16x16x32_bf16 v[140:143], v[4:7], v[100:103], v[140:143]
	v_mfma_f32_16x16x32_bf16 v[148:151], v[4:7], v[108:111], v[148:151]
	v_mfma_f32_16x16x32_bf16 v[156:159], v[4:7], v[116:119], v[156:159]
	v_mfma_f32_16x16x32_bf16 v[0:3], v[4:7], v[124:127], v[0:3]
	v_mfma_f32_16x16x32_bf16 v[4:7], v[8:11], v[120:123], 0
	v_mfma_f32_16x16x32_bf16 v[144:147], v[8:11], v[60:63], 0
	v_mfma_f32_16x16x32_bf16 v[152:155], v[8:11], v[104:107], 0
	v_mfma_f32_16x16x32_bf16 v[160:163], v[8:11], v[112:115], 0
	v_mfma_f32_16x16x32_bf16 v[4:7], v[12:15], v[124:127], v[4:7]
	v_mfma_f32_16x16x32_bf16 v[144:147], v[12:15], v[100:103], v[144:147]
	v_mfma_f32_16x16x32_bf16 v[152:155], v[12:15], v[108:111], v[152:155]
	v_mfma_f32_16x16x32_bf16 v[160:163], v[12:15], v[116:119], v[160:163]
	v_mfma_f32_16x16x32_bf16 v[8:11], v[16:19], v[60:63], 0
	v_mfma_f32_16x16x32_bf16 v[12:15], v[24:27], v[60:63], 0
	v_mfma_f32_16x16x32_bf16 v[8:11], v[20:23], v[100:103], v[8:11]
	v_mfma_f32_16x16x32_bf16 v[12:15], v[28:31], v[100:103], v[12:15]
	v_mfma_f32_16x16x32_bf16 v[60:63], v[16:19], v[104:107], 0
	v_mfma_f32_16x16x32_bf16 v[100:103], v[24:27], v[104:107], 0
	v_mfma_f32_16x16x32_bf16 v[104:107], v[16:19], v[112:115], 0
	v_mfma_f32_16x16x32_bf16 v[16:19], v[16:19], v[120:123], 0
	v_mfma_f32_16x16x32_bf16 v[60:63], v[20:23], v[108:111], v[60:63]
	v_mfma_f32_16x16x32_bf16 v[100:103], v[28:31], v[108:111], v[100:103]
	v_mfma_f32_16x16x32_bf16 v[104:107], v[20:23], v[116:119], v[104:107]
	v_mfma_f32_16x16x32_bf16 v[108:111], v[24:27], v[112:115], 0
	v_mfma_f32_16x16x32_bf16 v[16:19], v[20:23], v[124:127], v[16:19]
	v_mfma_f32_16x16x32_bf16 v[20:23], v[24:27], v[120:123], 0
	v_mfma_f32_16x16x32_bf16 v[108:111], v[28:31], v[116:119], v[108:111]
	v_mfma_f32_16x16x32_bf16 v[20:23], v[28:31], v[124:127], v[20:23]
	s_barrier
	s_add_u32 s58, s36, 0x10100
	s_addc_u32 s59, s37, 0
	s_mov_b32 m0, s90
	v_lshl_add_u64 v[212:213], s[58:59], 0, v[130:131]
	global_load_lds_dwordx4 v[212:213], off
	v_lshl_add_u64 v[212:213], s[58:59], 0, v[128:129]
	s_mov_b32 m0, s47
	s_nop 0
	global_load_lds_dwordx4 v[212:213], off
	ds_read_b128 v[24:27], v137
	ds_read_b128 v[28:31], v137 offset:1024
	ds_read_b128 v[112:115], v137 offset:2048
	ds_read_b128 v[116:119], v137 offset:3072
	ds_read_b128 v[120:123], v138
	ds_read_b128 v[124:127], v138 offset:1024
	ds_read_b128 v[164:167], v138 offset:2048
	ds_read_b128 v[168:171], v138 offset:3072
	ds_read_b128 v[172:175], v136 offset:32768
	ds_read_b128 v[176:179], v136 offset:33792
	ds_read_b128 v[180:183], v136 offset:34816
	ds_read_b128 v[184:187], v136 offset:35840
	ds_read_b128 v[188:191], v136 offset:36864
	ds_read_b128 v[192:195], v136 offset:37888
	ds_read_b128 v[196:199], v136 offset:38912
	ds_read_b128 v[200:203], v136 offset:39936
	s_waitcnt vmcnt(8)
	s_waitcnt lgkmcnt(0)
	s_barrier
	s_waitcnt lgkmcnt(0)
	v_mfma_f32_16x16x32_bf16 v[64:67], v[24:27], v[172:175], v[64:67]
	v_mfma_f32_16x16x32_bf16 v[68:71], v[112:115], v[172:175], v[68:71]
	v_mfma_f32_16x16x32_bf16 v[72:75], v[24:27], v[180:183], v[72:75]
	v_mfma_f32_16x16x32_bf16 v[76:79], v[112:115], v[180:183], v[76:79]
	v_mfma_f32_16x16x32_bf16 v[80:83], v[24:27], v[188:191], v[80:83]
	v_mfma_f32_16x16x32_bf16 v[84:87], v[112:115], v[188:191], v[84:87]
	v_mfma_f32_16x16x32_bf16 v[88:91], v[24:27], v[196:199], v[88:91]
	v_mfma_f32_16x16x32_bf16 v[92:95], v[112:115], v[196:199], v[92:95]
	v_mfma_f32_16x16x32_bf16 v[64:67], v[28:31], v[176:179], v[64:67]
	v_mfma_f32_16x16x32_bf16 v[68:71], v[116:119], v[176:179], v[68:71]
	v_mfma_f32_16x16x32_bf16 v[72:75], v[28:31], v[184:187], v[72:75]
	v_mfma_f32_16x16x32_bf16 v[76:79], v[116:119], v[184:187], v[76:79]
	v_mfma_f32_16x16x32_bf16 v[80:83], v[28:31], v[192:195], v[80:83]
	v_mfma_f32_16x16x32_bf16 v[84:87], v[116:119], v[192:195], v[84:87]
	v_mfma_f32_16x16x32_bf16 v[88:91], v[28:31], v[200:203], v[88:91]
	v_mfma_f32_16x16x32_bf16 v[92:95], v[116:119], v[200:203], v[92:95]
	v_mfma_f32_16x16x32_bf16 v[96:99], v[120:123], v[172:175], v[96:99]
	v_mfma_f32_16x16x32_bf16 v[32:35], v[164:167], v[172:175], v[32:35]
	v_mfma_f32_16x16x32_bf16 v[36:39], v[120:123], v[180:183], v[36:39]
	v_mfma_f32_16x16x32_bf16 v[40:43], v[164:167], v[180:183], v[40:43]
	v_mfma_f32_16x16x32_bf16 v[44:47], v[120:123], v[188:191], v[44:47]
	v_mfma_f32_16x16x32_bf16 v[48:51], v[164:167], v[188:191], v[48:51]
	v_mfma_f32_16x16x32_bf16 v[52:55], v[120:123], v[196:199], v[52:55]
	v_mfma_f32_16x16x32_bf16 v[56:59], v[164:167], v[196:199], v[56:59]
	v_mfma_f32_16x16x32_bf16 v[96:99], v[124:127], v[176:179], v[96:99]
	v_mfma_f32_16x16x32_bf16 v[32:35], v[168:171], v[176:179], v[32:35]
	v_mfma_f32_16x16x32_bf16 v[36:39], v[124:127], v[184:187], v[36:39]
	v_mfma_f32_16x16x32_bf16 v[40:43], v[168:171], v[184:187], v[40:43]
	v_mfma_f32_16x16x32_bf16 v[44:47], v[124:127], v[192:195], v[44:47]
	v_mfma_f32_16x16x32_bf16 v[48:51], v[168:171], v[192:195], v[48:51]
	v_mfma_f32_16x16x32_bf16 v[52:55], v[124:127], v[200:203], v[52:55]
	v_mfma_f32_16x16x32_bf16 v[56:59], v[168:171], v[200:203], v[56:59]
	s_barrier
; #define PG8_STAGE(bufoff, gbase, voff) do { _Pragma("unroll") for (int _i = 0; _i < 2; ++_i) \
;         __builtin_amdgcn_global_load_lds((const unsigned*)((const char*)(gbase) + (voff)[_i]), (PG8_LAS unsigned*)(lds + (bufoff) + ldsw + _i * 8192), 16, 0, 0); } while (0)
; #define PG8_LDA(dst, b, h) do { _Pragma("unroll") for (int m = 0; m < 4; ++m) _Pragma("unroll") for (int k = 0; k < 2; ++k) dst[m][k] = *(const PG8_LAS bf16x8*)(lds + PG8_SA(b, h) + aoff + m * 2048 + k * 1024); } while (0)
; #define PG8_LDB(dst, b, h) do { _Pragma("unroll") for (int n = 0; n < 2; ++n) _Pragma("unroll") for (int k = 0; k < 2; ++k) dst[n][k] = *(const PG8_LAS bf16x8*)(lds + PG8_SB(b, h) + boff + n * 2048 + k * 1024); } while (0)
; #define PG8_MMA(ai, bj, At, Bt) do { __builtin_amdgcn_s_setprio(1); _Pragma("unroll") for (int m = 0; m < 4; ++m) _Pragma("unroll") for (int n = 0; n < 2; ++n) _Pragma("unroll") for (int k = 0; k < 2; ++k) \
;         acc[ai][bj][m][n] = mma16<F16>(Bt[n][k], At[m][k], acc[ai][bj][m][n]); __builtin_amdgcn_s_setprio(0); } while (0)
; #define PG8_WAIT_V(n) asm volatile("s_waitcnt vmcnt(" #n ")" ::: "memory")
; template <class Epi, class Sched, bool ALIGN_EPI = false, bool SP2 = false, bool F16 = false>
; __device__ __forceinline__ void gemm_phase(PG8_LAS unsigned char* lds, const Gemm g, const Sched& S, const Epi& E, const int wid_in) {
;     ...
;             PG8_LDB(B0, 0, 0); PG8_LDB(B1, 0, 1); PG8_SCHED; PG8_LDA(At, 0, 0); PG8_STAGE(PG8_SA(1, 1), a1 + hstep, voffA);
;             PG8_WAIT_V(8); PG8_WAIT_L(0); PG8_BAR; PG8_MMA(0, 0, At, B0); PG8_MMA(0, 1, At, B1); PG8_BAR; PG8_SCHED;
;             PG8_LDA(At, 0, 1); PG8_STAGE(PG8_SB(0, 0), b2, voffB); PG8_STAGE(PG8_SB(0, 1), b2 + hstep, voffB); PG8_STAGE(PG8_SA(0, 0), a2, voffA);
;             PG8_WAIT_V(8); PG8_WAIT_L(0); PG8_BAR; PG8_MMA(1, 0, At, B0); PG8_MMA(1, 1, At, B1); PG8_BAR; PG8_SCHED;
;             PG8_LDB(B0, 1, 0); PG8_LDB(B1, 1, 1); PG8_SCHED; PG8_LDA(At, 1, 0); PG8_STAGE(PG8_SA(0, 1), a2 + hstep, voffA);
;             PG8_WAIT_V(8); PG8_WAIT_L(0); PG8_BAR; PG8_MMA(0, 0, At, B0); PG8_MMA(0, 1, At, B1); PG8_BAR; PG8_SCHED;
;             PG8_LDA(At, 1, 1); PG8_STAGE(PG8_SB(1, 0), b3, voffB); PG8_STAGE(PG8_SB(1, 1), b3 + hstep, voffB); PG8_STAGE(PG8_SA(1, 0), a3, voffA);
;             PG8_WAIT_V(8); PG8_WAIT_L(0); PG8_BAR; PG8_MMA(1, 0, At, B0); PG8_MMA(1, 1, At, B1); PG8_BAR; PG8_SCHED;
	s_mov_b32 m0, s51
	v_lshl_add_u64 v[204:205], v[204:205], 0, s[24:25]
	s_add_u32 s42, s42, 0x10180
	global_load_lds_dwordx4 v[204:205], off
	v_lshl_add_u64 v[204:205], v[206:207], 0, s[24:25]
	s_mov_b32 m0, s52
	s_addc_u32 s43, s43, 0
	global_load_lds_dwordx4 v[204:205], off
	v_lshl_add_u64 v[204:205], s[42:43], 0, v[130:131]
	s_mov_b32 m0, s53
	s_nop 0
	global_load_lds_dwordx4 v[204:205], off
	v_lshl_add_u64 v[204:205], s[42:43], 0, v[128:129]
	s_mov_b32 m0, s54
	s_nop 0
	global_load_lds_dwordx4 v[204:205], off
	v_lshl_add_u64 v[204:205], v[208:209], 0, s[24:25]
	s_mov_b32 m0, s75
	s_nop 0
	global_load_lds_dwordx4 v[204:205], off
	v_lshl_add_u64 v[204:205], v[210:211], 0, s[24:25]
	s_mov_b32 m0, s67
	s_nop 0
	global_load_lds_dwordx4 v[204:205], off
	ds_read_b128 v[172:175], v136 offset:49152
	ds_read_b128 v[176:179], v136 offset:50176
	ds_read_b128 v[180:183], v136 offset:51200
	ds_read_b128 v[184:187], v136 offset:52224
	ds_read_b128 v[188:191], v136 offset:53248
	ds_read_b128 v[192:195], v136 offset:54272
	ds_read_b128 v[196:199], v136 offset:55296
	ds_read_b128 v[200:203], v136 offset:56320
	s_waitcnt vmcnt(8)
	s_waitcnt lgkmcnt(0)
	s_barrier
	s_waitcnt lgkmcnt(0)
	v_mfma_f32_16x16x32_bf16 v[0:3], v[24:27], v[196:199], v[0:3]
	v_mfma_f32_16x16x32_bf16 v[4:7], v[112:115], v[196:199], v[4:7]
	v_mfma_f32_16x16x32_bf16 v[140:143], v[24:27], v[172:175], v[140:143]
	v_mfma_f32_16x16x32_bf16 v[144:147], v[112:115], v[172:175], v[144:147]
	v_mfma_f32_16x16x32_bf16 v[148:151], v[24:27], v[180:183], v[148:151]
	v_mfma_f32_16x16x32_bf16 v[152:155], v[112:115], v[180:183], v[152:155]
	v_mfma_f32_16x16x32_bf16 v[156:159], v[24:27], v[188:191], v[156:159]
	v_mfma_f32_16x16x32_bf16 v[160:163], v[112:115], v[188:191], v[160:163]
	v_mfma_f32_16x16x32_bf16 v[0:3], v[28:31], v[200:203], v[0:3]
	v_mfma_f32_16x16x32_bf16 v[4:7], v[116:119], v[200:203], v[4:7]
	v_mfma_f32_16x16x32_bf16 v[140:143], v[28:31], v[176:179], v[140:143]
	v_mfma_f32_16x16x32_bf16 v[144:147], v[116:119], v[176:179], v[144:147]
	v_mfma_f32_16x16x32_bf16 v[148:151], v[28:31], v[184:187], v[148:151]
	v_mfma_f32_16x16x32_bf16 v[152:155], v[116:119], v[184:187], v[152:155]
	v_mfma_f32_16x16x32_bf16 v[156:159], v[28:31], v[192:195], v[156:159]
	v_mfma_f32_16x16x32_bf16 v[160:163], v[116:119], v[192:195], v[160:163]
	v_mfma_f32_16x16x32_bf16 v[8:11], v[120:123], v[172:175], v[8:11]
	v_mfma_f32_16x16x32_bf16 v[12:15], v[164:167], v[172:175], v[12:15]
	v_mfma_f32_16x16x32_bf16 v[24:27], v[120:123], v[180:183], v[60:63]
	v_mfma_f32_16x16x32_bf16 v[28:31], v[164:167], v[180:183], v[100:103]
	v_mfma_f32_16x16x32_bf16 v[60:63], v[120:123], v[188:191], v[104:107]
	v_mfma_f32_16x16x32_bf16 v[100:103], v[164:167], v[188:191], v[108:111]
	v_mfma_f32_16x16x32_bf16 v[16:19], v[120:123], v[196:199], v[16:19]
	v_mfma_f32_16x16x32_bf16 v[20:23], v[164:167], v[196:199], v[20:23]
	v_mfma_f32_16x16x32_bf16 v[8:11], v[124:127], v[176:179], v[8:11]
	v_mfma_f32_16x16x32_bf16 v[12:15], v[168:171], v[176:179], v[12:15]
	v_mfma_f32_16x16x32_bf16 v[24:27], v[124:127], v[184:187], v[24:27]
	v_mfma_f32_16x16x32_bf16 v[28:31], v[168:171], v[184:187], v[28:31]
	v_mfma_f32_16x16x32_bf16 v[60:63], v[124:127], v[192:195], v[60:63]
	v_mfma_f32_16x16x32_bf16 v[100:103], v[168:171], v[192:195], v[100:103]
	v_mfma_f32_16x16x32_bf16 v[16:19], v[124:127], v[200:203], v[16:19]
	v_mfma_f32_16x16x32_bf16 v[20:23], v[168:171], v[200:203], v[20:23]
	s_barrier
	s_add_u32 s36, s36, 0x10180
	s_addc_u32 s37, s37, 0
	s_mov_b32 m0, s91
	v_lshl_add_u64 v[204:205], s[36:37], 0, v[130:131]
	global_load_lds_dwordx4 v[204:205], off
	v_lshl_add_u64 v[204:205], s[36:37], 0, v[128:129]
	s_mov_b32 m0, s14
	s_nop 0
	global_load_lds_dwordx4 v[204:205], off
	ds_read_b128 v[104:107], v134
	ds_read_b128 v[108:111], v134 offset:1024
	ds_read_b128 v[112:115], v134 offset:2048
	ds_read_b128 v[116:119], v134 offset:3072
	ds_read_b128 v[120:123], v135
	ds_read_b128 v[124:127], v135 offset:1024
	ds_read_b128 v[164:167], v135 offset:2048
	ds_read_b128 v[168:171], v135 offset:3072
	ds_read_b128 v[172:175], v136
	ds_read_b128 v[176:179], v136 offset:1024
	ds_read_b128 v[180:183], v136 offset:2048
	ds_read_b128 v[184:187], v136 offset:3072
	ds_read_b128 v[188:191], v136 offset:4096
	ds_read_b128 v[192:195], v136 offset:5120
	ds_read_b128 v[196:199], v136 offset:6144
	ds_read_b128 v[200:203], v136 offset:7168
	s_waitcnt vmcnt(8)
	s_waitcnt lgkmcnt(0)
	s_barrier
	s_waitcnt lgkmcnt(0)
	v_mfma_f32_16x16x32_bf16 v[64:67], v[104:107], v[172:175], v[64:67]
	v_mfma_f32_16x16x32_bf16 v[68:71], v[112:115], v[172:175], v[68:71]
	v_mfma_f32_16x16x32_bf16 v[72:75], v[104:107], v[180:183], v[72:75]
	v_mfma_f32_16x16x32_bf16 v[76:79], v[112:115], v[180:183], v[76:79]
	v_mfma_f32_16x16x32_bf16 v[80:83], v[104:107], v[188:191], v[80:83]
	v_mfma_f32_16x16x32_bf16 v[84:87], v[112:115], v[188:191], v[84:87]
	v_mfma_f32_16x16x32_bf16 v[88:91], v[104:107], v[196:199], v[88:91]
	v_mfma_f32_16x16x32_bf16 v[92:95], v[112:115], v[196:199], v[92:95]
	v_mfma_f32_16x16x32_bf16 v[64:67], v[108:111], v[176:179], v[64:67]
	v_mfma_f32_16x16x32_bf16 v[68:71], v[116:119], v[176:179], v[68:71]
	v_mfma_f32_16x16x32_bf16 v[72:75], v[108:111], v[184:187], v[72:75]
	v_mfma_f32_16x16x32_bf16 v[76:79], v[116:119], v[184:187], v[76:79]
	v_mfma_f32_16x16x32_bf16 v[80:83], v[108:111], v[192:195], v[80:83]
	v_mfma_f32_16x16x32_bf16 v[84:87], v[116:119], v[192:195], v[84:87]
	v_mfma_f32_16x16x32_bf16 v[88:91], v[108:111], v[200:203], v[88:91]
	v_mfma_f32_16x16x32_bf16 v[92:95], v[116:119], v[200:203], v[92:95]
	v_mfma_f32_16x16x32_bf16 v[32:35], v[164:167], v[172:175], v[32:35]
	v_mfma_f32_16x16x32_bf16 v[96:99], v[120:123], v[172:175], v[96:99]
	v_mfma_f32_16x16x32_bf16 v[172:175], v[168:171], v[176:179], v[32:35]
	v_mfma_f32_16x16x32_bf16 v[32:35], v[120:123], v[180:183], v[36:39]
	v_mfma_f32_16x16x32_bf16 v[204:207], v[124:127], v[176:179], v[96:99]
	v_mfma_f32_16x16x32_bf16 v[176:179], v[124:127], v[184:187], v[32:35]
	v_mfma_f32_16x16x32_bf16 v[32:35], v[164:167], v[180:183], v[40:43]
	v_mfma_f32_16x16x32_bf16 v[40:43], v[168:171], v[184:187], v[32:35]
	v_mfma_f32_16x16x32_bf16 v[32:35], v[120:123], v[188:191], v[44:47]
	v_mfma_f32_16x16x32_bf16 v[44:47], v[124:127], v[192:195], v[32:35]
	v_mfma_f32_16x16x32_bf16 v[32:35], v[164:167], v[188:191], v[48:51]
	v_mfma_f32_16x16x32_bf16 v[48:51], v[168:171], v[192:195], v[32:35]
	v_mfma_f32_16x16x32_bf16 v[32:35], v[120:123], v[196:199], v[52:55]
	v_mfma_f32_16x16x32_bf16 v[52:55], v[124:127], v[200:203], v[32:35]
	v_mfma_f32_16x16x32_bf16 v[32:35], v[164:167], v[196:199], v[56:59]
	v_mfma_f32_16x16x32_bf16 v[56:59], v[168:171], v[200:203], v[32:35]
	s_barrier
; #define PG8_STAGE(bufoff, gbase, voff) do { _Pragma("unroll") for (int _i = 0; _i < 2; ++_i) \
;         __builtin_amdgcn_global_load_lds((const unsigned*)((const char*)(gbase) + (voff)[_i]), (PG8_LAS unsigned*)(lds + (bufoff) + ldsw + _i * 8192), 16, 0, 0); } while (0)
; #define PG8_LDA(dst, b, h) do { _Pragma("unroll") for (int m = 0; m < 4; ++m) _Pragma("unroll") for (int k = 0; k < 2; ++k) dst[m][k] = *(const PG8_LAS bf16x8*)(lds + PG8_SA(b, h) + aoff + m * 2048 + k * 1024); } while (0)
; #define PG8_LDB(dst, b, h) do { _Pragma("unroll") for (int n = 0; n < 2; ++n) _Pragma("unroll") for (int k = 0; k < 2; ++k) dst[n][k] = *(const PG8_LAS bf16x8*)(lds + PG8_SB(b, h) + boff + n * 2048 + k * 1024); } while (0)
; #define PG8_MMA(ai, bj, At, Bt) do { __builtin_amdgcn_s_setprio(1); _Pragma("unroll") for (int m = 0; m < 4; ++m) _Pragma("unroll") for (int n = 0; n < 2; ++n) _Pragma("unroll") for (int k = 0; k < 2; ++k) \
;         acc[ai][bj][m][n] = mma16<F16>(Bt[n][k], At[m][k], acc[ai][bj][m][n]); __builtin_amdgcn_s_setprio(0); } while (0)
; #define PG8_WAIT_V(n) asm volatile("s_waitcnt vmcnt(" #n ")" ::: "memory")
; #define PG8_WAIT_L(n) asm volatile("s_waitcnt lgkmcnt(" #n ")" ::: "memory")
; #define PG8_BAR __builtin_amdgcn_s_barrier()
; #define PG8_SCHED __builtin_amdgcn_sched_barrier(0)
; template <class Epi, class Sched, bool ALIGN_EPI = false, bool SP2 = false, bool F16 = false>
; __device__ __forceinline__ void gemm_phase(PG8_LAS unsigned char* lds, const Gemm g, const Sched& S, const Epi& E, const int wid_in) {
;     ...
;             PG8_LDA(At, 0, 1); PG8_STAGE(PG8_SB(0, 0), b2, voffB); PG8_STAGE(PG8_SB(0, 1), b2 + hstep, voffB); PG8_STAGE(PG8_SA(0, 0), a2, voffA);
;             PG8_WAIT_V(8); PG8_WAIT_L(0); PG8_BAR; PG8_MMA(1, 0, At, B0); PG8_MMA(1, 1, At, B1); PG8_BAR; PG8_SCHED;
;             PG8_LDB(B0, 1, 0); PG8_LDB(B1, 1, 1); PG8_SCHED; PG8_LDA(At, 1, 0); PG8_STAGE(PG8_SA(0, 1), a2 + hstep, voffA);
;             PG8_WAIT_V(8); PG8_WAIT_L(0); PG8_BAR; PG8_MMA(0, 0, At, B0); PG8_MMA(0, 1, At, B1); PG8_BAR; PG8_SCHED;
	s_mov_b32 m0, s15
	v_lshl_add_u64 v[240:241], s[30:31], 0, v[130:131]
	s_add_u32 s36, s30, 0x10000
	s_nop 1
	global_load_lds_dwordx4 v[240:241], off
	v_lshl_add_u64 v[242:243], s[30:31], 0, v[128:129]
	s_mov_b32 m0, s48
	s_addc_u32 s37, s31, 0
	global_load_lds_dwordx4 v[242:243], off
	v_lshl_add_u64 v[200:201], s[36:37], 0, v[130:131]
	s_mov_b32 m0, s49
	v_lshl_add_u64 v[244:245], s[34:35], 0, v[130:131]
	global_load_lds_dwordx4 v[200:201], off
	v_lshl_add_u64 v[200:201], s[36:37], 0, v[128:129]
	s_mov_b32 m0, s50
	v_lshl_add_u64 v[246:247], s[34:35], 0, v[128:129]
	global_load_lds_dwordx4 v[200:201], off
	s_mov_b32 m0, s74
	s_nop 0
	global_load_lds_dwordx4 v[244:245], off
	s_mov_b32 m0, s66
	s_nop 0
	global_load_lds_dwordx4 v[246:247], off
	ds_read_b128 v[32:35], v136 offset:16384
	ds_read_b128 v[36:39], v136 offset:17408
	ds_read_b128 v[96:99], v136 offset:18432
	ds_read_b128 v[180:183], v136 offset:19456
	ds_read_b128 v[184:187], v136 offset:20480
	ds_read_b128 v[188:191], v136 offset:21504
	ds_read_b128 v[192:195], v136 offset:22528
	ds_read_b128 v[196:199], v136 offset:23552
	s_waitcnt vmcnt(8)
	s_waitcnt lgkmcnt(0)
	s_barrier
	s_waitcnt lgkmcnt(0)
	v_mfma_f32_16x16x32_bf16 v[0:3], v[104:107], v[192:195], v[0:3]
	v_mfma_f32_16x16x32_bf16 v[140:143], v[104:107], v[32:35], v[140:143]
	v_mfma_f32_16x16x32_bf16 v[144:147], v[112:115], v[32:35], v[144:147]
	v_mfma_f32_16x16x32_bf16 v[148:151], v[104:107], v[96:99], v[148:151]
	v_mfma_f32_16x16x32_bf16 v[152:155], v[112:115], v[96:99], v[152:155]
	v_mfma_f32_16x16x32_bf16 v[156:159], v[104:107], v[184:187], v[156:159]
	v_mfma_f32_16x16x32_bf16 v[160:163], v[112:115], v[184:187], v[160:163]
	v_mfma_f32_16x16x32_bf16 v[0:3], v[108:111], v[196:199], v[0:3]
	v_mfma_f32_16x16x32_bf16 v[4:7], v[112:115], v[192:195], v[4:7]
	v_mfma_f32_16x16x32_bf16 v[140:143], v[108:111], v[36:39], v[140:143]
	v_mfma_f32_16x16x32_bf16 v[144:147], v[116:119], v[36:39], v[144:147]
	v_mfma_f32_16x16x32_bf16 v[148:151], v[108:111], v[180:183], v[148:151]
	v_mfma_f32_16x16x32_bf16 v[152:155], v[116:119], v[180:183], v[152:155]
	v_mfma_f32_16x16x32_bf16 v[156:159], v[108:111], v[188:191], v[156:159]
	v_mfma_f32_16x16x32_bf16 v[160:163], v[116:119], v[188:191], v[160:163]
	v_mfma_f32_16x16x32_bf16 v[200:203], v[116:119], v[196:199], v[4:7]
	v_mfma_f32_16x16x32_bf16 v[4:7], v[120:123], v[32:35], v[8:11]
	v_mfma_f32_16x16x32_bf16 v[8:11], v[124:127], v[36:39], v[4:7]
	v_mfma_f32_16x16x32_bf16 v[4:7], v[164:167], v[32:35], v[12:15]
	v_mfma_f32_16x16x32_bf16 v[12:15], v[168:171], v[36:39], v[4:7]
	v_mfma_f32_16x16x32_bf16 v[4:7], v[120:123], v[96:99], v[24:27]
	v_mfma_f32_16x16x32_bf16 v[24:27], v[124:127], v[180:183], v[4:7]
	v_mfma_f32_16x16x32_bf16 v[4:7], v[164:167], v[96:99], v[28:31]
	v_mfma_f32_16x16x32_bf16 v[28:31], v[168:171], v[180:183], v[4:7]
	v_mfma_f32_16x16x32_bf16 v[4:7], v[120:123], v[184:187], v[60:63]
	v_mfma_f32_16x16x32_bf16 v[180:183], v[124:127], v[188:191], v[4:7]
	v_mfma_f32_16x16x32_bf16 v[4:7], v[164:167], v[184:187], v[100:103]
	v_mfma_f32_16x16x32_bf16 v[184:187], v[168:171], v[188:191], v[4:7]
	v_mfma_f32_16x16x32_bf16 v[4:7], v[120:123], v[192:195], v[16:19]
	v_mfma_f32_16x16x32_bf16 v[188:191], v[124:127], v[196:199], v[4:7]
	v_mfma_f32_16x16x32_bf16 v[4:7], v[164:167], v[192:195], v[20:23]
	v_mfma_f32_16x16x32_bf16 v[164:167], v[168:171], v[196:199], v[4:7]
	s_barrier
	s_nop 4
	s_add_u32 s34, s34, 0x10000
	s_addc_u32 s35, s35, 0
	s_mov_b32 m0, s90
	v_lshl_add_u64 v[32:33], s[34:35], 0, v[130:131]
	global_load_lds_dwordx4 v[32:33], off
	v_lshl_add_u64 v[32:33], s[34:35], 0, v[128:129]
	s_mov_b32 m0, s47
	s_nop 0
	global_load_lds_dwordx4 v[32:33], off
	ds_read_b128 v[4:7], v137
	ds_read_b128 v[60:63], v137 offset:1024
	ds_read_b128 v[168:171], v137 offset:2048
	ds_read_b128 v[192:195], v137 offset:3072
	ds_read_b128 v[196:199], v138
	ds_read_b128 v[208:211], v138 offset:1024
	ds_read_b128 v[212:215], v138 offset:2048
	ds_read_b128 v[216:219], v138 offset:3072
	ds_read_b128 v[16:19], v136 offset:32768
	ds_read_b128 v[20:23], v136 offset:33792
	ds_read_b128 v[104:107], v136 offset:34816
	ds_read_b128 v[220:223], v136 offset:35840
	ds_read_b128 v[224:227], v136 offset:36864
	ds_read_b128 v[228:231], v136 offset:37888
	ds_read_b128 v[232:235], v136 offset:38912
	ds_read_b128 v[236:239], v136 offset:39936
	s_waitcnt vmcnt(8)
	s_waitcnt lgkmcnt(0)
	s_barrier
; #define PG8_STAGE(bufoff, gbase, voff) do { _Pragma("unroll") for (int _i = 0; _i < 2; ++_i) \
;         __builtin_amdgcn_global_load_lds((const unsigned*)((const char*)(gbase) + (voff)[_i]), (PG8_LAS unsigned*)(lds + (bufoff) + ldsw + _i * 8192), 16, 0, 0); } while (0)
; #define PG8_LDA(dst, b, h) do { _Pragma("unroll") for (int m = 0; m < 4; ++m) _Pragma("unroll") for (int k = 0; k < 2; ++k) dst[m][k] = *(const PG8_LAS bf16x8*)(lds + PG8_SA(b, h) + aoff + m * 2048 + k * 1024); } while (0)
; #define PG8_LDB(dst, b, h) do { _Pragma("unroll") for (int n = 0; n < 2; ++n) _Pragma("unroll") for (int k = 0; k < 2; ++k) dst[n][k] = *(const PG8_LAS bf16x8*)(lds + PG8_SB(b, h) + boff + n * 2048 + k * 1024); } while (0)
; #define PG8_MMA(ai, bj, At, Bt) do { __builtin_amdgcn_s_setprio(1); _Pragma("unroll") for (int m = 0; m < 4; ++m) _Pragma("unroll") for (int n = 0; n < 2; ++n) _Pragma("unroll") for (int k = 0; k < 2; ++k) \
;         acc[ai][bj][m][n] = mma16<F16>(Bt[n][k], At[m][k], acc[ai][bj][m][n]); __builtin_amdgcn_s_setprio(0); } while (0)
; #define PG8_WAIT_V(n) asm volatile("s_waitcnt vmcnt(" #n ")" ::: "memory")
; #define PG8_WAIT_L(n) asm volatile("s_waitcnt lgkmcnt(" #n ")" ::: "memory")
; #define PG8_BAR __builtin_amdgcn_s_barrier()
; #define PG8_SCHED __builtin_amdgcn_sched_barrier(0)
; template <class Epi, class Sched, bool ALIGN_EPI = false, bool SP2 = false, bool F16 = false>
; __device__ __forceinline__ void gemm_phase(PG8_LAS unsigned char* lds, const Gemm g, const Sched& S, const Epi& E, const int wid_in) {
;     ...
;             PG8_WAIT_V(8); PG8_WAIT_L(0); PG8_BAR; PG8_MMA(1, 0, At, B0); PG8_MMA(1, 1, At, B1); PG8_BAR; PG8_SCHED;
;             PG8_LDB(B0, 1, 0); PG8_LDB(B1, 1, 1); PG8_SCHED; PG8_LDA(At, 1, 0); PG8_STAGE(PG8_SA(0, 1), a2 + hstep, voffA);
;             PG8_WAIT_V(8); PG8_WAIT_L(0); PG8_BAR; PG8_MMA(0, 0, At, B0); PG8_MMA(0, 1, At, B1); PG8_BAR; PG8_SCHED;
;             PG8_LDA(At, 1, 1); PG8_STAGE(PG8_SB(1, 0), b3, voffB); PG8_STAGE(PG8_SB(1, 1), b3 + hstep, voffB); PG8_STAGE(PG8_SA(1, 0), a3, voffA);
;             PG8_WAIT_V(8); PG8_WAIT_L(0); PG8_BAR; PG8_MMA(1, 0, At, B0); PG8_MMA(1, 1, At, B1); PG8_BAR; PG8_SCHED;
	s_waitcnt lgkmcnt(0)
	v_mfma_f32_16x16x32_bf16 v[32:35], v[4:7], v[16:19], v[64:67]
	v_mfma_f32_16x16x32_bf16 v[116:119], v[60:63], v[20:23], v[32:35]
	v_mfma_f32_16x16x32_bf16 v[32:35], v[168:171], v[16:19], v[68:71]
	v_mfma_f32_16x16x32_bf16 v[112:115], v[192:195], v[20:23], v[32:35]
	v_mfma_f32_16x16x32_bf16 v[32:35], v[4:7], v[104:107], v[72:75]
	v_mfma_f32_16x16x32_bf16 v[100:103], v[60:63], v[220:223], v[32:35]
	v_mfma_f32_16x16x32_bf16 v[32:35], v[168:171], v[104:107], v[76:79]
	v_mfma_f32_16x16x32_bf16 v[96:99], v[192:195], v[220:223], v[32:35]
	v_mfma_f32_16x16x32_bf16 v[32:35], v[4:7], v[224:227], v[80:83]
	v_mfma_f32_16x16x32_bf16 v[68:71], v[60:63], v[228:231], v[32:35]
	v_mfma_f32_16x16x32_bf16 v[32:35], v[168:171], v[224:227], v[84:87]
	v_mfma_f32_16x16x32_bf16 v[64:67], v[192:195], v[228:231], v[32:35]
	v_mfma_f32_16x16x32_bf16 v[32:35], v[4:7], v[232:235], v[88:91]
	v_mfma_f32_16x16x32_bf16 v[36:39], v[60:63], v[236:239], v[32:35]
	v_mfma_f32_16x16x32_bf16 v[32:35], v[168:171], v[232:235], v[92:95]
	v_mfma_f32_16x16x32_bf16 v[32:35], v[192:195], v[236:239], v[32:35]
	v_mfma_f32_16x16x32_bf16 v[72:75], v[196:199], v[16:19], v[204:207]
	v_mfma_f32_16x16x32_bf16 v[16:19], v[212:215], v[16:19], v[172:175]
	v_mfma_f32_16x16x32_bf16 v[120:123], v[216:219], v[20:23], v[16:19]
	v_mfma_f32_16x16x32_bf16 v[16:19], v[196:199], v[104:107], v[176:179]
	v_mfma_f32_16x16x32_bf16 v[108:111], v[208:211], v[220:223], v[16:19]
	v_mfma_f32_16x16x32_bf16 v[16:19], v[212:215], v[104:107], v[40:43]
	v_mfma_f32_16x16x32_bf16 v[104:107], v[216:219], v[220:223], v[16:19]
	v_mfma_f32_16x16x32_bf16 v[16:19], v[196:199], v[224:227], v[44:47]
	v_mfma_f32_16x16x32_bf16 v[80:83], v[208:211], v[228:231], v[16:19]
	v_mfma_f32_16x16x32_bf16 v[16:19], v[212:215], v[224:227], v[48:51]
	v_mfma_f32_16x16x32_bf16 v[124:127], v[208:211], v[20:23], v[72:75]
	v_mfma_f32_16x16x32_bf16 v[72:75], v[216:219], v[228:231], v[16:19]
	v_mfma_f32_16x16x32_bf16 v[16:19], v[196:199], v[232:235], v[52:55]
	v_mfma_f32_16x16x32_bf16 v[48:51], v[208:211], v[236:239], v[16:19]
	v_mfma_f32_16x16x32_bf16 v[16:19], v[212:215], v[232:235], v[56:59]
	v_mfma_f32_16x16x32_bf16 v[40:43], v[216:219], v[236:239], v[16:19]
	s_barrier
	s_mov_b32 m0, s51
	s_nop 3
	v_lshl_add_u64 v[16:17], v[240:241], 0, s[20:21]
	s_add_u32 s30, s30, 0x10080
	global_load_lds_dwordx4 v[16:17], off
	v_lshl_add_u64 v[16:17], v[242:243], 0, s[20:21]
	s_mov_b32 m0, s52
	s_addc_u32 s31, s31, 0
	global_load_lds_dwordx4 v[16:17], off
	v_lshl_add_u64 v[16:17], s[30:31], 0, v[130:131]
	s_mov_b32 m0, s53
	s_nop 0
	global_load_lds_dwordx4 v[16:17], off
	v_lshl_add_u64 v[16:17], s[30:31], 0, v[128:129]
	s_mov_b32 m0, s54
	s_nop 0
	global_load_lds_dwordx4 v[16:17], off
	v_lshl_add_u64 v[16:17], v[244:245], 0, s[20:21]
	s_mov_b32 m0, s75
	s_nop 0
	global_load_lds_dwordx4 v[16:17], off
	v_lshl_add_u64 v[16:17], v[246:247], 0, s[20:21]
	s_mov_b32 m0, s67
	s_nop 0
	global_load_lds_dwordx4 v[16:17], off
	ds_read_b128 v[56:59], v136 offset:49152
	ds_read_b128 v[88:91], v136 offset:50176
	ds_read_b128 v[172:175], v136 offset:51200
	ds_read_b128 v[176:179], v136 offset:52224
	ds_read_b128 v[204:207], v136 offset:53248
	ds_read_b128 v[220:223], v136 offset:54272
	ds_read_b128 v[224:227], v136 offset:55296
	ds_read_b128 v[228:231], v136 offset:56320
	s_waitcnt vmcnt(8)
	s_waitcnt lgkmcnt(0)
	s_barrier
	s_waitcnt lgkmcnt(0)
	v_mfma_f32_16x16x32_bf16 v[16:19], v[4:7], v[56:59], v[140:143]
	v_mfma_f32_16x16x32_bf16 v[84:87], v[60:63], v[88:91], v[16:19]
	v_mfma_f32_16x16x32_bf16 v[16:19], v[168:171], v[56:59], v[144:147]
	v_mfma_f32_16x16x32_bf16 v[76:79], v[192:195], v[88:91], v[16:19]
	v_mfma_f32_16x16x32_bf16 v[16:19], v[4:7], v[172:175], v[148:151]
	v_mfma_f32_16x16x32_bf16 v[52:55], v[60:63], v[176:179], v[16:19]
	v_mfma_f32_16x16x32_bf16 v[16:19], v[168:171], v[172:175], v[152:155]
	v_mfma_f32_16x16x32_bf16 v[44:47], v[192:195], v[176:179], v[16:19]
	v_mfma_f32_16x16x32_bf16 v[16:19], v[4:7], v[204:207], v[156:159]
	v_mfma_f32_16x16x32_bf16 v[0:3], v[4:7], v[224:227], v[0:3]
	v_mfma_f32_16x16x32_bf16 v[20:23], v[60:63], v[220:223], v[16:19]
	v_mfma_f32_16x16x32_bf16 v[16:19], v[168:171], v[204:207], v[160:163]
	v_mfma_f32_16x16x32_bf16 v[4:7], v[60:63], v[228:231], v[0:3]
	v_mfma_f32_16x16x32_bf16 v[0:3], v[168:171], v[224:227], v[200:203]
	v_mfma_f32_16x16x32_bf16 v[16:19], v[192:195], v[220:223], v[16:19]
	v_mfma_f32_16x16x32_bf16 v[0:3], v[192:195], v[228:231], v[0:3]
	v_mfma_f32_16x16x32_bf16 v[8:11], v[196:199], v[56:59], v[8:11]
	v_mfma_f32_16x16x32_bf16 v[92:95], v[208:211], v[88:91], v[8:11]
	v_mfma_f32_16x16x32_bf16 v[8:11], v[212:215], v[56:59], v[12:15]
	v_mfma_f32_16x16x32_bf16 v[88:91], v[216:219], v[88:91], v[8:11]
	v_mfma_f32_16x16x32_bf16 v[8:11], v[196:199], v[172:175], v[24:27]
	v_mfma_f32_16x16x32_bf16 v[60:63], v[208:211], v[176:179], v[8:11]
	v_mfma_f32_16x16x32_bf16 v[8:11], v[212:215], v[172:175], v[28:31]
	v_mfma_f32_16x16x32_bf16 v[56:59], v[216:219], v[176:179], v[8:11]
	v_mfma_f32_16x16x32_bf16 v[8:11], v[196:199], v[204:207], v[180:183]
	v_mfma_f32_16x16x32_bf16 v[28:31], v[208:211], v[220:223], v[8:11]
	v_mfma_f32_16x16x32_bf16 v[8:11], v[212:215], v[204:207], v[184:187]
	v_mfma_f32_16x16x32_bf16 v[24:27], v[216:219], v[220:223], v[8:11]
	v_mfma_f32_16x16x32_bf16 v[8:11], v[196:199], v[224:227], v[188:191]
	v_mfma_f32_16x16x32_bf16 v[12:15], v[208:211], v[228:231], v[8:11]
	v_mfma_f32_16x16x32_bf16 v[8:11], v[212:215], v[224:227], v[164:167]
	v_mfma_f32_16x16x32_bf16 v[8:11], v[216:219], v[228:231], v[8:11]
	s_barrier
	s_and_b64 vcc, exec, s[8:9]
	s_cbranch_vccnz .LBB0_2603
	s_barrier

; #define PG8_STAGE(bufoff, gbase, voff) do { _Pragma("unroll") for (int _i = 0; _i < 2; ++_i) \
;         __builtin_amdgcn_global_load_lds((const unsigned*)((const char*)(gbase) + (voff)[_i]), (PG8_LAS unsigned*)(lds + (bufoff) + ldsw + _i * 8192), 16, 0, 0); } while (0)
; #define PG8_LDA(dst, b, h) do { _Pragma("unroll") for (int m = 0; m < 4; ++m) _Pragma("unroll") for (int k = 0; k < 2; ++k) dst[m][k] = *(const PG8_LAS bf16x8*)(lds + PG8_SA(b, h) + aoff + m * 2048 + k * 1024); } while (0)
; #define PG8_LDB(dst, b, h) do { _Pragma("unroll") for (int n = 0; n < 2; ++n) _Pragma("unroll") for (int k = 0; k < 2; ++k) dst[n][k] = *(const PG8_LAS bf16x8*)(lds + PG8_SB(b, h) + boff + n * 2048 + k * 1024); } while (0)
; #define PG8_MMA(ai, bj, At, Bt) do { __builtin_amdgcn_s_setprio(1); _Pragma("unroll") for (int m = 0; m < 4; ++m) _Pragma("unroll") for (int n = 0; n < 2; ++n) _Pragma("unroll") for (int k = 0; k < 2; ++k) \
;         acc[ai][bj][m][n] = mma16<F16>(Bt[n][k], At[m][k], acc[ai][bj][m][n]); __builtin_amdgcn_s_setprio(0); } while (0)
; #define PG8_WAIT_V(n) asm volatile("s_waitcnt vmcnt(" #n ")" ::: "memory")
; #define PG8_WAIT_L(n) asm volatile("s_waitcnt lgkmcnt(" #n ")" ::: "memory")
; template <class Epi, class Sched, bool ALIGN_EPI = false, bool SP2 = false, bool F16 = false>
; __device__ __forceinline__ void gemm_phase(PG8_LAS unsigned char* lds, const Gemm g, const Sched& S, const Epi& E, const int wid_in) {
;     ...
;             const bool last = (t == nt - 2);
;             const char* a1 = cA + (size_t)(t + 1) * kstep;
;             const char* a2 = last ? nA : cA + (size_t)(t + 2) * kstep; const char* b2 = last ? nB : cB + (size_t)(t + 2) * kstep;
;             const char* a3 = a2 + kstep; const char* b3 = b2 + kstep;
;             if (last && has_next) S.a_ready(nxt);
;             if constexpr (SP2) {
;             PG8_LDB(B0, 0, 0); PG8_LDB(B1, 0, 1); PG8_SCHED; PG8_LDA(At, 0, 0); PG8_STAGE(PG8_SA(1, 1), a1 + hstep, voffA);
;             PG8_WAIT_V(8); PG8_WAIT_L(0); PG8_BAR; PG8_MMA(0, 0, At, B0); PG8_MMA(0, 1, At, B1); PG8_BAR; PG8_SCHED;
;             PG8_LDA(At, 0, 1); PG8_STAGE(PG8_SB(0, 0), b2, voffB); PG8_STAGE(PG8_SB(0, 1), b2 + hstep, voffB); PG8_STAGE(PG8_SA(0, 0), a2, voffA);
;             PG8_WAIT_V(8); PG8_WAIT_L(0); PG8_BAR; PG8_MMA(1, 0, At, B0); PG8_MMA(1, 1, At, B1); PG8_BAR; PG8_SCHED;
.LBB0_2697:
	ds_read_b128 v[128:131], v189
	ds_read_b128 v[132:135], v189 offset:1024
	ds_read_b128 v[136:139], v189 offset:2048
	ds_read_b128 v[140:143], v189 offset:3072
	ds_read_b128 v[144:147], v190
	ds_read_b128 v[148:151], v190 offset:1024
	ds_read_b128 v[168:171], v190 offset:2048
	ds_read_b128 v[172:175], v190 offset:3072
	s_add_u32 s30, s28, 0x100
	s_addc_u32 s31, s29, 0
	s_cmp_eq_u32 s55, 40
	s_cselect_b32 s37, s11, s31
	s_cselect_b32 s36, s10, s30
	s_cselect_b32 s35, s27, s54
	s_cselect_b32 s34, s26, s53
	s_mov_b32 m0, s91
	v_lshl_add_u64 v[184:185], s[28:29], 0, v[160:161]
	ds_read_b128 v[176:179], v191
	ds_read_b128 v[180:183], v191 offset:1024
	ds_read_b128 v[192:195], v191 offset:2048
	ds_read_b128 v[196:199], v191 offset:3072
	ds_read_b128 v[200:203], v191 offset:4096
	ds_read_b128 v[204:207], v191 offset:5120
	ds_read_b128 v[208:211], v191 offset:6144
	ds_read_b128 v[212:215], v191 offset:7168
	global_load_lds_dwordx4 v[184:185], off
	v_lshl_add_u64 v[184:185], s[28:29], 0, v[162:163]
	s_add_i32 m0, s74, 0xe000
	s_nop 0
	global_load_lds_dwordx4 v[184:185], off
	s_waitcnt vmcnt(8)
	s_waitcnt lgkmcnt(0)
	s_barrier
	s_waitcnt lgkmcnt(0)
	v_mfma_f32_16x16x32_bf16 v[124:127], v[128:131], v[176:179], v[124:127]
	v_mfma_f32_16x16x32_bf16 v[120:123], v[136:139], v[176:179], v[120:123]
	v_mfma_f32_16x16x32_bf16 v[108:111], v[128:131], v[192:195], v[108:111]
	v_mfma_f32_16x16x32_bf16 v[104:107], v[136:139], v[192:195], v[104:107]
	v_mfma_f32_16x16x32_bf16 v[92:95], v[128:131], v[200:203], v[92:95]
	v_mfma_f32_16x16x32_bf16 v[88:91], v[136:139], v[200:203], v[88:91]
	v_mfma_f32_16x16x32_bf16 v[76:79], v[128:131], v[208:211], v[76:79]
	v_mfma_f32_16x16x32_bf16 v[72:75], v[136:139], v[208:211], v[72:75]
	v_mfma_f32_16x16x32_bf16 v[124:127], v[132:135], v[180:183], v[124:127]
	v_mfma_f32_16x16x32_bf16 v[120:123], v[140:143], v[180:183], v[120:123]
	v_mfma_f32_16x16x32_bf16 v[108:111], v[132:135], v[196:199], v[108:111]
	v_mfma_f32_16x16x32_bf16 v[104:107], v[140:143], v[196:199], v[104:107]
	v_mfma_f32_16x16x32_bf16 v[92:95], v[132:135], v[204:207], v[92:95]
	v_mfma_f32_16x16x32_bf16 v[88:91], v[140:143], v[204:207], v[88:91]
	v_mfma_f32_16x16x32_bf16 v[76:79], v[132:135], v[212:215], v[76:79]
	v_mfma_f32_16x16x32_bf16 v[72:75], v[140:143], v[212:215], v[72:75]
	v_mfma_f32_16x16x32_bf16 v[116:119], v[144:147], v[176:179], v[116:119]
	v_mfma_f32_16x16x32_bf16 v[112:115], v[168:171], v[176:179], v[112:115]
	v_mfma_f32_16x16x32_bf16 v[100:103], v[144:147], v[192:195], v[100:103]
	v_mfma_f32_16x16x32_bf16 v[96:99], v[168:171], v[192:195], v[96:99]
	v_mfma_f32_16x16x32_bf16 v[84:87], v[144:147], v[200:203], v[84:87]
	v_mfma_f32_16x16x32_bf16 v[80:83], v[168:171], v[200:203], v[80:83]
	v_mfma_f32_16x16x32_bf16 v[68:71], v[144:147], v[208:211], v[68:71]
	v_mfma_f32_16x16x32_bf16 v[64:67], v[168:171], v[208:211], v[64:67]
	v_mfma_f32_16x16x32_bf16 v[116:119], v[148:151], v[180:183], v[116:119]
	v_mfma_f32_16x16x32_bf16 v[112:115], v[172:175], v[180:183], v[112:115]
	v_mfma_f32_16x16x32_bf16 v[100:103], v[148:151], v[196:199], v[100:103]
	v_mfma_f32_16x16x32_bf16 v[96:99], v[172:175], v[196:199], v[96:99]
	v_mfma_f32_16x16x32_bf16 v[84:87], v[148:151], v[204:207], v[84:87]
	v_mfma_f32_16x16x32_bf16 v[80:83], v[172:175], v[204:207], v[80:83]
	v_mfma_f32_16x16x32_bf16 v[68:71], v[148:151], v[212:215], v[68:71]
	v_mfma_f32_16x16x32_bf16 v[64:67], v[172:175], v[212:215], v[64:67]
	s_barrier
	s_add_i32 s28, s47, s68
	v_lshl_add_u64 v[184:185], s[34:35], 0, v[154:155]
	s_mov_b32 m0, s28
	s_nop 0
	global_load_lds_dwordx4 v[184:185], off
	s_add_i32 m0, s28, 0x2000
	s_add_u32 s28, s34, 0xb0000
	v_lshl_add_u64 v[216:217], s[34:35], 0, v[158:159]
	s_addc_u32 s29, s35, 0
	s_add_i32 s56, s48, s68
	global_load_lds_dwordx4 v[216:217], off
	v_lshl_add_u64 v[218:219], s[28:29], 0, v[154:155]
	s_mov_b32 m0, s56
	v_lshl_add_u64 v[220:221], s[36:37], 0, v[156:157]
	global_load_lds_dwordx4 v[218:219], off
	v_lshl_add_u64 v[218:219], s[28:29], 0, v[158:159]
	s_add_i32 m0, s56, 0x2000
	s_nop 0
	global_load_lds_dwordx4 v[218:219], off
	v_lshl_add_u64 v[218:219], s[36:37], 0, v[152:153]
	s_mov_b32 m0, s74
	s_nop 0
	global_load_lds_dwordx4 v[218:219], off
	s_mov_b32 m0, s66
	s_nop 0
	global_load_lds_dwordx4 v[220:221], off
	ds_read_b128 v[176:179], v191 offset:16384
	ds_read_b128 v[180:183], v191 offset:17408
	ds_read_b128 v[192:195], v191 offset:18432
	ds_read_b128 v[196:199], v191 offset:19456
	ds_read_b128 v[200:203], v191 offset:20480
	ds_read_b128 v[204:207], v191 offset:21504
	ds_read_b128 v[208:211], v191 offset:22528
	ds_read_b128 v[212:215], v191 offset:23552
	s_waitcnt vmcnt(8)
	s_waitcnt lgkmcnt(0)
	s_barrier
; #define PG8_STAGE(bufoff, gbase, voff) do { _Pragma("unroll") for (int _i = 0; _i < 2; ++_i) \
;         __builtin_amdgcn_global_load_lds((const unsigned*)((const char*)(gbase) + (voff)[_i]), (PG8_LAS unsigned*)(lds + (bufoff) + ldsw + _i * 8192), 16, 0, 0); } while (0)
; #define PG8_LDA(dst, b, h) do { _Pragma("unroll") for (int m = 0; m < 4; ++m) _Pragma("unroll") for (int k = 0; k < 2; ++k) dst[m][k] = *(const PG8_LAS bf16x8*)(lds + PG8_SA(b, h) + aoff + m * 2048 + k * 1024); } while (0)
; #define PG8_LDB(dst, b, h) do { _Pragma("unroll") for (int n = 0; n < 2; ++n) _Pragma("unroll") for (int k = 0; k < 2; ++k) dst[n][k] = *(const PG8_LAS bf16x8*)(lds + PG8_SB(b, h) + boff + n * 2048 + k * 1024); } while (0)
; #define PG8_MMA(ai, bj, At, Bt) do { __builtin_amdgcn_s_setprio(1); _Pragma("unroll") for (int m = 0; m < 4; ++m) _Pragma("unroll") for (int n = 0; n < 2; ++n) _Pragma("unroll") for (int k = 0; k < 2; ++k) \
;         acc[ai][bj][m][n] = mma16<F16>(Bt[n][k], At[m][k], acc[ai][bj][m][n]); __builtin_amdgcn_s_setprio(0); } while (0)
; #define PG8_WAIT_V(n) asm volatile("s_waitcnt vmcnt(" #n ")" ::: "memory")
; #define PG8_WAIT_L(n) asm volatile("s_waitcnt lgkmcnt(" #n ")" ::: "memory")
; #define PG8_BAR __builtin_amdgcn_s_barrier()
; #define PG8_SCHED __builtin_amdgcn_sched_barrier(0)
; template <class Epi, class Sched, bool ALIGN_EPI = false, bool SP2 = false, bool F16 = false>
; __device__ __forceinline__ void gemm_phase(PG8_LAS unsigned char* lds, const Gemm g, const Sched& S, const Epi& E, const int wid_in) {
;     ...
;             PG8_WAIT_V(8); PG8_WAIT_L(0); PG8_BAR; PG8_MMA(1, 0, At, B0); PG8_MMA(1, 1, At, B1); PG8_BAR; PG8_SCHED;
;             PG8_LDB(B0, 1, 0); PG8_LDB(B1, 1, 1); PG8_SCHED; PG8_LDA(At, 1, 0); PG8_STAGE(PG8_SA(0, 1), a2 + hstep, voffA);
;             PG8_WAIT_V(8); PG8_WAIT_L(0); PG8_BAR; PG8_MMA(0, 0, At, B0); PG8_MMA(0, 1, At, B1); PG8_BAR; PG8_SCHED;
	s_waitcnt lgkmcnt(0)
	v_mfma_f32_16x16x32_bf16 v[60:63], v[128:131], v[176:179], v[60:63]
	v_mfma_f32_16x16x32_bf16 v[56:59], v[136:139], v[176:179], v[56:59]
	v_mfma_f32_16x16x32_bf16 v[44:47], v[128:131], v[192:195], v[44:47]
	v_mfma_f32_16x16x32_bf16 v[40:43], v[136:139], v[192:195], v[40:43]
	v_mfma_f32_16x16x32_bf16 v[28:31], v[128:131], v[200:203], v[28:31]
	v_mfma_f32_16x16x32_bf16 v[24:27], v[136:139], v[200:203], v[24:27]
	v_mfma_f32_16x16x32_bf16 v[12:15], v[128:131], v[208:211], v[12:15]
	v_mfma_f32_16x16x32_bf16 v[8:11], v[136:139], v[208:211], v[8:11]
	v_mfma_f32_16x16x32_bf16 v[60:63], v[132:135], v[180:183], v[60:63]
	v_mfma_f32_16x16x32_bf16 v[56:59], v[140:143], v[180:183], v[56:59]
	v_mfma_f32_16x16x32_bf16 v[44:47], v[132:135], v[196:199], v[44:47]
	v_mfma_f32_16x16x32_bf16 v[40:43], v[140:143], v[196:199], v[40:43]
	v_mfma_f32_16x16x32_bf16 v[28:31], v[132:135], v[204:207], v[28:31]
	v_mfma_f32_16x16x32_bf16 v[24:27], v[140:143], v[204:207], v[24:27]
	v_mfma_f32_16x16x32_bf16 v[12:15], v[132:135], v[212:215], v[12:15]
	v_mfma_f32_16x16x32_bf16 v[8:11], v[140:143], v[212:215], v[8:11]
	v_mfma_f32_16x16x32_bf16 v[52:55], v[144:147], v[176:179], v[52:55]
	v_mfma_f32_16x16x32_bf16 v[48:51], v[168:171], v[176:179], v[48:51]
	v_mfma_f32_16x16x32_bf16 v[36:39], v[144:147], v[192:195], v[36:39]
	v_mfma_f32_16x16x32_bf16 v[32:35], v[168:171], v[192:195], v[32:35]
	v_mfma_f32_16x16x32_bf16 v[20:23], v[144:147], v[200:203], v[20:23]
	v_mfma_f32_16x16x32_bf16 v[16:19], v[168:171], v[200:203], v[16:19]
	v_mfma_f32_16x16x32_bf16 v[4:7], v[144:147], v[208:211], v[4:7]
	v_mfma_f32_16x16x32_bf16 v[0:3], v[168:171], v[208:211], v[0:3]
	v_mfma_f32_16x16x32_bf16 v[52:55], v[148:151], v[180:183], v[52:55]
	v_mfma_f32_16x16x32_bf16 v[48:51], v[172:175], v[180:183], v[48:51]
	v_mfma_f32_16x16x32_bf16 v[36:39], v[148:151], v[196:199], v[36:39]
	v_mfma_f32_16x16x32_bf16 v[32:35], v[172:175], v[196:199], v[32:35]
	v_mfma_f32_16x16x32_bf16 v[20:23], v[148:151], v[204:207], v[20:23]
	v_mfma_f32_16x16x32_bf16 v[16:19], v[172:175], v[204:207], v[16:19]
	v_mfma_f32_16x16x32_bf16 v[4:7], v[148:151], v[212:215], v[4:7]
	v_mfma_f32_16x16x32_bf16 v[0:3], v[172:175], v[212:215], v[0:3]
	s_barrier
	s_add_i32 s56, 0, 0x18000
	s_add_i32 s57, 0, 0x1c000
	v_add_u32_e32 v140, s56, v188
	v_add_u32_e32 v172, s57, v188
	s_add_u32 s28, s36, 0xb0000
	s_addc_u32 s29, s37, 0
	s_mov_b32 m0, s90
	v_lshl_add_u64 v[222:223], s[28:29], 0, v[152:153]
	global_load_lds_dwordx4 v[222:223], off
	v_lshl_add_u64 v[222:223], s[28:29], 0, v[156:157]
	s_mov_b32 m0, s43
	s_nop 0
	global_load_lds_dwordx4 v[222:223], off
	ds_read_b128 v[128:131], v140
	ds_read_b128 v[132:135], v140 offset:1024
	ds_read_b128 v[136:139], v140 offset:2048
	ds_read_b128 v[140:143], v140 offset:3072
	ds_read_b128 v[144:147], v172
	ds_read_b128 v[148:151], v172 offset:1024
	ds_read_b128 v[168:171], v172 offset:2048
	ds_read_b128 v[172:175], v172 offset:3072
	ds_read_b128 v[176:179], v191 offset:32768
	ds_read_b128 v[180:183], v191 offset:33792
	ds_read_b128 v[192:195], v191 offset:34816
	ds_read_b128 v[196:199], v191 offset:35840
	ds_read_b128 v[200:203], v191 offset:36864
	ds_read_b128 v[204:207], v191 offset:37888
	ds_read_b128 v[208:211], v191 offset:38912
	ds_read_b128 v[212:215], v191 offset:39936
	s_waitcnt vmcnt(8)
	s_waitcnt lgkmcnt(0)
	s_barrier
	s_waitcnt lgkmcnt(0)
	v_mfma_f32_16x16x32_bf16 v[124:127], v[128:131], v[176:179], v[124:127]
	v_mfma_f32_16x16x32_bf16 v[120:123], v[136:139], v[176:179], v[120:123]
	v_mfma_f32_16x16x32_bf16 v[108:111], v[128:131], v[192:195], v[108:111]
	v_mfma_f32_16x16x32_bf16 v[104:107], v[136:139], v[192:195], v[104:107]
	v_mfma_f32_16x16x32_bf16 v[92:95], v[128:131], v[200:203], v[92:95]
	v_mfma_f32_16x16x32_bf16 v[88:91], v[136:139], v[200:203], v[88:91]
	v_mfma_f32_16x16x32_bf16 v[76:79], v[128:131], v[208:211], v[76:79]
	v_mfma_f32_16x16x32_bf16 v[72:75], v[136:139], v[208:211], v[72:75]
	v_mfma_f32_16x16x32_bf16 v[124:127], v[132:135], v[180:183], v[124:127]
	v_mfma_f32_16x16x32_bf16 v[120:123], v[140:143], v[180:183], v[120:123]
	v_mfma_f32_16x16x32_bf16 v[108:111], v[132:135], v[196:199], v[108:111]
	v_mfma_f32_16x16x32_bf16 v[104:107], v[140:143], v[196:199], v[104:107]
	v_mfma_f32_16x16x32_bf16 v[92:95], v[132:135], v[204:207], v[92:95]
	v_mfma_f32_16x16x32_bf16 v[88:91], v[140:143], v[204:207], v[88:91]
	v_mfma_f32_16x16x32_bf16 v[76:79], v[132:135], v[212:215], v[76:79]
	v_mfma_f32_16x16x32_bf16 v[72:75], v[140:143], v[212:215], v[72:75]
	v_mfma_f32_16x16x32_bf16 v[116:119], v[144:147], v[176:179], v[116:119]
	v_mfma_f32_16x16x32_bf16 v[112:115], v[168:171], v[176:179], v[112:115]
	v_mfma_f32_16x16x32_bf16 v[100:103], v[144:147], v[192:195], v[100:103]
	v_mfma_f32_16x16x32_bf16 v[96:99], v[168:171], v[192:195], v[96:99]
	v_mfma_f32_16x16x32_bf16 v[84:87], v[144:147], v[200:203], v[84:87]
	v_mfma_f32_16x16x32_bf16 v[80:83], v[168:171], v[200:203], v[80:83]
	v_mfma_f32_16x16x32_bf16 v[68:71], v[144:147], v[208:211], v[68:71]
	v_mfma_f32_16x16x32_bf16 v[64:67], v[168:171], v[208:211], v[64:67]
	v_mfma_f32_16x16x32_bf16 v[116:119], v[148:151], v[180:183], v[116:119]
	v_mfma_f32_16x16x32_bf16 v[112:115], v[172:175], v[180:183], v[112:115]
	v_mfma_f32_16x16x32_bf16 v[100:103], v[148:151], v[196:199], v[100:103]
	v_mfma_f32_16x16x32_bf16 v[96:99], v[172:175], v[196:199], v[96:99]
	v_mfma_f32_16x16x32_bf16 v[84:87], v[148:151], v[204:207], v[84:87]
	v_mfma_f32_16x16x32_bf16 v[80:83], v[172:175], v[204:207], v[80:83]
	v_mfma_f32_16x16x32_bf16 v[68:71], v[148:151], v[212:215], v[68:71]
	v_mfma_f32_16x16x32_bf16 v[64:67], v[172:175], v[212:215], v[64:67]
	s_barrier
; #define PG8_STAGE(bufoff, gbase, voff) do { _Pragma("unroll") for (int _i = 0; _i < 2; ++_i) \
;         __builtin_amdgcn_global_load_lds((const unsigned*)((const char*)(gbase) + (voff)[_i]), (PG8_LAS unsigned*)(lds + (bufoff) + ldsw + _i * 8192), 16, 0, 0); } while (0)
; #define PG8_LDA(dst, b, h) do { _Pragma("unroll") for (int m = 0; m < 4; ++m) _Pragma("unroll") for (int k = 0; k < 2; ++k) dst[m][k] = *(const PG8_LAS bf16x8*)(lds + PG8_SA(b, h) + aoff + m * 2048 + k * 1024); } while (0)
; #define PG8_MMA(ai, bj, At, Bt) do { __builtin_amdgcn_s_setprio(1); _Pragma("unroll") for (int m = 0; m < 4; ++m) _Pragma("unroll") for (int n = 0; n < 2; ++n) _Pragma("unroll") for (int k = 0; k < 2; ++k) \
;         acc[ai][bj][m][n] = mma16<F16>(Bt[n][k], At[m][k], acc[ai][bj][m][n]); __builtin_amdgcn_s_setprio(0); } while (0)
; #define PG8_WAIT_V(n) asm volatile("s_waitcnt vmcnt(" #n ")" ::: "memory")
; #define PG8_WAIT_L(n) asm volatile("s_waitcnt lgkmcnt(" #n ")" ::: "memory")
; #define PG8_BAR __builtin_amdgcn_s_barrier()
; #define PG8_SCHED __builtin_amdgcn_sched_barrier(0)
; template <class Epi, class Sched, bool ALIGN_EPI = false, bool SP2 = false, bool F16 = false>
; __device__ __forceinline__ void gemm_phase(PG8_LAS unsigned char* lds, const Gemm g, const Sched& S, const Epi& E, const int wid_in) {
;     ...
;             PG8_LDA(At, 1, 1); PG8_STAGE(PG8_SB(1, 0), b3, voffB); PG8_STAGE(PG8_SB(1, 1), b3 + hstep, voffB); PG8_STAGE(PG8_SA(1, 0), a3, voffA);
;             PG8_WAIT_V(8); PG8_WAIT_L(0); PG8_BAR; PG8_MMA(1, 0, At, B0); PG8_MMA(1, 1, At, B1); PG8_BAR; PG8_SCHED;
	s_add_i32 s28, s56, s68
	v_lshl_add_u64 v[184:185], v[184:185], 0, s[24:25]
	s_mov_b32 m0, s28
	s_nop 0
	global_load_lds_dwordx4 v[184:185], off
	s_add_i32 m0, s28, 0x2000
	s_add_u32 s28, s34, 0xb0080
	v_lshl_add_u64 v[184:185], v[216:217], 0, s[24:25]
	s_addc_u32 s29, s35, 0
	s_add_i32 s34, s57, s68
	global_load_lds_dwordx4 v[184:185], off
	v_lshl_add_u64 v[184:185], s[28:29], 0, v[154:155]
	s_mov_b32 m0, s34
	s_nop 0
	global_load_lds_dwordx4 v[184:185], off
	v_lshl_add_u64 v[184:185], s[28:29], 0, v[158:159]
	s_add_i32 m0, s34, 0x2000
	s_nop 0
	global_load_lds_dwordx4 v[184:185], off
	v_lshl_add_u64 v[184:185], v[218:219], 0, s[24:25]
	s_mov_b32 m0, s75
	s_nop 0
	global_load_lds_dwordx4 v[184:185], off
	v_lshl_add_u64 v[184:185], v[220:221], 0, s[24:25]
	s_mov_b32 m0, s67
	s_nop 0
	global_load_lds_dwordx4 v[184:185], off
	ds_read_b128 v[176:179], v191 offset:49152
	ds_read_b128 v[180:183], v191 offset:50176
	ds_read_b128 v[192:195], v191 offset:51200
	ds_read_b128 v[196:199], v191 offset:52224
	ds_read_b128 v[200:203], v191 offset:53248
	ds_read_b128 v[204:207], v191 offset:54272
	ds_read_b128 v[208:211], v191 offset:55296
	ds_read_b128 v[212:215], v191 offset:56320
	s_waitcnt vmcnt(8)
	s_waitcnt lgkmcnt(0)
	s_barrier
	s_waitcnt lgkmcnt(0)
	v_mfma_f32_16x16x32_bf16 v[60:63], v[128:131], v[176:179], v[60:63]
	v_mfma_f32_16x16x32_bf16 v[56:59], v[136:139], v[176:179], v[56:59]
	v_mfma_f32_16x16x32_bf16 v[44:47], v[128:131], v[192:195], v[44:47]
	v_mfma_f32_16x16x32_bf16 v[40:43], v[136:139], v[192:195], v[40:43]
	v_mfma_f32_16x16x32_bf16 v[28:31], v[128:131], v[200:203], v[28:31]
	v_mfma_f32_16x16x32_bf16 v[24:27], v[136:139], v[200:203], v[24:27]
	v_mfma_f32_16x16x32_bf16 v[12:15], v[128:131], v[208:211], v[12:15]
	v_mfma_f32_16x16x32_bf16 v[8:11], v[136:139], v[208:211], v[8:11]
	v_mfma_f32_16x16x32_bf16 v[60:63], v[132:135], v[180:183], v[60:63]
	v_mfma_f32_16x16x32_bf16 v[56:59], v[140:143], v[180:183], v[56:59]
	v_mfma_f32_16x16x32_bf16 v[44:47], v[132:135], v[196:199], v[44:47]
	v_mfma_f32_16x16x32_bf16 v[40:43], v[140:143], v[196:199], v[40:43]
	v_mfma_f32_16x16x32_bf16 v[28:31], v[132:135], v[204:207], v[28:31]
	v_mfma_f32_16x16x32_bf16 v[24:27], v[140:143], v[204:207], v[24:27]
	v_mfma_f32_16x16x32_bf16 v[12:15], v[132:135], v[212:215], v[12:15]
	v_mfma_f32_16x16x32_bf16 v[8:11], v[140:143], v[212:215], v[8:11]
	v_mfma_f32_16x16x32_bf16 v[52:55], v[144:147], v[176:179], v[52:55]
	v_mfma_f32_16x16x32_bf16 v[48:51], v[168:171], v[176:179], v[48:51]
	v_mfma_f32_16x16x32_bf16 v[36:39], v[144:147], v[192:195], v[36:39]
	v_mfma_f32_16x16x32_bf16 v[32:35], v[168:171], v[192:195], v[32:35]
	v_mfma_f32_16x16x32_bf16 v[20:23], v[144:147], v[200:203], v[20:23]
	v_mfma_f32_16x16x32_bf16 v[16:19], v[168:171], v[200:203], v[16:19]
	v_mfma_f32_16x16x32_bf16 v[4:7], v[144:147], v[208:211], v[4:7]
	v_mfma_f32_16x16x32_bf16 v[0:3], v[168:171], v[208:211], v[0:3]
	v_mfma_f32_16x16x32_bf16 v[52:55], v[148:151], v[180:183], v[52:55]
	v_mfma_f32_16x16x32_bf16 v[48:51], v[172:175], v[180:183], v[48:51]
	v_mfma_f32_16x16x32_bf16 v[36:39], v[148:151], v[196:199], v[36:39]
	v_mfma_f32_16x16x32_bf16 v[32:35], v[172:175], v[196:199], v[32:35]
	v_mfma_f32_16x16x32_bf16 v[20:23], v[148:151], v[204:207], v[20:23]
	v_mfma_f32_16x16x32_bf16 v[16:19], v[172:175], v[204:207], v[16:19]
	v_mfma_f32_16x16x32_bf16 v[4:7], v[148:151], v[212:215], v[4:7]
	v_mfma_f32_16x16x32_bf16 v[0:3], v[172:175], v[212:215], v[0:3]
	s_barrier
	s_add_i32 s55, s55, 2
	s_add_u32 s53, s53, 0x100
	s_addc_u32 s54, s54, 0
	s_cmp_gt_u32 s55, 41
	s_mov_b64 s[28:29], s[30:31]
	s_cbranch_scc0 .LBB0_2697
	s_and_b64 vcc, exec, s[16:17]
	s_cbranch_vccz .LBB0_2700
	s_barrier

; #define PG8_STAGE(bufoff, gbase, voff) do { _Pragma("unroll") for (int _i = 0; _i < 2; ++_i) \
;         __builtin_amdgcn_global_load_lds((const unsigned*)((const char*)(gbase) + (voff)[_i]), (PG8_LAS unsigned*)(lds + (bufoff) + ldsw + _i * 8192), 16, 0, 0); } while (0)
; #define PG8_LDA(dst, b, h) do { _Pragma("unroll") for (int m = 0; m < 4; ++m) _Pragma("unroll") for (int k = 0; k < 2; ++k) dst[m][k] = *(const PG8_LAS bf16x8*)(lds + PG8_SA(b, h) + aoff + m * 2048 + k * 1024); } while (0)
; #define PG8_LDB(dst, b, h) do { _Pragma("unroll") for (int n = 0; n < 2; ++n) _Pragma("unroll") for (int k = 0; k < 2; ++k) dst[n][k] = *(const PG8_LAS bf16x8*)(lds + PG8_SB(b, h) + boff + n * 2048 + k * 1024); } while (0)
; #define PG8_MMA(ai, bj, At, Bt) do { __builtin_amdgcn_s_setprio(1); _Pragma("unroll") for (int m = 0; m < 4; ++m) _Pragma("unroll") for (int n = 0; n < 2; ++n) _Pragma("unroll") for (int k = 0; k < 2; ++k) \
;         acc[ai][bj][m][n] = mma16<F16>(Bt[n][k], At[m][k], acc[ai][bj][m][n]); __builtin_amdgcn_s_setprio(0); } while (0)
; #define PG8_WAIT_V(n) asm volatile("s_waitcnt vmcnt(" #n ")" ::: "memory")
; #define PG8_WAIT_L(n) asm volatile("s_waitcnt lgkmcnt(" #n ")" ::: "memory")
; template <class Epi, class Sched, bool ALIGN_EPI = false, bool SP2 = false, bool F16 = false>
; __device__ __forceinline__ void gemm_phase(PG8_LAS unsigned char* lds, const Gemm g, const Sched& S, const Epi& E, const int wid_in) {
;     ...
;             const bool last = (t == nt - 2);
;             const char* a1 = cA + (size_t)(t + 1) * kstep;
;             const char* a2 = last ? nA : cA + (size_t)(t + 2) * kstep; const char* b2 = last ? nB : cB + (size_t)(t + 2) * kstep;
;             const char* a3 = a2 + kstep; const char* b3 = b2 + kstep;
;             if (last && has_next) S.a_ready(nxt);
;             if constexpr (SP2) {
;             PG8_LDB(B0, 0, 0); PG8_LDB(B1, 0, 1); PG8_SCHED; PG8_LDA(At, 0, 0); PG8_STAGE(PG8_SA(1, 1), a1 + hstep, voffA);
;             PG8_WAIT_V(8); PG8_WAIT_L(0); PG8_BAR; PG8_MMA(0, 0, At, B0); PG8_MMA(0, 1, At, B1); PG8_BAR; PG8_SCHED;
;             PG8_LDA(At, 0, 1); PG8_STAGE(PG8_SB(0, 0), b2, voffB); PG8_STAGE(PG8_SB(0, 1), b2 + hstep, voffB); PG8_STAGE(PG8_SA(0, 0), a2, voffA);
;             PG8_WAIT_V(8); PG8_WAIT_L(0); PG8_BAR; PG8_MMA(1, 0, At, B0); PG8_MMA(1, 1, At, B1); PG8_BAR; PG8_SCHED;
.LBB0_2793:
	ds_read_b128 v[112:115], v235
	ds_read_b128 v[116:119], v235 offset:1024
	ds_read_b128 v[128:131], v235 offset:2048
	ds_read_b128 v[132:135], v235 offset:3072
	ds_read_b128 v[144:147], v236
	ds_read_b128 v[148:151], v236 offset:1024
	ds_read_b128 v[152:155], v236 offset:2048
	ds_read_b128 v[156:159], v236 offset:3072
	s_add_u32 s44, s42, 0xfffc0080
	s_addc_u32 s45, s43, -1
	s_cmp_eq_u32 s59, 12
	s_cselect_b32 s47, s14, s45
	s_cselect_b32 s46, s15, s44
	s_cselect_b32 s45, s29, s58
	s_cselect_b32 s44, s31, s41
	s_mov_b32 m0, s91
	v_lshl_add_u64 v[192:193], s[42:43], 0, v[204:205]
	ds_read_b128 v[160:163], v237
	ds_read_b128 v[164:167], v237 offset:1024
	ds_read_b128 v[168:171], v237 offset:2048
	ds_read_b128 v[172:175], v237 offset:3072
	ds_read_b128 v[176:179], v237 offset:4096
	ds_read_b128 v[180:183], v237 offset:5120
	ds_read_b128 v[184:187], v237 offset:6144
	ds_read_b128 v[188:191], v237 offset:7168
	global_load_lds_dwordx4 v[192:193], off
	v_lshl_add_u64 v[192:193], s[42:43], 0, v[206:207]
	s_add_i32 m0, s74, 0xe000
	s_nop 0
	global_load_lds_dwordx4 v[192:193], off
	s_waitcnt vmcnt(8)
	s_waitcnt lgkmcnt(0)
	s_barrier
	s_waitcnt lgkmcnt(0)
	v_mfma_f32_16x16x32_f16 v[140:143], v[112:115], v[160:163], v[140:143]
	v_mfma_f32_16x16x32_f16 v[136:139], v[128:131], v[160:163], v[136:139]
	v_mfma_f32_16x16x32_f16 v[108:111], v[112:115], v[168:171], v[108:111]
	v_mfma_f32_16x16x32_f16 v[104:107], v[128:131], v[168:171], v[104:107]
	v_mfma_f32_16x16x32_f16 v[92:95], v[112:115], v[176:179], v[92:95]
	v_mfma_f32_16x16x32_f16 v[88:91], v[128:131], v[176:179], v[88:91]
	v_mfma_f32_16x16x32_f16 v[76:79], v[112:115], v[184:187], v[76:79]
	v_mfma_f32_16x16x32_f16 v[72:75], v[128:131], v[184:187], v[72:75]
	v_mfma_f32_16x16x32_f16 v[140:143], v[116:119], v[164:167], v[140:143]
	v_mfma_f32_16x16x32_f16 v[136:139], v[132:135], v[164:167], v[136:139]
	v_mfma_f32_16x16x32_f16 v[108:111], v[116:119], v[172:175], v[108:111]
	v_mfma_f32_16x16x32_f16 v[104:107], v[132:135], v[172:175], v[104:107]
	v_mfma_f32_16x16x32_f16 v[92:95], v[116:119], v[180:183], v[92:95]
	v_mfma_f32_16x16x32_f16 v[88:91], v[132:135], v[180:183], v[88:91]
	v_mfma_f32_16x16x32_f16 v[76:79], v[116:119], v[188:191], v[76:79]
	v_mfma_f32_16x16x32_f16 v[72:75], v[132:135], v[188:191], v[72:75]
	v_mfma_f32_16x16x32_f16 v[124:127], v[144:147], v[160:163], v[124:127]
	v_mfma_f32_16x16x32_f16 v[120:123], v[152:155], v[160:163], v[120:123]
	v_mfma_f32_16x16x32_f16 v[100:103], v[144:147], v[168:171], v[100:103]
	v_mfma_f32_16x16x32_f16 v[96:99], v[152:155], v[168:171], v[96:99]
	v_mfma_f32_16x16x32_f16 v[84:87], v[144:147], v[176:179], v[84:87]
	v_mfma_f32_16x16x32_f16 v[80:83], v[152:155], v[176:179], v[80:83]
	v_mfma_f32_16x16x32_f16 v[68:71], v[144:147], v[184:187], v[68:71]
	v_mfma_f32_16x16x32_f16 v[64:67], v[152:155], v[184:187], v[64:67]
	v_mfma_f32_16x16x32_f16 v[124:127], v[148:151], v[164:167], v[124:127]
	v_mfma_f32_16x16x32_f16 v[120:123], v[156:159], v[164:167], v[120:123]
	v_mfma_f32_16x16x32_f16 v[100:103], v[148:151], v[172:175], v[100:103]
	v_mfma_f32_16x16x32_f16 v[96:99], v[156:159], v[172:175], v[96:99]
	v_mfma_f32_16x16x32_f16 v[84:87], v[148:151], v[180:183], v[84:87]
	v_mfma_f32_16x16x32_f16 v[80:83], v[156:159], v[180:183], v[80:83]
	v_mfma_f32_16x16x32_f16 v[68:71], v[148:151], v[188:191], v[68:71]
	v_mfma_f32_16x16x32_f16 v[64:67], v[156:159], v[188:191], v[64:67]
	s_barrier
	s_add_i32 s60, s55, s68
	v_lshl_add_u64 v[192:193], s[44:45], 0, v[198:199]
	s_mov_b32 m0, s60
	s_nop 0
	global_load_lds_dwordx4 v[192:193], off
	s_add_i32 m0, s60, 0x2000
	s_add_u32 s60, s44, 0x40000
	v_lshl_add_u64 v[194:195], s[44:45], 0, v[202:203]
	s_addc_u32 s61, s45, 0
	s_add_i32 s62, s56, s68
	global_load_lds_dwordx4 v[194:195], off
	v_lshl_add_u64 v[212:213], s[60:61], 0, v[198:199]
	s_mov_b32 m0, s62
	v_lshl_add_u64 v[214:215], s[46:47], 0, v[200:201]
	global_load_lds_dwordx4 v[212:213], off
	v_lshl_add_u64 v[212:213], s[60:61], 0, v[202:203]
	s_add_i32 m0, s62, 0x2000
	s_nop 0
	global_load_lds_dwordx4 v[212:213], off
	v_lshl_add_u64 v[212:213], s[46:47], 0, v[196:197]
	s_mov_b32 m0, s74
	s_nop 0
	global_load_lds_dwordx4 v[212:213], off
	s_mov_b32 m0, s66
	s_nop 0
	global_load_lds_dwordx4 v[214:215], off
	ds_read_b128 v[160:163], v237 offset:16384
	ds_read_b128 v[164:167], v237 offset:17408
	ds_read_b128 v[168:171], v237 offset:18432
	ds_read_b128 v[172:175], v237 offset:19456
	ds_read_b128 v[176:179], v237 offset:20480
	ds_read_b128 v[180:183], v237 offset:21504
	ds_read_b128 v[184:187], v237 offset:22528
	ds_read_b128 v[188:191], v237 offset:23552
	s_waitcnt vmcnt(8)
	s_waitcnt lgkmcnt(0)
	s_barrier
; #define PG8_STAGE(bufoff, gbase, voff) do { _Pragma("unroll") for (int _i = 0; _i < 2; ++_i) \
;         __builtin_amdgcn_global_load_lds((const unsigned*)((const char*)(gbase) + (voff)[_i]), (PG8_LAS unsigned*)(lds + (bufoff) + ldsw + _i * 8192), 16, 0, 0); } while (0)
; #define PG8_LDA(dst, b, h) do { _Pragma("unroll") for (int m = 0; m < 4; ++m) _Pragma("unroll") for (int k = 0; k < 2; ++k) dst[m][k] = *(const PG8_LAS bf16x8*)(lds + PG8_SA(b, h) + aoff + m * 2048 + k * 1024); } while (0)
; #define PG8_LDB(dst, b, h) do { _Pragma("unroll") for (int n = 0; n < 2; ++n) _Pragma("unroll") for (int k = 0; k < 2; ++k) dst[n][k] = *(const PG8_LAS bf16x8*)(lds + PG8_SB(b, h) + boff + n * 2048 + k * 1024); } while (0)
; #define PG8_MMA(ai, bj, At, Bt) do { __builtin_amdgcn_s_setprio(1); _Pragma("unroll") for (int m = 0; m < 4; ++m) _Pragma("unroll") for (int n = 0; n < 2; ++n) _Pragma("unroll") for (int k = 0; k < 2; ++k) \
;         acc[ai][bj][m][n] = mma16<F16>(Bt[n][k], At[m][k], acc[ai][bj][m][n]); __builtin_amdgcn_s_setprio(0); } while (0)
; #define PG8_WAIT_V(n) asm volatile("s_waitcnt vmcnt(" #n ")" ::: "memory")
; #define PG8_WAIT_L(n) asm volatile("s_waitcnt lgkmcnt(" #n ")" ::: "memory")
; #define PG8_BAR __builtin_amdgcn_s_barrier()
; #define PG8_SCHED __builtin_amdgcn_sched_barrier(0)
; template <class Epi, class Sched, bool ALIGN_EPI = false, bool SP2 = false, bool F16 = false>
; __device__ __forceinline__ void gemm_phase(PG8_LAS unsigned char* lds, const Gemm g, const Sched& S, const Epi& E, const int wid_in) {
;     ...
;             PG8_WAIT_V(8); PG8_WAIT_L(0); PG8_BAR; PG8_MMA(1, 0, At, B0); PG8_MMA(1, 1, At, B1); PG8_BAR; PG8_SCHED;
;             PG8_LDB(B0, 1, 0); PG8_LDB(B1, 1, 1); PG8_SCHED; PG8_LDA(At, 1, 0); PG8_STAGE(PG8_SA(0, 1), a2 + hstep, voffA);
;             PG8_WAIT_V(8); PG8_WAIT_L(0); PG8_BAR; PG8_MMA(0, 0, At, B0); PG8_MMA(0, 1, At, B1); PG8_BAR; PG8_SCHED;
	s_waitcnt lgkmcnt(0)
	v_mfma_f32_16x16x32_f16 v[60:63], v[112:115], v[160:163], v[60:63]
	v_mfma_f32_16x16x32_f16 v[56:59], v[128:131], v[160:163], v[56:59]
	v_mfma_f32_16x16x32_f16 v[44:47], v[112:115], v[168:171], v[44:47]
	v_mfma_f32_16x16x32_f16 v[40:43], v[128:131], v[168:171], v[40:43]
	v_mfma_f32_16x16x32_f16 v[28:31], v[112:115], v[176:179], v[28:31]
	v_mfma_f32_16x16x32_f16 v[24:27], v[128:131], v[176:179], v[24:27]
	v_mfma_f32_16x16x32_f16 v[12:15], v[112:115], v[184:187], v[12:15]
	v_mfma_f32_16x16x32_f16 v[8:11], v[128:131], v[184:187], v[8:11]
	v_mfma_f32_16x16x32_f16 v[60:63], v[116:119], v[164:167], v[60:63]
	v_mfma_f32_16x16x32_f16 v[56:59], v[132:135], v[164:167], v[56:59]
	v_mfma_f32_16x16x32_f16 v[44:47], v[116:119], v[172:175], v[44:47]
	v_mfma_f32_16x16x32_f16 v[40:43], v[132:135], v[172:175], v[40:43]
	v_mfma_f32_16x16x32_f16 v[28:31], v[116:119], v[180:183], v[28:31]
	v_mfma_f32_16x16x32_f16 v[24:27], v[132:135], v[180:183], v[24:27]
	v_mfma_f32_16x16x32_f16 v[12:15], v[116:119], v[188:191], v[12:15]
	v_mfma_f32_16x16x32_f16 v[8:11], v[132:135], v[188:191], v[8:11]
	v_mfma_f32_16x16x32_f16 v[52:55], v[144:147], v[160:163], v[52:55]
	v_mfma_f32_16x16x32_f16 v[48:51], v[152:155], v[160:163], v[48:51]
	v_mfma_f32_16x16x32_f16 v[36:39], v[144:147], v[168:171], v[36:39]
	v_mfma_f32_16x16x32_f16 v[32:35], v[152:155], v[168:171], v[32:35]
	v_mfma_f32_16x16x32_f16 v[20:23], v[144:147], v[176:179], v[20:23]
	v_mfma_f32_16x16x32_f16 v[16:19], v[152:155], v[176:179], v[16:19]
	v_mfma_f32_16x16x32_f16 v[4:7], v[144:147], v[184:187], v[4:7]
	v_mfma_f32_16x16x32_f16 v[0:3], v[152:155], v[184:187], v[0:3]
	v_mfma_f32_16x16x32_f16 v[52:55], v[148:151], v[164:167], v[52:55]
	v_mfma_f32_16x16x32_f16 v[48:51], v[156:159], v[164:167], v[48:51]
	v_mfma_f32_16x16x32_f16 v[36:39], v[148:151], v[172:175], v[36:39]
	v_mfma_f32_16x16x32_f16 v[32:35], v[156:159], v[172:175], v[32:35]
	v_mfma_f32_16x16x32_f16 v[20:23], v[148:151], v[180:183], v[20:23]
	v_mfma_f32_16x16x32_f16 v[16:19], v[156:159], v[180:183], v[16:19]
	v_mfma_f32_16x16x32_f16 v[4:7], v[148:151], v[188:191], v[4:7]
	v_mfma_f32_16x16x32_f16 v[0:3], v[156:159], v[188:191], v[0:3]
	s_barrier
	s_add_i32 s60, 0, 0x18000
	s_add_i32 s61, 0, 0x1c000
	v_add_u32_e32 v132, s60, v234
	v_add_u32_e32 v156, s61, v234
	s_add_u32 s46, s46, 0x40000
	s_addc_u32 s47, s47, 0
	s_mov_b32 m0, s90
	v_lshl_add_u64 v[216:217], s[46:47], 0, v[196:197]
	global_load_lds_dwordx4 v[216:217], off
	v_lshl_add_u64 v[216:217], s[46:47], 0, v[200:201]
	s_mov_b32 m0, s51
	s_nop 0
	global_load_lds_dwordx4 v[216:217], off
	ds_read_b128 v[112:115], v132
	ds_read_b128 v[116:119], v132 offset:1024
	ds_read_b128 v[128:131], v132 offset:2048
	ds_read_b128 v[132:135], v132 offset:3072
	ds_read_b128 v[144:147], v156
	ds_read_b128 v[148:151], v156 offset:1024
	ds_read_b128 v[152:155], v156 offset:2048
	ds_read_b128 v[156:159], v156 offset:3072
	ds_read_b128 v[160:163], v237 offset:32768
	ds_read_b128 v[164:167], v237 offset:33792
	ds_read_b128 v[168:171], v237 offset:34816
	ds_read_b128 v[172:175], v237 offset:35840
	ds_read_b128 v[176:179], v237 offset:36864
	ds_read_b128 v[180:183], v237 offset:37888
	ds_read_b128 v[184:187], v237 offset:38912
	ds_read_b128 v[188:191], v237 offset:39936
	s_waitcnt vmcnt(8)
	s_waitcnt lgkmcnt(0)
	s_barrier
	s_waitcnt lgkmcnt(0)
	v_mfma_f32_16x16x32_f16 v[140:143], v[112:115], v[160:163], v[140:143]
	v_mfma_f32_16x16x32_f16 v[136:139], v[128:131], v[160:163], v[136:139]
	v_mfma_f32_16x16x32_f16 v[108:111], v[112:115], v[168:171], v[108:111]
	v_mfma_f32_16x16x32_f16 v[104:107], v[128:131], v[168:171], v[104:107]
	v_mfma_f32_16x16x32_f16 v[92:95], v[112:115], v[176:179], v[92:95]
	v_mfma_f32_16x16x32_f16 v[88:91], v[128:131], v[176:179], v[88:91]
	v_mfma_f32_16x16x32_f16 v[76:79], v[112:115], v[184:187], v[76:79]
	v_mfma_f32_16x16x32_f16 v[72:75], v[128:131], v[184:187], v[72:75]
	v_mfma_f32_16x16x32_f16 v[140:143], v[116:119], v[164:167], v[140:143]
	v_mfma_f32_16x16x32_f16 v[136:139], v[132:135], v[164:167], v[136:139]
	v_mfma_f32_16x16x32_f16 v[108:111], v[116:119], v[172:175], v[108:111]
	v_mfma_f32_16x16x32_f16 v[104:107], v[132:135], v[172:175], v[104:107]
	v_mfma_f32_16x16x32_f16 v[92:95], v[116:119], v[180:183], v[92:95]
	v_mfma_f32_16x16x32_f16 v[88:91], v[132:135], v[180:183], v[88:91]
	v_mfma_f32_16x16x32_f16 v[76:79], v[116:119], v[188:191], v[76:79]
	v_mfma_f32_16x16x32_f16 v[72:75], v[132:135], v[188:191], v[72:75]
	v_mfma_f32_16x16x32_f16 v[124:127], v[144:147], v[160:163], v[124:127]
	v_mfma_f32_16x16x32_f16 v[120:123], v[152:155], v[160:163], v[120:123]
	v_mfma_f32_16x16x32_f16 v[100:103], v[144:147], v[168:171], v[100:103]
	v_mfma_f32_16x16x32_f16 v[96:99], v[152:155], v[168:171], v[96:99]
	v_mfma_f32_16x16x32_f16 v[84:87], v[144:147], v[176:179], v[84:87]
	v_mfma_f32_16x16x32_f16 v[80:83], v[152:155], v[176:179], v[80:83]
	v_mfma_f32_16x16x32_f16 v[68:71], v[144:147], v[184:187], v[68:71]
	v_mfma_f32_16x16x32_f16 v[64:67], v[152:155], v[184:187], v[64:67]
	v_mfma_f32_16x16x32_f16 v[124:127], v[148:151], v[164:167], v[124:127]
	v_mfma_f32_16x16x32_f16 v[120:123], v[156:159], v[164:167], v[120:123]
	v_mfma_f32_16x16x32_f16 v[100:103], v[148:151], v[172:175], v[100:103]
	v_mfma_f32_16x16x32_f16 v[96:99], v[156:159], v[172:175], v[96:99]
	v_mfma_f32_16x16x32_f16 v[84:87], v[148:151], v[180:183], v[84:87]
	v_mfma_f32_16x16x32_f16 v[80:83], v[156:159], v[180:183], v[80:83]
	v_mfma_f32_16x16x32_f16 v[68:71], v[148:151], v[188:191], v[68:71]
	v_mfma_f32_16x16x32_f16 v[64:67], v[156:159], v[188:191], v[64:67]
	s_barrier
; #define PG8_STAGE(bufoff, gbase, voff) do { _Pragma("unroll") for (int _i = 0; _i < 2; ++_i) \
;         __builtin_amdgcn_global_load_lds((const unsigned*)((const char*)(gbase) + (voff)[_i]), (PG8_LAS unsigned*)(lds + (bufoff) + ldsw + _i * 8192), 16, 0, 0); } while (0)
; #define PG8_LDA(dst, b, h) do { _Pragma("unroll") for (int m = 0; m < 4; ++m) _Pragma("unroll") for (int k = 0; k < 2; ++k) dst[m][k] = *(const PG8_LAS bf16x8*)(lds + PG8_SA(b, h) + aoff + m * 2048 + k * 1024); } while (0)
; #define PG8_MMA(ai, bj, At, Bt) do { __builtin_amdgcn_s_setprio(1); _Pragma("unroll") for (int m = 0; m < 4; ++m) _Pragma("unroll") for (int n = 0; n < 2; ++n) _Pragma("unroll") for (int k = 0; k < 2; ++k) \
;         acc[ai][bj][m][n] = mma16<F16>(Bt[n][k], At[m][k], acc[ai][bj][m][n]); __builtin_amdgcn_s_setprio(0); } while (0)
; #define PG8_WAIT_V(n) asm volatile("s_waitcnt vmcnt(" #n ")" ::: "memory")
; #define PG8_WAIT_L(n) asm volatile("s_waitcnt lgkmcnt(" #n ")" ::: "memory")
; #define PG8_BAR __builtin_amdgcn_s_barrier()
; #define PG8_SCHED __builtin_amdgcn_sched_barrier(0)
; template <class Epi, class Sched, bool ALIGN_EPI = false, bool SP2 = false, bool F16 = false>
; __device__ __forceinline__ void gemm_phase(PG8_LAS unsigned char* lds, const Gemm g, const Sched& S, const Epi& E, const int wid_in) {
;     ...
;             PG8_LDA(At, 1, 1); PG8_STAGE(PG8_SB(1, 0), b3, voffB); PG8_STAGE(PG8_SB(1, 1), b3 + hstep, voffB); PG8_STAGE(PG8_SA(1, 0), a3, voffA);
;             PG8_WAIT_V(8); PG8_WAIT_L(0); PG8_BAR; PG8_MMA(1, 0, At, B0); PG8_MMA(1, 1, At, B1); PG8_BAR; PG8_SCHED;
	s_add_i32 s46, s60, s68
	v_lshl_add_u64 v[192:193], v[192:193], 0, s[26:27]
	s_mov_b32 m0, s46
	s_nop 0
	global_load_lds_dwordx4 v[192:193], off
	s_add_i32 m0, s46, 0x2000
	s_add_u32 s44, s44, 0x40080
	v_lshl_add_u64 v[192:193], v[194:195], 0, s[26:27]
	s_addc_u32 s45, s45, 0
	s_add_i32 s46, s61, s68
	global_load_lds_dwordx4 v[192:193], off
	v_lshl_add_u64 v[192:193], s[44:45], 0, v[198:199]
	s_mov_b32 m0, s46
	s_nop 0
	global_load_lds_dwordx4 v[192:193], off
	v_lshl_add_u64 v[192:193], s[44:45], 0, v[202:203]
	s_add_i32 m0, s46, 0x2000
	s_nop 0
	global_load_lds_dwordx4 v[192:193], off
	v_lshl_add_u64 v[192:193], v[212:213], 0, s[26:27]
	s_mov_b32 m0, s75
	s_nop 0
	global_load_lds_dwordx4 v[192:193], off
	v_lshl_add_u64 v[192:193], v[214:215], 0, s[26:27]
	s_mov_b32 m0, s67
	s_nop 0
	global_load_lds_dwordx4 v[192:193], off
	ds_read_b128 v[160:163], v237 offset:49152
	ds_read_b128 v[164:167], v237 offset:50176
	ds_read_b128 v[168:171], v237 offset:51200
	ds_read_b128 v[172:175], v237 offset:52224
	ds_read_b128 v[176:179], v237 offset:53248
	ds_read_b128 v[180:183], v237 offset:54272
	ds_read_b128 v[184:187], v237 offset:55296
	ds_read_b128 v[188:191], v237 offset:56320
	s_waitcnt vmcnt(8)
	s_waitcnt lgkmcnt(0)
	s_barrier
	s_waitcnt lgkmcnt(0)
	v_mfma_f32_16x16x32_f16 v[60:63], v[112:115], v[160:163], v[60:63]
	v_mfma_f32_16x16x32_f16 v[56:59], v[128:131], v[160:163], v[56:59]
	v_mfma_f32_16x16x32_f16 v[44:47], v[112:115], v[168:171], v[44:47]
	v_mfma_f32_16x16x32_f16 v[40:43], v[128:131], v[168:171], v[40:43]
	v_mfma_f32_16x16x32_f16 v[28:31], v[112:115], v[176:179], v[28:31]
	v_mfma_f32_16x16x32_f16 v[24:27], v[128:131], v[176:179], v[24:27]
	v_mfma_f32_16x16x32_f16 v[12:15], v[112:115], v[184:187], v[12:15]
	v_mfma_f32_16x16x32_f16 v[8:11], v[128:131], v[184:187], v[8:11]
	v_mfma_f32_16x16x32_f16 v[60:63], v[116:119], v[164:167], v[60:63]
	v_mfma_f32_16x16x32_f16 v[56:59], v[132:135], v[164:167], v[56:59]
	v_mfma_f32_16x16x32_f16 v[44:47], v[116:119], v[172:175], v[44:47]
	v_mfma_f32_16x16x32_f16 v[40:43], v[132:135], v[172:175], v[40:43]
	v_mfma_f32_16x16x32_f16 v[28:31], v[116:119], v[180:183], v[28:31]
	v_mfma_f32_16x16x32_f16 v[24:27], v[132:135], v[180:183], v[24:27]
	v_mfma_f32_16x16x32_f16 v[12:15], v[116:119], v[188:191], v[12:15]
	v_mfma_f32_16x16x32_f16 v[8:11], v[132:135], v[188:191], v[8:11]
	v_mfma_f32_16x16x32_f16 v[52:55], v[144:147], v[160:163], v[52:55]
	v_mfma_f32_16x16x32_f16 v[48:51], v[152:155], v[160:163], v[48:51]
	v_mfma_f32_16x16x32_f16 v[36:39], v[144:147], v[168:171], v[36:39]
	v_mfma_f32_16x16x32_f16 v[32:35], v[152:155], v[168:171], v[32:35]
	v_mfma_f32_16x16x32_f16 v[20:23], v[144:147], v[176:179], v[20:23]
	v_mfma_f32_16x16x32_f16 v[16:19], v[152:155], v[176:179], v[16:19]
	v_mfma_f32_16x16x32_f16 v[4:7], v[144:147], v[184:187], v[4:7]
	v_mfma_f32_16x16x32_f16 v[0:3], v[152:155], v[184:187], v[0:3]
	v_mfma_f32_16x16x32_f16 v[52:55], v[148:151], v[164:167], v[52:55]
	v_mfma_f32_16x16x32_f16 v[48:51], v[156:159], v[164:167], v[48:51]
	v_mfma_f32_16x16x32_f16 v[36:39], v[148:151], v[172:175], v[36:39]
	v_mfma_f32_16x16x32_f16 v[32:35], v[156:159], v[172:175], v[32:35]
	v_mfma_f32_16x16x32_f16 v[20:23], v[148:151], v[180:183], v[20:23]
	v_mfma_f32_16x16x32_f16 v[16:19], v[156:159], v[180:183], v[16:19]
	v_mfma_f32_16x16x32_f16 v[4:7], v[148:151], v[188:191], v[4:7]
	v_mfma_f32_16x16x32_f16 v[0:3], v[156:159], v[188:191], v[0:3]
	s_barrier
	s_add_i32 s59, s59, 2
	s_add_u32 s42, s42, 0x100
	s_addc_u32 s43, s43, 0
	s_add_u32 s41, s41, 0x100
	s_addc_u32 s58, s58, 0
	s_cmp_gt_u32 s59, 13
	s_cbranch_scc0 .LBB0_2793
	s_and_b64 vcc, exec, s[16:17]
	s_cbranch_vccz .LBB0_2796
	s_barrier
